# all flat_* memory ops re-encoded as global_* (all addresses are global): waits on lgkmcnt no longer include global round trips
# speedup vs baseline: 1.0097x; 1.0097x over previous
;   DI const float* c() const { return (const float*)sp[1]; }
;   DI const float* c_ctx() const { return (const float*)sp[3]; }
; DI float silu(float v) { return v / (1.f + __expf(-v)); }
; DI void phase_prep0(const Params& p, char* smem) {
;     ...
;     for (int i = tid; i < 9 * 2048; i += NT) { const int r = i >> 11, k = i & 2047; tl[i] = silu(r < 8 ? p.c()[r * 2048 + k] : p.c_ctx()[k]); }
.LBB0_11:
	v_and_b32_e32 v8, 0x7ff, v10
	v_lshlrev_b32_e32 v8, 2, v8
	s_waitcnt lgkmcnt(0)
	v_lshl_add_u64 v[12:13], v[4:5], 0, v[8:9]
	v_cmp_gt_i32_e32 vcc, s6, v10
	v_add_u32_e32 v11, 0x100, v10
	s_nop 0
	v_cndmask_b32_e32 v13, v13, v7, vcc
	v_cndmask_b32_e32 v12, v12, v6, vcc
	global_load_dword v8, v[12:13], off
	v_cmp_lt_i32_e32 vcc, s7, v10
	v_mov_b32_e32 v10, v11
	s_or_b64 s[2:3], vcc, s[2:3]
	v_lshl_add_u64 v[6:7], v[6:7], 0, s[4:5]
	s_waitcnt vmcnt(0) lgkmcnt(0)
	v_mul_f32_e32 v11, 0xbfb8aa3b, v8
	v_exp_f32_e32 v11, v11
	s_nop 0
	v_add_f32_e32 v11, 1.0, v11
	v_div_scale_f32 v12, s[10:11], v11, v11, v8
	v_rcp_f32_e32 v13, v12
	v_div_scale_f32 v14, vcc, v8, v11, v8
	v_fma_f32 v15, -v12, v13, 1.0
	v_fmac_f32_e32 v13, v15, v13
	v_mul_f32_e32 v15, v14, v13
	v_fma_f32 v16, -v12, v15, v14
	v_fmac_f32_e32 v15, v16, v13
	v_fma_f32 v12, -v12, v15, v14
	v_div_fmas_f32 v12, v12, v13, v15
	v_div_fixup_f32 v8, v12, v11, v8
	ds_write_b32 v3, v8
	v_add_u32_e32 v3, 0x400, v3
	s_andn2_b64 exec, exec, s[2:3]
	s_cbranch_execnz .LBB0_11

; DI void phase_prep0(const Params& p, char* smem) {
;     ...
; #pragma unroll 16
;       for (int k = kq * 512; k < kq * 512 + 512; ++k) {
;         const float wv = w[(long)k * 6144];
; #pragma unroll
;         for (int r = 0; r < 9; ++r) acc[r] += tl[r * 2048 + k] * wv;
;       }
.LBB0_15:
	v_add_co_u32_e64 v20, s[0:1], s7, v8
	v_add_co_u32_e32 v18, vcc, 0xfffa6000, v8
	s_nop 0
	v_addc_co_u32_e64 v21, s[0:1], -1, v9, s[0:1]
	v_add_co_u32_e64 v22, s[0:1], s10, v8
	v_add_u32_e32 v41, s33, v35
	s_nop 0
	v_addc_co_u32_e64 v23, s[0:1], -1, v9, s[0:1]
	v_add_co_u32_e64 v24, s[0:1], s11, v8
	v_addc_co_u32_e32 v19, vcc, -1, v9, vcc
	s_nop 0
	v_addc_co_u32_e64 v25, s[0:1], -1, v9, s[0:1]
	v_add_co_u32_e64 v26, s[0:1], s12, v8
	ds_read_b128 v[42:45], v41
	ds_read_b128 v[46:49], v41 offset:16
	ds_read_b128 v[50:53], v41 offset:32
	ds_read_b128 v[54:57], v41 offset:48
	v_addc_co_u32_e64 v27, s[0:1], -1, v9, s[0:1]
	v_add_co_u32_e64 v28, s[0:1], s13, v8
	global_load_dword v174, v[20:21], off
	global_load_dword v176, v[22:23], off
	global_load_dword v178, v[24:25], off
	global_load_dword v180, v[26:27], off
	v_addc_co_u32_e64 v29, s[0:1], -1, v9, s[0:1]
	v_add_co_u32_e64 v30, s[0:1], s14, v8
	ds_read_b128 v[20:23], v41 offset:8192
	ds_read_b128 v[24:27], v41 offset:8208
	ds_read_b128 v[58:61], v41 offset:16384
	ds_read_b128 v[62:65], v41 offset:16400
	ds_read_b128 v[66:69], v41 offset:24576
	ds_read_b128 v[70:73], v41 offset:24592
	ds_read_b128 v[74:77], v41 offset:32768
	ds_read_b128 v[78:81], v41 offset:32784
	ds_read_b128 v[82:85], v41 offset:40960
	ds_read_b128 v[86:89], v41 offset:40976
	ds_read_b128 v[90:93], v41 offset:49152
	ds_read_b128 v[94:97], v41 offset:49168
	ds_read_b128 v[98:101], v41 offset:57344
	ds_read_b128 v[102:105], v41 offset:57360
	v_addc_co_u32_e64 v31, s[0:1], -1, v9, s[0:1]
	v_add_co_u32_e64 v32, s[0:1], s15, v8
	v_add_u32_e32 v162, 0x10000, v41
	s_nop 0
	v_addc_co_u32_e64 v33, s[0:1], -1, v9, s[0:1]
	v_add_co_u32_e64 v106, s[0:1], s16, v8
	v_add_u32_e32 v163, 0x10010, v41
	s_nop 0
	v_addc_co_u32_e64 v107, s[0:1], -1, v9, s[0:1]
	v_add_co_u32_e64 v108, s[0:1], s17, v8
	global_load_dword v182, v[28:29], off
	global_load_dword v184, v[30:31], off
	global_load_dword v186, v[32:33], off
	s_nop 0
	global_load_dword v32, v[106:107], off
	v_addc_co_u32_e64 v109, s[0:1], -1, v9, s[0:1]
	v_add_co_u32_e64 v110, s[0:1], s18, v8
	v_add_u32_e32 v33, 0x10020, v41
	s_nop 0
	v_addc_co_u32_e64 v111, s[0:1], -1, v9, s[0:1]
	v_add_co_u32_e64 v112, s[0:1], s19, v8
	s_waitcnt lgkmcnt(0)
	v_mov_b32_e32 v204, v58
	v_addc_co_u32_e64 v113, s[0:1], -1, v9, s[0:1]
	v_add_co_u32_e64 v114, s[0:1], s21, v8
	v_mov_b32_e32 v205, v20
	s_nop 0
	v_addc_co_u32_e64 v115, s[0:1], -1, v9, s[0:1]
	v_add_co_u32_e64 v158, s[0:1], s22, v8
	global_load_dword v188, v[108:109], off
	global_load_dword v190, v[110:111], off
	global_load_dword v192, v[112:113], off
	global_load_dword v194, v[114:115], off
	v_addc_co_u32_e64 v159, s[0:1], -1, v9, s[0:1]
	v_add_co_u32_e64 v160, s[0:1], s23, v8
	ds_read_b128 v[28:31], v41 offset:8224
	ds_read_b128 v[106:109], v41 offset:8240
	ds_read_b128 v[110:113], v41 offset:16416
	ds_read_b128 v[114:117], v41 offset:16432
	ds_read_b128 v[118:121], v41 offset:24608
	ds_read_b128 v[122:125], v41 offset:24624
	ds_read_b128 v[126:129], v41 offset:32800
	ds_read_b128 v[130:133], v41 offset:32816
	ds_read_b128 v[134:137], v41 offset:40992
	ds_read_b128 v[138:141], v41 offset:41008
	ds_read_b128 v[142:145], v41 offset:49184
	ds_read_b128 v[146:149], v41 offset:49200
	ds_read_b128 v[150:153], v41 offset:57376
	ds_read_b128 v[154:157], v41 offset:57392
	v_addc_co_u32_e64 v161, s[0:1], -1, v9, s[0:1]
	global_load_dword v196, v[158:159], off
	global_load_dword v198, v[160:161], off
	global_load_dword v200, v[8:9], off
	v_add_u32_e32 v41, 0x10030, v41
	global_load_dword v18, v[18:19], off
	ds_read_b128 v[158:161], v162
	ds_read_b128 v[162:165], v163
	ds_read_b128 v[166:169], v33
	ds_read_b128 v[170:173], v41
	v_mov_b32_e32 v206, v74
	v_mov_b32_e32 v207, v66
	v_mov_b32_e32 v208, v90
	v_mov_b32_e32 v209, v82
	v_mov_b32_e32 v211, v98
	s_waitcnt lgkmcnt(0)
	v_mov_b32_e32 v210, v158
	v_mov_b32_e32 v20, v59
	v_mov_b32_e32 v66, v75
	v_mov_b32_e32 v82, v91
	v_mov_b32_e32 v98, v159
	v_mov_b32_e32 v58, v60
	v_mov_b32_e32 v59, v22
	v_mov_b32_e32 v74, v76
	v_mov_b32_e32 v75, v68
	v_mov_b32_e32 v90, v92
	v_mov_b32_e32 v91, v84
	v_mov_b32_e32 v213, v100
	v_mov_b32_e32 v212, v160
	v_mov_b32_e32 v22, v61
	v_mov_b32_e32 v68, v77
	v_mov_b32_e32 v84, v93
	v_mov_b32_e32 v100, v161
	v_mov_b32_e32 v60, v62
	v_mov_b32_e32 v61, v24
	v_mov_b32_e32 v76, v78
	v_mov_b32_e32 v77, v70
	v_mov_b32_e32 v92, v94
	v_mov_b32_e32 v93, v86
	v_mov_b32_e32 v215, v102
	v_mov_b32_e32 v214, v162
	v_mov_b32_e32 v24, v63
	v_mov_b32_e32 v70, v79
	v_mov_b32_e32 v86, v95
	v_mov_b32_e32 v102, v163
	v_mov_b32_e32 v62, v64
	v_mov_b32_e32 v63, v26
	v_mov_b32_e32 v78, v80
	v_mov_b32_e32 v79, v72
	v_mov_b32_e32 v94, v96
	v_mov_b32_e32 v95, v88
	v_mov_b32_e32 v217, v104
	v_mov_b32_e32 v216, v164
	v_mov_b32_e32 v26, v65
	v_mov_b32_e32 v72, v81
	v_mov_b32_e32 v88, v97
	v_mov_b32_e32 v104, v165
	v_mov_b32_e32 v64, v110
	v_mov_b32_e32 v65, v28
	v_mov_b32_e32 v80, v126
	v_mov_b32_e32 v81, v118
	v_mov_b32_e32 v96, v142
	v_mov_b32_e32 v97, v134
	v_mov_b32_e32 v219, v150
	v_mov_b32_e32 v218, v166
	v_mov_b32_e32 v28, v111
	v_mov_b32_e32 v118, v127
	v_mov_b32_e32 v134, v143
	v_mov_b32_e32 v150, v167
	v_mov_b32_e32 v110, v112
	v_mov_b32_e32 v111, v30
	v_mov_b32_e32 v126, v128
	v_mov_b32_e32 v127, v120
	v_mov_b32_e32 v142, v144
	v_mov_b32_e32 v143, v136
	v_mov_b32_e32 v221, v152
	v_mov_b32_e32 v220, v168
	v_mov_b32_e32 v30, v113
	v_mov_b32_e32 v120, v129
	v_mov_b32_e32 v136, v145
	v_mov_b32_e32 v152, v169
	v_mov_b32_e32 v112, v114
	v_mov_b32_e32 v113, v106
	v_mov_b32_e32 v128, v130
	v_mov_b32_e32 v129, v122
	v_mov_b32_e32 v144, v146
	v_mov_b32_e32 v145, v138
	v_mov_b32_e32 v223, v154
	v_mov_b32_e32 v222, v170
	s_waitcnt vmcnt(0)
; DI void phase_prep0(const Params& p, char* smem) {
;     ...
;       for (int k = kq * 512; k < kq * 512 + 512; ++k) {
;         const float wv = w[(long)k * 6144];
; #pragma unroll
;         for (int r = 0; r < 9; ++r) acc[r] += tl[r * 2048 + k] * wv;
;       }
	v_fmac_f32_e32 v40, v18, v42
	v_pk_fma_f32 v[16:17], v[18:19], v[204:205], v[16:17] op_sel_hi:[0,1,1]
	v_pk_fma_f32 v[14:15], v[18:19], v[206:207], v[14:15] op_sel_hi:[0,1,1]
	v_pk_fma_f32 v[12:13], v[18:19], v[208:209], v[12:13] op_sel_hi:[0,1,1]
	v_pk_fma_f32 v[10:11], v[18:19], v[210:211], v[10:11] op_sel_hi:[0,1,1]
	v_fmac_f32_e32 v40, v174, v43
	v_pk_fma_f32 v[16:17], v[174:175], v[20:21], v[16:17] op_sel_hi:[0,1,1]
	v_pk_fma_f32 v[14:15], v[174:175], v[66:67], v[14:15] op_sel_hi:[0,1,1]
	v_pk_fma_f32 v[12:13], v[174:175], v[82:83], v[12:13] op_sel_hi:[0,1,1]
	v_pk_fma_f32 v[10:11], v[174:175], v[98:99], v[10:11] op_sel_hi:[0,1,1]
	v_fmac_f32_e32 v40, v176, v44
	v_pk_fma_f32 v[16:17], v[176:177], v[58:59], v[16:17] op_sel_hi:[0,1,1]
	v_pk_fma_f32 v[14:15], v[176:177], v[74:75], v[14:15] op_sel_hi:[0,1,1]
	v_pk_fma_f32 v[12:13], v[176:177], v[90:91], v[12:13] op_sel_hi:[0,1,1]
	v_pk_fma_f32 v[10:11], v[176:177], v[212:213], v[10:11] op_sel_hi:[0,1,1]
	v_fmac_f32_e32 v40, v178, v45
	v_pk_fma_f32 v[16:17], v[178:179], v[22:23], v[16:17] op_sel_hi:[0,1,1]
	v_pk_fma_f32 v[14:15], v[178:179], v[68:69], v[14:15] op_sel_hi:[0,1,1]
	v_pk_fma_f32 v[12:13], v[178:179], v[84:85], v[12:13] op_sel_hi:[0,1,1]
	v_pk_fma_f32 v[10:11], v[178:179], v[100:101], v[10:11] op_sel_hi:[0,1,1]
	v_fmac_f32_e32 v40, v180, v46
	v_pk_fma_f32 v[16:17], v[180:181], v[60:61], v[16:17] op_sel_hi:[0,1,1]
	v_pk_fma_f32 v[14:15], v[180:181], v[76:77], v[14:15] op_sel_hi:[0,1,1]
	v_pk_fma_f32 v[12:13], v[180:181], v[92:93], v[12:13] op_sel_hi:[0,1,1]
	v_pk_fma_f32 v[10:11], v[180:181], v[214:215], v[10:11] op_sel_hi:[0,1,1]
	v_fmac_f32_e32 v40, v182, v47
	v_pk_fma_f32 v[16:17], v[182:183], v[24:25], v[16:17] op_sel_hi:[0,1,1]
	v_pk_fma_f32 v[14:15], v[182:183], v[70:71], v[14:15] op_sel_hi:[0,1,1]
	v_pk_fma_f32 v[12:13], v[182:183], v[86:87], v[12:13] op_sel_hi:[0,1,1]
	v_pk_fma_f32 v[10:11], v[182:183], v[102:103], v[10:11] op_sel_hi:[0,1,1]
	v_fmac_f32_e32 v40, v184, v48
	v_pk_fma_f32 v[16:17], v[184:185], v[62:63], v[16:17] op_sel_hi:[0,1,1]
	v_pk_fma_f32 v[14:15], v[184:185], v[78:79], v[14:15] op_sel_hi:[0,1,1]
	v_pk_fma_f32 v[12:13], v[184:185], v[94:95], v[12:13] op_sel_hi:[0,1,1]
	v_pk_fma_f32 v[10:11], v[184:185], v[216:217], v[10:11] op_sel_hi:[0,1,1]
	v_fmac_f32_e32 v40, v186, v49
	v_pk_fma_f32 v[16:17], v[186:187], v[26:27], v[16:17] op_sel_hi:[0,1,1]
	v_pk_fma_f32 v[14:15], v[186:187], v[72:73], v[14:15] op_sel_hi:[0,1,1]
	v_pk_fma_f32 v[12:13], v[186:187], v[88:89], v[12:13] op_sel_hi:[0,1,1]
	v_pk_fma_f32 v[10:11], v[186:187], v[104:105], v[10:11] op_sel_hi:[0,1,1]
	v_fmac_f32_e32 v40, v32, v50
	v_pk_fma_f32 v[16:17], v[32:33], v[64:65], v[16:17] op_sel_hi:[0,1,1]
	v_pk_fma_f32 v[14:15], v[32:33], v[80:81], v[14:15] op_sel_hi:[0,1,1]
	v_pk_fma_f32 v[12:13], v[32:33], v[96:97], v[12:13] op_sel_hi:[0,1,1]
	v_pk_fma_f32 v[10:11], v[32:33], v[218:219], v[10:11] op_sel_hi:[0,1,1]
	v_fmac_f32_e32 v40, v188, v51
	v_pk_fma_f32 v[16:17], v[188:189], v[28:29], v[16:17] op_sel_hi:[0,1,1]
	v_pk_fma_f32 v[14:15], v[188:189], v[118:119], v[14:15] op_sel_hi:[0,1,1]
	v_pk_fma_f32 v[12:13], v[188:189], v[134:135], v[12:13] op_sel_hi:[0,1,1]
	v_pk_fma_f32 v[10:11], v[188:189], v[150:151], v[10:11] op_sel_hi:[0,1,1]
	v_fmac_f32_e32 v40, v190, v52
	v_pk_fma_f32 v[16:17], v[190:191], v[110:111], v[16:17] op_sel_hi:[0,1,1]
	v_pk_fma_f32 v[14:15], v[190:191], v[126:127], v[14:15] op_sel_hi:[0,1,1]
	v_pk_fma_f32 v[12:13], v[190:191], v[142:143], v[12:13] op_sel_hi:[0,1,1]
	v_pk_fma_f32 v[10:11], v[190:191], v[220:221], v[10:11] op_sel_hi:[0,1,1]
	v_fmac_f32_e32 v40, v192, v53
	v_pk_fma_f32 v[16:17], v[192:193], v[30:31], v[16:17] op_sel_hi:[0,1,1]
	v_pk_fma_f32 v[14:15], v[192:193], v[120:121], v[14:15] op_sel_hi:[0,1,1]
	v_pk_fma_f32 v[12:13], v[192:193], v[136:137], v[12:13] op_sel_hi:[0,1,1]
	v_pk_fma_f32 v[10:11], v[192:193], v[152:153], v[10:11] op_sel_hi:[0,1,1]
	v_mov_b32_e32 v106, v115
	v_mov_b32_e32 v122, v131
	v_mov_b32_e32 v138, v147
	v_mov_b32_e32 v154, v171
	v_fmac_f32_e32 v40, v194, v54
	v_pk_fma_f32 v[16:17], v[194:195], v[112:113], v[16:17] op_sel_hi:[0,1,1]
	v_pk_fma_f32 v[14:15], v[194:195], v[128:129], v[14:15] op_sel_hi:[0,1,1]
	v_pk_fma_f32 v[12:13], v[194:195], v[144:145], v[12:13] op_sel_hi:[0,1,1]
	v_pk_fma_f32 v[10:11], v[194:195], v[222:223], v[10:11] op_sel_hi:[0,1,1]
	v_mov_b32_e32 v114, v116
	v_mov_b32_e32 v115, v108
	v_mov_b32_e32 v130, v132
	v_mov_b32_e32 v131, v124
	v_mov_b32_e32 v146, v148
	v_mov_b32_e32 v147, v140
	v_mov_b32_e32 v225, v156
	v_mov_b32_e32 v224, v172
	v_fmac_f32_e32 v40, v196, v55
	v_pk_fma_f32 v[16:17], v[196:197], v[106:107], v[16:17] op_sel_hi:[0,1,1]
	v_pk_fma_f32 v[14:15], v[196:197], v[122:123], v[14:15] op_sel_hi:[0,1,1]
	v_pk_fma_f32 v[12:13], v[196:197], v[138:139], v[12:13] op_sel_hi:[0,1,1]
	v_pk_fma_f32 v[10:11], v[196:197], v[154:155], v[10:11] op_sel_hi:[0,1,1]
	s_add_i32 s33, s33, 64
	v_mov_b32_e32 v108, v117
	v_mov_b32_e32 v124, v133
	v_mov_b32_e32 v140, v149
	v_mov_b32_e32 v156, v173
	v_fmac_f32_e32 v40, v198, v56
	v_pk_fma_f32 v[16:17], v[198:199], v[114:115], v[16:17] op_sel_hi:[0,1,1]
	v_pk_fma_f32 v[14:15], v[198:199], v[130:131], v[14:15] op_sel_hi:[0,1,1]
	v_pk_fma_f32 v[12:13], v[198:199], v[146:147], v[12:13] op_sel_hi:[0,1,1]
	v_pk_fma_f32 v[10:11], v[198:199], v[224:225], v[10:11] op_sel_hi:[0,1,1]
	v_lshl_add_u64 v[8:9], v[8:9], 0, s[4:5]
	s_cmpk_eq_i32 s33, 0x800
	v_fmac_f32_e32 v40, v200, v57
	v_pk_fma_f32 v[16:17], v[200:201], v[108:109], v[16:17] op_sel_hi:[0,1,1]
	v_pk_fma_f32 v[14:15], v[200:201], v[124:125], v[14:15] op_sel_hi:[0,1,1]
	v_pk_fma_f32 v[12:13], v[200:201], v[140:141], v[12:13] op_sel_hi:[0,1,1]
	v_pk_fma_f32 v[10:11], v[200:201], v[156:157], v[10:11] op_sel_hi:[0,1,1]
	s_cbranch_scc0 .LBB0_15
;   DI const float* ada_b() const { return (const float*)sp[5]; }
; DI void phase_prep0(const Params& p, char* smem) {
;     ...
;       __syncthreads();
;       float* red = tl;
;       for (int r = 0; r < 9; ++r) red[(kq * 9 + r) * 64 + (tid & 63)] = acc[r];
;       __syncthreads();
;       if (tid < 64) {
;         for (int r = 0; r < 9; ++r) {
;           float sm = red[r * 64 + tid] + red[(9 + r) * 64 + tid] + red[(18 + r) * 64 + tid] + red[(27 + r) * 64 + tid];
;           P_MOD[((long)layer * 9 + r) * 6144 + col] = sm + p.ada_b()[layer * 6144 + col];
;         }
;       }
;       __syncthreads();
	s_barrier
	ds_write2st64_b32 v34, v40, v17 offset1:1
	ds_write2st64_b32 v34, v16, v15 offset0:2 offset1:3
	ds_write2st64_b32 v34, v14, v13 offset0:4 offset1:5
	ds_write2st64_b32 v34, v12, v11 offset0:6 offset1:7
	ds_write_b32 v34, v10 offset:2048
	s_waitcnt lgkmcnt(0)
	s_barrier
	s_and_saveexec_b64 s[0:1], s[2:3]
	s_cbranch_execz .LBB0_13
	ds_read_b64 v[8:9], v38
	s_mul_i32 s33, s31, 0x1800
	v_add_u32_e32 v10, s33, v6
	v_ashrrev_i32_e32 v11, 31, v10
	v_lshl_add_u64 v[6:7], v[6:7], 2, s[48:49]
	s_waitcnt lgkmcnt(0)
	v_lshl_add_u64 v[8:9], v[10:11], 2, v[8:9]
	global_load_dword v48, v[8:9], off
	ds_read2st64_b32 v[10:11], v1 offset0:8 offset1:9
	ds_read2st64_b32 v[12:13], v1 offset0:10 offset1:11
	ds_read2st64_b32 v[14:15], v1 offset0:12 offset1:13
	ds_read2st64_b32 v[16:17], v1 offset0:14 offset1:15
	ds_read2st64_b32 v[18:19], v1 offset1:1
	ds_read2st64_b32 v[20:21], v1 offset0:2 offset1:3
	ds_read2st64_b32 v[22:23], v1 offset0:4 offset1:5
	ds_read2st64_b32 v[24:25], v1 offset0:6 offset1:7
	ds_read2st64_b32 v[26:27], v1 offset0:26 offset1:27
	ds_read2st64_b32 v[28:29], v1 offset0:28 offset1:29
	ds_read2st64_b32 v[30:31], v1 offset0:30 offset1:31
	ds_read2st64_b32 v[32:33], v1 offset0:24 offset1:25
	ds_read2st64_b32 v[40:41], v1 offset0:18 offset1:19
	ds_read2st64_b32 v[42:43], v1 offset0:20 offset1:21
	ds_read2st64_b32 v[44:45], v1 offset0:22 offset1:23
	ds_read2st64_b32 v[46:47], v1 offset0:16 offset1:17
	s_waitcnt lgkmcnt(0)
	v_add_f32_e32 v11, v18, v11
	v_add_f32_e32 v11, v11, v40
	v_add_f32_e32 v11, v11, v27
	v_mad_i64_i32 v[6:7], s[34:35], s31, v39, v[6:7]
	v_add_f32_e32 v12, v19, v12
	v_add_f32_e32 v12, v12, v41
	v_add_f32_e32 v12, v12, v28
	v_add_f32_e32 v14, v21, v14
	v_add_f32_e32 v14, v14, v43
	v_add_f32_e32 v14, v14, v30
	v_add_f32_e32 v16, v23, v16
	v_add_f32_e32 v16, v16, v45
	s_waitcnt vmcnt(0)
	v_add_f32_e32 v11, v11, v48
	global_store_dword v[6:7], v11, off
	global_load_dword v11, v[8:9], off
	v_add_co_u32_e32 v48, vcc, s6, v6
	s_waitcnt vmcnt(0) lgkmcnt(0)
	v_add_f32_e32 v11, v12, v11
	v_addc_co_u32_e32 v49, vcc, 0, v7, vcc
	global_store_dword v[48:49], v11, off
	global_load_dword v11, v[8:9], off
	v_add_f32_e32 v12, v20, v13
	v_add_f32_e32 v12, v12, v42
	v_add_co_u32_e32 v18, vcc, s24, v6
	v_add_f32_e32 v12, v12, v29
	s_nop 0
	v_addc_co_u32_e32 v19, vcc, 0, v7, vcc
	s_waitcnt vmcnt(0) lgkmcnt(0)
	v_add_f32_e32 v11, v12, v11
	global_store_dword v[18:19], v11, off
	global_load_dword v11, v[8:9], off
	v_add_co_u32_e32 v12, vcc, s25, v6
	s_waitcnt vmcnt(0) lgkmcnt(0)
	v_add_f32_e32 v11, v14, v11
	v_addc_co_u32_e32 v13, vcc, 0, v7, vcc
	global_store_dword v[12:13], v11, off
	global_load_dword v11, v[8:9], off
	v_add_f32_e32 v14, v22, v15
	v_add_f32_e32 v14, v14, v44
	v_add_co_u32_e32 v12, vcc, s26, v6
	v_add_f32_e32 v14, v14, v31
	s_nop 0
	v_addc_co_u32_e32 v13, vcc, 0, v7, vcc
	v_add_co_u32_e32 v18, vcc, s27, v6
	s_waitcnt vmcnt(0) lgkmcnt(0)
	v_add_f32_e32 v11, v14, v11
	global_store_dword v[12:13], v11, off
	global_load_dword v11, v[8:9], off
	ds_read2st64_b32 v[12:13], v1 offset0:32 offset1:33
	ds_read2st64_b32 v[14:15], v1 offset0:34 offset1:35
	v_addc_co_u32_e32 v19, vcc, 0, v7, vcc
	s_waitcnt lgkmcnt(0)
	v_add_f32_e32 v12, v16, v12
	v_add_f32_e32 v16, v25, v46
	v_add_f32_e32 v16, v16, v33
	v_add_f32_e32 v14, v16, v14
	s_waitcnt vmcnt(0)
	v_add_f32_e32 v11, v12, v11
	global_store_dword v[18:19], v11, off
	global_load_dword v11, v[8:9], off
	v_add_f32_e32 v12, v24, v17
	v_add_f32_e32 v12, v12, v32
	v_add_co_u32_e32 v18, vcc, s28, v6
	v_add_f32_e32 v12, v12, v13
	s_nop 0
	v_addc_co_u32_e32 v19, vcc, 0, v7, vcc
	s_waitcnt vmcnt(0) lgkmcnt(0)
	v_add_f32_e32 v11, v12, v11
	global_store_dword v[18:19], v11, off
	global_load_dword v11, v[8:9], off
	v_add_co_u32_e32 v12, vcc, s29, v6
	s_waitcnt vmcnt(0) lgkmcnt(0)
	v_add_f32_e32 v11, v14, v11
	v_addc_co_u32_e32 v13, vcc, 0, v7, vcc
	global_store_dword v[12:13], v11, off
	global_load_dword v8, v[8:9], off
	v_add_f32_e32 v9, v10, v47
	v_add_f32_e32 v9, v9, v26
	v_add_co_u32_e32 v6, vcc, 0x30000, v6
	v_add_f32_e32 v9, v9, v15
	s_nop 0
	v_addc_co_u32_e32 v7, vcc, 0, v7, vcc
	s_waitcnt vmcnt(0) lgkmcnt(0)
	v_add_f32_e32 v8, v9, v8
	global_store_dword v[6:7], v8, off
	s_branch .LBB0_13

;   DI const float* x() const { return (const float*)sp[0]; }
;   DI const float* ab_w_in() const { return (const float*)sp[8]; }
;   DI const float* ab_w_out() const { return (const float*)sp[13]; }
; DI int TID() { int t = threadIdx.x; asm volatile("" : "+v"(t)); return t; }
; DI void tr_load(const float* __restrict__ src, int ld, int K, int mapid, const float* __restrict__ ks, int tile, f32x4 (&v)[4]) {
;   const int tid = TID();
;   const int kT = K >> 6, nt = tile / kT, kt = tile % kT, n0 = nt * 64, k0 = kt * 64;
;   const int n4 = (tid & 15) * 4, kr = tid >> 4;
;   const int n = n0 + n4;
;   const int sc = mapid == 1 ? srccol1(n) : (mapid == 2 ? srccol2(n) : n);
; #pragma unroll
;   for (int i = 0; i < 4; ++i) {
;     const int k = i * 16 + kr;
;     f32x4 x = {0.f, 0.f, 0.f, 0.f};
;     if (sc >= 0) x = *reinterpret_cast<const f32x4*>(src + (long)(k0 + k) * ld + sc);
;     if (ks) { const float g_ = ks[k0 + k]; x *= g_; }
;     v[i] = x;
;   }
; DI void phase_prep0(const Params& p, char* smem) {
;     ...
;   const int t1 = (N1 / 64) * 32, t2 = 32 * 64;
;   {
;     auto ld_ = [&](int it, f32x4 (&v)[4]) {
;       if (it < t1) tr_load(p.ab_w_in(), 16416, 2048, 1, nullptr, it, v);
;       else tr_load(p.ab_w_out(), 2048, 4096, 0, nullptr, it - t1, v);
;     };
;     auto fin_ = [&](int it, const f32x4 (&v)[4]) {
;       if (it < t1) tr_finish(2048, P_WA, it, v, tl);
;       else tr_finish(4096, P_WO1, it - t1, v, tl);
;     };
;     f32x4 va[4], vb[4];
;     int it = b;
;     if (it < t1 + t2) ld_(it, va);
.LBB0_41:
	s_or_b64 exec, exec, s[10:11]
	v_readlane_b32 s3, v254, 0
	s_cmpk_lt_i32 s3, 0x2040
	s_cselect_b64 s[0:1], -1, 0
	v_writelane_b32 v254, s0, 5
	s_cmpk_gt_i32 s3, 0x203f
	s_nop 0
	v_writelane_b32 v254, s1, 6
	s_cselect_b64 s[0:1], -1, 0
	s_lshl_b32 s2, s3, 6
	v_writelane_b32 v254, s2, 7
	s_and_b32 s2, s2, 0xfc0
	v_writelane_b32 v254, s2, 8
	s_ashr_i32 s2, s3, 31
	s_lshr_b32 s2, s2, 27
	s_add_i32 s2, s3, s2
	s_ashr_i32 s88, s2, 5
	s_and_b32 s2, s2, 0x3ffffe0
	s_sub_i32 s2, s3, s2
	s_lshl_b32 s4, s88, 6
	v_writelane_b32 v254, s4, 9
	s_lshl_b32 s2, s2, 6
	v_writelane_b32 v254, s2, 10
	s_add_u32 s2, s58, 0xd080000
	v_writelane_b32 v254, s2, 11
	s_addc_u32 s2, s59, 0
	v_writelane_b32 v254, s2, 12
	s_add_u32 s2, s58, 0x9000000
	v_writelane_b32 v254, s2, 13
	s_addc_u32 s2, s59, 0
	v_writelane_b32 v254, s2, 14
	s_cmpk_lt_i32 s3, 0x2840
	s_cbranch_scc0 .LBB0_75
	s_and_b64 vcc, exec, s[0:1]
	s_cbranch_vccz .LBB0_44
	v_mov_b32_e32 v1, 0x12268
	v_readlane_b32 s0, v254, 0
	ds_read_b64 v[2:3], v1
	s_add_i32 s0, s0, 0xdfc0
	v_mov_b32_e32 v1, v202
	s_and_b32 s0, s0, 0xffc0
	v_mov_b32_e32 v5, 0
	v_lshlrev_b32_e32 v4, 2, v1
	v_and_or_b32 v4, v4, 60, s0
	v_ashrrev_i32_e32 v1, 4, v1
	v_lshlrev_b32_e32 v4, 2, v4
	v_readlane_b32 s0, v254, 8
	s_waitcnt lgkmcnt(0)
	v_lshl_add_u64 v[2:3], v[2:3], 0, v[4:5]
	v_add_u32_e32 v4, s0, v1
	v_ashrrev_i32_e32 v5, 31, v4
	v_lshlrev_b64 v[4:5], 13, v[4:5]
	v_lshl_add_u64 v[10:11], v[2:3], 0, v[4:5]
	s_mov_b32 s0, 0x20000
	v_add_co_u32_e32 v12, vcc, s0, v10
	s_mov_b32 s0, 0x40000
	s_nop 0
	v_addc_co_u32_e32 v13, vcc, 0, v11, vcc
	global_load_dwordx4 v[2:5], v[10:11], off
	global_load_dwordx4 v[6:9], v[12:13], off
	v_add_co_u32_e32 v12, vcc, s0, v10
	s_nop 1
	v_addc_co_u32_e32 v13, vcc, 0, v11, vcc
	v_add_co_u32_e32 v10, vcc, 0x60000, v10
	s_nop 1
	v_addc_co_u32_e32 v11, vcc, 0, v11, vcc
	global_load_dwordx4 v[14:17], v[12:13], off
	global_load_dwordx4 v[18:21], v[10:11], off
	s_cbranch_execz .LBB0_45
	s_branch .LBB0_54

;   DI const float* x() const { return (const float*)sp[0]; }
; DI int TID() { int t = threadIdx.x; asm volatile("" : "+v"(t)); return t; }
; DI void tr_load(const float* __restrict__ src, int ld, int K, int mapid, const float* __restrict__ ks, int tile, f32x4 (&v)[4]) {
;   const int tid = TID();
;   const int kT = K >> 6, nt = tile / kT, kt = tile % kT, n0 = nt * 64, k0 = kt * 64;
;   const int n4 = (tid & 15) * 4, kr = tid >> 4;
;   const int n = n0 + n4;
;   const int sc = mapid == 1 ? srccol1(n) : (mapid == 2 ? srccol2(n) : n);
; #pragma unroll
;   for (int i = 0; i < 4; ++i) {
;     const int k = i * 16 + kr;
;     f32x4 x = {0.f, 0.f, 0.f, 0.f};
;     if (sc >= 0) x = *reinterpret_cast<const f32x4*>(src + (long)(k0 + k) * ld + sc);
;     if (ks) { const float g_ = ks[k0 + k]; x *= g_; }
;     v[i] = x;
;   }
.LBB0_51:
	s_or_b64 exec, exec, s[0:1]
	v_mov_b32_e32 v18, 0
	v_cmp_lt_i32_e32 vcc, -1, v12
	v_mov_b32_e32 v19, v18
	v_mov_b32_e32 v20, v18
	v_mov_b32_e32 v21, v18
	v_mov_b32_e32 v2, v18
	v_mov_b32_e32 v3, v18
	v_mov_b32_e32 v4, v18
	v_mov_b32_e32 v5, v18
	v_mov_b32_e32 v6, v18
	v_mov_b32_e32 v7, v18
	v_mov_b32_e32 v8, v18
	v_mov_b32_e32 v9, v18
	v_mov_b32_e32 v14, v18
	v_mov_b32_e32 v15, v18
	v_mov_b32_e32 v16, v18
	v_mov_b32_e32 v17, v18
	s_and_saveexec_b64 s[0:1], vcc
	s_cbranch_execz .LBB0_53
	v_ashrrev_i32_e32 v1, 4, v1
	v_mov_b32_e32 v13, 0
	v_readlane_b32 s2, v254, 10
	v_lshl_add_u64 v[10:11], v[12:13], 2, v[10:11]
	s_mov_b32 s4, 0x10080
	v_add_u32_e32 v1, s2, v1
	v_mad_i64_i32 v[12:13], s[2:3], v1, s4, v[10:11]
	v_add_u32_e32 v2, 16, v1
	v_mad_i64_i32 v[14:15], s[2:3], v2, s4, v[10:11]
	global_load_dwordx4 v[2:5], v[12:13], off
	global_load_dwordx4 v[6:9], v[14:15], off
	v_add_u32_e32 v12, 32, v1
	v_mad_i64_i32 v[12:13], s[2:3], v12, s4, v[10:11]
	v_add_u32_e32 v1, 48, v1
	v_mad_i64_i32 v[10:11], s[2:3], v1, s4, v[10:11]
	global_load_dwordx4 v[14:17], v[12:13], off
	global_load_dwordx4 v[18:21], v[10:11], off

;   DI const float* x() const { return (const float*)sp[0]; }
; DI int TID() { int t = threadIdx.x; asm volatile("" : "+v"(t)); return t; }
; DI void tr_load(const float* __restrict__ src, int ld, int K, int mapid, const float* __restrict__ ks, int tile, f32x4 (&v)[4]) {
;   const int tid = TID();
;   const int kT = K >> 6, nt = tile / kT, kt = tile % kT, n0 = nt * 64, k0 = kt * 64;
;   const int n4 = (tid & 15) * 4, kr = tid >> 4;
;   const int n = n0 + n4;
;   const int sc = mapid == 1 ? srccol1(n) : (mapid == 2 ? srccol2(n) : n);
; #pragma unroll
;   for (int i = 0; i < 4; ++i) {
;     const int k = i * 16 + kr;
;     f32x4 x = {0.f, 0.f, 0.f, 0.f};
;     if (sc >= 0) x = *reinterpret_cast<const f32x4*>(src + (long)(k0 + k) * ld + sc);
;     if (ks) { const float g_ = ks[k0 + k]; x *= g_; }
;     v[i] = x;
;   }
; DI void phase_prep0(const Params& p, char* smem) {
;     ...
;     while (it < t1 + t2) {
;       const int nx = it + G_;
;       if (nx < t1 + t2) ld_(nx, vb);
;       fin_(it, va);
.LBB0_57:
	s_add_i32 s16, s17, s62
	s_cmpk_gt_i32 s16, 0x283f
	s_cselect_b64 s[0:1], -1, 0
	s_and_b64 vcc, exec, s[0:1]
	s_cbranch_vccnz .LBB0_72
	s_cmpk_gt_i32 s16, 0x203f
	s_mov_b64 s[2:3], -1
	s_cbranch_scc0 .LBB0_60
	ds_read_b64 v[12:13], v1
	s_add_i32 s2, s16, 0xdfc0
	v_mov_b32_e32 v11, v202
	s_and_b32 s2, s2, 0xffc0
	v_lshlrev_b32_e32 v22, 2, v11
	s_add_i32 s3, s6, s15
	v_and_or_b32 v22, v22, 60, s2
	s_and_b32 s3, s3, 0xfc0
	v_ashrrev_i32_e32 v11, 4, v11
	v_lshlrev_b32_e32 v22, 2, v22
	v_mov_b32_e32 v23, v10
	s_waitcnt lgkmcnt(0)
	v_lshl_add_u64 v[12:13], v[12:13], 0, v[22:23]
	v_add_u32_e32 v22, s3, v11
	v_ashrrev_i32_e32 v23, 31, v22
	v_lshlrev_b64 v[22:23], 13, v[22:23]
	v_lshl_add_u64 v[12:13], v[12:13], 0, v[22:23]
	v_add_co_u32_e32 v30, vcc, s7, v12
	s_mov_b64 s[2:3], 0
	s_nop 0
	v_addc_co_u32_e32 v31, vcc, 0, v13, vcc
	v_add_co_u32_e32 v38, vcc, 0x40000, v12
	global_load_dwordx4 v[22:25], v[12:13], off
	global_load_dwordx4 v[26:29], v[30:31], off
	v_addc_co_u32_e32 v39, vcc, 0, v13, vcc
	v_add_co_u32_e32 v12, vcc, 0x60000, v12
	s_nop 1
	v_addc_co_u32_e32 v13, vcc, 0, v13, vcc
	global_load_dwordx4 v[30:33], v[38:39], off
	global_load_dwordx4 v[34:37], v[12:13], off

;   DI const float* x() const { return (const float*)sp[0]; }
; DI int TID() { int t = threadIdx.x; asm volatile("" : "+v"(t)); return t; }
; DI void tr_load(const float* __restrict__ src, int ld, int K, int mapid, const float* __restrict__ ks, int tile, f32x4 (&v)[4]) {
;   const int tid = TID();
;   const int kT = K >> 6, nt = tile / kT, kt = tile % kT, n0 = nt * 64, k0 = kt * 64;
;   const int n4 = (tid & 15) * 4, kr = tid >> 4;
;   const int n = n0 + n4;
;   const int sc = mapid == 1 ? srccol1(n) : (mapid == 2 ? srccol2(n) : n);
; #pragma unroll
;   for (int i = 0; i < 4; ++i) {
;     const int k = i * 16 + kr;
;     f32x4 x = {0.f, 0.f, 0.f, 0.f};
;     if (sc >= 0) x = *reinterpret_cast<const f32x4*>(src + (long)(k0 + k) * ld + sc);
;     if (ks) { const float g_ = ks[k0 + k]; x *= g_; }
;     v[i] = x;
;   }
.LBB0_67:
	s_or_b64 exec, exec, s[2:3]
	v_cmp_gt_i32_e32 vcc, 0, v40
	s_and_saveexec_b64 s[2:3], vcc
	s_xor_b64 s[2:3], exec, s[2:3]
	s_or_saveexec_b64 s[2:3], s[2:3]
	v_mov_b32_e32 v12, v10
	v_mov_b32_e32 v13, v10
	v_mov_b32_e32 v11, v10
	s_waitcnt vmcnt(0) lgkmcnt(0)
	v_mov_b64_e32 v[36:37], v[12:13]
	v_mov_b32_e32 v22, 0
	v_mov_b64_e32 v[34:35], v[10:11]
	v_mov_b32_e32 v23, 0
	v_mov_b32_e32 v24, 0
	v_mov_b32_e32 v25, 0
	v_mov_b32_e32 v26, 0
	v_mov_b32_e32 v27, 0
	v_mov_b32_e32 v28, 0
	v_mov_b32_e32 v29, 0
	v_mov_b32_e32 v30, 0
	v_mov_b32_e32 v31, 0
	v_mov_b32_e32 v32, 0
	v_mov_b32_e32 v33, 0
	s_xor_b64 exec, exec, s[2:3]
	s_cbranch_execz .LBB0_71
	v_ashrrev_i32_e32 v11, 4, v41
	s_lshl_b32 s4, s18, 11
	v_mov_b32_e32 v41, v10
	v_subrev_u32_e32 v11, s4, v11
	s_add_i32 s4, s6, s15
	v_lshl_add_u64 v[12:13], v[40:41], 2, v[38:39]
	v_add_u32_e32 v11, s4, v11
	v_mad_i64_i32 v[30:31], s[4:5], v11, s12, v[12:13]
	v_add_u32_e32 v22, 16, v11
	v_mad_i64_i32 v[32:33], s[4:5], v22, s12, v[12:13]
	global_load_dwordx4 v[22:25], v[30:31], off
	global_load_dwordx4 v[26:29], v[32:33], off
	v_add_u32_e32 v30, 32, v11
	v_mad_i64_i32 v[38:39], s[4:5], v30, s12, v[12:13]
	v_add_u32_e32 v11, 48, v11
	v_mad_i64_i32 v[12:13], s[4:5], v11, s12, v[12:13]
	global_load_dwordx4 v[30:33], v[38:39], off
	global_load_dwordx4 v[34:37], v[12:13], off

;   DI const float* x() const { return (const float*)sp[0]; }
;   DI const float* c() const { return (const float*)sp[1]; }
; __device__ __forceinline__ unsigned xb_ld(unsigned* p)              { return __hip_atomic_load(p, __ATOMIC_RELAXED, __HIP_MEMORY_SCOPE_AGENT); }
; __device__ __forceinline__ void xcd_barrier_complete(unsigned* bar, unsigned x, unsigned& nloc, unsigned& nx) {
;     const unsigned G = gridDim.x * gridDim.y * gridDim.z;
;     unsigned sum, cnt, mine, sp = 0u;
;     for (;;) {
;         sum = 0u; cnt = 0u; mine = 0u;
; #pragma unroll
;         for (unsigned j = 0; j < 16; ++j) { const unsigned c = xb_ld(&bar[XB_XCNT(j)]); sum += c; cnt += (c > 0u) ? 1u : 0u; mine = (j == x) ? c : mine; }
;         if (sum == G) break;
;         __builtin_amdgcn_s_sleep(1);
;         if ((++sp & 255u) == 0u) { if (xb_ld(&bar[XB_TMO])) break; if (sp > XB_SPIN_CAP) { atomicAdd(&bar[XB_TMO], 1u); break; } }
;     }
;     nloc = mine > 0u ? mine : 1u; nx = cnt > 0u ? cnt : 1u;
; }
.LBB0_92:
	global_load_dword v47, v[0:1], off sc1
	global_load_dword v32, v[2:3], off sc1
	global_load_dword v33, v[4:5], off sc1
	global_load_dword v34, v[6:7], off sc1
	global_load_dword v35, v[8:9], off sc1
	global_load_dword v36, v[10:11], off sc1
	global_load_dword v37, v[12:13], off sc1
	global_load_dword v38, v[14:15], off sc1
	global_load_dword v39, v[16:17], off sc1
	global_load_dword v40, v[18:19], off sc1
	global_load_dword v41, v[20:21], off sc1
	global_load_dword v42, v[22:23], off sc1
	global_load_dword v43, v[24:25], off sc1
	global_load_dword v44, v[26:27], off sc1
	global_load_dword v45, v[28:29], off sc1
	global_load_dword v46, v[30:31], off sc1
	v_readlane_b32 s10, v254, 15
	s_or_b64 s[8:9], s[8:9], exec
	s_or_b64 s[6:7], s[6:7], exec
	s_waitcnt vmcnt(0) lgkmcnt(0)
	v_add_u32_e32 v48, v32, v47
	v_add_u32_e32 v48, v48, v33
	v_add_u32_e32 v48, v48, v34
	v_add_u32_e32 v48, v48, v35
	v_add_u32_e32 v48, v48, v36
	v_add_u32_e32 v48, v48, v37
	v_add_u32_e32 v48, v48, v38
	v_add_u32_e32 v48, v48, v39
	v_add_u32_e32 v48, v48, v40
	v_add_u32_e32 v48, v48, v41
	v_add_u32_e32 v48, v48, v42
	v_add_u32_e32 v48, v48, v43
	v_add_u32_e32 v48, v48, v44
	v_add_u32_e32 v48, v48, v45
	v_add_u32_e32 v48, v48, v46
	v_cmp_ne_u32_e32 vcc, s10, v48
	s_and_saveexec_b64 s[10:11], vcc
	s_cbranch_execz .LBB0_91
	s_and_b32 s14, s20, 0xff
	s_mov_b64 s[12:13], -1
	s_cmp_eq_u32 s14, 0
	s_mov_b64 s[16:17], -1
	s_mov_b64 s[14:15], -1
	s_sleep 1
	s_cbranch_scc1 .LBB0_95
	s_and_saveexec_b64 s[18:19], s[16:17]
	s_cbranch_execz .LBB0_90
	s_branch .LBB0_98
.LBB0_95:
	v_mov_b64_e32 v[48:49], s[0:1]
	global_load_dword v48, v[48:49], off sc1
	s_mov_b64 s[16:17], 0
	s_waitcnt vmcnt(0) lgkmcnt(0)
	v_cmp_eq_u32_e32 vcc, 0, v48
	s_and_saveexec_b64 s[18:19], vcc
	s_cmp_lt_u32 s20, 0x40001
	s_cselect_b64 s[16:17], -1, 0
	s_xor_b64 s[14:15], exec, -1
	s_and_b64 s[16:17], s[16:17], exec
	s_or_b64 exec, exec, s[18:19]
	s_and_saveexec_b64 s[18:19], s[16:17]
	s_cbranch_execz .LBB0_90

; __device__ __forceinline__ unsigned xb_ld(unsigned* p)              { return __hip_atomic_load(p, __ATOMIC_RELAXED, __HIP_MEMORY_SCOPE_AGENT); }
; __device__ __forceinline__ void xcd_barrier_complete(unsigned* bar, unsigned x, unsigned& nloc, unsigned& nx) {
;     ...
;         if ((++sp & 255u) == 0u) { if (xb_ld(&bar[XB_TMO])) break; if (sp > XB_SPIN_CAP) { atomicAdd(&bar[XB_TMO], 1u); break; } }
.LBB0_99:
	s_or_b64 exec, exec, s[2:3]
	s_xor_b64 s[2:3], s[4:5], -1
	s_and_saveexec_b64 s[4:5], s[2:3]
	s_xor_b64 s[2:3], exec, s[4:5]
	s_cbranch_execz .LBB0_101
	v_mov_b32_e32 v2, 1
	v_mov_b64_e32 v[0:1], s[0:1]
	global_atomic_add v[0:1], v2, off

;   DI const float* x() const { return (const float*)sp[0]; }
; __device__ __forceinline__ unsigned xb_ld(unsigned* p)              { return __hip_atomic_load(p, __ATOMIC_RELAXED, __HIP_MEMORY_SCOPE_AGENT); }
; __device__ __forceinline__ unsigned xb_add(unsigned* p, unsigned v) { return __hip_atomic_fetch_add(p, v, __ATOMIC_RELAXED, __HIP_MEMORY_SCOPE_AGENT); }
; #define XB_SPIN(cond, bar) do { unsigned _sp = 0; while (cond) { __builtin_amdgcn_s_sleep(1); \
;     if ((++_sp & 255u) == 0u) { if (xb_ld(&(bar)[XB_TMO])) break; if (_sp > XB_SPIN_CAP) { atomicAdd(&(bar)[XB_TMO], 1u); break; } } } } while (0)
; __device__ __forceinline__ void xcd_barrier(const XcdBarrier& b) {
;     ...
;         const unsigned old = xb_add(&bar[XB_XSUB(b.x)], 1u);
;         const unsigned gen = old / nloc;
;         if (old + 1u == (gen + 1u) * nloc) {
;             __builtin_amdgcn_fence(__ATOMIC_RELEASE, "agent");
;             asm volatile("s_waitcnt vmcnt(0)" ::: "memory");
;             const unsigned og = xb_add(&bar[XB_TOP], 1u);
;             const unsigned tg = og / nx;
;             if (og + 1u == (tg + 1u) * nx) xb_add(&bar[XB_TOPGEN], 1u);
;             else XB_SPIN(xb_ld(&bar[XB_TOPGEN]) == tg, bar);
;             __builtin_amdgcn_fence(__ATOMIC_ACQUIRE, "agent");
;             xb_add(&bar[XB_XGEN(b.x)], 1u);
;             asm volatile("s_waitcnt vmcnt(0)" ::: "memory");
;         } else {
;             XB_SPIN(xb_ld(&bar[XB_XGEN(b.x)]) == gen, bar);
.LBB0_102:
	s_add_u32 s22, s34, 0xe36d000
	s_addc_u32 s23, s35, 0
	s_lshl_b32 s24, s33, 6
	s_add_i32 s2, s24, 0x500
	s_mov_b32 s3, 0
	s_lshl_b64 s[0:1], s[2:3], 2
	s_add_u32 s0, s22, s0
	s_addc_u32 s1, s23, s1
	v_mov_b32_e32 v1, 1
	v_mov_b64_e32 v[4:5], s[0:1]
	global_atomic_add v1, v[4:5], v1, off sc0
	v_cvt_f32_u32_e32 v3, v2
	v_sub_u32_e32 v4, 0, v2
	v_rcp_iflag_f32_e32 v3, v3
	s_nop 0
	v_mul_f32_e32 v3, 0x4f7ffffe, v3
	v_cvt_u32_f32_e32 v3, v3
	v_mul_lo_u32 v4, v4, v3
	v_mul_hi_u32 v4, v3, v4
	v_add_u32_e32 v3, v3, v4
	s_waitcnt vmcnt(0) lgkmcnt(0)
	v_mul_hi_u32 v3, v1, v3
	v_mul_lo_u32 v5, v3, v2
	v_add_u32_e32 v4, 1, v1
	v_sub_u32_e32 v1, v1, v5
	v_add_u32_e32 v6, 1, v3
	v_cmp_ge_u32_e32 vcc, v1, v2
	v_sub_u32_e32 v5, v1, v2
	s_nop 0
	v_cndmask_b32_e32 v3, v3, v6, vcc
	v_cndmask_b32_e32 v1, v1, v5, vcc
	v_add_u32_e32 v5, 1, v3
	v_cmp_ge_u32_e32 vcc, v1, v2
	s_nop 1
	v_cndmask_b32_e32 v1, v3, v5, vcc
	v_mad_u64_u32 v[2:3], s[0:1], v2, v1, v[2:3]
	v_cmp_ne_u32_e32 vcc, v4, v2
	s_and_saveexec_b64 s[0:1], vcc
	s_xor_b64 s[0:1], exec, s[0:1]
	s_cbranch_execz .LBB0_115
	s_add_i32 s2, s24, 0x900
	s_lshl_b64 s[2:3], s[2:3], 2
	s_add_u32 s4, s22, s2
	s_addc_u32 s5, s23, s3
	v_mov_b64_e32 v[2:3], s[4:5]
	global_load_dword v0, v[2:3], off sc1
	s_waitcnt vmcnt(0) lgkmcnt(0)
	v_cmp_eq_u32_e32 vcc, v0, v1
	s_and_saveexec_b64 s[2:3], vcc
	s_cbranch_execz .LBB0_114
	s_add_u32 s6, s34, 0xe36d200
	s_addc_u32 s7, s35, 0
	s_mov_b32 s25, 1
	s_mov_b64 s[8:9], 0
	s_branch .LBB0_106

;   DI const float* x() const { return (const float*)sp[0]; }
; __device__ __forceinline__ unsigned xb_ld(unsigned* p)              { return __hip_atomic_load(p, __ATOMIC_RELAXED, __HIP_MEMORY_SCOPE_AGENT); }
; #define XB_SPIN(cond, bar) do { unsigned _sp = 0; while (cond) { __builtin_amdgcn_s_sleep(1); \
;     if ((++_sp & 255u) == 0u) { if (xb_ld(&(bar)[XB_TMO])) break; if (_sp > XB_SPIN_CAP) { atomicAdd(&(bar)[XB_TMO], 1u); break; } } } } while (0)
; __device__ __forceinline__ void xcd_barrier(const XcdBarrier& b) {
;     ...
;             XB_SPIN(xb_ld(&bar[XB_XGEN(b.x)]) == gen, bar);
.LBB0_106:
	s_and_b32 s16, s25, 0xff
	s_mov_b64 s[14:15], -1
	s_cmp_lg_u32 s16, 0
	s_mov_b64 s[16:17], -1
	s_sleep 1
	s_cbranch_scc1 .LBB0_110
	v_mov_b64_e32 v[2:3], s[6:7]
	global_load_dword v0, v[2:3], off sc1
	s_mov_b64 s[16:17], 0
	s_mov_b64 s[18:19], -1
	s_waitcnt vmcnt(0) lgkmcnt(0)
	v_cmp_eq_u32_e32 vcc, 0, v0
	s_and_saveexec_b64 s[20:21], vcc
	s_cmp_lt_u32 s25, 0x40001
	s_cselect_b64 s[16:17], -1, 0
	s_xor_b64 s[18:19], exec, -1
	s_and_b64 s[16:17], s[16:17], exec
	s_or_b64 exec, exec, s[20:21]
.LBB0_110:
	s_andn2_b64 s[12:13], s[12:13], exec
	s_and_b64 s[18:19], s[18:19], exec
	s_or_b64 s[12:13], s[12:13], s[18:19]
	s_and_saveexec_b64 s[18:19], s[16:17]
	s_cbranch_execz .LBB0_105
	v_mov_b64_e32 v[2:3], s[4:5]
	global_load_dword v0, v[2:3], off sc1
	s_add_i32 s25, s25, 1
	s_or_b64 s[12:13], s[12:13], exec
	s_waitcnt vmcnt(0) lgkmcnt(0)
	v_cmp_ne_u32_e32 vcc, v0, v1
	s_orn2_b64 s[14:15], vcc, exec
	s_branch .LBB0_105
.LBB0_112:
	s_or_b64 exec, exec, s[8:9]
	s_xor_b64 s[4:5], s[10:11], -1
	s_and_saveexec_b64 s[8:9], s[4:5]
	s_xor_b64 s[8:9], exec, s[8:9]
	s_cbranch_execz .LBB0_114
	v_mov_b32_e32 v2, 1
	v_mov_b64_e32 v[0:1], s[6:7]
	global_atomic_add v[0:1], v2, off

; __device__ __forceinline__ unsigned xb_ld(unsigned* p)              { return __hip_atomic_load(p, __ATOMIC_RELAXED, __HIP_MEMORY_SCOPE_AGENT); }
; __device__ __forceinline__ unsigned xb_add(unsigned* p, unsigned v) { return __hip_atomic_fetch_add(p, v, __ATOMIC_RELAXED, __HIP_MEMORY_SCOPE_AGENT); }
; #define XB_SPIN(cond, bar) do { unsigned _sp = 0; while (cond) { __builtin_amdgcn_s_sleep(1); \
;     if ((++_sp & 255u) == 0u) { if (xb_ld(&(bar)[XB_TMO])) break; if (_sp > XB_SPIN_CAP) { atomicAdd(&(bar)[XB_TMO], 1u); break; } } } } while (0)
; __device__ __forceinline__ void xcd_barrier(const XcdBarrier& b) {
;     ...
;         if (old + 1u == (gen + 1u) * nloc) {
;             __builtin_amdgcn_fence(__ATOMIC_RELEASE, "agent");
;             asm volatile("s_waitcnt vmcnt(0)" ::: "memory");
;             const unsigned og = xb_add(&bar[XB_TOP], 1u);
;             const unsigned tg = og / nx;
;             if (og + 1u == (tg + 1u) * nx) xb_add(&bar[XB_TOPGEN], 1u);
;             else XB_SPIN(xb_ld(&bar[XB_TOPGEN]) == tg, bar);
.LBB0_115:
	s_andn2_saveexec_b64 s[0:1], s[0:1]
	s_cbranch_execz .LBB0_131
	v_mov_b32_e32 v1, s34
	v_add_co_u32_e32 v2, vcc, 0xe370000, v1
	v_mov_b32_e32 v1, s35
	buffer_wbl2 sc1
	s_waitcnt vmcnt(0)
	v_addc_co_u32_e32 v3, vcc, 0, v1, vcc
	v_mov_b32_e32 v1, 1
	global_atomic_add v1, v[2:3], v1, off offset:1024 sc0
	v_cvt_f32_u32_e32 v2, v0
	v_sub_u32_e32 v3, 0, v0
	s_add_u32 s0, s34, 0xe370500
	s_addc_u32 s1, s35, 0
	v_rcp_iflag_f32_e32 v2, v2
	s_mov_b64 s[4:5], -1
	v_mul_f32_e32 v2, 0x4f7ffffe, v2
	v_cvt_u32_f32_e32 v2, v2
	v_mul_lo_u32 v3, v3, v2
	v_mul_hi_u32 v3, v2, v3
	v_add_u32_e32 v2, v2, v3
	s_waitcnt vmcnt(0) lgkmcnt(0)
	v_mul_hi_u32 v2, v1, v2
	v_mul_lo_u32 v4, v2, v0
	v_add_u32_e32 v3, 1, v1
	v_sub_u32_e32 v1, v1, v4
	v_add_u32_e32 v5, 1, v2
	v_cmp_ge_u32_e32 vcc, v1, v0
	v_sub_u32_e32 v4, v1, v0
	s_nop 0
	v_cndmask_b32_e32 v2, v2, v5, vcc
	v_cndmask_b32_e32 v1, v1, v4, vcc
	v_add_u32_e32 v4, 1, v2
	v_cmp_ge_u32_e32 vcc, v1, v0
	s_nop 1
	v_cndmask_b32_e32 v2, v2, v4, vcc
	v_mad_u64_u32 v[0:1], s[2:3], v0, v2, v[0:1]
	v_cmp_ne_u32_e32 vcc, v3, v0
	v_mov_b64_e32 v[0:1], s[0:1]
	s_and_saveexec_b64 s[2:3], vcc
	s_cbranch_execz .LBB0_128
	v_mov_b64_e32 v[0:1], s[0:1]
	global_load_dword v0, v[0:1], off sc1
	s_mov_b64 s[8:9], 0
	s_waitcnt vmcnt(0) lgkmcnt(0)
	v_cmp_eq_u32_e32 vcc, v0, v2
	s_and_saveexec_b64 s[6:7], vcc
	s_cbranch_execz .LBB0_127
	s_add_u32 s4, s34, 0xe36d200
	s_addc_u32 s5, s35, 0
	s_mov_b32 s20, 1
	s_branch .LBB0_120

; __device__ __forceinline__ unsigned xb_ld(unsigned* p)              { return __hip_atomic_load(p, __ATOMIC_RELAXED, __HIP_MEMORY_SCOPE_AGENT); }
; #define XB_SPIN(cond, bar) do { unsigned _sp = 0; while (cond) { __builtin_amdgcn_s_sleep(1); \
;     if ((++_sp & 255u) == 0u) { if (xb_ld(&(bar)[XB_TMO])) break; if (_sp > XB_SPIN_CAP) { atomicAdd(&(bar)[XB_TMO], 1u); break; } } } } while (0)
; __device__ __forceinline__ void xcd_barrier(const XcdBarrier& b) {
;     ...
;             else XB_SPIN(xb_ld(&bar[XB_TOPGEN]) == tg, bar);
.LBB0_122:
	v_mov_b64_e32 v[0:1], s[4:5]
	global_load_dword v0, v[0:1], off sc1
	s_mov_b64 s[14:15], 0
	s_mov_b64 s[12:13], -1
	s_waitcnt vmcnt(0) lgkmcnt(0)
	v_cmp_eq_u32_e32 vcc, 0, v0
	s_and_saveexec_b64 s[16:17], vcc
	s_cmp_lt_u32 s20, 0x40001
	s_cselect_b64 s[14:15], -1, 0
	s_xor_b64 s[12:13], exec, -1
	s_and_b64 s[14:15], s[14:15], exec
	s_or_b64 exec, exec, s[16:17]
	s_mov_b64 s[16:17], -1
	s_and_saveexec_b64 s[18:19], s[14:15]
	s_cbranch_execz .LBB0_119
.LBB0_125:
	v_mov_b64_e32 v[0:1], s[0:1]
	global_load_dword v0, v[0:1], off sc1
	s_add_i32 s20, s20, 1
	s_or_b64 s[12:13], s[12:13], exec
	s_waitcnt vmcnt(0) lgkmcnt(0)
	v_cmp_ne_u32_e32 vcc, v0, v2
	s_orn2_b64 s[16:17], vcc, exec
	s_branch .LBB0_119

;   DI const float* x() const { return (const float*)sp[0]; }
; __device__ __forceinline__ unsigned xb_ld(unsigned* p)              { return __hip_atomic_load(p, __ATOMIC_RELAXED, __HIP_MEMORY_SCOPE_AGENT); }
; __device__ __forceinline__ unsigned xb_add(unsigned* p, unsigned v) { return __hip_atomic_fetch_add(p, v, __ATOMIC_RELAXED, __HIP_MEMORY_SCOPE_AGENT); }
; #define XB_SPIN(cond, bar) do { unsigned _sp = 0; while (cond) { __builtin_amdgcn_s_sleep(1); \
;     if ((++_sp & 255u) == 0u) { if (xb_ld(&(bar)[XB_TMO])) break; if (_sp > XB_SPIN_CAP) { atomicAdd(&(bar)[XB_TMO], 1u); break; } } } } while (0)
; __device__ __forceinline__ void xcd_barrier(const XcdBarrier& b) {
;     ...
;             if (og + 1u == (tg + 1u) * nx) xb_add(&bar[XB_TOPGEN], 1u);
;             else XB_SPIN(xb_ld(&bar[XB_TOPGEN]) == tg, bar);
;             __builtin_amdgcn_fence(__ATOMIC_ACQUIRE, "agent");
;             xb_add(&bar[XB_XGEN(b.x)], 1u);
;             asm volatile("s_waitcnt vmcnt(0)" ::: "memory");
.LBB0_128:
	s_or_b64 exec, exec, s[2:3]
	s_and_saveexec_b64 s[0:1], s[4:5]
	s_cbranch_execz .LBB0_130
	v_mov_b32_e32 v2, 1
	global_atomic_add v[0:1], v2, off
.LBB0_130:
	s_or_b64 exec, exec, s[0:1]
	s_add_i32 s0, s24, 0x900
	s_mov_b32 s1, 0
	s_lshl_b64 s[0:1], s[0:1], 2
	s_add_u32 s0, s22, s0
	s_addc_u32 s1, s23, s1
	v_mov_b32_e32 v2, 1
	v_mov_b64_e32 v[0:1], s[0:1]
	s_waitcnt vmcnt(0) lgkmcnt(0)
	buffer_inv sc1
	global_atomic_add v[0:1], v2, off
	s_waitcnt vmcnt(0)

;   DI const float* x() const { return (const float*)sp[0]; }
;   DI const float* ctx() const { return (const float*)sp[2]; }
;   DI const float* ln_g() const { return (const float*)sp[6]; }
;   DI const float* ln_b() const { return (const float*)sp[7]; }
; DI unsigned cvtpk(float lo, float hi) { f32x2_t v = {lo, hi}; bf16x2_t b = __builtin_convertvector(v, bf16x2_t); return __builtin_bit_cast(unsigned, b); }
; DI void phase_mod(const Params& p, int g, int layer, char* smem) {
;     ...
;   for (int i = blockIdx.x * 4 + w; i < MG; i += gridDim.x * 4) {
;     const long r = (long)g * MG + i; const int b = (int)(r / T), t = (int)(r % T);
;     float v[32];
;     if (layer == 0) {
;       const float* s = t < CTX ? p.ctx() + ((long)b * CTX + t) * DM : p.x() + ((long)b * SEQ + (t - CTX)) * DM;
; #pragma unroll
;       for (int j = 0; j < 8; ++j) { const f32x4 a = *(const f32x4*)(s + lane * 4 + 256 * j); v[4 * j] = a[0]; v[4 * j + 1] = a[1]; v[4 * j + 2] = a[2]; v[4 * j + 3] = a[3]; }
;     } else {
;       float* s = P_ZX + r * DM;
; #pragma unroll
;       for (int j = 0; j < 8; ++j) { const f32x4 a = *(const f32x4*)(s + lane * 4 + 256 * j); v[4 * j] = a[0]; v[4 * j + 1] = a[1]; v[4 * j + 2] = a[2]; v[4 * j + 3] = a[3]; }
;       row_ln(v, p.ln_g(), p.ln_b(), lane);
; #pragma unroll
;       for (int j = 0; j < 8; ++j) { const f32x4 o = {v[4 * j], v[4 * j + 1], v[4 * j + 2], v[4 * j + 3]}; *(f32x4*)(s + lane * 4 + 256 * j) = o; }
;     }
;     const float* md = P_MOD + ((long)layer * 9 + (t < CTX ? 8 : b)) * 6144;
; #pragma unroll
;     for (int j = 0; j < 8; ++j) {
;       const f32x4 sh = *(const f32x4*)(md + lane * 4 + 256 * j), sc = *(const f32x4*)(md + 2048 + lane * 4 + 256 * j);
;       u32x2 o = {cvtpk(v[4 * j] * (1.f + sc[0]) + sh[0], v[4 * j + 1] * (1.f + sc[1]) + sh[1]), cvtpk(v[4 * j + 2] * (1.f + sc[2]) + sh[2], v[4 * j + 3] * (1.f + sc[3]) + sh[3])};
;       *reinterpret_cast<u32x2*>(h + (long)i * DM + lane * 4 + 256 * j) = o;
;     }
.LBB0_133:
	s_or_b64 exec, exec, s[0:1]
	ds_read_b64 v[12:13], v1
	v_lshlrev_b64 v[10:11], 13, v[10:11]
	v_lshl_add_u64 v[8:9], s[48:49], 0, v[8:9]
	v_lshl_add_u64 v[48:49], v[8:9], 0, v[6:7]
	v_ashrrev_i32_e32 v1, 31, v0
	s_waitcnt lgkmcnt(0)
	v_lshl_add_u64 v[8:9], v[12:13], 0, v[10:11]
	v_lshl_add_u64 v[32:33], v[8:9], 0, v[6:7]
	v_add_co_u32_e32 v50, vcc, 0x1000, v32
	s_mov_b64 s[0:1], vcc
	v_add_co_u32_e32 v20, vcc, 0x2000, v48
	v_lshl_add_u64 v[52:53], v[48:49], 0, s[6:7]
	s_nop 0
	v_addc_co_u32_e32 v21, vcc, 0, v49, vcc
	global_load_dwordx4 v[8:11], v[20:21], off
	global_load_dwordx4 v[12:15], v[48:49], off
	global_load_dwordx4 v[16:19], v[32:33], off
	v_lshlrev_b64 v[20:21], 12, v[0:1]
	v_lshl_add_u64 v[54:55], v[4:5], 0, v[20:21]
	v_addc_co_u32_e64 v51, vcc, 0, v33, s[0:1]
	global_load_dwordx4 v[20:23], v[32:33], off offset:1024
	global_load_dwordx4 v[24:27], v[32:33], off offset:2048
	global_load_dwordx4 v[28:31], v[32:33], off offset:3072
	s_nop 0
	global_load_dwordx4 v[32:35], v[50:51], off
	global_load_dwordx4 v[36:39], v[50:51], off offset:1024
	global_load_dwordx4 v[40:43], v[50:51], off offset:2048
	global_load_dwordx4 v[44:47], v[50:51], off offset:3072
	v_add_u32_e32 v0, s8, v0
	s_waitcnt vmcnt(0)
	v_pk_add_f32 v[8:9], v[8:9], 1.0 op_sel_hi:[1,0]
	v_pk_add_f32 v[10:11], v[10:11], 1.0 op_sel_hi:[1,0]
	s_waitcnt lgkmcnt(0)
	v_pk_fma_f32 v[8:9], v[16:17], v[8:9], v[12:13]
	v_pk_fma_f32 v[10:11], v[18:19], v[10:11], v[14:15]
	v_cvt_pk_bf16_f32 v8, v8, v9
	v_cvt_pk_bf16_f32 v9, v10, v11
	global_store_dwordx2 v[54:55], v[8:9], off
	global_load_dwordx4 v[8:11], v[52:53], off offset:1024
	s_nop 0
	global_load_dwordx4 v[12:15], v[48:49], off offset:1024
	v_add_co_u32_e32 v16, vcc, s12, v48
	s_waitcnt vmcnt(0)
	v_pk_add_f32 v[8:9], v[8:9], 1.0 op_sel_hi:[1,0]
	v_pk_add_f32 v[10:11], v[10:11], 1.0 op_sel_hi:[1,0]
	v_pk_fma_f32 v[8:9], v[20:21], v[8:9], v[12:13]
	v_pk_fma_f32 v[10:11], v[22:23], v[10:11], v[14:15]
	v_cvt_pk_bf16_f32 v8, v8, v9
	v_cvt_pk_bf16_f32 v9, v10, v11
	global_store_dwordx2 v[54:55], v[8:9], off offset:512
	global_load_dwordx4 v[8:11], v[52:53], off offset:2048
	s_nop 0
	global_load_dwordx4 v[12:15], v[48:49], off offset:2048
	v_addc_co_u32_e32 v17, vcc, 0, v49, vcc
	v_add_co_u32_e32 v18, vcc, s11, v48
	s_waitcnt vmcnt(0)
	v_pk_add_f32 v[8:9], v[8:9], 1.0 op_sel_hi:[1,0]
	v_pk_add_f32 v[10:11], v[10:11], 1.0 op_sel_hi:[1,0]
	v_pk_fma_f32 v[8:9], v[24:25], v[8:9], v[12:13]
	v_pk_fma_f32 v[10:11], v[26:27], v[10:11], v[14:15]
	v_cvt_pk_bf16_f32 v8, v8, v9
	v_cvt_pk_bf16_f32 v9, v10, v11
	global_store_dwordx2 v[54:55], v[8:9], off offset:1024
	global_load_dwordx4 v[8:11], v[52:53], off offset:3072
	s_nop 0
	global_load_dwordx4 v[12:15], v[48:49], off offset:3072
	v_addc_co_u32_e32 v19, vcc, 0, v49, vcc
	v_cmp_lt_i32_e32 vcc, s13, v0
	s_or_b64 s[4:5], vcc, s[4:5]
	s_waitcnt vmcnt(0)
	v_pk_add_f32 v[8:9], v[8:9], 1.0 op_sel_hi:[1,0]
	v_pk_add_f32 v[10:11], v[10:11], 1.0 op_sel_hi:[1,0]
	v_pk_fma_f32 v[8:9], v[28:29], v[8:9], v[12:13]
	v_pk_fma_f32 v[10:11], v[30:31], v[10:11], v[14:15]
	v_cvt_pk_bf16_f32 v8, v8, v9
	v_cvt_pk_bf16_f32 v9, v10, v11
	global_store_dwordx2 v[54:55], v[8:9], off offset:1536
	global_load_dwordx4 v[8:11], v[16:17], off
	s_nop 0
	global_load_dwordx4 v[12:15], v[18:19], off
	s_waitcnt vmcnt(0)
	v_pk_add_f32 v[8:9], v[8:9], 1.0 op_sel_hi:[1,0]
	v_pk_add_f32 v[10:11], v[10:11], 1.0 op_sel_hi:[1,0]
	v_pk_fma_f32 v[8:9], v[32:33], v[8:9], v[12:13]
	v_pk_fma_f32 v[10:11], v[34:35], v[10:11], v[14:15]
	v_cvt_pk_bf16_f32 v8, v8, v9
	v_cvt_pk_bf16_f32 v9, v10, v11
	global_store_dwordx2 v[54:55], v[8:9], off offset:2048
	global_load_dwordx4 v[8:11], v[16:17], off offset:1024
	s_nop 0
	global_load_dwordx4 v[12:15], v[18:19], off offset:1024
	s_waitcnt vmcnt(0)
	v_pk_add_f32 v[8:9], v[8:9], 1.0 op_sel_hi:[1,0]
	v_pk_add_f32 v[10:11], v[10:11], 1.0 op_sel_hi:[1,0]
	v_pk_fma_f32 v[8:9], v[36:37], v[8:9], v[12:13]
	v_pk_fma_f32 v[10:11], v[38:39], v[10:11], v[14:15]
	v_cvt_pk_bf16_f32 v8, v8, v9
	v_cvt_pk_bf16_f32 v9, v10, v11
	global_store_dwordx2 v[54:55], v[8:9], off offset:2560
	global_load_dwordx4 v[8:11], v[16:17], off offset:2048
	s_nop 0
	global_load_dwordx4 v[12:15], v[18:19], off offset:2048
	s_waitcnt vmcnt(0)
	v_pk_add_f32 v[8:9], v[8:9], 1.0 op_sel_hi:[1,0]
	v_pk_add_f32 v[10:11], v[10:11], 1.0 op_sel_hi:[1,0]
	v_pk_fma_f32 v[8:9], v[40:41], v[8:9], v[12:13]
	v_pk_fma_f32 v[10:11], v[42:43], v[10:11], v[14:15]
	v_cvt_pk_bf16_f32 v8, v8, v9
	v_cvt_pk_bf16_f32 v9, v10, v11
	global_store_dwordx2 v[54:55], v[8:9], off offset:3072
	global_load_dwordx4 v[8:11], v[16:17], off offset:3072
	s_nop 0
	global_load_dwordx4 v[12:15], v[18:19], off offset:3072
	s_waitcnt vmcnt(0)
	v_pk_add_f32 v[8:9], v[8:9], 1.0 op_sel_hi:[1,0]
	v_pk_add_f32 v[10:11], v[10:11], 1.0 op_sel_hi:[1,0]
	v_pk_fma_f32 v[8:9], v[44:45], v[8:9], v[12:13]
	v_pk_fma_f32 v[10:11], v[46:47], v[10:11], v[14:15]
	v_cvt_pk_bf16_f32 v8, v8, v9
	v_cvt_pk_bf16_f32 v9, v10, v11
	global_store_dwordx2 v[54:55], v[8:9], off offset:3584
	s_andn2_b64 exec, exec, s[4:5]
	s_cbranch_execz .LBB0_138

; DI int TID() { int t = threadIdx.x; asm volatile("" : "+v"(t)); return t; }
; DI void gemm_preload(const bfu* __restrict__ A, const bfu* __restrict__ Bt, int K, int kt, bf16x8 (&ra)[4], bf16x8 (&rb)[8]) {
;   const int tid = TID(), sr = tid >> 3, sc = (tid & 7) * 8;
;   const bfu* Ag = A + (long)sr * K + sc + kt * BK; const bfu* Bg = Bt + (long)sr * K + sc + kt * BK;
; #pragma unroll
;   for (int i = 0; i < 4; ++i) ra[i] = ld8(Ag + (long)(32 * i) * K);
; #pragma unroll
;   for (int i = 0; i < 8; ++i) rb[i] = ld8(Bg + (long)(32 * i) * K);
; }
.LBB0_190:
	v_mov_b32_e32 v4, v202
	v_mov_b32_e32 v5, 0
	v_ashrrev_i32_e32 v0, 3, v4
	v_ashrrev_i32_e32 v1, 31, v0
	v_lshlrev_b64 v[0:1], 12, v[0:1]
	v_lshlrev_b32_e32 v4, 4, v4
	v_lshl_add_u64 v[2:3], s[36:37], 0, v[0:1]
	v_and_b32_e32 v4, 0x70, v4
	v_lshl_add_u64 v[2:3], v[2:3], 0, v[4:5]
	v_lshl_add_u64 v[0:1], s[38:39], 0, v[0:1]
	s_mov_b32 s4, 0x20000
	v_lshl_add_u64 v[0:1], v[0:1], 0, v[4:5]
	v_add_co_u32_e32 v4, vcc, s4, v2
	s_mov_b32 s5, 0x40000
	s_nop 0
	v_addc_co_u32_e32 v5, vcc, 0, v3, vcc
	v_add_co_u32_e32 v6, vcc, s5, v2
	s_mov_b32 s6, 0x60000
	s_nop 0
	v_addc_co_u32_e32 v7, vcc, 0, v3, vcc
	global_load_dwordx4 v[128:131], v[2:3], off
	v_add_co_u32_e32 v2, vcc, s6, v2
	global_load_dwordx4 v[132:135], v[4:5], off
	global_load_dwordx4 v[136:139], v[6:7], off
	v_addc_co_u32_e32 v3, vcc, 0, v3, vcc
	global_load_dwordx4 v[140:143], v[2:3], off
	global_load_dwordx4 v[144:147], v[0:1], off
	v_add_co_u32_e32 v2, vcc, s4, v0
	s_mov_b32 s4, 0x80000
	s_nop 0
	v_addc_co_u32_e32 v3, vcc, 0, v1, vcc
	v_add_co_u32_e32 v4, vcc, s5, v0
	s_nop 1
	v_addc_co_u32_e32 v5, vcc, 0, v1, vcc
	global_load_dwordx4 v[148:151], v[2:3], off
	global_load_dwordx4 v[152:155], v[4:5], off
	v_add_co_u32_e32 v2, vcc, s6, v0
	s_nop 1
	v_addc_co_u32_e32 v3, vcc, 0, v1, vcc
	v_add_co_u32_e32 v4, vcc, s4, v0
	s_mov_b32 s4, 0xa0000
	s_nop 0
	v_addc_co_u32_e32 v5, vcc, 0, v1, vcc
	global_load_dwordx4 v[156:159], v[2:3], off
	global_load_dwordx4 v[160:163], v[4:5], off
	v_add_co_u32_e32 v2, vcc, s4, v0
	s_nop 1
	v_addc_co_u32_e32 v3, vcc, 0, v1, vcc
	v_add_co_u32_e32 v4, vcc, 0xc0000, v0
	s_nop 1
	v_addc_co_u32_e32 v5, vcc, 0, v1, vcc
	v_add_co_u32_e32 v0, vcc, 0xe0000, v0
	global_load_dwordx4 v[164:167], v[2:3], off
	global_load_dwordx4 v[168:171], v[4:5], off
	v_addc_co_u32_e32 v1, vcc, 0, v1, vcc
	global_load_dwordx4 v[172:175], v[0:1], off

; #define MFMA(a, b, c) __builtin_amdgcn_mfma_f32_32x32x16_bf16((a), (b), (c), 0, 0, 0)
; DI int TID() { int t = threadIdx.x; asm volatile("" : "+v"(t)); return t; }
; DI void gemm_preload(const bfu* __restrict__ A, const bfu* __restrict__ Bt, int K, int kt, bf16x8 (&ra)[4], bf16x8 (&rb)[8]) {
;   const int tid = TID(), sr = tid >> 3, sc = (tid & 7) * 8;
;   const bfu* Ag = A + (long)sr * K + sc + kt * BK; const bfu* Bg = Bt + (long)sr * K + sc + kt * BK;
; #pragma unroll
;   for (int i = 0; i < 4; ++i) ra[i] = ld8(Ag + (long)(32 * i) * K);
; #pragma unroll
;   for (int i = 0; i < 8; ++i) rb[i] = ld8(Bg + (long)(32 * i) * K);
; }
; DI void gemm_main2(const bfu* __restrict__ A, const bfu* __restrict__ Bt, int K, char* smem, f32x16 (&acc)[2][4], bf16x8 (&ra)[4], bf16x8 (&rb)[8]) {
;     ...
;   for (int kt = 0; kt < nk; ++kt) {
;     __syncthreads();
; #pragma unroll
;     for (int i = 0; i < 4; ++i) st8(As + (sr + 32 * i) * LDT + sc, ra[i]);
; #pragma unroll
;     for (int i = 0; i < 8; ++i) st8(Bs + (sr + 32 * i) * LDT + sc, rb[i]);
;     __syncthreads();
;     if (kt + 1 < nk) gemm_preload(A, Bt, K, kt + 1, ra, rb);
; #pragma unroll
;     for (int ks = 0; ks < 4; ++ks) {
;       const bf16x8 a0 = ld8(as + ks * 16), a1 = ld8(as + 32 * LDT + ks * 16);
; #pragma unroll
;       for (int j = 0; j < 4; ++j) {
;         const bf16x8 b = ld8(bs + j * 32 * LDT + ks * 16);
;         acc[0][j] = MFMA(a0, b, acc[0][j]); acc[1][j] = MFMA(a1, b, acc[1][j]);
;       }
;     }
;   }
.LBB0_196:
	s_waitcnt lgkmcnt(0)
	s_barrier
	s_waitcnt vmcnt(0)
	ds_write_b128 v179, v[128:131]
	ds_write_b128 v179, v[132:135] offset:4608
	ds_write_b128 v179, v[136:139] offset:9216
	ds_write_b128 v179, v[140:143] offset:13824
	ds_write_b128 v179, v[144:147] offset:18432
	ds_write_b128 v179, v[148:151] offset:23040
	ds_write_b128 v179, v[152:155] offset:27648
	ds_write_b128 v179, v[156:159] offset:32256
	ds_write_b128 v179, v[160:163] offset:36864
	ds_write_b128 v179, v[164:167] offset:41472
	ds_write_b128 v179, v[168:171] offset:46080
	ds_write_b128 v179, v[172:175] offset:50688
	v_mov_b32_e32 v164, v202
	s_waitcnt lgkmcnt(0)
	s_barrier
	ds_read_b128 v[128:131], v178
	ds_read_b128 v[132:135], v176 offset:18432
	ds_read_b128 v[136:139], v178 offset:32
	ds_read_b128 v[140:143], v176 offset:18464
	ds_read_b128 v[144:147], v178 offset:4608
	ds_read_b128 v[148:151], v178 offset:4640
	s_waitcnt lgkmcnt(4)
	v_mfma_f32_32x32x16_bf16 v[112:127], v[128:131], v[132:135], v[112:127]
	s_mov_b32 s1, 0x80000
	s_waitcnt lgkmcnt(1)
	v_mfma_f32_32x32x16_bf16 v[48:63], v[144:147], v[132:135], v[48:63]
	ds_read_b128 v[132:135], v176 offset:23040
	ds_read_b128 v[152:155], v176 offset:23072
	s_waitcnt lgkmcnt(1)
	v_mfma_f32_32x32x16_bf16 v[96:111], v[128:131], v[132:135], v[96:111]
	v_mfma_f32_32x32x16_bf16 v[32:47], v[144:147], v[132:135], v[32:47]
	ds_read_b128 v[132:135], v176 offset:27648
	ds_read_b128 v[156:159], v176 offset:27680
	s_waitcnt lgkmcnt(1)
	v_mfma_f32_32x32x16_bf16 v[80:95], v[128:131], v[132:135], v[80:95]
	v_mfma_f32_32x32x16_bf16 v[16:31], v[144:147], v[132:135], v[16:31]
	ds_read_b128 v[132:135], v176 offset:32256
	ds_read_b128 v[160:163], v176 offset:32288
	s_waitcnt lgkmcnt(1)
	v_mfma_f32_32x32x16_bf16 v[64:79], v[128:131], v[132:135], v[64:79]
	v_mfma_f32_32x32x16_bf16 v[112:127], v[136:139], v[140:143], v[112:127]
	v_mfma_f32_32x32x16_bf16 v[48:63], v[148:151], v[140:143], v[48:63]
	v_mfma_f32_32x32x16_bf16 v[0:15], v[144:147], v[132:135], v[0:15]
	ds_read_b128 v[128:131], v178 offset:64
	ds_read_b128 v[132:135], v176 offset:18496
	ds_read_b128 v[168:171], v178 offset:96
	ds_read_b128 v[144:147], v176 offset:18528
	v_mfma_f32_32x32x16_bf16 v[96:111], v[136:139], v[152:155], v[96:111]
	v_mfma_f32_32x32x16_bf16 v[32:47], v[148:151], v[152:155], v[32:47]
	v_mfma_f32_32x32x16_bf16 v[80:95], v[136:139], v[156:159], v[80:95]
	s_waitcnt lgkmcnt(4)
	v_mfma_f32_32x32x16_bf16 v[64:79], v[136:139], v[160:163], v[64:79]
	ds_read_b128 v[136:139], v178 offset:4672
	ds_read_b128 v[194:197], v178 offset:4704
	v_mfma_f32_32x32x16_bf16 v[16:31], v[148:151], v[156:159], v[16:31]
	s_waitcnt lgkmcnt(4)
	v_mfma_f32_32x32x16_bf16 v[112:127], v[128:131], v[132:135], v[112:127]
	s_waitcnt lgkmcnt(1)
	v_mfma_f32_32x32x16_bf16 v[48:63], v[136:139], v[132:135], v[48:63]
	ds_read_b128 v[132:135], v176 offset:23104
	ds_read_b128 v[152:155], v176 offset:23136
	s_waitcnt lgkmcnt(1)
	v_mfma_f32_32x32x16_bf16 v[96:111], v[128:131], v[132:135], v[96:111]
	v_mfma_f32_32x32x16_bf16 v[32:47], v[136:139], v[132:135], v[32:47]
	ds_read_b128 v[132:135], v176 offset:27712
	ds_read_b128 v[172:175], v176 offset:27744
	s_waitcnt lgkmcnt(1)
	v_mfma_f32_32x32x16_bf16 v[80:95], v[128:131], v[132:135], v[80:95]
	v_mfma_f32_32x32x16_bf16 v[16:31], v[136:139], v[132:135], v[16:31]
	ds_read_b128 v[132:135], v176 offset:32320
	ds_read_b128 v[198:201], v176 offset:32352
	v_mfma_f32_32x32x16_bf16 v[0:15], v[148:151], v[160:163], v[0:15]
	s_waitcnt lgkmcnt(1)
	v_mfma_f32_32x32x16_bf16 v[64:79], v[128:131], v[132:135], v[64:79]
	v_ashrrev_i32_e32 v128, 3, v164
	v_ashrrev_i32_e32 v129, 31, v128
	v_lshlrev_b64 v[128:129], 12, v[128:129]
	v_and_b32_e32 v130, 7, v164
	v_lshl_or_b32 v128, v130, 4, v128
	v_lshl_add_u64 v[148:149], s[2:3], 0, v[128:129]
	v_lshl_add_u64 v[180:181], s[38:39], 0, v[148:149]
	v_mfma_f32_32x32x16_bf16 v[0:15], v[136:139], v[132:135], v[0:15]
	v_lshl_add_u64 v[136:137], s[36:37], 0, v[148:149]
	v_add_co_u32_e32 v132, vcc, s82, v136
	s_add_u32 s2, s2, 0x80
	s_nop 0
	v_addc_co_u32_e32 v133, vcc, 0, v137, vcc
	v_add_co_u32_e32 v138, vcc, s83, v136
	v_mfma_f32_32x32x16_bf16 v[80:95], v[168:171], v[172:175], v[80:95]
	s_nop 0
	v_addc_co_u32_e32 v139, vcc, 0, v137, vcc
	v_add_co_u32_e32 v140, vcc, s86, v136
	global_load_dwordx4 v[128:131], v[136:137], off offset:128
	s_nop 0
	global_load_dwordx4 v[132:135], v[132:133], off offset:128
	v_addc_co_u32_e32 v141, vcc, 0, v137, vcc
	v_add_co_u32_e32 v148, vcc, s82, v180
	v_mfma_f32_32x32x16_bf16 v[16:31], v[194:197], v[172:175], v[16:31]
	s_nop 0
	v_addc_co_u32_e32 v149, vcc, 0, v181, vcc
	v_add_co_u32_e32 v156, vcc, s83, v180
	global_load_dwordx4 v[136:139], v[138:139], off offset:128
	s_nop 0
	global_load_dwordx4 v[140:143], v[140:141], off offset:128
	v_addc_co_u32_e32 v157, vcc, 0, v181, vcc
	v_add_co_u32_e32 v158, vcc, s86, v180
	v_mfma_f32_32x32x16_bf16 v[112:127], v[168:171], v[144:147], v[112:127]
	s_nop 0
	v_addc_co_u32_e32 v159, vcc, 0, v181, vcc
	v_add_co_u32_e32 v160, vcc, s1, v180
	s_mov_b32 s1, 0xa0000
	s_nop 0
	v_addc_co_u32_e32 v161, vcc, 0, v181, vcc
	v_add_co_u32_e32 v164, vcc, s1, v180
	s_mov_b32 s1, 0xc0000
	s_nop 0
	v_addc_co_u32_e32 v165, vcc, 0, v181, vcc
	v_add_co_u32_e32 v172, vcc, s1, v180
	s_mov_b32 s1, 0xe0000
	s_nop 0
	v_addc_co_u32_e32 v173, vcc, 0, v181, vcc
	v_add_co_u32_e32 v174, vcc, s1, v180
	v_mfma_f32_32x32x16_bf16 v[48:63], v[194:197], v[144:147], v[48:63]
	s_nop 0
	v_addc_co_u32_e32 v175, vcc, 0, v181, vcc
	global_load_dwordx4 v[144:147], v[180:181], off offset:128
	s_nop 0
	global_load_dwordx4 v[148:151], v[148:149], off offset:128
	s_addc_u32 s3, s3, 0
	s_cmpk_lg_i32 s2, 0xf80
	v_mfma_f32_32x32x16_bf16 v[96:111], v[168:171], v[152:155], v[96:111]
	v_mfma_f32_32x32x16_bf16 v[32:47], v[194:197], v[152:155], v[32:47]
	global_load_dwordx4 v[152:155], v[156:157], off offset:128
	s_nop 0
	global_load_dwordx4 v[156:159], v[158:159], off offset:128
	s_nop 0
	global_load_dwordx4 v[160:163], v[160:161], off offset:128
	s_nop 0
	global_load_dwordx4 v[164:167], v[164:165], off offset:128
	s_waitcnt lgkmcnt(0)
	v_mfma_f32_32x32x16_bf16 v[64:79], v[168:171], v[198:201], v[64:79]
	global_load_dwordx4 v[168:171], v[172:173], off offset:128
	s_nop 0
	global_load_dwordx4 v[172:175], v[174:175], off offset:128
	v_mfma_f32_32x32x16_bf16 v[0:15], v[194:197], v[198:201], v[0:15]
	s_cbranch_scc1 .LBB0_196
; #define MFMA(a, b, c) __builtin_amdgcn_mfma_f32_32x32x16_bf16((a), (b), (c), 0, 0, 0)
; DI int TID() { int t = threadIdx.x; asm volatile("" : "+v"(t)); return t; }
; DI void gemm_main2(const bfu* __restrict__ A, const bfu* __restrict__ Bt, int K, char* smem, f32x16 (&acc)[2][4], bf16x8 (&ra)[4], bf16x8 (&rb)[8]) {
;     ...
;   for (int kt = 0; kt < nk; ++kt) {
;     __syncthreads();
; #pragma unroll
;     for (int i = 0; i < 4; ++i) st8(As + (sr + 32 * i) * LDT + sc, ra[i]);
; #pragma unroll
;     for (int i = 0; i < 8; ++i) st8(Bs + (sr + 32 * i) * LDT + sc, rb[i]);
;     __syncthreads();
;     if (kt + 1 < nk) gemm_preload(A, Bt, K, kt + 1, ra, rb);
; #pragma unroll
;     for (int ks = 0; ks < 4; ++ks) {
;       const bf16x8 a0 = ld8(as + ks * 16), a1 = ld8(as + 32 * LDT + ks * 16);
; #pragma unroll
;       for (int j = 0; j < 4; ++j) {
;         const bf16x8 b = ld8(bs + j * 32 * LDT + ks * 16);
;         acc[0][j] = MFMA(a0, b, acc[0][j]); acc[1][j] = MFMA(a1, b, acc[1][j]);
;       }
;     }
;   }
; DI void phase_gemm(const Params& p, int g, int kind, char* smem, float* rsl, int* s_item, int vlo, int vhi, int cslot) {
;     ...
;       __syncthreads();
;       if (TID() == 0) *s_item = atomicAdd(qctr, 1);
	s_barrier
	s_waitcnt vmcnt(0)
	ds_write_b128 v179, v[128:131]
	ds_write_b128 v179, v[132:135] offset:4608
	ds_write_b128 v179, v[136:139] offset:9216
	ds_write_b128 v179, v[140:143] offset:13824
	ds_write_b128 v179, v[144:147] offset:18432
	ds_write_b128 v179, v[148:151] offset:23040
	ds_write_b128 v179, v[152:155] offset:27648
	ds_write_b128 v179, v[156:159] offset:32256
	ds_write_b128 v179, v[160:163] offset:36864
	ds_write_b128 v179, v[164:167] offset:41472
	ds_write_b128 v179, v[168:171] offset:46080
	ds_write_b128 v179, v[172:175] offset:50688
	s_waitcnt lgkmcnt(0)
	s_barrier
	ds_read_b128 v[194:197], v178
	ds_read_b128 v[198:201], v176 offset:18432
	ds_read_b128 v[204:207], v178 offset:32
	ds_read_b128 v[208:211], v176 offset:18464
	ds_read_b128 v[212:215], v178 offset:4608
	ds_read_b128 v[216:219], v178 offset:4640
	s_waitcnt lgkmcnt(4)
	v_mfma_f32_32x32x16_bf16 v[112:127], v[194:197], v[198:201], v[112:127]
	s_waitcnt lgkmcnt(1)
	v_mfma_f32_32x32x16_bf16 v[48:63], v[212:215], v[198:201], v[48:63]
	ds_read_b128 v[198:201], v176 offset:23040
	ds_read_b128 v[220:223], v176 offset:23072
	s_waitcnt lgkmcnt(1)
	v_mfma_f32_32x32x16_bf16 v[96:111], v[194:197], v[198:201], v[96:111]
	v_mfma_f32_32x32x16_bf16 v[32:47], v[212:215], v[198:201], v[32:47]
	ds_read_b128 v[198:201], v176 offset:27648
	ds_read_b128 v[224:227], v176 offset:27680
	s_waitcnt lgkmcnt(1)
	v_mfma_f32_32x32x16_bf16 v[80:95], v[194:197], v[198:201], v[80:95]
	v_mfma_f32_32x32x16_bf16 v[16:31], v[212:215], v[198:201], v[16:31]
	ds_read_b128 v[198:201], v176 offset:32256
	ds_read_b128 v[228:231], v176 offset:32288
	s_waitcnt lgkmcnt(1)
	v_mfma_f32_32x32x16_bf16 v[64:79], v[194:197], v[198:201], v[64:79]
	v_mfma_f32_32x32x16_bf16 v[0:15], v[212:215], v[198:201], v[0:15]
	v_mfma_f32_32x32x16_bf16 v[112:127], v[204:207], v[208:211], v[112:127]
	v_mfma_f32_32x32x16_bf16 v[48:63], v[216:219], v[208:211], v[48:63]
	v_mfma_f32_32x32x16_bf16 v[96:111], v[204:207], v[220:223], v[96:111]
	v_mfma_f32_32x32x16_bf16 v[32:47], v[216:219], v[220:223], v[32:47]
	v_mfma_f32_32x32x16_bf16 v[80:95], v[204:207], v[224:227], v[80:95]
	s_waitcnt lgkmcnt(0)
	v_mfma_f32_32x32x16_bf16 v[64:79], v[204:207], v[228:231], v[64:79]
	ds_read_b128 v[194:197], v178 offset:64
	ds_read_b128 v[198:201], v176 offset:18496
	ds_read_b128 v[204:207], v178 offset:96
	ds_read_b128 v[208:211], v176 offset:18528
	ds_read_b128 v[212:215], v178 offset:4672
	ds_read_b128 v[178:181], v178 offset:4704
	v_mfma_f32_32x32x16_bf16 v[16:31], v[216:219], v[224:227], v[16:31]
	v_mfma_f32_32x32x16_bf16 v[0:15], v[216:219], v[228:231], v[0:15]
	s_waitcnt lgkmcnt(4)
	v_mfma_f32_32x32x16_bf16 v[112:127], v[194:197], v[198:201], v[112:127]
	s_waitcnt lgkmcnt(1)
	v_mfma_f32_32x32x16_bf16 v[48:63], v[212:215], v[198:201], v[48:63]
	ds_read_b128 v[198:201], v176 offset:23104
	ds_read_b128 v[216:219], v176 offset:23136
	s_waitcnt lgkmcnt(1)
	v_mfma_f32_32x32x16_bf16 v[96:111], v[194:197], v[198:201], v[96:111]
	v_mfma_f32_32x32x16_bf16 v[32:47], v[212:215], v[198:201], v[32:47]
	ds_read_b128 v[198:201], v176 offset:27712
	ds_read_b128 v[220:223], v176 offset:27744
	s_waitcnt lgkmcnt(1)
	v_mfma_f32_32x32x16_bf16 v[80:95], v[194:197], v[198:201], v[80:95]
	v_mfma_f32_32x32x16_bf16 v[16:31], v[212:215], v[198:201], v[16:31]
	ds_read_b128 v[198:201], v176 offset:32320
	ds_read_b128 v[224:227], v176 offset:32352
	v_mov_b32_e32 v176, v202
	s_waitcnt lgkmcnt(0)
	s_barrier
	v_mfma_f32_32x32x16_bf16 v[64:79], v[194:197], v[198:201], v[64:79]
	v_cmp_eq_u32_e32 vcc, 0, v176
	v_mfma_f32_32x32x16_bf16 v[0:15], v[212:215], v[198:201], v[0:15]
	v_mfma_f32_32x32x16_bf16 v[112:127], v[204:207], v[208:211], v[112:127]
	v_mfma_f32_32x32x16_bf16 v[48:63], v[178:181], v[208:211], v[48:63]
	v_mfma_f32_32x32x16_bf16 v[96:111], v[204:207], v[216:219], v[96:111]
	v_mfma_f32_32x32x16_bf16 v[32:47], v[178:181], v[216:219], v[32:47]
	v_mfma_f32_32x32x16_bf16 v[80:95], v[204:207], v[220:223], v[80:95]
	v_mfma_f32_32x32x16_bf16 v[16:31], v[178:181], v[220:223], v[16:31]
	v_mfma_f32_32x32x16_bf16 v[64:79], v[204:207], v[224:227], v[64:79]
	v_mfma_f32_32x32x16_bf16 v[0:15], v[178:181], v[224:227], v[0:15]
	s_and_saveexec_b64 s[2:3], vcc
	s_cbranch_execz .LBB0_201
	s_mov_b64 s[6:7], exec
	v_mbcnt_lo_u32_b32 v176, s6, 0
	v_mbcnt_hi_u32_b32 v176, s7, v176
	v_cmp_eq_u32_e32 vcc, 0, v176
	s_and_saveexec_b64 s[4:5], vcc
	s_cbranch_execz .LBB0_200
	s_bcnt1_i32_b64 s1, s[6:7]
	v_readlane_b32 s6, v254, 19
	v_mov_b32_e32 v178, s1
	v_readlane_b32 s7, v254, 20
	s_nop 4
	global_atomic_add v178, v177, v178, s[6:7] sc0

; DI int TID() { int t = threadIdx.x; asm volatile("" : "+v"(t)); return t; }
; DI void gemm_preload(const bfu* __restrict__ A, const bfu* __restrict__ Bt, int K, int kt, bf16x8 (&ra)[4], bf16x8 (&rb)[8]) {
;   const int tid = TID(), sr = tid >> 3, sc = (tid & 7) * 8;
;   const bfu* Ag = A + (long)sr * K + sc + kt * BK; const bfu* Bg = Bt + (long)sr * K + sc + kt * BK;
; #pragma unroll
;   for (int i = 0; i < 4; ++i) ra[i] = ld8(Ag + (long)(32 * i) * K);
; #pragma unroll
;   for (int i = 0; i < 8; ++i) rb[i] = ld8(Bg + (long)(32 * i) * K);
; }
; DI void phase_gemm(const Params& p, int g, int kind, char* smem, float* rsl, int* s_item, int vlo, int vhi, int cslot) {
;     ...
;     TD nxt; fetch(nxt);
;     if (nxt.ok) gemm_preload(nxt.A, nxt.Bt, nxt.K, 0, ra, rb);
.LBB0_203:
	s_andn2_b64 vcc, exec, s[2:3]
	s_cbranch_vccnz .LBB0_205
	v_mov_b32_e32 v132, v202
	s_nop 0
	v_ashrrev_i32_e32 v128, 3, v132
	v_ashrrev_i32_e32 v129, 31, v128
	v_lshlrev_b64 v[128:129], 12, v[128:129]
	v_lshlrev_b32_e32 v132, 4, v132
	v_lshl_add_u64 v[130:131], s[36:37], 0, v[128:129]
	v_and_b32_e32 v176, 0x70, v132
	v_lshl_add_u64 v[140:141], v[130:131], 0, v[176:177]
	v_add_co_u32_e32 v132, vcc, 0x20000, v140
	v_lshl_add_u64 v[128:129], s[38:39], 0, v[128:129]
	s_nop 0
	v_addc_co_u32_e32 v133, vcc, 0, v141, vcc
	v_add_co_u32_e32 v136, vcc, 0x40000, v140
	v_lshl_add_u64 v[172:173], v[128:129], 0, v[176:177]
	s_nop 0
	v_addc_co_u32_e32 v137, vcc, 0, v141, vcc
	global_load_dwordx4 v[128:131], v[140:141], off
	v_add_co_u32_e32 v140, vcc, 0x60000, v140
	global_load_dwordx4 v[132:135], v[132:133], off
	s_nop 0
	global_load_dwordx4 v[136:139], v[136:137], off
	v_addc_co_u32_e32 v141, vcc, 0, v141, vcc
	v_add_co_u32_e32 v148, vcc, s82, v172
	global_load_dwordx4 v[140:143], v[140:141], off
	s_nop 0
	global_load_dwordx4 v[144:147], v[172:173], off
	v_addc_co_u32_e32 v149, vcc, 0, v173, vcc
	v_add_co_u32_e32 v152, vcc, 0x40000, v172
	s_nop 1
	v_addc_co_u32_e32 v153, vcc, 0, v173, vcc
	v_add_co_u32_e32 v156, vcc, 0x60000, v172
	global_load_dwordx4 v[148:151], v[148:149], off
	s_nop 0
	global_load_dwordx4 v[152:155], v[152:153], off
	v_addc_co_u32_e32 v157, vcc, 0, v173, vcc
	v_add_co_u32_e32 v160, vcc, 0x80000, v172
	s_nop 1
	v_addc_co_u32_e32 v161, vcc, 0, v173, vcc
	v_add_co_u32_e32 v164, vcc, 0xa0000, v172
	global_load_dwordx4 v[156:159], v[156:157], off
	s_nop 0
	global_load_dwordx4 v[160:163], v[160:161], off
	v_addc_co_u32_e32 v165, vcc, 0, v173, vcc
	v_add_co_u32_e32 v168, vcc, 0xc0000, v172
	s_nop 1
	v_addc_co_u32_e32 v169, vcc, 0, v173, vcc
	v_add_co_u32_e32 v172, vcc, 0xe0000, v172
	global_load_dwordx4 v[164:167], v[164:165], off
	s_nop 0
	global_load_dwordx4 v[168:171], v[168:169], off
	v_addc_co_u32_e32 v173, vcc, 0, v173, vcc
	global_load_dwordx4 v[172:175], v[172:173], off

; DI int TID() { int t = threadIdx.x; asm volatile("" : "+v"(t)); return t; }
; DI unsigned cvtpk(float lo, float hi) { f32x2_t v = {lo, hi}; bf16x2_t b = __builtin_convertvector(v, bf16x2_t); return __builtin_bit_cast(unsigned, b); }
; DI void store_T_regs(const f32x16 (&acc)[2][4], int h, bfu* dst, const float* rs) {
;   const int tid = TID(), lane = tid & 63, w = tid >> 6, wm = w >> 1, wn = w & 1, l32 = lane & 31, hi = lane >> 5;
;   if (wn != h) return;
; #pragma unroll
;   for (int mi = 0; mi < 2; ++mi)
; #pragma unroll
;     for (int ni = 0; ni < 4; ++ni)
; #pragma unroll
;       for (int rg = 0; rg < 4; ++rg) {
;         const int row = wm * 64 + mi * 32 + 8 * rg + 4 * hi;
;         float s0 = 1.f, s1 = 1.f, s2 = 1.f, s3 = 1.f;
;         if (rs) { s0 = rs[row]; s1 = rs[row + 1]; s2 = rs[row + 2]; s3 = rs[row + 3]; }
;         const u32x2 v = {cvtpk(acc[mi][ni][4 * rg] * s0, acc[mi][ni][4 * rg + 1] * s1), cvtpk(acc[mi][ni][4 * rg + 2] * s2, acc[mi][ni][4 * rg + 3] * s3)};
;         *reinterpret_cast<u32x2*>(dst + (long)(ni * 32 + l32) * T + row) = v;
;       }
; }
.LBB0_211:
	s_cmpk_gt_i32 s52, 0xff
	s_cselect_b64 s[68:69], -1, 0
	s_cmp_eq_u64 s[4:5], 0
	s_cbranch_scc1 .LBB0_215
	v_mov_b32_e32 v176, v202
	s_nop 0
	v_and_b32_e32 v178, 64, v176
	v_cmp_eq_u32_e32 vcc, 0, v178
	s_and_saveexec_b64 s[2:3], vcc
	s_cbranch_execz .LBB0_214
	v_and_b32_e32 v179, 31, v176
	v_ashrrev_i32_e32 v178, 1, v176
	v_lshrrev_b32_e32 v176, 3, v176
	v_and_b32_e32 v176, 4, v176
	v_and_or_b32 v178, v178, s13, v176
	v_mul_u32_u24_e32 v176, 0x900, v179
	v_lshlrev_b32_e32 v176, 1, v176
	v_ashrrev_i32_e32 v179, 31, v178
	v_lshl_add_u64 v[180:181], s[4:5], 0, v[176:177]
	v_lshlrev_b64 v[196:197], 1, v[178:179]
	v_cvt_pk_bf16_f32 v194, v112, v113
	v_cvt_pk_bf16_f32 v195, v114, v115
	v_lshl_add_u64 v[198:199], v[180:181], 0, v[196:197]
	global_store_dwordx2 v[198:199], v[194:195], off
	v_or_b32_e32 v194, 8, v178
	v_cvt_pk_bf16_f32 v200, v116, v117
	v_cvt_pk_bf16_f32 v201, v118, v119
	v_cvt_pk_bf16_f32 v206, v124, v125
	v_cvt_pk_bf16_f32 v207, v126, v127
	v_ashrrev_i32_e32 v195, 31, v194
	global_store_dwordx2 v[198:199], v[200:201], off offset:16
	v_or_b32_e32 v200, 16, v178
	v_cvt_pk_bf16_f32 v204, v120, v121
	v_cvt_pk_bf16_f32 v205, v122, v123
	global_store_dwordx2 v[198:199], v[206:207], off offset:48
	v_lshl_add_u64 v[206:207], v[180:181], 0, s[14:15]
	v_ashrrev_i32_e32 v201, 31, v200
	global_store_dwordx2 v[198:199], v[204:205], off offset:32
	v_or_b32_e32 v204, 24, v178
	v_cvt_pk_bf16_f32 v208, v96, v97
	v_cvt_pk_bf16_f32 v209, v98, v99
	v_lshl_add_u64 v[210:211], v[206:207], 0, v[196:197]
	v_lshlrev_b64 v[194:195], 1, v[194:195]
	v_ashrrev_i32_e32 v205, 31, v204
	global_store_dwordx2 v[210:211], v[208:209], off
	v_cvt_pk_bf16_f32 v208, v100, v101
	v_cvt_pk_bf16_f32 v209, v102, v103
	v_lshl_add_u64 v[210:211], v[206:207], 0, v[194:195]
	v_lshlrev_b64 v[200:201], 1, v[200:201]
	global_store_dwordx2 v[210:211], v[208:209], off
	v_cvt_pk_bf16_f32 v208, v104, v105
	v_cvt_pk_bf16_f32 v209, v106, v107
	v_lshl_add_u64 v[210:211], v[206:207], 0, v[200:201]
	v_lshlrev_b64 v[204:205], 1, v[204:205]
	global_store_dwordx2 v[210:211], v[208:209], off
	v_cvt_pk_bf16_f32 v208, v108, v109
	v_cvt_pk_bf16_f32 v209, v110, v111
	v_lshl_add_u64 v[210:211], v[206:207], 0, v[204:205]
	global_store_dwordx2 v[210:211], v[208:209], off
	v_lshl_add_u64 v[208:209], v[180:181], 0, s[16:17]
	v_cvt_pk_bf16_f32 v210, v80, v81
	v_cvt_pk_bf16_f32 v211, v82, v83
	v_lshl_add_u64 v[212:213], v[208:209], 0, v[196:197]
	global_store_dwordx2 v[212:213], v[210:211], off
	v_cvt_pk_bf16_f32 v210, v84, v85
	v_cvt_pk_bf16_f32 v211, v86, v87
	v_lshl_add_u64 v[212:213], v[208:209], 0, v[194:195]
	global_store_dwordx2 v[212:213], v[210:211], off
	v_cvt_pk_bf16_f32 v210, v88, v89
	v_cvt_pk_bf16_f32 v211, v90, v91
	v_lshl_add_u64 v[212:213], v[208:209], 0, v[200:201]
	global_store_dwordx2 v[212:213], v[210:211], off
	v_cvt_pk_bf16_f32 v210, v92, v93
	v_cvt_pk_bf16_f32 v211, v94, v95
	v_lshl_add_u64 v[212:213], v[208:209], 0, v[204:205]
	v_lshl_add_u64 v[180:181], v[180:181], 0, s[46:47]
	global_store_dwordx2 v[212:213], v[210:211], off
	v_cvt_pk_bf16_f32 v210, v64, v65
	v_cvt_pk_bf16_f32 v211, v66, v67
	v_lshl_add_u64 v[196:197], v[180:181], 0, v[196:197]
	global_store_dwordx2 v[196:197], v[210:211], off
	v_cvt_pk_bf16_f32 v196, v68, v69
	v_cvt_pk_bf16_f32 v197, v70, v71
	v_lshl_add_u64 v[194:195], v[180:181], 0, v[194:195]
	global_store_dwordx2 v[194:195], v[196:197], off
	v_cvt_pk_bf16_f32 v194, v72, v73
	v_cvt_pk_bf16_f32 v195, v74, v75
	v_lshl_add_u64 v[196:197], v[180:181], 0, v[200:201]
	global_store_dwordx2 v[196:197], v[194:195], off
	v_cvt_pk_bf16_f32 v194, v76, v77
	v_cvt_pk_bf16_f32 v195, v78, v79
	v_lshl_add_u64 v[196:197], v[180:181], 0, v[204:205]
	global_store_dwordx2 v[196:197], v[194:195], off
	v_or_b32_e32 v194, 32, v178
	v_cvt_pk_bf16_f32 v196, v48, v49
	v_cvt_pk_bf16_f32 v197, v50, v51
	v_ashrrev_i32_e32 v195, 31, v194
	global_store_dwordx2 v[198:199], v[196:197], off offset:64
	v_or_b32_e32 v196, 40, v178
	v_cvt_pk_bf16_f32 v200, v52, v53
	v_cvt_pk_bf16_f32 v201, v54, v55
	v_cvt_pk_bf16_f32 v204, v56, v57
	v_cvt_pk_bf16_f32 v205, v58, v59
	v_ashrrev_i32_e32 v197, 31, v196
	global_store_dwordx2 v[198:199], v[200:201], off offset:80
	v_or_b32_e32 v200, 48, v178
	global_store_dwordx2 v[198:199], v[204:205], off offset:96
	v_cvt_pk_bf16_f32 v204, v60, v61
	v_cvt_pk_bf16_f32 v205, v62, v63
	v_lshlrev_b64 v[194:195], 1, v[194:195]
	v_ashrrev_i32_e32 v201, 31, v200
	v_or_b32_e32 v178, 56, v178
	global_store_dwordx2 v[198:199], v[204:205], off offset:112
	v_cvt_pk_bf16_f32 v198, v32, v33
	v_cvt_pk_bf16_f32 v199, v34, v35
	v_lshl_add_u64 v[204:205], v[206:207], 0, v[194:195]
	v_lshlrev_b64 v[196:197], 1, v[196:197]
	v_ashrrev_i32_e32 v179, 31, v178
	global_store_dwordx2 v[204:205], v[198:199], off
	v_cvt_pk_bf16_f32 v198, v36, v37
	v_cvt_pk_bf16_f32 v199, v38, v39
	v_lshl_add_u64 v[204:205], v[206:207], 0, v[196:197]
	v_lshlrev_b64 v[200:201], 1, v[200:201]
	global_store_dwordx2 v[204:205], v[198:199], off
	v_cvt_pk_bf16_f32 v198, v40, v41
	v_cvt_pk_bf16_f32 v199, v42, v43
	v_lshl_add_u64 v[204:205], v[206:207], 0, v[200:201]
	v_lshlrev_b64 v[178:179], 1, v[178:179]
	global_store_dwordx2 v[204:205], v[198:199], off
	v_cvt_pk_bf16_f32 v198, v44, v45
	v_cvt_pk_bf16_f32 v199, v46, v47
	v_lshl_add_u64 v[204:205], v[206:207], 0, v[178:179]
	global_store_dwordx2 v[204:205], v[198:199], off
	v_cvt_pk_bf16_f32 v198, v16, v17
	v_cvt_pk_bf16_f32 v199, v18, v19
	v_lshl_add_u64 v[204:205], v[208:209], 0, v[194:195]
	global_store_dwordx2 v[204:205], v[198:199], off
	v_cvt_pk_bf16_f32 v198, v20, v21
	v_cvt_pk_bf16_f32 v199, v22, v23
	v_lshl_add_u64 v[204:205], v[208:209], 0, v[196:197]
	global_store_dwordx2 v[204:205], v[198:199], off
	v_cvt_pk_bf16_f32 v198, v24, v25
	v_cvt_pk_bf16_f32 v199, v26, v27
	v_lshl_add_u64 v[204:205], v[208:209], 0, v[200:201]
	global_store_dwordx2 v[204:205], v[198:199], off
	v_cvt_pk_bf16_f32 v198, v28, v29
	v_cvt_pk_bf16_f32 v199, v30, v31
	v_lshl_add_u64 v[204:205], v[208:209], 0, v[178:179]
	global_store_dwordx2 v[204:205], v[198:199], off
	v_cvt_pk_bf16_f32 v198, v0, v1
	v_cvt_pk_bf16_f32 v199, v2, v3
	v_lshl_add_u64 v[194:195], v[180:181], 0, v[194:195]
	global_store_dwordx2 v[194:195], v[198:199], off
	v_cvt_pk_bf16_f32 v194, v4, v5
	v_cvt_pk_bf16_f32 v195, v6, v7
	v_lshl_add_u64 v[196:197], v[180:181], 0, v[196:197]
	global_store_dwordx2 v[196:197], v[194:195], off
	v_cvt_pk_bf16_f32 v194, v8, v9
	v_cvt_pk_bf16_f32 v195, v10, v11
	v_lshl_add_u64 v[196:197], v[180:181], 0, v[200:201]
	global_store_dwordx2 v[196:197], v[194:195], off
	v_cvt_pk_bf16_f32 v194, v12, v13
	v_cvt_pk_bf16_f32 v195, v14, v15
	v_lshl_add_u64 v[178:179], v[180:181], 0, v[178:179]
	global_store_dwordx2 v[178:179], v[194:195], off

;   DI const float* ab_b_if() const { return (const float*)sp[9]; }
; DI float logsig(float v) { return fminf(v, 0.f) - log1pf(__expf(-fabsf(v))); }
; DI void epi_in0(const Params& p, float* Cs, int m0, int n0) {
;     ...
;     for (int sidx = w; sidx < 32; sidx += 4) {
;       const int ch = sidx & 1, dh = sidx >> 1, dir = dh >> 3, head = dh & 7, row = ch * 64 + lane;
;       const float ig = Cs[row * CLD + dir * 8 + head] + p.ab_b_if()[dir * 8 + head];
;       const float f = logsig(Cs[row * CLD + 16 + dir * 8 + head] + p.ab_b_if()[16 + dir * 8 + head]);
;       float bc = f;
;       for (int off = 1; off < 64; off <<= 1) {
;         const float yu = __shfl_up(bc, off), yd = __shfl_down(bc, off);
;         const bool ok = dir == 0 ? lane >= off : lane + off < 64;
.LBB0_228:
	v_ashrrev_i32_e32 v209, 4, v200
	v_bfe_u32 v208, v200, 1, 3
	v_lshlrev_b32_e32 v214, 3, v209
	v_and_or_b32 v176, v207, 64, v193
	v_or_b32_e32 v212, v214, v208
	v_mul_u32_u24_e32 v180, 0x210, v176
	v_lshlrev_b32_e32 v181, 5, v209
	v_lshlrev_b32_e32 v210, 2, v208
	v_ashrrev_i32_e32 v213, 31, v212
	v_add3_u32 v180, v180, v181, v210
	s_waitcnt lgkmcnt(0)
	v_lshl_add_u64 v[210:211], v[212:213], 2, v[178:179]
	v_ashrrev_i32_e32 v213, 31, v214
	v_lshl_add_u64 v[212:213], v[212:213], 2, v[178:179]
	global_load_dword v210, v[210:211], off
	ds_read2_b32 v[180:181], v180 offset1:16
	global_load_dword v211, v[212:213], off offset:64
	v_add_u32_e32 v207, 0x100, v207
	s_waitcnt vmcnt(0) lgkmcnt(0)
	v_add_f32_e32 v180, v180, v210
	v_add_f32_e32 v181, v181, v211
	v_min_f32_e32 v211, 0, v181
	v_mul_f32_e64 v181, |v181|, s19
	v_exp_f32_e32 v181, v181
	v_cmp_gt_u32_e64 s[18:19], 16, v200
	s_xor_b64 s[28:29], s[16:17], s[18:19]
	v_add_f32_e32 v214, 1.0, v181
	v_add_f32_e32 v212, -1.0, v214
	v_sub_f32_e32 v213, v212, v214
	v_add_f32_e32 v213, 1.0, v213
	v_sub_f32_e32 v212, v181, v212
	v_add_f32_e32 v215, v212, v213
	v_frexp_mant_f32_e32 v212, v214
	v_cmp_gt_f32_e64 s[0:1], s20, v212
	v_cvt_f64_f32_e32 v[212:213], v214
	v_frexp_exp_i32_f64_e32 v212, v[212:213]
	v_subbrev_co_u32_e64 v212, s[0:1], 0, v212, s[0:1]
	v_sub_u32_e32 v213, 0, v212
	v_ldexp_f32 v214, v214, v213
	v_ldexp_f32 v213, v215, v213
	v_add_f32_e32 v215, -1.0, v214
	v_add_f32_e32 v216, 1.0, v215
	v_sub_f32_e32 v216, v214, v216
	v_add_f32_e32 v216, v213, v216
	v_add_f32_e32 v217, v215, v216
	v_sub_f32_e32 v215, v217, v215
	v_sub_f32_e32 v215, v216, v215
	v_add_f32_e32 v216, 1.0, v214
	v_add_f32_e32 v218, -1.0, v216
	v_sub_f32_e32 v214, v214, v218
	v_add_f32_e32 v213, v213, v214
	v_add_f32_e32 v214, v216, v213
	v_sub_f32_e32 v216, v214, v216
	v_sub_f32_e32 v213, v213, v216
	v_rcp_f32_e32 v216, v214
	v_cvt_f32_i32_e32 v212, v212
	v_cmp_neq_f32_e64 s[0:1], s22, v181
	v_mul_f32_e32 v218, v217, v216
	v_mul_f32_e32 v219, v214, v218
	v_fma_f32 v220, v218, v214, -v219
	v_fmac_f32_e32 v220, v218, v213
	v_add_f32_e32 v221, v219, v220
	v_sub_f32_e32 v222, v217, v221
	v_sub_f32_e32 v217, v217, v222
	v_sub_f32_e32 v219, v221, v219
	v_sub_f32_e32 v217, v217, v221
	v_add_f32_e32 v215, v215, v217
	v_sub_f32_e32 v217, v219, v220
	v_add_f32_e32 v215, v217, v215
	v_add_f32_e32 v217, v222, v215
	v_mul_f32_e32 v219, v216, v217
	v_mul_f32_e32 v220, v214, v219
	v_fma_f32 v214, v219, v214, -v220
	v_fmac_f32_e32 v214, v219, v213
	v_sub_f32_e32 v213, v222, v217
	v_add_f32_e32 v213, v215, v213
	v_add_f32_e32 v215, v220, v214
	v_sub_f32_e32 v221, v217, v215
	v_sub_f32_e32 v217, v217, v221
	v_sub_f32_e32 v220, v215, v220
	v_sub_f32_e32 v215, v217, v215
	v_add_f32_e32 v213, v213, v215
	v_sub_f32_e32 v214, v220, v214
	v_add_f32_e32 v213, v214, v213
	v_add_f32_e32 v214, v218, v219
	v_add_f32_e32 v213, v221, v213
	v_sub_f32_e32 v215, v214, v218
	v_mul_f32_e32 v213, v216, v213
	v_sub_f32_e32 v215, v219, v215
	v_add_f32_e32 v213, v215, v213
	v_mul_f32_e32 v218, 0x3f317218, v212
	v_add_f32_e32 v215, v214, v213
	v_fma_f32 v219, v212, s21, -v218
	v_mul_f32_e32 v216, v215, v215
	v_fmac_f32_e32 v219, 0xb102e308, v212
	v_sub_f32_e32 v212, v215, v214
	v_fmamk_f32 v217, v216, 0x3e9b6dac, v185
	v_sub_f32_e32 v212, v213, v212
	v_add_f32_e32 v213, v218, v219
	v_fmaak_f32 v217, v216, v217, 0x3f2aaada
	v_sub_f32_e32 v214, v213, v218
	v_ldexp_f32 v218, v215, 1
	v_mul_f32_e32 v215, v215, v216
	v_mul_f32_e32 v215, v215, v217
	v_add_f32_e32 v216, v218, v215
	v_sub_f32_e32 v217, v216, v218
	v_ldexp_f32 v212, v212, 1
	v_sub_f32_e32 v215, v215, v217
	v_add_f32_e32 v212, v212, v215
	v_add_f32_e32 v215, v216, v212
	v_sub_f32_e32 v216, v215, v216
	v_sub_f32_e32 v212, v212, v216
	v_add_f32_e32 v216, v213, v215
	v_sub_f32_e32 v217, v216, v213
	v_sub_f32_e32 v218, v216, v217
	v_sub_f32_e32 v214, v219, v214
	v_sub_f32_e32 v213, v213, v218
	v_sub_f32_e32 v215, v215, v217
	v_add_f32_e32 v213, v215, v213
	v_add_f32_e32 v215, v214, v212
	v_sub_f32_e32 v217, v215, v214
	v_sub_f32_e32 v218, v215, v217
	v_sub_f32_e32 v214, v214, v218
	v_sub_f32_e32 v212, v212, v217
	v_add_f32_e32 v213, v215, v213
	v_add_f32_e32 v212, v212, v214
	v_add_f32_e32 v214, v216, v213
	v_sub_f32_e32 v215, v214, v216
	v_sub_f32_e32 v213, v213, v215
	v_add_f32_e32 v212, v212, v213
	v_add_f32_e32 v212, v214, v212
	v_cndmask_b32_e64 v212, v188, v212, s[0:1]
	v_cmp_ngt_f32_e64 s[0:1], -1.0, v181
	v_cndmask_b32_e64 v213, 63, 0, s[18:19]
	v_cmp_eq_u32_e64 s[20:21], v193, v213
	v_cndmask_b32_e64 v212, v189, v212, s[0:1]
	v_cmp_neq_f32_e64 s[0:1], -1.0, v181
	v_cndmask_b32_e64 v213, 0, 1, vcc
	v_cndmask_b32_e64 v214, 0, 1, s[2:3]
	v_cndmask_b32_e64 v212, v190, v212, s[0:1]
	v_cmp_lt_f32_e64 s[0:1], |v181|, s23
	v_cndmask_b32_e64 v213, v214, v213, s[18:19]
	v_and_b32_e32 v213, 1, v213
	v_cndmask_b32_e64 v181, v212, v181, s[0:1]
	v_sub_f32_e32 v181, v211, v181
	ds_bpermute_b32 v211, v194, v181
	ds_bpermute_b32 v212, v195, v181
	v_cmp_eq_u32_e64 s[22:23], 1, v213
	v_cndmask_b32_e64 v213, 0, 1, s[4:5]
	v_cndmask_b32_e64 v214, 0, 1, s[6:7]
	v_cndmask_b32_e64 v213, v214, v213, s[18:19]
	s_waitcnt lgkmcnt(0)
; DI void epi_in0(const Params& p, float* Cs, int m0, int n0) {
;     ...
;       float bc = f;
;       for (int off = 1; off < 64; off <<= 1) {
;         const float yu = __shfl_up(bc, off), yd = __shfl_down(bc, off);
;         const bool ok = dir == 0 ? lane >= off : lane + off < 64;
;         if (ok) bc += dir == 0 ? yu : yd;
;       }
;       const float gs = ig - bc;
;       float cm = gs;
;       for (int off = 1; off < 64; off <<= 1) {
;         const float yu = __shfl_up(cm, off), yd = __shfl_down(cm, off);
;         const bool ok = dir == 0 ? lane >= off : lane + off < 64;
;         if (ok) cm = fmaxf(cm, dir == 0 ? yu : yd);
;       }
;       const long o = ((long)(dir * GB + bg) * 8 + head) * T + t0 + row;
;       gb[o] = bc; gsv[o] = gs; gc[o] = cm;
	v_cndmask_b32_e64 v211, v212, v211, s[18:19]
	v_add_f32_e32 v211, v181, v211
	v_cndmask_b32_e64 v181, v211, v181, s[20:21]
	ds_bpermute_b32 v211, v196, v181
	ds_bpermute_b32 v212, v197, v181
	v_and_b32_e32 v213, 1, v213
	v_cmp_eq_u32_e64 s[24:25], 1, v213
	v_cndmask_b32_e64 v213, 0, 1, s[8:9]
	v_cndmask_b32_e64 v214, 0, 1, s[10:11]
	s_waitcnt lgkmcnt(0)
	v_cndmask_b32_e64 v211, v212, v211, s[18:19]
	v_add_f32_e32 v211, v181, v211
	v_cndmask_b32_e64 v181, v181, v211, s[22:23]
	ds_bpermute_b32 v211, v198, v181
	ds_bpermute_b32 v212, v199, v181
	v_cndmask_b32_e64 v213, v214, v213, s[18:19]
	v_and_b32_e32 v213, 1, v213
	v_cmp_eq_u32_e64 s[0:1], 1, v213
	v_cndmask_b32_e64 v213, 0, 1, s[12:13]
	s_waitcnt lgkmcnt(0)
	v_cndmask_b32_e64 v211, v212, v211, s[18:19]
	v_add_f32_e32 v211, v181, v211
	v_cndmask_b32_e64 v181, v181, v211, s[24:25]
	ds_bpermute_b32 v211, v201, v181
	ds_bpermute_b32 v212, v203, v181
	v_cndmask_b32_e64 v214, 0, 1, s[14:15]
	v_cndmask_b32_e64 v213, v214, v213, s[18:19]
	v_and_b32_e32 v213, 1, v213
	v_cmp_eq_u32_e64 s[26:27], 1, v213
	s_waitcnt lgkmcnt(0)
	v_cndmask_b32_e64 v211, v212, v211, s[18:19]
	v_add_f32_e32 v211, v181, v211
	v_cndmask_b32_e64 v181, v181, v211, s[0:1]
	ds_bpermute_b32 v211, v204, v181
	ds_bpermute_b32 v212, v205, v181
	s_waitcnt lgkmcnt(0)
	v_cndmask_b32_e64 v211, v212, v211, s[18:19]
	v_add_f32_e32 v211, v181, v211
	v_cndmask_b32_e64 v181, v181, v211, s[26:27]
	ds_bpermute_b32 v211, v206, v181
	ds_bpermute_b32 v212, v187, v181
	s_waitcnt lgkmcnt(0)
	v_cndmask_b32_e64 v211, v212, v211, s[18:19]
	v_add_f32_e32 v211, v181, v211
	v_cndmask_b32_e64 v211, v181, v211, s[28:29]
	v_sub_f32_e32 v210, v180, v211
	ds_bpermute_b32 v180, v194, v210
	ds_bpermute_b32 v181, v195, v210
	s_waitcnt lgkmcnt(0)
	v_cndmask_b32_e64 v180, v181, v180, s[18:19]
	v_max_f32_e32 v180, v180, v180
	v_max_f32_e32 v180, v210, v180
	v_cndmask_b32_e64 v180, v180, v210, s[20:21]
	ds_bpermute_b32 v181, v196, v180
	ds_bpermute_b32 v212, v197, v180
	s_mov_b32 s21, 0x3f317218
	s_mov_b32 s20, 0x3f2aaaab
	s_waitcnt lgkmcnt(0)
	v_cndmask_b32_e64 v181, v212, v181, s[18:19]
	v_max_f32_e32 v181, v181, v181
	v_max_f32_e32 v181, v180, v181
	v_cndmask_b32_e64 v180, v180, v181, s[22:23]
	ds_bpermute_b32 v181, v198, v180
	ds_bpermute_b32 v212, v199, v180
	s_mov_b32 s23, 0x33800000
	s_mov_b32 s22, 0x7f800000
	s_waitcnt lgkmcnt(0)
	v_cndmask_b32_e64 v181, v212, v181, s[18:19]
	v_max_f32_e32 v181, v181, v181
	v_max_f32_e32 v181, v180, v181
	v_cndmask_b32_e64 v180, v180, v181, s[24:25]
	ds_bpermute_b32 v181, v201, v180
	ds_bpermute_b32 v212, v203, v180
	s_waitcnt lgkmcnt(0)
	v_cndmask_b32_e64 v181, v212, v181, s[18:19]
	v_max_f32_e32 v181, v181, v181
	v_max_f32_e32 v181, v180, v181
	v_cndmask_b32_e64 v180, v180, v181, s[0:1]
	ds_bpermute_b32 v181, v204, v180
	ds_bpermute_b32 v212, v205, v180
	s_waitcnt lgkmcnt(0)
	v_cndmask_b32_e64 v181, v212, v181, s[18:19]
	v_max_f32_e32 v181, v181, v181
	v_max_f32_e32 v181, v180, v181
	v_cndmask_b32_e64 v180, v180, v181, s[26:27]
	ds_bpermute_b32 v181, v206, v180
	ds_bpermute_b32 v212, v187, v180
	s_waitcnt lgkmcnt(0)
	v_cndmask_b32_e64 v181, v212, v181, s[18:19]
	v_max_f32_e32 v181, v181, v181
	v_max_f32_e32 v212, v180, v180
	v_max_f32_e32 v181, v212, v181
	v_cndmask_b32_e64 v212, v180, v181, s[28:29]
	v_lshl_add_u32 v180, v209, 1, s97
	s_movk_i32 s18, 0x900
	v_ashrrev_i32_e32 v209, 31, v180
	v_lshl_or_b32 v208, v180, 3, v208
	v_lshl_add_u64 v[180:181], v[176:177], 0, s[52:53]
	v_mad_u64_u32 v[180:181], s[0:1], v208, s18, v[180:181]
	v_mad_i32_i24 v181, v209, s18, v181
	v_lshlrev_b64 v[180:181], 2, v[180:181]
	v_lshl_add_u64 v[208:209], s[80:81], 0, v[180:181]
	v_add_u32_e32 v176, 4, v200
	v_cmp_lt_i32_e64 s[0:1], 27, v200
	s_mov_b32 s19, 0xbfb8aa3b
	global_store_dword v[208:209], v211, off
	v_lshl_add_u64 v[208:209], s[88:89], 0, v[180:181]
	v_lshl_add_u64 v[180:181], s[84:85], 0, v[180:181]
	s_or_b64 s[62:63], s[0:1], s[62:63]
	v_mov_b32_e32 v200, v176
	global_store_dword v[208:209], v210, off
	global_store_dword v[180:181], v212, off
	s_andn2_b64 exec, exec, s[62:63]
	s_cbranch_execnz .LBB0_228

; DI int TID() { int t = threadIdx.x; asm volatile("" : "+v"(t)); return t; }
; DI bf16x8 pack8f(const float* v) { u32x4 w = {cvtpk(v[0], v[1]), cvtpk(v[2], v[3]), cvtpk(v[4], v[5]), cvtpk(v[6], v[7])}; return __builtin_bit_cast(bf16x8, w); }
; DI void store_R(const float* Cs, int cb, int nc, bfu* dst, long ld, float scale, const float* rs = nullptr) {
;   const int cpr = nc >> 3;
;   for (int u = TID(); u < 128 * cpr; u += NT) {
;     int row = u / cpr, c8 = (u % cpr) * 8; float v[8]; ldrow8(Cs, row, cb + c8, v);
;     float s = rs ? scale * rs[row] : scale;
;     for (int j = 0; j < 8; ++j) v[j] *= s;
;     st8(dst + row * ld + c8, pack8f(v));
;   }
; }
.LBB0_233:
	v_ashrrev_i32_e32 v180, 31, v176
	v_lshrrev_b32_e32 v180, 28, v180
	v_add_u32_e32 v181, 0x100, v176
	v_add_u32_e32 v193, v176, v180
	v_cmp_lt_i32_e32 vcc, s54, v176
	v_mov_b32_e32 v176, v181
	v_and_b32_e32 v181, -16, v193
	v_add_u32_e32 v198, v179, v181
	ds_read_b128 v[194:197], v198
	ds_read_b128 v[198:201], v198 offset:16
	v_ashrrev_i32_e32 v180, 4, v193
	v_lshlrev_b32_e32 v193, 7, v180
	v_ashrrev_i32_e32 v181, 31, v180
	v_sub_u32_e32 v204, v178, v193
	v_lshlrev_b64 v[180:181], 13, v[180:181]
	v_lshl_add_u64 v[180:181], s[2:3], 0, v[180:181]
	v_ashrrev_i32_e32 v205, 31, v204
	s_or_b64 s[4:5], vcc, s[4:5]
	v_add_u32_e32 v179, 0x2000, v179
	v_add_u32_e32 v178, 0x800, v178
	v_lshl_add_u64 v[180:181], v[204:205], 1, v[180:181]
	s_waitcnt lgkmcnt(0)
	v_cvt_pk_bf16_f32 v194, v194, v195
	v_cvt_pk_bf16_f32 v195, v196, v197
	v_cvt_pk_bf16_f32 v196, v198, v199
	v_cvt_pk_bf16_f32 v197, v200, v201
	global_store_dwordx4 v[180:181], v[194:197], off
	s_andn2_b64 exec, exec, s[4:5]
	s_cbranch_execnz .LBB0_233

; DI int TID() { int t = threadIdx.x; asm volatile("" : "+v"(t)); return t; }
; DI bf16x8 pack8f(const float* v) { u32x4 w = {cvtpk(v[0], v[1]), cvtpk(v[2], v[3]), cvtpk(v[4], v[5]), cvtpk(v[6], v[7])}; return __builtin_bit_cast(bf16x8, w); }
; DI void store_R(const float* Cs, int cb, int nc, bfu* dst, long ld, float scale, const float* rs = nullptr) {
;   const int cpr = nc >> 3;
;   for (int u = TID(); u < 128 * cpr; u += NT) {
;     int row = u / cpr, c8 = (u % cpr) * 8; float v[8]; ldrow8(Cs, row, cb + c8, v);
;     float s = rs ? scale * rs[row] : scale;
;     for (int j = 0; j < 8; ++j) v[j] *= s;
;     st8(dst + row * ld + c8, pack8f(v));
;   }
; }
.LBB0_239:
	v_ashrrev_i32_e32 v180, 31, v176
	v_lshrrev_b32_e32 v180, 28, v180
	v_add_u32_e32 v181, 0x100, v176
	v_add_u32_e32 v193, v176, v180
	v_cmp_lt_i32_e32 vcc, s54, v176
	v_mov_b32_e32 v176, v181
	v_and_b32_e32 v181, -16, v193
	v_add_u32_e32 v198, v179, v181
	ds_read_b128 v[194:197], v198
	ds_read_b128 v[198:201], v198 offset:16
	v_ashrrev_i32_e32 v180, 4, v193
	v_lshlrev_b32_e32 v193, 7, v180
	v_ashrrev_i32_e32 v181, 31, v180
	v_sub_u32_e32 v204, v178, v193
	v_lshlrev_b64 v[180:181], 12, v[180:181]
	v_lshl_add_u64 v[180:181], s[2:3], 0, v[180:181]
	v_ashrrev_i32_e32 v205, 31, v204
	s_or_b64 s[4:5], vcc, s[4:5]
	v_add_u32_e32 v179, 0x2000, v179
	v_add_u32_e32 v178, 0x800, v178
	v_lshl_add_u64 v[180:181], v[204:205], 1, v[180:181]
	s_waitcnt lgkmcnt(0)
	v_cvt_pk_bf16_f32 v194, v194, v195
	v_cvt_pk_bf16_f32 v195, v196, v197
	v_cvt_pk_bf16_f32 v196, v198, v199
	v_cvt_pk_bf16_f32 v197, v200, v201
	global_store_dwordx4 v[180:181], v[194:197], off
	s_andn2_b64 exec, exec, s[4:5]
	s_cbranch_execnz .LBB0_239

;   DI const float* c() const { return (const float*)sp[1]; }
; DI int TID() { int t = threadIdx.x; asm volatile("" : "+v"(t)); return t; }
; DI bf16x8 pack8f(const float* v) { u32x4 w = {cvtpk(v[0], v[1]), cvtpk(v[2], v[3]), cvtpk(v[4], v[5]), cvtpk(v[6], v[7])}; return __builtin_bit_cast(bf16x8, w); }
; DI void store_T(const float* Cs, int cb, int nc, bfu* dst, long ldT, float scale, const float* rs = nullptr) {
;   for (int u = TID(); u < nc * 16; u += NT) {
;     int c = u % nc, rc = (u / nc) * 8; float v[8];
;     for (int j = 0; j < 8; ++j) v[j] = Cs[(rc + j) * CLD + cb + c] * (rs ? scale * rs[rc + j] : scale);
;     st8(dst + c * ldT + rc, pack8f(v));
;   }
; }
.LBB0_245:
	v_ashrrev_i32_e32 v180, 31, v179
	v_lshrrev_b32_e32 v180, 25, v180
	v_add_u32_e32 v181, 0x100, v179
	v_add_u32_e32 v180, v179, v180
	v_cmp_lt_i32_e32 vcc, s54, v179
	v_mov_b32_e32 v179, v181
	v_ashrrev_i32_e32 v181, 7, v180
	v_mad_u64_u32 v[194:195], s[6:7], v181, s55, v[178:179]
	v_add_u32_e32 v193, 0x400, v194
	ds_read2_b32 v[198:199], v194 offset1:132
	v_add_u32_e32 v195, 0x800, v194
	v_add_u32_e32 v194, 0xc00, v194
	ds_read2_b32 v[200:201], v193 offset0:8 offset1:140
	ds_read2_b32 v[204:205], v195 offset0:16 offset1:148
	ds_read2_b32 v[206:207], v194 offset0:24 offset1:156
	v_mad_u64_u32 v[196:197], s[6:7], v181, s96, v[176:177]
	v_lshlrev_b32_e32 v180, 3, v181
	v_ashrrev_i32_e32 v197, 31, v196
	v_ashrrev_i32_e32 v181, 31, v180
	v_lshl_add_u64 v[194:195], s[2:3], 0, v[196:197]
	s_or_b64 s[4:5], vcc, s[4:5]
	v_add_u32_e32 v176, 0x120000, v176
	v_add_u32_e32 v178, 0x400, v178
	v_lshl_add_u64 v[180:181], v[180:181], 1, v[194:195]
	s_waitcnt lgkmcnt(0)
	v_cvt_pk_bf16_f32 v194, v198, v199
	v_cvt_pk_bf16_f32 v195, v200, v201
	v_cvt_pk_bf16_f32 v196, v204, v205
	v_cvt_pk_bf16_f32 v197, v206, v207
	global_store_dwordx4 v[180:181], v[194:197], off
	s_andn2_b64 exec, exec, s[4:5]
	s_cbranch_execnz .LBB0_245

; DI int TID() { int t = threadIdx.x; asm volatile("" : "+v"(t)); return t; }
; DI bf16x8 pack8f(const float* v) { u32x4 w = {cvtpk(v[0], v[1]), cvtpk(v[2], v[3]), cvtpk(v[4], v[5]), cvtpk(v[6], v[7])}; return __builtin_bit_cast(bf16x8, w); }
; DI void store_R(const float* Cs, int cb, int nc, bfu* dst, long ld, float scale, const float* rs = nullptr) {
;   const int cpr = nc >> 3;
;   for (int u = TID(); u < 128 * cpr; u += NT) {
;     int row = u / cpr, c8 = (u % cpr) * 8; float v[8]; ldrow8(Cs, row, cb + c8, v);
;     float s = rs ? scale * rs[row] : scale;
;     for (int j = 0; j < 8; ++j) v[j] *= s;
;     st8(dst + row * ld + c8, pack8f(v));
;   }
; }
.LBB0_251:
	v_ashrrev_i32_e32 v180, 31, v176
	v_lshrrev_b32_e32 v180, 28, v180
	v_add_u32_e32 v181, 0x100, v176
	v_add_u32_e32 v193, v176, v180
	v_cmp_lt_i32_e32 vcc, s54, v176
	v_mov_b32_e32 v176, v181
	v_and_b32_e32 v181, -16, v193
	v_add_u32_e32 v198, v179, v181
	ds_read_b128 v[194:197], v198
	ds_read_b128 v[198:201], v198 offset:16
	v_ashrrev_i32_e32 v180, 4, v193
	v_lshlrev_b32_e32 v193, 7, v180
	v_ashrrev_i32_e32 v181, 31, v180
	v_sub_u32_e32 v204, v178, v193
	v_lshlrev_b64 v[180:181], 8, v[180:181]
	v_lshl_add_u64 v[180:181], s[2:3], 0, v[180:181]
	v_ashrrev_i32_e32 v205, 31, v204
	s_or_b64 s[4:5], vcc, s[4:5]
	v_add_u32_e32 v179, 0x2000, v179
	v_add_u32_e32 v178, 0x800, v178
	v_lshl_add_u64 v[180:181], v[204:205], 1, v[180:181]
	s_waitcnt lgkmcnt(0)
	v_cvt_pk_bf16_f32 v194, v194, v195
	v_cvt_pk_bf16_f32 v195, v196, v197
	v_cvt_pk_bf16_f32 v196, v198, v199
	v_cvt_pk_bf16_f32 v197, v200, v201
	global_store_dwordx4 v[180:181], v[194:197], off
	s_andn2_b64 exec, exec, s[4:5]
	s_cbranch_execnz .LBB0_251

; DI int TID() { int t = threadIdx.x; asm volatile("" : "+v"(t)); return t; }
; DI bf16x8 pack8f(const float* v) { u32x4 w = {cvtpk(v[0], v[1]), cvtpk(v[2], v[3]), cvtpk(v[4], v[5]), cvtpk(v[6], v[7])}; return __builtin_bit_cast(bf16x8, w); }
; DI void store_R(const float* Cs, int cb, int nc, bfu* dst, long ld, float scale, const float* rs = nullptr) {
;   const int cpr = nc >> 3;
;   for (int u = TID(); u < 128 * cpr; u += NT) {
;     int row = u / cpr, c8 = (u % cpr) * 8; float v[8]; ldrow8(Cs, row, cb + c8, v);
;     float s = rs ? scale * rs[row] : scale;
;     for (int j = 0; j < 8; ++j) v[j] *= s;
;     st8(dst + row * ld + c8, pack8f(v));
;   }
; }
.LBB0_260:
	v_ashrrev_i32_e32 v180, 31, v176
	v_lshrrev_b32_e32 v180, 28, v180
	v_add_u32_e32 v181, 0x100, v176
	v_add_u32_e32 v193, v176, v180
	v_cmp_lt_i32_e32 vcc, s54, v176
	v_mov_b32_e32 v176, v181
	v_and_b32_e32 v181, -16, v193
	v_add_u32_e32 v198, v179, v181
	ds_read_b128 v[194:197], v198
	ds_read_b128 v[198:201], v198 offset:16
	v_ashrrev_i32_e32 v180, 4, v193
	v_lshlrev_b32_e32 v193, 7, v180
	v_ashrrev_i32_e32 v181, 31, v180
	v_sub_u32_e32 v204, v178, v193
	v_lshlrev_b64 v[180:181], 8, v[180:181]
	v_lshl_add_u64 v[180:181], s[2:3], 0, v[180:181]
	v_ashrrev_i32_e32 v205, 31, v204
	s_waitcnt lgkmcnt(0)
	v_pk_mul_f32 v[194:195], v[194:195], s[48:49] op_sel_hi:[1,0]
	v_pk_mul_f32 v[196:197], v[196:197], s[48:49] op_sel_hi:[1,0]
	v_pk_mul_f32 v[198:199], v[198:199], s[48:49] op_sel_hi:[1,0]
	v_pk_mul_f32 v[200:201], v[200:201], s[48:49] op_sel_hi:[1,0]
	s_or_b64 s[4:5], vcc, s[4:5]
	v_add_u32_e32 v179, 0x2000, v179
	v_add_u32_e32 v178, 0x800, v178
	v_lshl_add_u64 v[180:181], v[204:205], 1, v[180:181]
	v_cvt_pk_bf16_f32 v194, v194, v195
	v_cvt_pk_bf16_f32 v195, v196, v197
	v_cvt_pk_bf16_f32 v196, v198, v199
	v_cvt_pk_bf16_f32 v197, v200, v201
	global_store_dwordx4 v[180:181], v[194:197], off
	s_andn2_b64 exec, exec, s[4:5]
	s_cbranch_execnz .LBB0_260

; DI int TID() { int t = threadIdx.x; asm volatile("" : "+v"(t)); return t; }
; DI bf16x8 pack8f(const float* v) { u32x4 w = {cvtpk(v[0], v[1]), cvtpk(v[2], v[3]), cvtpk(v[4], v[5]), cvtpk(v[6], v[7])}; return __builtin_bit_cast(bf16x8, w); }
; DI void store_R(const float* Cs, int cb, int nc, bfu* dst, long ld, float scale, const float* rs = nullptr) {
;   const int cpr = nc >> 3;
;   for (int u = TID(); u < 128 * cpr; u += NT) {
;     int row = u / cpr, c8 = (u % cpr) * 8; float v[8]; ldrow8(Cs, row, cb + c8, v);
;     float s = rs ? scale * rs[row] : scale;
;     for (int j = 0; j < 8; ++j) v[j] *= s;
;     st8(dst + row * ld + c8, pack8f(v));
;   }
; }
.LBB0_280:
	v_ashrrev_i32_e32 v193, 31, v180
	v_lshrrev_b32_e32 v193, 29, v193
	v_add_u32_e32 v193, v180, v193
	v_ashrrev_i32_e32 v204, 3, v193
	v_add_u32_e32 v194, 0x100, v180
	v_mad_u64_u32 v[198:199], s[10:11], v204, s90, v[176:177]
	v_cmp_lt_i32_e32 vcc, s91, v180
	v_mov_b32_e32 v180, v194
	ds_read_b128 v[194:197], v198
	ds_read_b128 v[198:201], v198 offset:16
	v_lshlrev_b32_e32 v193, 6, v204
	v_ashrrev_i32_e32 v205, 31, v204
	v_sub_u32_e32 v206, v181, v193
	v_lshlrev_b64 v[204:205], 7, v[204:205]
	v_lshl_add_u64 v[204:205], s[2:3], 0, v[204:205]
	v_ashrrev_i32_e32 v207, 31, v206
	s_waitcnt lgkmcnt(0)
	v_pk_mul_f32 v[194:195], v[178:179], v[194:195]
	v_pk_mul_f32 v[196:197], v[178:179], v[196:197]
	v_pk_mul_f32 v[198:199], v[178:179], v[198:199]
	v_pk_mul_f32 v[200:201], v[178:179], v[200:201]
	s_or_b64 s[4:5], vcc, s[4:5]
	v_add_u32_e32 v176, 0x2000, v176
	v_add_u32_e32 v181, 0x800, v181
	v_lshl_add_u64 v[204:205], v[206:207], 1, v[204:205]
	v_cvt_pk_bf16_f32 v194, v194, v195
	v_cvt_pk_bf16_f32 v195, v196, v197
	v_cvt_pk_bf16_f32 v196, v198, v199
	v_cvt_pk_bf16_f32 v197, v200, v201
	global_store_dwordx4 v[204:205], v[194:197], off
	s_andn2_b64 exec, exec, s[4:5]
	s_cbranch_execnz .LBB0_280

; DI int TID() { int t = threadIdx.x; asm volatile("" : "+v"(t)); return t; }
; DI bf16x8 pack8f(const float* v) { u32x4 w = {cvtpk(v[0], v[1]), cvtpk(v[2], v[3]), cvtpk(v[4], v[5]), cvtpk(v[6], v[7])}; return __builtin_bit_cast(bf16x8, w); }
; DI void store_R(const float* Cs, int cb, int nc, bfu* dst, long ld, float scale, const float* rs = nullptr) {
;   const int cpr = nc >> 3;
;   for (int u = TID(); u < 128 * cpr; u += NT) {
;     int row = u / cpr, c8 = (u % cpr) * 8; float v[8]; ldrow8(Cs, row, cb + c8, v);
;     float s = rs ? scale * rs[row] : scale;
;     for (int j = 0; j < 8; ++j) v[j] *= s;
;     st8(dst + row * ld + c8, pack8f(v));
;   }
; }
.LBB0_283:
	v_ashrrev_i32_e32 v193, 31, v180
	v_lshrrev_b32_e32 v193, 29, v193
	v_add_u32_e32 v193, v180, v193
	v_ashrrev_i32_e32 v204, 3, v193
	v_add_u32_e32 v194, 0x100, v180
	v_mad_u64_u32 v[198:199], s[6:7], v204, s90, v[176:177]
	v_cmp_lt_i32_e32 vcc, s91, v180
	v_mov_b32_e32 v180, v194
	ds_read_b128 v[194:197], v198
	ds_read_b128 v[198:201], v198 offset:16
	v_lshlrev_b32_e32 v193, 6, v204
	v_ashrrev_i32_e32 v205, 31, v204
	v_sub_u32_e32 v206, v181, v193
	v_lshlrev_b64 v[204:205], 7, v[204:205]
	v_lshl_add_u64 v[204:205], s[2:3], 0, v[204:205]
	v_ashrrev_i32_e32 v207, 31, v206
	s_waitcnt lgkmcnt(0)
	v_pk_mul_f32 v[194:195], v[178:179], v[194:195]
	v_pk_mul_f32 v[196:197], v[178:179], v[196:197]
	v_pk_mul_f32 v[198:199], v[178:179], v[198:199]
	v_pk_mul_f32 v[200:201], v[178:179], v[200:201]
	s_or_b64 s[4:5], vcc, s[4:5]
	v_add_u32_e32 v176, 0x2000, v176
	v_add_u32_e32 v181, 0x800, v181
	v_lshl_add_u64 v[204:205], v[206:207], 1, v[204:205]
	v_cvt_pk_bf16_f32 v194, v194, v195
	v_cvt_pk_bf16_f32 v195, v196, v197
	v_cvt_pk_bf16_f32 v196, v198, v199
	v_cvt_pk_bf16_f32 v197, v200, v201
	global_store_dwordx4 v[204:205], v[194:197], off
	s_andn2_b64 exec, exec, s[4:5]
	s_cbranch_execnz .LBB0_283

; DI int TID() { int t = threadIdx.x; asm volatile("" : "+v"(t)); return t; }
; DI unsigned cvtpk(float lo, float hi) { f32x2_t v = {lo, hi}; bf16x2_t b = __builtin_convertvector(v, bf16x2_t); return __builtin_bit_cast(unsigned, b); }
; DI void store_T_regs(const f32x16 (&acc)[2][4], int h, bfu* dst, const float* rs) {
;   const int tid = TID(), lane = tid & 63, w = tid >> 6, wm = w >> 1, wn = w & 1, l32 = lane & 31, hi = lane >> 5;
;   if (wn != h) return;
; #pragma unroll
;   for (int mi = 0; mi < 2; ++mi)
; #pragma unroll
;     for (int ni = 0; ni < 4; ++ni)
; #pragma unroll
;       for (int rg = 0; rg < 4; ++rg) {
;         const int row = wm * 64 + mi * 32 + 8 * rg + 4 * hi;
;         float s0 = 1.f, s1 = 1.f, s2 = 1.f, s3 = 1.f;
;         if (rs) { s0 = rs[row]; s1 = rs[row + 1]; s2 = rs[row + 2]; s3 = rs[row + 3]; }
;         const u32x2 v = {cvtpk(acc[mi][ni][4 * rg] * s0, acc[mi][ni][4 * rg + 1] * s1), cvtpk(acc[mi][ni][4 * rg + 2] * s2, acc[mi][ni][4 * rg + 3] * s3)};
;         *reinterpret_cast<u32x2*>(dst + (long)(ni * 32 + l32) * T + row) = v;
;       }
; }
.LBB0_292:
	s_cmp_eq_u64 s[2:3], 0
	s_cbranch_scc1 .LBB0_296
	v_mov_b32_e32 v176, v202
	s_nop 0
	v_and_b32_e32 v178, 64, v176
	v_cmp_ne_u32_e32 vcc, 0, v178
	s_and_saveexec_b64 s[0:1], vcc
	s_cbranch_execz .LBB0_295
	v_and_b32_e32 v179, 31, v176
	v_ashrrev_i32_e32 v178, 1, v176
	v_lshrrev_b32_e32 v176, 3, v176
	v_and_b32_e32 v176, 4, v176
	v_and_or_b32 v178, v178, s13, v176
	v_mul_u32_u24_e32 v176, 0x900, v179
	v_lshlrev_b32_e32 v176, 1, v176
	v_ashrrev_i32_e32 v179, 31, v178
	v_lshl_add_u64 v[180:181], s[2:3], 0, v[176:177]
	v_lshlrev_b64 v[196:197], 1, v[178:179]
	v_cvt_pk_bf16_f32 v194, v112, v113
	v_cvt_pk_bf16_f32 v195, v114, v115
	v_lshl_add_u64 v[198:199], v[180:181], 0, v[196:197]
	global_store_dwordx2 v[198:199], v[194:195], off
	v_or_b32_e32 v194, 8, v178
	v_cvt_pk_bf16_f32 v200, v116, v117
	v_cvt_pk_bf16_f32 v201, v118, v119
	v_cvt_pk_bf16_f32 v206, v124, v125
	v_cvt_pk_bf16_f32 v207, v126, v127
	v_ashrrev_i32_e32 v195, 31, v194
	global_store_dwordx2 v[198:199], v[200:201], off offset:16
	v_or_b32_e32 v200, 16, v178
	v_cvt_pk_bf16_f32 v204, v120, v121
	v_cvt_pk_bf16_f32 v205, v122, v123
	global_store_dwordx2 v[198:199], v[206:207], off offset:48
	v_lshl_add_u64 v[206:207], v[180:181], 0, s[14:15]
	v_ashrrev_i32_e32 v201, 31, v200
	global_store_dwordx2 v[198:199], v[204:205], off offset:32
	v_or_b32_e32 v204, 24, v178
	v_cvt_pk_bf16_f32 v208, v96, v97
	v_cvt_pk_bf16_f32 v209, v98, v99
	v_lshl_add_u64 v[210:211], v[206:207], 0, v[196:197]
	v_lshlrev_b64 v[194:195], 1, v[194:195]
	v_ashrrev_i32_e32 v205, 31, v204
	global_store_dwordx2 v[210:211], v[208:209], off
	v_cvt_pk_bf16_f32 v208, v100, v101
	v_cvt_pk_bf16_f32 v209, v102, v103
	v_lshl_add_u64 v[210:211], v[206:207], 0, v[194:195]
	v_lshlrev_b64 v[200:201], 1, v[200:201]
	global_store_dwordx2 v[210:211], v[208:209], off
	v_cvt_pk_bf16_f32 v208, v104, v105
	v_cvt_pk_bf16_f32 v209, v106, v107
	v_lshl_add_u64 v[210:211], v[206:207], 0, v[200:201]
	v_lshlrev_b64 v[204:205], 1, v[204:205]
	global_store_dwordx2 v[210:211], v[208:209], off
	v_cvt_pk_bf16_f32 v208, v108, v109
	v_cvt_pk_bf16_f32 v209, v110, v111
	v_lshl_add_u64 v[210:211], v[206:207], 0, v[204:205]
	global_store_dwordx2 v[210:211], v[208:209], off
	v_lshl_add_u64 v[208:209], v[180:181], 0, s[16:17]
	v_cvt_pk_bf16_f32 v210, v80, v81
	v_cvt_pk_bf16_f32 v211, v82, v83
	v_lshl_add_u64 v[212:213], v[208:209], 0, v[196:197]
	global_store_dwordx2 v[212:213], v[210:211], off
	v_cvt_pk_bf16_f32 v210, v84, v85
	v_cvt_pk_bf16_f32 v211, v86, v87
	v_lshl_add_u64 v[212:213], v[208:209], 0, v[194:195]
	global_store_dwordx2 v[212:213], v[210:211], off
	v_cvt_pk_bf16_f32 v210, v88, v89
	v_cvt_pk_bf16_f32 v211, v90, v91
	v_lshl_add_u64 v[212:213], v[208:209], 0, v[200:201]
	global_store_dwordx2 v[212:213], v[210:211], off
	v_cvt_pk_bf16_f32 v210, v92, v93
	v_cvt_pk_bf16_f32 v211, v94, v95
	v_lshl_add_u64 v[212:213], v[208:209], 0, v[204:205]
	v_lshl_add_u64 v[180:181], v[180:181], 0, s[46:47]
	global_store_dwordx2 v[212:213], v[210:211], off
	v_cvt_pk_bf16_f32 v210, v64, v65
	v_cvt_pk_bf16_f32 v211, v66, v67
	v_lshl_add_u64 v[196:197], v[180:181], 0, v[196:197]
	global_store_dwordx2 v[196:197], v[210:211], off
	v_cvt_pk_bf16_f32 v196, v68, v69
	v_cvt_pk_bf16_f32 v197, v70, v71
	v_lshl_add_u64 v[194:195], v[180:181], 0, v[194:195]
	global_store_dwordx2 v[194:195], v[196:197], off
	v_cvt_pk_bf16_f32 v194, v72, v73
	v_cvt_pk_bf16_f32 v195, v74, v75
	v_lshl_add_u64 v[196:197], v[180:181], 0, v[200:201]
	global_store_dwordx2 v[196:197], v[194:195], off
	v_cvt_pk_bf16_f32 v194, v76, v77
	v_cvt_pk_bf16_f32 v195, v78, v79
	v_lshl_add_u64 v[196:197], v[180:181], 0, v[204:205]
	global_store_dwordx2 v[196:197], v[194:195], off
	v_or_b32_e32 v194, 32, v178
	v_cvt_pk_bf16_f32 v196, v48, v49
	v_cvt_pk_bf16_f32 v197, v50, v51
	v_ashrrev_i32_e32 v195, 31, v194
	global_store_dwordx2 v[198:199], v[196:197], off offset:64
	v_or_b32_e32 v196, 40, v178
	v_cvt_pk_bf16_f32 v200, v52, v53
	v_cvt_pk_bf16_f32 v201, v54, v55
	v_cvt_pk_bf16_f32 v204, v56, v57
	v_cvt_pk_bf16_f32 v205, v58, v59
	v_ashrrev_i32_e32 v197, 31, v196
	global_store_dwordx2 v[198:199], v[200:201], off offset:80
	v_or_b32_e32 v200, 48, v178
	global_store_dwordx2 v[198:199], v[204:205], off offset:96
	v_cvt_pk_bf16_f32 v204, v60, v61
	v_cvt_pk_bf16_f32 v205, v62, v63
	v_lshlrev_b64 v[194:195], 1, v[194:195]
	v_ashrrev_i32_e32 v201, 31, v200
	v_or_b32_e32 v178, 56, v178
	global_store_dwordx2 v[198:199], v[204:205], off offset:112
	v_cvt_pk_bf16_f32 v198, v32, v33
	v_cvt_pk_bf16_f32 v199, v34, v35
	v_lshl_add_u64 v[204:205], v[206:207], 0, v[194:195]
	v_lshlrev_b64 v[196:197], 1, v[196:197]
	v_ashrrev_i32_e32 v179, 31, v178
	global_store_dwordx2 v[204:205], v[198:199], off
	v_cvt_pk_bf16_f32 v198, v36, v37
	v_cvt_pk_bf16_f32 v199, v38, v39
	v_lshl_add_u64 v[204:205], v[206:207], 0, v[196:197]
	v_lshlrev_b64 v[200:201], 1, v[200:201]
	global_store_dwordx2 v[204:205], v[198:199], off
	v_cvt_pk_bf16_f32 v198, v40, v41
	v_cvt_pk_bf16_f32 v199, v42, v43
	v_lshl_add_u64 v[204:205], v[206:207], 0, v[200:201]
	v_lshlrev_b64 v[178:179], 1, v[178:179]
	global_store_dwordx2 v[204:205], v[198:199], off
	v_cvt_pk_bf16_f32 v198, v44, v45
	v_cvt_pk_bf16_f32 v199, v46, v47
	v_lshl_add_u64 v[204:205], v[206:207], 0, v[178:179]
	global_store_dwordx2 v[204:205], v[198:199], off
	v_cvt_pk_bf16_f32 v198, v16, v17
	v_cvt_pk_bf16_f32 v199, v18, v19
	v_lshl_add_u64 v[204:205], v[208:209], 0, v[194:195]
	global_store_dwordx2 v[204:205], v[198:199], off
	v_cvt_pk_bf16_f32 v198, v20, v21
	v_cvt_pk_bf16_f32 v199, v22, v23
	v_lshl_add_u64 v[204:205], v[208:209], 0, v[196:197]
	global_store_dwordx2 v[204:205], v[198:199], off
	v_cvt_pk_bf16_f32 v198, v24, v25
	v_cvt_pk_bf16_f32 v199, v26, v27
	v_lshl_add_u64 v[204:205], v[208:209], 0, v[200:201]
	global_store_dwordx2 v[204:205], v[198:199], off
	v_cvt_pk_bf16_f32 v198, v28, v29
	v_cvt_pk_bf16_f32 v199, v30, v31
	v_lshl_add_u64 v[204:205], v[208:209], 0, v[178:179]
	global_store_dwordx2 v[204:205], v[198:199], off
	v_cvt_pk_bf16_f32 v198, v0, v1
	v_cvt_pk_bf16_f32 v199, v2, v3
	v_lshl_add_u64 v[194:195], v[180:181], 0, v[194:195]
	global_store_dwordx2 v[194:195], v[198:199], off
	v_cvt_pk_bf16_f32 v194, v4, v5
	v_cvt_pk_bf16_f32 v195, v6, v7
	v_lshl_add_u64 v[196:197], v[180:181], 0, v[196:197]
	global_store_dwordx2 v[196:197], v[194:195], off
	v_cvt_pk_bf16_f32 v194, v8, v9
	v_cvt_pk_bf16_f32 v195, v10, v11
	v_lshl_add_u64 v[196:197], v[180:181], 0, v[200:201]
	global_store_dwordx2 v[196:197], v[194:195], off
	v_cvt_pk_bf16_f32 v194, v12, v13
	v_cvt_pk_bf16_f32 v195, v14, v15
	v_lshl_add_u64 v[178:179], v[180:181], 0, v[178:179]
	global_store_dwordx2 v[178:179], v[194:195], off

;   DI const float* ab_b_if() const { return (const float*)sp[9]; }
; DI float logsig(float v) { return fminf(v, 0.f) - log1pf(__expf(-fabsf(v))); }
; DI void epi_in0(const Params& p, float* Cs, int m0, int n0) {
;     ...
;     for (int sidx = w; sidx < 32; sidx += 4) {
;       const int ch = sidx & 1, dh = sidx >> 1, dir = dh >> 3, head = dh & 7, row = ch * 64 + lane;
;       const float ig = Cs[row * CLD + dir * 8 + head] + p.ab_b_if()[dir * 8 + head];
;       const float f = logsig(Cs[row * CLD + 16 + dir * 8 + head] + p.ab_b_if()[16 + dir * 8 + head]);
;       float bc = f;
;       for (int off = 1; off < 64; off <<= 1) {
;         const float yu = __shfl_up(bc, off), yd = __shfl_down(bc, off);
;         const bool ok = dir == 0 ? lane >= off : lane + off < 64;
.LBB0_308:
	v_ashrrev_i32_e32 v19, 4, v11
	v_bfe_u32 v18, v11, 1, 3
	v_lshlrev_b32_e32 v24, 3, v19
	v_and_or_b32 v176, v17, 64, v4
	v_or_b32_e32 v22, v24, v18
	v_mul_u32_u24_e32 v2, 0x210, v176
	v_lshlrev_b32_e32 v3, 5, v19
	v_lshlrev_b32_e32 v20, 2, v18
	v_ashrrev_i32_e32 v23, 31, v22
	v_add3_u32 v2, v2, v3, v20
	s_waitcnt lgkmcnt(0)
	v_lshl_add_u64 v[20:21], v[22:23], 2, v[0:1]
	v_ashrrev_i32_e32 v23, 31, v24
	v_lshl_add_u64 v[22:23], v[22:23], 2, v[0:1]
	global_load_dword v20, v[20:21], off
	ds_read2_b32 v[2:3], v2 offset1:16
	global_load_dword v21, v[22:23], off offset:64
	v_add_u32_e32 v17, 0x100, v17
	s_waitcnt vmcnt(0) lgkmcnt(0)
	v_add_f32_e32 v2, v2, v20
	v_add_f32_e32 v3, v3, v21
	v_min_f32_e32 v21, 0, v3
	v_mul_f32_e64 v3, |v3|, s19
	v_exp_f32_e32 v3, v3
	v_cmp_gt_u32_e64 s[18:19], 16, v11
	s_xor_b64 s[28:29], s[16:17], s[18:19]
	v_add_f32_e32 v24, 1.0, v3
	v_add_f32_e32 v22, -1.0, v24
	v_sub_f32_e32 v23, v22, v24
	v_add_f32_e32 v23, 1.0, v23
	v_sub_f32_e32 v22, v3, v22
	v_add_f32_e32 v25, v22, v23
	v_frexp_mant_f32_e32 v22, v24
	v_cmp_gt_f32_e64 s[0:1], s20, v22
	v_cvt_f64_f32_e32 v[22:23], v24
	v_frexp_exp_i32_f64_e32 v22, v[22:23]
	v_subbrev_co_u32_e64 v22, s[0:1], 0, v22, s[0:1]
	v_sub_u32_e32 v23, 0, v22
	v_ldexp_f32 v24, v24, v23
	v_ldexp_f32 v23, v25, v23
	v_add_f32_e32 v25, -1.0, v24
	v_add_f32_e32 v26, 1.0, v25
	v_sub_f32_e32 v26, v24, v26
	v_add_f32_e32 v26, v23, v26
	v_add_f32_e32 v27, v25, v26
	v_sub_f32_e32 v25, v27, v25
	v_sub_f32_e32 v25, v26, v25
	v_add_f32_e32 v26, 1.0, v24
	v_add_f32_e32 v28, -1.0, v26
	v_sub_f32_e32 v24, v24, v28
	v_add_f32_e32 v23, v23, v24
	v_add_f32_e32 v24, v26, v23
	v_sub_f32_e32 v26, v24, v26
	v_sub_f32_e32 v23, v23, v26
	v_rcp_f32_e32 v26, v24
	v_cvt_f32_i32_e32 v22, v22
	v_cmp_neq_f32_e64 s[0:1], s22, v3
	v_mul_f32_e32 v28, v27, v26
	v_mul_f32_e32 v29, v24, v28
	v_fma_f32 v30, v28, v24, -v29
	v_fmac_f32_e32 v30, v28, v23
	v_add_f32_e32 v31, v29, v30
	v_sub_f32_e32 v32, v27, v31
	v_sub_f32_e32 v27, v27, v32
	v_sub_f32_e32 v29, v31, v29
	v_sub_f32_e32 v27, v27, v31
	v_add_f32_e32 v25, v25, v27
	v_sub_f32_e32 v27, v29, v30
	v_add_f32_e32 v25, v27, v25
	v_add_f32_e32 v27, v32, v25
	v_mul_f32_e32 v29, v26, v27
	v_mul_f32_e32 v30, v24, v29
	v_fma_f32 v24, v29, v24, -v30
	v_fmac_f32_e32 v24, v29, v23
	v_sub_f32_e32 v23, v32, v27
	v_add_f32_e32 v23, v25, v23
	v_add_f32_e32 v25, v30, v24
	v_sub_f32_e32 v31, v27, v25
	v_sub_f32_e32 v27, v27, v31
	v_sub_f32_e32 v30, v25, v30
	v_sub_f32_e32 v25, v27, v25
	v_add_f32_e32 v23, v23, v25
	v_sub_f32_e32 v24, v30, v24
	v_add_f32_e32 v23, v24, v23
	v_add_f32_e32 v24, v28, v29
	v_add_f32_e32 v23, v31, v23
	v_sub_f32_e32 v25, v24, v28
	v_mul_f32_e32 v23, v26, v23
	v_sub_f32_e32 v25, v29, v25
	v_add_f32_e32 v23, v25, v23
	v_mul_f32_e32 v28, 0x3f317218, v22
	v_add_f32_e32 v25, v24, v23
	v_fma_f32 v29, v22, s21, -v28
	v_mul_f32_e32 v26, v25, v25
	v_fmac_f32_e32 v29, 0xb102e308, v22
	v_sub_f32_e32 v22, v25, v24
	v_fmamk_f32 v27, v26, 0x3e9b6dac, v185
	v_sub_f32_e32 v22, v23, v22
	v_add_f32_e32 v23, v28, v29
	v_fmaak_f32 v27, v26, v27, 0x3f2aaada
	v_sub_f32_e32 v24, v23, v28
	v_ldexp_f32 v28, v25, 1
	v_mul_f32_e32 v25, v25, v26
	v_mul_f32_e32 v25, v25, v27
	v_add_f32_e32 v26, v28, v25
	v_sub_f32_e32 v27, v26, v28
	v_ldexp_f32 v22, v22, 1
	v_sub_f32_e32 v25, v25, v27
	v_add_f32_e32 v22, v22, v25
	v_add_f32_e32 v25, v26, v22
	v_sub_f32_e32 v26, v25, v26
	v_sub_f32_e32 v22, v22, v26
	v_add_f32_e32 v26, v23, v25
	v_sub_f32_e32 v27, v26, v23
	v_sub_f32_e32 v28, v26, v27
	v_sub_f32_e32 v24, v29, v24
	v_sub_f32_e32 v23, v23, v28
	v_sub_f32_e32 v25, v25, v27
	v_add_f32_e32 v23, v25, v23
	v_add_f32_e32 v25, v24, v22
	v_sub_f32_e32 v27, v25, v24
	v_sub_f32_e32 v28, v25, v27
	v_sub_f32_e32 v24, v24, v28
	v_sub_f32_e32 v22, v22, v27
	v_add_f32_e32 v23, v25, v23
	v_add_f32_e32 v22, v22, v24
	v_add_f32_e32 v24, v26, v23
	v_sub_f32_e32 v25, v24, v26
	v_sub_f32_e32 v23, v23, v25
	v_add_f32_e32 v22, v22, v23
	v_add_f32_e32 v22, v24, v22
	v_cndmask_b32_e64 v22, v188, v22, s[0:1]
	v_cmp_ngt_f32_e64 s[0:1], -1.0, v3
	v_cndmask_b32_e64 v23, 63, 0, s[18:19]
	v_cmp_eq_u32_e64 s[20:21], v4, v23
	v_cndmask_b32_e64 v22, v189, v22, s[0:1]
	v_cmp_neq_f32_e64 s[0:1], -1.0, v3
	v_cndmask_b32_e64 v24, 0, 1, vcc
	s_nop 0
	v_cndmask_b32_e64 v22, v190, v22, s[0:1]
	v_cmp_lt_f32_e64 s[0:1], |v3|, s23
	s_nop 1
	v_cndmask_b32_e64 v3, v22, v3, s[0:1]
	v_sub_f32_e32 v3, v21, v3
	ds_bpermute_b32 v21, v5, v3
	ds_bpermute_b32 v22, v6, v3
	v_readlane_b32 s0, v254, 27
	v_readlane_b32 s1, v254, 28
	s_waitcnt lgkmcnt(0)
; DI void epi_in0(const Params& p, float* Cs, int m0, int n0) {
;     ...
;       float bc = f;
;       for (int off = 1; off < 64; off <<= 1) {
;         const float yu = __shfl_up(bc, off), yd = __shfl_down(bc, off);
;         const bool ok = dir == 0 ? lane >= off : lane + off < 64;
;         if (ok) bc += dir == 0 ? yu : yd;
;       }
;       const float gs = ig - bc;
;       float cm = gs;
;       for (int off = 1; off < 64; off <<= 1) {
;         const float yu = __shfl_up(cm, off), yd = __shfl_down(cm, off);
;         const bool ok = dir == 0 ? lane >= off : lane + off < 64;
;         if (ok) cm = fmaxf(cm, dir == 0 ? yu : yd);
;       }
;       const long o = ((long)(dir * GB + bg) * 8 + head) * T + t0 + row;
;       gb[o] = bc; gsv[o] = gs; gc[o] = cm;
	v_cndmask_b32_e64 v21, v22, v21, s[18:19]
	v_add_f32_e32 v21, v3, v21
	v_cndmask_b32_e64 v3, v21, v3, s[20:21]
	ds_bpermute_b32 v21, v7, v3
	ds_bpermute_b32 v22, v8, v3
	v_cndmask_b32_e64 v23, 0, 1, s[0:1]
	v_cndmask_b32_e64 v23, v24, v23, s[18:19]
	v_and_b32_e32 v23, 1, v23
	v_cmp_eq_u32_e64 s[22:23], 1, v23
	s_waitcnt lgkmcnt(0)
	v_cndmask_b32_e64 v21, v22, v21, s[18:19]
	v_add_f32_e32 v21, v3, v21
	v_cndmask_b32_e64 v3, v3, v21, s[22:23]
	ds_bpermute_b32 v21, v9, v3
	ds_bpermute_b32 v22, v10, v3
	v_cndmask_b32_e64 v23, 0, 1, s[4:5]
	v_cndmask_b32_e64 v24, 0, 1, s[6:7]
	v_cndmask_b32_e64 v23, v24, v23, s[18:19]
	v_and_b32_e32 v23, 1, v23
	s_waitcnt lgkmcnt(0)
	v_cndmask_b32_e64 v21, v22, v21, s[18:19]
	v_cmp_eq_u32_e64 s[24:25], 1, v23
	v_add_f32_e32 v21, v3, v21
	v_cndmask_b32_e64 v23, 0, 1, s[8:9]
	v_cndmask_b32_e64 v3, v3, v21, s[24:25]
	ds_bpermute_b32 v21, v12, v3
	ds_bpermute_b32 v22, v13, v3
	v_cndmask_b32_e64 v24, 0, 1, s[10:11]
	v_cndmask_b32_e64 v23, v24, v23, s[18:19]
	v_and_b32_e32 v23, 1, v23
	v_cmp_eq_u32_e64 s[0:1], 1, v23
	s_waitcnt lgkmcnt(0)
	v_cndmask_b32_e64 v21, v22, v21, s[18:19]
	v_add_f32_e32 v21, v3, v21
	v_cndmask_b32_e64 v3, v3, v21, s[0:1]
	ds_bpermute_b32 v21, v14, v3
	ds_bpermute_b32 v22, v15, v3
	v_cndmask_b32_e64 v23, 0, 1, s[12:13]
	v_cndmask_b32_e64 v24, 0, 1, s[14:15]
	v_cndmask_b32_e64 v23, v24, v23, s[18:19]
	v_and_b32_e32 v23, 1, v23
	s_waitcnt lgkmcnt(0)
	v_cndmask_b32_e64 v21, v22, v21, s[18:19]
	v_cmp_eq_u32_e64 s[26:27], 1, v23
	v_add_f32_e32 v21, v3, v21
	s_nop 0
	v_cndmask_b32_e64 v3, v3, v21, s[26:27]
	ds_bpermute_b32 v21, v16, v3
	ds_bpermute_b32 v22, v187, v3
	s_waitcnt lgkmcnt(0)
	v_cndmask_b32_e64 v21, v22, v21, s[18:19]
	v_add_f32_e32 v21, v3, v21
	v_cndmask_b32_e64 v21, v3, v21, s[28:29]
	v_sub_f32_e32 v20, v2, v21
	ds_bpermute_b32 v2, v5, v20
	ds_bpermute_b32 v3, v6, v20
	s_waitcnt lgkmcnt(0)
	v_cndmask_b32_e64 v2, v3, v2, s[18:19]
	v_max_f32_e32 v2, v2, v2
	v_max_f32_e32 v2, v20, v2
	v_cndmask_b32_e64 v2, v2, v20, s[20:21]
	ds_bpermute_b32 v3, v7, v2
	ds_bpermute_b32 v22, v8, v2
	s_mov_b32 s21, 0x3f317218
	s_mov_b32 s20, 0x3f2aaaab
	s_waitcnt lgkmcnt(0)
	v_cndmask_b32_e64 v3, v22, v3, s[18:19]
	v_max_f32_e32 v3, v3, v3
	v_max_f32_e32 v3, v2, v3
	v_cndmask_b32_e64 v2, v2, v3, s[22:23]
	ds_bpermute_b32 v3, v9, v2
	ds_bpermute_b32 v22, v10, v2
	s_mov_b32 s23, 0x33800000
	s_mov_b32 s22, 0x7f800000
	s_waitcnt lgkmcnt(0)
	v_cndmask_b32_e64 v3, v22, v3, s[18:19]
	v_max_f32_e32 v3, v3, v3
	v_max_f32_e32 v3, v2, v3
	v_cndmask_b32_e64 v2, v2, v3, s[24:25]
	ds_bpermute_b32 v3, v12, v2
	ds_bpermute_b32 v22, v13, v2
	s_waitcnt lgkmcnt(0)
	v_cndmask_b32_e64 v3, v22, v3, s[18:19]
	v_max_f32_e32 v3, v3, v3
	v_max_f32_e32 v3, v2, v3
	v_cndmask_b32_e64 v2, v2, v3, s[0:1]
	ds_bpermute_b32 v3, v14, v2
	ds_bpermute_b32 v22, v15, v2
	s_waitcnt lgkmcnt(0)
	v_cndmask_b32_e64 v3, v22, v3, s[18:19]
	v_max_f32_e32 v3, v3, v3
	v_max_f32_e32 v3, v2, v3
	v_cndmask_b32_e64 v2, v2, v3, s[26:27]
	ds_bpermute_b32 v3, v16, v2
	ds_bpermute_b32 v22, v187, v2
	s_waitcnt lgkmcnt(0)
	v_cndmask_b32_e64 v3, v22, v3, s[18:19]
	v_max_f32_e32 v3, v3, v3
	v_max_f32_e32 v22, v2, v2
	v_max_f32_e32 v3, v22, v3
	v_cndmask_b32_e64 v22, v2, v3, s[28:29]
	v_lshl_add_u32 v2, v19, 1, s97
	s_movk_i32 s18, 0x900
	v_ashrrev_i32_e32 v19, 31, v2
	v_lshl_or_b32 v18, v2, 3, v18
	v_lshl_add_u64 v[2:3], v[176:177], 0, s[52:53]
	v_mad_u64_u32 v[2:3], s[0:1], v18, s18, v[2:3]
	v_mad_i32_i24 v3, v19, s18, v3
	v_lshlrev_b64 v[2:3], 2, v[2:3]
	v_lshl_add_u64 v[18:19], s[2:3], 0, v[2:3]
	global_store_dword v[18:19], v21, off
	v_lshl_add_u64 v[18:19], s[84:85], 0, v[2:3]
	v_lshl_add_u64 v[2:3], s[62:63], 0, v[2:3]
	global_store_dword v[2:3], v22, off
	v_add_u32_e32 v2, 4, v11
	v_cmp_lt_i32_e64 s[0:1], 27, v11
	s_mov_b32 s19, 0xbfb8aa3b
	s_or_b64 s[88:89], s[0:1], s[88:89]
	v_mov_b32_e32 v11, v2
	global_store_dword v[18:19], v20, off
	s_andn2_b64 exec, exec, s[88:89]
	s_cbranch_execnz .LBB0_308

; DI int TID() { int t = threadIdx.x; asm volatile("" : "+v"(t)); return t; }
; DI bf16x8 pack8f(const float* v) { u32x4 w = {cvtpk(v[0], v[1]), cvtpk(v[2], v[3]), cvtpk(v[4], v[5]), cvtpk(v[6], v[7])}; return __builtin_bit_cast(bf16x8, w); }
; DI void store_R(const float* Cs, int cb, int nc, bfu* dst, long ld, float scale, const float* rs = nullptr) {
;   const int cpr = nc >> 3;
;   for (int u = TID(); u < 128 * cpr; u += NT) {
;     int row = u / cpr, c8 = (u % cpr) * 8; float v[8]; ldrow8(Cs, row, cb + c8, v);
;     float s = rs ? scale * rs[row] : scale;
;     for (int j = 0; j < 8; ++j) v[j] *= s;
;     st8(dst + row * ld + c8, pack8f(v));
;   }
; }
.LBB0_313:
	v_ashrrev_i32_e32 v3, 31, v0
	v_lshrrev_b32_e32 v3, 28, v3
	v_add_u32_e32 v3, v0, v3
	v_add_u32_e32 v4, 0x100, v0
	v_ashrrev_i32_e32 v12, 4, v3
	v_and_b32_e32 v3, -16, v3
	v_cmp_lt_i32_e32 vcc, s54, v0
	v_mov_b32_e32 v0, v4
	v_lshlrev_b32_e32 v4, 7, v12
	v_add_u32_e32 v3, v2, v3
	v_sub_u32_e32 v14, v1, v4
	ds_read_b128 v[4:7], v3
	ds_read_b128 v[8:11], v3 offset:16
	v_ashrrev_i32_e32 v13, 31, v12
	v_lshlrev_b64 v[12:13], 13, v[12:13]
	v_lshl_add_u64 v[12:13], s[2:3], 0, v[12:13]
	v_ashrrev_i32_e32 v15, 31, v14
	s_or_b64 s[4:5], vcc, s[4:5]
	v_add_u32_e32 v2, 0x2000, v2
	v_add_u32_e32 v1, 0x800, v1
	v_lshl_add_u64 v[12:13], v[14:15], 1, v[12:13]
	s_waitcnt lgkmcnt(0)
	v_cvt_pk_bf16_f32 v4, v4, v5
	v_cvt_pk_bf16_f32 v5, v6, v7
	v_cvt_pk_bf16_f32 v6, v8, v9
	v_cvt_pk_bf16_f32 v7, v10, v11
	global_store_dwordx4 v[12:13], v[4:7], off
	s_andn2_b64 exec, exec, s[4:5]
	s_cbranch_execnz .LBB0_313

; DI int TID() { int t = threadIdx.x; asm volatile("" : "+v"(t)); return t; }
; DI bf16x8 pack8f(const float* v) { u32x4 w = {cvtpk(v[0], v[1]), cvtpk(v[2], v[3]), cvtpk(v[4], v[5]), cvtpk(v[6], v[7])}; return __builtin_bit_cast(bf16x8, w); }
; DI void store_R(const float* Cs, int cb, int nc, bfu* dst, long ld, float scale, const float* rs = nullptr) {
;   const int cpr = nc >> 3;
;   for (int u = TID(); u < 128 * cpr; u += NT) {
;     int row = u / cpr, c8 = (u % cpr) * 8; float v[8]; ldrow8(Cs, row, cb + c8, v);
;     float s = rs ? scale * rs[row] : scale;
;     for (int j = 0; j < 8; ++j) v[j] *= s;
;     st8(dst + row * ld + c8, pack8f(v));
;   }
; }
.LBB0_319:
	v_ashrrev_i32_e32 v3, 31, v0
	v_lshrrev_b32_e32 v3, 28, v3
	v_add_u32_e32 v3, v0, v3
	v_add_u32_e32 v4, 0x100, v0
	v_ashrrev_i32_e32 v12, 4, v3
	v_and_b32_e32 v3, -16, v3
	v_cmp_lt_i32_e32 vcc, s54, v0
	v_mov_b32_e32 v0, v4
	v_lshlrev_b32_e32 v4, 7, v12
	v_add_u32_e32 v3, v2, v3
	v_sub_u32_e32 v14, v1, v4
	ds_read_b128 v[4:7], v3
	ds_read_b128 v[8:11], v3 offset:16
	v_ashrrev_i32_e32 v13, 31, v12
	v_lshlrev_b64 v[12:13], 12, v[12:13]
	v_lshl_add_u64 v[12:13], s[2:3], 0, v[12:13]
	v_ashrrev_i32_e32 v15, 31, v14
	s_or_b64 s[4:5], vcc, s[4:5]
	v_add_u32_e32 v2, 0x2000, v2
	v_add_u32_e32 v1, 0x800, v1
	v_lshl_add_u64 v[12:13], v[14:15], 1, v[12:13]
	s_waitcnt lgkmcnt(0)
	v_cvt_pk_bf16_f32 v4, v4, v5
	v_cvt_pk_bf16_f32 v5, v6, v7
	v_cvt_pk_bf16_f32 v6, v8, v9
	v_cvt_pk_bf16_f32 v7, v10, v11
	global_store_dwordx4 v[12:13], v[4:7], off
	s_andn2_b64 exec, exec, s[4:5]
	s_cbranch_execnz .LBB0_319

;   DI const float* c() const { return (const float*)sp[1]; }
; DI int TID() { int t = threadIdx.x; asm volatile("" : "+v"(t)); return t; }
; DI bf16x8 pack8f(const float* v) { u32x4 w = {cvtpk(v[0], v[1]), cvtpk(v[2], v[3]), cvtpk(v[4], v[5]), cvtpk(v[6], v[7])}; return __builtin_bit_cast(bf16x8, w); }
; DI void store_T(const float* Cs, int cb, int nc, bfu* dst, long ldT, float scale, const float* rs = nullptr) {
;   for (int u = TID(); u < nc * 16; u += NT) {
;     int c = u % nc, rc = (u / nc) * 8; float v[8];
;     for (int j = 0; j < 8; ++j) v[j] = Cs[(rc + j) * CLD + cb + c] * (rs ? scale * rs[rc + j] : scale);
;     st8(dst + c * ldT + rc, pack8f(v));
;   }
; }
.LBB0_325:
	v_ashrrev_i32_e32 v3, 31, v1
	v_lshrrev_b32_e32 v3, 25, v3
	v_add_u32_e32 v3, v1, v3
	v_add_u32_e32 v4, 0x100, v1
	v_ashrrev_i32_e32 v3, 7, v3
	v_cmp_lt_i32_e32 vcc, s54, v1
	v_mov_b32_e32 v1, v4
	v_mad_u64_u32 v[6:7], s[6:7], v3, s55, v[2:3]
	v_lshlrev_b32_e32 v4, 3, v3
	v_mad_u64_u32 v[8:9], s[6:7], v3, s96, v[0:1]
	v_add_u32_e32 v3, 0x400, v6
	v_add_u32_e32 v12, 0x800, v6
	v_add_u32_e32 v14, 0xc00, v6
	ds_read2_b32 v[10:11], v6 offset1:132
	ds_read2_b32 v[6:7], v3 offset0:8 offset1:140
	ds_read2_b32 v[12:13], v12 offset0:16 offset1:148
	ds_read2_b32 v[14:15], v14 offset0:24 offset1:156
	v_ashrrev_i32_e32 v9, 31, v8
	v_ashrrev_i32_e32 v5, 31, v4
	v_lshl_add_u64 v[8:9], s[2:3], 0, v[8:9]
	s_or_b64 s[4:5], vcc, s[4:5]
	v_add_u32_e32 v0, 0x120000, v0
	v_add_u32_e32 v2, 0x400, v2
	v_lshl_add_u64 v[8:9], v[4:5], 1, v[8:9]
	s_waitcnt lgkmcnt(0)
	v_cvt_pk_bf16_f32 v4, v10, v11
	v_cvt_pk_bf16_f32 v5, v6, v7
	v_cvt_pk_bf16_f32 v6, v12, v13
	v_cvt_pk_bf16_f32 v7, v14, v15
	global_store_dwordx4 v[8:9], v[4:7], off
	s_andn2_b64 exec, exec, s[4:5]
	s_cbranch_execnz .LBB0_325

; DI int TID() { int t = threadIdx.x; asm volatile("" : "+v"(t)); return t; }
; DI bf16x8 pack8f(const float* v) { u32x4 w = {cvtpk(v[0], v[1]), cvtpk(v[2], v[3]), cvtpk(v[4], v[5]), cvtpk(v[6], v[7])}; return __builtin_bit_cast(bf16x8, w); }
; DI void store_R(const float* Cs, int cb, int nc, bfu* dst, long ld, float scale, const float* rs = nullptr) {
;   const int cpr = nc >> 3;
;   for (int u = TID(); u < 128 * cpr; u += NT) {
;     int row = u / cpr, c8 = (u % cpr) * 8; float v[8]; ldrow8(Cs, row, cb + c8, v);
;     float s = rs ? scale * rs[row] : scale;
;     for (int j = 0; j < 8; ++j) v[j] *= s;
;     st8(dst + row * ld + c8, pack8f(v));
;   }
; }
.LBB0_331:
	v_ashrrev_i32_e32 v3, 31, v0
	v_lshrrev_b32_e32 v3, 28, v3
	v_add_u32_e32 v3, v0, v3
	v_add_u32_e32 v4, 0x100, v0
	v_ashrrev_i32_e32 v12, 4, v3
	v_and_b32_e32 v3, -16, v3
	v_cmp_lt_i32_e32 vcc, s54, v0
	v_mov_b32_e32 v0, v4
	v_lshlrev_b32_e32 v4, 7, v12
	v_add_u32_e32 v3, v2, v3
	v_sub_u32_e32 v14, v1, v4
	ds_read_b128 v[4:7], v3
	ds_read_b128 v[8:11], v3 offset:16
	v_ashrrev_i32_e32 v13, 31, v12
	v_lshlrev_b64 v[12:13], 8, v[12:13]
	v_lshl_add_u64 v[12:13], s[2:3], 0, v[12:13]
	v_ashrrev_i32_e32 v15, 31, v14
	s_or_b64 s[4:5], vcc, s[4:5]
	v_add_u32_e32 v2, 0x2000, v2
	v_add_u32_e32 v1, 0x800, v1
	v_lshl_add_u64 v[12:13], v[14:15], 1, v[12:13]
	s_waitcnt lgkmcnt(0)
	v_cvt_pk_bf16_f32 v4, v4, v5
	v_cvt_pk_bf16_f32 v5, v6, v7
	v_cvt_pk_bf16_f32 v6, v8, v9
	v_cvt_pk_bf16_f32 v7, v10, v11
	global_store_dwordx4 v[12:13], v[4:7], off
	s_andn2_b64 exec, exec, s[4:5]
	s_cbranch_execnz .LBB0_331

; DI int TID() { int t = threadIdx.x; asm volatile("" : "+v"(t)); return t; }
; DI bf16x8 pack8f(const float* v) { u32x4 w = {cvtpk(v[0], v[1]), cvtpk(v[2], v[3]), cvtpk(v[4], v[5]), cvtpk(v[6], v[7])}; return __builtin_bit_cast(bf16x8, w); }
; DI void store_R(const float* Cs, int cb, int nc, bfu* dst, long ld, float scale, const float* rs = nullptr) {
;   const int cpr = nc >> 3;
;   for (int u = TID(); u < 128 * cpr; u += NT) {
;     int row = u / cpr, c8 = (u % cpr) * 8; float v[8]; ldrow8(Cs, row, cb + c8, v);
;     float s = rs ? scale * rs[row] : scale;
;     for (int j = 0; j < 8; ++j) v[j] *= s;
;     st8(dst + row * ld + c8, pack8f(v));
;   }
; }
.LBB0_340:
	v_ashrrev_i32_e32 v3, 31, v0
	v_lshrrev_b32_e32 v3, 28, v3
	v_add_u32_e32 v3, v0, v3
	v_add_u32_e32 v4, 0x100, v0
	v_ashrrev_i32_e32 v12, 4, v3
	v_and_b32_e32 v3, -16, v3
	v_cmp_lt_i32_e32 vcc, s54, v0
	v_mov_b32_e32 v0, v4
	v_lshlrev_b32_e32 v4, 7, v12
	v_add_u32_e32 v3, v2, v3
	v_sub_u32_e32 v14, v1, v4
	ds_read_b128 v[4:7], v3
	ds_read_b128 v[8:11], v3 offset:16
	v_ashrrev_i32_e32 v13, 31, v12
	v_lshlrev_b64 v[12:13], 8, v[12:13]
	v_lshl_add_u64 v[12:13], s[2:3], 0, v[12:13]
	v_ashrrev_i32_e32 v15, 31, v14
	s_waitcnt lgkmcnt(0)
	v_pk_mul_f32 v[4:5], v[4:5], s[48:49] op_sel_hi:[1,0]
	v_pk_mul_f32 v[6:7], v[6:7], s[48:49] op_sel_hi:[1,0]
	v_pk_mul_f32 v[8:9], v[8:9], s[48:49] op_sel_hi:[1,0]
	v_pk_mul_f32 v[10:11], v[10:11], s[48:49] op_sel_hi:[1,0]
	s_or_b64 s[4:5], vcc, s[4:5]
	v_add_u32_e32 v2, 0x2000, v2
	v_add_u32_e32 v1, 0x800, v1
	v_lshl_add_u64 v[12:13], v[14:15], 1, v[12:13]
	v_cvt_pk_bf16_f32 v4, v4, v5
	v_cvt_pk_bf16_f32 v5, v6, v7
	v_cvt_pk_bf16_f32 v6, v8, v9
	v_cvt_pk_bf16_f32 v7, v10, v11
	global_store_dwordx4 v[12:13], v[4:7], off
	s_andn2_b64 exec, exec, s[4:5]
	s_cbranch_execnz .LBB0_340

; DI int TID() { int t = threadIdx.x; asm volatile("" : "+v"(t)); return t; }
; DI bf16x8 pack8f(const float* v) { u32x4 w = {cvtpk(v[0], v[1]), cvtpk(v[2], v[3]), cvtpk(v[4], v[5]), cvtpk(v[6], v[7])}; return __builtin_bit_cast(bf16x8, w); }
; DI void store_R(const float* Cs, int cb, int nc, bfu* dst, long ld, float scale, const float* rs = nullptr) {
;   const int cpr = nc >> 3;
;   for (int u = TID(); u < 128 * cpr; u += NT) {
;     int row = u / cpr, c8 = (u % cpr) * 8; float v[8]; ldrow8(Cs, row, cb + c8, v);
;     float s = rs ? scale * rs[row] : scale;
;     for (int j = 0; j < 8; ++j) v[j] *= s;
;     st8(dst + row * ld + c8, pack8f(v));
;   }
; }
.LBB0_360:
	v_ashrrev_i32_e32 v5, 31, v3
	v_lshrrev_b32_e32 v5, 29, v5
	v_add_u32_e32 v6, 0x100, v3
	v_add_u32_e32 v5, v3, v5
	v_cmp_lt_i32_e32 vcc, s91, v3
	v_mov_b32_e32 v3, v6
	v_ashrrev_i32_e32 v14, 3, v5
	v_mad_u64_u32 v[10:11], s[10:11], v14, s90, v[2:3]
	ds_read_b128 v[6:9], v10
	ds_read_b128 v[10:13], v10 offset:16
	v_lshlrev_b32_e32 v5, 6, v14
	v_ashrrev_i32_e32 v15, 31, v14
	v_sub_u32_e32 v16, v4, v5
	v_lshlrev_b64 v[14:15], 7, v[14:15]
	v_lshl_add_u64 v[14:15], s[2:3], 0, v[14:15]
	v_ashrrev_i32_e32 v17, 31, v16
	s_waitcnt lgkmcnt(0)
	v_pk_mul_f32 v[6:7], v[0:1], v[6:7]
	v_pk_mul_f32 v[8:9], v[0:1], v[8:9]
	v_pk_mul_f32 v[10:11], v[0:1], v[10:11]
	v_pk_mul_f32 v[12:13], v[0:1], v[12:13]
	s_or_b64 s[4:5], vcc, s[4:5]
	v_add_u32_e32 v2, 0x2000, v2
	v_add_u32_e32 v4, 0x800, v4
	v_lshl_add_u64 v[14:15], v[16:17], 1, v[14:15]
	v_cvt_pk_bf16_f32 v6, v6, v7
	v_cvt_pk_bf16_f32 v7, v8, v9
	v_cvt_pk_bf16_f32 v8, v10, v11
	v_cvt_pk_bf16_f32 v9, v12, v13
	global_store_dwordx4 v[14:15], v[6:9], off
	s_andn2_b64 exec, exec, s[4:5]
	s_cbranch_execnz .LBB0_360

; DI int TID() { int t = threadIdx.x; asm volatile("" : "+v"(t)); return t; }
; DI bf16x8 pack8f(const float* v) { u32x4 w = {cvtpk(v[0], v[1]), cvtpk(v[2], v[3]), cvtpk(v[4], v[5]), cvtpk(v[6], v[7])}; return __builtin_bit_cast(bf16x8, w); }
; DI void store_R(const float* Cs, int cb, int nc, bfu* dst, long ld, float scale, const float* rs = nullptr) {
;   const int cpr = nc >> 3;
;   for (int u = TID(); u < 128 * cpr; u += NT) {
;     int row = u / cpr, c8 = (u % cpr) * 8; float v[8]; ldrow8(Cs, row, cb + c8, v);
;     float s = rs ? scale * rs[row] : scale;
;     for (int j = 0; j < 8; ++j) v[j] *= s;
;     st8(dst + row * ld + c8, pack8f(v));
;   }
; }
.LBB0_363:
	v_ashrrev_i32_e32 v5, 31, v3
	v_lshrrev_b32_e32 v5, 29, v5
	v_add_u32_e32 v6, 0x100, v3
	v_add_u32_e32 v5, v3, v5
	v_cmp_lt_i32_e32 vcc, s91, v3
	v_mov_b32_e32 v3, v6
	v_ashrrev_i32_e32 v14, 3, v5
	v_mad_u64_u32 v[10:11], s[6:7], v14, s90, v[2:3]
	ds_read_b128 v[6:9], v10
	ds_read_b128 v[10:13], v10 offset:16
	v_lshlrev_b32_e32 v5, 6, v14
	v_ashrrev_i32_e32 v15, 31, v14
	v_sub_u32_e32 v16, v4, v5
	v_lshlrev_b64 v[14:15], 7, v[14:15]
	v_lshl_add_u64 v[14:15], s[2:3], 0, v[14:15]
	v_ashrrev_i32_e32 v17, 31, v16
	s_waitcnt lgkmcnt(0)
	v_pk_mul_f32 v[6:7], v[0:1], v[6:7]
	v_pk_mul_f32 v[8:9], v[0:1], v[8:9]
	v_pk_mul_f32 v[10:11], v[0:1], v[10:11]
	v_pk_mul_f32 v[12:13], v[0:1], v[12:13]
	s_or_b64 s[4:5], vcc, s[4:5]
	v_add_u32_e32 v2, 0x2000, v2
	v_add_u32_e32 v4, 0x800, v4
	v_lshl_add_u64 v[14:15], v[16:17], 1, v[14:15]
	v_cvt_pk_bf16_f32 v6, v6, v7
	v_cvt_pk_bf16_f32 v7, v8, v9
	v_cvt_pk_bf16_f32 v8, v10, v11
	v_cvt_pk_bf16_f32 v9, v12, v13
	global_store_dwordx4 v[14:15], v[6:9], off
	s_andn2_b64 exec, exec, s[4:5]
	s_cbranch_execnz .LBB0_363
	s_branch .LBB0_193

;   DI const float* x() const { return (const float*)sp[0]; }
; __device__ __forceinline__ unsigned xb_ld(unsigned* p)              { return __hip_atomic_load(p, __ATOMIC_RELAXED, __HIP_MEMORY_SCOPE_AGENT); }
; __device__ __forceinline__ unsigned xb_add(unsigned* p, unsigned v) { return __hip_atomic_fetch_add(p, v, __ATOMIC_RELAXED, __HIP_MEMORY_SCOPE_AGENT); }
; #define XB_SPIN(cond, bar) do { unsigned _sp = 0; while (cond) { __builtin_amdgcn_s_sleep(1); \
;     if ((++_sp & 255u) == 0u) { if (xb_ld(&(bar)[XB_TMO])) break; if (_sp > XB_SPIN_CAP) { atomicAdd(&(bar)[XB_TMO], 1u); break; } } } } while (0)
; __device__ __forceinline__ void xcd_barrier(const XcdBarrier& b) {
;     ...
;         const unsigned old = xb_add(&bar[XB_XSUB(b.x)], 1u);
;         const unsigned gen = old / nloc;
;         if (old + 1u == (gen + 1u) * nloc) {
;             __builtin_amdgcn_fence(__ATOMIC_RELEASE, "agent");
;             asm volatile("s_waitcnt vmcnt(0)" ::: "memory");
;             const unsigned og = xb_add(&bar[XB_TOP], 1u);
;             const unsigned tg = og / nx;
;             if (og + 1u == (tg + 1u) * nx) xb_add(&bar[XB_TOPGEN], 1u);
;             else XB_SPIN(xb_ld(&bar[XB_TOPGEN]) == tg, bar);
;             __builtin_amdgcn_fence(__ATOMIC_ACQUIRE, "agent");
;             xb_add(&bar[XB_XGEN(b.x)], 1u);
;             asm volatile("s_waitcnt vmcnt(0)" ::: "memory");
;         } else {
;             XB_SPIN(xb_ld(&bar[XB_XGEN(b.x)]) == gen, bar);
.LBB0_379:
	s_add_u32 s22, s34, 0xe36d000
	s_addc_u32 s23, s35, 0
	s_lshl_b32 s24, s36, 6
	s_add_i32 s2, s24, 0x500
	s_mov_b32 s3, 0
	s_lshl_b64 s[0:1], s[2:3], 2
	s_add_u32 s0, s22, s0
	s_addc_u32 s1, s23, s1
	v_mov_b32_e32 v1, 1
	v_mov_b64_e32 v[4:5], s[0:1]
	global_atomic_add v1, v[4:5], v1, off sc0
	v_cvt_f32_u32_e32 v3, v2
	v_sub_u32_e32 v4, 0, v2
	v_rcp_iflag_f32_e32 v3, v3
	s_nop 0
	v_mul_f32_e32 v3, 0x4f7ffffe, v3
	v_cvt_u32_f32_e32 v3, v3
	v_mul_lo_u32 v4, v4, v3
	v_mul_hi_u32 v4, v3, v4
	v_add_u32_e32 v3, v3, v4
	s_waitcnt vmcnt(0) lgkmcnt(0)
	v_mul_hi_u32 v3, v1, v3
	v_mul_lo_u32 v5, v3, v2
	v_add_u32_e32 v4, 1, v1
	v_sub_u32_e32 v1, v1, v5
	v_add_u32_e32 v6, 1, v3
	v_cmp_ge_u32_e32 vcc, v1, v2
	v_sub_u32_e32 v5, v1, v2
	s_nop 0
	v_cndmask_b32_e32 v3, v3, v6, vcc
	v_cndmask_b32_e32 v1, v1, v5, vcc
	v_add_u32_e32 v5, 1, v3
	v_cmp_ge_u32_e32 vcc, v1, v2
	s_nop 1
	v_cndmask_b32_e32 v1, v3, v5, vcc
	v_mad_u64_u32 v[2:3], s[0:1], v2, v1, v[2:3]
	v_cmp_ne_u32_e32 vcc, v4, v2
	s_and_saveexec_b64 s[0:1], vcc
	s_xor_b64 s[0:1], exec, s[0:1]
	s_cbranch_execz .LBB0_392
	s_add_i32 s2, s24, 0x900
	s_lshl_b64 s[2:3], s[2:3], 2
	s_add_u32 s4, s22, s2
	s_addc_u32 s5, s23, s3
	v_mov_b64_e32 v[2:3], s[4:5]
	global_load_dword v0, v[2:3], off sc1
	s_waitcnt vmcnt(0) lgkmcnt(0)
	v_cmp_eq_u32_e32 vcc, v0, v1
	s_and_saveexec_b64 s[2:3], vcc
	s_cbranch_execz .LBB0_391
	s_add_u32 s6, s34, 0xe36d200
	s_addc_u32 s7, s35, 0
	s_mov_b32 s25, 1
	s_mov_b64 s[8:9], 0
	s_branch .LBB0_383

;   DI const float* x() const { return (const float*)sp[0]; }
; __device__ __forceinline__ unsigned xb_add(unsigned* p, unsigned v) { return __hip_atomic_fetch_add(p, v, __ATOMIC_RELAXED, __HIP_MEMORY_SCOPE_AGENT); }
; __device__ __forceinline__ void xcd_barrier(const XcdBarrier& b) {
;     ...
;             __builtin_amdgcn_fence(__ATOMIC_ACQUIRE, "agent");
;             xb_add(&bar[XB_XGEN(b.x)], 1u);
;             asm volatile("s_waitcnt vmcnt(0)" ::: "memory");
.LBB0_409:
	s_or_b64 exec, exec, s[0:1]
	s_add_i32 s76, s26, 0x900
	s_lshl_b64 s[0:1], s[76:77], 2
	s_add_u32 s0, s24, s0
	s_addc_u32 s1, s25, s1
	v_mov_b64_e32 v[0:1], s[0:1]
	s_waitcnt vmcnt(0) lgkmcnt(0)
	buffer_inv sc1
	global_atomic_add v[0:1], v208, off
	s_waitcnt vmcnt(0)

; template <bool ML>
; DI void scan_block(const Params& p, int sitem, char* smem) {
;     ...
;   if (ML) { const int which = sitem % 3, rest = sitem / 3; dir = rest & 1; head = (rest >> 1) & 7; bg = rest >> 4; isden = which == 2; dvg = isden ? 0 : which; }
;   else { half = sitem & 1; dvg = (sitem >> 1) & 1; const int rest = sitem >> 2; dir = rest & 1; head = (rest >> 1) & 7; bg = rest >> 4; }
;   const long hb = (long)(bg * 8 + head);
;   const bfu* q = (const bfu*)(G + (ML ? L0_MQ : L1_RQ)) + hb * T * DKS + half * 128;
;   const bfu* k = (const bfu*)(G + (ML ? L0_MK : L1_RK)) + hb * T * DKS + half * 128;
;   const bfu* kT = (const bfu*)(G + (ML ? L0_MKT : L1_RKT)) + (hb * DKS + half * 128) * T;
;   const bfu* vT = (const bfu*)(G + (ML ? L0_MVT : L1_RVT)) + (hb * 256 + dvg * 128) * T;
;   const float* gbp = (const float*)(G + L0_SM + SM_GI) + ((long)(dir * GB + bg) * 8 + head) * T;
;   const float* gsp = (const float*)(G + L0_SM + SM_GF) + ((long)(dir * GB + bg) * 8 + head) * T;
;   const float* gcp = (const float*)(G + L0_SM + SM_GC) + ((long)(dir * GB + bg) * 8 + head) * T;
;   float* dnp = (float*)(G + L0_SM + SM_DN) + ((long)(dir * GB + bg) * 8 + head) * T;
;   bfu* outp = ML ? (bfu*)(G + L0_HN) + ((long)dir * MG + (long)bg * T) * 2048 + head * 256 + dvg * 128 + w * 32
;                  : (bfu*)(G + L1_R) + ((long)(dir * 2 + half) * MG + (long)bg * T) * 2048 + head * 256 + dvg * 128 + w * 32;
;   bfu* qS = (bfu*)smem; bfu* kS = qS + 64 * LQ; bfu* kTS = kS + 64 * LQ; bfu* vTS = kTS + 128 * LT; float* wsm = (float*)(vTS + 128 * LT);
;   float lg2 = 0.f;
;   if (!ML) lg2 = logsig(p.ret_decay()[dir * 8 + head]) * LOG2E;
;   const bf16x8 ones = {0x3F80, 0x3F80, 0x3F80, 0x3F80, 0x3F80, 0x3F80, 0x3F80, 0x3F80};
;   const bool active = !isden || w == 0;
;   const int r16 = tid >> 4, c16 = (tid & 15) * 8, r8 = tid >> 3, c8 = (tid & 7) * 8;
;   bf16x8 ra[4], rb[4];
;   float bN = 0.f, gsN = 0.f, cmN = 0.f;
;     ...
;   __syncthreads();
;   if (!ML && tid < 64) {
;     wsm[128 + tid] = __builtin_amdgcn_exp2f(lg2 * (dir == 0 ? (float)(tid + 1) : (float)(64 - tid)));
;     wsm[192 + tid] = __builtin_amdgcn_exp2f(lg2 * (dir == 0 ? (float)(63 - tid) : (float)tid));
;     wsm[tid] = __builtin_amdgcn_exp2f(lg2 * (dir == 0 ? (float)tid : -(float)tid));
;     wsm[64 + tid] = __builtin_amdgcn_exp2f(lg2 * (dir == 0 ? -(float)tid : (float)tid));
.LBB0_421:
	s_mul_hi_i32 s0, s2, 0x55555556
	s_lshr_b32 s1, s0, 31
	s_add_i32 s0, s0, s1
	s_lshl_b32 s1, s0, 3
	s_or_b32 s1, s1, s33
	s_mul_i32 s0, s0, 3
	s_mul_i32 s18, s1, 3
	s_sub_i32 s0, s2, s0
	s_add_i32 s18, s18, s0
	s_setprio 3
	s_mul_hi_i32 s19, s18, 0x55555556
	s_lshr_b32 s0, s19, 31
	s_add_i32 s19, s19, s0
	s_ashr_i32 s22, s19, 4
	s_bfe_u32 s7, s19, 0x30001
	s_lshl_b32 s0, s22, 3
	v_readlane_b32 s14, v254, 16
	s_or_b32 s2, s0, s7
	v_readlane_b32 s15, v254, 17
	s_bfe_i32 s3, s19, 0x10000
	s_and_b32 s6, s19, 1
	s_mul_i32 s1, s2, 0x90000
	s_mul_hi_i32 s0, s2, 0x90000
	s_add_u32 s4, s14, s1
	s_addc_u32 s5, s15, s0
	s_lshl_b32 s0, s6, 1
	s_add_i32 s0, s0, s22
	s_lshl_b32 s0, s0, 3
	v_mov_b32_e32 v227, v202
	s_or_b32 s10, s0, s7
	s_cmp_eq_u32 s6, 0
	v_lshlrev_b32_e32 v33, 3, v227
	v_and_b32_e32 v34, 0x78, v33
	s_cselect_b64 s[8:9], -1, 0
	s_cmp_eq_u32 s6, 1
	v_ashrrev_i32_e32 v228, 4, v227
	s_cselect_b64 s[0:1], -1, 0
	s_and_b32 s3, s3, 0xc0
	v_lshlrev_b32_e32 v128, 1, v34
	v_add_u32_e32 v0, s3, v228
	v_lshl_add_u64 v[2:3], s[4:5], 0, v[128:129]
	s_mov_b64 s[4:5], 0x3600000
	v_lshl_add_u64 v[130:131], v[2:3], 0, s[4:5]
	s_mov_b64 s[4:5], 0x3f00000
	v_ashrrev_i32_e32 v1, 31, v0
	s_waitcnt vmcnt(0)
	v_lshl_add_u64 v[168:169], v[2:3], 0, s[4:5]
	v_lshlrev_b64 v[24:25], 8, v[0:1]
	s_mov_b64 s[4:5], 0x1000
	v_lshl_add_u64 v[8:9], v[24:25], 0, s[4:5]
	s_mov_b64 s[4:5], 0x3000
	v_lshl_add_u64 v[0:1], v[130:131], 0, v[24:25]
	v_lshl_add_u64 v[4:5], v[168:169], 0, v[24:25]
	v_lshl_add_u64 v[16:17], v[24:25], 0, s[90:91]
	v_lshl_add_u64 v[24:25], v[24:25], 0, s[4:5]
	v_lshl_add_u64 v[10:11], v[130:131], 0, v[8:9]
	v_lshl_add_u64 v[12:13], v[168:169], 0, v[8:9]
	v_lshl_add_u64 v[18:19], v[130:131], 0, v[16:17]
	v_lshl_add_u64 v[20:21], v[168:169], 0, v[16:17]
	v_lshl_add_u64 v[26:27], v[130:131], 0, v[24:25]
	v_lshl_add_u64 v[28:29], v[168:169], 0, v[24:25]
	s_barrier
	global_load_dwordx4 v[0:3], v[0:1], off
	s_nop 0
	global_load_dwordx4 v[4:7], v[4:5], off
	s_nop 0
	global_load_dwordx4 v[8:11], v[10:11], off
	s_nop 0
	global_load_dwordx4 v[12:15], v[12:13], off
	s_nop 0
	global_load_dwordx4 v[16:19], v[18:19], off
	s_nop 0
	global_load_dwordx4 v[20:23], v[20:21], off
	s_nop 0
	global_load_dwordx4 v[24:27], v[26:27], off
	s_nop 0
	global_load_dwordx4 v[28:31], v[28:29], off
	s_mul_hi_i32 s5, s10, 0x900
	s_mul_i32 s4, s10, 0x900
	s_lshl_b64 s[16:17], s[4:5], 2
	s_add_u32 s12, s14, s16
	s_addc_u32 s13, s15, s17
	s_add_u32 s4, s12, 0xe100000
	s_addc_u32 s5, s13, 0
	s_add_u32 s80, s12, 0xe148000
	s_addc_u32 s81, s13, 0
	s_add_u32 s70, s12, 0xe1f3000
	v_cmp_gt_u32_e64 s[10:11], 64, v227
	s_addc_u32 s71, s13, 0
	v_mov_b32_e32 v66, 0
	v_mov_b32_e32 v64, 0
	v_mov_b32_e32 v65, 0
	s_and_saveexec_b64 s[12:13], s[10:11]
	s_cbranch_execz .LBB0_423
	v_or_b32_e32 v128, s3, v227
	v_lshlrev_b64 v[36:37], 2, v[128:129]
	v_lshl_add_u64 v[38:39], s[70:71], 0, v[36:37]
	v_lshl_add_u64 v[40:41], s[80:81], 0, v[36:37]
	v_lshl_add_u64 v[36:37], s[4:5], 0, v[36:37]
	global_load_dword v65, v[36:37], off
	global_load_dword v64, v[40:41], off
	global_load_dword v66, v[38:39], off
.LBB0_423:
	s_or_b64 exec, exec, s[12:13]
	s_mul_i32 s19, s19, 3
	s_ashr_i32 s3, s2, 31
	s_sub_i32 s18, s18, s19
	s_cmp_eq_u32 s18, 2
	s_cselect_b64 s[94:95], -1, 0
	s_lshl_b64 s[12:13], s[2:3], 8
	s_lshl_b32 s20, s18, 7
	s_cmp_lg_u32 s18, 2
	s_cselect_b64 s[18:19], -1, 0
	s_mul_hi_i32 s23, s2, 0x90000
	s_mul_i32 s24, s2, 0x90000
	s_and_b64 s[2:3], s[18:19], exec
	s_cselect_b32 s20, s20, 0
	s_ashr_i32 s21, s20, 31
	s_add_u32 s2, s12, s20
	s_addc_u32 s3, s13, s21
	s_mulk_i32 s3, 0x1200
	s_mul_hi_u32 s12, s2, 0x1200
	s_add_i32 s12, s12, s3
	s_mulk_i32 s2, 0x1200
	s_add_u32 s2, s14, s2
	s_addc_u32 s3, s15, s12
	s_add_u32 s52, s2, 0x5100000
	s_addc_u32 s53, s3, 0
	s_add_u32 s2, s14, s24
	s_addc_u32 s3, s15, s23
	s_add_u32 s54, s2, 0x4800000
	s_addc_u32 s55, s3, 0
	s_movk_i32 s2, 0x110
	v_mul_lo_u32 v35, v228, s2
	s_and_b64 s[2:3], s[8:9], exec
	s_cselect_b32 s12, 0, 0x180
	v_and_b32_e32 v33, 56, v33
	s_add_u32 s2, s54, s12
	v_ashrrev_i32_e32 v32, 3, v227
	v_lshl_add_u32 v229, v34, 1, v35
	s_addc_u32 s3, s55, 0
	v_lshlrev_b32_e32 v128, 1, v33
	s_waitcnt vmcnt(0) lgkmcnt(0)
	ds_write_b128 v229, v[0:3]
	ds_write_b128 v229, v[4:7] offset:17408
	ds_write_b128 v229, v[8:11] offset:4352
	ds_write_b128 v229, v[12:15] offset:21760
	ds_write_b128 v229, v[16:19] offset:8704
	ds_write_b128 v229, v[20:23] offset:26112
	ds_write_b128 v229, v[24:27] offset:13056
	ds_write_b128 v229, v[28:31] offset:30464
	v_lshl_add_u64 v[8:9], s[2:3], 0, v[128:129]
	v_mad_i64_i32 v[0:1], s[2:3], v32, s60, 0
	v_lshl_add_u64 v[2:3], v[0:1], 1, v[8:9]
	global_load_dwordx4 v[136:139], v[2:3], off
	s_add_u32 s2, s52, s12
	s_addc_u32 s3, s53, 0
	v_lshl_add_u64 v[10:11], s[2:3], 0, v[128:129]
	s_and_b64 vcc, exec, s[94:95]
	s_cbranch_vccnz .LBB0_425
	v_lshl_add_u64 v[2:3], v[0:1], 1, v[10:11]
	global_load_dwordx4 v[140:143], v[2:3], off
	s_branch .LBB0_426

.LBB0_426:
	v_add_u32_e32 v2, 32, v32
	v_mad_i64_i32 v[2:3], s[2:3], v2, s60, 0
	v_lshl_add_u64 v[4:5], v[2:3], 1, v[8:9]
	global_load_dwordx4 v[144:147], v[4:5], off
	v_cndmask_b32_e64 v4, 0, 1, s[18:19]
	v_cmp_ne_u32_e64 s[12:13], 1, v4
	s_andn2_b64 vcc, exec, s[18:19]
	s_cbranch_vccnz .LBB0_428
	v_lshl_add_u64 v[4:5], v[2:3], 1, v[10:11]
	global_load_dwordx4 v[148:151], v[4:5], off
	s_branch .LBB0_429

.LBB0_429:
	v_add_u32_e32 v4, 64, v32
	v_mad_i64_i32 v[4:5], s[2:3], v4, s60, 0
	v_lshl_add_u64 v[6:7], v[4:5], 1, v[8:9]
	global_load_dwordx4 v[152:155], v[6:7], off
	s_and_b64 vcc, exec, s[12:13]
	s_cbranch_vccnz .LBB0_431
	v_lshl_add_u64 v[6:7], v[4:5], 1, v[10:11]
	global_load_dwordx4 v[156:159], v[6:7], off
	s_branch .LBB0_432

.LBB0_432:
	v_add_u32_e32 v6, 0x60, v32
	v_mad_i64_i32 v[6:7], s[2:3], v6, s60, 0
	v_lshl_add_u64 v[8:9], v[6:7], 1, v[8:9]
	global_load_dwordx4 v[160:163], v[8:9], off
	s_and_b64 vcc, exec, s[12:13]
	s_cbranch_vccnz .LBB0_434
	v_lshl_add_u64 v[8:9], v[6:7], 1, v[10:11]
	global_load_dwordx4 v[164:167], v[8:9], off
	s_branch .LBB0_435

; #define SC_STORE_T()                                                                                      \
;   _Pragma("unroll") for (int i = 0; i < 4; ++i) { st8(kTS + (r8 + 32 * i) * LT + c8, ra[i]); st8(vTS + (r8 + 32 * i) * LT + c8, rb[i]); }
; template <bool ML>
; DI void scan_block(const Params& p, int sitem, char* smem) {
;     ...
;   for (int ci = 0; ci < 36; ++ci) {
;     const int p0 = SC_CHUNK(ci) * 64;
;     __syncthreads();
;     SC_STORE_T();
;     const float b = bN, gs = gsN, cm = cmN;
;     if (ci + 1 < 36) SC_LOAD_QK(SC_CHUNK(ci + 1) * 64);
.LBB0_437:
	s_add_i32 s6, s7, 1
	s_cmp_lg_u32 s7, 35
	s_cselect_b64 s[54:55], -1, 0
	s_cmp_eq_u32 s7, 35
	s_waitcnt lgkmcnt(0)
	s_barrier
	s_waitcnt vmcnt(0)
	ds_write_b128 v240, v[136:139] offset:34816
	ds_write_b128 v240, v[140:143] offset:53248
	ds_write_b128 v240, v[144:147] offset:39424
	ds_write_b128 v240, v[148:151] offset:57856
	ds_write_b128 v240, v[152:155] offset:44032
	ds_write_b128 v240, v[156:159] offset:62464
	ds_write_b128 v240, v[160:163] offset:48640
	ds_write_b128 v241, v[164:167] offset:62464
	s_cbranch_scc1 .LBB0_456
	s_cmp_gt_u32 s7, 2
	s_cselect_b32 s2, 38, 2
	s_sub_i32 s52, s2, s7
	s_and_b64 s[2:3], s[8:9], exec
	s_cselect_b32 s2, s6, s52
	v_lshl_add_u32 v68, s2, 6, v228
	v_ashrrev_i32_e32 v69, 31, v68
	v_lshlrev_b64 v[70:71], 8, v[68:69]
	v_lshl_add_u64 v[72:73], v[130:131], 0, v[70:71]
	v_lshl_add_u64 v[70:71], v[168:169], 0, v[70:71]
	global_load_dwordx4 v[136:139], v[72:73], off
	global_load_dwordx4 v[140:143], v[70:71], off
	v_add_u32_e32 v70, 16, v68
	v_ashrrev_i32_e32 v71, 31, v70
	v_lshlrev_b64 v[70:71], 8, v[70:71]
	v_lshl_add_u64 v[72:73], v[130:131], 0, v[70:71]
	v_lshl_add_u64 v[70:71], v[168:169], 0, v[70:71]
	global_load_dwordx4 v[144:147], v[72:73], off
	global_load_dwordx4 v[148:151], v[70:71], off
	v_add_u32_e32 v70, 32, v68
	v_ashrrev_i32_e32 v71, 31, v70
	v_add_u32_e32 v68, 48, v68
	v_lshlrev_b64 v[70:71], 8, v[70:71]
	v_ashrrev_i32_e32 v69, 31, v68
	v_lshl_add_u64 v[72:73], v[130:131], 0, v[70:71]
	v_lshl_add_u64 v[70:71], v[168:169], 0, v[70:71]
	v_lshlrev_b64 v[68:69], 8, v[68:69]
	global_load_dwordx4 v[152:155], v[72:73], off
	global_load_dwordx4 v[156:159], v[70:71], off
	v_lshl_add_u64 v[70:71], v[130:131], 0, v[68:69]
	v_lshl_add_u64 v[68:69], v[168:169], 0, v[68:69]
	global_load_dwordx4 v[160:163], v[70:71], off
	global_load_dwordx4 v[164:167], v[68:69], off
	v_mov_b32_e32 v249, v65
	v_mov_b32_e32 v250, v64
	v_mov_b32_e32 v251, v66
	s_and_saveexec_b64 s[2:3], s[10:11]
	s_cbranch_execz .LBB0_455
	v_cndmask_b32_e64 v67, 0, 1, s[0:1]
	v_cmp_ne_u32_e64 s[52:53], 1, v67
	s_andn2_b64 vcc, exec, s[0:1]
	s_mov_b32 s76, s6
	s_cbranch_vccnz .LBB0_444
	s_cmp_gt_u32 s7, 2
	s_mov_b64 s[62:63], -1
	s_cbranch_scc0 .LBB0_442
	s_sub_i32 s76, 38, s7
	s_mov_b64 s[62:63], 0

.LBB0_444:
	v_lshl_or_b32 v68, s76, 6, v227
	v_ashrrev_i32_e32 v69, 31, v68
	v_lshl_add_u64 v[68:69], v[68:69], 2, s[4:5]
	global_load_dword v249, v[68:69], off
	s_and_b64 vcc, exec, s[52:53]
	s_mov_b32 s76, s6
	s_cbranch_vccnz .LBB0_449
	s_cmp_gt_u32 s7, 2
	s_mov_b64 s[62:63], -1
	s_cbranch_scc0 .LBB0_447
	s_sub_i32 s76, 38, s7
	s_mov_b64 s[62:63], 0

.LBB0_449:
	v_lshl_or_b32 v68, s76, 6, v227
	v_ashrrev_i32_e32 v69, 31, v68
	v_lshl_add_u64 v[68:69], v[68:69], 2, s[80:81]
	global_load_dword v250, v[68:69], off
	s_and_b64 vcc, exec, s[52:53]
	s_mov_b32 s62, s6
	s_cbranch_vccnz .LBB0_454
	s_cmp_gt_u32 s7, 2
	s_mov_b64 s[52:53], -1
	s_cbranch_scc0 .LBB0_452
	s_sub_i32 s62, 38, s7
	s_mov_b64 s[52:53], 0

.LBB0_454:
	v_lshl_or_b32 v68, s62, 6, v227
	v_ashrrev_i32_e32 v69, 31, v68
	v_lshl_add_u64 v[68:69], v[68:69], 2, s[70:71]
	global_load_dword v251, v[68:69], off

; #define MFMA(a, b, c) __builtin_amdgcn_mfma_f32_32x32x16_bf16((a), (b), (c), 0, 0, 0)
; DI int crow(int r, int hi) { return (r & 3) + 8 * (r >> 2) + 4 * hi; }
; DI unsigned cvtpk(float lo, float hi) { f32x2_t v = {lo, hi}; bf16x2_t b = __builtin_convertvector(v, bf16x2_t); return __builtin_bit_cast(unsigned, b); }
; template <bool ML>
; DI void scan_block(const Params& p, int sitem, char* smem) {
;     ...
;       {
;         f32x16 sa, sb_;
; #pragma unroll
;         for (int r = 0; r < 16; ++r) { sa[r] = 0.f; sb_[r] = 0.f; }
;         const bfu* k1 = kS + (32 + l32) * LQ + hi * 8; const bfu* q1 = qS + (32 + l32) * LQ + hi * 8;
; #pragma unroll 2
;         for (int ks = 0; ks < 8; ks += 2) {
;           sa = MFMA(ld8(k1 + ks * 16), ld8(q1 + ks * 16), sa);
;           sb_ = MFMA(ld8(k1 + ks * 16 + 16), ld8(q1 + ks * 16 + 16), sb_);
;         }
; #pragma unroll
;         for (int r = 0; r < 16; ++r) {
;           const int sl = crow(r, hi);
;           const bool valid = dir == 0 ? sl <= l32 : sl >= l32;
;           float w1;
;           if (ML) w1 = __expf(sB1 + wsm[96 + sl]);
;           else w1 = sB1 * wsm[96 + sl];
;           sa[r] = valid ? (sa[r] + sb_[r]) * w1 : 0.f;
;         }
; #pragma unroll
;         for (int s2 = 0; s2 < 2; ++s2) out1 = MFMA(ld44(v1 + 16 * s2), packacc(sa, s2), out1);
;       }
;       if (!isden) {
;         bfu* orow0 = outp + (long)(p0 + l32) * 2048; bfu* orow1 = orow0 + 32 * 2048;
; #pragma unroll
;         for (int rg = 0; rg < 4; ++rg) {
;           u32x2 va = {cvtpk(out0[4 * rg], out0[4 * rg + 1]), cvtpk(out0[4 * rg + 2], out0[4 * rg + 3])};
;           u32x2 vb = {cvtpk(out1[4 * rg], out1[4 * rg + 1]), cvtpk(out1[4 * rg + 2], out1[4 * rg + 3])};
;           *reinterpret_cast<u32x2*>(orow0 + 8 * rg + 4 * hi) = va;
;           *reinterpret_cast<u32x2*>(orow1 + 8 * rg + 4 * hi) = vb;
;         }
;       } else if (hi == 0) {
;         dnp[p0 + l32] = fmaxf(fabsf(out0[0]), wsm[256 + l32]);
;         dnp[p0 + 32 + l32] = fmaxf(fabsf(out1[0]), wsm[288 + l32]);
;       }
.LBB0_476:
	ds_read_b128 v[192:195], v134 offset:17408
	ds_read_b128 v[196:199], v134
	s_add_i32 s2, s2, 4
	s_cmp_gt_u32 s2, 5
	s_waitcnt lgkmcnt(0)
	v_mfma_f32_32x32x16_bf16 v[112:127], v[192:195], v[196:199], v[112:127]
	ds_read_b128 v[192:195], v134 offset:17440
	ds_read_b128 v[196:199], v134 offset:32
	s_waitcnt lgkmcnt(0)
	v_mfma_f32_32x32x16_bf16 v[96:111], v[192:195], v[196:199], v[96:111]
	ds_read_b128 v[192:195], v134 offset:17472
	ds_read_b128 v[196:199], v134 offset:64
	s_waitcnt lgkmcnt(0)
	v_mfma_f32_32x32x16_bf16 v[112:127], v[192:195], v[196:199], v[112:127]
	ds_read_b128 v[192:195], v134 offset:17504
	ds_read_b128 v[196:199], v134 offset:96
	v_add_u32_e32 v134, 0x80, v134
	s_waitcnt lgkmcnt(0)
	v_mfma_f32_32x32x16_bf16 v[96:111], v[192:195], v[196:199], v[96:111]
	s_cbranch_scc0 .LBB0_476
	ds_read_b128 v[192:195], v242 offset:384
	s_nop 9
	v_add_f32_e32 v96, v112, v96
	v_add_f32_e32 v97, v113, v97
	v_add_f32_e32 v98, v114, v98
	v_add_f32_e32 v99, v115, v99
	s_waitcnt lgkmcnt(0)
	v_add_f32_e32 v112, v133, v193
	v_mul_f32_e32 v112, 0x3fb8aa3b, v112
	v_exp_f32_e32 v112, v112
	v_add_f32_e32 v100, v116, v100
	v_add_f32_e32 v101, v117, v101
	v_add_f32_e32 v104, v120, v104
	v_mul_f32_e32 v97, v97, v112
	v_add_f32_e32 v112, v133, v194
	v_mul_f32_e32 v112, 0x3fb8aa3b, v112
	v_exp_f32_e32 v112, v112
	v_add_f32_e32 v134, v133, v192
	v_mul_f32_e32 v134, 0x3fb8aa3b, v134
	v_exp_f32_e32 v134, v134
	v_mul_f32_e32 v98, v98, v112
	v_add_f32_e32 v112, v133, v195
	v_mul_f32_e32 v112, 0x3fb8aa3b, v112
	v_exp_f32_e32 v112, v112
	v_mul_f32_e32 v96, v96, v134
	v_cndmask_b32_e64 v96, 0, v96, s[18:19]
	v_cndmask_b32_e64 v97, 0, v97, s[20:21]
	v_mul_f32_e32 v99, v99, v112
	ds_read_b128 v[112:115], v244 offset:384
	v_cndmask_b32_e64 v98, 0, v98, s[22:23]
	v_cndmask_b32_e64 v99, 0, v99, s[24:25]
	v_cvt_pk_bf16_f32 v96, v96, v97
	v_cvt_pk_bf16_f32 v97, v98, v99
	s_waitcnt lgkmcnt(0)
	v_add_f32_e32 v112, v133, v112
	v_mul_f32_e32 v112, 0x3fb8aa3b, v112
	v_exp_f32_e32 v112, v112
	s_cmp_gt_u32 s7, 3
	s_cselect_b32 s2, 39, 3
	s_sub_i32 s62, s2, s7
	v_mul_f32_e32 v100, v100, v112
	v_cndmask_b32_e64 v112, 0, v100, s[26:27]
	v_add_f32_e32 v100, v133, v113
	v_mul_f32_e32 v100, 0x3fb8aa3b, v100
	v_exp_f32_e32 v100, v100
	s_and_b64 s[2:3], s[8:9], exec
	s_cselect_b32 s2, s7, s62
	s_lshl_b32 s62, s2, 6
	v_mul_f32_e32 v100, v101, v100
	v_cndmask_b32_e64 v113, 0, v100, s[28:29]
	v_add_f32_e32 v100, v133, v114
	v_mul_f32_e32 v100, 0x3fb8aa3b, v100
	v_exp_f32_e32 v100, v100
	v_add_f32_e32 v101, v118, v102
	v_cvt_pk_bf16_f32 v98, v112, v113
	s_mov_b64 s[2:3], -1
	v_mul_f32_e32 v100, v101, v100
	v_cndmask_b32_e64 v114, 0, v100, s[30:31]
	v_add_f32_e32 v100, v133, v115
	v_mul_f32_e32 v100, 0x3fb8aa3b, v100
	v_exp_f32_e32 v100, v100
	v_add_f32_e32 v101, v119, v103
	s_and_b64 vcc, exec, s[94:95]
	v_mul_f32_e32 v100, v101, v100
	v_cndmask_b32_e64 v115, 0, v100, s[34:35]
	ds_read_b128 v[100:103], v245 offset:384
	v_cvt_pk_bf16_f32 v99, v114, v115
	s_waitcnt lgkmcnt(0)
	v_add_f32_e32 v100, v133, v100
	v_mul_f32_e32 v100, 0x3fb8aa3b, v100
	v_exp_f32_e32 v100, v100
	s_nop 0
	v_mul_f32_e32 v100, v104, v100
	v_cndmask_b32_e64 v116, 0, v100, s[36:37]
	v_add_f32_e32 v100, v133, v101
	v_mul_f32_e32 v100, 0x3fb8aa3b, v100
	v_exp_f32_e32 v100, v100
	v_add_f32_e32 v101, v121, v105
	v_add_f32_e32 v104, v124, v108
	v_mul_f32_e32 v100, v101, v100
	v_cndmask_b32_e64 v117, 0, v100, s[38:39]
	v_add_f32_e32 v100, v133, v102
	v_mul_f32_e32 v100, 0x3fb8aa3b, v100
	v_exp_f32_e32 v100, v100
	v_add_f32_e32 v101, v122, v106
	v_mul_f32_e32 v100, v101, v100
	v_cndmask_b32_e64 v118, 0, v100, s[40:41]
	v_add_f32_e32 v100, v133, v103
	v_mul_f32_e32 v100, 0x3fb8aa3b, v100
	v_exp_f32_e32 v100, v100
	v_add_f32_e32 v101, v123, v107
	v_mul_f32_e32 v100, v101, v100
	v_cndmask_b32_e64 v119, 0, v100, s[42:43]
	ds_read_b128 v[100:103], v246 offset:384
	s_waitcnt lgkmcnt(0)
	v_add_f32_e32 v100, v133, v100
	v_mul_f32_e32 v100, 0x3fb8aa3b, v100
	v_exp_f32_e32 v100, v100
	s_nop 0
	v_mul_f32_e32 v100, v104, v100
	v_cndmask_b32_e64 v108, 0, v100, s[44:45]
	v_add_f32_e32 v100, v133, v101
	v_mul_f32_e32 v100, 0x3fb8aa3b, v100
	v_exp_f32_e32 v100, v100
	v_add_f32_e32 v101, v125, v109
	v_mul_f32_e32 v100, v101, v100
	v_cndmask_b32_e64 v109, 0, v100, s[46:47]
	v_add_f32_e32 v100, v133, v102
	v_mul_f32_e32 v100, 0x3fb8aa3b, v100
	v_exp_f32_e32 v100, v100
	v_add_f32_e32 v101, v126, v110
	v_mul_f32_e32 v100, v101, v100
	v_cndmask_b32_e64 v110, 0, v100, s[48:49]
	v_add_f32_e32 v100, v133, v103
	v_mul_f32_e32 v100, 0x3fb8aa3b, v100
	v_exp_f32_e32 v100, v100
	v_add_f32_e32 v101, v127, v111
	v_mul_f32_e32 v100, v101, v100
	v_cndmask_b32_e64 v111, 0, v100, s[50:51]
	ds_read2_b64 v[100:103], v135 offset0:8 offset1:10
	ds_read2_b64 v[104:107], v135 offset0:12 offset1:14
	s_waitcnt lgkmcnt(0)
	v_mfma_f32_32x32x16_bf16 v[64:79], v[100:103], v[96:99], v[64:79]
	v_cvt_pk_bf16_f32 v96, v116, v117
	v_cvt_pk_bf16_f32 v97, v118, v119
	v_cvt_pk_bf16_f32 v98, v108, v109
	v_cvt_pk_bf16_f32 v99, v110, v111
	s_nop 1
	v_mfma_f32_32x32x16_bf16 v[64:79], v[104:107], v[96:99], v[64:79]
	s_cbranch_vccz .LBB0_481
	s_and_saveexec_b64 s[2:3], s[16:17]
	s_cbranch_execz .LBB0_480
	ds_read_b32 v98, v235 offset:1024
	v_or_b32_e32 v96, s62, v230
	v_max_f32_e64 v99, |v80|, |v80|
	v_ashrrev_i32_e32 v97, 31, v96
	v_lshl_add_u64 v[96:97], v[96:97], 2, s[96:97]
	s_waitcnt lgkmcnt(0)
	v_max_f32_e32 v98, v98, v98
	v_max_f32_e32 v98, v99, v98
	global_store_dword v[96:97], v98, off
	ds_read_b32 v98, v235 offset:1152
	v_max_f32_e64 v99, |v64|, |v64|
	s_waitcnt lgkmcnt(0)
	v_max_f32_e32 v98, v98, v98
	v_max_f32_e32 v98, v99, v98
	global_store_dword v[96:97], v98, off offset:128

; DI unsigned cvtpk(float lo, float hi) { f32x2_t v = {lo, hi}; bf16x2_t b = __builtin_convertvector(v, bf16x2_t); return __builtin_bit_cast(unsigned, b); }
; #define SC_STORE_QK()                                                                                     \
;   _Pragma("unroll") for (int i = 0; i < 4; ++i) { st8(qS + (r16 + 16 * i) * LQ + c16, ra[i]); st8(kS + (r16 + 16 * i) * LQ + c16, rb[i]); }
; template <bool ML>
; DI void scan_block(const Params& p, int sitem, char* smem) {
;     ...
;       if (!isden) {
;         bfu* orow0 = outp + (long)(p0 + l32) * 2048; bfu* orow1 = orow0 + 32 * 2048;
; #pragma unroll
;         for (int rg = 0; rg < 4; ++rg) {
;           u32x2 va = {cvtpk(out0[4 * rg], out0[4 * rg + 1]), cvtpk(out0[4 * rg + 2], out0[4 * rg + 3])};
;           u32x2 vb = {cvtpk(out1[4 * rg], out1[4 * rg + 1]), cvtpk(out1[4 * rg + 2], out1[4 * rg + 3])};
;           *reinterpret_cast<u32x2*>(orow0 + 8 * rg + 4 * hi) = va;
;           *reinterpret_cast<u32x2*>(orow1 + 8 * rg + 4 * hi) = vb;
;         }
;       } else if (hi == 0) {
;         dnp[p0 + l32] = fmaxf(fabsf(out0[0]), wsm[256 + l32]);
;         dnp[p0 + 32 + l32] = fmaxf(fabsf(out1[0]), wsm[288 + l32]);
;       }
;     }
;     __syncthreads();
;     if (ci + 1 < 36) { SC_STORE_QK(); SC_LOAD_T(SC_CHUNK(ci + 1) * 64); }
.LBB0_481:
	s_andn2_b64 vcc, exec, s[2:3]
	s_cbranch_vccnz .LBB0_483
	v_or_b32_e32 v96, s62, v230
	v_ashrrev_i32_e32 v97, 31, v96
	v_lshlrev_b64 v[96:97], 12, v[96:97]
	v_lshl_add_u64 v[96:97], v[170:171], 0, v[96:97]
	v_lshl_add_u64 v[96:97], v[96:97], 0, v[128:129]
	s_nop 3
	v_cvt_pk_bf16_f32 v64, v64, v65
	v_cvt_pk_bf16_f32 v65, v66, v67
	v_add_co_u32_e32 v66, vcc, s72, v96
	s_mov_b64 s[2:3], 0x20000
	s_nop 0
	v_addc_co_u32_e32 v67, vcc, 0, v97, vcc
	v_cvt_pk_bf16_f32 v80, v80, v81
	v_cvt_pk_bf16_f32 v81, v82, v83
	global_store_dwordx2 v[66:67], v[64:65], off
	v_cvt_pk_bf16_f32 v64, v84, v85
	v_cvt_pk_bf16_f32 v65, v86, v87
	v_lshl_add_u64 v[98:99], v[96:97], 0, s[2:3]
	global_store_dwordx2 v[96:97], v[80:81], off
	v_cvt_pk_bf16_f32 v66, v68, v69
	v_cvt_pk_bf16_f32 v67, v70, v71
	global_store_dwordx2 v[96:97], v[64:65], off offset:16
	global_store_dwordx2 v[98:99], v[66:67], off offset:16
	v_cvt_pk_bf16_f32 v64, v88, v89
	v_cvt_pk_bf16_f32 v65, v90, v91
	v_cvt_pk_bf16_f32 v66, v72, v73
	v_cvt_pk_bf16_f32 v67, v74, v75
	global_store_dwordx2 v[96:97], v[64:65], off offset:32
	global_store_dwordx2 v[98:99], v[66:67], off offset:32
	v_cvt_pk_bf16_f32 v64, v92, v93
	v_cvt_pk_bf16_f32 v65, v94, v95
	v_cvt_pk_bf16_f32 v66, v76, v77
	v_cvt_pk_bf16_f32 v67, v78, v79
	global_store_dwordx2 v[96:97], v[64:65], off offset:48
	global_store_dwordx2 v[98:99], v[66:67], off offset:48
.LBB0_483:
	s_or_b64 exec, exec, s[52:53]
	s_andn2_b64 vcc, exec, s[54:55]
	s_waitcnt lgkmcnt(0)
	s_barrier
	s_cbranch_vccnz .LBB0_489
	s_cmp_gt_u32 s7, 2
	s_cselect_b32 s2, 38, 2
	s_sub_i32 s7, s2, s7
	s_and_b64 s[2:3], s[8:9], exec
	s_cselect_b32 s2, s6, s7
	s_lshl_b32 s76, s2, 6
	s_waitcnt vmcnt(0)
	ds_write_b128 v229, v[136:139]
	ds_write_b128 v229, v[140:143] offset:17408
	ds_write_b128 v229, v[144:147] offset:4352
	ds_write_b128 v229, v[148:151] offset:21760
	ds_write_b128 v229, v[152:155] offset:8704
	ds_write_b128 v229, v[156:159] offset:26112
	ds_write_b128 v229, v[160:163] offset:13056
	ds_write_b128 v229, v[164:167] offset:30464
	v_lshl_add_u64 v[64:65], s[76:77], 1, v[172:173]
	global_load_dwordx4 v[136:139], v[64:65], off
	s_and_b64 vcc, exec, s[12:13]
	s_cbranch_vccnz .LBB0_491
	v_lshl_add_u64 v[64:65], s[76:77], 1, v[174:175]
	global_load_dwordx4 v[140:143], v[64:65], off
	v_lshl_add_u64 v[64:65], s[76:77], 1, v[176:177]
	global_load_dwordx4 v[144:147], v[64:65], off
	s_and_b64 vcc, exec, s[12:13]
	s_cbranch_vccz .LBB0_492
.LBB0_486:
	v_mov_b32_e32 v134, v132
	v_mov_b32_e32 v135, v132
	v_mov_b32_e32 v133, v132
	v_mov_b64_e32 v[150:151], v[134:135]
	v_mov_b64_e32 v[148:149], v[132:133]
	v_lshl_add_u64 v[64:65], s[76:77], 1, v[180:181]
	global_load_dwordx4 v[152:155], v[64:65], off
	s_and_b64 vcc, exec, s[12:13]
	s_cbranch_vccz .LBB0_493
.LBB0_487:
	v_mov_b32_e32 v134, v132
	v_mov_b32_e32 v135, v132
	v_mov_b32_e32 v133, v132
	v_mov_b64_e32 v[158:159], v[134:135]
	v_mov_b64_e32 v[156:157], v[132:133]
	v_lshl_add_u64 v[64:65], s[76:77], 1, v[184:185]
	global_load_dwordx4 v[160:163], v[64:65], off
	s_and_b64 vcc, exec, s[12:13]
	s_cbranch_vccz .LBB0_494

.LBB0_491:
	v_mov_b32_e32 v134, v132
	v_mov_b32_e32 v135, v132
	v_mov_b32_e32 v133, v132
	v_mov_b64_e32 v[142:143], v[134:135]
	v_mov_b64_e32 v[140:141], v[132:133]
	v_lshl_add_u64 v[64:65], s[76:77], 1, v[176:177]
	global_load_dwordx4 v[144:147], v[64:65], off
	s_and_b64 vcc, exec, s[12:13]
	s_cbranch_vccnz .LBB0_486
.LBB0_492:
	v_lshl_add_u64 v[64:65], s[76:77], 1, v[178:179]
	global_load_dwordx4 v[148:151], v[64:65], off
	v_lshl_add_u64 v[64:65], s[76:77], 1, v[180:181]
	global_load_dwordx4 v[152:155], v[64:65], off
	s_and_b64 vcc, exec, s[12:13]
	s_cbranch_vccnz .LBB0_487
.LBB0_493:
	v_lshl_add_u64 v[64:65], s[76:77], 1, v[182:183]
	global_load_dwordx4 v[156:159], v[64:65], off
	v_lshl_add_u64 v[64:65], s[76:77], 1, v[184:185]
	global_load_dwordx4 v[160:163], v[64:65], off
	s_and_b64 vcc, exec, s[12:13]
	s_cbranch_vccnz .LBB0_488
.LBB0_494:
	v_lshl_add_u64 v[64:65], s[76:77], 1, v[186:187]
	global_load_dwordx4 v[164:167], v[64:65], off
	s_and_saveexec_b64 s[52:53], s[78:79]
	s_cbranch_execz .LBB0_436
	s_branch .LBB0_490

; DI int TID() { int t = threadIdx.x; asm volatile("" : "+v"(t)); return t; }
; #define ATT_LOADK(key0)                                                                                  \
;   do {                                                                                                   \
;     _Pragma("unroll") for (int i = 0; i < KCH; ++i) { int c = tid + NT * i; kr[i] = ld8(Kp + (long)((key0) + c / CPR) * DK + (c % CPR) * 8); } \
;   } while (0)
; #define ATT_LOADV(key0)                                                                                  \
;   do {                                                                                                   \
;     _Pragma("unroll") for (int i = 0; i < VCH; ++i) { int c = tid + NT * i; vr[i] = ld8(Vtp + (long)(c / VPR) * T + (key0) + (c % VPR) * 8); }  \
;   } while (0)
; template <int DK, int KT>
; DI void attn_item(const bfu* __restrict__ Qp, const bfu* __restrict__ Kp, const bfu* __restrict__ Vtp, int nkeys, bfu* __restrict__ Op, int ldo, char* smem) {
;     ...
;   const int tid = TID(), lane = tid & 63, w = tid >> 6, l32 = lane & 31, hi = lane >> 5;
;   bf16x8 qf[NKS];
;   {
;     const bfu* qrow = Qp + (long)(w * 32 + l32) * DK + hi * 8;
; #pragma unroll
;     for (int ks = 0; ks < NKS; ++ks) qf[ks] = ld8(qrow + ks * 16);
;   }
;   f32x16 o[4];
; #pragma unroll
;   for (int d = 0; d < 4; ++d)
; #pragma unroll
;     for (int r = 0; r < 16; ++r) o[d][r] = 0.f;
;   float m = -1e30f, lsum = 0.f;
;   bf16x8 kr[KCH], vr[VCH];
;     ...
;   ATT_LOADK(0); ATT_LOADV(0);
; template <int layer, int part>
; DI void phase_mix(const Params& p, int cidx, char* smem, int* s_item) {
;     ...
;     if (layer == 0) {
;       int pl, t0, nkeys;
;       if (a < 128) { pl = a >> 4; t0 = CTX + (a & 15) * 128; nkeys = T; }
;       else { a -= 128; pl = a >> 1; t0 = (a & 1) * 128; nkeys = CTX; }
;       const int bh = (pl >> 1) * 8 + xcd, bg = bh >> 4, hv = (bh & 15) * 2 + (pl & 1);
;       attn_item<64, 64>((const bfu*)(G + L0_QD) + ((long)(bg * 32 + hv) * T + t0) * 64, (const bfu*)(G + L0_KD) + (long)(bg * 32 + hv) * T * 64,
;                     (const bfu*)(G + L0_VT) + (long)(bg * 16 + (hv >> 1)) * 128 * T, nkeys, (bfu*)(G + L0_OA) + ((long)bg * T + t0) * 4096 + hv * 128, 4096, smem);
.LBB0_503:
	s_add_i32 s5, s2, -12
	s_lshl_b32 s0, s5, 7
	s_and_b32 s0, s0, 0x780
	s_add_i32 s2, s0, 0x100
	s_lshr_b32 s0, s5, 2
	s_and_b32 s18, s0, 8
	s_or_b32 s16, s18, s33
	s_ashr_i32 s4, s5, 6
	s_lshl_b32 s0, s16, 1
	s_bfe_u32 s19, s5, 0x10004
	s_or_b32 s3, s0, s19
	s_lshl_b32 s20, s4, 5
	s_or_b32 s17, s3, s20
	s_mul_i32 s0, s17, 0x900
	s_mul_hi_i32 s1, s17, 0x900
	s_add_u32 s0, s0, s2
	v_mov_b32_e32 v20, v202
	s_addc_u32 s1, s1, 0
	s_lshl_b64 s[0:1], s[0:1], 7
	v_ashrrev_i32_e32 v0, 1, v20
	v_bfi_b32 v120, s34, v0, v20
	s_add_u32 s8, s68, s0
	v_ashrrev_i32_e32 v121, 31, v120
	s_addc_u32 s9, s69, s1
	s_mul_hi_i32 s1, s17, 0x48000
	s_mul_i32 s17, s17, 0x48000
	v_bfe_u32 v21, v20, 5, 1
	v_lshlrev_b64 v[0:1], 7, v[120:121]
	v_add_u32_e32 v10, 0x300, v20
	s_add_u32 s0, s10, s17
	v_lshl_add_u64 v[0:1], s[8:9], 0, v[0:1]
	v_lshlrev_b32_e32 v122, 4, v21
	v_mov_b32_e32 v123, v129
	v_add_u32_e32 v8, 0x200, v20
	v_ashrrev_i32_e32 v11, 31, v10
	s_addc_u32 s1, s11, s1
	s_lshl_b32 s21, s4, 4
	v_lshl_add_u64 v[0:1], v[0:1], 0, v[122:123]
	v_add_u32_e32 v6, 0x100, v20
	v_ashrrev_i32_e32 v9, 31, v8
	v_lshrrev_b32_e32 v11, 29, v11
	s_or_b32 s16, s16, s21
	global_load_dwordx4 v[108:111], v[0:1], off
	global_load_dwordx4 v[104:107], v[0:1], off offset:32
	global_load_dwordx4 v[100:103], v[0:1], off offset:64
	global_load_dwordx4 v[96:99], v[0:1], off offset:96
	v_ashrrev_i32_e32 v0, 31, v20
	v_ashrrev_i32_e32 v4, 31, v6
	v_lshrrev_b32_e32 v9, 29, v9
	v_add_u32_e32 v11, v10, v11
	s_mul_hi_i32 s17, s16, 0x90000
	s_mul_i32 s16, s16, 0x90000
	v_lshrrev_b32_e32 v0, 29, v0
	v_lshrrev_b32_e32 v4, 29, v4
	v_add_u32_e32 v9, v8, v9
	v_ashrrev_i32_e32 v26, 3, v11
	v_and_b32_e32 v11, -8, v11
	s_add_u32 s16, s12, s16
	v_add_u32_e32 v2, v20, v0
	v_add_u32_e32 v7, v6, v4
	v_ashrrev_i32_e32 v24, 3, v9
	v_and_b32_e32 v9, -8, v9
	v_sub_u32_e32 v27, v10, v11
	s_addc_u32 s17, s13, s17
	v_ashrrev_i32_e32 v0, 3, v2
	v_and_b32_e32 v2, -8, v2
	v_ashrrev_i32_e32 v4, 3, v7
	v_and_b32_e32 v7, -8, v7
	v_sub_u32_e32 v25, v8, v9
	v_lshlrev_b32_e32 v10, 3, v27
	v_sub_u32_e32 v22, v20, v2
	v_sub_u32_e32 v23, v6, v7
	v_lshlrev_b32_e32 v8, 3, v25
	v_ashrrev_i32_e32 v11, 31, v10
	v_mov_b64_e32 v[12:13], s[16:17]
	s_movk_i32 s16, 0x1200
	v_lshlrev_b32_e32 v2, 3, v22
	v_lshlrev_b32_e32 v6, 3, v23
	v_ashrrev_i32_e32 v9, 31, v8
	v_mad_i64_i32 v[14:15], s[8:9], v26, s16, v[12:13]
	v_lshlrev_b64 v[10:11], 1, v[10:11]
	v_ashrrev_i32_e32 v3, 31, v2
	v_ashrrev_i32_e32 v7, 31, v6
	v_lshl_add_u64 v[14:15], v[14:15], 0, v[10:11]
	v_mad_i64_i32 v[16:17], s[8:9], v24, s16, v[12:13]
	v_lshlrev_b64 v[8:9], 1, v[8:9]
	v_lshl_add_u64 v[16:17], v[16:17], 0, v[8:9]
	global_load_dwordx4 v[64:67], v[14:15], off
	global_load_dwordx4 v[68:71], v[16:17], off
	v_mad_i64_i32 v[14:15], s[8:9], v4, s16, v[12:13]
	v_lshlrev_b64 v[6:7], 1, v[6:7]
	v_mad_i64_i32 v[12:13], s[8:9], v0, s16, v[12:13]
	v_lshlrev_b64 v[2:3], 1, v[2:3]
	v_ashrrev_i32_e32 v5, 31, v4
	v_lshl_add_u64 v[14:15], v[14:15], 0, v[6:7]
	v_lshl_add_u64 v[12:13], v[12:13], 0, v[2:3]
	v_ashrrev_i32_e32 v1, 31, v0
	global_load_dwordx4 v[72:75], v[14:15], off
	global_load_dwordx4 v[76:79], v[12:13], off
	v_lshlrev_b64 v[12:13], 7, v[4:5]
	v_lshl_add_u64 v[14:15], s[0:1], 0, v[12:13]
	v_lshlrev_b64 v[16:17], 7, v[0:1]
	v_lshl_add_u64 v[14:15], v[14:15], 0, v[6:7]
	v_lshl_add_u64 v[18:19], s[0:1], 0, v[16:17]
	v_lshl_add_u64 v[18:19], v[18:19], 0, v[2:3]
	global_load_dwordx4 v[112:115], v[14:15], off
	global_load_dwordx4 v[116:119], v[18:19], off
	s_or_b32 s0, s33, s21
	s_or_b32 s0, s0, s18
	s_mul_hi_i32 s1, s0, 0x90000
	s_mul_i32 s0, s0, 0x90000
	v_and_b32_e32 v1, 31, v20
	v_and_b32_e32 v5, 64, v203
	s_add_u32 s0, s0, 0x2400080
	s_waitcnt vmcnt(0)
	v_mul_u32_u24_e32 v145, 0x90, v1
	v_xor_b32_e32 v1, 32, v203
	v_add_u32_e32 v5, 64, v5
	s_addc_u32 s1, s1, 0
	v_cmp_lt_i32_e32 vcc, v1, v5
	v_mov_b64_e32 v[14:15], s[0:1]
	v_mad_i64_i32 v[18:19], s[0:1], v26, s16, v[14:15]
	v_cndmask_b32_e32 v1, v203, v1, vcc
	v_lshlrev_b32_e32 v128, 3, v21
	v_lshlrev_b32_e32 v123, 2, v1
	v_mul_lo_u32 v21, v0, s94
	v_mul_lo_u32 v28, v4, s94
	v_lshl_add_u64 v[124:125], v[18:19], 0, v[10:11]
	v_mad_i64_i32 v[10:11], s[0:1], v24, s16, v[14:15]
	v_mad_i64_i32 v[4:5], s[0:1], v4, s16, v[14:15]
	v_mad_i64_i32 v[0:1], s[0:1], v0, s16, v[14:15]
	v_readlane_b32 s0, v254, 27
	s_lshr_b32 s1, s5, 1
	s_or_b32 s0, s0, s20
	s_and_b32 s1, s1, 16
	s_or_b32 s0, s0, s1
	s_add_i32 s0, s0, s19
	s_mul_hi_i32 s1, s0, 0x48000
	s_mul_i32 s0, s0, 0x48000
	s_add_u32 s0, s0, 0x1202000
	s_addc_u32 s1, s1, 0
	v_lshl_add_u64 v[134:135], v[0:1], 0, v[2:3]
	v_lshl_add_u64 v[0:1], s[0:1], 0, v[12:13]
	v_sub_u32_e32 v20, v122, v128
	v_lshlrev_b32_e32 v22, 4, v22
	v_lshlrev_b32_e32 v23, 4, v23
	v_mul_lo_u32 v29, v24, s94
	v_lshlrev_b32_e32 v25, 4, v25
	v_mul_lo_u32 v30, v26, s94
	v_lshlrev_b32_e32 v27, 4, v27
	v_lshl_add_u64 v[136:137], v[0:1], 0, v[6:7]
	v_lshl_add_u64 v[0:1], s[0:1], 0, v[16:17]
	v_mov_b32_e32 v14, v129
	v_mov_b32_e32 v15, v129
	v_lshl_add_u64 v[126:127], v[10:11], 0, v[8:9]
	v_lshl_add_u64 v[130:131], v[4:5], 0, v[6:7]
	v_lshl_add_u64 v[138:139], v[0:1], 0, v[2:3]
	v_mov_b32_e32 v0, v129
	v_mov_b32_e32 v1, v129
	v_mov_b32_e32 v2, v129
	v_mov_b32_e32 v3, v129
	v_mov_b32_e32 v4, v129
	v_mov_b32_e32 v5, v129
	v_mov_b32_e32 v6, v129
	v_mov_b32_e32 v7, v129
	v_mov_b32_e32 v8, v129
	v_mov_b32_e32 v9, v129
	v_mov_b32_e32 v10, v129
	v_mov_b32_e32 v11, v129
	v_mov_b32_e32 v12, v129
	v_mov_b32_e32 v13, v129
	v_add_u32_e32 v146, v21, v22
	v_add_u32_e32 v147, v28, v23
	v_add_u32_e32 v148, v29, v25
	v_add_u32_e32 v149, v30, v27
	v_add_u32_e32 v150, v20, v145
	v_mov_b64_e32 v[30:31], v[14:15]
	v_mov_b64_e32 v[46:47], v[14:15]
	v_mov_b64_e32 v[62:63], v[14:15]
	v_mov_b32_e32 v141, 0xf149f2ca
	v_mov_b32_e32 v142, 0
	s_mov_b32 s0, 35
	v_mov_b64_e32 v[28:29], v[12:13]
	v_mov_b64_e32 v[26:27], v[10:11]
	v_mov_b64_e32 v[24:25], v[8:9]
	v_mov_b64_e32 v[22:23], v[6:7]
	v_mov_b64_e32 v[20:21], v[4:5]
	v_mov_b64_e32 v[18:19], v[2:3]
	v_mov_b64_e32 v[16:17], v[0:1]
	v_mov_b64_e32 v[44:45], v[12:13]
	v_mov_b64_e32 v[42:43], v[10:11]
	v_mov_b64_e32 v[40:41], v[8:9]
	v_mov_b64_e32 v[38:39], v[6:7]
	v_mov_b64_e32 v[36:37], v[4:5]
	v_mov_b64_e32 v[34:35], v[2:3]
	v_mov_b64_e32 v[32:33], v[0:1]
	v_mov_b64_e32 v[60:61], v[12:13]
	v_mov_b64_e32 v[58:59], v[10:11]
	v_mov_b64_e32 v[56:57], v[8:9]
	v_mov_b64_e32 v[54:55], v[6:7]
	v_mov_b64_e32 v[52:53], v[4:5]
	v_mov_b64_e32 v[50:51], v[2:3]
	v_mov_b64_e32 v[48:49], v[0:1]
; #define MFMA(a, b, c) __builtin_amdgcn_mfma_f32_32x32x16_bf16((a), (b), (c), 0, 0, 0)
;   DI const float* c() const { return (const float*)sp[1]; }
; #define ATT_LOADK(key0)                                                                                  \
;   do {                                                                                                   \
;     _Pragma("unroll") for (int i = 0; i < KCH; ++i) { int c = tid + NT * i; kr[i] = ld8(Kp + (long)((key0) + c / CPR) * DK + (c % CPR) * 8); } \
;   } while (0)
; template <int DK, int KT>
; DI void attn_item(const bfu* __restrict__ Qp, const bfu* __restrict__ Kp, const bfu* __restrict__ Vtp, int nkeys, bfu* __restrict__ Op, int ldo, char* smem) {
;     ...
;   for (int j = 0; j < NTL; ++j) {
;     __syncthreads();
; #pragma unroll
;     for (int i = 0; i < KCH; ++i) { int c = tid + NT * i; st8(Ks + (c / CPR) * LK + (c % CPR) * 8, kr[i]); }
; #pragma unroll
;     for (int i = 0; i < VCH; ++i) { int c = tid + NT * i; st8(Vs + (c / VPR) * LV + (c % VPR) * 8, vr[i]); }
;     __syncthreads();
;     if (j + 1 < NTL) ATT_LOADK((j + 1) * KT);
;     f32x16 sv[NBK];
; #pragma unroll
;     for (int bk = 0; bk < NBK; ++bk)
; #pragma unroll
;       for (int r = 0; r < 16; ++r) sv[bk][r] = 0.f;
;     const bfu* k0p = Ks + l32 * LK + hi * 8;
; #pragma unroll
;     for (int ks = 0; ks < NKS; ++ks)
; #pragma unroll
;       for (int bk = 0; bk < NBK; ++bk) sv[bk] = MFMA(ld8(k0p + bk * 32 * LK + ks * 16), qf[ks], sv[bk]);
;     float mx = sv[0][0];
; #pragma unroll
;     for (int bk = 0; bk < NBK; ++bk)
; #pragma unroll
;       for (int r = 0; r < 16; ++r) mx = fmaxf(mx, sv[bk][r]);
;     mx = fmaxf(mx, __shfl_xor(mx, 32));
;     float mn = m, alpha = 1.f;
;     const bool moved = __builtin_amdgcn_ballot_w64(mx > m + 8.f) != 0ull;
;     if (moved) { mn = fmaxf(m, mx); alpha = __builtin_amdgcn_exp2f(m - mn); m = mn; }
;     float rs = 0.f;
; #pragma unroll
;     for (int bk = 0; bk < NBK; ++bk)
; #pragma unroll
;       for (int r = 0; r < 16; ++r) { sv[bk][r] = __builtin_amdgcn_exp2f(sv[bk][r] - mn); rs += sv[bk][r]; }
;     lsum = lsum * alpha + rs;
;     if (moved) {
; #pragma unroll
;       for (int d = 0; d < 4; ++d)
; #pragma unroll
;         for (int r = 0; r < 16; ++r) o[d][r] *= alpha;
;     }
.LBB0_504:
	s_waitcnt lgkmcnt(0)
	s_barrier
	s_waitcnt vmcnt(0)
	ds_write_b128 v146, v[116:119]
	ds_write_b128 v147, v[112:115]
	ds_write_b128 v146, v[76:79] offset:9216
	ds_write_b128 v147, v[72:75] offset:9216
	ds_write_b128 v148, v[68:71] offset:9216
	ds_write_b128 v149, v[64:67] offset:9216
	v_lshl_add_u64 v[64:65], s[68:69], 0, v[138:139]
	s_waitcnt lgkmcnt(0)
	s_barrier
	global_load_dwordx4 v[116:119], v[64:65], off
	v_lshl_add_u64 v[64:65], s[68:69], 0, v[136:137]
	v_add_u32_e32 v151, v122, v145
	global_load_dwordx4 v[112:115], v[64:65], off
	ds_read_b128 v[64:67], v151
	ds_read_b128 v[152:155], v151 offset:32
	s_waitcnt lgkmcnt(0)
	v_mfma_f32_32x32x16_bf16 v[80:95], v[64:67], v[108:111], 0
	ds_read_b128 v[64:67], v151 offset:4608
	v_mfma_f32_32x32x16_bf16 v[80:95], v[152:155], v[104:107], v[80:95]
	ds_read_b128 v[152:155], v151 offset:4640
	s_waitcnt lgkmcnt(0)
	v_mfma_f32_32x32x16_bf16 v[64:79], v[64:67], v[108:111], 0
	v_mfma_f32_32x32x16_bf16 v[64:79], v[152:155], v[104:107], v[64:79]
	ds_read_b128 v[152:155], v151 offset:64
	s_waitcnt lgkmcnt(0)
	v_mfma_f32_32x32x16_bf16 v[80:95], v[152:155], v[100:103], v[80:95]
	ds_read_b128 v[152:155], v151 offset:4672
	s_waitcnt lgkmcnt(0)
	v_mfma_f32_32x32x16_bf16 v[64:79], v[152:155], v[100:103], v[64:79]
	ds_read_b128 v[152:155], v151 offset:96
	s_waitcnt lgkmcnt(0)
	v_mfma_f32_32x32x16_bf16 v[80:95], v[152:155], v[96:99], v[80:95]
	ds_read_b128 v[152:155], v151 offset:4704
	s_waitcnt lgkmcnt(0)
	v_mfma_f32_32x32x16_bf16 v[64:79], v[152:155], v[96:99], v[64:79]
	s_nop 8
	v_max_f32_e32 v133, v81, v81
	v_max_f32_e32 v140, v80, v80
	v_max_f32_e32 v133, v140, v133
	v_max3_f32 v133, v133, v82, v83
	v_max3_f32 v133, v133, v84, v85
	v_max3_f32 v133, v133, v86, v87
	v_max3_f32 v133, v133, v88, v89
	v_max3_f32 v133, v133, v90, v91
	v_max3_f32 v133, v133, v92, v93
	v_max3_f32 v133, v133, v94, v95
	v_max3_f32 v133, v133, v64, v65
	v_max3_f32 v133, v133, v66, v67
	v_max3_f32 v133, v133, v68, v69
	v_max3_f32 v133, v133, v70, v71
	v_max3_f32 v133, v133, v72, v73
	v_max3_f32 v133, v133, v74, v75
	v_max3_f32 v133, v133, v76, v77
	v_max3_f32 v133, v133, v78, v79
	ds_bpermute_b32 v140, v123, v133
	s_waitcnt lgkmcnt(0)
	v_max_f32_e32 v140, v140, v140
	v_max_f32_e32 v133, v133, v140
	v_add_f32_e32 v140, 0x41000000, v141
	v_cmp_gt_f32_e32 vcc, v133, v140
	v_max_f32_e32 v140, v141, v141
	v_max_f32_e32 v133, v140, v133
	v_sub_f32_e32 v140, v141, v133
	v_exp_f32_e32 v140, v140
	s_cmp_eq_u64 vcc, 0
	s_cselect_b64 s[8:9], -1, 0
	s_and_b64 vcc, exec, s[8:9]
	s_cbranch_vccnz .LBB0_506
	v_pk_mul_f32 v[62:63], v[62:63], v[140:141] op_sel_hi:[1,0]
	v_pk_mul_f32 v[60:61], v[60:61], v[140:141] op_sel_hi:[1,0]
	v_pk_mul_f32 v[58:59], v[58:59], v[140:141] op_sel_hi:[1,0]
	v_pk_mul_f32 v[56:57], v[56:57], v[140:141] op_sel_hi:[1,0]
	v_pk_mul_f32 v[54:55], v[54:55], v[140:141] op_sel_hi:[1,0]
	v_pk_mul_f32 v[52:53], v[52:53], v[140:141] op_sel_hi:[1,0]
	v_pk_mul_f32 v[50:51], v[50:51], v[140:141] op_sel_hi:[1,0]
	v_pk_mul_f32 v[48:49], v[48:49], v[140:141] op_sel_hi:[1,0]
	v_pk_mul_f32 v[46:47], v[46:47], v[140:141] op_sel_hi:[1,0]
	v_pk_mul_f32 v[44:45], v[44:45], v[140:141] op_sel_hi:[1,0]
	v_pk_mul_f32 v[42:43], v[42:43], v[140:141] op_sel_hi:[1,0]
	v_pk_mul_f32 v[40:41], v[40:41], v[140:141] op_sel_hi:[1,0]
	v_pk_mul_f32 v[38:39], v[38:39], v[140:141] op_sel_hi:[1,0]
	v_pk_mul_f32 v[36:37], v[36:37], v[140:141] op_sel_hi:[1,0]
	v_pk_mul_f32 v[34:35], v[34:35], v[140:141] op_sel_hi:[1,0]
	v_pk_mul_f32 v[32:33], v[32:33], v[140:141] op_sel_hi:[1,0]
	v_pk_mul_f32 v[30:31], v[30:31], v[140:141] op_sel_hi:[1,0]
	v_pk_mul_f32 v[28:29], v[28:29], v[140:141] op_sel_hi:[1,0]
	v_pk_mul_f32 v[26:27], v[26:27], v[140:141] op_sel_hi:[1,0]
	v_pk_mul_f32 v[24:25], v[24:25], v[140:141] op_sel_hi:[1,0]
	v_pk_mul_f32 v[22:23], v[22:23], v[140:141] op_sel_hi:[1,0]
	v_pk_mul_f32 v[20:21], v[20:21], v[140:141] op_sel_hi:[1,0]
	v_pk_mul_f32 v[18:19], v[18:19], v[140:141] op_sel_hi:[1,0]
	v_pk_mul_f32 v[16:17], v[16:17], v[140:141] op_sel_hi:[1,0]
	v_pk_mul_f32 v[14:15], v[14:15], v[140:141] op_sel_hi:[1,0]
	v_pk_mul_f32 v[12:13], v[12:13], v[140:141] op_sel_hi:[1,0]
	v_pk_mul_f32 v[10:11], v[10:11], v[140:141] op_sel_hi:[1,0]
	v_pk_mul_f32 v[8:9], v[8:9], v[140:141] op_sel_hi:[1,0]
	v_pk_mul_f32 v[6:7], v[6:7], v[140:141] op_sel_hi:[1,0]
	v_pk_mul_f32 v[4:5], v[4:5], v[140:141] op_sel_hi:[1,0]
	v_pk_mul_f32 v[2:3], v[2:3], v[140:141] op_sel_hi:[1,0]
	v_pk_mul_f32 v[0:1], v[0:1], v[140:141] op_sel_hi:[1,0]
; #define MFMA(a, b, c) __builtin_amdgcn_mfma_f32_32x32x16_bf16((a), (b), (c), 0, 0, 0)
; #define ATT_LOADV(key0)                                                                                  \
;   do {                                                                                                   \
;     _Pragma("unroll") for (int i = 0; i < VCH; ++i) { int c = tid + NT * i; vr[i] = ld8(Vtp + (long)(c / VPR) * T + (key0) + (c % VPR) * 8); }  \
;   } while (0)
; template <int DK, int KT>
; DI void attn_item(const bfu* __restrict__ Qp, const bfu* __restrict__ Kp, const bfu* __restrict__ Vtp, int nkeys, bfu* __restrict__ Op, int ldo, char* smem) {
;     ...
;     float rs = 0.f;
; #pragma unroll
;     for (int bk = 0; bk < NBK; ++bk)
; #pragma unroll
;       for (int r = 0; r < 16; ++r) { sv[bk][r] = __builtin_amdgcn_exp2f(sv[bk][r] - mn); rs += sv[bk][r]; }
;     lsum = lsum * alpha + rs;
;     if (moved) {
; #pragma unroll
;       for (int d = 0; d < 4; ++d)
; #pragma unroll
;         for (int r = 0; r < 16; ++r) o[d][r] *= alpha;
;     }
;     bf16x8 pf[2 * NBK];
; #pragma unroll
;     for (int bk = 0; bk < NBK; ++bk) { pf[2 * bk] = packacc(sv[bk], 0); pf[2 * bk + 1] = packacc(sv[bk], 1); }
;     if (j + 1 < NTL) ATT_LOADV((j + 1) * KT);
; #pragma unroll
;     for (int kk = 0; kk < 2 * NBK; ++kk)
; #pragma unroll
;       for (int d = 0; d < 4; ++d) o[d] = MFMA(ld44(Vs + (d * 32 + l32) * LV + kk * 16 + 4 * hi), pf[kk], o[d]);
.LBB0_506:
	v_cndmask_b32_e64 v141, v133, v141, s[8:9]
	v_sub_f32_e32 v80, v80, v141
	v_exp_f32_e32 v80, v80
	v_sub_f32_e32 v81, v81, v141
	v_exp_f32_e32 v81, v81
	v_sub_f32_e32 v82, v82, v141
	v_exp_f32_e32 v82, v82
	v_sub_f32_e32 v83, v83, v141
	v_exp_f32_e32 v83, v83
	v_sub_f32_e32 v84, v84, v141
	v_add_f32_e32 v133, 0, v80
	v_exp_f32_e32 v84, v84
	v_sub_f32_e32 v85, v85, v141
	v_add_f32_e32 v133, v81, v133
	v_exp_f32_e32 v85, v85
	v_sub_f32_e32 v86, v86, v141
	v_add_f32_e32 v133, v82, v133
	v_exp_f32_e32 v86, v86
	v_sub_f32_e32 v87, v87, v141
	v_add_f32_e32 v133, v83, v133
	v_exp_f32_e32 v87, v87
	v_sub_f32_e32 v88, v88, v141
	v_add_f32_e32 v133, v84, v133
	v_exp_f32_e32 v88, v88
	v_sub_f32_e32 v89, v89, v141
	v_add_f32_e32 v133, v85, v133
	v_exp_f32_e32 v89, v89
	v_sub_f32_e32 v90, v90, v141
	v_add_f32_e32 v133, v86, v133
	v_exp_f32_e32 v90, v90
	v_sub_f32_e32 v91, v91, v141
	v_add_f32_e32 v133, v87, v133
	v_exp_f32_e32 v91, v91
	v_sub_f32_e32 v92, v92, v141
	v_add_f32_e32 v133, v88, v133
	v_exp_f32_e32 v143, v92
	v_sub_f32_e32 v93, v93, v141
	v_add_f32_e32 v133, v89, v133
	v_exp_f32_e32 v144, v93
	v_sub_f32_e32 v93, v94, v141
	v_add_f32_e32 v133, v90, v133
	v_exp_f32_e32 v152, v93
	v_sub_f32_e32 v93, v95, v141
	v_add_f32_e32 v133, v91, v133
	v_exp_f32_e32 v153, v93
	v_sub_f32_e32 v64, v64, v141
	v_add_f32_e32 v92, v143, v133
	v_exp_f32_e32 v64, v64
	v_sub_f32_e32 v65, v65, v141
	v_add_f32_e32 v92, v144, v92
	v_exp_f32_e32 v65, v65
	v_sub_f32_e32 v66, v66, v141
	v_add_f32_e32 v92, v152, v92
	v_exp_f32_e32 v66, v66
	v_sub_f32_e32 v67, v67, v141
	v_add_f32_e32 v92, v153, v92
	v_exp_f32_e32 v67, v67
	v_sub_f32_e32 v68, v68, v141
	v_add_f32_e32 v92, v64, v92
	v_exp_f32_e32 v68, v68
	v_sub_f32_e32 v69, v69, v141
	v_add_f32_e32 v92, v65, v92
	v_exp_f32_e32 v69, v69
	v_sub_f32_e32 v70, v70, v141
	v_add_f32_e32 v92, v66, v92
	v_exp_f32_e32 v70, v70
	v_sub_f32_e32 v71, v71, v141
	v_add_f32_e32 v92, v67, v92
	v_exp_f32_e32 v71, v71
	v_sub_f32_e32 v72, v72, v141
	v_add_f32_e32 v92, v68, v92
	v_exp_f32_e32 v72, v72
	v_sub_f32_e32 v73, v73, v141
	v_add_f32_e32 v92, v69, v92
	v_exp_f32_e32 v73, v73
	v_sub_f32_e32 v74, v74, v141
	v_add_f32_e32 v92, v70, v92
	v_exp_f32_e32 v74, v74
	v_sub_f32_e32 v75, v75, v141
	v_add_f32_e32 v92, v71, v92
	v_exp_f32_e32 v75, v75
	v_sub_f32_e32 v76, v76, v141
	v_add_f32_e32 v92, v72, v92
	v_exp_f32_e32 v76, v76
	v_sub_f32_e32 v77, v77, v141
	v_add_f32_e32 v92, v73, v92
	v_exp_f32_e32 v77, v77
	v_sub_f32_e32 v78, v78, v141
	v_add_f32_e32 v92, v74, v92
	v_exp_f32_e32 v78, v78
	v_sub_f32_e32 v79, v79, v141
	v_add_f32_e32 v92, v75, v92
	v_exp_f32_e32 v79, v79
	v_add_f32_e32 v92, v76, v92
	v_add_f32_e32 v92, v77, v92
	v_add_f32_e32 v92, v78, v92
	v_cvt_pk_bf16_f32 v94, v84, v85
	v_cvt_pk_bf16_f32 v84, v64, v65
	v_lshl_add_u64 v[64:65], s[68:69], 0, v[134:135]
	v_add_f32_e32 v133, v79, v92
	v_cndmask_b32_e64 v92, v140, 1.0, s[8:9]
	v_cvt_pk_bf16_f32 v93, v82, v83
	v_cvt_pk_bf16_f32 v82, v76, v77
	v_cvt_pk_bf16_f32 v83, v78, v79
	global_load_dwordx4 v[76:79], v[64:65], off
	v_lshl_add_u64 v[64:65], s[68:69], 0, v[130:131]
	v_fmac_f32_e32 v133, v142, v92
	v_cvt_pk_bf16_f32 v92, v80, v81
	v_cvt_pk_bf16_f32 v80, v72, v73
	v_cvt_pk_bf16_f32 v81, v74, v75
	global_load_dwordx4 v[72:75], v[64:65], off
	v_lshl_add_u64 v[64:65], s[68:69], 0, v[126:127]
	v_cvt_pk_bf16_f32 v95, v86, v87
	v_cvt_pk_bf16_f32 v86, v68, v69
	v_cvt_pk_bf16_f32 v87, v70, v71
	global_load_dwordx4 v[68:71], v[64:65], off
	v_lshl_add_u64 v[64:65], s[68:69], 0, v[124:125]
	v_add_u32_e32 v140, 0x2000, v150
	v_cvt_pk_bf16_f32 v88, v88, v89
	v_cvt_pk_bf16_f32 v89, v90, v91
	v_cvt_pk_bf16_f32 v91, v152, v153
	v_cvt_pk_bf16_f32 v85, v66, v67
	global_load_dwordx4 v[64:67], v[64:65], off
	ds_read2_b64 v[152:155], v140 offset0:128 offset1:130
	ds_read2_b64 v[156:159], v140 offset0:132 offset1:134
	v_add_u32_e32 v142, 0x3000, v150
	s_waitcnt lgkmcnt(0)
	v_mfma_f32_32x32x16_bf16 v[48:63], v[152:155], v[92:95], v[48:63]
	ds_read2_b64 v[152:155], v142 offset0:192 offset1:194
	v_cvt_pk_bf16_f32 v90, v143, v144
	v_add_u32_e32 v143, 0x4800, v150
	v_add_u32_e32 v144, 0x5800, v150
	s_add_i32 s0, s0, -1
	v_lshl_add_u64 v[124:125], v[124:125], 0, s[92:93]
	v_lshl_add_u64 v[126:127], v[126:127], 0, s[92:93]
	s_waitcnt lgkmcnt(0)
	v_mfma_f32_32x32x16_bf16 v[32:47], v[152:155], v[92:95], v[32:47]
	ds_read2_b64 v[152:155], v143 offset1:2
	v_lshl_add_u64 v[130:131], v[130:131], 0, s[92:93]
	v_lshl_add_u64 v[134:135], v[134:135], 0, s[92:93]
	v_lshl_add_u64 v[136:137], v[136:137], 0, s[90:91]
	v_lshl_add_u64 v[138:139], v[138:139], 0, s[90:91]
	s_cmp_eq_u32 s0, 0
	s_waitcnt lgkmcnt(0)
	v_mfma_f32_32x32x16_bf16 v[16:31], v[152:155], v[92:95], v[16:31]
	ds_read2_b64 v[152:155], v144 offset0:64 offset1:66
	s_waitcnt lgkmcnt(0)
	v_mfma_f32_32x32x16_bf16 v[0:15], v[152:155], v[92:95], v[0:15]
	ds_read2_b64 v[92:95], v142 offset0:196 offset1:198
	s_waitcnt lgkmcnt(0)
	v_mfma_f32_32x32x16_bf16 v[32:47], v[92:95], v[88:91], v[32:47]
	ds_read2_b64 v[92:95], v143 offset0:4 offset1:6
	s_waitcnt lgkmcnt(0)
	v_mfma_f32_32x32x16_bf16 v[16:31], v[92:95], v[88:91], v[16:31]
	ds_read2_b64 v[92:95], v144 offset0:68 offset1:70
	v_mfma_f32_32x32x16_bf16 v[48:63], v[156:159], v[88:91], v[48:63]
	s_waitcnt lgkmcnt(0)
	v_mfma_f32_32x32x16_bf16 v[0:15], v[92:95], v[88:91], v[0:15]
	ds_read2_b64 v[88:91], v140 offset0:136 offset1:138
	s_waitcnt lgkmcnt(0)
	v_mfma_f32_32x32x16_bf16 v[48:63], v[88:91], v[84:87], v[48:63]
	ds_read2_b64 v[88:91], v142 offset0:200 offset1:202
	s_waitcnt lgkmcnt(0)
	v_mfma_f32_32x32x16_bf16 v[32:47], v[88:91], v[84:87], v[32:47]
	ds_read2_b64 v[88:91], v143 offset0:8 offset1:10
	s_waitcnt lgkmcnt(0)
	v_mfma_f32_32x32x16_bf16 v[16:31], v[88:91], v[84:87], v[16:31]
	ds_read2_b64 v[88:91], v144 offset0:72 offset1:74
	s_waitcnt lgkmcnt(0)
	v_mfma_f32_32x32x16_bf16 v[0:15], v[88:91], v[84:87], v[0:15]
	ds_read2_b64 v[84:87], v140 offset0:140 offset1:142
	s_waitcnt lgkmcnt(0)
	v_mfma_f32_32x32x16_bf16 v[48:63], v[84:87], v[80:83], v[48:63]
	ds_read2_b64 v[84:87], v142 offset0:204 offset1:206
	s_waitcnt lgkmcnt(0)
	v_mfma_f32_32x32x16_bf16 v[32:47], v[84:87], v[80:83], v[32:47]
	ds_read2_b64 v[84:87], v143 offset0:12 offset1:14
	s_waitcnt lgkmcnt(0)
	v_mfma_f32_32x32x16_bf16 v[16:31], v[84:87], v[80:83], v[16:31]
	ds_read2_b64 v[84:87], v144 offset0:76 offset1:78
	s_waitcnt lgkmcnt(0)
	v_mfma_f32_32x32x16_bf16 v[0:15], v[84:87], v[80:83], v[0:15]
	s_cbranch_scc1 .LBB0_508
	v_mov_b32_e32 v142, v133
	s_branch .LBB0_504

; #define MFMA(a, b, c) __builtin_amdgcn_mfma_f32_32x32x16_bf16((a), (b), (c), 0, 0, 0)
; #define ATT_LOADV(key0)                                                                                  \
;   do {                                                                                                   \
;     _Pragma("unroll") for (int i = 0; i < VCH; ++i) { int c = tid + NT * i; vr[i] = ld8(Vtp + (long)(c / VPR) * T + (key0) + (c % VPR) * 8); }  \
;   } while (0)
; template <int DK, int KT>
; DI void attn_item(const bfu* __restrict__ Qp, const bfu* __restrict__ Kp, const bfu* __restrict__ Vtp, int nkeys, bfu* __restrict__ Op, int ldo, char* smem) {
;     ...
;     float rs = 0.f;
; #pragma unroll
;     for (int bk = 0; bk < NBK; ++bk)
; #pragma unroll
;       for (int r = 0; r < 16; ++r) { sv[bk][r] = __builtin_amdgcn_exp2f(sv[bk][r] - mn); rs += sv[bk][r]; }
;     lsum = lsum * alpha + rs;
;     if (moved) {
; #pragma unroll
;       for (int d = 0; d < 4; ++d)
; #pragma unroll
;         for (int r = 0; r < 16; ++r) o[d][r] *= alpha;
;     }
;     bf16x8 pf[2 * NBK];
; #pragma unroll
;     for (int bk = 0; bk < NBK; ++bk) { pf[2 * bk] = packacc(sv[bk], 0); pf[2 * bk + 1] = packacc(sv[bk], 1); }
;     if (j + 1 < NTL) ATT_LOADV((j + 1) * KT);
; #pragma unroll
;     for (int kk = 0; kk < 2 * NBK; ++kk)
; #pragma unroll
;       for (int d = 0; d < 4; ++d) o[d] = MFMA(ld44(Vs + (d * 32 + l32) * LV + kk * 16 + 4 * hi), pf[kk], o[d]);
;   }
;     ...
;   const float inv = 1.f / (lsum + __shfl_xor(lsum, 32));
.LBB0_511:
	v_sub_f32_e32 v71, v71, v141
	v_sub_f32_e32 v70, v70, v141
	v_sub_f32_e32 v69, v69, v141
	v_sub_f32_e32 v68, v68, v141
	v_sub_f32_e32 v67, v67, v141
	v_sub_f32_e32 v66, v66, v141
	v_sub_f32_e32 v65, v65, v141
	v_sub_f32_e32 v64, v64, v141
	v_exp_f32_e32 v101, v71
	v_exp_f32_e32 v102, v70
	v_exp_f32_e32 v103, v69
	v_exp_f32_e32 v104, v68
	v_exp_f32_e32 v105, v67
	v_exp_f32_e32 v106, v66
	v_exp_f32_e32 v107, v65
	v_exp_f32_e32 v108, v64
	ds_read2_b64 v[114:117], v140 offset0:128 offset1:130
	ds_read2_b64 v[124:127], v140 offset0:132 offset1:134
	v_cvt_pk_bf16_f32 v111, v106, v105
	v_cvt_pk_bf16_f32 v112, v104, v103
	v_cvt_pk_bf16_f32 v110, v108, v107
	v_cvt_pk_bf16_f32 v113, v102, v101
	v_sub_f32_e32 v79, v79, v141
	v_sub_f32_e32 v78, v78, v141
	s_waitcnt lgkmcnt(1)
	v_mfma_f32_32x32x16_bf16 v[48:63], v[114:117], v[110:113], v[48:63]
	ds_read2_b64 v[114:117], v142 offset0:192 offset1:194
	v_sub_f32_e32 v77, v77, v141
	v_sub_f32_e32 v76, v76, v141
	v_sub_f32_e32 v75, v75, v141
	v_sub_f32_e32 v74, v74, v141
	v_sub_f32_e32 v73, v73, v141
	v_sub_f32_e32 v72, v72, v141
	s_waitcnt lgkmcnt(0)
	v_mfma_f32_32x32x16_bf16 v[32:47], v[114:117], v[110:113], v[32:47]
	ds_read2_b64 v[114:117], v143 offset1:2
	v_exp_f32_e32 v79, v79
	v_exp_f32_e32 v78, v78
	v_exp_f32_e32 v77, v77
	v_exp_f32_e32 v76, v76
	v_exp_f32_e32 v97, v75
	v_exp_f32_e32 v98, v74
	s_waitcnt lgkmcnt(0)
	v_mfma_f32_32x32x16_bf16 v[16:31], v[114:117], v[110:113], v[16:31]
	ds_read2_b64 v[114:117], v144 offset0:64 offset1:66
	v_exp_f32_e32 v99, v73
	v_exp_f32_e32 v100, v72
	v_cvt_pk_bf16_f32 v73, v98, v97
	v_cvt_pk_bf16_f32 v74, v76, v77
	v_cvt_pk_bf16_f32 v75, v78, v79
	v_cvt_pk_bf16_f32 v72, v100, v99
	s_waitcnt lgkmcnt(0)
	v_mfma_f32_32x32x16_bf16 v[0:15], v[114:117], v[110:113], v[0:15]
	ds_read2_b64 v[110:113], v142 offset0:196 offset1:198
	v_sub_f32_e32 v87, v87, v141
	v_sub_f32_e32 v86, v86, v141
	v_sub_f32_e32 v85, v85, v141
	v_sub_f32_e32 v84, v84, v141
	v_sub_f32_e32 v83, v83, v141
	v_sub_f32_e32 v82, v82, v141
	s_waitcnt lgkmcnt(0)
	v_mfma_f32_32x32x16_bf16 v[32:47], v[110:113], v[72:75], v[32:47]
	ds_read2_b64 v[110:113], v143 offset0:4 offset1:6
	v_sub_f32_e32 v81, v81, v141
	v_sub_f32_e32 v80, v80, v141
	v_exp_f32_e32 v87, v87
	v_exp_f32_e32 v86, v86
	v_exp_f32_e32 v85, v85
	v_exp_f32_e32 v84, v84
	s_waitcnt lgkmcnt(0)
	v_mfma_f32_32x32x16_bf16 v[16:31], v[110:113], v[72:75], v[16:31]
	ds_read2_b64 v[110:113], v144 offset0:68 offset1:70
	v_exp_f32_e32 v83, v83
	v_exp_f32_e32 v82, v82
	v_exp_f32_e32 v81, v81
	v_exp_f32_e32 v80, v80
	v_cvt_pk_bf16_f32 v70, v84, v85
	v_cvt_pk_bf16_f32 v69, v82, v83
	v_mfma_f32_32x32x16_bf16 v[48:63], v[124:127], v[72:75], v[48:63]
	v_cvt_pk_bf16_f32 v68, v80, v81
	v_cvt_pk_bf16_f32 v71, v86, v87
	v_sub_f32_e32 v95, v95, v141
	v_sub_f32_e32 v94, v94, v141
	v_sub_f32_e32 v93, v93, v141
	v_sub_f32_e32 v92, v92, v141
	v_sub_f32_e32 v91, v91, v141
	s_waitcnt lgkmcnt(0)
	v_mfma_f32_32x32x16_bf16 v[0:15], v[110:113], v[72:75], v[0:15]
	ds_read2_b64 v[72:75], v140 offset0:136 offset1:138
	v_sub_f32_e32 v90, v90, v141
	v_sub_f32_e32 v89, v89, v141
	v_sub_f32_e32 v88, v88, v141
	v_exp_f32_e32 v95, v95
	v_exp_f32_e32 v94, v94
	v_exp_f32_e32 v93, v93
	s_waitcnt lgkmcnt(0)
	v_mfma_f32_32x32x16_bf16 v[48:63], v[72:75], v[68:71], v[48:63]
	ds_read2_b64 v[72:75], v142 offset0:200 offset1:202
	v_exp_f32_e32 v92, v92
	v_exp_f32_e32 v91, v91
	v_exp_f32_e32 v90, v90
	v_exp_f32_e32 v89, v89
	v_exp_f32_e32 v88, v88
	v_cvt_pk_bf16_f32 v66, v92, v93
	s_waitcnt lgkmcnt(0)
	v_mfma_f32_32x32x16_bf16 v[32:47], v[72:75], v[68:71], v[32:47]
	ds_read2_b64 v[72:75], v143 offset0:8 offset1:10
	v_cvt_pk_bf16_f32 v64, v88, v89
	v_cvt_pk_bf16_f32 v65, v90, v91
	v_cvt_pk_bf16_f32 v67, v94, v95
	s_mul_hi_i32 s1, s4, 0x900
	s_mulk_i32 s4, 0x900
	s_add_u32 s0, s4, s2
	s_waitcnt lgkmcnt(0)
	v_mfma_f32_32x32x16_bf16 v[16:31], v[72:75], v[68:71], v[16:31]
	ds_read2_b64 v[72:75], v144 offset0:72 offset1:74
	s_addc_u32 s1, s1, 0
	s_lshl_b64 s[0:1], s[0:1], 13
	s_add_u32 s0, s14, s0
	s_addc_u32 s1, s15, s1
	s_lshl_b32 s2, s3, 8
	s_add_u32 s0, s0, s2
	s_waitcnt lgkmcnt(0)
	v_mfma_f32_32x32x16_bf16 v[0:15], v[72:75], v[68:71], v[0:15]
	ds_read2_b64 v[68:71], v140 offset0:140 offset1:142
	s_addc_u32 s1, s1, 0
	s_waitcnt lgkmcnt(0)
	v_mfma_f32_32x32x16_bf16 v[48:63], v[68:71], v[64:67], v[48:63]
	ds_read2_b64 v[68:71], v142 offset0:204 offset1:206
	s_waitcnt lgkmcnt(0)
	v_mfma_f32_32x32x16_bf16 v[32:47], v[68:71], v[64:67], v[32:47]
	ds_read2_b64 v[68:71], v143 offset0:12 offset1:14
	s_waitcnt lgkmcnt(0)
	v_mfma_f32_32x32x16_bf16 v[16:31], v[68:71], v[64:67], v[16:31]
	ds_read2_b64 v[68:71], v144 offset0:76 offset1:78
	s_waitcnt lgkmcnt(0)
	v_mfma_f32_32x32x16_bf16 v[0:15], v[68:71], v[64:67], v[0:15]
	v_add_f32_e32 v64, 0, v108
	v_add_f32_e32 v64, v107, v64
	v_add_f32_e32 v64, v106, v64
	v_add_f32_e32 v64, v105, v64
	v_add_f32_e32 v64, v104, v64
	v_add_f32_e32 v64, v103, v64
	v_add_f32_e32 v64, v102, v64
	v_add_f32_e32 v64, v101, v64
	v_add_f32_e32 v64, v100, v64
	v_add_f32_e32 v64, v99, v64
	v_add_f32_e32 v64, v98, v64
	v_add_f32_e32 v64, v97, v64
	v_add_f32_e32 v64, v76, v64
	v_add_f32_e32 v64, v77, v64
	v_add_f32_e32 v64, v78, v64
	v_add_f32_e32 v64, v79, v64
	v_add_f32_e32 v64, v80, v64
	v_add_f32_e32 v64, v81, v64
	v_add_f32_e32 v64, v82, v64
	v_add_f32_e32 v64, v83, v64
	v_add_f32_e32 v64, v84, v64
	v_add_f32_e32 v64, v85, v64
	v_add_f32_e32 v64, v86, v64
	v_add_f32_e32 v64, v87, v64
	v_add_f32_e32 v64, v88, v64
	v_add_f32_e32 v64, v89, v64
	v_add_f32_e32 v64, v90, v64
	v_add_f32_e32 v64, v91, v64
	v_add_f32_e32 v64, v92, v64
	v_add_f32_e32 v64, v93, v64
	v_add_f32_e32 v64, v94, v64
	v_add_f32_e32 v64, v95, v64
	v_fmac_f32_e32 v64, v133, v96
	ds_bpermute_b32 v65, v123, v64
	s_waitcnt lgkmcnt(0)
; DI unsigned cvtpk(float lo, float hi) { f32x2_t v = {lo, hi}; bf16x2_t b = __builtin_convertvector(v, bf16x2_t); return __builtin_bit_cast(unsigned, b); }
; template <int DK, int KT>
; DI void attn_item(const bfu* __restrict__ Qp, const bfu* __restrict__ Kp, const bfu* __restrict__ Vtp, int nkeys, bfu* __restrict__ Op, int ldo, char* smem) {
;     ...
;   const float inv = 1.f / (lsum + __shfl_xor(lsum, 32));
;   bfu* orow = Op + (long)(w * 32 + l32) * ldo;
; #pragma unroll
;   for (int d = 0; d < 4; ++d)
; #pragma unroll
;     for (int rg = 0; rg < 4; ++rg) {
;       u32x2 v = {cvtpk(o[d][4 * rg] * inv, o[d][4 * rg + 1] * inv), cvtpk(o[d][4 * rg + 2] * inv, o[d][4 * rg + 3] * inv)};
;       *reinterpret_cast<u32x2*>(orow + d * 32 + 8 * rg + 4 * hi) = v;
;     }
	v_add_f32_e32 v64, v64, v65
	v_div_scale_f32 v65, s[2:3], v64, v64, 1.0
	v_rcp_f32_e32 v66, v65
	s_nop 0
	v_fma_f32 v67, -v65, v66, 1.0
	v_fmac_f32_e32 v66, v67, v66
	v_div_scale_f32 v67, vcc, 1.0, v64, 1.0
	v_mul_f32_e32 v68, v67, v66
	v_fma_f32 v69, -v65, v68, v67
	v_fmac_f32_e32 v68, v69, v66
	v_fma_f32 v65, -v65, v68, v67
	v_div_fmas_f32 v65, v65, v66, v68
	v_div_fixup_f32 v64, v65, v64, 1.0
	v_lshlrev_b64 v[66:67], 13, v[120:121]
	v_lshl_add_u64 v[66:67], s[0:1], 0, v[66:67]
	v_pk_mul_f32 v[48:49], v[48:49], v[64:65] op_sel_hi:[1,0]
	v_pk_mul_f32 v[50:51], v[50:51], v[64:65] op_sel_hi:[1,0]
	v_pk_mul_f32 v[32:33], v[32:33], v[64:65] op_sel_hi:[1,0]
	v_pk_mul_f32 v[34:35], v[34:35], v[64:65] op_sel_hi:[1,0]
	v_pk_mul_f32 v[16:17], v[16:17], v[64:65] op_sel_hi:[1,0]
	v_pk_mul_f32 v[18:19], v[18:19], v[64:65] op_sel_hi:[1,0]
	v_pk_mul_f32 v[0:1], v[0:1], v[64:65] op_sel_hi:[1,0]
	v_pk_mul_f32 v[2:3], v[2:3], v[64:65] op_sel_hi:[1,0]
	v_lshl_add_u64 v[66:67], v[66:67], 0, v[128:129]
	v_cvt_pk_bf16_f32 v48, v48, v49
	v_cvt_pk_bf16_f32 v49, v50, v51
	v_cvt_pk_bf16_f32 v32, v32, v33
	v_cvt_pk_bf16_f32 v33, v34, v35
	v_cvt_pk_bf16_f32 v16, v16, v17
	v_cvt_pk_bf16_f32 v17, v18, v19
	v_cvt_pk_bf16_f32 v0, v0, v1
	v_cvt_pk_bf16_f32 v1, v2, v3
	global_store_dwordx2 v[66:67], v[48:49], off
	v_pk_mul_f32 v[48:49], v[52:53], v[64:65] op_sel_hi:[1,0]
	v_pk_mul_f32 v[50:51], v[54:55], v[64:65] op_sel_hi:[1,0]
	global_store_dwordx2 v[66:67], v[32:33], off offset:64
	v_pk_mul_f32 v[32:33], v[36:37], v[64:65] op_sel_hi:[1,0]
	v_pk_mul_f32 v[34:35], v[38:39], v[64:65] op_sel_hi:[1,0]
	global_store_dwordx2 v[66:67], v[16:17], off offset:128
	v_pk_mul_f32 v[16:17], v[20:21], v[64:65] op_sel_hi:[1,0]
	v_pk_mul_f32 v[18:19], v[22:23], v[64:65] op_sel_hi:[1,0]
	global_store_dwordx2 v[66:67], v[0:1], off offset:192
	v_pk_mul_f32 v[0:1], v[4:5], v[64:65] op_sel_hi:[1,0]
	v_pk_mul_f32 v[2:3], v[6:7], v[64:65] op_sel_hi:[1,0]
	v_cvt_pk_bf16_f32 v48, v48, v49
	v_cvt_pk_bf16_f32 v49, v50, v51
	v_cvt_pk_bf16_f32 v32, v32, v33
	v_cvt_pk_bf16_f32 v33, v34, v35
	v_cvt_pk_bf16_f32 v16, v16, v17
	v_cvt_pk_bf16_f32 v17, v18, v19
	v_cvt_pk_bf16_f32 v0, v0, v1
	v_cvt_pk_bf16_f32 v1, v2, v3
	global_store_dwordx2 v[66:67], v[48:49], off offset:16
	v_pk_mul_f32 v[48:49], v[56:57], v[64:65] op_sel_hi:[1,0]
	v_pk_mul_f32 v[50:51], v[58:59], v[64:65] op_sel_hi:[1,0]
	global_store_dwordx2 v[66:67], v[32:33], off offset:80
	v_pk_mul_f32 v[32:33], v[40:41], v[64:65] op_sel_hi:[1,0]
	v_pk_mul_f32 v[34:35], v[42:43], v[64:65] op_sel_hi:[1,0]
	global_store_dwordx2 v[66:67], v[16:17], off offset:144
	v_pk_mul_f32 v[16:17], v[24:25], v[64:65] op_sel_hi:[1,0]
	v_pk_mul_f32 v[18:19], v[26:27], v[64:65] op_sel_hi:[1,0]
	global_store_dwordx2 v[66:67], v[0:1], off offset:208
	v_pk_mul_f32 v[0:1], v[8:9], v[64:65] op_sel_hi:[1,0]
	v_pk_mul_f32 v[2:3], v[10:11], v[64:65] op_sel_hi:[1,0]
	v_cvt_pk_bf16_f32 v48, v48, v49
	v_cvt_pk_bf16_f32 v49, v50, v51
	v_cvt_pk_bf16_f32 v32, v32, v33
	v_cvt_pk_bf16_f32 v33, v34, v35
	v_cvt_pk_bf16_f32 v16, v16, v17
	v_cvt_pk_bf16_f32 v17, v18, v19
	v_cvt_pk_bf16_f32 v0, v0, v1
	v_cvt_pk_bf16_f32 v1, v2, v3
	global_store_dwordx2 v[66:67], v[48:49], off offset:32
	v_pk_mul_f32 v[48:49], v[60:61], v[64:65] op_sel_hi:[1,0]
	v_pk_mul_f32 v[50:51], v[62:63], v[64:65] op_sel_hi:[1,0]
	global_store_dwordx2 v[66:67], v[32:33], off offset:96
	v_pk_mul_f32 v[32:33], v[44:45], v[64:65] op_sel_hi:[1,0]
	v_pk_mul_f32 v[34:35], v[46:47], v[64:65] op_sel_hi:[1,0]
	global_store_dwordx2 v[66:67], v[16:17], off offset:160
	v_pk_mul_f32 v[16:17], v[28:29], v[64:65] op_sel_hi:[1,0]
	v_pk_mul_f32 v[18:19], v[30:31], v[64:65] op_sel_hi:[1,0]
	global_store_dwordx2 v[66:67], v[0:1], off offset:224
	v_pk_mul_f32 v[0:1], v[12:13], v[64:65] op_sel_hi:[1,0]
	v_pk_mul_f32 v[2:3], v[14:15], v[64:65] op_sel_hi:[1,0]
	v_cvt_pk_bf16_f32 v48, v48, v49
	v_cvt_pk_bf16_f32 v49, v50, v51
	v_cvt_pk_bf16_f32 v32, v32, v33
	v_cvt_pk_bf16_f32 v33, v34, v35
	v_cvt_pk_bf16_f32 v16, v16, v17
	v_cvt_pk_bf16_f32 v17, v18, v19
	v_cvt_pk_bf16_f32 v0, v0, v1
	v_cvt_pk_bf16_f32 v1, v2, v3
	global_store_dwordx2 v[66:67], v[48:49], off offset:48
	global_store_dwordx2 v[66:67], v[32:33], off offset:112
	global_store_dwordx2 v[66:67], v[16:17], off offset:176
	global_store_dwordx2 v[66:67], v[0:1], off offset:240
	s_waitcnt lgkmcnt(0)
	s_barrier
	s_and_saveexec_b64 s[0:1], s[6:7]
	s_cbranch_execz .LBB0_502
	s_mov_b64 s[4:5], exec
	v_mbcnt_lo_u32_b32 v0, s4, 0
	v_mbcnt_hi_u32_b32 v0, s5, v0
	v_cmp_eq_u32_e32 vcc, 0, v0
	s_and_saveexec_b64 s[2:3], vcc
	s_cbranch_execz .LBB0_501
	s_bcnt1_i32_b64 s4, s[4:5]
	v_mov_b32_e32 v1, s4
	v_readlane_b32 s4, v255, 5
	v_readlane_b32 s5, v255, 6
	s_nop 4
	global_atomic_add v1, v129, v1, s[4:5] sc0
	s_branch .LBB0_501

; DI int TID() { int t = threadIdx.x; asm volatile("" : "+v"(t)); return t; }
; DI void gemm_preload(const bfu* __restrict__ A, const bfu* __restrict__ Bt, int K, int kt, bf16x8 (&ra)[4], bf16x8 (&rb)[8]) {
;   const int tid = TID(), sr = tid >> 3, sc = (tid & 7) * 8;
;   const bfu* Ag = A + (long)sr * K + sc + kt * BK; const bfu* Bg = Bt + (long)sr * K + sc + kt * BK;
; #pragma unroll
;   for (int i = 0; i < 4; ++i) ra[i] = ld8(Ag + (long)(32 * i) * K);
; #pragma unroll
;   for (int i = 0; i < 8; ++i) rb[i] = ld8(Bg + (long)(32 * i) * K);
; }
; DI void phase_gemm(const Params& p, int g, int kind, char* smem, float* rsl, int* s_item, int vlo, int vhi, int cslot) {
;     ...
;   TD cur; fetch(cur);
;   bf16x8 ra[4], rb[8];
;   if (cur.ok) gemm_preload(cur.A, cur.Bt, cur.K, 0, ra, rb);
.LBB0_524:
	v_cndmask_b32_e64 v0, 0, 1, s[2:3]
	v_mov_b32_e32 v242, 0xff800000
	v_mov_b32_e32 v214, 0x7fc00000
	v_mov_b32_e32 v209, 0x7f800000
	v_mov_b32_e32 v201, 0x3ecc95a3
	v_cmp_ne_u32_e64 s[6:7], 1, v0
	s_andn2_b64 vcc, exec, s[2:3]
	s_cbranch_vccnz .LBB0_526
	v_mov_b32_e32 v4, v202
	s_nop 0
	v_ashrrev_i32_e32 v0, 3, v4
	v_ashrrev_i32_e32 v1, 31, v0
	v_lshlrev_b64 v[0:1], 12, v[0:1]
	v_lshlrev_b32_e32 v4, 4, v4
	v_lshl_add_u64 v[2:3], s[42:43], 0, v[0:1]
	v_and_b32_e32 v128, 0x70, v4
	v_lshl_add_u64 v[2:3], v[2:3], 0, v[128:129]
	v_add_co_u32_e32 v4, vcc, 0x20000, v2
	v_lshl_add_u64 v[0:1], s[44:45], 0, v[0:1]
	s_nop 0
	v_addc_co_u32_e32 v5, vcc, 0, v3, vcc
	v_add_co_u32_e32 v6, vcc, 0x40000, v2
	s_waitcnt vmcnt(0)
	global_load_dwordx4 v[134:137], v[2:3], off
	v_addc_co_u32_e32 v7, vcc, 0, v3, vcc
	v_add_co_u32_e32 v2, vcc, 0x60000, v2
	v_lshl_add_u64 v[0:1], v[0:1], 0, v[128:129]
	s_nop 0
	v_addc_co_u32_e32 v3, vcc, 0, v3, vcc
	global_load_dwordx4 v[138:141], v[4:5], off
	global_load_dwordx4 v[142:145], v[6:7], off
	global_load_dwordx4 v[146:149], v[2:3], off
	global_load_dwordx4 v[150:153], v[0:1], off
	v_add_co_u32_e32 v2, vcc, s72, v0
	s_nop 1
	v_addc_co_u32_e32 v3, vcc, 0, v1, vcc
	v_add_co_u32_e32 v4, vcc, 0x40000, v0
	s_nop 1
	v_addc_co_u32_e32 v5, vcc, 0, v1, vcc
	global_load_dwordx4 v[154:157], v[2:3], off
	global_load_dwordx4 v[158:161], v[4:5], off
	v_add_co_u32_e32 v2, vcc, 0x60000, v0
	s_nop 1
	v_addc_co_u32_e32 v3, vcc, 0, v1, vcc
	v_add_co_u32_e32 v4, vcc, 0x80000, v0
	s_nop 1
	v_addc_co_u32_e32 v5, vcc, 0, v1, vcc
	global_load_dwordx4 v[162:165], v[2:3], off
	global_load_dwordx4 v[166:169], v[4:5], off
	v_add_co_u32_e32 v2, vcc, 0xa0000, v0
	s_nop 1
	v_addc_co_u32_e32 v3, vcc, 0, v1, vcc
	v_add_co_u32_e32 v4, vcc, 0xc0000, v0
	s_nop 1
	v_addc_co_u32_e32 v5, vcc, 0, v1, vcc
	v_add_co_u32_e32 v0, vcc, 0xe0000, v0
	global_load_dwordx4 v[170:173], v[2:3], off
	global_load_dwordx4 v[174:177], v[4:5], off
	v_addc_co_u32_e32 v1, vcc, 0, v1, vcc
	global_load_dwordx4 v[178:181], v[0:1], off

; #define MFMA(a, b, c) __builtin_amdgcn_mfma_f32_32x32x16_bf16((a), (b), (c), 0, 0, 0)
; DI int TID() { int t = threadIdx.x; asm volatile("" : "+v"(t)); return t; }
; DI void gemm_preload(const bfu* __restrict__ A, const bfu* __restrict__ Bt, int K, int kt, bf16x8 (&ra)[4], bf16x8 (&rb)[8]) {
;   const int tid = TID(), sr = tid >> 3, sc = (tid & 7) * 8;
;   const bfu* Ag = A + (long)sr * K + sc + kt * BK; const bfu* Bg = Bt + (long)sr * K + sc + kt * BK;
; #pragma unroll
;   for (int i = 0; i < 4; ++i) ra[i] = ld8(Ag + (long)(32 * i) * K);
; #pragma unroll
;   for (int i = 0; i < 8; ++i) rb[i] = ld8(Bg + (long)(32 * i) * K);
; }
; DI void gemm_main2(const bfu* __restrict__ A, const bfu* __restrict__ Bt, int K, char* smem, f32x16 (&acc)[2][4], bf16x8 (&ra)[4], bf16x8 (&rb)[8]) {
;     ...
;   for (int kt = 0; kt < nk; ++kt) {
;     __syncthreads();
; #pragma unroll
;     for (int i = 0; i < 4; ++i) st8(As + (sr + 32 * i) * LDT + sc, ra[i]);
; #pragma unroll
;     for (int i = 0; i < 8; ++i) st8(Bs + (sr + 32 * i) * LDT + sc, rb[i]);
;     __syncthreads();
;     if (kt + 1 < nk) gemm_preload(A, Bt, K, kt + 1, ra, rb);
; #pragma unroll
;     for (int ks = 0; ks < 4; ++ks) {
;       const bf16x8 a0 = ld8(as + ks * 16), a1 = ld8(as + 32 * LDT + ks * 16);
; #pragma unroll
;       for (int j = 0; j < 4; ++j) {
;         const bf16x8 b = ld8(bs + j * 32 * LDT + ks * 16);
;         acc[0][j] = MFMA(a0, b, acc[0][j]); acc[1][j] = MFMA(a1, b, acc[1][j]);
;       }
;     }
.LBB0_531:
	v_mov_b32_e32 v133, v202
	s_waitcnt lgkmcnt(0)
	s_barrier
	s_waitcnt vmcnt(0)
	ds_write_b128 v131, v[134:137]
	ds_write_b128 v131, v[138:141] offset:4608
	ds_write_b128 v131, v[142:145] offset:9216
	ds_write_b128 v131, v[146:149] offset:13824
	ds_write_b128 v131, v[150:153] offset:18432
	ds_write_b128 v131, v[154:157] offset:23040
	ds_write_b128 v131, v[158:161] offset:27648
	ds_write_b128 v131, v[162:165] offset:32256
	ds_write_b128 v131, v[166:169] offset:36864
	ds_write_b128 v131, v[170:173] offset:41472
	ds_write_b128 v131, v[174:177] offset:46080
	ds_write_b128 v131, v[178:181] offset:50688
	s_waitcnt lgkmcnt(0)
	s_barrier
	ds_read_b128 v[134:137], v130
	ds_read_b128 v[138:141], v128 offset:18432
	ds_read_b128 v[142:145], v130 offset:32
	ds_read_b128 v[146:149], v128 offset:18464
	ds_read_b128 v[150:153], v130 offset:4608
	ds_read_b128 v[154:157], v130 offset:4640
	s_waitcnt lgkmcnt(4)
	v_mfma_f32_32x32x16_bf16 v[112:127], v[134:137], v[138:141], v[112:127]
	s_waitcnt lgkmcnt(1)
	v_mfma_f32_32x32x16_bf16 v[48:63], v[150:153], v[138:141], v[48:63]
	ds_read_b128 v[138:141], v128 offset:23040
	ds_read_b128 v[158:161], v128 offset:23072
	s_waitcnt lgkmcnt(1)
	v_mfma_f32_32x32x16_bf16 v[96:111], v[134:137], v[138:141], v[96:111]
	v_mfma_f32_32x32x16_bf16 v[32:47], v[150:153], v[138:141], v[32:47]
	ds_read_b128 v[138:141], v128 offset:27648
	ds_read_b128 v[162:165], v128 offset:27680
	s_waitcnt lgkmcnt(1)
	v_mfma_f32_32x32x16_bf16 v[80:95], v[134:137], v[138:141], v[80:95]
	v_mfma_f32_32x32x16_bf16 v[16:31], v[150:153], v[138:141], v[16:31]
	ds_read_b128 v[138:141], v128 offset:32256
	ds_read_b128 v[166:169], v128 offset:32288
	s_waitcnt lgkmcnt(1)
	v_mfma_f32_32x32x16_bf16 v[64:79], v[134:137], v[138:141], v[64:79]
	v_mfma_f32_32x32x16_bf16 v[112:127], v[142:145], v[146:149], v[112:127]
	v_mfma_f32_32x32x16_bf16 v[48:63], v[154:157], v[146:149], v[48:63]
	v_mfma_f32_32x32x16_bf16 v[0:15], v[150:153], v[138:141], v[0:15]
	v_mfma_f32_32x32x16_bf16 v[96:111], v[142:145], v[158:161], v[96:111]
	v_mfma_f32_32x32x16_bf16 v[32:47], v[154:157], v[158:161], v[32:47]
	v_mfma_f32_32x32x16_bf16 v[80:95], v[142:145], v[162:165], v[80:95]
	s_waitcnt lgkmcnt(0)
	v_mfma_f32_32x32x16_bf16 v[64:79], v[142:145], v[166:169], v[64:79]
	ds_read_b128 v[134:137], v130 offset:64
	ds_read_b128 v[138:141], v128 offset:18496
	ds_read_b128 v[174:177], v130 offset:96
	ds_read_b128 v[142:145], v128 offset:18528
	ds_read_b128 v[146:149], v130 offset:4672
	ds_read_b128 v[182:185], v130 offset:4704
	v_mfma_f32_32x32x16_bf16 v[16:31], v[154:157], v[162:165], v[16:31]
	s_waitcnt lgkmcnt(4)
	v_mfma_f32_32x32x16_bf16 v[112:127], v[134:137], v[138:141], v[112:127]
	s_waitcnt lgkmcnt(1)
	v_mfma_f32_32x32x16_bf16 v[48:63], v[146:149], v[138:141], v[48:63]
	ds_read_b128 v[138:141], v128 offset:23104
	ds_read_b128 v[158:161], v128 offset:23136
	s_waitcnt lgkmcnt(1)
	v_mfma_f32_32x32x16_bf16 v[96:111], v[134:137], v[138:141], v[96:111]
	v_mfma_f32_32x32x16_bf16 v[32:47], v[146:149], v[138:141], v[32:47]
	ds_read_b128 v[138:141], v128 offset:27712
	ds_read_b128 v[178:181], v128 offset:27744
	s_waitcnt lgkmcnt(1)
	v_mfma_f32_32x32x16_bf16 v[80:95], v[134:137], v[138:141], v[80:95]
	v_mfma_f32_32x32x16_bf16 v[16:31], v[146:149], v[138:141], v[16:31]
	ds_read_b128 v[138:141], v128 offset:32320
	ds_read_b128 v[186:189], v128 offset:32352
	v_mfma_f32_32x32x16_bf16 v[0:15], v[154:157], v[166:169], v[0:15]
	s_waitcnt lgkmcnt(1)
	v_mfma_f32_32x32x16_bf16 v[64:79], v[134:137], v[138:141], v[64:79]
	v_ashrrev_i32_e32 v134, 3, v133
	v_ashrrev_i32_e32 v135, 31, v134
	v_lshlrev_b64 v[134:135], 12, v[134:135]
	v_and_b32_e32 v133, 7, v133
	v_lshl_or_b32 v134, v133, 4, v134
	v_lshl_add_u64 v[150:151], s[4:5], 0, v[134:135]
	v_lshl_add_u64 v[192:193], s[44:45], 0, v[150:151]
	v_mfma_f32_32x32x16_bf16 v[0:15], v[146:149], v[138:141], v[0:15]
	v_lshl_add_u64 v[146:147], s[42:43], 0, v[150:151]
	v_add_co_u32_e32 v138, vcc, s72, v146
	s_add_u32 s4, s4, 0x80
	s_nop 0
	v_addc_co_u32_e32 v139, vcc, 0, v147, vcc
	global_load_dwordx4 v[134:137], v[146:147], off offset:128
	s_nop 0
	global_load_dwordx4 v[138:141], v[138:139], off offset:128
	v_mfma_f32_32x32x16_bf16 v[112:127], v[174:177], v[142:145], v[112:127]
	s_addc_u32 s5, s5, 0
	s_cmpk_lg_i32 s4, 0xf80
	v_mfma_f32_32x32x16_bf16 v[48:63], v[182:185], v[142:145], v[48:63]
	v_add_co_u32_e32 v142, vcc, s86, v146
	s_nop 1
	v_addc_co_u32_e32 v143, vcc, 0, v147, vcc
	v_add_co_u32_e32 v146, vcc, s64, v146
	v_mfma_f32_32x32x16_bf16 v[96:111], v[174:177], v[158:161], v[96:111]
	s_nop 0
	v_addc_co_u32_e32 v147, vcc, 0, v147, vcc
	v_add_co_u32_e32 v154, vcc, s72, v192
	global_load_dwordx4 v[142:145], v[142:143], off offset:128
	s_nop 0
	global_load_dwordx4 v[146:149], v[146:147], off offset:128
	v_addc_co_u32_e32 v155, vcc, 0, v193, vcc
	v_mfma_f32_32x32x16_bf16 v[32:47], v[182:185], v[158:161], v[32:47]
	v_add_co_u32_e32 v158, vcc, s86, v192
	global_load_dwordx4 v[150:153], v[192:193], off offset:128
	s_nop 0
	global_load_dwordx4 v[154:157], v[154:155], off offset:128
	v_addc_co_u32_e32 v159, vcc, 0, v193, vcc
	v_add_co_u32_e32 v162, vcc, s64, v192
	v_mfma_f32_32x32x16_bf16 v[80:95], v[174:177], v[178:181], v[80:95]
	s_nop 0
	v_addc_co_u32_e32 v163, vcc, 0, v193, vcc
	v_add_co_u32_e32 v166, vcc, s65, v192
	global_load_dwordx4 v[158:161], v[158:159], off offset:128
	s_nop 0
	global_load_dwordx4 v[162:165], v[162:163], off offset:128
	v_addc_co_u32_e32 v167, vcc, 0, v193, vcc
	v_add_co_u32_e32 v170, vcc, s66, v192
	v_mfma_f32_32x32x16_bf16 v[16:31], v[182:185], v[178:181], v[16:31]
	s_nop 0
	v_addc_co_u32_e32 v171, vcc, 0, v193, vcc
	v_add_co_u32_e32 v178, vcc, s67, v192
	global_load_dwordx4 v[166:169], v[166:167], off offset:128
	s_nop 0
	global_load_dwordx4 v[170:173], v[170:171], off offset:128
	v_addc_co_u32_e32 v179, vcc, 0, v193, vcc
	v_add_co_u32_e32 v180, vcc, s61, v192
	s_waitcnt lgkmcnt(0)
	v_mfma_f32_32x32x16_bf16 v[64:79], v[174:177], v[186:189], v[64:79]
	v_addc_co_u32_e32 v181, vcc, 0, v193, vcc
	global_load_dwordx4 v[174:177], v[178:179], off offset:128
	s_nop 0
	global_load_dwordx4 v[178:181], v[180:181], off offset:128
	v_mfma_f32_32x32x16_bf16 v[0:15], v[182:185], v[186:189], v[0:15]
	s_cbranch_scc1 .LBB0_531
; #define MFMA(a, b, c) __builtin_amdgcn_mfma_f32_32x32x16_bf16((a), (b), (c), 0, 0, 0)
; DI int TID() { int t = threadIdx.x; asm volatile("" : "+v"(t)); return t; }
; DI void gemm_main2(const bfu* __restrict__ A, const bfu* __restrict__ Bt, int K, char* smem, f32x16 (&acc)[2][4], bf16x8 (&ra)[4], bf16x8 (&rb)[8]) {
;     ...
;   for (int kt = 0; kt < nk; ++kt) {
;     __syncthreads();
; #pragma unroll
;     for (int i = 0; i < 4; ++i) st8(As + (sr + 32 * i) * LDT + sc, ra[i]);
; #pragma unroll
;     for (int i = 0; i < 8; ++i) st8(Bs + (sr + 32 * i) * LDT + sc, rb[i]);
;     __syncthreads();
;     if (kt + 1 < nk) gemm_preload(A, Bt, K, kt + 1, ra, rb);
; #pragma unroll
;     for (int ks = 0; ks < 4; ++ks) {
;       const bf16x8 a0 = ld8(as + ks * 16), a1 = ld8(as + 32 * LDT + ks * 16);
; #pragma unroll
;       for (int j = 0; j < 4; ++j) {
;         const bf16x8 b = ld8(bs + j * 32 * LDT + ks * 16);
;         acc[0][j] = MFMA(a0, b, acc[0][j]); acc[1][j] = MFMA(a1, b, acc[1][j]);
;       }
;     }
; DI void phase_gemm(const Params& p, int g, int kind, char* smem, float* rsl, int* s_item, int vlo, int vhi, int cslot) {
;     ...
;   auto fetch = [&](TD& d) {
;     for (;;) {
;       __syncthreads();
;       if (TID() == 0) *s_item = atomicAdd(qctr, 1);
;       __syncthreads();
	s_barrier
	s_waitcnt vmcnt(0)
	ds_write_b128 v131, v[134:137]
	ds_write_b128 v131, v[138:141] offset:4608
	ds_write_b128 v131, v[142:145] offset:9216
	ds_write_b128 v131, v[146:149] offset:13824
	ds_write_b128 v131, v[150:153] offset:18432
	ds_write_b128 v131, v[154:157] offset:23040
	ds_write_b128 v131, v[158:161] offset:27648
	ds_write_b128 v131, v[162:165] offset:32256
	ds_write_b128 v131, v[166:169] offset:36864
	ds_write_b128 v131, v[170:173] offset:41472
	ds_write_b128 v131, v[174:177] offset:46080
	ds_write_b128 v131, v[178:181] offset:50688
	s_waitcnt lgkmcnt(0)
	s_barrier
	ds_read_b128 v[182:185], v130
	ds_read_b128 v[186:189], v128 offset:18432
	ds_read_b128 v[192:195], v130 offset:4608
	s_waitcnt lgkmcnt(1)
	v_mfma_f32_32x32x16_bf16 v[112:127], v[182:185], v[186:189], v[112:127]
	s_waitcnt lgkmcnt(0)
	v_mfma_f32_32x32x16_bf16 v[48:63], v[192:195], v[186:189], v[48:63]
	ds_read_b128 v[186:189], v128 offset:23040
	s_waitcnt lgkmcnt(0)
	v_mfma_f32_32x32x16_bf16 v[96:111], v[182:185], v[186:189], v[96:111]
	v_mfma_f32_32x32x16_bf16 v[32:47], v[192:195], v[186:189], v[32:47]
	ds_read_b128 v[186:189], v128 offset:27648
	s_waitcnt lgkmcnt(0)
	v_mfma_f32_32x32x16_bf16 v[80:95], v[182:185], v[186:189], v[80:95]
	v_mfma_f32_32x32x16_bf16 v[16:31], v[192:195], v[186:189], v[16:31]
	ds_read_b128 v[186:189], v128 offset:32256
	s_waitcnt lgkmcnt(0)
	v_mfma_f32_32x32x16_bf16 v[64:79], v[182:185], v[186:189], v[64:79]
	v_mfma_f32_32x32x16_bf16 v[0:15], v[192:195], v[186:189], v[0:15]
	ds_read_b128 v[182:185], v130 offset:32
	ds_read_b128 v[186:189], v128 offset:18464
	ds_read_b128 v[192:195], v130 offset:4640
	s_waitcnt lgkmcnt(1)
	v_mfma_f32_32x32x16_bf16 v[112:127], v[182:185], v[186:189], v[112:127]
	s_waitcnt lgkmcnt(0)
	v_mfma_f32_32x32x16_bf16 v[48:63], v[192:195], v[186:189], v[48:63]
	ds_read_b128 v[186:189], v128 offset:23072
	s_waitcnt lgkmcnt(0)
	v_mfma_f32_32x32x16_bf16 v[96:111], v[182:185], v[186:189], v[96:111]
	v_mfma_f32_32x32x16_bf16 v[32:47], v[192:195], v[186:189], v[32:47]
	ds_read_b128 v[186:189], v128 offset:27680
	s_waitcnt lgkmcnt(0)
	v_mfma_f32_32x32x16_bf16 v[80:95], v[182:185], v[186:189], v[80:95]
	v_mfma_f32_32x32x16_bf16 v[16:31], v[192:195], v[186:189], v[16:31]
	ds_read_b128 v[186:189], v128 offset:32288
	s_waitcnt lgkmcnt(0)
	v_mfma_f32_32x32x16_bf16 v[64:79], v[182:185], v[186:189], v[64:79]
	v_mfma_f32_32x32x16_bf16 v[0:15], v[192:195], v[186:189], v[0:15]
	ds_read_b128 v[182:185], v130 offset:64
	ds_read_b128 v[186:189], v128 offset:18496
	ds_read_b128 v[192:195], v130 offset:4672
	s_waitcnt lgkmcnt(1)
	v_mfma_f32_32x32x16_bf16 v[112:127], v[182:185], v[186:189], v[112:127]
	s_waitcnt lgkmcnt(0)
	v_mfma_f32_32x32x16_bf16 v[48:63], v[192:195], v[186:189], v[48:63]
	ds_read_b128 v[186:189], v128 offset:23104
	s_waitcnt lgkmcnt(0)
	v_mfma_f32_32x32x16_bf16 v[96:111], v[182:185], v[186:189], v[96:111]
	v_mfma_f32_32x32x16_bf16 v[32:47], v[192:195], v[186:189], v[32:47]
	ds_read_b128 v[186:189], v128 offset:27712
	s_waitcnt lgkmcnt(0)
	v_mfma_f32_32x32x16_bf16 v[80:95], v[182:185], v[186:189], v[80:95]
	v_mfma_f32_32x32x16_bf16 v[16:31], v[192:195], v[186:189], v[16:31]
	ds_read_b128 v[186:189], v128 offset:32320
	s_waitcnt lgkmcnt(0)
	v_mfma_f32_32x32x16_bf16 v[64:79], v[182:185], v[186:189], v[64:79]
	v_mfma_f32_32x32x16_bf16 v[0:15], v[192:195], v[186:189], v[0:15]
	ds_read_b128 v[182:185], v130 offset:96
	ds_read_b128 v[186:189], v128 offset:18528
	ds_read_b128 v[192:195], v130 offset:4704
	s_waitcnt lgkmcnt(1)
	v_mfma_f32_32x32x16_bf16 v[112:127], v[182:185], v[186:189], v[112:127]
	s_waitcnt lgkmcnt(0)
	v_mfma_f32_32x32x16_bf16 v[48:63], v[192:195], v[186:189], v[48:63]
	ds_read_b128 v[186:189], v128 offset:23136
	s_waitcnt lgkmcnt(0)
	v_mfma_f32_32x32x16_bf16 v[96:111], v[182:185], v[186:189], v[96:111]
	v_mfma_f32_32x32x16_bf16 v[32:47], v[192:195], v[186:189], v[32:47]
	ds_read_b128 v[186:189], v128 offset:27744
	s_waitcnt lgkmcnt(0)
	v_mfma_f32_32x32x16_bf16 v[80:95], v[182:185], v[186:189], v[80:95]
	v_mfma_f32_32x32x16_bf16 v[16:31], v[192:195], v[186:189], v[16:31]
	ds_read_b128 v[186:189], v128 offset:32352
	v_mov_b32_e32 v128, v202
	s_waitcnt lgkmcnt(0)
	s_barrier
	v_mfma_f32_32x32x16_bf16 v[64:79], v[182:185], v[186:189], v[64:79]
	v_cmp_eq_u32_e32 vcc, 0, v128
	v_mfma_f32_32x32x16_bf16 v[0:15], v[192:195], v[186:189], v[0:15]
	s_and_saveexec_b64 s[2:3], vcc
	s_cbranch_execz .LBB0_536
	s_mov_b64 s[6:7], exec
	v_mbcnt_lo_u32_b32 v128, s6, 0
	v_mbcnt_hi_u32_b32 v128, s7, v128
	v_cmp_eq_u32_e32 vcc, 0, v128
	s_and_saveexec_b64 s[4:5], vcc
	s_cbranch_execz .LBB0_535
	s_bcnt1_i32_b64 s1, s[6:7]
	v_mov_b32_e32 v130, s1
	global_atomic_add v130, v129, v130, s[36:37] offset:32 sc0

; DI int TID() { int t = threadIdx.x; asm volatile("" : "+v"(t)); return t; }
; DI void gemm_preload(const bfu* __restrict__ A, const bfu* __restrict__ Bt, int K, int kt, bf16x8 (&ra)[4], bf16x8 (&rb)[8]) {
;   const int tid = TID(), sr = tid >> 3, sc = (tid & 7) * 8;
;   const bfu* Ag = A + (long)sr * K + sc + kt * BK; const bfu* Bg = Bt + (long)sr * K + sc + kt * BK;
; #pragma unroll
;   for (int i = 0; i < 4; ++i) ra[i] = ld8(Ag + (long)(32 * i) * K);
; #pragma unroll
;   for (int i = 0; i < 8; ++i) rb[i] = ld8(Bg + (long)(32 * i) * K);
; }
; DI void phase_gemm(const Params& p, int g, int kind, char* smem, float* rsl, int* s_item, int vlo, int vhi, int cslot) {
;     ...
;     TD nxt; fetch(nxt);
;     if (nxt.ok) gemm_preload(nxt.A, nxt.Bt, nxt.K, 0, ra, rb);
.LBB0_544:
	v_mov_b32_e32 v128, v202
	s_nop 0
	v_ashrrev_i32_e32 v130, 3, v128
	v_ashrrev_i32_e32 v131, 31, v130
	v_lshlrev_b64 v[130:131], 12, v[130:131]
	v_lshlrev_b32_e32 v128, 4, v128
	v_lshl_add_u64 v[134:135], s[42:43], 0, v[130:131]
	v_and_b32_e32 v128, 0x70, v128
	v_lshl_add_u64 v[146:147], v[134:135], 0, v[128:129]
	v_add_co_u32_e32 v138, vcc, 0x20000, v146
	v_lshl_add_u64 v[130:131], s[44:45], 0, v[130:131]
	s_nop 0
	v_addc_co_u32_e32 v139, vcc, 0, v147, vcc
	v_add_co_u32_e32 v142, vcc, 0x40000, v146
	global_load_dwordx4 v[134:137], v[146:147], off
	s_nop 0
	v_addc_co_u32_e32 v143, vcc, 0, v147, vcc
	v_add_co_u32_e32 v146, vcc, 0x60000, v146
	v_lshl_add_u64 v[130:131], v[130:131], 0, v[128:129]
	s_nop 0
	v_addc_co_u32_e32 v147, vcc, 0, v147, vcc
	v_add_co_u32_e32 v154, vcc, s72, v130
	global_load_dwordx4 v[138:141], v[138:139], off
	s_nop 0
	global_load_dwordx4 v[142:145], v[142:143], off
	v_addc_co_u32_e32 v155, vcc, 0, v131, vcc
	v_add_co_u32_e32 v158, vcc, 0x40000, v130
	global_load_dwordx4 v[146:149], v[146:147], off
	s_nop 0
	global_load_dwordx4 v[150:153], v[130:131], off
	v_addc_co_u32_e32 v159, vcc, 0, v131, vcc
	v_add_co_u32_e32 v162, vcc, 0x60000, v130
	global_load_dwordx4 v[154:157], v[154:155], off
	s_nop 0
	global_load_dwordx4 v[158:161], v[158:159], off
	v_addc_co_u32_e32 v163, vcc, 0, v131, vcc
	v_add_co_u32_e32 v166, vcc, 0x80000, v130
	s_nop 1
	v_addc_co_u32_e32 v167, vcc, 0, v131, vcc
	v_add_co_u32_e32 v170, vcc, 0xa0000, v130
	global_load_dwordx4 v[162:165], v[162:163], off
	s_nop 0
	global_load_dwordx4 v[166:169], v[166:167], off
	v_addc_co_u32_e32 v171, vcc, 0, v131, vcc
	v_add_co_u32_e32 v174, vcc, 0xc0000, v130
	s_nop 1
	v_addc_co_u32_e32 v175, vcc, 0, v131, vcc
	v_add_co_u32_e32 v130, vcc, 0xe0000, v130
	global_load_dwordx4 v[170:173], v[170:171], off
	s_nop 0
	global_load_dwordx4 v[174:177], v[174:175], off
	v_addc_co_u32_e32 v131, vcc, 0, v131, vcc
	global_load_dwordx4 v[178:181], v[130:131], off
	s_cmp_gt_i32 s62, 64
	s_cbranch_scc1 .LBB0_529

; DI int TID() { int t = threadIdx.x; asm volatile("" : "+v"(t)); return t; }
; DI unsigned cvtpk(float lo, float hi) { f32x2_t v = {lo, hi}; bf16x2_t b = __builtin_convertvector(v, bf16x2_t); return __builtin_bit_cast(unsigned, b); }
; DI void store_T_regs(const f32x16 (&acc)[2][4], int h, bfu* dst, const float* rs) {
;   const int tid = TID(), lane = tid & 63, w = tid >> 6, wm = w >> 1, wn = w & 1, l32 = lane & 31, hi = lane >> 5;
;   if (wn != h) return;
; #pragma unroll
;   for (int mi = 0; mi < 2; ++mi)
; #pragma unroll
;     for (int ni = 0; ni < 4; ++ni)
; #pragma unroll
;       for (int rg = 0; rg < 4; ++rg) {
;         const int row = wm * 64 + mi * 32 + 8 * rg + 4 * hi;
;         float s0 = 1.f, s1 = 1.f, s2 = 1.f, s3 = 1.f;
;         if (rs) { s0 = rs[row]; s1 = rs[row + 1]; s2 = rs[row + 2]; s3 = rs[row + 3]; }
;         const u32x2 v = {cvtpk(acc[mi][ni][4 * rg] * s0, acc[mi][ni][4 * rg + 1] * s1), cvtpk(acc[mi][ni][4 * rg + 2] * s2, acc[mi][ni][4 * rg + 3] * s3)};
;         *reinterpret_cast<u32x2*>(dst + (long)(ni * 32 + l32) * T + row) = v;
;       }
; }
; DI void phase_gemm(const Params& p, int g, int kind, char* smem, float* rsl, int* s_item, int vlo, int vhi, int cslot) {
;     ...
;         const int bgq = m0 / T, t0q = m0 % T; bfu* td = nullptr; const float* trs = nullptr;
;         if (kind == 0 && nh >= 4096 && nh < 6144) td = (bfu*)(G + L0_VT) + ((long)(bgq * 16 + ((nh - 4096) >> 7)) * 128) * T + t0q;
;         else if (kind == 0 && nh >= 8192 && nh < 10240) td = (bfu*)(G + L0_MVT) + ((long)(bgq * 8 + ((nh - 8192) >> 8)) * 256 + ((nh - 8192) & 255)) * T + t0q;
;         else if (kind == 1 && nh >= 4096 && nh < 6144) td = (bfu*)(G + L1_RVT) + ((long)(bgq * 8 + ((nh - 4096) >> 8)) * 256 + ((nh - 4096) & 255)) * T + t0q;
;         else if (kind == 2 && nt >= 12 && (nh & 255) == 128) { td = (bfu*)(G + L1_VT) + ((long)(bgq * 16 + (nh >> 8)) * 128) * T + t0q; trs = rsl; }
;         if (td) { store_T_regs(acc, h, td, trs); continue; }
.LBB0_551:
	s_cmpk_gt_i32 s48, 0xff
	s_cselect_b64 s[50:51], -1, 0
	s_cmp_eq_u64 s[2:3], 0
	s_cbranch_scc1 .LBB0_555
	v_mov_b32_e32 v128, v202
	s_nop 0
	v_and_b32_e32 v130, 64, v128
	v_cmp_eq_u32_e32 vcc, 0, v130
	s_and_saveexec_b64 s[4:5], vcc
	s_cbranch_execz .LBB0_554
	v_and_b32_e32 v131, 31, v128
	v_ashrrev_i32_e32 v130, 1, v128
	v_lshrrev_b32_e32 v128, 3, v128
	v_and_b32_e32 v128, 4, v128
	s_movk_i32 s1, 0xffc0
	v_and_or_b32 v130, v130, s1, v128
	v_mul_u32_u24_e32 v128, 0x900, v131
	v_lshlrev_b32_e32 v128, 1, v128
	v_ashrrev_i32_e32 v131, 31, v130
	v_lshl_add_u64 v[182:183], s[2:3], 0, v[128:129]
	v_lshlrev_b64 v[186:187], 1, v[130:131]
	v_cvt_pk_bf16_f32 v184, v112, v113
	v_cvt_pk_bf16_f32 v185, v114, v115
	v_lshl_add_u64 v[188:189], v[182:183], 0, v[186:187]
	global_store_dwordx2 v[188:189], v[184:185], off
	v_or_b32_e32 v184, 8, v130
	v_cvt_pk_bf16_f32 v192, v116, v117
	v_cvt_pk_bf16_f32 v193, v118, v119
	v_cvt_pk_bf16_f32 v196, v124, v125
	v_cvt_pk_bf16_f32 v197, v126, v127
	s_mov_b64 s[2:3], 0x24000
	v_ashrrev_i32_e32 v185, 31, v184
	global_store_dwordx2 v[188:189], v[192:193], off offset:16
	v_or_b32_e32 v192, 16, v130
	v_cvt_pk_bf16_f32 v194, v120, v121
	v_cvt_pk_bf16_f32 v195, v122, v123
	global_store_dwordx2 v[188:189], v[196:197], off offset:48
	v_lshl_add_u64 v[196:197], v[182:183], 0, s[2:3]
	v_ashrrev_i32_e32 v193, 31, v192
	global_store_dwordx2 v[188:189], v[194:195], off offset:32
	v_or_b32_e32 v194, 24, v130
	v_cvt_pk_bf16_f32 v198, v96, v97
	v_cvt_pk_bf16_f32 v199, v98, v99
	v_lshl_add_u64 v[204:205], v[196:197], 0, v[186:187]
	v_lshlrev_b64 v[184:185], 1, v[184:185]
	v_ashrrev_i32_e32 v195, 31, v194
	global_store_dwordx2 v[204:205], v[198:199], off
	v_cvt_pk_bf16_f32 v198, v100, v101
	v_cvt_pk_bf16_f32 v199, v102, v103
	v_lshl_add_u64 v[204:205], v[196:197], 0, v[184:185]
	v_lshlrev_b64 v[192:193], 1, v[192:193]
	global_store_dwordx2 v[204:205], v[198:199], off
	v_cvt_pk_bf16_f32 v198, v104, v105
	v_cvt_pk_bf16_f32 v199, v106, v107
	v_lshl_add_u64 v[204:205], v[196:197], 0, v[192:193]
	v_lshlrev_b64 v[194:195], 1, v[194:195]
	global_store_dwordx2 v[204:205], v[198:199], off
	v_cvt_pk_bf16_f32 v198, v108, v109
	v_cvt_pk_bf16_f32 v199, v110, v111
	v_lshl_add_u64 v[204:205], v[196:197], 0, v[194:195]
	s_mov_b64 s[2:3], 0x48000
	global_store_dwordx2 v[204:205], v[198:199], off
	v_lshl_add_u64 v[198:199], v[182:183], 0, s[2:3]
	v_cvt_pk_bf16_f32 v204, v80, v81
	v_cvt_pk_bf16_f32 v205, v82, v83
	v_lshl_add_u64 v[206:207], v[198:199], 0, v[186:187]
	global_store_dwordx2 v[206:207], v[204:205], off
	v_cvt_pk_bf16_f32 v204, v84, v85
	v_cvt_pk_bf16_f32 v205, v86, v87
	v_lshl_add_u64 v[206:207], v[198:199], 0, v[184:185]
	global_store_dwordx2 v[206:207], v[204:205], off
	v_cvt_pk_bf16_f32 v204, v88, v89
	v_cvt_pk_bf16_f32 v205, v90, v91
	v_lshl_add_u64 v[206:207], v[198:199], 0, v[192:193]
	s_mov_b64 s[2:3], 0x6c000
	global_store_dwordx2 v[206:207], v[204:205], off
	v_cvt_pk_bf16_f32 v204, v92, v93
	v_cvt_pk_bf16_f32 v205, v94, v95
	v_lshl_add_u64 v[206:207], v[198:199], 0, v[194:195]
	v_lshl_add_u64 v[182:183], v[182:183], 0, s[2:3]
	global_store_dwordx2 v[206:207], v[204:205], off
	v_cvt_pk_bf16_f32 v204, v64, v65
	v_cvt_pk_bf16_f32 v205, v66, v67
	v_lshl_add_u64 v[186:187], v[182:183], 0, v[186:187]
	global_store_dwordx2 v[186:187], v[204:205], off
	v_cvt_pk_bf16_f32 v186, v68, v69
	v_cvt_pk_bf16_f32 v187, v70, v71
	v_lshl_add_u64 v[184:185], v[182:183], 0, v[184:185]
	global_store_dwordx2 v[184:185], v[186:187], off
	v_cvt_pk_bf16_f32 v184, v72, v73
	v_cvt_pk_bf16_f32 v185, v74, v75
	v_lshl_add_u64 v[186:187], v[182:183], 0, v[192:193]
	global_store_dwordx2 v[186:187], v[184:185], off
	v_cvt_pk_bf16_f32 v184, v76, v77
	v_cvt_pk_bf16_f32 v185, v78, v79
	v_lshl_add_u64 v[186:187], v[182:183], 0, v[194:195]
	global_store_dwordx2 v[186:187], v[184:185], off
	v_or_b32_e32 v184, 32, v130
	v_cvt_pk_bf16_f32 v186, v48, v49
	v_cvt_pk_bf16_f32 v187, v50, v51
	v_ashrrev_i32_e32 v185, 31, v184
	global_store_dwordx2 v[188:189], v[186:187], off offset:64
	v_or_b32_e32 v186, 40, v130
	v_cvt_pk_bf16_f32 v192, v52, v53
	v_cvt_pk_bf16_f32 v193, v54, v55
	v_cvt_pk_bf16_f32 v194, v56, v57
	v_cvt_pk_bf16_f32 v195, v58, v59
	v_ashrrev_i32_e32 v187, 31, v186
	global_store_dwordx2 v[188:189], v[192:193], off offset:80
	v_or_b32_e32 v192, 48, v130
	global_store_dwordx2 v[188:189], v[194:195], off offset:96
	v_cvt_pk_bf16_f32 v194, v60, v61
	v_cvt_pk_bf16_f32 v195, v62, v63
	v_lshlrev_b64 v[184:185], 1, v[184:185]
	v_ashrrev_i32_e32 v193, 31, v192
	v_or_b32_e32 v130, 56, v130
	global_store_dwordx2 v[188:189], v[194:195], off offset:112
	v_cvt_pk_bf16_f32 v188, v32, v33
	v_cvt_pk_bf16_f32 v189, v34, v35
	v_lshl_add_u64 v[194:195], v[196:197], 0, v[184:185]
	v_lshlrev_b64 v[186:187], 1, v[186:187]
	v_ashrrev_i32_e32 v131, 31, v130
	global_store_dwordx2 v[194:195], v[188:189], off
	v_cvt_pk_bf16_f32 v188, v36, v37
	v_cvt_pk_bf16_f32 v189, v38, v39
	v_lshl_add_u64 v[194:195], v[196:197], 0, v[186:187]
	v_lshlrev_b64 v[192:193], 1, v[192:193]
	global_store_dwordx2 v[194:195], v[188:189], off
	v_cvt_pk_bf16_f32 v188, v40, v41
	v_cvt_pk_bf16_f32 v189, v42, v43
	v_lshl_add_u64 v[194:195], v[196:197], 0, v[192:193]
	v_lshlrev_b64 v[130:131], 1, v[130:131]
	global_store_dwordx2 v[194:195], v[188:189], off
	v_cvt_pk_bf16_f32 v188, v44, v45
	v_cvt_pk_bf16_f32 v189, v46, v47
	v_lshl_add_u64 v[194:195], v[196:197], 0, v[130:131]
	global_store_dwordx2 v[194:195], v[188:189], off
	v_cvt_pk_bf16_f32 v188, v16, v17
	v_cvt_pk_bf16_f32 v189, v18, v19
	v_lshl_add_u64 v[194:195], v[198:199], 0, v[184:185]
	global_store_dwordx2 v[194:195], v[188:189], off
	v_cvt_pk_bf16_f32 v188, v20, v21
	v_cvt_pk_bf16_f32 v189, v22, v23
	v_lshl_add_u64 v[194:195], v[198:199], 0, v[186:187]
	global_store_dwordx2 v[194:195], v[188:189], off
	v_cvt_pk_bf16_f32 v188, v24, v25
	v_cvt_pk_bf16_f32 v189, v26, v27
	v_lshl_add_u64 v[194:195], v[198:199], 0, v[192:193]
	global_store_dwordx2 v[194:195], v[188:189], off
	v_cvt_pk_bf16_f32 v188, v28, v29
	v_cvt_pk_bf16_f32 v189, v30, v31
	v_lshl_add_u64 v[194:195], v[198:199], 0, v[130:131]
	global_store_dwordx2 v[194:195], v[188:189], off
	v_cvt_pk_bf16_f32 v188, v0, v1
	v_cvt_pk_bf16_f32 v189, v2, v3
	v_lshl_add_u64 v[184:185], v[182:183], 0, v[184:185]
	global_store_dwordx2 v[184:185], v[188:189], off
	v_cvt_pk_bf16_f32 v184, v4, v5
	v_cvt_pk_bf16_f32 v185, v6, v7
	v_lshl_add_u64 v[186:187], v[182:183], 0, v[186:187]
	global_store_dwordx2 v[186:187], v[184:185], off
	v_cvt_pk_bf16_f32 v184, v8, v9
	v_cvt_pk_bf16_f32 v185, v10, v11
	v_lshl_add_u64 v[186:187], v[182:183], 0, v[192:193]
	global_store_dwordx2 v[186:187], v[184:185], off
	v_cvt_pk_bf16_f32 v184, v12, v13
	v_cvt_pk_bf16_f32 v185, v14, v15
	v_lshl_add_u64 v[130:131], v[182:183], 0, v[130:131]
	global_store_dwordx2 v[130:131], v[184:185], off

;   DI const float* ab_b_if() const { return (const float*)sp[9]; }
; DI float logsig(float v) { return fminf(v, 0.f) - log1pf(__expf(-fabsf(v))); }
; DI void epi_in0(const Params& p, float* Cs, int m0, int n0) {
;     ...
;       const int ch = sidx & 1, dh = sidx >> 1, dir = dh >> 3, head = dh & 7, row = ch * 64 + lane;
;       const float ig = Cs[row * CLD + dir * 8 + head] + p.ab_b_if()[dir * 8 + head];
;       const float f = logsig(Cs[row * CLD + 16 + dir * 8 + head] + p.ab_b_if()[16 + dir * 8 + head]);
;       float bc = f;
;       for (int off = 1; off < 64; off <<= 1) {
;         const float yu = __shfl_up(bc, off), yd = __shfl_down(bc, off);
;         const bool ok = dir == 0 ? lane >= off : lane + off < 64;
;         if (ok) bc += dir == 0 ? yu : yd;
;       }
;       const float gs = ig - bc;
;       float cm = gs;
;       for (int off = 1; off < 64; off <<= 1) {
;         const float yu = __shfl_up(cm, off), yd = __shfl_down(cm, off);
;         const bool ok = dir == 0 ? lane >= off : lane + off < 64;
;         if (ok) cm = fmaxf(cm, dir == 0 ? yu : yd);
;       }
.LBB0_568:
	v_ashrrev_i32_e32 v227, 4, v188
	v_bfe_u32 v226, v188, 1, 3
	v_and_or_b32 v128, v199, 64, v133
	v_lshlrev_b32_e32 v201, 3, v227
	v_mul_u32_u24_e32 v182, 0x210, v128
	v_lshlrev_b32_e32 v183, 5, v227
	v_lshlrev_b32_e32 v204, 2, v226
	v_add3_u32 v182, v182, v183, v204
	v_or_b32_e32 v204, v201, v226
	v_ashrrev_i32_e32 v205, 31, v204
	s_waitcnt lgkmcnt(0)
	v_lshl_add_u64 v[206:207], v[204:205], 2, v[130:131]
	v_ashrrev_i32_e32 v205, 31, v201
	v_lshl_add_u64 v[204:205], v[204:205], 2, v[130:131]
	global_load_dword v228, v[206:207], off
	global_load_dword v201, v[204:205], off offset:64
	ds_read2_b32 v[182:183], v182 offset1:16
	v_add_u32_e32 v199, 0x100, v199
	s_waitcnt vmcnt(0) lgkmcnt(0)
	v_add_f32_e32 v182, v182, v228
	v_add_f32_e32 v183, v183, v201
	v_min_f32_e32 v201, 0, v183
	v_mul_f32_e64 v183, |v183|, s22
	v_exp_f32_e32 v183, v183
	s_nop 0
	v_add_f32_e32 v206, 1.0, v183
	v_add_f32_e32 v204, -1.0, v206
	v_sub_f32_e32 v205, v204, v206
	v_add_f32_e32 v205, 1.0, v205
	v_sub_f32_e32 v204, v183, v204
	v_add_f32_e32 v207, v204, v205
	v_frexp_mant_f32_e32 v204, v206
	v_cmp_gt_f32_e64 s[0:1], s23, v204
	v_cvt_f64_f32_e32 v[204:205], v206
	v_frexp_exp_i32_f64_e32 v204, v[204:205]
	v_subbrev_co_u32_e64 v204, s[0:1], 0, v204, s[0:1]
	v_sub_u32_e32 v205, 0, v204
	v_ldexp_f32 v206, v206, v205
	v_ldexp_f32 v205, v207, v205
	v_add_f32_e32 v207, -1.0, v206
	v_add_f32_e32 v209, 1.0, v207
	v_sub_f32_e32 v209, v206, v209
	v_add_f32_e32 v209, v205, v209
	v_add_f32_e32 v210, v207, v209
	v_sub_f32_e32 v207, v210, v207
	v_sub_f32_e32 v207, v209, v207
	v_add_f32_e32 v209, 1.0, v206
	v_add_f32_e32 v211, -1.0, v209
	v_sub_f32_e32 v206, v206, v211
	v_add_f32_e32 v205, v205, v206
	v_add_f32_e32 v206, v209, v205
	v_sub_f32_e32 v209, v206, v209
	v_sub_f32_e32 v205, v205, v209
	v_rcp_f32_e32 v209, v206
	v_cvt_f32_i32_e32 v204, v204
	v_cmp_neq_f32_e64 s[0:1], s19, v183
	v_cmp_gt_u32_e64 s[22:23], 16, v188
	v_mul_f32_e32 v211, v210, v209
	v_mul_f32_e32 v214, v206, v211
	v_fma_f32 v229, v211, v206, -v214
	v_fmac_f32_e32 v229, v211, v205
	v_add_f32_e32 v230, v214, v229
	v_sub_f32_e32 v231, v210, v230
	v_sub_f32_e32 v210, v210, v231
	v_sub_f32_e32 v214, v230, v214
	v_sub_f32_e32 v210, v210, v230
	v_add_f32_e32 v207, v207, v210
	v_sub_f32_e32 v210, v214, v229
	v_add_f32_e32 v207, v210, v207
	v_add_f32_e32 v210, v231, v207
	v_mul_f32_e32 v214, v209, v210
	v_mul_f32_e32 v229, v206, v214
	v_fma_f32 v206, v214, v206, -v229
	v_fmac_f32_e32 v206, v214, v205
	v_sub_f32_e32 v205, v231, v210
	v_add_f32_e32 v205, v207, v205
	v_add_f32_e32 v207, v229, v206
	v_sub_f32_e32 v230, v210, v207
	v_sub_f32_e32 v210, v210, v230
	v_sub_f32_e32 v229, v207, v229
	v_sub_f32_e32 v207, v210, v207
	v_add_f32_e32 v205, v205, v207
	v_sub_f32_e32 v206, v229, v206
	v_add_f32_e32 v205, v206, v205
	v_add_f32_e32 v206, v211, v214
	v_add_f32_e32 v205, v230, v205
	v_sub_f32_e32 v207, v206, v211
	v_mul_f32_e32 v205, v209, v205
	v_sub_f32_e32 v207, v214, v207
	v_add_f32_e32 v205, v207, v205
	v_mul_f32_e32 v211, 0x3f317218, v204
	v_add_f32_e32 v207, v206, v205
	v_fma_f32 v214, v204, s75, -v211
	v_mul_f32_e32 v209, v207, v207
	v_fmac_f32_e32 v214, 0xb102e308, v204
	v_sub_f32_e32 v204, v207, v206
	v_fmamk_f32 v210, v209, 0x3e9b6dac, v232
	v_sub_f32_e32 v204, v205, v204
	v_add_f32_e32 v205, v211, v214
	v_fmaak_f32 v210, v209, v210, 0x3f2aaada
	v_sub_f32_e32 v206, v205, v211
	v_ldexp_f32 v211, v207, 1
	v_mul_f32_e32 v207, v207, v209
	v_mul_f32_e32 v207, v207, v210
	v_add_f32_e32 v209, v211, v207
	v_sub_f32_e32 v210, v209, v211
	v_ldexp_f32 v204, v204, 1
	v_sub_f32_e32 v207, v207, v210
	v_add_f32_e32 v204, v204, v207
	v_add_f32_e32 v207, v209, v204
	v_sub_f32_e32 v209, v207, v209
	v_sub_f32_e32 v204, v204, v209
	v_add_f32_e32 v209, v205, v207
	v_sub_f32_e32 v210, v209, v205
	v_sub_f32_e32 v211, v209, v210
	v_sub_f32_e32 v206, v214, v206
	v_sub_f32_e32 v205, v205, v211
	v_sub_f32_e32 v207, v207, v210
	v_add_f32_e32 v205, v207, v205
	v_add_f32_e32 v207, v206, v204
	v_sub_f32_e32 v210, v207, v206
	v_sub_f32_e32 v211, v207, v210
	v_sub_f32_e32 v206, v206, v211
	v_sub_f32_e32 v204, v204, v210
	v_add_f32_e32 v205, v207, v205
	v_add_f32_e32 v204, v204, v206
	v_add_f32_e32 v206, v209, v205
	v_sub_f32_e32 v207, v206, v209
	v_sub_f32_e32 v205, v205, v207
	v_add_f32_e32 v204, v204, v205
	v_add_f32_e32 v204, v206, v204
	v_cndmask_b32_e64 v204, v233, v204, s[0:1]
	v_cmp_ngt_f32_e64 s[0:1], -1.0, v183
	v_cndmask_b32_e64 v205, 63, 0, s[22:23]
	v_cmp_eq_u32_e64 s[24:25], v133, v205
	v_cndmask_b32_e64 v204, v234, v204, s[0:1]
	v_cmp_neq_f32_e64 s[0:1], -1.0, v183
	s_xor_b64 s[34:35], s[20:21], s[22:23]
	s_nop 0
	v_cndmask_b32_e64 v204, v242, v204, s[0:1]
	v_cmp_lt_f32_e64 s[0:1], |v183|, s74
	s_nop 1
	v_cndmask_b32_e64 v183, v204, v183, s[0:1]
	v_sub_f32_e32 v183, v201, v183
	ds_bpermute_b32 v201, v184, v183
	ds_bpermute_b32 v204, v185, v183
	v_readlane_b32 s0, v254, 29
	v_readlane_b32 s1, v254, 30
	s_waitcnt lgkmcnt(0)
; DI void epi_in0(const Params& p, float* Cs, int m0, int n0) {
;     ...
;       for (int off = 1; off < 64; off <<= 1) {
;         const float yu = __shfl_up(bc, off), yd = __shfl_down(bc, off);
;         const bool ok = dir == 0 ? lane >= off : lane + off < 64;
;         if (ok) bc += dir == 0 ? yu : yd;
;       }
;       const float gs = ig - bc;
;       float cm = gs;
;       for (int off = 1; off < 64; off <<= 1) {
;         const float yu = __shfl_up(cm, off), yd = __shfl_down(cm, off);
;         const bool ok = dir == 0 ? lane >= off : lane + off < 64;
;         if (ok) cm = fmaxf(cm, dir == 0 ? yu : yd);
;       }
;       const long o = ((long)(dir * GB + bg) * 8 + head) * T + t0 + row;
;       gb[o] = bc; gsv[o] = gs; gc[o] = cm;
	v_cndmask_b32_e64 v201, v204, v201, s[22:23]
	v_add_f32_e32 v201, v183, v201
	v_cndmask_b32_e64 v183, v201, v183, s[24:25]
	ds_bpermute_b32 v201, v186, v183
	ds_bpermute_b32 v204, v187, v183
	v_cndmask_b32_e64 v205, 0, 1, s[0:1]
	v_readlane_b32 s0, v255, 9
	v_readlane_b32 s1, v255, 10
	s_waitcnt lgkmcnt(0)
	v_cndmask_b32_e64 v201, v204, v201, s[22:23]
	v_cndmask_b32_e64 v206, 0, 1, s[0:1]
	v_cndmask_b32_e64 v205, v206, v205, s[22:23]
	v_and_b32_e32 v205, 1, v205
	v_cmp_eq_u32_e64 s[26:27], 1, v205
	v_add_f32_e32 v201, v183, v201
	v_readlane_b32 s0, v255, 11
	v_cndmask_b32_e64 v183, v183, v201, s[26:27]
	ds_bpermute_b32 v201, v189, v183
	ds_bpermute_b32 v204, v192, v183
	v_readlane_b32 s1, v255, 12
	s_waitcnt lgkmcnt(0)
	v_cndmask_b32_e64 v201, v204, v201, s[22:23]
	v_cndmask_b32_e64 v205, 0, 1, s[0:1]
	v_readlane_b32 s0, v255, 13
	v_readlane_b32 s1, v255, 14
	v_add_f32_e32 v201, v183, v201
	s_nop 0
	v_cndmask_b32_e64 v206, 0, 1, s[0:1]
	v_cndmask_b32_e64 v205, v206, v205, s[22:23]
	v_and_b32_e32 v205, 1, v205
	v_cmp_eq_u32_e64 s[28:29], 1, v205
	v_readlane_b32 s0, v255, 15
	v_readlane_b32 s1, v255, 16
	v_cndmask_b32_e64 v183, v183, v201, s[28:29]
	ds_bpermute_b32 v201, v193, v183
	ds_bpermute_b32 v204, v194, v183
	v_cndmask_b32_e64 v205, 0, 1, s[0:1]
	v_cndmask_b32_e64 v206, 0, 1, s[2:3]
	v_cndmask_b32_e64 v205, v206, v205, s[22:23]
	v_and_b32_e32 v205, 1, v205
	s_waitcnt lgkmcnt(0)
	v_cndmask_b32_e64 v201, v204, v201, s[22:23]
	v_cmp_eq_u32_e64 s[0:1], 1, v205
	v_add_f32_e32 v201, v183, v201
	v_cndmask_b32_e64 v205, 0, 1, s[6:7]
	v_cndmask_b32_e64 v183, v183, v201, s[0:1]
	ds_bpermute_b32 v201, v195, v183
	ds_bpermute_b32 v204, v196, v183
	v_cndmask_b32_e64 v206, 0, 1, vcc
	v_cndmask_b32_e64 v205, v206, v205, s[22:23]
	v_and_b32_e32 v205, 1, v205
	v_cmp_eq_u32_e64 s[30:31], 1, v205
	s_waitcnt lgkmcnt(0)
	v_cndmask_b32_e64 v201, v204, v201, s[22:23]
	v_add_f32_e32 v201, v183, v201
	v_cndmask_b32_e64 v183, v183, v201, s[30:31]
	ds_bpermute_b32 v201, v197, v183
	ds_bpermute_b32 v204, v198, v183
	s_waitcnt lgkmcnt(0)
	v_cndmask_b32_e64 v201, v204, v201, s[22:23]
	v_add_f32_e32 v201, v183, v201
	v_cndmask_b32_e64 v201, v183, v201, s[34:35]
	v_sub_f32_e32 v206, v182, v201
	ds_bpermute_b32 v182, v184, v206
	ds_bpermute_b32 v183, v185, v206
	s_waitcnt lgkmcnt(0)
	v_cndmask_b32_e64 v182, v183, v182, s[22:23]
	v_max_f32_e32 v182, v182, v182
	v_max_f32_e32 v182, v206, v182
	v_cndmask_b32_e64 v182, v182, v206, s[24:25]
	ds_bpermute_b32 v183, v186, v182
	ds_bpermute_b32 v204, v187, v182
	s_waitcnt lgkmcnt(0)
	v_cndmask_b32_e64 v183, v204, v183, s[22:23]
	v_max_f32_e32 v183, v183, v183
	v_max_f32_e32 v183, v182, v183
	v_cndmask_b32_e64 v182, v182, v183, s[26:27]
	ds_bpermute_b32 v183, v189, v182
	ds_bpermute_b32 v204, v192, v182
	s_waitcnt lgkmcnt(0)
	v_cndmask_b32_e64 v183, v204, v183, s[22:23]
	v_max_f32_e32 v183, v183, v183
	v_max_f32_e32 v183, v182, v183
	v_cndmask_b32_e64 v182, v182, v183, s[28:29]
	ds_bpermute_b32 v183, v193, v182
	ds_bpermute_b32 v204, v194, v182
	s_waitcnt lgkmcnt(0)
	v_cndmask_b32_e64 v183, v204, v183, s[22:23]
	v_max_f32_e32 v183, v183, v183
	v_max_f32_e32 v183, v182, v183
	v_cndmask_b32_e64 v182, v182, v183, s[0:1]
	ds_bpermute_b32 v183, v195, v182
	ds_bpermute_b32 v204, v196, v182
	s_waitcnt lgkmcnt(0)
	v_cndmask_b32_e64 v183, v204, v183, s[22:23]
	v_max_f32_e32 v183, v183, v183
	v_max_f32_e32 v183, v182, v183
	v_cndmask_b32_e64 v182, v182, v183, s[30:31]
	ds_bpermute_b32 v183, v197, v182
	ds_bpermute_b32 v204, v198, v182
	s_waitcnt lgkmcnt(0)
	v_cndmask_b32_e64 v183, v204, v183, s[22:23]
	v_max_f32_e32 v183, v183, v183
	v_max_f32_e32 v204, v182, v182
	v_max_f32_e32 v183, v204, v183
	v_cndmask_b32_e64 v207, v182, v183, s[34:35]
	v_lshl_add_u32 v182, v227, 1, s15
	v_ashrrev_i32_e32 v204, 31, v182
	v_lshl_or_b32 v205, v182, 3, v226
	v_lshl_add_u64 v[182:183], v[128:129], 0, s[48:49]
	v_mad_u64_u32 v[182:183], s[0:1], v205, s60, v[182:183]
	v_mad_i32_i24 v183, v204, s60, v183
	v_lshlrev_b64 v[182:183], 2, v[182:183]
	v_lshl_add_u64 v[204:205], s[78:79], 0, v[182:183]
	v_add_u32_e32 v128, 4, v188
	v_cmp_lt_i32_e64 s[0:1], 27, v188
	s_mov_b32 s23, 0x3f2aaaab
	s_mov_b32 s22, 0xbfb8aa3b
	global_store_dword v[204:205], v201, off
	v_lshl_add_u64 v[204:205], s[80:81], 0, v[182:183]
	v_lshl_add_u64 v[182:183], s[94:95], 0, v[182:183]
	s_or_b64 s[96:97], s[0:1], s[96:97]
	v_mov_b32_e32 v188, v128
	global_store_dword v[204:205], v206, off
	global_store_dword v[182:183], v207, off
	s_andn2_b64 exec, exec, s[96:97]
	s_cbranch_execnz .LBB0_568

; DI int TID() { int t = threadIdx.x; asm volatile("" : "+v"(t)); return t; }
; DI bf16x8 pack8f(const float* v) { u32x4 w = {cvtpk(v[0], v[1]), cvtpk(v[2], v[3]), cvtpk(v[4], v[5]), cvtpk(v[6], v[7])}; return __builtin_bit_cast(bf16x8, w); }
; DI void store_R(const float* Cs, int cb, int nc, bfu* dst, long ld, float scale, const float* rs = nullptr) {
;   const int cpr = nc >> 3;
;   for (int u = TID(); u < 128 * cpr; u += NT) {
;     int row = u / cpr, c8 = (u % cpr) * 8; float v[8]; ldrow8(Cs, row, cb + c8, v);
;     float s = rs ? scale * rs[row] : scale;
;     for (int j = 0; j < 8; ++j) v[j] *= s;
;     st8(dst + row * ld + c8, pack8f(v));
;   }
; }
.LBB0_573:
	v_ashrrev_i32_e32 v133, 31, v128
	v_lshrrev_b32_e32 v133, 28, v133
	v_add_u32_e32 v133, v128, v133
	v_add_u32_e32 v182, 0x100, v128
	v_ashrrev_i32_e32 v192, 4, v133
	v_and_b32_e32 v133, -16, v133
	v_cmp_lt_i32_e32 vcc, s87, v128
	v_mov_b32_e32 v128, v182
	v_lshlrev_b32_e32 v182, 7, v192
	v_add_u32_e32 v133, v131, v133
	v_sub_u32_e32 v194, v130, v182
	ds_read_b128 v[182:185], v133
	ds_read_b128 v[186:189], v133 offset:16
	v_ashrrev_i32_e32 v193, 31, v192
	v_lshlrev_b64 v[192:193], 13, v[192:193]
	v_lshl_add_u64 v[192:193], s[2:3], 0, v[192:193]
	v_ashrrev_i32_e32 v195, 31, v194
	s_or_b64 s[6:7], vcc, s[6:7]
	v_add_u32_e32 v131, 0x2000, v131
	v_add_u32_e32 v130, 0x800, v130
	v_lshl_add_u64 v[192:193], v[194:195], 1, v[192:193]
	s_waitcnt lgkmcnt(0)
	v_cvt_pk_bf16_f32 v182, v182, v183
	v_cvt_pk_bf16_f32 v183, v184, v185
	v_cvt_pk_bf16_f32 v184, v186, v187
	v_cvt_pk_bf16_f32 v185, v188, v189
	global_store_dwordx4 v[192:193], v[182:185], off
	s_andn2_b64 exec, exec, s[6:7]
	s_cbranch_execnz .LBB0_573

; DI int TID() { int t = threadIdx.x; asm volatile("" : "+v"(t)); return t; }
; DI bf16x8 pack8f(const float* v) { u32x4 w = {cvtpk(v[0], v[1]), cvtpk(v[2], v[3]), cvtpk(v[4], v[5]), cvtpk(v[6], v[7])}; return __builtin_bit_cast(bf16x8, w); }
; DI void store_R(const float* Cs, int cb, int nc, bfu* dst, long ld, float scale, const float* rs = nullptr) {
;   const int cpr = nc >> 3;
;   for (int u = TID(); u < 128 * cpr; u += NT) {
;     int row = u / cpr, c8 = (u % cpr) * 8; float v[8]; ldrow8(Cs, row, cb + c8, v);
;     float s = rs ? scale * rs[row] : scale;
;     for (int j = 0; j < 8; ++j) v[j] *= s;
;     st8(dst + row * ld + c8, pack8f(v));
;   }
; }
.LBB0_579:
	v_ashrrev_i32_e32 v133, 31, v128
	v_lshrrev_b32_e32 v133, 28, v133
	v_add_u32_e32 v133, v128, v133
	v_add_u32_e32 v182, 0x100, v128
	v_ashrrev_i32_e32 v192, 4, v133
	v_and_b32_e32 v133, -16, v133
	v_cmp_lt_i32_e32 vcc, s87, v128
	v_mov_b32_e32 v128, v182
	v_lshlrev_b32_e32 v182, 7, v192
	v_add_u32_e32 v133, v131, v133
	v_sub_u32_e32 v194, v130, v182
	ds_read_b128 v[182:185], v133
	ds_read_b128 v[186:189], v133 offset:16
	v_ashrrev_i32_e32 v193, 31, v192
	v_lshlrev_b64 v[192:193], 12, v[192:193]
	v_lshl_add_u64 v[192:193], s[2:3], 0, v[192:193]
	v_ashrrev_i32_e32 v195, 31, v194
	s_or_b64 s[6:7], vcc, s[6:7]
	v_add_u32_e32 v131, 0x2000, v131
	v_add_u32_e32 v130, 0x800, v130
	v_lshl_add_u64 v[192:193], v[194:195], 1, v[192:193]
	s_waitcnt lgkmcnt(0)
	v_cvt_pk_bf16_f32 v182, v182, v183
	v_cvt_pk_bf16_f32 v183, v184, v185
	v_cvt_pk_bf16_f32 v184, v186, v187
	v_cvt_pk_bf16_f32 v185, v188, v189
	global_store_dwordx4 v[192:193], v[182:185], off
	s_andn2_b64 exec, exec, s[6:7]
	s_cbranch_execnz .LBB0_579

;   DI const float* c() const { return (const float*)sp[1]; }
; DI int TID() { int t = threadIdx.x; asm volatile("" : "+v"(t)); return t; }
; DI bf16x8 pack8f(const float* v) { u32x4 w = {cvtpk(v[0], v[1]), cvtpk(v[2], v[3]), cvtpk(v[4], v[5]), cvtpk(v[6], v[7])}; return __builtin_bit_cast(bf16x8, w); }
; DI void store_T(const float* Cs, int cb, int nc, bfu* dst, long ldT, float scale, const float* rs = nullptr) {
;   for (int u = TID(); u < nc * 16; u += NT) {
;     int c = u % nc, rc = (u / nc) * 8; float v[8];
;     for (int j = 0; j < 8; ++j) v[j] = Cs[(rc + j) * CLD + cb + c] * (rs ? scale * rs[rc + j] : scale);
;     st8(dst + c * ldT + rc, pack8f(v));
;   }
; }
.LBB0_585:
	v_ashrrev_i32_e32 v133, 31, v131
	v_lshrrev_b32_e32 v133, 25, v133
	v_add_u32_e32 v182, 0x100, v131
	v_add_u32_e32 v133, v131, v133
	v_cmp_lt_i32_e32 vcc, s87, v131
	v_mov_b32_e32 v131, v182
	v_ashrrev_i32_e32 v133, 7, v133
	v_mad_u64_u32 v[184:185], s[20:21], v133, s19, v[130:131]
	v_lshlrev_b32_e32 v182, 3, v133
	v_mad_u64_u32 v[186:187], s[20:21], v133, s22, v[128:129]
	v_add_u32_e32 v133, 0x400, v184
	v_add_u32_e32 v192, 0x800, v184
	v_add_u32_e32 v194, 0xc00, v184
	ds_read2_b32 v[188:189], v184 offset1:132
	ds_read2_b32 v[184:185], v133 offset0:8 offset1:140
	ds_read2_b32 v[192:193], v192 offset0:16 offset1:148
	ds_read2_b32 v[194:195], v194 offset0:24 offset1:156
	v_ashrrev_i32_e32 v187, 31, v186
	v_ashrrev_i32_e32 v183, 31, v182
	v_lshl_add_u64 v[186:187], s[2:3], 0, v[186:187]
	s_or_b64 s[6:7], vcc, s[6:7]
	v_add_u32_e32 v128, 0x120000, v128
	v_add_u32_e32 v130, 0x400, v130
	v_lshl_add_u64 v[186:187], v[182:183], 1, v[186:187]
	s_waitcnt lgkmcnt(0)
	v_cvt_pk_bf16_f32 v182, v188, v189
	v_cvt_pk_bf16_f32 v183, v184, v185
	v_cvt_pk_bf16_f32 v184, v192, v193
	v_cvt_pk_bf16_f32 v185, v194, v195
	global_store_dwordx4 v[186:187], v[182:185], off
	s_andn2_b64 exec, exec, s[6:7]
	s_cbranch_execnz .LBB0_585

; DI int TID() { int t = threadIdx.x; asm volatile("" : "+v"(t)); return t; }
; DI bf16x8 pack8f(const float* v) { u32x4 w = {cvtpk(v[0], v[1]), cvtpk(v[2], v[3]), cvtpk(v[4], v[5]), cvtpk(v[6], v[7])}; return __builtin_bit_cast(bf16x8, w); }
; DI void store_R(const float* Cs, int cb, int nc, bfu* dst, long ld, float scale, const float* rs = nullptr) {
;   const int cpr = nc >> 3;
;   for (int u = TID(); u < 128 * cpr; u += NT) {
;     int row = u / cpr, c8 = (u % cpr) * 8; float v[8]; ldrow8(Cs, row, cb + c8, v);
;     float s = rs ? scale * rs[row] : scale;
;     for (int j = 0; j < 8; ++j) v[j] *= s;
;     st8(dst + row * ld + c8, pack8f(v));
;   }
; }
.LBB0_591:
	v_ashrrev_i32_e32 v133, 31, v128
	v_lshrrev_b32_e32 v133, 28, v133
	v_add_u32_e32 v133, v128, v133
	v_add_u32_e32 v182, 0x100, v128
	v_ashrrev_i32_e32 v192, 4, v133
	v_and_b32_e32 v133, -16, v133
	v_cmp_lt_i32_e32 vcc, s87, v128
	v_mov_b32_e32 v128, v182
	v_lshlrev_b32_e32 v182, 7, v192
	v_add_u32_e32 v133, v131, v133
	v_sub_u32_e32 v194, v130, v182
	ds_read_b128 v[182:185], v133
	ds_read_b128 v[186:189], v133 offset:16
	v_ashrrev_i32_e32 v193, 31, v192
	v_lshlrev_b64 v[192:193], 8, v[192:193]
	v_lshl_add_u64 v[192:193], s[2:3], 0, v[192:193]
	v_ashrrev_i32_e32 v195, 31, v194
	s_or_b64 s[6:7], vcc, s[6:7]
	v_add_u32_e32 v131, 0x2000, v131
	v_add_u32_e32 v130, 0x800, v130
	v_lshl_add_u64 v[192:193], v[194:195], 1, v[192:193]
	s_waitcnt lgkmcnt(0)
	v_cvt_pk_bf16_f32 v182, v182, v183
	v_cvt_pk_bf16_f32 v183, v184, v185
	v_cvt_pk_bf16_f32 v184, v186, v187
	v_cvt_pk_bf16_f32 v185, v188, v189
	global_store_dwordx4 v[192:193], v[182:185], off
	s_andn2_b64 exec, exec, s[6:7]
	s_cbranch_execnz .LBB0_591

;   DI const float* c() const { return (const float*)sp[1]; }
; DI int TID() { int t = threadIdx.x; asm volatile("" : "+v"(t)); return t; }
; DI bf16x8 pack8f(const float* v) { u32x4 w = {cvtpk(v[0], v[1]), cvtpk(v[2], v[3]), cvtpk(v[4], v[5]), cvtpk(v[6], v[7])}; return __builtin_bit_cast(bf16x8, w); }
; DI void store_T(const float* Cs, int cb, int nc, bfu* dst, long ldT, float scale, const float* rs = nullptr) {
;   for (int u = TID(); u < nc * 16; u += NT) {
;     int c = u % nc, rc = (u / nc) * 8; float v[8];
;     for (int j = 0; j < 8; ++j) v[j] = Cs[(rc + j) * CLD + cb + c] * (rs ? scale * rs[rc + j] : scale);
;     st8(dst + c * ldT + rc, pack8f(v));
;   }
; }
.LBB0_594:
	v_ashrrev_i32_e32 v133, 31, v131
	v_lshrrev_b32_e32 v133, 25, v133
	v_add_u32_e32 v182, 0x100, v131
	v_add_u32_e32 v133, v131, v133
	v_cmp_lt_i32_e32 vcc, s87, v131
	v_mov_b32_e32 v131, v182
	v_ashrrev_i32_e32 v133, 7, v133
	v_mad_u64_u32 v[184:185], s[20:21], v133, s22, v[130:131]
	v_lshlrev_b32_e32 v182, 3, v133
	v_mad_u64_u32 v[186:187], s[20:21], v133, s23, v[128:129]
	v_add_u32_e32 v133, 0x400, v184
	v_add_u32_e32 v192, 0x800, v184
	v_add_u32_e32 v194, 0xc00, v184
	ds_read2_b32 v[188:189], v184 offset1:132
	ds_read2_b32 v[184:185], v133 offset0:8 offset1:140
	ds_read2_b32 v[192:193], v192 offset0:16 offset1:148
	ds_read2_b32 v[194:195], v194 offset0:24 offset1:156
	v_ashrrev_i32_e32 v187, 31, v186
	v_ashrrev_i32_e32 v183, 31, v182
	v_lshl_add_u64 v[186:187], s[2:3], 0, v[186:187]
	s_or_b64 s[6:7], vcc, s[6:7]
	v_add_u32_e32 v128, 0x120000, v128
	v_add_u32_e32 v130, 0x400, v130
	v_lshl_add_u64 v[186:187], v[182:183], 1, v[186:187]
	s_waitcnt lgkmcnt(0)
	v_cvt_pk_bf16_f32 v182, v188, v189
	v_cvt_pk_bf16_f32 v183, v184, v185
	v_cvt_pk_bf16_f32 v184, v192, v193
	v_cvt_pk_bf16_f32 v185, v194, v195
	global_store_dwordx4 v[186:187], v[182:185], off
	s_andn2_b64 exec, exec, s[6:7]
	s_cbranch_execnz .LBB0_594

; DI int TID() { int t = threadIdx.x; asm volatile("" : "+v"(t)); return t; }
; DI bf16x8 pack8f(const float* v) { u32x4 w = {cvtpk(v[0], v[1]), cvtpk(v[2], v[3]), cvtpk(v[4], v[5]), cvtpk(v[6], v[7])}; return __builtin_bit_cast(bf16x8, w); }
; DI void store_R(const float* Cs, int cb, int nc, bfu* dst, long ld, float scale, const float* rs = nullptr) {
;   const int cpr = nc >> 3;
;   for (int u = TID(); u < 128 * cpr; u += NT) {
;     int row = u / cpr, c8 = (u % cpr) * 8; float v[8]; ldrow8(Cs, row, cb + c8, v);
;     float s = rs ? scale * rs[row] : scale;
;     for (int j = 0; j < 8; ++j) v[j] *= s;
;     st8(dst + row * ld + c8, pack8f(v));
;   }
; }
.LBB0_600:
	v_ashrrev_i32_e32 v133, 31, v128
	v_lshrrev_b32_e32 v133, 28, v133
	v_add_u32_e32 v133, v128, v133
	v_add_u32_e32 v182, 0x100, v128
	v_ashrrev_i32_e32 v192, 4, v133
	v_and_b32_e32 v133, -16, v133
	v_cmp_lt_i32_e32 vcc, s87, v128
	v_mov_b32_e32 v128, v182
	v_lshlrev_b32_e32 v182, 7, v192
	v_add_u32_e32 v133, v131, v133
	v_sub_u32_e32 v194, v130, v182
	ds_read_b128 v[182:185], v133
	ds_read_b128 v[186:189], v133 offset:16
	v_ashrrev_i32_e32 v193, 31, v192
	v_lshlrev_b64 v[192:193], 8, v[192:193]
	v_lshl_add_u64 v[192:193], s[2:3], 0, v[192:193]
	v_ashrrev_i32_e32 v195, 31, v194
	s_waitcnt lgkmcnt(0)
	v_pk_mul_f32 v[182:183], v[182:183], s[20:21] op_sel_hi:[1,0]
	v_pk_mul_f32 v[184:185], v[184:185], s[20:21] op_sel_hi:[1,0]
	v_pk_mul_f32 v[186:187], v[186:187], s[20:21] op_sel_hi:[1,0]
	v_pk_mul_f32 v[188:189], v[188:189], s[20:21] op_sel_hi:[1,0]
	s_or_b64 s[6:7], vcc, s[6:7]
	v_add_u32_e32 v131, 0x2000, v131
	v_add_u32_e32 v130, 0x800, v130
	v_lshl_add_u64 v[192:193], v[194:195], 1, v[192:193]
	v_cvt_pk_bf16_f32 v182, v182, v183
	v_cvt_pk_bf16_f32 v183, v184, v185
	v_cvt_pk_bf16_f32 v184, v186, v187
	v_cvt_pk_bf16_f32 v185, v188, v189
	global_store_dwordx4 v[192:193], v[182:185], off
	s_andn2_b64 exec, exec, s[6:7]
	s_cbranch_execnz .LBB0_600

; DI int TID() { int t = threadIdx.x; asm volatile("" : "+v"(t)); return t; }
; DI bf16x8 pack8f(const float* v) { u32x4 w = {cvtpk(v[0], v[1]), cvtpk(v[2], v[3]), cvtpk(v[4], v[5]), cvtpk(v[6], v[7])}; return __builtin_bit_cast(bf16x8, w); }
; DI void store_R(const float* Cs, int cb, int nc, bfu* dst, long ld, float scale, const float* rs = nullptr) {
;   const int cpr = nc >> 3;
;   for (int u = TID(); u < 128 * cpr; u += NT) {
;     int row = u / cpr, c8 = (u % cpr) * 8; float v[8]; ldrow8(Cs, row, cb + c8, v);
;     float s = rs ? scale * rs[row] : scale;
;     for (int j = 0; j < 8; ++j) v[j] *= s;
;     st8(dst + row * ld + c8, pack8f(v));
;   }
; }
; DI void epi_in0(const Params& p, float* Cs, int m0, int n0) {
;     ...
;     for (int m = 0; m < 2; ++m) store_R(Cs, m * 64, 64, dst + ((long)(bg * 32 + head * 2 + m) * T + t0) * 64, 64, isq ? 0.125f * LOG2E : 1.f);
.LBB0_620:
	v_ashrrev_i32_e32 v183, 31, v133
	v_lshrrev_b32_e32 v183, 29, v183
	v_add_u32_e32 v183, v133, v183
	v_ashrrev_i32_e32 v188, 3, v183
	v_add_u32_e32 v184, 0x100, v133
	v_mad_u64_u32 v[192:193], s[22:23], v188, s24, v[128:129]
	v_cmp_lt_i32_e32 vcc, s25, v133
	v_mov_b32_e32 v133, v184
	ds_read_b128 v[184:187], v192
	ds_read_b128 v[192:195], v192 offset:16
	v_lshlrev_b32_e32 v183, 6, v188
	v_ashrrev_i32_e32 v189, 31, v188
	v_sub_u32_e32 v196, v182, v183
	v_lshlrev_b64 v[188:189], 7, v[188:189]
	v_lshl_add_u64 v[188:189], s[2:3], 0, v[188:189]
	v_ashrrev_i32_e32 v197, 31, v196
	s_waitcnt lgkmcnt(0)
	v_pk_mul_f32 v[184:185], v[130:131], v[184:185]
	v_pk_mul_f32 v[186:187], v[130:131], v[186:187]
	v_pk_mul_f32 v[192:193], v[130:131], v[192:193]
	v_pk_mul_f32 v[194:195], v[130:131], v[194:195]
	s_or_b64 s[6:7], vcc, s[6:7]
	v_add_u32_e32 v128, 0x2000, v128
	v_add_u32_e32 v182, 0x800, v182
	v_lshl_add_u64 v[188:189], v[196:197], 1, v[188:189]
	v_cvt_pk_bf16_f32 v184, v184, v185
	v_cvt_pk_bf16_f32 v185, v186, v187
	v_cvt_pk_bf16_f32 v186, v192, v193
	v_cvt_pk_bf16_f32 v187, v194, v195
	global_store_dwordx4 v[188:189], v[184:187], off
	s_andn2_b64 exec, exec, s[6:7]
	s_cbranch_execnz .LBB0_620

; DI int TID() { int t = threadIdx.x; asm volatile("" : "+v"(t)); return t; }
; DI bf16x8 pack8f(const float* v) { u32x4 w = {cvtpk(v[0], v[1]), cvtpk(v[2], v[3]), cvtpk(v[4], v[5]), cvtpk(v[6], v[7])}; return __builtin_bit_cast(bf16x8, w); }
; DI void store_R(const float* Cs, int cb, int nc, bfu* dst, long ld, float scale, const float* rs = nullptr) {
;   const int cpr = nc >> 3;
;   for (int u = TID(); u < 128 * cpr; u += NT) {
;     int row = u / cpr, c8 = (u % cpr) * 8; float v[8]; ldrow8(Cs, row, cb + c8, v);
;     float s = rs ? scale * rs[row] : scale;
;     for (int j = 0; j < 8; ++j) v[j] *= s;
;     st8(dst + row * ld + c8, pack8f(v));
;   }
; }
; DI void epi_in0(const Params& p, float* Cs, int m0, int n0) {
;     ...
;     for (int m = 0; m < 2; ++m) store_R(Cs, m * 64, 64, dst + ((long)(bg * 32 + head * 2 + m) * T + t0) * 64, 64, isq ? 0.125f * LOG2E : 1.f);
.LBB0_623:
	v_ashrrev_i32_e32 v183, 31, v133
	v_lshrrev_b32_e32 v183, 29, v183
	v_add_u32_e32 v183, v133, v183
	v_ashrrev_i32_e32 v188, 3, v183
	v_add_u32_e32 v184, 0x100, v133
	v_mad_u64_u32 v[192:193], s[20:21], v188, s22, v[128:129]
	v_cmp_lt_i32_e32 vcc, s23, v133
	v_mov_b32_e32 v133, v184
	ds_read_b128 v[184:187], v192
	ds_read_b128 v[192:195], v192 offset:16
	v_lshlrev_b32_e32 v183, 6, v188
	v_ashrrev_i32_e32 v189, 31, v188
	v_sub_u32_e32 v196, v182, v183
	v_lshlrev_b64 v[188:189], 7, v[188:189]
	v_lshl_add_u64 v[188:189], s[2:3], 0, v[188:189]
	v_ashrrev_i32_e32 v197, 31, v196
	s_waitcnt lgkmcnt(0)
	v_pk_mul_f32 v[184:185], v[130:131], v[184:185]
	v_pk_mul_f32 v[186:187], v[130:131], v[186:187]
	v_pk_mul_f32 v[192:193], v[130:131], v[192:193]
	v_pk_mul_f32 v[194:195], v[130:131], v[194:195]
	s_or_b64 s[6:7], vcc, s[6:7]
	v_add_u32_e32 v128, 0x2000, v128
	v_add_u32_e32 v182, 0x800, v182
	v_lshl_add_u64 v[188:189], v[196:197], 1, v[188:189]
	v_cvt_pk_bf16_f32 v184, v184, v185
	v_cvt_pk_bf16_f32 v185, v186, v187
	v_cvt_pk_bf16_f32 v186, v192, v193
	v_cvt_pk_bf16_f32 v187, v194, v195
	global_store_dwordx4 v[188:189], v[184:187], off
	s_andn2_b64 exec, exec, s[6:7]
	s_cbranch_execnz .LBB0_623

; DI int TID() { int t = threadIdx.x; asm volatile("" : "+v"(t)); return t; }
; DI unsigned cvtpk(float lo, float hi) { f32x2_t v = {lo, hi}; bf16x2_t b = __builtin_convertvector(v, bf16x2_t); return __builtin_bit_cast(unsigned, b); }
; DI void store_T_regs(const f32x16 (&acc)[2][4], int h, bfu* dst, const float* rs) {
;   const int tid = TID(), lane = tid & 63, w = tid >> 6, wm = w >> 1, wn = w & 1, l32 = lane & 31, hi = lane >> 5;
;   if (wn != h) return;
; #pragma unroll
;   for (int mi = 0; mi < 2; ++mi)
; #pragma unroll
;     for (int ni = 0; ni < 4; ++ni)
; #pragma unroll
;       for (int rg = 0; rg < 4; ++rg) {
;         const int row = wm * 64 + mi * 32 + 8 * rg + 4 * hi;
;         float s0 = 1.f, s1 = 1.f, s2 = 1.f, s3 = 1.f;
;         if (rs) { s0 = rs[row]; s1 = rs[row + 1]; s2 = rs[row + 2]; s3 = rs[row + 3]; }
;         const u32x2 v = {cvtpk(acc[mi][ni][4 * rg] * s0, acc[mi][ni][4 * rg + 1] * s1), cvtpk(acc[mi][ni][4 * rg + 2] * s2, acc[mi][ni][4 * rg + 3] * s3)};
;         *reinterpret_cast<u32x2*>(dst + (long)(ni * 32 + l32) * T + row) = v;
;       }
; }
; DI void phase_gemm(const Params& p, int g, int kind, char* smem, float* rsl, int* s_item, int vlo, int vhi, int cslot) {
;     ...
;         const int bgq = m0 / T, t0q = m0 % T; bfu* td = nullptr; const float* trs = nullptr;
;         if (kind == 0 && nh >= 4096 && nh < 6144) td = (bfu*)(G + L0_VT) + ((long)(bgq * 16 + ((nh - 4096) >> 7)) * 128) * T + t0q;
;         else if (kind == 0 && nh >= 8192 && nh < 10240) td = (bfu*)(G + L0_MVT) + ((long)(bgq * 8 + ((nh - 8192) >> 8)) * 256 + ((nh - 8192) & 255)) * T + t0q;
;         else if (kind == 1 && nh >= 4096 && nh < 6144) td = (bfu*)(G + L1_RVT) + ((long)(bgq * 8 + ((nh - 4096) >> 8)) * 256 + ((nh - 4096) & 255)) * T + t0q;
;         else if (kind == 2 && nt >= 12 && (nh & 255) == 128) { td = (bfu*)(G + L1_VT) + ((long)(bgq * 16 + (nh >> 8)) * 128) * T + t0q; trs = rsl; }
;         if (td) { store_T_regs(acc, h, td, trs); continue; }
.LBB0_632:
	s_cmp_eq_u64 s[2:3], 0
	s_cbranch_scc1 .LBB0_636
	v_mov_b32_e32 v128, v202
	s_nop 0
	v_and_b32_e32 v130, 64, v128
	v_cmp_ne_u32_e32 vcc, 0, v130
	s_and_saveexec_b64 s[0:1], vcc
	s_cbranch_execz .LBB0_635
	v_and_b32_e32 v131, 31, v128
	v_ashrrev_i32_e32 v130, 1, v128
	v_lshrrev_b32_e32 v128, 3, v128
	v_and_b32_e32 v128, 4, v128
	s_movk_i32 s6, 0xffc0
	v_and_or_b32 v130, v130, s6, v128
	v_mul_u32_u24_e32 v128, 0x900, v131
	v_lshlrev_b32_e32 v128, 1, v128
	v_ashrrev_i32_e32 v131, 31, v130
	v_lshl_add_u64 v[182:183], s[2:3], 0, v[128:129]
	v_lshlrev_b64 v[186:187], 1, v[130:131]
	v_cvt_pk_bf16_f32 v184, v112, v113
	v_cvt_pk_bf16_f32 v185, v114, v115
	v_lshl_add_u64 v[188:189], v[182:183], 0, v[186:187]
	global_store_dwordx2 v[188:189], v[184:185], off
	v_or_b32_e32 v184, 8, v130
	v_cvt_pk_bf16_f32 v192, v116, v117
	v_cvt_pk_bf16_f32 v193, v118, v119
	v_cvt_pk_bf16_f32 v196, v124, v125
	v_cvt_pk_bf16_f32 v197, v126, v127
	s_mov_b64 s[2:3], 0x24000
	v_ashrrev_i32_e32 v185, 31, v184
	global_store_dwordx2 v[188:189], v[192:193], off offset:16
	v_or_b32_e32 v192, 16, v130
	v_cvt_pk_bf16_f32 v194, v120, v121
	v_cvt_pk_bf16_f32 v195, v122, v123
	global_store_dwordx2 v[188:189], v[196:197], off offset:48
	v_lshl_add_u64 v[196:197], v[182:183], 0, s[2:3]
	v_ashrrev_i32_e32 v193, 31, v192
	global_store_dwordx2 v[188:189], v[194:195], off offset:32
	v_or_b32_e32 v194, 24, v130
	v_cvt_pk_bf16_f32 v198, v96, v97
	v_cvt_pk_bf16_f32 v199, v98, v99
	v_lshl_add_u64 v[204:205], v[196:197], 0, v[186:187]
	v_lshlrev_b64 v[184:185], 1, v[184:185]
	v_ashrrev_i32_e32 v195, 31, v194
	global_store_dwordx2 v[204:205], v[198:199], off
	v_cvt_pk_bf16_f32 v198, v100, v101
	v_cvt_pk_bf16_f32 v199, v102, v103
	v_lshl_add_u64 v[204:205], v[196:197], 0, v[184:185]
	v_lshlrev_b64 v[192:193], 1, v[192:193]
	global_store_dwordx2 v[204:205], v[198:199], off
	v_cvt_pk_bf16_f32 v198, v104, v105
	v_cvt_pk_bf16_f32 v199, v106, v107
	v_lshl_add_u64 v[204:205], v[196:197], 0, v[192:193]
	v_lshlrev_b64 v[194:195], 1, v[194:195]
	global_store_dwordx2 v[204:205], v[198:199], off
	v_cvt_pk_bf16_f32 v198, v108, v109
	v_cvt_pk_bf16_f32 v199, v110, v111
	v_lshl_add_u64 v[204:205], v[196:197], 0, v[194:195]
	s_mov_b64 s[2:3], 0x48000
	global_store_dwordx2 v[204:205], v[198:199], off
	v_lshl_add_u64 v[198:199], v[182:183], 0, s[2:3]
	v_cvt_pk_bf16_f32 v204, v80, v81
	v_cvt_pk_bf16_f32 v205, v82, v83
	v_lshl_add_u64 v[206:207], v[198:199], 0, v[186:187]
	global_store_dwordx2 v[206:207], v[204:205], off
	v_cvt_pk_bf16_f32 v204, v84, v85
	v_cvt_pk_bf16_f32 v205, v86, v87
	v_lshl_add_u64 v[206:207], v[198:199], 0, v[184:185]
	global_store_dwordx2 v[206:207], v[204:205], off
	v_cvt_pk_bf16_f32 v204, v88, v89
	v_cvt_pk_bf16_f32 v205, v90, v91
	v_lshl_add_u64 v[206:207], v[198:199], 0, v[192:193]
	s_mov_b64 s[2:3], 0x6c000
	global_store_dwordx2 v[206:207], v[204:205], off
	v_cvt_pk_bf16_f32 v204, v92, v93
	v_cvt_pk_bf16_f32 v205, v94, v95
	v_lshl_add_u64 v[206:207], v[198:199], 0, v[194:195]
	v_lshl_add_u64 v[182:183], v[182:183], 0, s[2:3]
	global_store_dwordx2 v[206:207], v[204:205], off
	v_cvt_pk_bf16_f32 v204, v64, v65
	v_cvt_pk_bf16_f32 v205, v66, v67
	v_lshl_add_u64 v[186:187], v[182:183], 0, v[186:187]
	global_store_dwordx2 v[186:187], v[204:205], off
	v_cvt_pk_bf16_f32 v186, v68, v69
	v_cvt_pk_bf16_f32 v187, v70, v71
	v_lshl_add_u64 v[184:185], v[182:183], 0, v[184:185]
	global_store_dwordx2 v[184:185], v[186:187], off
	v_cvt_pk_bf16_f32 v184, v72, v73
	v_cvt_pk_bf16_f32 v185, v74, v75
	v_lshl_add_u64 v[186:187], v[182:183], 0, v[192:193]
	global_store_dwordx2 v[186:187], v[184:185], off
	v_cvt_pk_bf16_f32 v184, v76, v77
	v_cvt_pk_bf16_f32 v185, v78, v79
	v_lshl_add_u64 v[186:187], v[182:183], 0, v[194:195]
	global_store_dwordx2 v[186:187], v[184:185], off
	v_or_b32_e32 v184, 32, v130
	v_cvt_pk_bf16_f32 v186, v48, v49
	v_cvt_pk_bf16_f32 v187, v50, v51
	v_ashrrev_i32_e32 v185, 31, v184
	global_store_dwordx2 v[188:189], v[186:187], off offset:64
	v_or_b32_e32 v186, 40, v130
	v_cvt_pk_bf16_f32 v192, v52, v53
	v_cvt_pk_bf16_f32 v193, v54, v55
	v_cvt_pk_bf16_f32 v194, v56, v57
	v_cvt_pk_bf16_f32 v195, v58, v59
	v_ashrrev_i32_e32 v187, 31, v186
	global_store_dwordx2 v[188:189], v[192:193], off offset:80
	v_or_b32_e32 v192, 48, v130
	global_store_dwordx2 v[188:189], v[194:195], off offset:96
	v_cvt_pk_bf16_f32 v194, v60, v61
	v_cvt_pk_bf16_f32 v195, v62, v63
	v_lshlrev_b64 v[184:185], 1, v[184:185]
	v_ashrrev_i32_e32 v193, 31, v192
	v_or_b32_e32 v130, 56, v130
	global_store_dwordx2 v[188:189], v[194:195], off offset:112
	v_cvt_pk_bf16_f32 v188, v32, v33
	v_cvt_pk_bf16_f32 v189, v34, v35
	v_lshl_add_u64 v[194:195], v[196:197], 0, v[184:185]
	v_lshlrev_b64 v[186:187], 1, v[186:187]
	v_ashrrev_i32_e32 v131, 31, v130
	global_store_dwordx2 v[194:195], v[188:189], off
	v_cvt_pk_bf16_f32 v188, v36, v37
	v_cvt_pk_bf16_f32 v189, v38, v39
	v_lshl_add_u64 v[194:195], v[196:197], 0, v[186:187]
	v_lshlrev_b64 v[192:193], 1, v[192:193]
	global_store_dwordx2 v[194:195], v[188:189], off
	v_cvt_pk_bf16_f32 v188, v40, v41
	v_cvt_pk_bf16_f32 v189, v42, v43
	v_lshl_add_u64 v[194:195], v[196:197], 0, v[192:193]
	v_lshlrev_b64 v[130:131], 1, v[130:131]
	global_store_dwordx2 v[194:195], v[188:189], off
	v_cvt_pk_bf16_f32 v188, v44, v45
	v_cvt_pk_bf16_f32 v189, v46, v47
	v_lshl_add_u64 v[194:195], v[196:197], 0, v[130:131]
	global_store_dwordx2 v[194:195], v[188:189], off
	v_cvt_pk_bf16_f32 v188, v16, v17
	v_cvt_pk_bf16_f32 v189, v18, v19
	v_lshl_add_u64 v[194:195], v[198:199], 0, v[184:185]
	global_store_dwordx2 v[194:195], v[188:189], off
	v_cvt_pk_bf16_f32 v188, v20, v21
	v_cvt_pk_bf16_f32 v189, v22, v23
	v_lshl_add_u64 v[194:195], v[198:199], 0, v[186:187]
	global_store_dwordx2 v[194:195], v[188:189], off
	v_cvt_pk_bf16_f32 v188, v24, v25
	v_cvt_pk_bf16_f32 v189, v26, v27
	v_lshl_add_u64 v[194:195], v[198:199], 0, v[192:193]
	global_store_dwordx2 v[194:195], v[188:189], off
	v_cvt_pk_bf16_f32 v188, v28, v29
	v_cvt_pk_bf16_f32 v189, v30, v31
	v_lshl_add_u64 v[194:195], v[198:199], 0, v[130:131]
	global_store_dwordx2 v[194:195], v[188:189], off
	v_cvt_pk_bf16_f32 v188, v0, v1
	v_cvt_pk_bf16_f32 v189, v2, v3
	v_lshl_add_u64 v[184:185], v[182:183], 0, v[184:185]
	global_store_dwordx2 v[184:185], v[188:189], off
	v_cvt_pk_bf16_f32 v184, v4, v5
	v_cvt_pk_bf16_f32 v185, v6, v7
	v_lshl_add_u64 v[186:187], v[182:183], 0, v[186:187]
	global_store_dwordx2 v[186:187], v[184:185], off
	v_cvt_pk_bf16_f32 v184, v8, v9
	v_cvt_pk_bf16_f32 v185, v10, v11
	v_lshl_add_u64 v[186:187], v[182:183], 0, v[192:193]
	global_store_dwordx2 v[186:187], v[184:185], off
	v_cvt_pk_bf16_f32 v184, v12, v13
	v_cvt_pk_bf16_f32 v185, v14, v15
	v_lshl_add_u64 v[130:131], v[182:183], 0, v[130:131]
	global_store_dwordx2 v[130:131], v[184:185], off

;   DI const float* ab_b_if() const { return (const float*)sp[9]; }
; DI float logsig(float v) { return fminf(v, 0.f) - log1pf(__expf(-fabsf(v))); }
; DI void epi_in0(const Params& p, float* Cs, int m0, int n0) {
;     ...
;       const int ch = sidx & 1, dh = sidx >> 1, dir = dh >> 3, head = dh & 7, row = ch * 64 + lane;
;       const float ig = Cs[row * CLD + dir * 8 + head] + p.ab_b_if()[dir * 8 + head];
;       const float f = logsig(Cs[row * CLD + 16 + dir * 8 + head] + p.ab_b_if()[16 + dir * 8 + head]);
;       float bc = f;
;       for (int off = 1; off < 64; off <<= 1) {
;         const float yu = __shfl_up(bc, off), yd = __shfl_down(bc, off);
;         const bool ok = dir == 0 ? lane >= off : lane + off < 64;
;         if (ok) bc += dir == 0 ? yu : yd;
;       }
;       const float gs = ig - bc;
;       float cm = gs;
;       for (int off = 1; off < 64; off <<= 1) {
;         const float yu = __shfl_up(cm, off), yd = __shfl_down(cm, off);
;         const bool ok = dir == 0 ? lane >= off : lane + off < 64;
;         if (ok) cm = fmaxf(cm, dir == 0 ? yu : yd);
;       }
.LBB0_648:
	v_ashrrev_i32_e32 v20, 4, v9
	v_bfe_u32 v19, v9, 1, 3
	v_lshlrev_b32_e32 v26, 3, v20
	v_or_b32_e32 v22, v26, v19
	v_ashrrev_i32_e32 v23, 31, v22
	v_and_or_b32 v128, v18, 64, v4
	s_waitcnt lgkmcnt(0)
	v_lshl_add_u64 v[24:25], v[22:23], 2, v[0:1]
	v_ashrrev_i32_e32 v23, 31, v26
	v_mul_u32_u24_e32 v2, 0x210, v128
	v_lshlrev_b32_e32 v3, 5, v20
	v_lshlrev_b32_e32 v21, 2, v19
	v_lshl_add_u64 v[22:23], v[22:23], 2, v[0:1]
	v_add3_u32 v2, v2, v3, v21
	global_load_dword v21, v[24:25], off
	ds_read2_b32 v[2:3], v2 offset1:16
	global_load_dword v22, v[22:23], off offset:64
	v_cmp_gt_u32_e64 s[22:23], 16, v9
	s_xor_b64 s[34:35], s[20:21], s[22:23]
	v_add_u32_e32 v18, 0x100, v18
	s_waitcnt vmcnt(0) lgkmcnt(0)
	v_add_f32_e32 v2, v2, v21
	v_add_f32_e32 v3, v3, v22
	v_min_f32_e32 v24, 0, v3
	v_mul_f32_e64 v3, |v3|, s17
	v_exp_f32_e32 v3, v3
	s_nop 0
	v_add_f32_e32 v25, 1.0, v3
	v_add_f32_e32 v22, -1.0, v25
	v_sub_f32_e32 v23, v22, v25
	v_add_f32_e32 v23, 1.0, v23
	v_sub_f32_e32 v22, v3, v22
	v_add_f32_e32 v26, v22, v23
	v_frexp_mant_f32_e32 v22, v25
	v_cmp_gt_f32_e64 s[0:1], s62, v22
	v_cvt_f64_f32_e32 v[22:23], v25
	v_frexp_exp_i32_f64_e32 v22, v[22:23]
	v_subbrev_co_u32_e64 v22, s[0:1], 0, v22, s[0:1]
	v_sub_u32_e32 v23, 0, v22
	v_ldexp_f32 v25, v25, v23
	v_ldexp_f32 v23, v26, v23
	v_add_f32_e32 v26, -1.0, v25
	v_add_f32_e32 v27, 1.0, v26
	v_sub_f32_e32 v27, v25, v27
	v_add_f32_e32 v27, v23, v27
	v_add_f32_e32 v28, v26, v27
	v_sub_f32_e32 v26, v28, v26
	v_sub_f32_e32 v26, v27, v26
	v_add_f32_e32 v27, 1.0, v25
	v_add_f32_e32 v29, -1.0, v27
	v_sub_f32_e32 v25, v25, v29
	v_add_f32_e32 v23, v23, v25
	v_add_f32_e32 v25, v27, v23
	v_sub_f32_e32 v27, v25, v27
	v_sub_f32_e32 v23, v23, v27
	v_rcp_f32_e32 v27, v25
	v_cvt_f32_i32_e32 v22, v22
	v_cmp_neq_f32_e64 s[0:1], s74, v3
	v_mul_f32_e32 v29, v28, v27
	v_mul_f32_e32 v30, v25, v29
	v_fma_f32 v31, v29, v25, -v30
	v_fmac_f32_e32 v31, v29, v23
	v_add_f32_e32 v32, v30, v31
	v_sub_f32_e32 v33, v28, v32
	v_sub_f32_e32 v28, v28, v33
	v_sub_f32_e32 v30, v32, v30
	v_sub_f32_e32 v28, v28, v32
	v_add_f32_e32 v26, v26, v28
	v_sub_f32_e32 v28, v30, v31
	v_add_f32_e32 v26, v28, v26
	v_add_f32_e32 v28, v33, v26
	v_mul_f32_e32 v30, v27, v28
	v_mul_f32_e32 v31, v25, v30
	v_fma_f32 v25, v30, v25, -v31
	v_fmac_f32_e32 v25, v30, v23
	v_sub_f32_e32 v23, v33, v28
	v_add_f32_e32 v23, v26, v23
	v_add_f32_e32 v26, v31, v25
	v_sub_f32_e32 v32, v28, v26
	v_sub_f32_e32 v28, v28, v32
	v_sub_f32_e32 v31, v26, v31
	v_sub_f32_e32 v26, v28, v26
	v_add_f32_e32 v23, v23, v26
	v_sub_f32_e32 v25, v31, v25
	v_add_f32_e32 v23, v25, v23
	v_add_f32_e32 v25, v29, v30
	v_add_f32_e32 v23, v32, v23
	v_sub_f32_e32 v26, v25, v29
	v_mul_f32_e32 v23, v27, v23
	v_sub_f32_e32 v26, v30, v26
	v_add_f32_e32 v23, v26, v23
	v_mul_f32_e32 v29, 0x3f317218, v22
	v_add_f32_e32 v26, v25, v23
	v_fma_f32 v30, v22, s71, -v29
	v_mul_f32_e32 v27, v26, v26
	v_fmac_f32_e32 v30, 0xb102e308, v22
	v_sub_f32_e32 v22, v26, v25
	v_fmamk_f32 v28, v27, 0x3e9b6dac, v201
	v_sub_f32_e32 v22, v23, v22
	v_add_f32_e32 v23, v29, v30
	v_fmaak_f32 v28, v27, v28, 0x3f2aaada
	v_sub_f32_e32 v25, v23, v29
	v_ldexp_f32 v29, v26, 1
	v_mul_f32_e32 v26, v26, v27
	v_mul_f32_e32 v26, v26, v28
	v_add_f32_e32 v27, v29, v26
	v_sub_f32_e32 v28, v27, v29
	v_ldexp_f32 v22, v22, 1
	v_sub_f32_e32 v26, v26, v28
	v_add_f32_e32 v22, v22, v26
	v_add_f32_e32 v26, v27, v22
	v_sub_f32_e32 v27, v26, v27
	v_sub_f32_e32 v22, v22, v27
	v_add_f32_e32 v27, v23, v26
	v_sub_f32_e32 v28, v27, v23
	v_sub_f32_e32 v29, v27, v28
	v_sub_f32_e32 v25, v30, v25
	v_sub_f32_e32 v23, v23, v29
	v_sub_f32_e32 v26, v26, v28
	v_add_f32_e32 v23, v26, v23
	v_add_f32_e32 v26, v25, v22
	v_sub_f32_e32 v28, v26, v25
	v_sub_f32_e32 v29, v26, v28
	v_sub_f32_e32 v25, v25, v29
	v_sub_f32_e32 v22, v22, v28
	v_add_f32_e32 v23, v26, v23
	v_add_f32_e32 v22, v22, v25
	v_add_f32_e32 v25, v27, v23
	v_sub_f32_e32 v26, v25, v27
	v_sub_f32_e32 v23, v23, v26
	v_add_f32_e32 v22, v22, v23
	v_add_f32_e32 v22, v25, v22
	v_cndmask_b32_e64 v22, v209, v22, s[0:1]
	v_cmp_ngt_f32_e64 s[0:1], -1.0, v3
	s_nop 1
	v_cndmask_b32_e64 v22, v214, v22, s[0:1]
	v_cmp_neq_f32_e64 s[0:1], -1.0, v3
	s_nop 1
	v_cndmask_b32_e64 v22, v242, v22, s[0:1]
	v_cmp_lt_f32_e64 s[0:1], |v3|, s75
	s_nop 1
	v_cndmask_b32_e64 v3, v22, v3, s[0:1]
	v_sub_f32_e32 v3, v24, v3
	ds_bpermute_b32 v22, v5, v3
	ds_bpermute_b32 v23, v6, v3
	v_cndmask_b32_e64 v24, 63, 0, s[22:23]
	v_cmp_eq_u32_e64 s[24:25], v4, v24
	v_readlane_b32 s0, v254, 29
	v_readlane_b32 s1, v254, 30
	s_waitcnt lgkmcnt(0)
; DI void epi_in0(const Params& p, float* Cs, int m0, int n0) {
;     ...
;       for (int off = 1; off < 64; off <<= 1) {
;         const float yu = __shfl_up(bc, off), yd = __shfl_down(bc, off);
;         const bool ok = dir == 0 ? lane >= off : lane + off < 64;
;         if (ok) bc += dir == 0 ? yu : yd;
;       }
;       const float gs = ig - bc;
;       float cm = gs;
;       for (int off = 1; off < 64; off <<= 1) {
;         const float yu = __shfl_up(cm, off), yd = __shfl_down(cm, off);
;         const bool ok = dir == 0 ? lane >= off : lane + off < 64;
;         if (ok) cm = fmaxf(cm, dir == 0 ? yu : yd);
;       }
;       const long o = ((long)(dir * GB + bg) * 8 + head) * T + t0 + row;
;       gb[o] = bc; gsv[o] = gs; gc[o] = cm;
	v_cndmask_b32_e64 v22, v23, v22, s[22:23]
	v_add_f32_e32 v22, v3, v22
	v_cndmask_b32_e64 v3, v22, v3, s[24:25]
	ds_bpermute_b32 v22, v7, v3
	ds_bpermute_b32 v23, v8, v3
	v_cndmask_b32_e64 v24, 0, 1, s[0:1]
	v_readlane_b32 s0, v255, 9
	v_readlane_b32 s1, v255, 10
	s_waitcnt lgkmcnt(0)
	v_cndmask_b32_e64 v22, v23, v22, s[22:23]
	v_cndmask_b32_e64 v25, 0, 1, s[0:1]
	v_cndmask_b32_e64 v24, v25, v24, s[22:23]
	v_and_b32_e32 v24, 1, v24
	v_cmp_eq_u32_e64 s[26:27], 1, v24
	v_add_f32_e32 v22, v3, v22
	v_readlane_b32 s0, v255, 11
	v_cndmask_b32_e64 v3, v3, v22, s[26:27]
	ds_bpermute_b32 v22, v10, v3
	ds_bpermute_b32 v23, v11, v3
	v_readlane_b32 s1, v255, 12
	s_waitcnt lgkmcnt(0)
	v_cndmask_b32_e64 v22, v23, v22, s[22:23]
	v_cndmask_b32_e64 v24, 0, 1, s[0:1]
	v_readlane_b32 s0, v255, 13
	v_readlane_b32 s1, v255, 14
	v_add_f32_e32 v22, v3, v22
	s_nop 0
	v_cndmask_b32_e64 v25, 0, 1, s[0:1]
	v_cndmask_b32_e64 v24, v25, v24, s[22:23]
	v_and_b32_e32 v24, 1, v24
	v_cmp_eq_u32_e64 s[28:29], 1, v24
	v_cndmask_b32_e64 v24, 0, 1, s[2:3]
	v_cndmask_b32_e64 v25, 0, 1, s[6:7]
	v_cndmask_b32_e64 v3, v3, v22, s[28:29]
	ds_bpermute_b32 v22, v12, v3
	ds_bpermute_b32 v23, v13, v3
	v_cndmask_b32_e64 v24, v25, v24, s[22:23]
	v_and_b32_e32 v24, 1, v24
	v_cmp_eq_u32_e64 s[0:1], 1, v24
	v_cndmask_b32_e64 v24, 0, 1, vcc
	s_waitcnt lgkmcnt(0)
	v_cndmask_b32_e64 v22, v23, v22, s[22:23]
	v_add_f32_e32 v22, v3, v22
	v_cndmask_b32_e64 v3, v3, v22, s[0:1]
	ds_bpermute_b32 v22, v14, v3
	ds_bpermute_b32 v23, v15, v3
	v_cndmask_b32_e64 v25, 0, 1, s[18:19]
	v_cndmask_b32_e64 v24, v25, v24, s[22:23]
	v_and_b32_e32 v24, 1, v24
	v_cmp_eq_u32_e64 s[30:31], 1, v24
	s_waitcnt lgkmcnt(0)
	v_cndmask_b32_e64 v22, v23, v22, s[22:23]
	v_add_f32_e32 v22, v3, v22
	v_cndmask_b32_e64 v3, v3, v22, s[30:31]
	ds_bpermute_b32 v22, v16, v3
	ds_bpermute_b32 v23, v17, v3
	s_waitcnt lgkmcnt(0)
	v_cndmask_b32_e64 v22, v23, v22, s[22:23]
	v_add_f32_e32 v22, v3, v22
	v_cndmask_b32_e64 v22, v3, v22, s[34:35]
	v_sub_f32_e32 v23, v2, v22
	ds_bpermute_b32 v2, v5, v23
	ds_bpermute_b32 v3, v6, v23
	s_waitcnt lgkmcnt(0)
	v_cndmask_b32_e64 v2, v3, v2, s[22:23]
	v_max_f32_e32 v2, v2, v2
	v_max_f32_e32 v2, v23, v2
	v_cndmask_b32_e64 v2, v2, v23, s[24:25]
	ds_bpermute_b32 v3, v7, v2
	ds_bpermute_b32 v21, v8, v2
	s_waitcnt lgkmcnt(0)
	v_cndmask_b32_e64 v3, v21, v3, s[22:23]
	v_max_f32_e32 v3, v3, v3
	v_max_f32_e32 v3, v2, v3
	v_cndmask_b32_e64 v2, v2, v3, s[26:27]
	ds_bpermute_b32 v3, v10, v2
	ds_bpermute_b32 v21, v11, v2
	s_waitcnt lgkmcnt(0)
	v_cndmask_b32_e64 v3, v21, v3, s[22:23]
	v_max_f32_e32 v3, v3, v3
	v_max_f32_e32 v3, v2, v3
	v_cndmask_b32_e64 v2, v2, v3, s[28:29]
	ds_bpermute_b32 v3, v12, v2
	ds_bpermute_b32 v21, v13, v2
	s_waitcnt lgkmcnt(0)
	v_cndmask_b32_e64 v3, v21, v3, s[22:23]
	v_max_f32_e32 v3, v3, v3
	v_max_f32_e32 v3, v2, v3
	v_cndmask_b32_e64 v2, v2, v3, s[0:1]
	ds_bpermute_b32 v3, v14, v2
	ds_bpermute_b32 v21, v15, v2
	s_waitcnt lgkmcnt(0)
	v_cndmask_b32_e64 v3, v21, v3, s[22:23]
	v_max_f32_e32 v3, v3, v3
	v_max_f32_e32 v3, v2, v3
	v_cndmask_b32_e64 v2, v2, v3, s[30:31]
	ds_bpermute_b32 v3, v16, v2
	ds_bpermute_b32 v21, v17, v2
	s_waitcnt lgkmcnt(0)
	v_cndmask_b32_e64 v3, v21, v3, s[22:23]
	v_max_f32_e32 v3, v3, v3
	v_max_f32_e32 v21, v2, v2
	v_max_f32_e32 v3, v21, v3
	v_cndmask_b32_e64 v24, v2, v3, s[34:35]
	v_lshl_add_u32 v2, v20, 1, s15
	v_ashrrev_i32_e32 v20, 31, v2
	v_lshl_or_b32 v19, v2, 3, v19
	v_lshl_add_u64 v[2:3], v[128:129], 0, s[48:49]
	v_mad_u64_u32 v[2:3], s[0:1], v19, s60, v[2:3]
	v_mad_i32_i24 v3, v20, s60, v3
	v_lshlrev_b64 v[2:3], 2, v[2:3]
	v_lshl_add_u64 v[20:21], s[80:81], 0, v[2:3]
	global_store_dword v[20:21], v22, off
	v_lshl_add_u64 v[20:21], s[94:95], 0, v[2:3]
	v_lshl_add_u64 v[2:3], s[96:97], 0, v[2:3]
	global_store_dword v[2:3], v24, off
	v_add_u32_e32 v2, 4, v9
	v_cmp_lt_i32_e64 s[0:1], 27, v9
	s_or_b64 s[54:55], s[0:1], s[54:55]
	v_mov_b32_e32 v9, v2
	global_store_dword v[20:21], v23, off
	s_andn2_b64 exec, exec, s[54:55]
	s_cbranch_execnz .LBB0_648

; DI int TID() { int t = threadIdx.x; asm volatile("" : "+v"(t)); return t; }
; DI bf16x8 pack8f(const float* v) { u32x4 w = {cvtpk(v[0], v[1]), cvtpk(v[2], v[3]), cvtpk(v[4], v[5]), cvtpk(v[6], v[7])}; return __builtin_bit_cast(bf16x8, w); }
; DI void store_R(const float* Cs, int cb, int nc, bfu* dst, long ld, float scale, const float* rs = nullptr) {
;   const int cpr = nc >> 3;
;   for (int u = TID(); u < 128 * cpr; u += NT) {
;     int row = u / cpr, c8 = (u % cpr) * 8; float v[8]; ldrow8(Cs, row, cb + c8, v);
;     float s = rs ? scale * rs[row] : scale;
;     for (int j = 0; j < 8; ++j) v[j] *= s;
;     st8(dst + row * ld + c8, pack8f(v));
;   }
; }
.LBB0_653:
	v_ashrrev_i32_e32 v3, 31, v0
	v_lshrrev_b32_e32 v3, 28, v3
	v_add_u32_e32 v3, v0, v3
	v_add_u32_e32 v4, 0x100, v0
	v_ashrrev_i32_e32 v12, 4, v3
	v_and_b32_e32 v3, -16, v3
	v_cmp_lt_i32_e32 vcc, s87, v0
	v_mov_b32_e32 v0, v4
	v_lshlrev_b32_e32 v4, 7, v12
	v_add_u32_e32 v3, v2, v3
	v_sub_u32_e32 v14, v1, v4
	ds_read_b128 v[4:7], v3
	ds_read_b128 v[8:11], v3 offset:16
	v_ashrrev_i32_e32 v13, 31, v12
	v_lshlrev_b64 v[12:13], 13, v[12:13]
	v_lshl_add_u64 v[12:13], s[2:3], 0, v[12:13]
	v_ashrrev_i32_e32 v15, 31, v14
	s_or_b64 s[4:5], vcc, s[4:5]
	v_add_u32_e32 v2, 0x2000, v2
	v_add_u32_e32 v1, 0x800, v1
	v_lshl_add_u64 v[12:13], v[14:15], 1, v[12:13]
	s_waitcnt lgkmcnt(0)
	v_cvt_pk_bf16_f32 v4, v4, v5
	v_cvt_pk_bf16_f32 v5, v6, v7
	v_cvt_pk_bf16_f32 v6, v8, v9
	v_cvt_pk_bf16_f32 v7, v10, v11
	global_store_dwordx4 v[12:13], v[4:7], off
	s_andn2_b64 exec, exec, s[4:5]
	s_cbranch_execnz .LBB0_653

; DI int TID() { int t = threadIdx.x; asm volatile("" : "+v"(t)); return t; }
; DI bf16x8 pack8f(const float* v) { u32x4 w = {cvtpk(v[0], v[1]), cvtpk(v[2], v[3]), cvtpk(v[4], v[5]), cvtpk(v[6], v[7])}; return __builtin_bit_cast(bf16x8, w); }
; DI void store_R(const float* Cs, int cb, int nc, bfu* dst, long ld, float scale, const float* rs = nullptr) {
;   const int cpr = nc >> 3;
;   for (int u = TID(); u < 128 * cpr; u += NT) {
;     int row = u / cpr, c8 = (u % cpr) * 8; float v[8]; ldrow8(Cs, row, cb + c8, v);
;     float s = rs ? scale * rs[row] : scale;
;     for (int j = 0; j < 8; ++j) v[j] *= s;
;     st8(dst + row * ld + c8, pack8f(v));
;   }
; }
.LBB0_659:
	v_ashrrev_i32_e32 v3, 31, v0
	v_lshrrev_b32_e32 v3, 28, v3
	v_add_u32_e32 v3, v0, v3
	v_add_u32_e32 v4, 0x100, v0
	v_ashrrev_i32_e32 v12, 4, v3
	v_and_b32_e32 v3, -16, v3
	v_cmp_lt_i32_e32 vcc, s87, v0
	v_mov_b32_e32 v0, v4
	v_lshlrev_b32_e32 v4, 7, v12
	v_add_u32_e32 v3, v2, v3
	v_sub_u32_e32 v14, v1, v4
	ds_read_b128 v[4:7], v3
	ds_read_b128 v[8:11], v3 offset:16
	v_ashrrev_i32_e32 v13, 31, v12
	v_lshlrev_b64 v[12:13], 12, v[12:13]
	v_lshl_add_u64 v[12:13], s[2:3], 0, v[12:13]
	v_ashrrev_i32_e32 v15, 31, v14
	s_or_b64 s[4:5], vcc, s[4:5]
	v_add_u32_e32 v2, 0x2000, v2
	v_add_u32_e32 v1, 0x800, v1
	v_lshl_add_u64 v[12:13], v[14:15], 1, v[12:13]
	s_waitcnt lgkmcnt(0)
	v_cvt_pk_bf16_f32 v4, v4, v5
	v_cvt_pk_bf16_f32 v5, v6, v7
	v_cvt_pk_bf16_f32 v6, v8, v9
	v_cvt_pk_bf16_f32 v7, v10, v11
	global_store_dwordx4 v[12:13], v[4:7], off
	s_andn2_b64 exec, exec, s[4:5]
	s_cbranch_execnz .LBB0_659

;   DI const float* c() const { return (const float*)sp[1]; }
; DI int TID() { int t = threadIdx.x; asm volatile("" : "+v"(t)); return t; }
; DI bf16x8 pack8f(const float* v) { u32x4 w = {cvtpk(v[0], v[1]), cvtpk(v[2], v[3]), cvtpk(v[4], v[5]), cvtpk(v[6], v[7])}; return __builtin_bit_cast(bf16x8, w); }
; DI void store_T(const float* Cs, int cb, int nc, bfu* dst, long ldT, float scale, const float* rs = nullptr) {
;   for (int u = TID(); u < nc * 16; u += NT) {
;     int c = u % nc, rc = (u / nc) * 8; float v[8];
;     for (int j = 0; j < 8; ++j) v[j] = Cs[(rc + j) * CLD + cb + c] * (rs ? scale * rs[rc + j] : scale);
;     st8(dst + c * ldT + rc, pack8f(v));
;   }
; }
.LBB0_665:
	v_ashrrev_i32_e32 v3, 31, v1
	v_lshrrev_b32_e32 v3, 25, v3
	v_add_u32_e32 v3, v1, v3
	v_add_u32_e32 v4, 0x100, v1
	v_ashrrev_i32_e32 v3, 7, v3
	v_cmp_lt_i32_e32 vcc, s87, v1
	v_mov_b32_e32 v1, v4
	v_mad_u64_u32 v[6:7], s[6:7], v3, s15, v[2:3]
	v_lshlrev_b32_e32 v4, 3, v3
	v_mad_u64_u32 v[8:9], s[6:7], v3, s17, v[0:1]
	v_add_u32_e32 v3, 0x400, v6
	v_add_u32_e32 v12, 0x800, v6
	v_add_u32_e32 v14, 0xc00, v6
	ds_read2_b32 v[10:11], v6 offset1:132
	ds_read2_b32 v[6:7], v3 offset0:8 offset1:140
	ds_read2_b32 v[12:13], v12 offset0:16 offset1:148
	ds_read2_b32 v[14:15], v14 offset0:24 offset1:156
	v_ashrrev_i32_e32 v9, 31, v8
	v_ashrrev_i32_e32 v5, 31, v4
	v_lshl_add_u64 v[8:9], s[2:3], 0, v[8:9]
	s_or_b64 s[4:5], vcc, s[4:5]
	v_add_u32_e32 v0, 0x120000, v0
	v_add_u32_e32 v2, 0x400, v2
	v_lshl_add_u64 v[8:9], v[4:5], 1, v[8:9]
	s_waitcnt lgkmcnt(0)
	v_cvt_pk_bf16_f32 v4, v10, v11
	v_cvt_pk_bf16_f32 v5, v6, v7
	v_cvt_pk_bf16_f32 v6, v12, v13
	v_cvt_pk_bf16_f32 v7, v14, v15
	global_store_dwordx4 v[8:9], v[4:7], off
	s_andn2_b64 exec, exec, s[4:5]
	s_cbranch_execnz .LBB0_665

; DI int TID() { int t = threadIdx.x; asm volatile("" : "+v"(t)); return t; }
; DI bf16x8 pack8f(const float* v) { u32x4 w = {cvtpk(v[0], v[1]), cvtpk(v[2], v[3]), cvtpk(v[4], v[5]), cvtpk(v[6], v[7])}; return __builtin_bit_cast(bf16x8, w); }
; DI void store_R(const float* Cs, int cb, int nc, bfu* dst, long ld, float scale, const float* rs = nullptr) {
;   const int cpr = nc >> 3;
;   for (int u = TID(); u < 128 * cpr; u += NT) {
;     int row = u / cpr, c8 = (u % cpr) * 8; float v[8]; ldrow8(Cs, row, cb + c8, v);
;     float s = rs ? scale * rs[row] : scale;
;     for (int j = 0; j < 8; ++j) v[j] *= s;
;     st8(dst + row * ld + c8, pack8f(v));
;   }
; }
.LBB0_671:
	v_ashrrev_i32_e32 v3, 31, v0
	v_lshrrev_b32_e32 v3, 28, v3
	v_add_u32_e32 v3, v0, v3
	v_add_u32_e32 v4, 0x100, v0
	v_ashrrev_i32_e32 v12, 4, v3
	v_and_b32_e32 v3, -16, v3
	v_cmp_lt_i32_e32 vcc, s87, v0
	v_mov_b32_e32 v0, v4
	v_lshlrev_b32_e32 v4, 7, v12
	v_add_u32_e32 v3, v2, v3
	v_sub_u32_e32 v14, v1, v4
	ds_read_b128 v[4:7], v3
	ds_read_b128 v[8:11], v3 offset:16
	v_ashrrev_i32_e32 v13, 31, v12
	v_lshlrev_b64 v[12:13], 8, v[12:13]
	v_lshl_add_u64 v[12:13], s[2:3], 0, v[12:13]
	v_ashrrev_i32_e32 v15, 31, v14
	s_or_b64 s[4:5], vcc, s[4:5]
	v_add_u32_e32 v2, 0x2000, v2
	v_add_u32_e32 v1, 0x800, v1
	v_lshl_add_u64 v[12:13], v[14:15], 1, v[12:13]
	s_waitcnt lgkmcnt(0)
	v_cvt_pk_bf16_f32 v4, v4, v5
	v_cvt_pk_bf16_f32 v5, v6, v7
	v_cvt_pk_bf16_f32 v6, v8, v9
	v_cvt_pk_bf16_f32 v7, v10, v11
	global_store_dwordx4 v[12:13], v[4:7], off
	s_andn2_b64 exec, exec, s[4:5]
	s_cbranch_execnz .LBB0_671

; DI int TID() { int t = threadIdx.x; asm volatile("" : "+v"(t)); return t; }
; DI bf16x8 pack8f(const float* v) { u32x4 w = {cvtpk(v[0], v[1]), cvtpk(v[2], v[3]), cvtpk(v[4], v[5]), cvtpk(v[6], v[7])}; return __builtin_bit_cast(bf16x8, w); }
; DI void store_R(const float* Cs, int cb, int nc, bfu* dst, long ld, float scale, const float* rs = nullptr) {
;   const int cpr = nc >> 3;
;   for (int u = TID(); u < 128 * cpr; u += NT) {
;     int row = u / cpr, c8 = (u % cpr) * 8; float v[8]; ldrow8(Cs, row, cb + c8, v);
;     float s = rs ? scale * rs[row] : scale;
;     for (int j = 0; j < 8; ++j) v[j] *= s;
;     st8(dst + row * ld + c8, pack8f(v));
;   }
; }
.LBB0_680:
	v_ashrrev_i32_e32 v3, 31, v0
	v_lshrrev_b32_e32 v3, 28, v3
	v_add_u32_e32 v3, v0, v3
	v_add_u32_e32 v4, 0x100, v0
	v_ashrrev_i32_e32 v12, 4, v3
	v_and_b32_e32 v3, -16, v3
	v_cmp_lt_i32_e32 vcc, s87, v0
	v_mov_b32_e32 v0, v4
	v_lshlrev_b32_e32 v4, 7, v12
	v_add_u32_e32 v3, v2, v3
	v_sub_u32_e32 v14, v1, v4
	ds_read_b128 v[4:7], v3
	ds_read_b128 v[8:11], v3 offset:16
	v_ashrrev_i32_e32 v13, 31, v12
	v_lshlrev_b64 v[12:13], 8, v[12:13]
	v_lshl_add_u64 v[12:13], s[2:3], 0, v[12:13]
	v_ashrrev_i32_e32 v15, 31, v14
	s_waitcnt lgkmcnt(0)
	v_pk_mul_f32 v[4:5], v[4:5], s[6:7] op_sel_hi:[1,0]
	v_pk_mul_f32 v[6:7], v[6:7], s[6:7] op_sel_hi:[1,0]
	v_pk_mul_f32 v[8:9], v[8:9], s[6:7] op_sel_hi:[1,0]
	v_pk_mul_f32 v[10:11], v[10:11], s[6:7] op_sel_hi:[1,0]
	s_or_b64 s[4:5], vcc, s[4:5]
	v_add_u32_e32 v2, 0x2000, v2
	v_add_u32_e32 v1, 0x800, v1
	v_lshl_add_u64 v[12:13], v[14:15], 1, v[12:13]
	v_cvt_pk_bf16_f32 v4, v4, v5
	v_cvt_pk_bf16_f32 v5, v6, v7
	v_cvt_pk_bf16_f32 v6, v8, v9
	v_cvt_pk_bf16_f32 v7, v10, v11
	global_store_dwordx4 v[12:13], v[4:7], off
	s_andn2_b64 exec, exec, s[4:5]
	s_cbranch_execnz .LBB0_680

;   DI const float* c() const { return (const float*)sp[1]; }
; DI int TID() { int t = threadIdx.x; asm volatile("" : "+v"(t)); return t; }
; DI bf16x8 pack8f(const float* v) { u32x4 w = {cvtpk(v[0], v[1]), cvtpk(v[2], v[3]), cvtpk(v[4], v[5]), cvtpk(v[6], v[7])}; return __builtin_bit_cast(bf16x8, w); }
; DI void store_T(const float* Cs, int cb, int nc, bfu* dst, long ldT, float scale, const float* rs = nullptr) {
;   for (int u = TID(); u < nc * 16; u += NT) {
;     int c = u % nc, rc = (u / nc) * 8; float v[8];
;     for (int j = 0; j < 8; ++j) v[j] = Cs[(rc + j) * CLD + cb + c] * (rs ? scale * rs[rc + j] : scale);
;     st8(dst + c * ldT + rc, pack8f(v));
;   }
; }
.LBB0_686:
	v_ashrrev_i32_e32 v3, 31, v1
	v_lshrrev_b32_e32 v3, 25, v3
	v_add_u32_e32 v3, v1, v3
	v_add_u32_e32 v4, 0x100, v1
	v_ashrrev_i32_e32 v3, 7, v3
	v_cmp_lt_i32_e32 vcc, s87, v1
	v_mov_b32_e32 v1, v4
	v_mad_u64_u32 v[6:7], s[6:7], v3, s14, v[2:3]
	v_lshlrev_b32_e32 v4, 3, v3
	v_mad_u64_u32 v[8:9], s[6:7], v3, s15, v[0:1]
	v_add_u32_e32 v3, 0x400, v6
	v_add_u32_e32 v12, 0x800, v6
	v_add_u32_e32 v14, 0xc00, v6
	ds_read2_b32 v[10:11], v6 offset1:132
	ds_read2_b32 v[6:7], v3 offset0:8 offset1:140
	ds_read2_b32 v[12:13], v12 offset0:16 offset1:148
	ds_read2_b32 v[14:15], v14 offset0:24 offset1:156
	v_ashrrev_i32_e32 v9, 31, v8
	v_ashrrev_i32_e32 v5, 31, v4
	v_lshl_add_u64 v[8:9], s[2:3], 0, v[8:9]
	s_or_b64 s[4:5], vcc, s[4:5]
	v_add_u32_e32 v0, 0x120000, v0
	v_add_u32_e32 v2, 0x400, v2
	v_lshl_add_u64 v[8:9], v[4:5], 1, v[8:9]
	s_waitcnt lgkmcnt(0)
	v_cvt_pk_bf16_f32 v4, v10, v11
	v_cvt_pk_bf16_f32 v5, v6, v7
	v_cvt_pk_bf16_f32 v6, v12, v13
	v_cvt_pk_bf16_f32 v7, v14, v15
	global_store_dwordx4 v[8:9], v[4:7], off
	s_andn2_b64 exec, exec, s[4:5]
	s_cbranch_execnz .LBB0_686

; DI int TID() { int t = threadIdx.x; asm volatile("" : "+v"(t)); return t; }
; DI bf16x8 pack8f(const float* v) { u32x4 w = {cvtpk(v[0], v[1]), cvtpk(v[2], v[3]), cvtpk(v[4], v[5]), cvtpk(v[6], v[7])}; return __builtin_bit_cast(bf16x8, w); }
; DI void store_R(const float* Cs, int cb, int nc, bfu* dst, long ld, float scale, const float* rs = nullptr) {
;   const int cpr = nc >> 3;
;   for (int u = TID(); u < 128 * cpr; u += NT) {
;     int row = u / cpr, c8 = (u % cpr) * 8; float v[8]; ldrow8(Cs, row, cb + c8, v);
;     float s = rs ? scale * rs[row] : scale;
;     for (int j = 0; j < 8; ++j) v[j] *= s;
;     st8(dst + row * ld + c8, pack8f(v));
;   }
; }
; DI void epi_in0(const Params& p, float* Cs, int m0, int n0) {
;     ...
;     for (int m = 0; m < 2; ++m) store_R(Cs, m * 64, 64, dst + ((long)(bg * 32 + head * 2 + m) * T + t0) * 64, 64, isq ? 0.125f * LOG2E : 1.f);
.LBB0_700:
	v_ashrrev_i32_e32 v5, 31, v3
	v_lshrrev_b32_e32 v5, 29, v5
	v_add_u32_e32 v6, 0x100, v3
	v_add_u32_e32 v5, v3, v5
	v_cmp_lt_i32_e32 vcc, s18, v3
	v_mov_b32_e32 v3, v6
	v_ashrrev_i32_e32 v14, 3, v5
	v_mad_u64_u32 v[10:11], s[14:15], v14, s17, v[2:3]
	ds_read_b128 v[6:9], v10
	ds_read_b128 v[10:13], v10 offset:16
	v_lshlrev_b32_e32 v5, 6, v14
	v_ashrrev_i32_e32 v15, 31, v14
	v_sub_u32_e32 v16, v4, v5
	v_lshlrev_b64 v[14:15], 7, v[14:15]
	v_lshl_add_u64 v[14:15], s[2:3], 0, v[14:15]
	v_ashrrev_i32_e32 v17, 31, v16
	s_waitcnt lgkmcnt(0)
	v_pk_mul_f32 v[6:7], v[0:1], v[6:7]
	v_pk_mul_f32 v[8:9], v[0:1], v[8:9]
	v_pk_mul_f32 v[10:11], v[0:1], v[10:11]
	v_pk_mul_f32 v[12:13], v[0:1], v[12:13]
	s_or_b64 s[4:5], vcc, s[4:5]
	v_add_u32_e32 v2, 0x2000, v2
	v_add_u32_e32 v4, 0x800, v4
	v_lshl_add_u64 v[14:15], v[16:17], 1, v[14:15]
	v_cvt_pk_bf16_f32 v6, v6, v7
	v_cvt_pk_bf16_f32 v7, v8, v9
	v_cvt_pk_bf16_f32 v8, v10, v11
	v_cvt_pk_bf16_f32 v9, v12, v13
	global_store_dwordx4 v[14:15], v[6:9], off
	s_andn2_b64 exec, exec, s[4:5]
	s_cbranch_execnz .LBB0_700

; DI int TID() { int t = threadIdx.x; asm volatile("" : "+v"(t)); return t; }
; DI bf16x8 pack8f(const float* v) { u32x4 w = {cvtpk(v[0], v[1]), cvtpk(v[2], v[3]), cvtpk(v[4], v[5]), cvtpk(v[6], v[7])}; return __builtin_bit_cast(bf16x8, w); }
; DI void store_R(const float* Cs, int cb, int nc, bfu* dst, long ld, float scale, const float* rs = nullptr) {
;   const int cpr = nc >> 3;
;   for (int u = TID(); u < 128 * cpr; u += NT) {
;     int row = u / cpr, c8 = (u % cpr) * 8; float v[8]; ldrow8(Cs, row, cb + c8, v);
;     float s = rs ? scale * rs[row] : scale;
;     for (int j = 0; j < 8; ++j) v[j] *= s;
;     st8(dst + row * ld + c8, pack8f(v));
;   }
; }
; DI void epi_in0(const Params& p, float* Cs, int m0, int n0) {
;     ...
;     for (int m = 0; m < 2; ++m) store_R(Cs, m * 64, 64, dst + ((long)(bg * 32 + head * 2 + m) * T + t0) * 64, 64, isq ? 0.125f * LOG2E : 1.f);
.LBB0_703:
	v_ashrrev_i32_e32 v5, 31, v3
	v_lshrrev_b32_e32 v5, 29, v5
	v_add_u32_e32 v6, 0x100, v3
	v_add_u32_e32 v5, v3, v5
	v_cmp_lt_i32_e32 vcc, s15, v3
	v_mov_b32_e32 v3, v6
	v_ashrrev_i32_e32 v14, 3, v5
	v_mad_u64_u32 v[10:11], s[6:7], v14, s14, v[2:3]
	ds_read_b128 v[6:9], v10
	ds_read_b128 v[10:13], v10 offset:16
	v_lshlrev_b32_e32 v5, 6, v14
	v_ashrrev_i32_e32 v15, 31, v14
	v_sub_u32_e32 v16, v4, v5
	v_lshlrev_b64 v[14:15], 7, v[14:15]
	v_lshl_add_u64 v[14:15], s[2:3], 0, v[14:15]
	v_ashrrev_i32_e32 v17, 31, v16
	s_waitcnt lgkmcnt(0)
	v_pk_mul_f32 v[6:7], v[0:1], v[6:7]
	v_pk_mul_f32 v[8:9], v[0:1], v[8:9]
	v_pk_mul_f32 v[10:11], v[0:1], v[10:11]
	v_pk_mul_f32 v[12:13], v[0:1], v[12:13]
	s_or_b64 s[4:5], vcc, s[4:5]
	v_add_u32_e32 v2, 0x2000, v2
	v_add_u32_e32 v4, 0x800, v4
	v_lshl_add_u64 v[14:15], v[16:17], 1, v[14:15]
	v_cvt_pk_bf16_f32 v6, v6, v7
	v_cvt_pk_bf16_f32 v7, v8, v9
	v_cvt_pk_bf16_f32 v8, v10, v11
	v_cvt_pk_bf16_f32 v9, v12, v13
	global_store_dwordx4 v[14:15], v[6:9], off
	s_andn2_b64 exec, exec, s[4:5]
	s_cbranch_execnz .LBB0_703
	s_branch .LBB0_528

;   DI const float* x() const { return (const float*)sp[0]; }
;   DI const float* c() const { return (const float*)sp[1]; }
; __device__ __forceinline__ unsigned xb_ld(unsigned* p)              { return __hip_atomic_load(p, __ATOMIC_RELAXED, __HIP_MEMORY_SCOPE_AGENT); }
; __device__ __forceinline__ void xcd_barrier_complete(unsigned* bar, unsigned x, unsigned& nloc, unsigned& nx) {
;     const unsigned G = gridDim.x * gridDim.y * gridDim.z;
;     unsigned sum, cnt, mine, sp = 0u;
;     for (;;) {
;         sum = 0u; cnt = 0u; mine = 0u;
; #pragma unroll
;         for (unsigned j = 0; j < 16; ++j) { const unsigned c = xb_ld(&bar[XB_XCNT(j)]); sum += c; cnt += (c > 0u) ? 1u : 0u; mine = (j == x) ? c : mine; }
;         if (sum == G) break;
;         __builtin_amdgcn_s_sleep(1);
;         if ((++sp & 255u) == 0u) { if (xb_ld(&bar[XB_TMO])) break; if (sp > XB_SPIN_CAP) { atomicAdd(&bar[XB_TMO], 1u); break; } }
;     }
;     nloc = mine > 0u ? mine : 1u; nx = cnt > 0u ? cnt : 1u;
; }
.LBB0_709:
	s_waitcnt lgkmcnt(0)
	v_mov_b64_e32 v[0:1], s[6:7]
	v_mov_b64_e32 v[2:3], s[8:9]
	global_load_dword v0, v[0:1], off sc1
	v_readlane_b32 s2, v254, 15
	global_load_dword v1, v[2:3], off sc1
	v_mov_b64_e32 v[2:3], s[10:11]
	global_load_dword v2, v[2:3], off sc1
	s_or_b64 s[50:51], s[50:51], exec
	s_or_b64 s[48:49], s[48:49], exec
	s_waitcnt vmcnt(0) lgkmcnt(0)
	v_add_u32_e32 v4, v1, v0
	v_add_u32_e32 v6, v4, v2
	v_mov_b64_e32 v[4:5], s[12:13]
	global_load_dword v3, v[4:5], off sc1
	v_mov_b64_e32 v[4:5], s[14:15]
	global_load_dword v4, v[4:5], off sc1
	s_waitcnt vmcnt(0) lgkmcnt(0)
	v_add_u32_e32 v6, v6, v3
	v_add_u32_e32 v8, v6, v4
	v_mov_b64_e32 v[6:7], s[16:17]
	global_load_dword v5, v[6:7], off sc1
	v_mov_b64_e32 v[6:7], s[18:19]
	global_load_dword v6, v[6:7], off sc1
	s_waitcnt vmcnt(0) lgkmcnt(0)
	v_add_u32_e32 v8, v8, v5
	v_add_u32_e32 v10, v8, v6
	v_mov_b64_e32 v[8:9], s[20:21]
	global_load_dword v7, v[8:9], off sc1
	v_mov_b64_e32 v[8:9], s[22:23]
	global_load_dword v8, v[8:9], off sc1
	s_waitcnt vmcnt(0) lgkmcnt(0)
	v_add_u32_e32 v10, v10, v7
	v_add_u32_e32 v12, v10, v8
	v_mov_b64_e32 v[10:11], s[24:25]
	global_load_dword v9, v[10:11], off sc1
	v_mov_b64_e32 v[10:11], s[26:27]
	global_load_dword v10, v[10:11], off sc1
	s_waitcnt vmcnt(0) lgkmcnt(0)
	v_add_u32_e32 v12, v12, v9
	v_add_u32_e32 v14, v12, v10
	v_mov_b64_e32 v[12:13], s[28:29]
	global_load_dword v11, v[12:13], off sc1
	v_mov_b64_e32 v[12:13], s[30:31]
	global_load_dword v12, v[12:13], off sc1
	s_waitcnt vmcnt(0) lgkmcnt(0)
	v_add_u32_e32 v14, v14, v11
	v_add_u32_e32 v16, v14, v12
	v_mov_b64_e32 v[14:15], s[34:35]
	global_load_dword v13, v[14:15], off sc1
	v_mov_b64_e32 v[14:15], s[40:41]
	global_load_dword v14, v[14:15], off sc1
	s_waitcnt vmcnt(0) lgkmcnt(0)
	v_add_u32_e32 v16, v16, v13
	v_add_u32_e32 v18, v16, v14
	v_mov_b64_e32 v[16:17], s[42:43]
	global_load_dword v15, v[16:17], off sc1
	s_waitcnt vmcnt(0) lgkmcnt(0)
	v_add_u32_e32 v16, v18, v15
	v_cmp_ne_u32_e32 vcc, s2, v16
	s_and_saveexec_b64 s[2:3], vcc
	s_cbranch_execz .LBB0_708
	s_and_b32 s54, s75, 0xff
	s_mov_b64 s[52:53], -1
	s_cmp_eq_u32 s54, 0
	s_mov_b64 s[68:69], -1
	s_mov_b64 s[54:55], -1
	s_sleep 1
	s_cbranch_scc1 .LBB0_712
	s_and_saveexec_b64 s[62:63], s[68:69]
	s_cbranch_execz .LBB0_707
	s_branch .LBB0_715
.LBB0_712:
	v_mov_b64_e32 v[16:17], s[0:1]
	global_load_dword v16, v[16:17], off sc1
	s_mov_b64 s[68:69], 0
	s_waitcnt vmcnt(0) lgkmcnt(0)
	v_cmp_eq_u32_e32 vcc, 0, v16
	s_and_saveexec_b64 s[70:71], vcc
	s_cmp_lt_u32 s75, 0x40001
	s_cselect_b64 s[62:63], -1, 0
	s_xor_b64 s[54:55], exec, -1
	s_and_b64 s[68:69], s[62:63], exec
	s_or_b64 exec, exec, s[70:71]
	s_and_saveexec_b64 s[62:63], s[68:69]
	s_cbranch_execz .LBB0_707

; __device__ __forceinline__ unsigned xb_ld(unsigned* p)              { return __hip_atomic_load(p, __ATOMIC_RELAXED, __HIP_MEMORY_SCOPE_AGENT); }
; __device__ __forceinline__ void xcd_barrier_complete(unsigned* bar, unsigned x, unsigned& nloc, unsigned& nx) {
;     ...
;         if ((++sp & 255u) == 0u) { if (xb_ld(&bar[XB_TMO])) break; if (sp > XB_SPIN_CAP) { atomicAdd(&bar[XB_TMO], 1u); break; } }
.LBB0_716:
	s_or_b64 exec, exec, s[44:45]
	s_xor_b64 s[2:3], s[46:47], -1
	s_and_saveexec_b64 s[6:7], s[2:3]
	s_xor_b64 s[2:3], exec, s[6:7]
	s_cbranch_execz .LBB0_718
	v_mov_b64_e32 v[16:17], s[0:1]
	global_atomic_add v[16:17], v208, off

;   DI const float* x() const { return (const float*)sp[0]; }
; __device__ __forceinline__ unsigned xb_ld(unsigned* p)              { return __hip_atomic_load(p, __ATOMIC_RELAXED, __HIP_MEMORY_SCOPE_AGENT); }
; __device__ __forceinline__ unsigned xb_add(unsigned* p, unsigned v) { return __hip_atomic_fetch_add(p, v, __ATOMIC_RELAXED, __HIP_MEMORY_SCOPE_AGENT); }
; #define XB_SPIN(cond, bar) do { unsigned _sp = 0; while (cond) { __builtin_amdgcn_s_sleep(1); \
;     if ((++_sp & 255u) == 0u) { if (xb_ld(&(bar)[XB_TMO])) break; if (_sp > XB_SPIN_CAP) { atomicAdd(&(bar)[XB_TMO], 1u); break; } } } } while (0)
; __device__ __forceinline__ void xcd_barrier(const XcdBarrier& b) {
;     ...
;         const unsigned old = xb_add(&bar[XB_XSUB(b.x)], 1u);
;         const unsigned gen = old / nloc;
;         if (old + 1u == (gen + 1u) * nloc) {
;             __builtin_amdgcn_fence(__ATOMIC_RELEASE, "agent");
;             asm volatile("s_waitcnt vmcnt(0)" ::: "memory");
;             const unsigned og = xb_add(&bar[XB_TOP], 1u);
;             const unsigned tg = og / nx;
;             if (og + 1u == (tg + 1u) * nx) xb_add(&bar[XB_TOPGEN], 1u);
;             else XB_SPIN(xb_ld(&bar[XB_TOPGEN]) == tg, bar);
;             __builtin_amdgcn_fence(__ATOMIC_ACQUIRE, "agent");
;             xb_add(&bar[XB_XGEN(b.x)], 1u);
;             asm volatile("s_waitcnt vmcnt(0)" ::: "memory");
;         } else {
;             XB_SPIN(xb_ld(&bar[XB_XGEN(b.x)]) == gen, bar);
.LBB0_719:
	s_add_u32 s24, s38, 0xe36d000
	s_addc_u32 s25, s39, 0
	s_lshl_b32 s26, s74, 6
	s_add_i32 s76, s26, 0x500
	s_lshl_b64 s[0:1], s[76:77], 2
	s_add_u32 s0, s24, s0
	s_addc_u32 s1, s25, s1
	v_mov_b64_e32 v[4:5], s[0:1]
	global_atomic_add v3, v[4:5], v208, off sc0
	v_cvt_f32_u32_e32 v1, v2
	v_sub_u32_e32 v4, 0, v2
	v_rcp_iflag_f32_e32 v1, v1
	s_nop 0
	v_mul_f32_e32 v1, 0x4f7ffffe, v1
	v_cvt_u32_f32_e32 v1, v1
	v_mul_lo_u32 v4, v4, v1
	v_mul_hi_u32 v4, v1, v4
	v_add_u32_e32 v1, v1, v4
	s_waitcnt vmcnt(0) lgkmcnt(0)
	v_mul_hi_u32 v1, v3, v1
	v_mul_lo_u32 v4, v1, v2
	v_sub_u32_e32 v4, v3, v4
	v_cmp_ge_u32_e32 vcc, v4, v2
	v_add_u32_e32 v5, 1, v1
	s_nop 0
	v_cndmask_b32_e32 v1, v1, v5, vcc
	v_sub_u32_e32 v5, v4, v2
	v_cndmask_b32_e32 v4, v4, v5, vcc
	v_cmp_ge_u32_e32 vcc, v4, v2
	v_add_u32_e32 v4, 1, v1
	s_nop 0
	v_cndmask_b32_e32 v1, v1, v4, vcc
	v_add_u32_e32 v4, 1, v3
	v_mad_u64_u32 v[2:3], s[0:1], v2, v1, v[2:3]
	v_cmp_ne_u32_e32 vcc, v4, v2
	s_and_saveexec_b64 s[0:1], vcc
	s_xor_b64 s[0:1], exec, s[0:1]
	s_cbranch_execz .LBB0_732
	s_add_i32 s76, s26, 0x900
	s_lshl_b64 s[2:3], s[76:77], 2
	s_add_u32 s6, s24, s2
	s_addc_u32 s7, s25, s3
	v_mov_b64_e32 v[2:3], s[6:7]
	global_load_dword v0, v[2:3], off sc1
	s_waitcnt vmcnt(0) lgkmcnt(0)
	v_cmp_eq_u32_e32 vcc, v0, v1
	s_and_saveexec_b64 s[2:3], vcc
	s_cbranch_execz .LBB0_731
	s_add_u32 s8, s38, 0xe36d200
	s_addc_u32 s9, s39, 0
	s_mov_b32 s27, 1
	s_mov_b64 s[10:11], 0
	s_branch .LBB0_723

;   DI const float* x() const { return (const float*)sp[0]; }
; __device__ __forceinline__ unsigned xb_ld(unsigned* p)              { return __hip_atomic_load(p, __ATOMIC_RELAXED, __HIP_MEMORY_SCOPE_AGENT); }
; #define XB_SPIN(cond, bar) do { unsigned _sp = 0; while (cond) { __builtin_amdgcn_s_sleep(1); \
;     if ((++_sp & 255u) == 0u) { if (xb_ld(&(bar)[XB_TMO])) break; if (_sp > XB_SPIN_CAP) { atomicAdd(&(bar)[XB_TMO], 1u); break; } } } } while (0)
; __device__ __forceinline__ void xcd_barrier(const XcdBarrier& b) {
;     ...
;             XB_SPIN(xb_ld(&bar[XB_XGEN(b.x)]) == gen, bar);
.LBB0_723:
	s_and_b32 s18, s27, 0xff
	s_mov_b64 s[16:17], -1
	s_cmp_lg_u32 s18, 0
	s_mov_b64 s[18:19], -1
	s_sleep 1
	s_cbranch_scc1 .LBB0_727
	v_mov_b64_e32 v[2:3], s[8:9]
	global_load_dword v0, v[2:3], off sc1
	s_mov_b64 s[18:19], 0
	s_mov_b64 s[20:21], -1
	s_waitcnt vmcnt(0) lgkmcnt(0)
	v_cmp_eq_u32_e32 vcc, 0, v0
	s_and_saveexec_b64 s[22:23], vcc
	s_cmp_lt_u32 s27, 0x40001
	s_cselect_b64 s[18:19], -1, 0
	s_xor_b64 s[20:21], exec, -1
	s_and_b64 s[18:19], s[18:19], exec
	s_or_b64 exec, exec, s[22:23]
.LBB0_727:
	s_andn2_b64 s[14:15], s[14:15], exec
	s_and_b64 s[20:21], s[20:21], exec
	s_or_b64 s[14:15], s[14:15], s[20:21]
	s_and_saveexec_b64 s[20:21], s[18:19]
	s_cbranch_execz .LBB0_722
	v_mov_b64_e32 v[2:3], s[6:7]
	global_load_dword v0, v[2:3], off sc1
	s_add_i32 s27, s27, 1
	s_or_b64 s[14:15], s[14:15], exec
	s_waitcnt vmcnt(0) lgkmcnt(0)
	v_cmp_ne_u32_e32 vcc, v0, v1
	s_orn2_b64 s[16:17], vcc, exec
	s_branch .LBB0_722
.LBB0_729:
	s_or_b64 exec, exec, s[10:11]
	s_xor_b64 s[6:7], s[12:13], -1
	s_and_saveexec_b64 s[10:11], s[6:7]
	s_xor_b64 s[10:11], exec, s[10:11]
	s_cbranch_execz .LBB0_731
	v_mov_b64_e32 v[0:1], s[8:9]
	global_atomic_add v[0:1], v208, off

; __device__ __forceinline__ unsigned xb_ld(unsigned* p)              { return __hip_atomic_load(p, __ATOMIC_RELAXED, __HIP_MEMORY_SCOPE_AGENT); }
; __device__ __forceinline__ unsigned xb_add(unsigned* p, unsigned v) { return __hip_atomic_fetch_add(p, v, __ATOMIC_RELAXED, __HIP_MEMORY_SCOPE_AGENT); }
; #define XB_SPIN(cond, bar) do { unsigned _sp = 0; while (cond) { __builtin_amdgcn_s_sleep(1); \
;     if ((++_sp & 255u) == 0u) { if (xb_ld(&(bar)[XB_TMO])) break; if (_sp > XB_SPIN_CAP) { atomicAdd(&(bar)[XB_TMO], 1u); break; } } } } while (0)
; __device__ __forceinline__ void xcd_barrier(const XcdBarrier& b) {
;     ...
;         if (old + 1u == (gen + 1u) * nloc) {
;             __builtin_amdgcn_fence(__ATOMIC_RELEASE, "agent");
;             asm volatile("s_waitcnt vmcnt(0)" ::: "memory");
;             const unsigned og = xb_add(&bar[XB_TOP], 1u);
;             const unsigned tg = og / nx;
;             if (og + 1u == (tg + 1u) * nx) xb_add(&bar[XB_TOPGEN], 1u);
;             else XB_SPIN(xb_ld(&bar[XB_TOPGEN]) == tg, bar);
.LBB0_732:
	s_andn2_saveexec_b64 s[0:1], s[0:1]
	s_cbranch_execz .LBB0_748
	v_mov_b32_e32 v1, s38
	v_add_co_u32_e32 v2, vcc, 0xe370000, v1
	v_mov_b32_e32 v1, s39
	buffer_wbl2 sc1
	s_waitcnt vmcnt(0)
	v_addc_co_u32_e32 v3, vcc, 0, v1, vcc
	global_atomic_add v1, v[2:3], v208, off offset:1024 sc0
	v_cvt_f32_u32_e32 v2, v0
	v_sub_u32_e32 v3, 0, v0
	s_mov_b64 s[6:7], -1
	v_rcp_iflag_f32_e32 v2, v2
	s_nop 0
	v_mul_f32_e32 v2, 0x4f7ffffe, v2
	v_cvt_u32_f32_e32 v2, v2
	v_mul_lo_u32 v3, v3, v2
	v_mul_hi_u32 v3, v2, v3
	v_add_u32_e32 v2, v2, v3
	s_waitcnt vmcnt(0) lgkmcnt(0)
	v_mul_hi_u32 v2, v1, v2
	v_mul_lo_u32 v3, v2, v0
	v_sub_u32_e32 v3, v1, v3
	v_cmp_ge_u32_e32 vcc, v3, v0
	v_add_u32_e32 v4, 1, v2
	s_nop 0
	v_cndmask_b32_e32 v2, v2, v4, vcc
	v_sub_u32_e32 v4, v3, v0
	v_cndmask_b32_e32 v3, v3, v4, vcc
	v_cmp_ge_u32_e32 vcc, v3, v0
	v_add_u32_e32 v3, 1, v2
	s_nop 0
	v_cndmask_b32_e32 v2, v2, v3, vcc
	v_add_u32_e32 v3, 1, v1
	v_mad_u64_u32 v[0:1], s[0:1], v0, v2, v[0:1]
	s_add_u32 s0, s38, 0xe370500
	s_addc_u32 s1, s39, 0
	v_cmp_ne_u32_e32 vcc, v3, v0
	v_mov_b64_e32 v[0:1], s[0:1]
	s_and_saveexec_b64 s[2:3], vcc
	s_cbranch_execz .LBB0_745
	v_mov_b64_e32 v[0:1], s[0:1]
	global_load_dword v0, v[0:1], off sc1
	s_mov_b64 s[10:11], 0
	s_waitcnt vmcnt(0) lgkmcnt(0)
	v_cmp_eq_u32_e32 vcc, v0, v2
	s_and_saveexec_b64 s[8:9], vcc
	s_cbranch_execz .LBB0_744
	s_add_u32 s6, s38, 0xe36d200
	s_addc_u32 s7, s39, 0
	s_mov_b32 s22, 1
	s_branch .LBB0_737

; __device__ __forceinline__ unsigned xb_ld(unsigned* p)              { return __hip_atomic_load(p, __ATOMIC_RELAXED, __HIP_MEMORY_SCOPE_AGENT); }
; #define XB_SPIN(cond, bar) do { unsigned _sp = 0; while (cond) { __builtin_amdgcn_s_sleep(1); \
;     if ((++_sp & 255u) == 0u) { if (xb_ld(&(bar)[XB_TMO])) break; if (_sp > XB_SPIN_CAP) { atomicAdd(&(bar)[XB_TMO], 1u); break; } } } } while (0)
; __device__ __forceinline__ void xcd_barrier(const XcdBarrier& b) {
;     ...
;             else XB_SPIN(xb_ld(&bar[XB_TOPGEN]) == tg, bar);
.LBB0_739:
	v_mov_b64_e32 v[0:1], s[6:7]
	global_load_dword v0, v[0:1], off sc1
	s_mov_b64 s[18:19], 0
	s_mov_b64 s[16:17], -1
	s_waitcnt vmcnt(0) lgkmcnt(0)
	v_cmp_eq_u32_e32 vcc, 0, v0
	s_and_saveexec_b64 s[20:21], vcc
	s_cmp_lt_u32 s22, 0x40001
	s_cselect_b64 s[18:19], -1, 0
	s_xor_b64 s[16:17], exec, -1
	s_and_b64 s[18:19], s[18:19], exec
	s_or_b64 exec, exec, s[20:21]
	s_and_saveexec_b64 s[20:21], s[18:19]
	s_cbranch_execz .LBB0_736
.LBB0_742:
	v_mov_b64_e32 v[0:1], s[0:1]
	global_load_dword v0, v[0:1], off sc1
	s_add_i32 s22, s22, 1
	s_or_b64 s[16:17], s[16:17], exec
	s_waitcnt vmcnt(0) lgkmcnt(0)
	v_cmp_ne_u32_e32 vcc, v0, v2
	s_orn2_b64 s[14:15], vcc, exec
	s_branch .LBB0_736

; __device__ __forceinline__ unsigned xb_add(unsigned* p, unsigned v) { return __hip_atomic_fetch_add(p, v, __ATOMIC_RELAXED, __HIP_MEMORY_SCOPE_AGENT); }
; __device__ __forceinline__ void xcd_barrier(const XcdBarrier& b) {
;     ...
;             if (og + 1u == (tg + 1u) * nx) xb_add(&bar[XB_TOPGEN], 1u);
.LBB0_745:
	s_or_b64 exec, exec, s[2:3]
	s_and_saveexec_b64 s[0:1], s[6:7]
	s_cbranch_execz .LBB0_747
	global_atomic_add v[0:1], v208, off

; DI int TID() { int t = threadIdx.x; asm volatile("" : "+v"(t)); return t; }
; #define ATT_LOADK(key0)                                                                                  \
;   do {                                                                                                   \
;     _Pragma("unroll") for (int i = 0; i < KCH; ++i) { int c = tid + NT * i; kr[i] = ld8(Kp + (long)((key0) + c / CPR) * DK + (c % CPR) * 8); } \
;   } while (0)
; #define ATT_LOADV(key0)                                                                                  \
;   do {                                                                                                   \
;     _Pragma("unroll") for (int i = 0; i < VCH; ++i) { int c = tid + NT * i; vr[i] = ld8(Vtp + (long)(c / VPR) * T + (key0) + (c % VPR) * 8); }  \
;   } while (0)
; template <int DK, int KT>
; DI void attn_item(const bfu* __restrict__ Qp, const bfu* __restrict__ Kp, const bfu* __restrict__ Vtp, int nkeys, bfu* __restrict__ Op, int ldo, char* smem) {
;     ...
;   const int tid = TID(), lane = tid & 63, w = tid >> 6, l32 = lane & 31, hi = lane >> 5;
;   bf16x8 qf[NKS];
;   {
;     const bfu* qrow = Qp + (long)(w * 32 + l32) * DK + hi * 8;
; #pragma unroll
;     for (int ks = 0; ks < NKS; ++ks) qf[ks] = ld8(qrow + ks * 16);
;   }
;   f32x16 o[4];
; #pragma unroll
;   for (int d = 0; d < 4; ++d)
; #pragma unroll
;     for (int r = 0; r < 16; ++r) o[d][r] = 0.f;
;   float m = -1e30f, lsum = 0.f;
;   bf16x8 kr[KCH], vr[VCH];
;     ...
;   ATT_LOADK(0); ATT_LOADV(0);
; template <int layer, int part>
; DI void phase_mix(const Params& p, int cidx, char* smem, int* s_item) {
;     ...
;     if (layer == 0) {
;       int pl, t0, nkeys;
;       if (a < 128) { pl = a >> 4; t0 = CTX + (a & 15) * 128; nkeys = T; }
;       else { a -= 128; pl = a >> 1; t0 = (a & 1) * 128; nkeys = CTX; }
;       const int bh = (pl >> 1) * 8 + xcd, bg = bh >> 4, hv = (bh & 15) * 2 + (pl & 1);
;       attn_item<64, 64>((const bfu*)(G + L0_QD) + ((long)(bg * 32 + hv) * T + t0) * 64, (const bfu*)(G + L0_KD) + (long)(bg * 32 + hv) * T * 64,
;                     (const bfu*)(G + L0_VT) + (long)(bg * 16 + (hv >> 1)) * 128 * T, nkeys, (bfu*)(G + L0_OA) + ((long)bg * T + t0) * 4096 + hv * 128, 4096, smem);
.LBB0_760:
	s_lshl_b32 s2, s8, 2
	s_and_b32 s17, s2, 8
	s_or_b32 s20, s17, s33
	s_ashr_i32 s16, s8, 2
	s_lshl_b32 s2, s20, 1
	s_and_b32 s22, s8, 1
	s_or_b32 s5, s2, s22
	s_lshl_b32 s23, s16, 5
	s_or_b32 s21, s5, s23
	s_mul_i32 s2, s21, 0x900
	s_mul_hi_i32 s3, s21, 0x900
	s_add_u32 s2, s2, s4
	v_mov_b32_e32 v20, v202
	s_addc_u32 s3, s3, 0
	s_lshl_b64 s[2:3], s[2:3], 7
	v_ashrrev_i32_e32 v0, 1, v20
	v_bfi_b32 v120, s30, v0, v20
	s_add_u32 s18, s0, s2
	v_ashrrev_i32_e32 v121, 31, v120
	s_addc_u32 s19, s1, s3
	s_mul_hi_i32 s3, s21, 0x48000
	s_mul_i32 s21, s21, 0x48000
	v_bfe_u32 v21, v20, 5, 1
	v_lshlrev_b64 v[0:1], 7, v[120:121]
	v_add_u32_e32 v10, 0x300, v20
	s_add_u32 s2, s10, s21
	v_lshl_add_u64 v[0:1], s[18:19], 0, v[0:1]
	v_lshlrev_b32_e32 v122, 4, v21
	v_mov_b32_e32 v123, v129
	v_add_u32_e32 v8, 0x200, v20
	v_ashrrev_i32_e32 v11, 31, v10
	s_addc_u32 s3, s11, s3
	s_lshl_b32 s24, s16, 4
	v_lshl_add_u64 v[0:1], v[0:1], 0, v[122:123]
	v_add_u32_e32 v6, 0x100, v20
	v_ashrrev_i32_e32 v9, 31, v8
	v_lshrrev_b32_e32 v11, 29, v11
	s_or_b32 s20, s20, s24
	global_load_dwordx4 v[108:111], v[0:1], off
	global_load_dwordx4 v[104:107], v[0:1], off offset:32
	global_load_dwordx4 v[100:103], v[0:1], off offset:64
	global_load_dwordx4 v[96:99], v[0:1], off offset:96
	v_ashrrev_i32_e32 v0, 31, v20
	v_ashrrev_i32_e32 v4, 31, v6
	v_lshrrev_b32_e32 v9, 29, v9
	v_add_u32_e32 v11, v10, v11
	s_mul_hi_i32 s21, s20, 0x90000
	s_mul_i32 s20, s20, 0x90000
	v_lshrrev_b32_e32 v0, 29, v0
	v_lshrrev_b32_e32 v4, 29, v4
	v_add_u32_e32 v9, v8, v9
	v_ashrrev_i32_e32 v26, 3, v11
	v_and_b32_e32 v11, -8, v11
	s_add_u32 s20, s12, s20
	v_add_u32_e32 v2, v20, v0
	v_add_u32_e32 v7, v6, v4
	v_ashrrev_i32_e32 v24, 3, v9
	v_and_b32_e32 v9, -8, v9
	v_sub_u32_e32 v27, v10, v11
	s_addc_u32 s21, s13, s21
	v_ashrrev_i32_e32 v0, 3, v2
	v_and_b32_e32 v2, -8, v2
	v_ashrrev_i32_e32 v4, 3, v7
	v_and_b32_e32 v7, -8, v7
	v_sub_u32_e32 v25, v8, v9
	v_lshlrev_b32_e32 v10, 3, v27
	v_sub_u32_e32 v22, v20, v2
	v_sub_u32_e32 v23, v6, v7
	v_lshlrev_b32_e32 v8, 3, v25
	v_ashrrev_i32_e32 v11, 31, v10
	v_mov_b64_e32 v[12:13], s[20:21]
	s_movk_i32 s20, 0x1200
	v_lshlrev_b32_e32 v2, 3, v22
	v_lshlrev_b32_e32 v6, 3, v23
	v_ashrrev_i32_e32 v9, 31, v8
	v_mad_i64_i32 v[14:15], s[18:19], v26, s20, v[12:13]
	v_lshlrev_b64 v[10:11], 1, v[10:11]
	v_ashrrev_i32_e32 v3, 31, v2
	v_ashrrev_i32_e32 v7, 31, v6
	v_lshl_add_u64 v[14:15], v[14:15], 0, v[10:11]
	v_mad_i64_i32 v[16:17], s[18:19], v24, s20, v[12:13]
	v_lshlrev_b64 v[8:9], 1, v[8:9]
	v_lshl_add_u64 v[16:17], v[16:17], 0, v[8:9]
	global_load_dwordx4 v[64:67], v[14:15], off
	global_load_dwordx4 v[68:71], v[16:17], off
	v_mad_i64_i32 v[14:15], s[18:19], v4, s20, v[12:13]
	v_lshlrev_b64 v[6:7], 1, v[6:7]
	v_mad_i64_i32 v[12:13], s[18:19], v0, s20, v[12:13]
	v_lshlrev_b64 v[2:3], 1, v[2:3]
	v_ashrrev_i32_e32 v5, 31, v4
	v_lshl_add_u64 v[14:15], v[14:15], 0, v[6:7]
	v_lshl_add_u64 v[12:13], v[12:13], 0, v[2:3]
	v_ashrrev_i32_e32 v1, 31, v0
	global_load_dwordx4 v[72:75], v[14:15], off
	global_load_dwordx4 v[76:79], v[12:13], off
	v_lshlrev_b64 v[12:13], 7, v[4:5]
	v_lshl_add_u64 v[14:15], s[2:3], 0, v[12:13]
	v_lshlrev_b64 v[16:17], 7, v[0:1]
	v_lshl_add_u64 v[14:15], v[14:15], 0, v[6:7]
	v_lshl_add_u64 v[18:19], s[2:3], 0, v[16:17]
	v_lshl_add_u64 v[18:19], v[18:19], 0, v[2:3]
	global_load_dwordx4 v[112:115], v[14:15], off
	global_load_dwordx4 v[116:119], v[18:19], off
	s_or_b32 s3, s33, s24
	s_or_b32 s3, s3, s17
	s_add_i32 s2, s9, 1
	s_mul_hi_i32 s9, s3, 0x90000
	s_mul_i32 s3, s3, 0x90000
	s_add_u32 s18, s3, 0x2400080
	s_addc_u32 s19, s9, 0
	v_readlane_b32 s3, v254, 27
	s_lshl_b32 s8, s8, 3
	s_or_b32 s3, s3, s23
	s_and_b32 s8, s8, 16
	v_and_b32_e32 v1, 31, v20
	v_and_b32_e32 v5, 64, v203
	s_or_b32 s3, s3, s8
	s_waitcnt vmcnt(0)
	v_mul_u32_u24_e32 v145, 0x90, v1
	v_xor_b32_e32 v1, 32, v203
	v_add_u32_e32 v5, 64, v5
	s_add_i32 s3, s3, s22
	v_cmp_lt_i32_e32 vcc, v1, v5
	s_mul_hi_i32 s9, s3, 0x48000
	s_mul_i32 s3, s3, 0x48000
	v_cndmask_b32_e32 v1, v203, v1, vcc
	v_mov_b64_e32 v[14:15], s[18:19]
	s_add_u32 s8, s3, 0x1202000
	v_lshlrev_b32_e32 v128, 3, v21
	v_lshlrev_b32_e32 v123, 2, v1
	v_mul_lo_u32 v21, v0, s94
	v_mad_i64_i32 v[0:1], s[18:19], v0, s20, v[14:15]
	s_addc_u32 s9, s9, 0
	v_mad_i64_i32 v[18:19], s[18:19], v26, s20, v[14:15]
	v_lshl_add_u64 v[134:135], v[0:1], 0, v[2:3]
	v_lshl_add_u64 v[0:1], s[8:9], 0, v[12:13]
	v_sub_u32_e32 v20, v122, v128
	v_lshlrev_b32_e32 v22, 4, v22
	v_mul_lo_u32 v28, v4, s94
	v_lshlrev_b32_e32 v23, 4, v23
	v_mul_lo_u32 v29, v24, s94
	v_lshlrev_b32_e32 v25, 4, v25
	v_mul_lo_u32 v30, v26, s94
	v_lshlrev_b32_e32 v27, 4, v27
	v_lshl_add_u64 v[124:125], v[18:19], 0, v[10:11]
	v_mad_i64_i32 v[10:11], s[18:19], v24, s20, v[14:15]
	v_mad_i64_i32 v[4:5], s[18:19], v4, s20, v[14:15]
	v_lshl_add_u64 v[136:137], v[0:1], 0, v[6:7]
	v_lshl_add_u64 v[0:1], s[8:9], 0, v[16:17]
	v_mov_b32_e32 v14, v129
	v_mov_b32_e32 v15, v129
	v_lshl_add_u64 v[126:127], v[10:11], 0, v[8:9]
	v_lshl_add_u64 v[130:131], v[4:5], 0, v[6:7]
	v_lshl_add_u64 v[138:139], v[0:1], 0, v[2:3]
	v_mov_b32_e32 v0, v129
	v_mov_b32_e32 v1, v129
	v_mov_b32_e32 v2, v129
	v_mov_b32_e32 v3, v129
	v_mov_b32_e32 v4, v129
	v_mov_b32_e32 v5, v129
	v_mov_b32_e32 v6, v129
	v_mov_b32_e32 v7, v129
	v_mov_b32_e32 v8, v129
	v_mov_b32_e32 v9, v129
	v_mov_b32_e32 v10, v129
	v_mov_b32_e32 v11, v129
	v_mov_b32_e32 v12, v129
	v_mov_b32_e32 v13, v129
	v_add_u32_e32 v146, v21, v22
	v_add_u32_e32 v147, v28, v23
	v_add_u32_e32 v148, v29, v25
	v_add_u32_e32 v149, v30, v27
	v_add_u32_e32 v150, v20, v145
	v_mov_b64_e32 v[30:31], v[14:15]
	v_mov_b64_e32 v[46:47], v[14:15]
	v_mov_b64_e32 v[62:63], v[14:15]
	v_mov_b32_e32 v141, 0xf149f2ca
	v_mov_b32_e32 v142, 0
	v_mov_b64_e32 v[28:29], v[12:13]
	v_mov_b64_e32 v[26:27], v[10:11]
	v_mov_b64_e32 v[24:25], v[8:9]
	v_mov_b64_e32 v[22:23], v[6:7]
	v_mov_b64_e32 v[20:21], v[4:5]
	v_mov_b64_e32 v[18:19], v[2:3]
	v_mov_b64_e32 v[16:17], v[0:1]
	v_mov_b64_e32 v[44:45], v[12:13]
	v_mov_b64_e32 v[42:43], v[10:11]
	v_mov_b64_e32 v[40:41], v[8:9]
	v_mov_b64_e32 v[38:39], v[6:7]
	v_mov_b64_e32 v[36:37], v[4:5]
	v_mov_b64_e32 v[34:35], v[2:3]
	v_mov_b64_e32 v[32:33], v[0:1]
	v_mov_b64_e32 v[60:61], v[12:13]
	v_mov_b64_e32 v[58:59], v[10:11]
	v_mov_b64_e32 v[56:57], v[8:9]
	v_mov_b64_e32 v[54:55], v[6:7]
	v_mov_b64_e32 v[52:53], v[4:5]
	v_mov_b64_e32 v[50:51], v[2:3]
	v_mov_b64_e32 v[48:49], v[0:1]
; #define MFMA(a, b, c) __builtin_amdgcn_mfma_f32_32x32x16_bf16((a), (b), (c), 0, 0, 0)
;   DI const float* c() const { return (const float*)sp[1]; }
; #define ATT_LOADK(key0)                                                                                  \
;   do {                                                                                                   \
;     _Pragma("unroll") for (int i = 0; i < KCH; ++i) { int c = tid + NT * i; kr[i] = ld8(Kp + (long)((key0) + c / CPR) * DK + (c % CPR) * 8); } \
;   } while (0)
; template <int DK, int KT>
; DI void attn_item(const bfu* __restrict__ Qp, const bfu* __restrict__ Kp, const bfu* __restrict__ Vtp, int nkeys, bfu* __restrict__ Op, int ldo, char* smem) {
;     ...
;   for (int j = 0; j < NTL; ++j) {
;     __syncthreads();
; #pragma unroll
;     for (int i = 0; i < KCH; ++i) { int c = tid + NT * i; st8(Ks + (c / CPR) * LK + (c % CPR) * 8, kr[i]); }
; #pragma unroll
;     for (int i = 0; i < VCH; ++i) { int c = tid + NT * i; st8(Vs + (c / VPR) * LV + (c % VPR) * 8, vr[i]); }
;     __syncthreads();
;     if (j + 1 < NTL) ATT_LOADK((j + 1) * KT);
;     f32x16 sv[NBK];
; #pragma unroll
;     for (int bk = 0; bk < NBK; ++bk)
; #pragma unroll
;       for (int r = 0; r < 16; ++r) sv[bk][r] = 0.f;
;     const bfu* k0p = Ks + l32 * LK + hi * 8;
; #pragma unroll
;     for (int ks = 0; ks < NKS; ++ks)
; #pragma unroll
;       for (int bk = 0; bk < NBK; ++bk) sv[bk] = MFMA(ld8(k0p + bk * 32 * LK + ks * 16), qf[ks], sv[bk]);
;     float mx = sv[0][0];
; #pragma unroll
;     for (int bk = 0; bk < NBK; ++bk)
; #pragma unroll
;       for (int r = 0; r < 16; ++r) mx = fmaxf(mx, sv[bk][r]);
;     mx = fmaxf(mx, __shfl_xor(mx, 32));
;     float mn = m, alpha = 1.f;
;     const bool moved = __builtin_amdgcn_ballot_w64(mx > m + 8.f) != 0ull;
;     if (moved) { mn = fmaxf(m, mx); alpha = __builtin_amdgcn_exp2f(m - mn); m = mn; }
;     float rs = 0.f;
; #pragma unroll
;     for (int bk = 0; bk < NBK; ++bk)
; #pragma unroll
;       for (int r = 0; r < 16; ++r) { sv[bk][r] = __builtin_amdgcn_exp2f(sv[bk][r] - mn); rs += sv[bk][r]; }
;     lsum = lsum * alpha + rs;
;     if (moved) {
; #pragma unroll
;       for (int d = 0; d < 4; ++d)
; #pragma unroll
;         for (int r = 0; r < 16; ++r) o[d][r] *= alpha;
;     }
.LBB0_761:
	s_waitcnt lgkmcnt(0)
	s_barrier
	s_waitcnt vmcnt(0)
	ds_write_b128 v146, v[116:119]
	ds_write_b128 v147, v[112:115]
	ds_write_b128 v146, v[76:79] offset:9216
	ds_write_b128 v147, v[72:75] offset:9216
	ds_write_b128 v148, v[68:71] offset:9216
	ds_write_b128 v149, v[64:67] offset:9216
	v_lshl_add_u64 v[64:65], s[0:1], 0, v[138:139]
	s_waitcnt lgkmcnt(0)
	s_barrier
	global_load_dwordx4 v[116:119], v[64:65], off
	v_lshl_add_u64 v[64:65], s[0:1], 0, v[136:137]
	v_add_u32_e32 v151, v122, v145
	global_load_dwordx4 v[112:115], v[64:65], off
	ds_read_b128 v[64:67], v151
	ds_read_b128 v[152:155], v151 offset:32
	s_waitcnt lgkmcnt(0)
	v_mfma_f32_32x32x16_bf16 v[80:95], v[64:67], v[108:111], 0
	ds_read_b128 v[64:67], v151 offset:4608
	v_mfma_f32_32x32x16_bf16 v[80:95], v[152:155], v[104:107], v[80:95]
	ds_read_b128 v[152:155], v151 offset:4640
	s_waitcnt lgkmcnt(0)
	v_mfma_f32_32x32x16_bf16 v[64:79], v[64:67], v[108:111], 0
	v_mfma_f32_32x32x16_bf16 v[64:79], v[152:155], v[104:107], v[64:79]
	ds_read_b128 v[152:155], v151 offset:64
	s_waitcnt lgkmcnt(0)
	v_mfma_f32_32x32x16_bf16 v[80:95], v[152:155], v[100:103], v[80:95]
	ds_read_b128 v[152:155], v151 offset:4672
	s_waitcnt lgkmcnt(0)
	v_mfma_f32_32x32x16_bf16 v[64:79], v[152:155], v[100:103], v[64:79]
	ds_read_b128 v[152:155], v151 offset:96
	s_waitcnt lgkmcnt(0)
	v_mfma_f32_32x32x16_bf16 v[80:95], v[152:155], v[96:99], v[80:95]
	ds_read_b128 v[152:155], v151 offset:4704
	s_waitcnt lgkmcnt(0)
	v_mfma_f32_32x32x16_bf16 v[64:79], v[152:155], v[96:99], v[64:79]
	s_nop 8
	v_max_f32_e32 v133, v81, v81
	v_max_f32_e32 v140, v80, v80
	v_max_f32_e32 v133, v140, v133
	v_max3_f32 v133, v133, v82, v83
	v_max3_f32 v133, v133, v84, v85
	v_max3_f32 v133, v133, v86, v87
	v_max3_f32 v133, v133, v88, v89
	v_max3_f32 v133, v133, v90, v91
	v_max3_f32 v133, v133, v92, v93
	v_max3_f32 v133, v133, v94, v95
	v_max3_f32 v133, v133, v64, v65
	v_max3_f32 v133, v133, v66, v67
	v_max3_f32 v133, v133, v68, v69
	v_max3_f32 v133, v133, v70, v71
	v_max3_f32 v133, v133, v72, v73
	v_max3_f32 v133, v133, v74, v75
	v_max3_f32 v133, v133, v76, v77
	v_max3_f32 v133, v133, v78, v79
	ds_bpermute_b32 v140, v123, v133
	s_waitcnt lgkmcnt(0)
	v_max_f32_e32 v140, v140, v140
	v_max_f32_e32 v133, v133, v140
	v_add_f32_e32 v140, 0x41000000, v141
	v_cmp_gt_f32_e32 vcc, v133, v140
	v_max_f32_e32 v140, v141, v141
	v_max_f32_e32 v133, v140, v133
	v_sub_f32_e32 v140, v141, v133
	v_exp_f32_e32 v140, v140
	s_cmp_eq_u64 vcc, 0
	s_cselect_b64 s[8:9], -1, 0
	s_and_b64 vcc, exec, s[8:9]
	s_cbranch_vccnz .LBB0_763
	v_pk_mul_f32 v[62:63], v[62:63], v[140:141] op_sel_hi:[1,0]
	v_pk_mul_f32 v[60:61], v[60:61], v[140:141] op_sel_hi:[1,0]
	v_pk_mul_f32 v[58:59], v[58:59], v[140:141] op_sel_hi:[1,0]
	v_pk_mul_f32 v[56:57], v[56:57], v[140:141] op_sel_hi:[1,0]
	v_pk_mul_f32 v[54:55], v[54:55], v[140:141] op_sel_hi:[1,0]
	v_pk_mul_f32 v[52:53], v[52:53], v[140:141] op_sel_hi:[1,0]
	v_pk_mul_f32 v[50:51], v[50:51], v[140:141] op_sel_hi:[1,0]
	v_pk_mul_f32 v[48:49], v[48:49], v[140:141] op_sel_hi:[1,0]
	v_pk_mul_f32 v[46:47], v[46:47], v[140:141] op_sel_hi:[1,0]
	v_pk_mul_f32 v[44:45], v[44:45], v[140:141] op_sel_hi:[1,0]
	v_pk_mul_f32 v[42:43], v[42:43], v[140:141] op_sel_hi:[1,0]
	v_pk_mul_f32 v[40:41], v[40:41], v[140:141] op_sel_hi:[1,0]
	v_pk_mul_f32 v[38:39], v[38:39], v[140:141] op_sel_hi:[1,0]
	v_pk_mul_f32 v[36:37], v[36:37], v[140:141] op_sel_hi:[1,0]
	v_pk_mul_f32 v[34:35], v[34:35], v[140:141] op_sel_hi:[1,0]
	v_pk_mul_f32 v[32:33], v[32:33], v[140:141] op_sel_hi:[1,0]
	v_pk_mul_f32 v[30:31], v[30:31], v[140:141] op_sel_hi:[1,0]
	v_pk_mul_f32 v[28:29], v[28:29], v[140:141] op_sel_hi:[1,0]
	v_pk_mul_f32 v[26:27], v[26:27], v[140:141] op_sel_hi:[1,0]
	v_pk_mul_f32 v[24:25], v[24:25], v[140:141] op_sel_hi:[1,0]
	v_pk_mul_f32 v[22:23], v[22:23], v[140:141] op_sel_hi:[1,0]
	v_pk_mul_f32 v[20:21], v[20:21], v[140:141] op_sel_hi:[1,0]
	v_pk_mul_f32 v[18:19], v[18:19], v[140:141] op_sel_hi:[1,0]
	v_pk_mul_f32 v[16:17], v[16:17], v[140:141] op_sel_hi:[1,0]
	v_pk_mul_f32 v[14:15], v[14:15], v[140:141] op_sel_hi:[1,0]
	v_pk_mul_f32 v[12:13], v[12:13], v[140:141] op_sel_hi:[1,0]
	v_pk_mul_f32 v[10:11], v[10:11], v[140:141] op_sel_hi:[1,0]
	v_pk_mul_f32 v[8:9], v[8:9], v[140:141] op_sel_hi:[1,0]
	v_pk_mul_f32 v[6:7], v[6:7], v[140:141] op_sel_hi:[1,0]
	v_pk_mul_f32 v[4:5], v[4:5], v[140:141] op_sel_hi:[1,0]
	v_pk_mul_f32 v[2:3], v[2:3], v[140:141] op_sel_hi:[1,0]
	v_pk_mul_f32 v[0:1], v[0:1], v[140:141] op_sel_hi:[1,0]
; #define MFMA(a, b, c) __builtin_amdgcn_mfma_f32_32x32x16_bf16((a), (b), (c), 0, 0, 0)
; #define ATT_LOADV(key0)                                                                                  \
;   do {                                                                                                   \
;     _Pragma("unroll") for (int i = 0; i < VCH; ++i) { int c = tid + NT * i; vr[i] = ld8(Vtp + (long)(c / VPR) * T + (key0) + (c % VPR) * 8); }  \
;   } while (0)
; template <int DK, int KT>
; DI void attn_item(const bfu* __restrict__ Qp, const bfu* __restrict__ Kp, const bfu* __restrict__ Vtp, int nkeys, bfu* __restrict__ Op, int ldo, char* smem) {
;     ...
;     const bool moved = __builtin_amdgcn_ballot_w64(mx > m + 8.f) != 0ull;
;     if (moved) { mn = fmaxf(m, mx); alpha = __builtin_amdgcn_exp2f(m - mn); m = mn; }
;     float rs = 0.f;
; #pragma unroll
;     for (int bk = 0; bk < NBK; ++bk)
; #pragma unroll
;       for (int r = 0; r < 16; ++r) { sv[bk][r] = __builtin_amdgcn_exp2f(sv[bk][r] - mn); rs += sv[bk][r]; }
;     lsum = lsum * alpha + rs;
;     if (moved) {
; #pragma unroll
;       for (int d = 0; d < 4; ++d)
; #pragma unroll
;         for (int r = 0; r < 16; ++r) o[d][r] *= alpha;
;     }
;     bf16x8 pf[2 * NBK];
; #pragma unroll
;     for (int bk = 0; bk < NBK; ++bk) { pf[2 * bk] = packacc(sv[bk], 0); pf[2 * bk + 1] = packacc(sv[bk], 1); }
;     if (j + 1 < NTL) ATT_LOADV((j + 1) * KT);
; #pragma unroll
;     for (int kk = 0; kk < 2 * NBK; ++kk)
; #pragma unroll
;       for (int d = 0; d < 4; ++d) o[d] = MFMA(ld44(Vs + (d * 32 + l32) * LV + kk * 16 + 4 * hi), pf[kk], o[d]);
.LBB0_763:
	v_cndmask_b32_e64 v141, v133, v141, s[8:9]
	v_sub_f32_e32 v80, v80, v141
	v_exp_f32_e32 v80, v80
	v_sub_f32_e32 v81, v81, v141
	v_exp_f32_e32 v81, v81
	v_sub_f32_e32 v82, v82, v141
	v_exp_f32_e32 v82, v82
	v_sub_f32_e32 v83, v83, v141
	v_exp_f32_e32 v83, v83
	v_sub_f32_e32 v84, v84, v141
	v_add_f32_e32 v133, 0, v80
	v_exp_f32_e32 v84, v84
	v_sub_f32_e32 v85, v85, v141
	v_add_f32_e32 v133, v81, v133
	v_exp_f32_e32 v85, v85
	v_sub_f32_e32 v86, v86, v141
	v_add_f32_e32 v133, v82, v133
	v_exp_f32_e32 v86, v86
	v_sub_f32_e32 v87, v87, v141
	v_add_f32_e32 v133, v83, v133
	v_exp_f32_e32 v87, v87
	v_sub_f32_e32 v88, v88, v141
	v_add_f32_e32 v133, v84, v133
	v_exp_f32_e32 v88, v88
	v_sub_f32_e32 v89, v89, v141
	v_add_f32_e32 v133, v85, v133
	v_exp_f32_e32 v89, v89
	v_sub_f32_e32 v90, v90, v141
	v_add_f32_e32 v133, v86, v133
	v_exp_f32_e32 v90, v90
	v_sub_f32_e32 v91, v91, v141
	v_add_f32_e32 v133, v87, v133
	v_exp_f32_e32 v91, v91
	v_sub_f32_e32 v92, v92, v141
	v_add_f32_e32 v133, v88, v133
	v_exp_f32_e32 v143, v92
	v_sub_f32_e32 v93, v93, v141
	v_add_f32_e32 v133, v89, v133
	v_exp_f32_e32 v144, v93
	v_sub_f32_e32 v93, v94, v141
	v_add_f32_e32 v133, v90, v133
	v_exp_f32_e32 v152, v93
	v_sub_f32_e32 v93, v95, v141
	v_add_f32_e32 v133, v91, v133
	v_exp_f32_e32 v153, v93
	v_sub_f32_e32 v64, v64, v141
	v_add_f32_e32 v92, v143, v133
	v_exp_f32_e32 v64, v64
	v_sub_f32_e32 v65, v65, v141
	v_add_f32_e32 v92, v144, v92
	v_exp_f32_e32 v65, v65
	v_sub_f32_e32 v66, v66, v141
	v_add_f32_e32 v92, v152, v92
	v_exp_f32_e32 v66, v66
	v_sub_f32_e32 v67, v67, v141
	v_add_f32_e32 v92, v153, v92
	v_exp_f32_e32 v67, v67
	v_sub_f32_e32 v68, v68, v141
	v_add_f32_e32 v92, v64, v92
	v_exp_f32_e32 v68, v68
	v_sub_f32_e32 v69, v69, v141
	v_add_f32_e32 v92, v65, v92
	v_exp_f32_e32 v69, v69
	v_sub_f32_e32 v70, v70, v141
	v_add_f32_e32 v92, v66, v92
	v_exp_f32_e32 v70, v70
	v_sub_f32_e32 v71, v71, v141
	v_add_f32_e32 v92, v67, v92
	v_exp_f32_e32 v71, v71
	v_sub_f32_e32 v72, v72, v141
	v_add_f32_e32 v92, v68, v92
	v_exp_f32_e32 v72, v72
	v_sub_f32_e32 v73, v73, v141
	v_add_f32_e32 v92, v69, v92
	v_exp_f32_e32 v73, v73
	v_sub_f32_e32 v74, v74, v141
	v_add_f32_e32 v92, v70, v92
	v_exp_f32_e32 v74, v74
	v_sub_f32_e32 v75, v75, v141
	v_add_f32_e32 v92, v71, v92
	v_exp_f32_e32 v75, v75
	v_sub_f32_e32 v76, v76, v141
	v_add_f32_e32 v92, v72, v92
	v_exp_f32_e32 v76, v76
	v_sub_f32_e32 v77, v77, v141
	v_add_f32_e32 v92, v73, v92
	v_exp_f32_e32 v77, v77
	v_sub_f32_e32 v78, v78, v141
	v_add_f32_e32 v92, v74, v92
	v_exp_f32_e32 v78, v78
	v_sub_f32_e32 v79, v79, v141
	v_add_f32_e32 v92, v75, v92
	v_exp_f32_e32 v79, v79
	v_add_f32_e32 v92, v76, v92
	v_add_f32_e32 v92, v77, v92
	v_add_f32_e32 v92, v78, v92
	v_cvt_pk_bf16_f32 v94, v84, v85
	v_cvt_pk_bf16_f32 v84, v64, v65
	v_lshl_add_u64 v[64:65], s[0:1], 0, v[134:135]
	v_add_f32_e32 v133, v79, v92
	v_cndmask_b32_e64 v92, v140, 1.0, s[8:9]
	v_cvt_pk_bf16_f32 v93, v82, v83
	v_cvt_pk_bf16_f32 v82, v76, v77
	v_cvt_pk_bf16_f32 v83, v78, v79
	global_load_dwordx4 v[76:79], v[64:65], off
	v_lshl_add_u64 v[64:65], s[0:1], 0, v[130:131]
	v_fmac_f32_e32 v133, v142, v92
	v_cvt_pk_bf16_f32 v92, v80, v81
	v_cvt_pk_bf16_f32 v80, v72, v73
	v_cvt_pk_bf16_f32 v81, v74, v75
	global_load_dwordx4 v[72:75], v[64:65], off
	v_lshl_add_u64 v[64:65], s[0:1], 0, v[126:127]
	v_cvt_pk_bf16_f32 v95, v86, v87
	v_cvt_pk_bf16_f32 v86, v68, v69
	v_cvt_pk_bf16_f32 v87, v70, v71
	global_load_dwordx4 v[68:71], v[64:65], off
	v_lshl_add_u64 v[64:65], s[0:1], 0, v[124:125]
	v_add_u32_e32 v140, 0x2000, v150
	v_cvt_pk_bf16_f32 v88, v88, v89
	v_cvt_pk_bf16_f32 v89, v90, v91
	v_cvt_pk_bf16_f32 v91, v152, v153
	v_cvt_pk_bf16_f32 v85, v66, v67
	global_load_dwordx4 v[64:67], v[64:65], off
	ds_read2_b64 v[152:155], v140 offset0:128 offset1:130
	ds_read2_b64 v[156:159], v140 offset0:132 offset1:134
	v_add_u32_e32 v142, 0x3000, v150
	s_waitcnt lgkmcnt(0)
	v_mfma_f32_32x32x16_bf16 v[48:63], v[152:155], v[92:95], v[48:63]
	ds_read2_b64 v[152:155], v142 offset0:192 offset1:194
	v_cvt_pk_bf16_f32 v90, v143, v144
	v_add_u32_e32 v143, 0x4800, v150
	v_add_u32_e32 v144, 0x5800, v150
	s_add_i32 s2, s2, -1
	v_lshl_add_u64 v[124:125], v[124:125], 0, s[92:93]
	v_lshl_add_u64 v[126:127], v[126:127], 0, s[92:93]
	s_waitcnt lgkmcnt(0)
	v_mfma_f32_32x32x16_bf16 v[32:47], v[152:155], v[92:95], v[32:47]
	ds_read2_b64 v[152:155], v143 offset1:2
	v_lshl_add_u64 v[130:131], v[130:131], 0, s[92:93]
	v_lshl_add_u64 v[134:135], v[134:135], 0, s[92:93]
	v_lshl_add_u64 v[136:137], v[136:137], 0, s[90:91]
	v_lshl_add_u64 v[138:139], v[138:139], 0, s[90:91]
	s_cmp_eq_u32 s2, 0
	s_waitcnt lgkmcnt(0)
	v_mfma_f32_32x32x16_bf16 v[16:31], v[152:155], v[92:95], v[16:31]
	ds_read2_b64 v[152:155], v144 offset0:64 offset1:66
	s_waitcnt lgkmcnt(0)
	v_mfma_f32_32x32x16_bf16 v[0:15], v[152:155], v[92:95], v[0:15]
	ds_read2_b64 v[92:95], v142 offset0:196 offset1:198
	s_waitcnt lgkmcnt(0)
	v_mfma_f32_32x32x16_bf16 v[32:47], v[92:95], v[88:91], v[32:47]
	ds_read2_b64 v[92:95], v143 offset0:4 offset1:6
	s_waitcnt lgkmcnt(0)
	v_mfma_f32_32x32x16_bf16 v[16:31], v[92:95], v[88:91], v[16:31]
	ds_read2_b64 v[92:95], v144 offset0:68 offset1:70
	v_mfma_f32_32x32x16_bf16 v[48:63], v[156:159], v[88:91], v[48:63]
	s_waitcnt lgkmcnt(0)
	v_mfma_f32_32x32x16_bf16 v[0:15], v[92:95], v[88:91], v[0:15]
	ds_read2_b64 v[88:91], v140 offset0:136 offset1:138
	s_waitcnt lgkmcnt(0)
	v_mfma_f32_32x32x16_bf16 v[48:63], v[88:91], v[84:87], v[48:63]
	ds_read2_b64 v[88:91], v142 offset0:200 offset1:202
	s_waitcnt lgkmcnt(0)
	v_mfma_f32_32x32x16_bf16 v[32:47], v[88:91], v[84:87], v[32:47]
	ds_read2_b64 v[88:91], v143 offset0:8 offset1:10
	s_waitcnt lgkmcnt(0)
	v_mfma_f32_32x32x16_bf16 v[16:31], v[88:91], v[84:87], v[16:31]
	ds_read2_b64 v[88:91], v144 offset0:72 offset1:74
	s_waitcnt lgkmcnt(0)
	v_mfma_f32_32x32x16_bf16 v[0:15], v[88:91], v[84:87], v[0:15]
	ds_read2_b64 v[84:87], v140 offset0:140 offset1:142
	s_waitcnt lgkmcnt(0)
	v_mfma_f32_32x32x16_bf16 v[48:63], v[84:87], v[80:83], v[48:63]
	ds_read2_b64 v[84:87], v142 offset0:204 offset1:206
	s_waitcnt lgkmcnt(0)
	v_mfma_f32_32x32x16_bf16 v[32:47], v[84:87], v[80:83], v[32:47]
	ds_read2_b64 v[84:87], v143 offset0:12 offset1:14
	s_waitcnt lgkmcnt(0)
	v_mfma_f32_32x32x16_bf16 v[16:31], v[84:87], v[80:83], v[16:31]
	ds_read2_b64 v[84:87], v144 offset0:76 offset1:78
	s_waitcnt lgkmcnt(0)
	v_mfma_f32_32x32x16_bf16 v[0:15], v[84:87], v[80:83], v[0:15]
	s_cbranch_scc1 .LBB0_765
	v_mov_b32_e32 v142, v133
	s_branch .LBB0_761

; #define MFMA(a, b, c) __builtin_amdgcn_mfma_f32_32x32x16_bf16((a), (b), (c), 0, 0, 0)
; #define ATT_LOADV(key0)                                                                                  \
;   do {                                                                                                   \
;     _Pragma("unroll") for (int i = 0; i < VCH; ++i) { int c = tid + NT * i; vr[i] = ld8(Vtp + (long)(c / VPR) * T + (key0) + (c % VPR) * 8); }  \
;   } while (0)
; template <int DK, int KT>
; DI void attn_item(const bfu* __restrict__ Qp, const bfu* __restrict__ Kp, const bfu* __restrict__ Vtp, int nkeys, bfu* __restrict__ Op, int ldo, char* smem) {
;     ...
;     float rs = 0.f;
; #pragma unroll
;     for (int bk = 0; bk < NBK; ++bk)
; #pragma unroll
;       for (int r = 0; r < 16; ++r) { sv[bk][r] = __builtin_amdgcn_exp2f(sv[bk][r] - mn); rs += sv[bk][r]; }
;     lsum = lsum * alpha + rs;
;     if (moved) {
; #pragma unroll
;       for (int d = 0; d < 4; ++d)
; #pragma unroll
;         for (int r = 0; r < 16; ++r) o[d][r] *= alpha;
;     }
;     bf16x8 pf[2 * NBK];
; #pragma unroll
;     for (int bk = 0; bk < NBK; ++bk) { pf[2 * bk] = packacc(sv[bk], 0); pf[2 * bk + 1] = packacc(sv[bk], 1); }
;     if (j + 1 < NTL) ATT_LOADV((j + 1) * KT);
; #pragma unroll
;     for (int kk = 0; kk < 2 * NBK; ++kk)
; #pragma unroll
;       for (int d = 0; d < 4; ++d) o[d] = MFMA(ld44(Vs + (d * 32 + l32) * LV + kk * 16 + 4 * hi), pf[kk], o[d]);
;   }
;     ...
;   const float inv = 1.f / (lsum + __shfl_xor(lsum, 32));
.LBB0_768:
	v_sub_f32_e32 v71, v71, v141
	v_sub_f32_e32 v70, v70, v141
	v_sub_f32_e32 v69, v69, v141
	v_sub_f32_e32 v68, v68, v141
	v_sub_f32_e32 v67, v67, v141
	v_sub_f32_e32 v66, v66, v141
	v_sub_f32_e32 v65, v65, v141
	v_sub_f32_e32 v64, v64, v141
	v_exp_f32_e32 v101, v71
	v_exp_f32_e32 v102, v70
	v_exp_f32_e32 v103, v69
	v_exp_f32_e32 v104, v68
	v_exp_f32_e32 v105, v67
	v_exp_f32_e32 v106, v66
	v_exp_f32_e32 v107, v65
	v_exp_f32_e32 v108, v64
	ds_read2_b64 v[114:117], v140 offset0:128 offset1:130
	ds_read2_b64 v[124:127], v140 offset0:132 offset1:134
	v_cvt_pk_bf16_f32 v111, v106, v105
	v_cvt_pk_bf16_f32 v112, v104, v103
	v_cvt_pk_bf16_f32 v110, v108, v107
	v_cvt_pk_bf16_f32 v113, v102, v101
	v_sub_f32_e32 v79, v79, v141
	v_sub_f32_e32 v78, v78, v141
	s_waitcnt lgkmcnt(1)
	v_mfma_f32_32x32x16_bf16 v[48:63], v[114:117], v[110:113], v[48:63]
	ds_read2_b64 v[114:117], v142 offset0:192 offset1:194
	v_sub_f32_e32 v77, v77, v141
	v_sub_f32_e32 v76, v76, v141
	v_sub_f32_e32 v75, v75, v141
	v_sub_f32_e32 v74, v74, v141
	v_sub_f32_e32 v73, v73, v141
	v_sub_f32_e32 v72, v72, v141
	s_waitcnt lgkmcnt(0)
	v_mfma_f32_32x32x16_bf16 v[32:47], v[114:117], v[110:113], v[32:47]
	ds_read2_b64 v[114:117], v143 offset1:2
	v_exp_f32_e32 v79, v79
	v_exp_f32_e32 v78, v78
	v_exp_f32_e32 v77, v77
	v_exp_f32_e32 v76, v76
	v_exp_f32_e32 v97, v75
	v_exp_f32_e32 v98, v74
	s_waitcnt lgkmcnt(0)
	v_mfma_f32_32x32x16_bf16 v[16:31], v[114:117], v[110:113], v[16:31]
	ds_read2_b64 v[114:117], v144 offset0:64 offset1:66
	v_exp_f32_e32 v99, v73
	v_exp_f32_e32 v100, v72
	v_cvt_pk_bf16_f32 v73, v98, v97
	v_cvt_pk_bf16_f32 v74, v76, v77
	v_cvt_pk_bf16_f32 v75, v78, v79
	v_cvt_pk_bf16_f32 v72, v100, v99
	s_waitcnt lgkmcnt(0)
	v_mfma_f32_32x32x16_bf16 v[0:15], v[114:117], v[110:113], v[0:15]
	ds_read2_b64 v[110:113], v142 offset0:196 offset1:198
	v_sub_f32_e32 v87, v87, v141
	v_sub_f32_e32 v86, v86, v141
	v_sub_f32_e32 v85, v85, v141
	v_sub_f32_e32 v84, v84, v141
	v_sub_f32_e32 v83, v83, v141
	v_sub_f32_e32 v82, v82, v141
	s_waitcnt lgkmcnt(0)
	v_mfma_f32_32x32x16_bf16 v[32:47], v[110:113], v[72:75], v[32:47]
	ds_read2_b64 v[110:113], v143 offset0:4 offset1:6
	v_sub_f32_e32 v81, v81, v141
	v_sub_f32_e32 v80, v80, v141
	v_exp_f32_e32 v87, v87
	v_exp_f32_e32 v86, v86
	v_exp_f32_e32 v85, v85
	v_exp_f32_e32 v84, v84
	s_waitcnt lgkmcnt(0)
	v_mfma_f32_32x32x16_bf16 v[16:31], v[110:113], v[72:75], v[16:31]
	ds_read2_b64 v[110:113], v144 offset0:68 offset1:70
	v_exp_f32_e32 v83, v83
	v_exp_f32_e32 v82, v82
	v_exp_f32_e32 v81, v81
	v_exp_f32_e32 v80, v80
	v_cvt_pk_bf16_f32 v70, v84, v85
	v_cvt_pk_bf16_f32 v69, v82, v83
	v_mfma_f32_32x32x16_bf16 v[48:63], v[124:127], v[72:75], v[48:63]
	v_cvt_pk_bf16_f32 v68, v80, v81
	v_cvt_pk_bf16_f32 v71, v86, v87
	v_sub_f32_e32 v95, v95, v141
	v_sub_f32_e32 v94, v94, v141
	v_sub_f32_e32 v93, v93, v141
	v_sub_f32_e32 v92, v92, v141
	v_sub_f32_e32 v91, v91, v141
	s_waitcnt lgkmcnt(0)
	v_mfma_f32_32x32x16_bf16 v[0:15], v[110:113], v[72:75], v[0:15]
	ds_read2_b64 v[72:75], v140 offset0:136 offset1:138
	v_sub_f32_e32 v90, v90, v141
	v_sub_f32_e32 v89, v89, v141
	v_sub_f32_e32 v88, v88, v141
	v_exp_f32_e32 v95, v95
	v_exp_f32_e32 v94, v94
	v_exp_f32_e32 v93, v93
	s_waitcnt lgkmcnt(0)
	v_mfma_f32_32x32x16_bf16 v[48:63], v[72:75], v[68:71], v[48:63]
	ds_read2_b64 v[72:75], v142 offset0:200 offset1:202
	v_exp_f32_e32 v92, v92
	v_exp_f32_e32 v91, v91
	v_exp_f32_e32 v90, v90
	v_exp_f32_e32 v89, v89
	v_exp_f32_e32 v88, v88
	v_cvt_pk_bf16_f32 v66, v92, v93
	s_waitcnt lgkmcnt(0)
	v_mfma_f32_32x32x16_bf16 v[32:47], v[72:75], v[68:71], v[32:47]
	ds_read2_b64 v[72:75], v143 offset0:8 offset1:10
	v_cvt_pk_bf16_f32 v64, v88, v89
	v_cvt_pk_bf16_f32 v65, v90, v91
	v_cvt_pk_bf16_f32 v67, v94, v95
	s_mul_hi_i32 s3, s16, 0x900
	s_mulk_i32 s16, 0x900
	s_add_u32 s2, s16, s4
	s_waitcnt lgkmcnt(0)
	v_mfma_f32_32x32x16_bf16 v[16:31], v[72:75], v[68:71], v[16:31]
	ds_read2_b64 v[72:75], v144 offset0:72 offset1:74
	s_addc_u32 s3, s3, 0
	s_lshl_b64 s[2:3], s[2:3], 13
	s_add_u32 s2, s14, s2
	s_addc_u32 s3, s15, s3
	s_lshl_b32 s4, s5, 8
	s_add_u32 s4, s2, s4
	s_waitcnt lgkmcnt(0)
	v_mfma_f32_32x32x16_bf16 v[0:15], v[72:75], v[68:71], v[0:15]
	ds_read2_b64 v[68:71], v140 offset0:140 offset1:142
	s_addc_u32 s5, s3, 0
	s_waitcnt lgkmcnt(0)
	v_mfma_f32_32x32x16_bf16 v[48:63], v[68:71], v[64:67], v[48:63]
	ds_read2_b64 v[68:71], v142 offset0:204 offset1:206
	s_waitcnt lgkmcnt(0)
	v_mfma_f32_32x32x16_bf16 v[32:47], v[68:71], v[64:67], v[32:47]
	ds_read2_b64 v[68:71], v143 offset0:12 offset1:14
	s_waitcnt lgkmcnt(0)
	v_mfma_f32_32x32x16_bf16 v[16:31], v[68:71], v[64:67], v[16:31]
	ds_read2_b64 v[68:71], v144 offset0:76 offset1:78
	s_waitcnt lgkmcnt(0)
	v_mfma_f32_32x32x16_bf16 v[0:15], v[68:71], v[64:67], v[0:15]
	v_add_f32_e32 v64, 0, v108
	v_add_f32_e32 v64, v107, v64
	v_add_f32_e32 v64, v106, v64
	v_add_f32_e32 v64, v105, v64
	v_add_f32_e32 v64, v104, v64
	v_add_f32_e32 v64, v103, v64
	v_add_f32_e32 v64, v102, v64
	v_add_f32_e32 v64, v101, v64
	v_add_f32_e32 v64, v100, v64
	v_add_f32_e32 v64, v99, v64
	v_add_f32_e32 v64, v98, v64
	v_add_f32_e32 v64, v97, v64
	v_add_f32_e32 v64, v76, v64
	v_add_f32_e32 v64, v77, v64
	v_add_f32_e32 v64, v78, v64
	v_add_f32_e32 v64, v79, v64
	v_add_f32_e32 v64, v80, v64
	v_add_f32_e32 v64, v81, v64
	v_add_f32_e32 v64, v82, v64
	v_add_f32_e32 v64, v83, v64
	v_add_f32_e32 v64, v84, v64
	v_add_f32_e32 v64, v85, v64
	v_add_f32_e32 v64, v86, v64
	v_add_f32_e32 v64, v87, v64
	v_add_f32_e32 v64, v88, v64
	v_add_f32_e32 v64, v89, v64
	v_add_f32_e32 v64, v90, v64
	v_add_f32_e32 v64, v91, v64
	v_add_f32_e32 v64, v92, v64
	v_add_f32_e32 v64, v93, v64
	v_add_f32_e32 v64, v94, v64
	v_add_f32_e32 v64, v95, v64
	v_fmac_f32_e32 v64, v133, v96
	ds_bpermute_b32 v65, v123, v64
	s_waitcnt lgkmcnt(0)
; DI unsigned cvtpk(float lo, float hi) { f32x2_t v = {lo, hi}; bf16x2_t b = __builtin_convertvector(v, bf16x2_t); return __builtin_bit_cast(unsigned, b); }
; template <int DK, int KT>
; DI void attn_item(const bfu* __restrict__ Qp, const bfu* __restrict__ Kp, const bfu* __restrict__ Vtp, int nkeys, bfu* __restrict__ Op, int ldo, char* smem) {
;     ...
;   const float inv = 1.f / (lsum + __shfl_xor(lsum, 32));
;   bfu* orow = Op + (long)(w * 32 + l32) * ldo;
; #pragma unroll
;   for (int d = 0; d < 4; ++d)
; #pragma unroll
;     for (int rg = 0; rg < 4; ++rg) {
;       u32x2 v = {cvtpk(o[d][4 * rg] * inv, o[d][4 * rg + 1] * inv), cvtpk(o[d][4 * rg + 2] * inv, o[d][4 * rg + 3] * inv)};
;       *reinterpret_cast<u32x2*>(orow + d * 32 + 8 * rg + 4 * hi) = v;
;     }
	v_add_f32_e32 v64, v64, v65
	v_div_scale_f32 v65, s[2:3], v64, v64, 1.0
	v_rcp_f32_e32 v66, v65
	s_nop 0
	v_fma_f32 v67, -v65, v66, 1.0
	v_fmac_f32_e32 v66, v67, v66
	v_div_scale_f32 v67, vcc, 1.0, v64, 1.0
	v_mul_f32_e32 v68, v67, v66
	v_fma_f32 v69, -v65, v68, v67
	v_fmac_f32_e32 v68, v69, v66
	v_fma_f32 v65, -v65, v68, v67
	v_div_fmas_f32 v65, v65, v66, v68
	v_div_fixup_f32 v64, v65, v64, 1.0
	v_lshlrev_b64 v[66:67], 13, v[120:121]
	v_lshl_add_u64 v[66:67], s[4:5], 0, v[66:67]
	v_pk_mul_f32 v[48:49], v[48:49], v[64:65] op_sel_hi:[1,0]
	v_pk_mul_f32 v[50:51], v[50:51], v[64:65] op_sel_hi:[1,0]
	v_pk_mul_f32 v[32:33], v[32:33], v[64:65] op_sel_hi:[1,0]
	v_pk_mul_f32 v[34:35], v[34:35], v[64:65] op_sel_hi:[1,0]
	v_pk_mul_f32 v[16:17], v[16:17], v[64:65] op_sel_hi:[1,0]
	v_pk_mul_f32 v[18:19], v[18:19], v[64:65] op_sel_hi:[1,0]
	v_pk_mul_f32 v[0:1], v[0:1], v[64:65] op_sel_hi:[1,0]
	v_pk_mul_f32 v[2:3], v[2:3], v[64:65] op_sel_hi:[1,0]
	v_lshl_add_u64 v[66:67], v[66:67], 0, v[128:129]
	v_cvt_pk_bf16_f32 v48, v48, v49
	v_cvt_pk_bf16_f32 v49, v50, v51
	v_cvt_pk_bf16_f32 v32, v32, v33
	v_cvt_pk_bf16_f32 v33, v34, v35
	v_cvt_pk_bf16_f32 v16, v16, v17
	v_cvt_pk_bf16_f32 v17, v18, v19
	v_cvt_pk_bf16_f32 v0, v0, v1
	v_cvt_pk_bf16_f32 v1, v2, v3
	global_store_dwordx2 v[66:67], v[48:49], off
	v_pk_mul_f32 v[48:49], v[52:53], v[64:65] op_sel_hi:[1,0]
	v_pk_mul_f32 v[50:51], v[54:55], v[64:65] op_sel_hi:[1,0]
	global_store_dwordx2 v[66:67], v[32:33], off offset:64
	v_pk_mul_f32 v[32:33], v[36:37], v[64:65] op_sel_hi:[1,0]
	v_pk_mul_f32 v[34:35], v[38:39], v[64:65] op_sel_hi:[1,0]
	global_store_dwordx2 v[66:67], v[16:17], off offset:128
	v_pk_mul_f32 v[16:17], v[20:21], v[64:65] op_sel_hi:[1,0]
	v_pk_mul_f32 v[18:19], v[22:23], v[64:65] op_sel_hi:[1,0]
	global_store_dwordx2 v[66:67], v[0:1], off offset:192
	v_pk_mul_f32 v[0:1], v[4:5], v[64:65] op_sel_hi:[1,0]
	v_pk_mul_f32 v[2:3], v[6:7], v[64:65] op_sel_hi:[1,0]
	v_cvt_pk_bf16_f32 v48, v48, v49
	v_cvt_pk_bf16_f32 v49, v50, v51
	v_cvt_pk_bf16_f32 v32, v32, v33
	v_cvt_pk_bf16_f32 v33, v34, v35
	v_cvt_pk_bf16_f32 v16, v16, v17
	v_cvt_pk_bf16_f32 v17, v18, v19
	v_cvt_pk_bf16_f32 v0, v0, v1
	v_cvt_pk_bf16_f32 v1, v2, v3
	global_store_dwordx2 v[66:67], v[48:49], off offset:16
	v_pk_mul_f32 v[48:49], v[56:57], v[64:65] op_sel_hi:[1,0]
	v_pk_mul_f32 v[50:51], v[58:59], v[64:65] op_sel_hi:[1,0]
	global_store_dwordx2 v[66:67], v[32:33], off offset:80
	v_pk_mul_f32 v[32:33], v[40:41], v[64:65] op_sel_hi:[1,0]
	v_pk_mul_f32 v[34:35], v[42:43], v[64:65] op_sel_hi:[1,0]
	global_store_dwordx2 v[66:67], v[16:17], off offset:144
	v_pk_mul_f32 v[16:17], v[24:25], v[64:65] op_sel_hi:[1,0]
	v_pk_mul_f32 v[18:19], v[26:27], v[64:65] op_sel_hi:[1,0]
	global_store_dwordx2 v[66:67], v[0:1], off offset:208
	v_pk_mul_f32 v[0:1], v[8:9], v[64:65] op_sel_hi:[1,0]
	v_pk_mul_f32 v[2:3], v[10:11], v[64:65] op_sel_hi:[1,0]
	v_cvt_pk_bf16_f32 v48, v48, v49
	v_cvt_pk_bf16_f32 v49, v50, v51
	v_cvt_pk_bf16_f32 v32, v32, v33
	v_cvt_pk_bf16_f32 v33, v34, v35
	v_cvt_pk_bf16_f32 v16, v16, v17
	v_cvt_pk_bf16_f32 v17, v18, v19
	v_cvt_pk_bf16_f32 v0, v0, v1
	v_cvt_pk_bf16_f32 v1, v2, v3
	global_store_dwordx2 v[66:67], v[48:49], off offset:32
	v_pk_mul_f32 v[48:49], v[60:61], v[64:65] op_sel_hi:[1,0]
	v_pk_mul_f32 v[50:51], v[62:63], v[64:65] op_sel_hi:[1,0]
	global_store_dwordx2 v[66:67], v[32:33], off offset:96
	v_pk_mul_f32 v[32:33], v[44:45], v[64:65] op_sel_hi:[1,0]
	v_pk_mul_f32 v[34:35], v[46:47], v[64:65] op_sel_hi:[1,0]
	global_store_dwordx2 v[66:67], v[16:17], off offset:160
	v_pk_mul_f32 v[16:17], v[28:29], v[64:65] op_sel_hi:[1,0]
	v_pk_mul_f32 v[18:19], v[30:31], v[64:65] op_sel_hi:[1,0]
	global_store_dwordx2 v[66:67], v[0:1], off offset:224
	v_pk_mul_f32 v[0:1], v[12:13], v[64:65] op_sel_hi:[1,0]
	v_pk_mul_f32 v[2:3], v[14:15], v[64:65] op_sel_hi:[1,0]
	v_cvt_pk_bf16_f32 v48, v48, v49
	v_cvt_pk_bf16_f32 v49, v50, v51
	v_cvt_pk_bf16_f32 v32, v32, v33
	v_cvt_pk_bf16_f32 v33, v34, v35
	v_cvt_pk_bf16_f32 v16, v16, v17
	v_cvt_pk_bf16_f32 v17, v18, v19
	v_cvt_pk_bf16_f32 v0, v0, v1
	v_cvt_pk_bf16_f32 v1, v2, v3
	global_store_dwordx2 v[66:67], v[48:49], off offset:48
	global_store_dwordx2 v[66:67], v[32:33], off offset:112
	global_store_dwordx2 v[66:67], v[16:17], off offset:176
	global_store_dwordx2 v[66:67], v[0:1], off offset:240
	s_waitcnt lgkmcnt(0)
	s_barrier
	s_and_saveexec_b64 s[2:3], s[6:7]
	s_cbranch_execz .LBB0_755
	s_mov_b64 s[8:9], exec
	v_mbcnt_lo_u32_b32 v0, s8, 0
	v_mbcnt_hi_u32_b32 v0, s9, v0
	v_cmp_eq_u32_e32 vcc, 0, v0
	s_and_saveexec_b64 s[4:5], vcc
	s_cbranch_execz .LBB0_754
	s_bcnt1_i32_b64 s8, s[8:9]
	v_mov_b32_e32 v1, s8
	v_readlane_b32 s8, v255, 5
	v_readlane_b32 s9, v255, 6
	s_nop 4
	global_atomic_add v1, v129, v1, s[8:9] offset:512 sc0
	s_branch .LBB0_754

;   DI const float* diff_lam() const { return (const float*)sp[10]; }
; DI int TID() { int t = threadIdx.x; asm volatile("" : "+v"(t)); return t; }
; DI char* OPQ(const void* ptr) { unsigned long long v = (unsigned long long)ptr; asm volatile("" : "+s"(v)); return (char*)v; }
; DI float wsum(float v) { for (int o = 32; o > 0; o >>= 1) v += __shfl_xor(v, o); return v; }
; DI void phase_comb0(const Params& p, char* smem) {
;   char* G = OPQ(p.ws + WS_G);
;   const int tid = TID(), c0 = tid * 8;
;   float* sl = (float*)smem;
;   __syncthreads();
;   if (tid < 64) {
;     float a = wsum(p.diff_lam()[tid] * p.diff_lam()[64 + tid]), b = wsum(p.diff_lam()[128 + tid] * p.diff_lam()[192 + tid]);
;     if (tid == 0) sl[0] = __expf(a) - __expf(b) + 0.2f;
;   }
.LBB0_815:
	s_or_b64 exec, exec, s[4:5]
	v_readlane_b32 s0, v254, 16
	v_readlane_b32 s1, v254, 17
	v_mov_b32_e32 v16, v202
	s_waitcnt lgkmcnt(0)
	s_barrier
	s_nop 0
	v_cmp_gt_i32_e32 vcc, 64, v16
	s_barrier
	s_and_saveexec_b64 s[2:3], vcc
	s_xor_b64 s[4:5], exec, s[2:3]
	s_cbranch_execz .LBB0_819
	v_mov_b32_e32 v0, 0x12250
	ds_read_b64 v[0:1], v0
	v_ashrrev_i32_e32 v17, 31, v16
	v_and_b32_e32 v5, 64, v203
	v_add_u32_e32 v5, 64, v5
	v_xor_b32_e32 v6, 32, v203
	s_waitcnt lgkmcnt(0)
	v_lshl_add_u64 v[2:3], v[16:17], 2, v[0:1]
	global_load_dword v0, v[2:3], off
	global_load_dword v1, v[2:3], off offset:256
	global_load_dword v10, v[2:3], off offset:512
	s_nop 0
	global_load_dword v2, v[2:3], off offset:768
	v_cmp_lt_i32_e32 vcc, v6, v5
	s_waitcnt vmcnt(0) lgkmcnt(0)
	v_mul_f32_e32 v4, v0, v1
	v_cndmask_b32_e32 v6, v203, v6, vcc
	v_lshlrev_b32_e32 v6, 2, v6
	ds_bpermute_b32 v4, v6, v4
	v_mul_f32_e32 v3, v10, v2
	ds_bpermute_b32 v3, v6, v3
	s_waitcnt lgkmcnt(1)
	v_fmac_f32_e32 v4, v0, v1
	v_xor_b32_e32 v0, 16, v203
	v_cmp_lt_i32_e32 vcc, v0, v5
	v_xor_b32_e32 v1, 8, v203
	s_waitcnt lgkmcnt(0)
	v_fmac_f32_e32 v3, v10, v2
	v_cndmask_b32_e32 v0, v203, v0, vcc
	v_lshlrev_b32_e32 v7, 2, v0
	ds_bpermute_b32 v0, v7, v4
	v_cmp_lt_i32_e32 vcc, v1, v5
	ds_bpermute_b32 v2, v7, v3
	s_waitcnt lgkmcnt(1)
	v_add_f32_e32 v0, v4, v0
	v_cndmask_b32_e32 v1, v203, v1, vcc
	v_lshlrev_b32_e32 v4, 2, v1
	ds_bpermute_b32 v1, v4, v0
	s_waitcnt lgkmcnt(1)
	v_add_f32_e32 v2, v3, v2
	ds_bpermute_b32 v3, v4, v2
	s_waitcnt lgkmcnt(1)
	v_add_f32_e32 v0, v0, v1
	v_xor_b32_e32 v1, 4, v203
	v_cmp_lt_i32_e32 vcc, v1, v5
	s_waitcnt lgkmcnt(0)
	v_add_f32_e32 v2, v2, v3
	v_cndmask_b32_e32 v1, v203, v1, vcc
	v_lshlrev_b32_e32 v8, 2, v1
	ds_bpermute_b32 v1, v8, v0
	ds_bpermute_b32 v3, v8, v2
	s_waitcnt lgkmcnt(1)
	v_add_f32_e32 v0, v0, v1
	v_xor_b32_e32 v1, 2, v203
	v_cmp_lt_i32_e32 vcc, v1, v5
	s_waitcnt lgkmcnt(0)
	v_add_f32_e32 v2, v2, v3
	v_cndmask_b32_e32 v1, v203, v1, vcc
	v_lshlrev_b32_e32 v9, 2, v1
	ds_bpermute_b32 v1, v9, v0
	ds_bpermute_b32 v3, v9, v2
	s_waitcnt lgkmcnt(1)
	v_add_f32_e32 v0, v0, v1
	v_xor_b32_e32 v1, 1, v203
	v_cmp_lt_i32_e32 vcc, v1, v5
	s_waitcnt lgkmcnt(0)
	v_add_f32_e32 v2, v2, v3
	v_cndmask_b32_e32 v1, v203, v1, vcc
	v_lshlrev_b32_e32 v5, 2, v1
	ds_bpermute_b32 v1, v5, v0
	ds_bpermute_b32 v3, v5, v2
	v_cmp_eq_u32_e32 vcc, 0, v16
	s_and_saveexec_b64 s[2:3], vcc
	s_cbranch_execz .LBB0_818
	s_waitcnt lgkmcnt(1)
	v_add_f32_e32 v0, v0, v1
	s_waitcnt lgkmcnt(0)
	v_add_f32_e32 v1, v2, v3
	v_mul_f32_e32 v0, 0x3fb8aa3b, v0
	v_mul_f32_e32 v1, 0x3fb8aa3b, v1
	v_exp_f32_e32 v0, v0
	v_exp_f32_e32 v1, v1
	s_nop 0
	v_sub_f32_e32 v0, v0, v1
	v_add_f32_e32 v0, 0x3e4ccccd, v0
	ds_write_b32 v129, v0

;   DI const float* x() const { return (const float*)sp[0]; }
;   DI const float* diff_g() const { return (const float*)sp[11]; }
;   DI const float* mlstm_g() const { return (const float*)sp[12]; }
; DI void phase_comb0(const Params& p, char* smem) {
;     ...
;   const bfu* Oa = (const bfu*)(G + L0_OA); const bfu* Hn = (const bfu*)(G + L0_HN); const bfu* og = (const bfu*)(G + L0_OG);
;   const bfu* gate = (const bfu*)(G + L0_GATE); const float* dn = (const float*)(G + L0_SM + SM_DN); bfu* mix = (bfu*)(G + L0_MIX);
;   float gd[8], gm[8];
;   for (int j = 0; j < 8; ++j) { gd[j] = p.diff_g()[c0 + j]; gm[j] = p.mlstm_g()[c0 + j]; }
;   for (int i = blockIdx.x; i < MG; i += gridDim.x) {
;     const int bg = i / T, t = i % T;
;     const bf16x8 r_o1 = ld8(Oa + (long)i * 4096 + ((c0 >> 7) * 2) * 128 + (c0 & 127)), r_o2 = ld8(Oa + (long)i * 4096 + ((c0 >> 7) * 2 + 1) * 128 + (c0 & 127));
;     const bf16x8 r_g0 = ld8(gate + (long)i * 4096 + c0), r_g1 = ld8(gate + (long)i * 4096 + 2048 + c0);
;     const bf16x8 r_h0 = ld8(Hn + (long)i * 2048 + c0), r_h1 = ld8(Hn + ((long)MG + i) * 2048 + c0), r_og = ld8(og + (long)i * 2048 + c0);
;     const float r_d0 = dn[((long)(0 * GB + bg) * 8 + (c0 >> 8)) * T + t], r_d1 = dn[((long)(1 * GB + bg) * 8 + (c0 >> 8)) * T + t];
.LBB0_819:
	s_or_b64 exec, exec, s[4:5]
	v_readlane_b32 s2, v254, 36
	v_readlane_b32 s3, v254, 37
	s_andn2_b64 vcc, exec, s[2:3]
	s_waitcnt lgkmcnt(0)
	s_barrier
	s_cbranch_vccnz .LBB0_822
	v_mov_b32_e32 v0, 0x12258
	ds_read2_b64 v[0:3], v0 offset1:1
	ds_read_b32 v44, v129
	v_lshlrev_b32_e32 v18, 3, v16
	v_ashrrev_i32_e32 v19, 31, v18
	v_lshlrev_b64 v[4:5], 2, v[18:19]
	s_waitcnt lgkmcnt(0)
	v_lshl_add_u64 v[6:7], v[0:1], 0, v[4:5]
	v_lshl_add_u64 v[12:13], v[2:3], 0, v[4:5]
	global_load_dwordx4 v[0:3], v[6:7], off
	s_nop 0
	global_load_dwordx4 v[4:7], v[6:7], off offset:16
	s_nop 0
	global_load_dwordx4 v[8:11], v[12:13], off
	s_nop 0
	global_load_dwordx4 v[12:15], v[12:13], off offset:16
	v_and_b32_e32 v17, 64, v203
	v_lshlrev_b32_e32 v22, 4, v16
	v_ashrrev_i32_e32 v52, 5, v16
	v_xor_b32_e32 v16, 1, v203
	v_add_u32_e32 v17, 64, v17
	v_cmp_lt_i32_e32 vcc, v16, v17
	s_add_u32 s4, s0, 0xe190000
	s_addc_u32 s5, s1, 0
	v_cndmask_b32_e32 v16, v203, v16, vcc
	v_lshlrev_b32_e32 v70, 2, v16
	v_xor_b32_e32 v16, 2, v203
	v_cmp_lt_i32_e32 vcc, v16, v17
	s_add_u32 s6, s0, 0xbd00000
	s_addc_u32 s7, s1, 0
	v_cndmask_b32_e32 v16, v203, v16, vcc
	v_lshlrev_b32_e32 v71, 2, v16
	v_xor_b32_e32 v16, 4, v203
	v_cmp_lt_i32_e32 vcc, v16, v17
	s_add_u32 s2, s0, 0x7500000
	v_and_b32_e32 v20, 0xffffff00, v22
	v_cndmask_b32_e32 v16, v203, v16, vcc
	v_lshlrev_b32_e32 v72, 2, v16
	v_xor_b32_e32 v16, 8, v203
	v_cmp_lt_i32_e32 vcc, v16, v17
	s_addc_u32 s3, s1, 0
	v_ashrrev_i32_e32 v21, 31, v20
	v_cndmask_b32_e32 v16, v203, v16, vcc
	v_lshlrev_b32_e32 v73, 2, v16
	v_xor_b32_e32 v16, 16, v203
	v_cmp_lt_i32_e32 vcc, v16, v17
	s_add_u32 s14, s0, 0xfc00000
	v_lshlrev_b64 v[46:47], 1, v[18:19]
	v_cndmask_b32_e32 v16, v203, v16, vcc
	v_lshlrev_b32_e32 v74, 2, v16
	v_lshl_add_u64 v[16:17], v[20:21], 1, s[0:1]
	v_and_b32_e32 v128, 0xf0, v22
	s_addc_u32 s15, s1, 0
	v_lshl_add_u64 v[18:19], s[0:1], 0, v[46:47]
	v_lshl_add_u64 v[16:17], v[16:17], 0, v[128:129]
	s_mov_b64 s[0:1], 0x9900000
	v_readlane_b32 s20, v254, 21
	s_mov_b64 s[8:9], 0x6300000
	v_lshl_add_u64 v[54:55], v[16:17], 0, s[0:1]
	v_readlane_b32 s0, v254, 0
	v_readlane_b32 s21, v254, 22
	s_mov_b32 s24, 0x3b800000
	v_lshl_add_u64 v[48:49], s[6:7], 0, v[46:47]
	v_lshl_add_u64 v[50:51], v[18:19], 0, s[8:9]
	v_ashrrev_i32_e32 v53, 31, v52
	v_mov_b32_e32 v45, v44
	s_mov_b32 s8, s0
	s_movk_i32 s21, 0x1000
	s_movk_i32 s22, 0x2400
	s_brev_b32 s25, 60
	s_mov_b32 s23, 0x800000
.LBB0_821:
	s_mul_hi_i32 s0, s8, 0x38e38e39
	s_lshr_b32 s1, s0, 31
	s_ashr_i32 s0, s0, 9
	s_add_i32 s12, s0, s1
	s_mul_i32 s0, s12, 0xfffff700
	s_ashr_i32 s9, s8, 31
	s_add_i32 s10, s8, s0
	s_lshl_b64 s[16:17], s[8:9], 12
	s_lshl_b64 s[0:1], s[8:9], 13
	s_add_u32 s18, s2, s0
	v_lshl_add_u64 v[16:17], v[54:55], 0, s[0:1]
	s_addc_u32 s19, s3, s1
	global_load_dwordx4 v[36:39], v[16:17], off
	global_load_dwordx4 v[32:35], v[16:17], off offset:256
	v_lshl_add_u64 v[16:17], s[18:19], 0, v[46:47]
	global_load_dwordx4 v[40:43], v[16:17], off
	s_add_u32 s18, s6, s16
	s_addc_u32 s19, s7, s17
	s_ashr_i32 s13, s12, 31
	s_lshl_b64 s[12:13], s[12:13], 3
	v_lshl_add_u64 v[56:57], s[12:13], 0, v[52:53]
	s_ashr_i32 s11, s10, 31
	v_mov_b64_e32 v[58:59], s[4:5]
	v_lshl_add_u64 v[20:21], v[48:49], 0, s[16:17]
	v_lshl_add_u64 v[28:29], v[50:51], 0, s[16:17]
	v_mad_u64_u32 v[60:61], s[16:17], v56, s22, v[58:59]
	s_lshl_b64 s[10:11], s[10:11], 2
	v_mad_i32_i24 v61, v57, s22, v61
	s_add_u32 s12, s12, 16
	v_lshl_add_u64 v[56:57], v[60:61], 0, s[10:11]
	s_addc_u32 s13, s13, 0
	global_load_dword v75, v[56:57], off
	v_lshl_add_u64 v[56:57], s[12:13], 0, v[52:53]
	v_mad_u64_u32 v[58:59], s[12:13], v56, s22, v[58:59]
	v_mad_i32_i24 v59, v57, s22, v59
	v_lshl_add_u64 v[56:57], v[58:59], 0, s[10:11]
	global_load_dwordx4 v[20:23], v[20:21], off
	v_add_co_u32_e32 v16, vcc, s21, v16
	global_load_dword v76, v[56:57], off
	s_nop 0
	v_addc_co_u32_e32 v17, vcc, 0, v17, vcc
	v_lshl_add_u64 v[24:25], s[18:19], 0, v[46:47]
	s_mov_b32 s9, 0x1200000
	v_add_co_u32_e32 v24, vcc, s9, v24
	global_load_dwordx4 v[28:31], v[28:29], off
	s_nop 0
	v_addc_co_u32_e32 v25, vcc, 0, v25, vcc
	global_load_dwordx4 v[16:19], v[16:17], off
	s_add_u32 s0, s14, s0
	global_load_dwordx4 v[24:27], v[24:25], off
	s_addc_u32 s1, s15, s1
	s_add_i32 s8, s8, s20
	s_cmpk_lt_i32 s8, 0x1200
	s_waitcnt vmcnt(0) lgkmcnt(0)
; DI void unpack8(bf16x8 v, float* f) { u32x4 w = __builtin_bit_cast(u32x4, v); for (int i = 0; i < 4; ++i) { f[2 * i] = bflo(w[i]); f[2 * i + 1] = bfhi(w[i]); } }
; DI float silu(float v) { return v / (1.f + __expf(-v)); }
; DI void phase_comb0(const Params& p, char* smem) {
;     ...
;     {
;       float o1[8], o2[8], gt[8];
;       unpack8(r_o1, o1); unpack8(r_o2, o2);
;       unpack8(r_g0, gt);
;       float ss = 0;
;       for (int j = 0; j < 8; ++j) { o1[j] -= lam * o2[j]; ss += o1[j] * o1[j]; }
;       ss += __shfl_xor(ss, 1); ss += __shfl_xor(ss, 2); ss += __shfl_xor(ss, 4); ss += __shfl_xor(ss, 8);
;       const float rms = rsqrtf(ss * (1.f / 128.f) + EPS) * 0.8f;
;       for (int j = 0; j < 8; ++j) o[j] = o1[j] * rms * gd[j] * silu(gt[j]);
	v_lshlrev_b32_e32 v56, 16, v39
	v_and_b32_e32 v57, 0xffff0000, v39
	v_lshlrev_b32_e32 v60, 16, v38
	v_and_b32_e32 v61, 0xffff0000, v38
	v_lshlrev_b32_e32 v38, 16, v34
	v_and_b32_e32 v39, 0xffff0000, v34
	v_lshlrev_b32_e32 v62, 16, v42
	v_and_b32_e32 v63, 0xffff0000, v42
	v_lshlrev_b32_e32 v58, 16, v35
	v_and_b32_e32 v59, 0xffff0000, v35
	v_pk_fma_f32 v[34:35], v[44:45], v[38:39], v[60:61] neg_lo:[1,0,0] neg_hi:[1,0,0]
	v_mul_f32_e32 v38, 0xbfb8aa3b, v62
	v_mul_f32_e32 v39, 0xbfb8aa3b, v63
	v_exp_f32_e32 v38, v38
	v_exp_f32_e32 v39, v39
	v_lshlrev_b32_e32 v68, 16, v43
	v_and_b32_e32 v69, 0xffff0000, v43
	v_pk_mul_f32 v[42:43], v[34:35], v[34:35]
	v_pk_add_f32 v[38:39], v[38:39], 1.0 op_sel_hi:[1,0]
	v_pk_fma_f32 v[56:57], v[44:45], v[58:59], v[56:57] neg_lo:[1,0,0] neg_hi:[1,0,0]
	v_div_scale_f32 v60, s[10:11], v39, v39, v63
	v_rcp_f32_e32 v61, v60
	v_pk_mul_f32 v[58:59], v[56:57], v[56:57]
	v_fma_f32 v64, -v60, v61, 1.0
	v_fmac_f32_e32 v61, v64, v61
	v_div_scale_f32 v64, vcc, v63, v39, v63
	v_mul_f32_e32 v65, v64, v61
	v_fma_f32 v66, -v60, v65, v64
	v_fmac_f32_e32 v65, v66, v61
	v_fma_f32 v60, -v60, v65, v64
	v_div_fmas_f32 v60, v60, v61, v65
	v_div_fixup_f32 v39, v60, v39, v63
	v_div_scale_f32 v60, s[10:11], v38, v38, v62
	v_rcp_f32_e32 v61, v60
	v_lshlrev_b32_e32 v82, 16, v31
	v_and_b32_e32 v83, 0xffff0000, v31
	v_lshlrev_b32_e32 v90, 16, v19
	v_fma_f32 v63, -v60, v61, 1.0
	v_fmac_f32_e32 v61, v63, v61
	v_div_scale_f32 v63, vcc, v62, v38, v62
	v_mul_f32_e32 v64, v63, v61
	v_fma_f32 v65, -v60, v64, v63
	v_fmac_f32_e32 v64, v65, v61
	v_fma_f32 v60, -v60, v64, v63
	v_div_fmas_f32 v60, v60, v61, v64
	v_div_fixup_f32 v38, v60, v38, v62
	v_lshlrev_b32_e32 v62, 16, v33
	v_and_b32_e32 v63, 0xffff0000, v33
	v_lshlrev_b32_e32 v33, 16, v41
	v_lshlrev_b32_e32 v60, 16, v37
	v_and_b32_e32 v61, 0xffff0000, v37
	v_and_b32_e32 v37, 0xffff0000, v41
	v_mul_f32_e32 v41, 0xbfb8aa3b, v33
	v_pk_fma_f32 v[60:61], v[44:45], v[62:63], v[60:61] neg_lo:[1,0,0] neg_hi:[1,0,0]
	v_exp_f32_e32 v62, v41
	v_mul_f32_e32 v41, 0xbfb8aa3b, v37
	v_exp_f32_e32 v63, v41
	v_and_b32_e32 v91, 0xffff0000, v19
	v_lshlrev_b32_e32 v84, 16, v23
	v_and_b32_e32 v85, 0xffff0000, v27
	v_pk_add_f32 v[62:63], v[62:63], 1.0 op_sel_hi:[1,0]
	v_pk_mul_f32 v[64:65], v[60:61], v[60:61]
	v_div_scale_f32 v41, s[10:11], v63, v63, v37
	v_rcp_f32_e32 v66, v41
	s_nop 0
	v_fma_f32 v67, -v41, v66, 1.0
	v_fmac_f32_e32 v66, v67, v66
	v_div_scale_f32 v67, vcc, v37, v63, v37
	v_mul_f32_e32 v77, v67, v66
	v_fma_f32 v78, -v41, v77, v67
	v_fmac_f32_e32 v77, v78, v66
	v_fma_f32 v41, -v41, v77, v67
	v_div_fmas_f32 v41, v41, v66, v77
	v_div_fixup_f32 v63, v41, v63, v37
	v_div_scale_f32 v37, s[10:11], v62, v62, v33
	v_rcp_f32_e32 v41, v37
	s_nop 0
	v_fma_f32 v66, -v37, v41, 1.0
	v_fmac_f32_e32 v41, v66, v41
	v_div_scale_f32 v66, vcc, v33, v62, v33
	v_mul_f32_e32 v67, v66, v41
	v_fma_f32 v77, -v37, v67, v66
	v_fmac_f32_e32 v67, v77, v41
	v_fma_f32 v37, -v37, v67, v66
	v_div_fmas_f32 v37, v37, v41, v67
	v_div_fixup_f32 v62, v37, v62, v33
	v_lshlrev_b32_e32 v66, 16, v36
	v_and_b32_e32 v67, 0xffff0000, v36
	v_lshlrev_b32_e32 v36, 16, v32
	v_and_b32_e32 v37, 0xffff0000, v32
	v_lshlrev_b32_e32 v41, 16, v40
	v_and_b32_e32 v40, 0xffff0000, v40
	v_pk_fma_f32 v[32:33], v[44:45], v[36:37], v[66:67] neg_lo:[1,0,0] neg_hi:[1,0,0]
	v_mul_f32_e32 v36, 0xbfb8aa3b, v41
	v_mul_f32_e32 v37, 0xbfb8aa3b, v40
	v_exp_f32_e32 v36, v36
	v_exp_f32_e32 v37, v37
	v_pk_mul_f32 v[66:67], v[32:33], v[32:33]
	v_pk_add_f32 v[36:37], v[36:37], 1.0 op_sel_hi:[1,0]
	s_nop 0
	v_div_scale_f32 v77, s[10:11], v37, v37, v40
	v_rcp_f32_e32 v78, v77
	s_nop 0
	v_fma_f32 v79, -v77, v78, 1.0
	v_fmac_f32_e32 v78, v79, v78
	v_div_scale_f32 v79, vcc, v40, v37, v40
	v_mul_f32_e32 v80, v79, v78
	v_fma_f32 v81, -v77, v80, v79
	v_fmac_f32_e32 v80, v81, v78
	v_fma_f32 v77, -v77, v80, v79
	v_div_fmas_f32 v77, v77, v78, v80
	v_div_fixup_f32 v37, v77, v37, v40
	v_div_scale_f32 v40, s[10:11], v36, v36, v41
	v_rcp_f32_e32 v77, v40
	s_nop 0
	v_fma_f32 v78, -v40, v77, 1.0
	v_fmac_f32_e32 v77, v78, v77
	v_div_scale_f32 v78, vcc, v41, v36, v41
	v_mul_f32_e32 v79, v78, v77
	v_fma_f32 v80, -v40, v79, v78
	v_fmac_f32_e32 v79, v80, v77
	v_fma_f32 v40, -v40, v79, v78
	v_div_fmas_f32 v40, v40, v77, v79
	v_div_fixup_f32 v36, v40, v36, v41
	v_mul_f32_e32 v40, 0xbfb8aa3b, v68
	v_mul_f32_e32 v41, 0xbfb8aa3b, v69
	v_exp_f32_e32 v40, v40
	v_exp_f32_e32 v41, v41
	s_nop 0
	v_pk_add_f32 v[40:41], v[40:41], 1.0 op_sel_hi:[1,0]
	s_nop 0
	v_div_scale_f32 v77, s[10:11], v41, v41, v69
	v_rcp_f32_e32 v78, v77
	s_nop 0
	v_fma_f32 v79, -v77, v78, 1.0
	v_fmac_f32_e32 v78, v79, v78
	v_div_scale_f32 v79, vcc, v69, v41, v69
	v_mul_f32_e32 v80, v79, v78
	v_fma_f32 v81, -v77, v80, v79
	v_fmac_f32_e32 v80, v81, v78
	v_fma_f32 v77, -v77, v80, v79
	v_div_fmas_f32 v77, v77, v78, v80
	v_div_fixup_f32 v41, v77, v41, v69
	v_div_scale_f32 v69, s[10:11], v40, v40, v68
	v_rcp_f32_e32 v77, v69
	v_and_b32_e32 v81, 0xffff0000, v30
	v_fma_f32 v78, -v69, v77, 1.0
	v_fmac_f32_e32 v77, v78, v77
	v_div_scale_f32 v78, vcc, v68, v40, v68
	v_mul_f32_e32 v79, v78, v77
	v_fma_f32 v80, -v69, v79, v78
	v_fmac_f32_e32 v79, v80, v77
	v_fma_f32 v69, -v69, v79, v78
	v_div_fmas_f32 v69, v69, v77, v79
	v_lshlrev_b32_e32 v77, 16, v28
	v_and_b32_e32 v28, 0xffff0000, v28
	v_lshlrev_b32_e32 v78, 16, v29
	v_mul_f32_e32 v28, 0xbfb8aa3b, v28
	v_div_fixup_f32 v40, v69, v40, v68
	v_lshl_add_u64 v[68:69], s[0:1], 0, v[46:47]
	v_and_b32_e32 v29, 0xffff0000, v29
	v_exp_f32_e32 v31, v28
	v_mul_f32_e32 v28, 0xbfb8aa3b, v78
	v_div_scale_f32 v19, s[0:1], v75, v75, 1.0
	v_exp_f32_e32 v78, v28
	v_mul_f32_e32 v28, 0xbfb8aa3b, v29
; DI void unpack8(bf16x8 v, float* f) { u32x4 w = __builtin_bit_cast(u32x4, v); for (int i = 0; i < 4; ++i) { f[2 * i] = bflo(w[i]); f[2 * i + 1] = bfhi(w[i]); } }
; DI float silu(float v) { return v / (1.f + __expf(-v)); }
; DI float sigm(float v) { return 1.f / (1.f + __expf(-v)); }
; DI void phase_comb0(const Params& p, char* smem) {
;     ...
;       float h0[8], h1[8], gt[8], ov[8];
;       unpack8(r_h0, h0); unpack8(r_h1, h1);
;       unpack8(r_g1, gt); unpack8(r_og, ov);
;       const float d0 = 1.f / r_d0, d1 = 1.f / r_d1;
;       float sm = 0;
;       for (int j = 0; j < 8; ++j) { h0[j] = h0[j] * d0 + h1[j] * d1; sm += h0[j]; }
;     ...
;       for (int j = 0; j < 8; ++j) o[j] = h0[j] * rstd * gm[j] * sigm(ov[j]) * silu(gt[j]);
	v_mul_f32_e32 v29, 0xbfb8aa3b, v83
	v_and_b32_e32 v83, 0xffff0000, v23
	v_rcp_f32_e32 v23, v19
	v_lshlrev_b32_e32 v80, 16, v30
	v_exp_f32_e32 v79, v28
	v_mul_f32_e32 v28, 0xbfb8aa3b, v80
	v_exp_f32_e32 v80, v28
	v_mul_f32_e32 v28, 0xbfb8aa3b, v81
	v_exp_f32_e32 v81, v28
	v_mul_f32_e32 v28, 0xbfb8aa3b, v82
	v_lshlrev_b32_e32 v82, 16, v27
	v_fma_f32 v27, -v19, v23, 1.0
	v_fmac_f32_e32 v23, v27, v23
	v_div_scale_f32 v27, vcc, 1.0, v75, 1.0
	v_mul_f32_e32 v30, 0xbfb8aa3b, v77
	v_mul_f32_e32 v77, v27, v23
	v_fma_f32 v86, -v19, v77, v27
	v_fmac_f32_e32 v77, v86, v23
	v_fma_f32 v19, -v19, v77, v27
	v_div_fmas_f32 v19, v19, v23, v77
	v_div_fixup_f32 v77, v19, v75, 1.0
	v_div_scale_f32 v19, s[0:1], v76, v76, 1.0
	v_rcp_f32_e32 v23, v19
	v_pk_add_f32 v[78:79], v[78:79], 1.0 op_sel_hi:[1,0]
	v_exp_f32_e32 v30, v30
	v_exp_f32_e32 v28, v28
	v_fma_f32 v27, -v19, v23, 1.0
	v_fmac_f32_e32 v23, v27, v23
	v_div_scale_f32 v27, vcc, 1.0, v76, 1.0
	v_mul_f32_e32 v75, v27, v23
	v_fma_f32 v86, -v19, v75, v27
	v_fmac_f32_e32 v75, v86, v23
	v_fma_f32 v19, -v19, v75, v27
	v_div_fmas_f32 v19, v19, v23, v75
	v_div_fixup_f32 v76, v19, v76, 1.0
	v_lshlrev_b32_e32 v75, 16, v18
	v_pk_mul_f32 v[84:85], v[76:77], v[84:85] op_sel:[1,0] op_sel_hi:[0,1]
	v_and_b32_e32 v86, 0xffff0000, v18
	v_mul_f32_e32 v18, 0xbfb8aa3b, v75
	v_pk_fma_f32 v[82:83], v[76:77], v[82:83], v[84:85]
	v_lshlrev_b32_e32 v84, 16, v26
	v_and_b32_e32 v23, 0xffff0000, v26
	v_exp_f32_e32 v26, v18
	v_pk_add_f32 v[18:19], v[80:81], 1.0 op_sel_hi:[1,0]
	v_and_b32_e32 v85, 0xffff0000, v22
	v_div_scale_f32 v27, s[0:1], v19, v19, 1.0
	v_rcp_f32_e32 v80, v27
	v_lshlrev_b32_e32 v22, 16, v22
	v_pk_mul_f32 v[22:23], v[76:77], v[22:23] op_sel:[1,0] op_sel_hi:[0,1]
	v_pk_fma_f32 v[22:23], v[76:77], v[84:85], v[22:23]
	v_fma_f32 v81, -v27, v80, 1.0
	v_fmac_f32_e32 v80, v81, v80
	v_div_scale_f32 v81, vcc, 1.0, v19, 1.0
	v_mul_f32_e32 v87, v81, v80
	v_fma_f32 v88, -v27, v87, v81
	v_fmac_f32_e32 v87, v88, v80
	v_fma_f32 v27, -v27, v87, v81
	v_div_fmas_f32 v27, v27, v80, v87
	v_div_fixup_f32 v19, v27, v19, 1.0
	v_div_scale_f32 v27, s[0:1], v18, v18, 1.0
	v_rcp_f32_e32 v80, v27
	v_lshlrev_b32_e32 v84, 16, v21
	v_and_b32_e32 v85, 0xffff0000, v25
	v_pk_mul_f32 v[84:85], v[76:77], v[84:85] op_sel:[1,0] op_sel_hi:[0,1]
	v_fma_f32 v81, -v27, v80, 1.0
	v_fmac_f32_e32 v80, v81, v80
	v_div_scale_f32 v81, vcc, 1.0, v18, 1.0
	v_mul_f32_e32 v87, v81, v80
	v_fma_f32 v88, -v27, v87, v81
	v_fmac_f32_e32 v87, v88, v80
	v_fma_f32 v27, -v27, v87, v81
	v_div_fmas_f32 v27, v27, v80, v87
	v_div_fixup_f32 v18, v27, v18, 1.0
	v_mul_f32_e32 v27, 0xbfb8aa3b, v86
	v_exp_f32_e32 v27, v27
	v_exp_f32_e32 v29, v29
	v_pk_add_f32 v[26:27], v[26:27], 1.0 op_sel_hi:[1,0]
	s_nop 0
	v_div_scale_f32 v80, s[0:1], v27, v27, v86
	v_rcp_f32_e32 v81, v80
	s_nop 0
	v_fma_f32 v87, -v80, v81, 1.0
	v_fmac_f32_e32 v81, v87, v81
	v_div_scale_f32 v87, vcc, v86, v27, v86
	v_mul_f32_e32 v88, v87, v81
	v_fma_f32 v89, -v80, v88, v87
	v_fmac_f32_e32 v88, v89, v81
	v_fma_f32 v80, -v80, v88, v87
	v_div_fmas_f32 v80, v80, v81, v88
	v_div_fixup_f32 v27, v80, v27, v86
	v_div_scale_f32 v80, s[0:1], v26, v26, v75
	v_rcp_f32_e32 v81, v80
	s_nop 0
	v_fma_f32 v86, -v80, v81, 1.0
	v_fmac_f32_e32 v81, v86, v81
	v_div_scale_f32 v86, vcc, v75, v26, v75
	v_mul_f32_e32 v87, v86, v81
	v_fma_f32 v88, -v80, v87, v86
	v_fmac_f32_e32 v87, v88, v81
	v_fma_f32 v80, -v80, v87, v86
	v_div_fmas_f32 v80, v80, v81, v87
	v_and_b32_e32 v81, 0xffff0000, v21
	v_lshlrev_b32_e32 v21, 16, v17
	v_div_fixup_f32 v26, v80, v26, v75
	v_lshlrev_b32_e32 v80, 16, v25
	v_mul_f32_e32 v25, 0xbfb8aa3b, v21
	v_exp_f32_e32 v86, v25
	v_div_scale_f32 v25, s[0:1], v79, v79, 1.0
	v_rcp_f32_e32 v75, v25
	v_and_b32_e32 v17, 0xffff0000, v17
	v_pk_fma_f32 v[80:81], v[76:77], v[80:81], v[84:85]
	v_lshlrev_b32_e32 v84, 16, v24
	v_fma_f32 v87, -v25, v75, 1.0
	v_fmac_f32_e32 v75, v87, v75
	v_div_scale_f32 v87, vcc, 1.0, v79, 1.0
	v_mul_f32_e32 v88, v87, v75
	v_fma_f32 v89, -v25, v88, v87
	v_fmac_f32_e32 v88, v89, v75
	v_fma_f32 v25, -v25, v88, v87
	v_div_fmas_f32 v25, v25, v75, v88
	v_div_fixup_f32 v79, v25, v79, 1.0
	v_div_scale_f32 v25, s[0:1], v78, v78, 1.0
	v_rcp_f32_e32 v75, v25
	v_and_b32_e32 v85, 0xffff0000, v20
	v_lshlrev_b32_e32 v20, 16, v20
	v_fma_f32 v87, -v25, v75, 1.0
	v_fmac_f32_e32 v75, v87, v75
	v_div_scale_f32 v87, vcc, 1.0, v78, 1.0
	v_mul_f32_e32 v88, v87, v75
	v_fma_f32 v89, -v25, v88, v87
	v_fmac_f32_e32 v88, v89, v75
	v_fma_f32 v25, -v25, v88, v87
	v_div_fmas_f32 v25, v25, v75, v88
	v_div_fixup_f32 v78, v25, v78, 1.0
	v_mul_f32_e32 v25, 0xbfb8aa3b, v17
	v_exp_f32_e32 v87, v25
	s_nop 0
	v_pk_add_f32 v[86:87], v[86:87], 1.0 op_sel_hi:[1,0]
	s_nop 0
	v_div_scale_f32 v25, s[0:1], v87, v87, v17
	v_rcp_f32_e32 v75, v25
	s_nop 0
	v_fma_f32 v88, -v25, v75, 1.0
	v_fmac_f32_e32 v75, v88, v75
	v_div_scale_f32 v88, vcc, v17, v87, v17
	v_mul_f32_e32 v89, v88, v75
	v_fma_f32 v92, -v25, v89, v88
	v_fmac_f32_e32 v89, v92, v75
	v_fma_f32 v25, -v25, v89, v88
	v_div_fmas_f32 v25, v25, v75, v89
	v_div_fixup_f32 v87, v25, v87, v17
	v_div_scale_f32 v17, s[0:1], v86, v86, v21
	v_rcp_f32_e32 v25, v17
	s_nop 0
	v_fma_f32 v75, -v17, v25, 1.0
	v_fmac_f32_e32 v25, v75, v25
	v_div_scale_f32 v75, vcc, v21, v86, v21
	v_mul_f32_e32 v88, v75, v25
	v_fma_f32 v89, -v17, v88, v75
	v_fmac_f32_e32 v88, v89, v25
	v_fma_f32 v17, -v17, v88, v75
	v_div_fmas_f32 v17, v17, v25, v88
	v_div_fixup_f32 v86, v17, v86, v21
	v_and_b32_e32 v21, 0xffff0000, v24
	v_pk_add_f32 v[24:25], v[30:31], 1.0 op_sel_hi:[1,0]
	v_lshlrev_b32_e32 v75, 16, v16
	v_div_scale_f32 v17, s[0:1], v25, v25, 1.0
	v_rcp_f32_e32 v30, v17
	v_and_b32_e32 v88, 0xffff0000, v16
; DI void phase_comb0(const Params& p, char* smem) {
;     ...
;       float ss = 0;
;       for (int j = 0; j < 8; ++j) { o1[j] -= lam * o2[j]; ss += o1[j] * o1[j]; }
;       ss += __shfl_xor(ss, 1); ss += __shfl_xor(ss, 2); ss += __shfl_xor(ss, 4); ss += __shfl_xor(ss, 8);
;     ...
;       float sm = 0;
;       for (int j = 0; j < 8; ++j) { h0[j] = h0[j] * d0 + h1[j] * d1; sm += h0[j]; }
;       sm += __shfl_xor(sm, 1); sm += __shfl_xor(sm, 2); sm += __shfl_xor(sm, 4); sm += __shfl_xor(sm, 8); sm += __shfl_xor(sm, 16);
;       const float mean = sm * (1.f / 256.f);
;       float sq = 0;
;       for (int j = 0; j < 8; ++j) { h0[j] -= mean; sq += h0[j] * h0[j]; }
;       sq += __shfl_xor(sq, 1); sq += __shfl_xor(sq, 2); sq += __shfl_xor(sq, 4); sq += __shfl_xor(sq, 8); sq += __shfl_xor(sq, 16);
	v_mul_f32_e32 v16, 0xbfb8aa3b, v75
	v_exp_f32_e32 v16, v16
	v_fma_f32 v31, -v17, v30, 1.0
	v_fmac_f32_e32 v30, v31, v30
	v_div_scale_f32 v31, vcc, 1.0, v25, 1.0
	v_mul_f32_e32 v89, v31, v30
	v_fma_f32 v92, -v17, v89, v31
	v_fmac_f32_e32 v89, v92, v30
	v_fma_f32 v17, -v17, v89, v31
	v_div_fmas_f32 v17, v17, v30, v89
	v_div_fixup_f32 v25, v17, v25, 1.0
	v_div_scale_f32 v17, s[0:1], v24, v24, 1.0
	v_rcp_f32_e32 v30, v17
	v_pk_mul_f32 v[20:21], v[76:77], v[20:21] op_sel:[1,0] op_sel_hi:[0,1]
	v_pk_fma_f32 v[20:21], v[76:77], v[84:85], v[20:21]
	v_fma_f32 v31, -v17, v30, 1.0
	v_fmac_f32_e32 v30, v31, v30
	v_div_scale_f32 v31, vcc, 1.0, v24, 1.0
	v_mul_f32_e32 v89, v31, v30
	v_fma_f32 v92, -v17, v89, v31
	v_fmac_f32_e32 v89, v92, v30
	v_fma_f32 v17, -v17, v89, v31
	v_div_fmas_f32 v17, v17, v30, v89
	v_div_fixup_f32 v24, v17, v24, 1.0
	v_mul_f32_e32 v17, 0xbfb8aa3b, v88
	v_exp_f32_e32 v17, v17
	s_nop 0
	v_pk_add_f32 v[16:17], v[16:17], 1.0 op_sel_hi:[1,0]
	s_nop 0
	v_div_scale_f32 v30, s[0:1], v17, v17, v88
	v_rcp_f32_e32 v31, v30
	s_nop 0
	v_fma_f32 v89, -v30, v31, 1.0
	v_fmac_f32_e32 v31, v89, v31
	v_div_scale_f32 v89, vcc, v88, v17, v88
	v_mul_f32_e32 v92, v89, v31
	v_fma_f32 v93, -v30, v92, v89
	v_fmac_f32_e32 v92, v93, v31
	v_fma_f32 v30, -v30, v92, v89
	v_div_fmas_f32 v30, v30, v31, v92
	v_div_fixup_f32 v17, v30, v17, v88
	v_div_scale_f32 v30, s[0:1], v16, v16, v75
	v_rcp_f32_e32 v31, v30
	s_nop 0
	v_fma_f32 v88, -v30, v31, 1.0
	v_fmac_f32_e32 v31, v88, v31
	v_div_scale_f32 v88, vcc, v75, v16, v75
	v_mul_f32_e32 v89, v88, v31
	v_fma_f32 v92, -v30, v89, v88
	v_fmac_f32_e32 v89, v92, v31
	v_fma_f32 v30, -v30, v89, v88
	v_div_fmas_f32 v30, v30, v31, v89
	v_div_fixup_f32 v16, v30, v16, v75
	v_add_f32_e32 v30, 0, v20
	v_add_f32_e32 v30, v21, v30
	v_add_f32_e32 v30, v80, v30
	v_add_f32_e32 v30, v81, v30
	v_add_f32_e32 v30, v22, v30
	v_add_f32_e32 v30, v23, v30
	v_add_f32_e32 v30, v82, v30
	v_add_f32_e32 v30, v83, v30
	ds_bpermute_b32 v31, v70, v30
	v_mov_b32_e32 v89, v66
	s_waitcnt lgkmcnt(0)
	v_add_f32_e32 v30, v30, v31
	ds_bpermute_b32 v31, v71, v30
	s_waitcnt lgkmcnt(0)
	v_add_f32_e32 v30, v30, v31
	ds_bpermute_b32 v31, v72, v30
	s_waitcnt lgkmcnt(0)
	v_add_f32_e32 v30, v30, v31
	ds_bpermute_b32 v31, v73, v30
	s_waitcnt lgkmcnt(0)
	v_add_f32_e32 v30, v30, v31
	ds_bpermute_b32 v31, v74, v30
	s_waitcnt lgkmcnt(0)
	v_add_f32_e32 v30, v30, v31
	v_mul_f32_e32 v30, 0x3b800000, v30
	v_pk_add_f32 v[76:77], v[20:21], v[30:31] op_sel_hi:[1,0] neg_lo:[0,1] neg_hi:[0,1]
	v_pk_add_f32 v[80:81], v[80:81], v[30:31] op_sel_hi:[1,0] neg_lo:[0,1] neg_hi:[0,1]
	v_mul_f32_e32 v20, v77, v77
	v_pk_fma_f32 v[20:21], v[76:77], v[76:77], v[20:21] op_sel_hi:[1,1,0]
	v_pk_mul_f32 v[84:85], v[80:81], v[80:81]
	v_mov_b32_e32 v21, v67
	v_mov_b32_e32 v88, v84
	v_pk_add_f32 v[20:21], v[88:89], v[20:21]
	v_pk_mov_b32 v[66:67], v[84:85], v[64:65] op_sel:[1,0]
	s_nop 0
	v_pk_add_f32 v[20:21], v[66:67], v[20:21]
	v_pk_add_f32 v[66:67], v[22:23], v[30:31] op_sel_hi:[1,0] neg_lo:[0,1] neg_hi:[0,1]
	v_pk_add_f32 v[30:31], v[82:83], v[30:31] op_sel_hi:[1,0] neg_lo:[0,1] neg_hi:[0,1]
	v_pk_mul_f32 v[22:23], v[66:67], v[66:67]
	v_pk_mul_f32 v[82:83], v[30:31], v[30:31]
	v_mov_b32_e32 v64, v22
	v_pk_add_f32 v[20:21], v[64:65], v[20:21]
	v_pk_mov_b32 v[22:23], v[22:23], v[42:43] op_sel:[1,0]
	v_mov_b32_e32 v42, v82
	v_pk_add_f32 v[20:21], v[22:23], v[20:21]
	v_pk_mov_b32 v[22:23], v[82:83], v[58:59] op_sel:[1,0]
	v_pk_add_f32 v[20:21], v[42:43], v[20:21]
	s_nop 0
	v_pk_add_f32 v[20:21], v[22:23], v[20:21]
	ds_bpermute_b32 v58, v70, v20
	s_waitcnt lgkmcnt(0)
	v_pk_add_f32 v[20:21], v[20:21], v[58:59]
	ds_bpermute_b32 v23, v70, v21
	ds_bpermute_b32 v22, v71, v20
	s_waitcnt lgkmcnt(0)
	v_pk_add_f32 v[20:21], v[20:21], v[22:23]
	ds_bpermute_b32 v23, v71, v21
	ds_bpermute_b32 v22, v72, v20
	s_waitcnt lgkmcnt(0)
	v_pk_add_f32 v[20:21], v[20:21], v[22:23]
	ds_bpermute_b32 v23, v72, v21
	ds_bpermute_b32 v22, v73, v20
	s_waitcnt lgkmcnt(0)
	v_pk_add_f32 v[20:21], v[20:21], v[22:23]
	ds_bpermute_b32 v23, v73, v21
	ds_bpermute_b32 v22, v74, v20
	s_waitcnt lgkmcnt(0)
; DI bf16x8 pack8f(const float* v) { u32x4 w = {cvtpk(v[0], v[1]), cvtpk(v[2], v[3]), cvtpk(v[4], v[5]), cvtpk(v[6], v[7])}; return __builtin_bit_cast(bf16x8, w); }
; DI float silu(float v) { return v / (1.f + __expf(-v)); }
; DI float sigm(float v) { return 1.f / (1.f + __expf(-v)); }
; DI void phase_comb0(const Params& p, char* smem) {
;     ...
;       const float rms = rsqrtf(ss * (1.f / 128.f) + EPS) * 0.8f;
;       for (int j = 0; j < 8; ++j) o[j] = o1[j] * rms * gd[j] * silu(gt[j]);
;       st8(mix + (long)i * 4096 + c0, pack8f(o));
;     ...
;       const float rstd = rsqrtf(sq * (1.f / 256.f) + EPS);
;       for (int j = 0; j < 8; ++j) o[j] = h0[j] * rstd * gm[j] * sigm(ov[j]) * silu(gt[j]);
;       st8(mix + (long)i * 4096 + 2048 + c0, pack8f(o));
	v_pk_add_f32 v[20:21], v[20:21], v[22:23]
	s_nop 0
	v_pk_fma_f32 v[42:43], v[20:21], s[24:25], v[190:191] op_sel_hi:[1,1,0]
	s_nop 0
	v_mul_f32_e32 v20, 0x4b800000, v43
	v_cmp_gt_f32_e64 s[0:1], s23, v43
	v_cmp_gt_f32_e32 vcc, s23, v42
	s_nop 0
	v_cndmask_b32_e64 v20, v43, v20, s[0:1]
	v_rsq_f32_e32 v20, v20
	s_nop 0
	v_mul_f32_e32 v21, 0x45800000, v20
	v_cndmask_b32_e64 v20, v20, v21, s[0:1]
	v_mul_f32_e32 v20, 0x3f4ccccd, v20
	v_pk_mul_f32 v[22:23], v[32:33], v[20:21] op_sel_hi:[1,0]
	v_pk_mul_f32 v[32:33], v[60:61], v[20:21] op_sel_hi:[1,0]
	v_pk_mul_f32 v[34:35], v[34:35], v[20:21] op_sel_hi:[1,0]
	v_pk_mul_f32 v[20:21], v[56:57], v[20:21] op_sel_hi:[1,0]
	v_pk_mul_f32 v[22:23], v[0:1], v[22:23]
	v_pk_mul_f32 v[32:33], v[2:3], v[32:33]
	v_pk_mul_f32 v[34:35], v[4:5], v[34:35]
	v_pk_mul_f32 v[20:21], v[6:7], v[20:21]
	v_pk_mul_f32 v[22:23], v[36:37], v[22:23]
	v_pk_mul_f32 v[32:33], v[62:63], v[32:33]
	v_pk_mul_f32 v[34:35], v[38:39], v[34:35]
	v_pk_mul_f32 v[36:37], v[40:41], v[20:21]
	v_cvt_pk_bf16_f32 v20, v22, v23
	v_cvt_pk_bf16_f32 v21, v32, v33
	v_cvt_pk_bf16_f32 v22, v34, v35
	v_cvt_pk_bf16_f32 v23, v36, v37
	global_store_dwordx4 v[68:69], v[20:23], off
	s_nop 1
	v_mul_f32_e32 v20, 0x4b800000, v42
	v_cndmask_b32_e32 v20, v42, v20, vcc
	v_rsq_f32_e32 v20, v20
	s_nop 0
	v_mul_f32_e32 v21, 0x45800000, v20
	v_cndmask_b32_e32 v20, v20, v21, vcc
	v_pk_mul_f32 v[22:23], v[76:77], v[20:21] op_sel_hi:[1,0]
	s_nop 0
	v_pk_mul_f32 v[22:23], v[8:9], v[22:23]
	s_nop 0
	v_pk_mul_f32 v[22:23], v[24:25], v[22:23]
	v_pk_mul_f32 v[24:25], v[66:67], v[20:21] op_sel_hi:[1,0]
	v_pk_mul_f32 v[16:17], v[16:17], v[22:23]
	v_pk_mul_f32 v[24:25], v[12:13], v[24:25]
	v_pk_mul_f32 v[22:23], v[80:81], v[20:21] op_sel_hi:[1,0]
	v_pk_mul_f32 v[18:19], v[18:19], v[24:25]
	v_mul_f32_e32 v21, 0xbfb8aa3b, v90
	v_pk_mul_f32 v[18:19], v[26:27], v[18:19]
	v_pk_add_f32 v[26:27], v[28:29], 1.0 op_sel_hi:[1,0]
	v_exp_f32_e32 v24, v21
	v_div_scale_f32 v25, s[0:1], v27, v27, 1.0
	v_rcp_f32_e32 v28, v25
	v_pk_mul_f32 v[20:21], v[30:31], v[20:21] op_sel_hi:[1,0]
	v_pk_mul_f32 v[22:23], v[10:11], v[22:23]
	v_pk_mul_f32 v[20:21], v[14:15], v[20:21]
	v_fma_f32 v29, -v25, v28, 1.0
	v_fmac_f32_e32 v28, v29, v28
	v_div_scale_f32 v29, vcc, 1.0, v27, 1.0
	v_mul_f32_e32 v30, v29, v28
	v_fma_f32 v31, -v25, v30, v29
	v_fmac_f32_e32 v30, v31, v28
	v_fma_f32 v25, -v25, v30, v29
	v_div_fmas_f32 v25, v25, v28, v30
	v_div_fixup_f32 v27, v25, v27, 1.0
	v_div_scale_f32 v25, s[0:1], v26, v26, 1.0
	v_rcp_f32_e32 v28, v25
	v_pk_mul_f32 v[22:23], v[78:79], v[22:23]
	v_cvt_pk_bf16_f32 v18, v18, v19
	v_pk_mul_f32 v[22:23], v[86:87], v[22:23]
	v_fma_f32 v29, -v25, v28, 1.0
	v_fmac_f32_e32 v28, v29, v28
	v_div_scale_f32 v29, vcc, 1.0, v26, 1.0
	v_mul_f32_e32 v30, v29, v28
	v_fma_f32 v31, -v25, v30, v29
	v_fmac_f32_e32 v30, v31, v28
	v_fma_f32 v25, -v25, v30, v29
	v_div_fmas_f32 v25, v25, v28, v30
	v_div_fixup_f32 v26, v25, v26, 1.0
	v_mul_f32_e32 v25, 0xbfb8aa3b, v91
	v_exp_f32_e32 v25, v25
	v_pk_mul_f32 v[20:21], v[26:27], v[20:21]
	v_cvt_pk_bf16_f32 v16, v16, v17
	v_cvt_pk_bf16_f32 v17, v22, v23
	v_pk_add_f32 v[24:25], v[24:25], 1.0 op_sel_hi:[1,0]
	s_nop 0
	v_div_scale_f32 v26, s[0:1], v25, v25, v91
	v_rcp_f32_e32 v27, v26
	s_nop 0
	v_fma_f32 v28, -v26, v27, 1.0
	v_fmac_f32_e32 v27, v28, v27
	v_div_scale_f32 v28, vcc, v91, v25, v91
	v_mul_f32_e32 v29, v28, v27
	v_fma_f32 v30, -v26, v29, v28
	v_fmac_f32_e32 v29, v30, v27
	v_fma_f32 v26, -v26, v29, v28
	v_div_fmas_f32 v26, v26, v27, v29
	v_div_fixup_f32 v25, v26, v25, v91
	v_div_scale_f32 v26, s[0:1], v24, v24, v90
	v_rcp_f32_e32 v27, v26
	s_nop 0
	v_fma_f32 v28, -v26, v27, 1.0
	v_fmac_f32_e32 v27, v28, v27
	v_div_scale_f32 v28, vcc, v90, v24, v90
	v_mul_f32_e32 v29, v28, v27
	v_fma_f32 v30, -v26, v29, v28
	v_fmac_f32_e32 v29, v30, v27
	v_fma_f32 v26, -v26, v29, v28
	v_div_fmas_f32 v26, v26, v27, v29
	v_div_fixup_f32 v24, v26, v24, v90
	v_pk_mul_f32 v[20:21], v[24:25], v[20:21]
	s_nop 0
	v_cvt_pk_bf16_f32 v19, v20, v21
	v_add_co_u32_e32 v20, vcc, 0x1000, v68
	s_nop 1
	v_addc_co_u32_e32 v21, vcc, 0, v69, vcc
	global_store_dwordx4 v[20:21], v[16:19], off
	s_cbranch_scc1 .LBB0_821

;   DI const float* x() const { return (const float*)sp[0]; }
;   DI const float* ctx() const { return (const float*)sp[2]; }
;   DI const float* ln_g() const { return (const float*)sp[6]; }
;   DI const float* ln_b() const { return (const float*)sp[7]; }
; DI unsigned cvtpk(float lo, float hi) { f32x2_t v = {lo, hi}; bf16x2_t b = __builtin_convertvector(v, bf16x2_t); return __builtin_bit_cast(unsigned, b); }
; DI void phase_mod(const Params& p, int g, int layer, char* smem) {
;     ...
;   for (int i = blockIdx.x * 4 + w; i < MG; i += gridDim.x * 4) {
;     const long r = (long)g * MG + i; const int b = (int)(r / T), t = (int)(r % T);
;     float v[32];
;     if (layer == 0) {
;       const float* s = t < CTX ? p.ctx() + ((long)b * CTX + t) * DM : p.x() + ((long)b * SEQ + (t - CTX)) * DM;
; #pragma unroll
;       for (int j = 0; j < 8; ++j) { const f32x4 a = *(const f32x4*)(s + lane * 4 + 256 * j); v[4 * j] = a[0]; v[4 * j + 1] = a[1]; v[4 * j + 2] = a[2]; v[4 * j + 3] = a[3]; }
;     } else {
;       float* s = P_ZX + r * DM;
; #pragma unroll
;       for (int j = 0; j < 8; ++j) { const f32x4 a = *(const f32x4*)(s + lane * 4 + 256 * j); v[4 * j] = a[0]; v[4 * j + 1] = a[1]; v[4 * j + 2] = a[2]; v[4 * j + 3] = a[3]; }
;       row_ln(v, p.ln_g(), p.ln_b(), lane);
; #pragma unroll
;       for (int j = 0; j < 8; ++j) { const f32x4 o = {v[4 * j], v[4 * j + 1], v[4 * j + 2], v[4 * j + 3]}; *(f32x4*)(s + lane * 4 + 256 * j) = o; }
;     }
;     const float* md = P_MOD + ((long)layer * 9 + (t < CTX ? 8 : b)) * 6144;
; #pragma unroll
;     for (int j = 0; j < 8; ++j) {
;       const f32x4 sh = *(const f32x4*)(md + lane * 4 + 256 * j), sc = *(const f32x4*)(md + 2048 + lane * 4 + 256 * j);
;       u32x2 o = {cvtpk(v[4 * j] * (1.f + sc[0]) + sh[0], v[4 * j + 1] * (1.f + sc[1]) + sh[1]), cvtpk(v[4 * j + 2] * (1.f + sc[2]) + sh[2], v[4 * j + 3] * (1.f + sc[3]) + sh[3])};
;       *reinterpret_cast<u32x2*>(h + (long)i * DM + lane * 4 + 256 * j) = o;
;     }
.LBB0_825:
	s_or_b64 exec, exec, s[2:3]
	ds_read_b64 v[2:3], v6
	v_lshlrev_b64 v[0:1], 13, v[0:1]
	v_mov_b32_e32 v29, v129
	v_readlane_b32 s2, v254, 23
	v_readlane_b32 s3, v254, 24
	s_waitcnt lgkmcnt(0)
	v_lshl_add_u64 v[0:1], v[2:3], 0, v[0:1]
	v_lshl_add_u64 v[0:1], v[0:1], 0, v[28:29]
	global_load_dwordx4 v[34:37], v[0:1], off
	global_load_dwordx4 v[38:41], v[0:1], off offset:1024
	global_load_dwordx4 v[20:23], v[0:1], off offset:2048
	global_load_dwordx4 v[16:19], v[0:1], off offset:3072
	v_add_co_u32_e32 v0, vcc, 0x1000, v0
	v_lshl_add_u64 v[30:31], s[2:3], 0, v[30:31]
	s_nop 0
	v_addc_co_u32_e32 v1, vcc, 0, v1, vcc
	v_lshl_add_u64 v[50:51], v[30:31], 0, v[28:29]
	s_movk_i32 s2, 0x3000
	v_add_co_u32_e32 v32, vcc, s2, v50
	global_load_dwordx4 v[12:15], v[0:1], off
	global_load_dwordx4 v[8:11], v[0:1], off offset:1024
	global_load_dwordx4 v[4:7], v[0:1], off offset:2048
	s_nop 0
	global_load_dwordx4 v[0:3], v[0:1], off offset:3072
	v_addc_co_u32_e32 v33, vcc, 0, v51, vcc
	global_load_dwordx4 v[42:45], v[50:51], off
	global_load_dwordx4 v[46:49], v[32:33], off offset:-4096
	v_lshlrev_b64 v[30:31], 12, v[24:25]
	v_lshl_add_u64 v[30:31], v[26:27], 0, v[30:31]
	v_lshl_add_u64 v[52:53], v[50:51], 0, s[90:91]
	s_movk_i32 s2, 0x1000
	v_add_u32_e32 v24, s80, v24
	s_waitcnt vmcnt(0)
	v_pk_add_f32 v[46:47], v[46:47], 1.0 op_sel_hi:[1,0]
	s_waitcnt lgkmcnt(0)
	v_pk_fma_f32 v[34:35], v[34:35], v[46:47], v[42:43]
	v_pk_add_f32 v[42:43], v[48:49], 1.0 op_sel_hi:[1,0]
	v_cvt_pk_bf16_f32 v34, v34, v35
	v_pk_fma_f32 v[36:37], v[36:37], v[42:43], v[44:45]
	s_nop 0
	v_cvt_pk_bf16_f32 v35, v36, v37
	global_store_dwordx2 v[30:31], v[34:35], off
	global_load_dwordx4 v[34:37], v[50:51], off offset:1024
	s_nop 0
	global_load_dwordx4 v[42:45], v[52:53], off offset:1024
	s_waitcnt vmcnt(0)
	v_pk_add_f32 v[42:43], v[42:43], 1.0 op_sel_hi:[1,0]
	s_nop 0
	v_pk_fma_f32 v[34:35], v[38:39], v[42:43], v[34:35]
	v_pk_add_f32 v[38:39], v[44:45], 1.0 op_sel_hi:[1,0]
	v_cvt_pk_bf16_f32 v34, v34, v35
	v_pk_fma_f32 v[36:37], v[40:41], v[38:39], v[36:37]
	s_nop 0
	v_cvt_pk_bf16_f32 v35, v36, v37
	global_store_dwordx2 v[30:31], v[34:35], off offset:512
	global_load_dwordx4 v[34:37], v[50:51], off offset:2048
	s_nop 0
	global_load_dwordx4 v[38:41], v[52:53], off offset:2048
	s_waitcnt vmcnt(0)
	v_pk_add_f32 v[38:39], v[38:39], 1.0 op_sel_hi:[1,0]
	s_nop 0
	v_pk_fma_f32 v[20:21], v[20:21], v[38:39], v[34:35]
	v_pk_add_f32 v[34:35], v[40:41], 1.0 op_sel_hi:[1,0]
	v_cvt_pk_bf16_f32 v20, v20, v21
	v_pk_fma_f32 v[22:23], v[22:23], v[34:35], v[36:37]
	s_nop 0
	v_cvt_pk_bf16_f32 v21, v22, v23
	global_store_dwordx2 v[30:31], v[20:21], off offset:1024
	global_load_dwordx4 v[20:23], v[50:51], off offset:3072
	s_nop 0
	global_load_dwordx4 v[34:37], v[52:53], off offset:3072
	s_waitcnt vmcnt(0)
	v_pk_add_f32 v[34:35], v[34:35], 1.0 op_sel_hi:[1,0]
	s_nop 0
	v_pk_fma_f32 v[16:17], v[16:17], v[34:35], v[20:21]
	v_pk_add_f32 v[20:21], v[36:37], 1.0 op_sel_hi:[1,0]
	v_cvt_pk_bf16_f32 v16, v16, v17
	v_pk_fma_f32 v[18:19], v[18:19], v[20:21], v[22:23]
	v_add_co_u32_e32 v34, vcc, s2, v50
	v_cvt_pk_bf16_f32 v17, v18, v19
	global_store_dwordx2 v[30:31], v[16:17], off offset:1536
	v_addc_co_u32_e32 v35, vcc, 0, v51, vcc
	global_load_dwordx4 v[16:19], v[34:35], off
	global_load_dwordx4 v[20:23], v[32:33], off
	s_movk_i32 s2, 0x11ff
	v_cmp_lt_i32_e32 vcc, s2, v24
	s_or_b64 s[6:7], vcc, s[6:7]
	s_waitcnt vmcnt(0)
	v_pk_add_f32 v[20:21], v[20:21], 1.0 op_sel_hi:[1,0]
	s_nop 0
	v_pk_fma_f32 v[12:13], v[12:13], v[20:21], v[16:17]
	v_pk_add_f32 v[16:17], v[22:23], 1.0 op_sel_hi:[1,0]
	v_cvt_pk_bf16_f32 v12, v12, v13
	v_pk_fma_f32 v[14:15], v[14:15], v[16:17], v[18:19]
	s_nop 0
	v_cvt_pk_bf16_f32 v13, v14, v15
	global_store_dwordx2 v[30:31], v[12:13], off offset:2048
	global_load_dwordx4 v[12:15], v[34:35], off offset:1024
	s_nop 0
	global_load_dwordx4 v[16:19], v[32:33], off offset:1024
	s_waitcnt vmcnt(0)
	v_pk_add_f32 v[16:17], v[16:17], 1.0 op_sel_hi:[1,0]
	s_nop 0
	v_pk_fma_f32 v[8:9], v[8:9], v[16:17], v[12:13]
	v_pk_add_f32 v[12:13], v[18:19], 1.0 op_sel_hi:[1,0]
	v_cvt_pk_bf16_f32 v8, v8, v9
	v_pk_fma_f32 v[10:11], v[10:11], v[12:13], v[14:15]
	s_nop 0
	v_cvt_pk_bf16_f32 v9, v10, v11
	global_store_dwordx2 v[30:31], v[8:9], off offset:2560
	global_load_dwordx4 v[8:11], v[34:35], off offset:2048
	s_nop 0
	global_load_dwordx4 v[12:15], v[32:33], off offset:2048
	s_waitcnt vmcnt(0)
	v_pk_add_f32 v[12:13], v[12:13], 1.0 op_sel_hi:[1,0]
	s_nop 0
	v_pk_fma_f32 v[4:5], v[4:5], v[12:13], v[8:9]
	v_pk_add_f32 v[8:9], v[14:15], 1.0 op_sel_hi:[1,0]
	v_cvt_pk_bf16_f32 v4, v4, v5
	v_pk_fma_f32 v[6:7], v[6:7], v[8:9], v[10:11]
	s_nop 0
	v_cvt_pk_bf16_f32 v5, v6, v7
	global_store_dwordx2 v[30:31], v[4:5], off offset:3072
	global_load_dwordx4 v[4:7], v[34:35], off offset:3072
	s_nop 0
	global_load_dwordx4 v[8:11], v[32:33], off offset:3072
	s_waitcnt vmcnt(0)
	v_pk_add_f32 v[8:9], v[8:9], 1.0 op_sel_hi:[1,0]
	s_nop 0
	v_pk_fma_f32 v[0:1], v[0:1], v[8:9], v[4:5]
	v_pk_add_f32 v[4:5], v[10:11], 1.0 op_sel_hi:[1,0]
	v_cvt_pk_bf16_f32 v0, v0, v1
	v_pk_fma_f32 v[2:3], v[2:3], v[4:5], v[6:7]
	s_nop 0
	v_cvt_pk_bf16_f32 v1, v2, v3
	global_store_dwordx2 v[30:31], v[0:1], off offset:3584
	s_andn2_b64 exec, exec, s[6:7]
	s_cbranch_execz .LBB0_830

;   DI const float* x() const { return (const float*)sp[0]; }
;   DI const float* c() const { return (const float*)sp[1]; }
; __device__ __forceinline__ unsigned xb_ld(unsigned* p)              { return __hip_atomic_load(p, __ATOMIC_RELAXED, __HIP_MEMORY_SCOPE_AGENT); }
; __device__ __forceinline__ void xcd_barrier_complete(unsigned* bar, unsigned x, unsigned& nloc, unsigned& nx) {
;     const unsigned G = gridDim.x * gridDim.y * gridDim.z;
;     unsigned sum, cnt, mine, sp = 0u;
;     for (;;) {
;         sum = 0u; cnt = 0u; mine = 0u;
; #pragma unroll
;         for (unsigned j = 0; j < 16; ++j) { const unsigned c = xb_ld(&bar[XB_XCNT(j)]); sum += c; cnt += (c > 0u) ? 1u : 0u; mine = (j == x) ? c : mine; }
;         if (sum == G) break;
;         __builtin_amdgcn_s_sleep(1);
;         if ((++sp & 255u) == 0u) { if (xb_ld(&bar[XB_TMO])) break; if (sp > XB_SPIN_CAP) { atomicAdd(&bar[XB_TMO], 1u); break; } }
;     }
.LBB0_836:
	s_waitcnt lgkmcnt(0)
	v_mov_b64_e32 v[0:1], s[6:7]
	v_mov_b64_e32 v[2:3], s[8:9]
	global_load_dword v0, v[0:1], off sc1
	v_readlane_b32 s2, v254, 15
	global_load_dword v1, v[2:3], off sc1
	v_mov_b64_e32 v[2:3], s[10:11]
	global_load_dword v2, v[2:3], off sc1
	s_or_b64 s[52:53], s[52:53], exec
	s_or_b64 s[50:51], s[50:51], exec
	s_waitcnt vmcnt(0) lgkmcnt(0)
	v_add_u32_e32 v4, v1, v0
	v_add_u32_e32 v6, v4, v2
	v_mov_b64_e32 v[4:5], s[12:13]
	global_load_dword v3, v[4:5], off sc1
	v_mov_b64_e32 v[4:5], s[14:15]
	global_load_dword v4, v[4:5], off sc1
	s_waitcnt vmcnt(0) lgkmcnt(0)
	v_add_u32_e32 v6, v6, v3
	v_add_u32_e32 v8, v6, v4
	v_mov_b64_e32 v[6:7], s[16:17]
	global_load_dword v5, v[6:7], off sc1
	v_mov_b64_e32 v[6:7], s[18:19]
	global_load_dword v6, v[6:7], off sc1
	s_waitcnt vmcnt(0) lgkmcnt(0)
	v_add_u32_e32 v8, v8, v5
	v_add_u32_e32 v10, v8, v6
	v_mov_b64_e32 v[8:9], s[20:21]
	global_load_dword v7, v[8:9], off sc1
	v_mov_b64_e32 v[8:9], s[22:23]
	global_load_dword v8, v[8:9], off sc1
	s_waitcnt vmcnt(0) lgkmcnt(0)
	v_add_u32_e32 v10, v10, v7
	v_add_u32_e32 v12, v10, v8
	v_mov_b64_e32 v[10:11], s[24:25]
	global_load_dword v9, v[10:11], off sc1
	v_mov_b64_e32 v[10:11], s[26:27]
	global_load_dword v10, v[10:11], off sc1
	s_waitcnt vmcnt(0) lgkmcnt(0)
	v_add_u32_e32 v12, v12, v9
	v_add_u32_e32 v14, v12, v10
	v_mov_b64_e32 v[12:13], s[28:29]
	global_load_dword v11, v[12:13], off sc1
	v_mov_b64_e32 v[12:13], s[30:31]
	global_load_dword v12, v[12:13], off sc1
	s_waitcnt vmcnt(0) lgkmcnt(0)
	v_add_u32_e32 v14, v14, v11
	v_add_u32_e32 v16, v14, v12
	v_mov_b64_e32 v[14:15], s[34:35]
	global_load_dword v13, v[14:15], off sc1
	v_mov_b64_e32 v[14:15], s[42:43]
	global_load_dword v14, v[14:15], off sc1
	s_waitcnt vmcnt(0) lgkmcnt(0)
	v_add_u32_e32 v16, v16, v13
	v_add_u32_e32 v18, v16, v14
	v_mov_b64_e32 v[16:17], s[44:45]
	global_load_dword v15, v[16:17], off sc1
	s_waitcnt vmcnt(0) lgkmcnt(0)
	v_add_u32_e32 v16, v18, v15
	v_cmp_ne_u32_e32 vcc, s2, v16
	s_and_saveexec_b64 s[2:3], vcc
	s_cbranch_execz .LBB0_835
	s_and_b32 s62, s78, 0xff
	s_mov_b64 s[54:55], -1
	s_cmp_eq_u32 s62, 0
	s_mov_b64 s[70:71], -1
	s_mov_b64 s[68:69], -1
	s_sleep 1
	s_cbranch_scc1 .LBB0_839
	s_and_saveexec_b64 s[62:63], s[70:71]
	s_cbranch_execz .LBB0_834
	s_branch .LBB0_842
.LBB0_839:
	v_mov_b64_e32 v[16:17], s[0:1]
	global_load_dword v16, v[16:17], off sc1
	s_mov_b64 s[70:71], 0
	s_waitcnt vmcnt(0) lgkmcnt(0)
	v_cmp_eq_u32_e32 vcc, 0, v16
	s_and_saveexec_b64 s[74:75], vcc
	s_cmp_lt_u32 s78, 0x40001
	s_cselect_b64 s[62:63], -1, 0
	s_xor_b64 s[68:69], exec, -1
	s_and_b64 s[70:71], s[62:63], exec
	s_or_b64 exec, exec, s[74:75]
	s_and_saveexec_b64 s[62:63], s[70:71]
	s_cbranch_execz .LBB0_834

; __device__ __forceinline__ unsigned xb_ld(unsigned* p)              { return __hip_atomic_load(p, __ATOMIC_RELAXED, __HIP_MEMORY_SCOPE_AGENT); }
; __device__ __forceinline__ void xcd_barrier_complete(unsigned* bar, unsigned x, unsigned& nloc, unsigned& nx) {
;     ...
;         if (sum == G) break;
;         __builtin_amdgcn_s_sleep(1);
;         if ((++sp & 255u) == 0u) { if (xb_ld(&bar[XB_TMO])) break; if (sp > XB_SPIN_CAP) { atomicAdd(&bar[XB_TMO], 1u); break; } }
;     }
;     nloc = mine > 0u ? mine : 1u; nx = cnt > 0u ? cnt : 1u;
.LBB0_843:
	s_or_b64 exec, exec, s[46:47]
	s_xor_b64 s[2:3], s[48:49], -1
	s_and_saveexec_b64 s[6:7], s[2:3]
	s_xor_b64 s[2:3], exec, s[6:7]
	s_cbranch_execz .LBB0_845
	v_mov_b64_e32 v[16:17], s[0:1]
	global_atomic_add v[16:17], v208, off

;   DI const float* x() const { return (const float*)sp[0]; }
; __device__ __forceinline__ unsigned xb_ld(unsigned* p)              { return __hip_atomic_load(p, __ATOMIC_RELAXED, __HIP_MEMORY_SCOPE_AGENT); }
; __device__ __forceinline__ unsigned xb_add(unsigned* p, unsigned v) { return __hip_atomic_fetch_add(p, v, __ATOMIC_RELAXED, __HIP_MEMORY_SCOPE_AGENT); }
; #define XB_SPIN(cond, bar) do { unsigned _sp = 0; while (cond) { __builtin_amdgcn_s_sleep(1); \
;     if ((++_sp & 255u) == 0u) { if (xb_ld(&(bar)[XB_TMO])) break; if (_sp > XB_SPIN_CAP) { atomicAdd(&(bar)[XB_TMO], 1u); break; } } } } while (0)
; __device__ __forceinline__ void xcd_barrier(const XcdBarrier& b) {
;     ...
;         const unsigned old = xb_add(&bar[XB_XSUB(b.x)], 1u);
;         const unsigned gen = old / nloc;
;         if (old + 1u == (gen + 1u) * nloc) {
;             __builtin_amdgcn_fence(__ATOMIC_RELEASE, "agent");
;             asm volatile("s_waitcnt vmcnt(0)" ::: "memory");
;             const unsigned og = xb_add(&bar[XB_TOP], 1u);
;             const unsigned tg = og / nx;
;             if (og + 1u == (tg + 1u) * nx) xb_add(&bar[XB_TOPGEN], 1u);
;             else XB_SPIN(xb_ld(&bar[XB_TOPGEN]) == tg, bar);
;             __builtin_amdgcn_fence(__ATOMIC_ACQUIRE, "agent");
;             xb_add(&bar[XB_XGEN(b.x)], 1u);
;             asm volatile("s_waitcnt vmcnt(0)" ::: "memory");
;         } else {
;             XB_SPIN(xb_ld(&bar[XB_XGEN(b.x)]) == gen, bar);
.LBB0_846:
	s_add_u32 s24, s40, 0xe36d000
	s_addc_u32 s25, s41, 0
	s_lshl_b32 s26, s76, 6
	s_add_i32 s76, s26, 0x500
	s_lshl_b64 s[0:1], s[76:77], 2
	s_add_u32 s0, s24, s0
	s_addc_u32 s1, s25, s1
	v_mov_b64_e32 v[4:5], s[0:1]
	global_atomic_add v3, v[4:5], v208, off sc0
	v_cvt_f32_u32_e32 v1, v2
	v_sub_u32_e32 v4, 0, v2
	v_rcp_iflag_f32_e32 v1, v1
	s_nop 0
	v_mul_f32_e32 v1, 0x4f7ffffe, v1
	v_cvt_u32_f32_e32 v1, v1
	v_mul_lo_u32 v4, v4, v1
	v_mul_hi_u32 v4, v1, v4
	v_add_u32_e32 v1, v1, v4
	s_waitcnt vmcnt(0) lgkmcnt(0)
	v_mul_hi_u32 v1, v3, v1
	v_mul_lo_u32 v4, v1, v2
	v_sub_u32_e32 v4, v3, v4
	v_cmp_ge_u32_e32 vcc, v4, v2
	v_add_u32_e32 v5, 1, v1
	s_nop 0
	v_cndmask_b32_e32 v1, v1, v5, vcc
	v_sub_u32_e32 v5, v4, v2
	v_cndmask_b32_e32 v4, v4, v5, vcc
	v_cmp_ge_u32_e32 vcc, v4, v2
	v_add_u32_e32 v4, 1, v1
	s_nop 0
	v_cndmask_b32_e32 v1, v1, v4, vcc
	v_add_u32_e32 v4, 1, v3
	v_mad_u64_u32 v[2:3], s[0:1], v2, v1, v[2:3]
	v_cmp_ne_u32_e32 vcc, v4, v2
	s_and_saveexec_b64 s[0:1], vcc
	s_xor_b64 s[0:1], exec, s[0:1]
	s_cbranch_execz .LBB0_859
	s_add_i32 s76, s26, 0x900
	s_lshl_b64 s[2:3], s[76:77], 2
	s_add_u32 s6, s24, s2
	s_addc_u32 s7, s25, s3
	v_mov_b64_e32 v[2:3], s[6:7]
	global_load_dword v0, v[2:3], off sc1
	s_waitcnt vmcnt(0) lgkmcnt(0)
	v_cmp_eq_u32_e32 vcc, v0, v1
	s_and_saveexec_b64 s[2:3], vcc
	s_cbranch_execz .LBB0_858
	s_add_u32 s8, s40, 0xe36d200
	s_addc_u32 s9, s41, 0
	s_mov_b32 s27, 1
	s_mov_b64 s[10:11], 0
	s_branch .LBB0_850

; __device__ __forceinline__ unsigned xb_ld(unsigned* p)              { return __hip_atomic_load(p, __ATOMIC_RELAXED, __HIP_MEMORY_SCOPE_AGENT); }
; __device__ __forceinline__ unsigned xb_add(unsigned* p, unsigned v) { return __hip_atomic_fetch_add(p, v, __ATOMIC_RELAXED, __HIP_MEMORY_SCOPE_AGENT); }
; #define XB_SPIN(cond, bar) do { unsigned _sp = 0; while (cond) { __builtin_amdgcn_s_sleep(1); \
;     if ((++_sp & 255u) == 0u) { if (xb_ld(&(bar)[XB_TMO])) break; if (_sp > XB_SPIN_CAP) { atomicAdd(&(bar)[XB_TMO], 1u); break; } } } } while (0)
; __device__ __forceinline__ void xcd_barrier(const XcdBarrier& b) {
;     ...
;         if (old + 1u == (gen + 1u) * nloc) {
;             __builtin_amdgcn_fence(__ATOMIC_RELEASE, "agent");
;             asm volatile("s_waitcnt vmcnt(0)" ::: "memory");
;             const unsigned og = xb_add(&bar[XB_TOP], 1u);
;             const unsigned tg = og / nx;
;             if (og + 1u == (tg + 1u) * nx) xb_add(&bar[XB_TOPGEN], 1u);
;             else XB_SPIN(xb_ld(&bar[XB_TOPGEN]) == tg, bar);
.LBB0_859:
	s_andn2_saveexec_b64 s[0:1], s[0:1]
	s_cbranch_execz .LBB0_875
	v_mov_b32_e32 v1, s40
	v_add_co_u32_e32 v2, vcc, 0xe370000, v1
	v_mov_b32_e32 v1, s41
	buffer_wbl2 sc1
	s_waitcnt vmcnt(0)
	v_addc_co_u32_e32 v3, vcc, 0, v1, vcc
	global_atomic_add v1, v[2:3], v208, off offset:1024 sc0
	v_cvt_f32_u32_e32 v2, v0
	v_sub_u32_e32 v3, 0, v0
	s_mov_b64 s[6:7], -1
	v_rcp_iflag_f32_e32 v2, v2
	s_nop 0
	v_mul_f32_e32 v2, 0x4f7ffffe, v2
	v_cvt_u32_f32_e32 v2, v2
	v_mul_lo_u32 v3, v3, v2
	v_mul_hi_u32 v3, v2, v3
	v_add_u32_e32 v2, v2, v3
	s_waitcnt vmcnt(0) lgkmcnt(0)
	v_mul_hi_u32 v2, v1, v2
	v_mul_lo_u32 v3, v2, v0
	v_sub_u32_e32 v3, v1, v3
	v_cmp_ge_u32_e32 vcc, v3, v0
	v_add_u32_e32 v4, 1, v2
	s_nop 0
	v_cndmask_b32_e32 v2, v2, v4, vcc
	v_sub_u32_e32 v4, v3, v0
	v_cndmask_b32_e32 v3, v3, v4, vcc
	v_cmp_ge_u32_e32 vcc, v3, v0
	v_add_u32_e32 v3, 1, v2
	s_nop 0
	v_cndmask_b32_e32 v2, v2, v3, vcc
	v_add_u32_e32 v3, 1, v1
	v_mad_u64_u32 v[0:1], s[0:1], v0, v2, v[0:1]
	s_add_u32 s0, s40, 0xe370500
	s_addc_u32 s1, s41, 0
	v_cmp_ne_u32_e32 vcc, v3, v0
	v_mov_b64_e32 v[0:1], s[0:1]
	s_and_saveexec_b64 s[2:3], vcc
	s_cbranch_execz .LBB0_872
	v_mov_b64_e32 v[0:1], s[0:1]
	global_load_dword v0, v[0:1], off sc1
	s_mov_b64 s[10:11], 0
	s_waitcnt vmcnt(0) lgkmcnt(0)
	v_cmp_eq_u32_e32 vcc, v0, v2
	s_and_saveexec_b64 s[8:9], vcc
	s_cbranch_execz .LBB0_871
	s_add_u32 s6, s40, 0xe36d200
	s_addc_u32 s7, s41, 0
	s_mov_b32 s22, 1
	s_branch .LBB0_864

; DI int TID() { int t = threadIdx.x; asm volatile("" : "+v"(t)); return t; }
; DI void gemm_preload(const bfu* __restrict__ A, const bfu* __restrict__ Bt, int K, int kt, bf16x8 (&ra)[4], bf16x8 (&rb)[8]) {
;   const int tid = TID(), sr = tid >> 3, sc = (tid & 7) * 8;
;   const bfu* Ag = A + (long)sr * K + sc + kt * BK; const bfu* Bg = Bt + (long)sr * K + sc + kt * BK;
; #pragma unroll
;   for (int i = 0; i < 4; ++i) ra[i] = ld8(Ag + (long)(32 * i) * K);
; #pragma unroll
;   for (int i = 0; i < 8; ++i) rb[i] = ld8(Bg + (long)(32 * i) * K);
; }
; DI void phase_gemm(const Params& p, int g, int kind, char* smem, float* rsl, int* s_item, int vlo, int vhi, int cslot) {
;     ...
;   if (cur.ok) gemm_preload(cur.A, cur.Bt, cur.K, 0, ra, rb);
.LBB0_881:
	v_cndmask_b32_e64 v0, 0, 1, s[2:3]
	v_cmp_ne_u32_e64 s[6:7], 1, v0
	s_andn2_b64 vcc, exec, s[2:3]
	s_cbranch_vccnz .LBB0_883
	v_mov_b32_e32 v4, v202
	s_nop 0
	v_ashrrev_i32_e32 v0, 3, v4
	v_ashrrev_i32_e32 v1, 31, v0
	v_lshlrev_b64 v[0:1], 13, v[0:1]
	v_lshlrev_b32_e32 v4, 4, v4
	v_lshl_add_u64 v[2:3], s[8:9], 0, v[0:1]
	v_and_b32_e32 v128, 0x70, v4
	v_lshl_add_u64 v[2:3], v[2:3], 0, v[128:129]
	v_add_co_u32_e32 v4, vcc, 0x40000, v2
	v_lshl_add_u64 v[0:1], s[10:11], 0, v[0:1]
	s_nop 0
	v_addc_co_u32_e32 v5, vcc, 0, v3, vcc
	v_add_co_u32_e32 v6, vcc, 0x80000, v2
	s_waitcnt vmcnt(0)
	global_load_dwordx4 v[134:137], v[2:3], off
	v_addc_co_u32_e32 v7, vcc, 0, v3, vcc
	v_add_co_u32_e32 v2, vcc, 0xc0000, v2
	v_lshl_add_u64 v[0:1], v[0:1], 0, v[128:129]
	s_nop 0
	v_addc_co_u32_e32 v3, vcc, 0, v3, vcc
	global_load_dwordx4 v[138:141], v[4:5], off
	global_load_dwordx4 v[142:145], v[6:7], off
	global_load_dwordx4 v[146:149], v[2:3], off
	global_load_dwordx4 v[150:153], v[0:1], off
	v_add_co_u32_e32 v2, vcc, s86, v0
	s_nop 1
	v_addc_co_u32_e32 v3, vcc, 0, v1, vcc
	v_add_co_u32_e32 v4, vcc, 0x80000, v0
	s_nop 1
	v_addc_co_u32_e32 v5, vcc, 0, v1, vcc
	global_load_dwordx4 v[154:157], v[2:3], off
	global_load_dwordx4 v[158:161], v[4:5], off
	v_add_co_u32_e32 v2, vcc, 0xc0000, v0
	s_nop 1
	v_addc_co_u32_e32 v3, vcc, 0, v1, vcc
	v_add_co_u32_e32 v4, vcc, 0x100000, v0
	s_nop 1
	v_addc_co_u32_e32 v5, vcc, 0, v1, vcc
	global_load_dwordx4 v[162:165], v[2:3], off
	global_load_dwordx4 v[166:169], v[4:5], off
	v_add_co_u32_e32 v2, vcc, 0x140000, v0
	s_nop 1
	v_addc_co_u32_e32 v3, vcc, 0, v1, vcc
	v_add_co_u32_e32 v4, vcc, 0x180000, v0
	s_nop 1
	v_addc_co_u32_e32 v5, vcc, 0, v1, vcc
	v_add_co_u32_e32 v0, vcc, 0x1c0000, v0
	global_load_dwordx4 v[170:173], v[2:3], off
	global_load_dwordx4 v[174:177], v[4:5], off
	v_addc_co_u32_e32 v1, vcc, 0, v1, vcc
	global_load_dwordx4 v[178:181], v[0:1], off
	s_and_b64 vcc, exec, s[6:7]
	s_cbranch_vccnz .LBB0_914
	s_branch .LBB0_884

; #define MFMA(a, b, c) __builtin_amdgcn_mfma_f32_32x32x16_bf16((a), (b), (c), 0, 0, 0)
; DI void gemm_main2(const bfu* __restrict__ A, const bfu* __restrict__ Bt, int K, char* smem, f32x16 (&acc)[2][4], bf16x8 (&ra)[4], bf16x8 (&rb)[8]) {
;     ...
;   for (int kt = 0; kt < nk; ++kt) {
;     __syncthreads();
; #pragma unroll
;     for (int i = 0; i < 4; ++i) st8(As + (sr + 32 * i) * LDT + sc, ra[i]);
; #pragma unroll
;     for (int i = 0; i < 8; ++i) st8(Bs + (sr + 32 * i) * LDT + sc, rb[i]);
;     __syncthreads();
;     if (kt + 1 < nk) gemm_preload(A, Bt, K, kt + 1, ra, rb);
; #pragma unroll
;     for (int ks = 0; ks < 4; ++ks) {
;       const bf16x8 a0 = ld8(as + ks * 16), a1 = ld8(as + 32 * LDT + ks * 16);
; #pragma unroll
;       for (int j = 0; j < 4; ++j) {
;         const bf16x8 b = ld8(bs + j * 32 * LDT + ks * 16);
;         acc[0][j] = MFMA(a0, b, acc[0][j]); acc[1][j] = MFMA(a1, b, acc[1][j]);
;       }
;     }
.LBB0_887:
	v_mov_b32_e32 v133, v202
	s_waitcnt lgkmcnt(0)
	s_barrier
	s_waitcnt vmcnt(0)
	ds_write_b128 v131, v[134:137]
	ds_write_b128 v131, v[138:141] offset:4608
	ds_write_b128 v131, v[142:145] offset:9216
	ds_write_b128 v131, v[146:149] offset:13824
	ds_write_b128 v131, v[150:153] offset:18432
	ds_write_b128 v131, v[154:157] offset:23040
	ds_write_b128 v131, v[158:161] offset:27648
	ds_write_b128 v131, v[162:165] offset:32256
	ds_write_b128 v131, v[166:169] offset:36864
	ds_write_b128 v131, v[170:173] offset:41472
	ds_write_b128 v131, v[174:177] offset:46080
	ds_write_b128 v131, v[178:181] offset:50688
	s_waitcnt lgkmcnt(0)
	s_barrier
	ds_read_b128 v[134:137], v130
	ds_read_b128 v[138:141], v128 offset:18432
	ds_read_b128 v[142:145], v130 offset:32
	ds_read_b128 v[146:149], v128 offset:18464
	ds_read_b128 v[150:153], v130 offset:4608
	ds_read_b128 v[154:157], v130 offset:4640
	s_waitcnt lgkmcnt(4)
	v_mfma_f32_32x32x16_bf16 v[112:127], v[134:137], v[138:141], v[112:127]
	s_mov_b32 s1, 0x100000
	s_waitcnt lgkmcnt(1)
	v_mfma_f32_32x32x16_bf16 v[48:63], v[150:153], v[138:141], v[48:63]
	ds_read_b128 v[138:141], v128 offset:23040
	ds_read_b128 v[158:161], v128 offset:23072
	s_waitcnt lgkmcnt(1)
	v_mfma_f32_32x32x16_bf16 v[96:111], v[134:137], v[138:141], v[96:111]
	v_mfma_f32_32x32x16_bf16 v[32:47], v[150:153], v[138:141], v[32:47]
	ds_read_b128 v[138:141], v128 offset:27648
	ds_read_b128 v[162:165], v128 offset:27680
	s_waitcnt lgkmcnt(1)
	v_mfma_f32_32x32x16_bf16 v[80:95], v[134:137], v[138:141], v[80:95]
	v_mfma_f32_32x32x16_bf16 v[16:31], v[150:153], v[138:141], v[16:31]
	ds_read_b128 v[138:141], v128 offset:32256
	ds_read_b128 v[166:169], v128 offset:32288
	s_waitcnt lgkmcnt(1)
	v_mfma_f32_32x32x16_bf16 v[64:79], v[134:137], v[138:141], v[64:79]
	v_mfma_f32_32x32x16_bf16 v[112:127], v[142:145], v[146:149], v[112:127]
	v_mfma_f32_32x32x16_bf16 v[48:63], v[154:157], v[146:149], v[48:63]
	v_mfma_f32_32x32x16_bf16 v[0:15], v[150:153], v[138:141], v[0:15]
	v_mfma_f32_32x32x16_bf16 v[96:111], v[142:145], v[158:161], v[96:111]
	v_mfma_f32_32x32x16_bf16 v[32:47], v[154:157], v[158:161], v[32:47]
	v_mfma_f32_32x32x16_bf16 v[80:95], v[142:145], v[162:165], v[80:95]
	s_waitcnt lgkmcnt(0)
	v_mfma_f32_32x32x16_bf16 v[64:79], v[142:145], v[166:169], v[64:79]
	ds_read_b128 v[134:137], v130 offset:64
	ds_read_b128 v[138:141], v128 offset:18496
	ds_read_b128 v[174:177], v130 offset:96
	ds_read_b128 v[142:145], v128 offset:18528
	ds_read_b128 v[146:149], v130 offset:4672
	ds_read_b128 v[182:185], v130 offset:4704
	v_mfma_f32_32x32x16_bf16 v[16:31], v[154:157], v[162:165], v[16:31]
	s_waitcnt lgkmcnt(4)
	v_mfma_f32_32x32x16_bf16 v[112:127], v[134:137], v[138:141], v[112:127]
	s_waitcnt lgkmcnt(1)
	v_mfma_f32_32x32x16_bf16 v[48:63], v[146:149], v[138:141], v[48:63]
	ds_read_b128 v[138:141], v128 offset:23104
	ds_read_b128 v[158:161], v128 offset:23136
	s_waitcnt lgkmcnt(1)
	v_mfma_f32_32x32x16_bf16 v[96:111], v[134:137], v[138:141], v[96:111]
	v_mfma_f32_32x32x16_bf16 v[32:47], v[146:149], v[138:141], v[32:47]
	ds_read_b128 v[138:141], v128 offset:27712
	ds_read_b128 v[178:181], v128 offset:27744
	s_waitcnt lgkmcnt(1)
	v_mfma_f32_32x32x16_bf16 v[80:95], v[134:137], v[138:141], v[80:95]
	v_mfma_f32_32x32x16_bf16 v[16:31], v[146:149], v[138:141], v[16:31]
	ds_read_b128 v[138:141], v128 offset:32320
	ds_read_b128 v[186:189], v128 offset:32352
	v_mfma_f32_32x32x16_bf16 v[0:15], v[154:157], v[166:169], v[0:15]
	s_waitcnt lgkmcnt(1)
	v_mfma_f32_32x32x16_bf16 v[64:79], v[134:137], v[138:141], v[64:79]
	v_ashrrev_i32_e32 v134, 3, v133
	v_ashrrev_i32_e32 v135, 31, v134
	v_lshlrev_b64 v[134:135], 13, v[134:135]
	v_and_b32_e32 v133, 7, v133
	v_lshl_or_b32 v134, v133, 4, v134
	v_lshl_add_u64 v[150:151], s[16:17], 0, v[134:135]
	v_lshl_add_u64 v[192:193], s[10:11], 0, v[150:151]
	v_mfma_f32_32x32x16_bf16 v[0:15], v[146:149], v[138:141], v[0:15]
	v_lshl_add_u64 v[146:147], s[8:9], 0, v[150:151]
	v_add_co_u32_e32 v138, vcc, s86, v146
	s_add_u32 s16, s16, 0x80
	s_nop 0
	v_addc_co_u32_e32 v139, vcc, 0, v147, vcc
	global_load_dwordx4 v[134:137], v[146:147], off offset:128
	s_nop 0
	global_load_dwordx4 v[138:141], v[138:139], off offset:128
	v_mfma_f32_32x32x16_bf16 v[112:127], v[174:177], v[142:145], v[112:127]
	s_addc_u32 s17, s17, 0
	s_cmpk_lg_i32 s16, 0x1f80
	v_mfma_f32_32x32x16_bf16 v[48:63], v[182:185], v[142:145], v[48:63]
	v_add_co_u32_e32 v142, vcc, s65, v146
	s_nop 1
	v_addc_co_u32_e32 v143, vcc, 0, v147, vcc
	v_add_co_u32_e32 v146, vcc, s67, v146
	v_mfma_f32_32x32x16_bf16 v[96:111], v[174:177], v[158:161], v[96:111]
	s_nop 0
	v_addc_co_u32_e32 v147, vcc, 0, v147, vcc
	v_add_co_u32_e32 v154, vcc, s86, v192
	global_load_dwordx4 v[142:145], v[142:143], off offset:128
	s_nop 0
	global_load_dwordx4 v[146:149], v[146:147], off offset:128
	v_addc_co_u32_e32 v155, vcc, 0, v193, vcc
	v_mfma_f32_32x32x16_bf16 v[32:47], v[182:185], v[158:161], v[32:47]
	v_add_co_u32_e32 v158, vcc, s65, v192
	global_load_dwordx4 v[150:153], v[192:193], off offset:128
	s_nop 0
	global_load_dwordx4 v[154:157], v[154:155], off offset:128
	v_addc_co_u32_e32 v159, vcc, 0, v193, vcc
	v_add_co_u32_e32 v162, vcc, s67, v192
	v_mfma_f32_32x32x16_bf16 v[80:95], v[174:177], v[178:181], v[80:95]
	s_nop 0
	v_addc_co_u32_e32 v163, vcc, 0, v193, vcc
	v_add_co_u32_e32 v166, vcc, s1, v192
	s_mov_b32 s1, 0x140000
	s_nop 0
	v_addc_co_u32_e32 v167, vcc, 0, v193, vcc
	v_add_co_u32_e32 v170, vcc, s1, v192
	s_mov_b32 s1, 0x180000
	s_nop 0
	v_addc_co_u32_e32 v171, vcc, 0, v193, vcc
	v_mfma_f32_32x32x16_bf16 v[16:31], v[182:185], v[178:181], v[16:31]
	v_add_co_u32_e32 v178, vcc, s1, v192
	s_mov_b32 s1, 0x1c0000
	s_nop 0
	v_addc_co_u32_e32 v179, vcc, 0, v193, vcc
	v_add_co_u32_e32 v180, vcc, s1, v192
	global_load_dwordx4 v[158:161], v[158:159], off offset:128
	s_nop 0
	global_load_dwordx4 v[162:165], v[162:163], off offset:128
	v_addc_co_u32_e32 v181, vcc, 0, v193, vcc
	global_load_dwordx4 v[166:169], v[166:167], off offset:128
	s_nop 0
	global_load_dwordx4 v[170:173], v[170:171], off offset:128
	s_waitcnt lgkmcnt(0)
	v_mfma_f32_32x32x16_bf16 v[64:79], v[174:177], v[186:189], v[64:79]
	global_load_dwordx4 v[174:177], v[178:179], off offset:128
	s_nop 0
	global_load_dwordx4 v[178:181], v[180:181], off offset:128
	v_mfma_f32_32x32x16_bf16 v[0:15], v[182:185], v[186:189], v[0:15]
	s_cbranch_scc1 .LBB0_887
; #define MFMA(a, b, c) __builtin_amdgcn_mfma_f32_32x32x16_bf16((a), (b), (c), 0, 0, 0)
; DI int TID() { int t = threadIdx.x; asm volatile("" : "+v"(t)); return t; }
; DI void gemm_main2(const bfu* __restrict__ A, const bfu* __restrict__ Bt, int K, char* smem, f32x16 (&acc)[2][4], bf16x8 (&ra)[4], bf16x8 (&rb)[8]) {
;     ...
;   for (int kt = 0; kt < nk; ++kt) {
;     __syncthreads();
; #pragma unroll
;     for (int i = 0; i < 4; ++i) st8(As + (sr + 32 * i) * LDT + sc, ra[i]);
; #pragma unroll
;     for (int i = 0; i < 8; ++i) st8(Bs + (sr + 32 * i) * LDT + sc, rb[i]);
;     __syncthreads();
;     if (kt + 1 < nk) gemm_preload(A, Bt, K, kt + 1, ra, rb);
; #pragma unroll
;     for (int ks = 0; ks < 4; ++ks) {
;       const bf16x8 a0 = ld8(as + ks * 16), a1 = ld8(as + 32 * LDT + ks * 16);
; #pragma unroll
;       for (int j = 0; j < 4; ++j) {
;         const bf16x8 b = ld8(bs + j * 32 * LDT + ks * 16);
;         acc[0][j] = MFMA(a0, b, acc[0][j]); acc[1][j] = MFMA(a1, b, acc[1][j]);
;       }
;     }
; DI void phase_gemm(const Params& p, int g, int kind, char* smem, float* rsl, int* s_item, int vlo, int vhi, int cslot) {
;     ...
;   auto fetch = [&](TD& d) {
;     for (;;) {
;       __syncthreads();
;       if (TID() == 0) *s_item = atomicAdd(qctr, 1);
;       __syncthreads();
;       const int kq = *s_item;
;       const int tile = ((kq >> 6) * 8 + xcd) * 64 + (kq & 63);
	s_barrier
	s_waitcnt vmcnt(0)
	ds_write_b128 v131, v[134:137]
	ds_write_b128 v131, v[138:141] offset:4608
	ds_write_b128 v131, v[142:145] offset:9216
	ds_write_b128 v131, v[146:149] offset:13824
	ds_write_b128 v131, v[150:153] offset:18432
	ds_write_b128 v131, v[154:157] offset:23040
	ds_write_b128 v131, v[158:161] offset:27648
	ds_write_b128 v131, v[162:165] offset:32256
	ds_write_b128 v131, v[166:169] offset:36864
	ds_write_b128 v131, v[170:173] offset:41472
	ds_write_b128 v131, v[174:177] offset:46080
	ds_write_b128 v131, v[178:181] offset:50688
	s_waitcnt lgkmcnt(0)
	s_barrier
	ds_read_b128 v[182:185], v130
	ds_read_b128 v[186:189], v128 offset:18432
	ds_read_b128 v[192:195], v130 offset:4608
	s_waitcnt lgkmcnt(1)
	v_mfma_f32_32x32x16_bf16 v[112:127], v[182:185], v[186:189], v[112:127]
	s_waitcnt lgkmcnt(0)
	v_mfma_f32_32x32x16_bf16 v[48:63], v[192:195], v[186:189], v[48:63]
	ds_read_b128 v[186:189], v128 offset:23040
	s_waitcnt lgkmcnt(0)
	v_mfma_f32_32x32x16_bf16 v[96:111], v[182:185], v[186:189], v[96:111]
	v_mfma_f32_32x32x16_bf16 v[32:47], v[192:195], v[186:189], v[32:47]
	ds_read_b128 v[186:189], v128 offset:27648
	s_waitcnt lgkmcnt(0)
	v_mfma_f32_32x32x16_bf16 v[80:95], v[182:185], v[186:189], v[80:95]
	v_mfma_f32_32x32x16_bf16 v[16:31], v[192:195], v[186:189], v[16:31]
	ds_read_b128 v[186:189], v128 offset:32256
	s_waitcnt lgkmcnt(0)
	v_mfma_f32_32x32x16_bf16 v[64:79], v[182:185], v[186:189], v[64:79]
	v_mfma_f32_32x32x16_bf16 v[0:15], v[192:195], v[186:189], v[0:15]
	ds_read_b128 v[182:185], v130 offset:32
	ds_read_b128 v[186:189], v128 offset:18464
	ds_read_b128 v[192:195], v130 offset:4640
	s_waitcnt lgkmcnt(1)
	v_mfma_f32_32x32x16_bf16 v[112:127], v[182:185], v[186:189], v[112:127]
	s_waitcnt lgkmcnt(0)
	v_mfma_f32_32x32x16_bf16 v[48:63], v[192:195], v[186:189], v[48:63]
	ds_read_b128 v[186:189], v128 offset:23072
	s_waitcnt lgkmcnt(0)
	v_mfma_f32_32x32x16_bf16 v[96:111], v[182:185], v[186:189], v[96:111]
	v_mfma_f32_32x32x16_bf16 v[32:47], v[192:195], v[186:189], v[32:47]
	ds_read_b128 v[186:189], v128 offset:27680
	s_waitcnt lgkmcnt(0)
	v_mfma_f32_32x32x16_bf16 v[80:95], v[182:185], v[186:189], v[80:95]
	v_mfma_f32_32x32x16_bf16 v[16:31], v[192:195], v[186:189], v[16:31]
	ds_read_b128 v[186:189], v128 offset:32288
	s_waitcnt lgkmcnt(0)
	v_mfma_f32_32x32x16_bf16 v[64:79], v[182:185], v[186:189], v[64:79]
	v_mfma_f32_32x32x16_bf16 v[0:15], v[192:195], v[186:189], v[0:15]
	ds_read_b128 v[182:185], v130 offset:64
	ds_read_b128 v[186:189], v128 offset:18496
	ds_read_b128 v[192:195], v130 offset:4672
	s_waitcnt lgkmcnt(1)
	v_mfma_f32_32x32x16_bf16 v[112:127], v[182:185], v[186:189], v[112:127]
	s_waitcnt lgkmcnt(0)
	v_mfma_f32_32x32x16_bf16 v[48:63], v[192:195], v[186:189], v[48:63]
	ds_read_b128 v[186:189], v128 offset:23104
	s_waitcnt lgkmcnt(0)
	v_mfma_f32_32x32x16_bf16 v[96:111], v[182:185], v[186:189], v[96:111]
	v_mfma_f32_32x32x16_bf16 v[32:47], v[192:195], v[186:189], v[32:47]
	ds_read_b128 v[186:189], v128 offset:27712
	s_waitcnt lgkmcnt(0)
	v_mfma_f32_32x32x16_bf16 v[80:95], v[182:185], v[186:189], v[80:95]
	v_mfma_f32_32x32x16_bf16 v[16:31], v[192:195], v[186:189], v[16:31]
	ds_read_b128 v[186:189], v128 offset:32320
	s_waitcnt lgkmcnt(0)
	v_mfma_f32_32x32x16_bf16 v[64:79], v[182:185], v[186:189], v[64:79]
	v_mfma_f32_32x32x16_bf16 v[0:15], v[192:195], v[186:189], v[0:15]
	ds_read_b128 v[182:185], v130 offset:96
	ds_read_b128 v[186:189], v128 offset:18528
	ds_read_b128 v[192:195], v130 offset:4704
	s_waitcnt lgkmcnt(1)
	v_mfma_f32_32x32x16_bf16 v[112:127], v[182:185], v[186:189], v[112:127]
	s_waitcnt lgkmcnt(0)
	v_mfma_f32_32x32x16_bf16 v[48:63], v[192:195], v[186:189], v[48:63]
	ds_read_b128 v[186:189], v128 offset:23136
	s_waitcnt lgkmcnt(0)
	v_mfma_f32_32x32x16_bf16 v[96:111], v[182:185], v[186:189], v[96:111]
	v_mfma_f32_32x32x16_bf16 v[32:47], v[192:195], v[186:189], v[32:47]
	ds_read_b128 v[186:189], v128 offset:27744
	s_waitcnt lgkmcnt(0)
	v_mfma_f32_32x32x16_bf16 v[80:95], v[182:185], v[186:189], v[80:95]
	v_mfma_f32_32x32x16_bf16 v[16:31], v[192:195], v[186:189], v[16:31]
	ds_read_b128 v[186:189], v128 offset:32352
	v_mov_b32_e32 v128, v202
	s_waitcnt lgkmcnt(0)
	s_barrier
	v_mfma_f32_32x32x16_bf16 v[64:79], v[182:185], v[186:189], v[64:79]
	v_cmp_eq_u32_e32 vcc, 0, v128
	v_mfma_f32_32x32x16_bf16 v[0:15], v[192:195], v[186:189], v[0:15]
	s_and_saveexec_b64 s[2:3], vcc
	s_cbranch_execz .LBB0_892
	s_mov_b64 s[18:19], exec
	v_mbcnt_lo_u32_b32 v128, s18, 0
	v_mbcnt_hi_u32_b32 v128, s19, v128
	v_cmp_eq_u32_e32 vcc, 0, v128
	s_and_saveexec_b64 s[16:17], vcc
	s_cbranch_execz .LBB0_891
	s_bcnt1_i32_b64 s1, s[18:19]
	v_mov_b32_e32 v130, s1
	global_atomic_add v130, v129, v130, s[36:37] offset:64 sc0

; DI int TID() { int t = threadIdx.x; asm volatile("" : "+v"(t)); return t; }
; DI void gemm_preload(const bfu* __restrict__ A, const bfu* __restrict__ Bt, int K, int kt, bf16x8 (&ra)[4], bf16x8 (&rb)[8]) {
;   const int tid = TID(), sr = tid >> 3, sc = (tid & 7) * 8;
;   const bfu* Ag = A + (long)sr * K + sc + kt * BK; const bfu* Bg = Bt + (long)sr * K + sc + kt * BK;
; #pragma unroll
;   for (int i = 0; i < 4; ++i) ra[i] = ld8(Ag + (long)(32 * i) * K);
; #pragma unroll
;   for (int i = 0; i < 8; ++i) rb[i] = ld8(Bg + (long)(32 * i) * K);
; }
; DI void phase_gemm(const Params& p, int g, int kind, char* smem, float* rsl, int* s_item, int vlo, int vhi, int cslot) {
;     ...
;     if (nxt.ok) gemm_preload(nxt.A, nxt.Bt, nxt.K, 0, ra, rb);
.LBB0_894:
	s_andn2_b64 vcc, exec, s[2:3]
	s_cbranch_vccnz .LBB0_896
	v_mov_b32_e32 v128, v202
	s_nop 0
	v_ashrrev_i32_e32 v130, 3, v128
	v_ashrrev_i32_e32 v131, 31, v130
	v_lshlrev_b64 v[130:131], 13, v[130:131]
	v_lshlrev_b32_e32 v128, 4, v128
	v_lshl_add_u64 v[134:135], s[8:9], 0, v[130:131]
	v_and_b32_e32 v128, 0x70, v128
	v_lshl_add_u64 v[146:147], v[134:135], 0, v[128:129]
	v_add_co_u32_e32 v138, vcc, 0x40000, v146
	v_lshl_add_u64 v[130:131], s[10:11], 0, v[130:131]
	s_nop 0
	v_addc_co_u32_e32 v139, vcc, 0, v147, vcc
	v_add_co_u32_e32 v142, vcc, 0x80000, v146
	global_load_dwordx4 v[134:137], v[146:147], off
	s_nop 0
	v_addc_co_u32_e32 v143, vcc, 0, v147, vcc
	v_add_co_u32_e32 v146, vcc, 0xc0000, v146
	v_lshl_add_u64 v[130:131], v[130:131], 0, v[128:129]
	s_nop 0
	v_addc_co_u32_e32 v147, vcc, 0, v147, vcc
	v_add_co_u32_e32 v154, vcc, s86, v130
	global_load_dwordx4 v[138:141], v[138:139], off
	s_nop 0
	global_load_dwordx4 v[142:145], v[142:143], off
	v_addc_co_u32_e32 v155, vcc, 0, v131, vcc
	v_add_co_u32_e32 v158, vcc, 0x80000, v130
	global_load_dwordx4 v[146:149], v[146:147], off
	s_nop 0
	global_load_dwordx4 v[150:153], v[130:131], off
	v_addc_co_u32_e32 v159, vcc, 0, v131, vcc
	v_add_co_u32_e32 v162, vcc, 0xc0000, v130
	global_load_dwordx4 v[154:157], v[154:155], off
	s_nop 0
	global_load_dwordx4 v[158:161], v[158:159], off
	v_addc_co_u32_e32 v163, vcc, 0, v131, vcc
	v_add_co_u32_e32 v166, vcc, 0x100000, v130
	s_nop 1
	v_addc_co_u32_e32 v167, vcc, 0, v131, vcc
	v_add_co_u32_e32 v170, vcc, 0x140000, v130
	global_load_dwordx4 v[162:165], v[162:163], off
	s_nop 0
	global_load_dwordx4 v[166:169], v[166:167], off
	v_addc_co_u32_e32 v171, vcc, 0, v131, vcc
	v_add_co_u32_e32 v174, vcc, 0x180000, v130
	s_nop 1
	v_addc_co_u32_e32 v175, vcc, 0, v131, vcc
	v_add_co_u32_e32 v130, vcc, 0x1c0000, v130
	global_load_dwordx4 v[170:173], v[170:171], off
	s_nop 0
	global_load_dwordx4 v[174:177], v[174:175], off
	v_addc_co_u32_e32 v131, vcc, 0, v131, vcc
	global_load_dwordx4 v[178:181], v[130:131], off

;   DI const float* x() const { return (const float*)sp[0]; }
;   DI const float* ctx() const { return (const float*)sp[2]; }
; DI int TID() { int t = threadIdx.x; asm volatile("" : "+v"(t)); return t; }
; DI void epi_out(const Params& p, const float* Cs, int g, int layer, int m0, int n0) {
;   for (int u = TID(); u < 2048; u += NT) {
;     int row = u >> 4, c8 = (u & 15) * 8; float v[8]; ldrow8(Cs, row, c8, v);
;     long r = (long)g * MG + m0 + row; int b = (int)(r / T), t = (int)(r % T);
;     float* z = P_ZX + r * DM + n0 + c8;
;     const float* xs = layer == 0 ? (t < CTX ? p.ctx() + ((long)b * CTX + t) * DM : p.x() + ((long)b * SEQ + (t - CTX)) * DM) + n0 + c8 : z;
;     const float* gt = P_MOD + ((long)layer * 9 + (t < CTX ? 8 : b)) * 6144 + 4096 + n0 + c8;
;     f32x4 x0 = *(const f32x4*)xs, x1 = *(const f32x4*)(xs + 4), o0, o1;
;     for (int j = 0; j < 4; ++j) { o0[j] = ALPHA * x0[j] + gt[j] * v[j]; o1[j] = ALPHA * x1[j] + gt[4 + j] * v[4 + j]; }
;     *(f32x4*)z = o0; *(f32x4*)(z + 4) = o1;
;   }
.LBB0_900:
	s_or_b64 exec, exec, s[2:3]
	ds_read_b64 v[196:197], v210
	v_lshl_add_u64 v[192:193], s[58:59], 0, v[192:193]
	v_lshlrev_b32_e32 v128, 2, v209
	v_lshlrev_b64 v[194:195], 13, v[194:195]
	v_lshl_add_u64 v[192:193], v[192:193], 0, s[20:21]
	s_waitcnt lgkmcnt(0)
	v_lshl_add_u64 v[194:195], v[196:197], 0, v[194:195]
	v_lshl_add_u64 v[204:205], v[192:193], 0, v[128:129]
	s_mov_b64 s[2:3], 0xe084000
	s_mov_b32 s1, 0xe084000
	v_lshl_add_u64 v[194:195], v[194:195], 0, s[20:21]
	v_lshl_add_u64 v[210:211], v[204:205], 0, s[2:3]
	v_add_co_u32_e32 v204, vcc, s1, v204
	v_lshl_add_u64 v[196:197], v[194:195], 0, v[128:129]
	s_nop 0
	v_addc_co_u32_e32 v205, vcc, 0, v205, vcc
	global_load_dwordx4 v[192:195], v[196:197], off
	s_nop 0
	global_load_dwordx4 v[196:199], v[196:197], off offset:16
	s_nop 0
	global_load_dwordx4 v[204:207], v[204:205], off
	s_nop 0
	global_load_dwordx4 v[226:229], v[210:211], off offset:16
	v_lshlrev_b64 v[130:131], 13, v[130:131]
	v_lshl_add_u64 v[130:131], s[22:23], 0, v[130:131]
	v_lshl_add_u64 v[130:131], v[130:131], 0, v[128:129]
	v_add_u32_e32 v128, 0x100, v201
	v_cmp_lt_i32_e32 vcc, s87, v201
	v_add_u32_e32 v133, 0x800, v133
	s_or_b64 s[24:25], vcc, s[24:25]
	v_mov_b32_e32 v201, v128
	s_waitcnt vmcnt(0)
	v_pk_mul_f32 v[188:189], v[188:189], v[206:207]
	v_pk_mul_f32 v[186:187], v[186:187], v[204:205]
	s_waitcnt lgkmcnt(0)
	v_pk_fma_f32 v[188:189], v[194:195], s[82:83], v[188:189] op_sel_hi:[1,0,1]
	v_pk_fma_f32 v[186:187], v[192:193], s[82:83], v[186:187] op_sel_hi:[1,0,1]
	v_pk_mul_f32 v[184:185], v[184:185], v[228:229]
	v_pk_mul_f32 v[182:183], v[182:183], v[226:227]
	v_pk_fma_f32 v[184:185], v[198:199], s[82:83], v[184:185] op_sel_hi:[1,0,1]
	v_pk_fma_f32 v[182:183], v[196:197], s[82:83], v[182:183] op_sel_hi:[1,0,1]
	global_store_dwordx4 v[130:131], v[186:189], off
	global_store_dwordx4 v[130:131], v[182:185], off offset:16
	s_andn2_b64 exec, exec, s[24:25]
	s_cbranch_execz .LBB0_905

;   DI const float* x() const { return (const float*)sp[0]; }
;   DI const float* ctx() const { return (const float*)sp[2]; }
; DI int TID() { int t = threadIdx.x; asm volatile("" : "+v"(t)); return t; }
; DI void epi_out(const Params& p, const float* Cs, int g, int layer, int m0, int n0) {
;   for (int u = TID(); u < 2048; u += NT) {
;     int row = u >> 4, c8 = (u & 15) * 8; float v[8]; ldrow8(Cs, row, c8, v);
;     long r = (long)g * MG + m0 + row; int b = (int)(r / T), t = (int)(r % T);
;     float* z = P_ZX + r * DM + n0 + c8;
;     const float* xs = layer == 0 ? (t < CTX ? p.ctx() + ((long)b * CTX + t) * DM : p.x() + ((long)b * SEQ + (t - CTX)) * DM) + n0 + c8 : z;
;     const float* gt = P_MOD + ((long)layer * 9 + (t < CTX ? 8 : b)) * 6144 + 4096 + n0 + c8;
;     f32x4 x0 = *(const f32x4*)xs, x1 = *(const f32x4*)(xs + 4), o0, o1;
;     for (int j = 0; j < 4; ++j) { o0[j] = ALPHA * x0[j] + gt[j] * v[j]; o1[j] = ALPHA * x1[j] + gt[4 + j] * v[4 + j]; }
;     *(f32x4*)z = o0; *(f32x4*)(z + 4) = o1;
;   }
.LBB0_909:
	s_or_b64 exec, exec, s[2:3]
	v_lshlrev_b64 v[8:9], 13, v[8:9]
	v_lshl_add_u64 v[8:9], s[22:23], 0, v[8:9]
	v_lshlrev_b32_e32 v128, 2, v20
	v_lshl_add_u64 v[16:17], v[8:9], 0, v[128:129]
	ds_read_b64 v[8:9], v21
	v_lshlrev_b64 v[12:13], 13, v[12:13]
	s_mov_b64 s[2:3], 0xe084000
	v_add_u32_e32 v18, 0x800, v18
	s_waitcnt lgkmcnt(0)
	v_lshl_add_u64 v[8:9], v[8:9], 0, v[12:13]
	v_lshl_add_u64 v[8:9], s[0:1], 2, v[8:9]
	v_lshl_add_u64 v[12:13], v[8:9], 0, v[128:129]
	v_lshl_add_u64 v[8:9], s[58:59], 0, v[10:11]
	v_lshl_add_u64 v[8:9], v[8:9], 0, v[128:129]
	v_lshl_add_u64 v[20:21], s[20:21], 2, v[8:9]
	v_lshl_add_u64 v[24:25], v[20:21], 0, s[2:3]
	s_mov_b32 s2, 0xe084000
	v_add_co_u32_e32 v20, vcc, s2, v20
	global_load_dwordx4 v[8:11], v[12:13], off offset:512
	s_nop 0
	global_load_dwordx4 v[12:15], v[12:13], off offset:528
	v_addc_co_u32_e32 v21, vcc, 0, v21, vcc
	global_load_dwordx4 v[20:23], v[20:21], off
	s_nop 0
	global_load_dwordx4 v[24:27], v[24:25], off offset:16
	v_cmp_lt_i32_e32 vcc, s87, v19
	s_or_b64 s[24:25], vcc, s[24:25]
	s_waitcnt vmcnt(0)
	v_pk_mul_f32 v[6:7], v[6:7], v[22:23]
	v_pk_mul_f32 v[4:5], v[4:5], v[20:21]
	v_pk_mul_f32 v[0:1], v[0:1], v[24:25]
	s_waitcnt lgkmcnt(0)
	v_pk_fma_f32 v[6:7], v[10:11], s[82:83], v[6:7] op_sel_hi:[1,0,1]
	v_pk_fma_f32 v[4:5], v[8:9], s[82:83], v[4:5] op_sel_hi:[1,0,1]
	v_pk_mul_f32 v[2:3], v[2:3], v[26:27]
	v_pk_fma_f32 v[0:1], v[12:13], s[82:83], v[0:1] op_sel_hi:[1,0,1]
	v_pk_fma_f32 v[2:3], v[14:15], s[82:83], v[2:3] op_sel_hi:[1,0,1]
	global_store_dwordx4 v[16:17], v[4:7], off offset:512
	global_store_dwordx4 v[16:17], v[0:3], off offset:528
	s_nop 1
	v_add_u32_e32 v0, 0x100, v19
	v_mov_b32_e32 v19, v0
	s_andn2_b64 exec, exec, s[24:25]
	s_cbranch_execz .LBB0_885

; DI int TID() { int t = threadIdx.x; asm volatile("" : "+v"(t)); return t; }
; DI void gemm_preload(const bfu* __restrict__ A, const bfu* __restrict__ Bt, int K, int kt, bf16x8 (&ra)[4], bf16x8 (&rb)[8]) {
;   const int tid = TID(), sr = tid >> 3, sc = (tid & 7) * 8;
;   const bfu* Ag = A + (long)sr * K + sc + kt * BK; const bfu* Bg = Bt + (long)sr * K + sc + kt * BK;
; #pragma unroll
;   for (int i = 0; i < 4; ++i) ra[i] = ld8(Ag + (long)(32 * i) * K);
; #pragma unroll
;   for (int i = 0; i < 8; ++i) rb[i] = ld8(Bg + (long)(32 * i) * K);
; }
; DI void phase_gemm(const Params& p, int g, int kind, char* smem, float* rsl, int* s_item, int vlo, int vhi, int cslot) {
;     ...
;   if (cur.ok) gemm_preload(cur.A, cur.Bt, cur.K, 0, ra, rb);
.LBB0_921:
	v_cndmask_b32_e64 v0, 0, 1, s[2:3]
	v_cmp_ne_u32_e64 s[6:7], 1, v0
	s_andn2_b64 vcc, exec, s[2:3]
	s_cbranch_vccnz .LBB0_923
	v_mov_b32_e32 v4, v202
	s_nop 0
	v_ashrrev_i32_e32 v0, 3, v4
	v_ashrrev_i32_e32 v1, 31, v0
	v_lshlrev_b64 v[0:1], 12, v[0:1]
	v_lshlrev_b32_e32 v4, 4, v4
	v_lshl_add_u64 v[2:3], s[42:43], 0, v[0:1]
	v_and_b32_e32 v128, 0x70, v4
	v_lshl_add_u64 v[2:3], v[2:3], 0, v[128:129]
	v_add_co_u32_e32 v4, vcc, 0x20000, v2
	v_lshl_add_u64 v[0:1], s[44:45], 0, v[0:1]
	s_nop 0
	v_addc_co_u32_e32 v5, vcc, 0, v3, vcc
	v_add_co_u32_e32 v6, vcc, 0x40000, v2
	s_waitcnt vmcnt(0)
	global_load_dwordx4 v[134:137], v[2:3], off
	v_addc_co_u32_e32 v7, vcc, 0, v3, vcc
	v_add_co_u32_e32 v2, vcc, 0x60000, v2
	v_lshl_add_u64 v[0:1], v[0:1], 0, v[128:129]
	s_nop 0
	v_addc_co_u32_e32 v3, vcc, 0, v3, vcc
	global_load_dwordx4 v[138:141], v[4:5], off
	global_load_dwordx4 v[142:145], v[6:7], off
	global_load_dwordx4 v[146:149], v[2:3], off
	global_load_dwordx4 v[150:153], v[0:1], off
	v_add_co_u32_e32 v2, vcc, s72, v0
	s_nop 1
	v_addc_co_u32_e32 v3, vcc, 0, v1, vcc
	v_add_co_u32_e32 v4, vcc, 0x40000, v0
	s_nop 1
	v_addc_co_u32_e32 v5, vcc, 0, v1, vcc
	global_load_dwordx4 v[154:157], v[2:3], off
	global_load_dwordx4 v[158:161], v[4:5], off
	v_add_co_u32_e32 v2, vcc, 0x60000, v0
	s_nop 1
	v_addc_co_u32_e32 v3, vcc, 0, v1, vcc
	v_add_co_u32_e32 v4, vcc, 0x80000, v0
	s_nop 1
	v_addc_co_u32_e32 v5, vcc, 0, v1, vcc
	global_load_dwordx4 v[162:165], v[2:3], off
	global_load_dwordx4 v[166:169], v[4:5], off
	v_add_co_u32_e32 v2, vcc, 0xa0000, v0
	s_nop 1
	v_addc_co_u32_e32 v3, vcc, 0, v1, vcc
	v_add_co_u32_e32 v4, vcc, 0xc0000, v0
	s_nop 1
	v_addc_co_u32_e32 v5, vcc, 0, v1, vcc
	v_add_co_u32_e32 v0, vcc, 0xe0000, v0
	global_load_dwordx4 v[170:173], v[2:3], off
	global_load_dwordx4 v[174:177], v[4:5], off
	v_addc_co_u32_e32 v1, vcc, 0, v1, vcc
	global_load_dwordx4 v[178:181], v[0:1], off
	s_and_b64 vcc, exec, s[6:7]
	s_cbranch_vccnz .LBB0_1096
	s_branch .LBB0_924

; #define MFMA(a, b, c) __builtin_amdgcn_mfma_f32_32x32x16_bf16((a), (b), (c), 0, 0, 0)
; DI void gemm_main2(const bfu* __restrict__ A, const bfu* __restrict__ Bt, int K, char* smem, f32x16 (&acc)[2][4], bf16x8 (&ra)[4], bf16x8 (&rb)[8]) {
;     ...
;   for (int kt = 0; kt < nk; ++kt) {
;     __syncthreads();
; #pragma unroll
;     for (int i = 0; i < 4; ++i) st8(As + (sr + 32 * i) * LDT + sc, ra[i]);
; #pragma unroll
;     for (int i = 0; i < 8; ++i) st8(Bs + (sr + 32 * i) * LDT + sc, rb[i]);
;     __syncthreads();
;     if (kt + 1 < nk) gemm_preload(A, Bt, K, kt + 1, ra, rb);
; #pragma unroll
;     for (int ks = 0; ks < 4; ++ks) {
;       const bf16x8 a0 = ld8(as + ks * 16), a1 = ld8(as + 32 * LDT + ks * 16);
; #pragma unroll
;       for (int j = 0; j < 4; ++j) {
;         const bf16x8 b = ld8(bs + j * 32 * LDT + ks * 16);
;         acc[0][j] = MFMA(a0, b, acc[0][j]); acc[1][j] = MFMA(a1, b, acc[1][j]);
;       }
;     }
.LBB0_928:
	v_mov_b32_e32 v133, v202
	s_waitcnt lgkmcnt(0)
	s_barrier
	s_waitcnt vmcnt(0)
	ds_write_b128 v131, v[134:137]
	ds_write_b128 v131, v[138:141] offset:4608
	ds_write_b128 v131, v[142:145] offset:9216
	ds_write_b128 v131, v[146:149] offset:13824
	ds_write_b128 v131, v[150:153] offset:18432
	ds_write_b128 v131, v[154:157] offset:23040
	ds_write_b128 v131, v[158:161] offset:27648
	ds_write_b128 v131, v[162:165] offset:32256
	ds_write_b128 v131, v[166:169] offset:36864
	ds_write_b128 v131, v[170:173] offset:41472
	ds_write_b128 v131, v[174:177] offset:46080
	ds_write_b128 v131, v[178:181] offset:50688
	s_waitcnt lgkmcnt(0)
	s_barrier
	ds_read_b128 v[134:137], v130
	ds_read_b128 v[138:141], v128 offset:18432
	ds_read_b128 v[142:145], v130 offset:32
	ds_read_b128 v[146:149], v128 offset:18464
	ds_read_b128 v[150:153], v130 offset:4608
	ds_read_b128 v[154:157], v130 offset:4640
	s_waitcnt lgkmcnt(4)
	v_mfma_f32_32x32x16_bf16 v[112:127], v[134:137], v[138:141], v[112:127]
	s_waitcnt lgkmcnt(1)
	v_mfma_f32_32x32x16_bf16 v[48:63], v[150:153], v[138:141], v[48:63]
	ds_read_b128 v[138:141], v128 offset:23040
	ds_read_b128 v[158:161], v128 offset:23072
	s_waitcnt lgkmcnt(1)
	v_mfma_f32_32x32x16_bf16 v[96:111], v[134:137], v[138:141], v[96:111]
	v_mfma_f32_32x32x16_bf16 v[32:47], v[150:153], v[138:141], v[32:47]
	ds_read_b128 v[138:141], v128 offset:27648
	ds_read_b128 v[162:165], v128 offset:27680
	s_waitcnt lgkmcnt(1)
	v_mfma_f32_32x32x16_bf16 v[80:95], v[134:137], v[138:141], v[80:95]
	v_mfma_f32_32x32x16_bf16 v[16:31], v[150:153], v[138:141], v[16:31]
	ds_read_b128 v[138:141], v128 offset:32256
	ds_read_b128 v[166:169], v128 offset:32288
	s_waitcnt lgkmcnt(1)
	v_mfma_f32_32x32x16_bf16 v[64:79], v[134:137], v[138:141], v[64:79]
	v_mfma_f32_32x32x16_bf16 v[112:127], v[142:145], v[146:149], v[112:127]
	v_mfma_f32_32x32x16_bf16 v[48:63], v[154:157], v[146:149], v[48:63]
	v_mfma_f32_32x32x16_bf16 v[0:15], v[150:153], v[138:141], v[0:15]
	v_mfma_f32_32x32x16_bf16 v[96:111], v[142:145], v[158:161], v[96:111]
	v_mfma_f32_32x32x16_bf16 v[32:47], v[154:157], v[158:161], v[32:47]
	v_mfma_f32_32x32x16_bf16 v[80:95], v[142:145], v[162:165], v[80:95]
	s_waitcnt lgkmcnt(0)
	v_mfma_f32_32x32x16_bf16 v[64:79], v[142:145], v[166:169], v[64:79]
	ds_read_b128 v[134:137], v130 offset:64
	ds_read_b128 v[138:141], v128 offset:18496
	ds_read_b128 v[174:177], v130 offset:96
	ds_read_b128 v[142:145], v128 offset:18528
	ds_read_b128 v[146:149], v130 offset:4672
	ds_read_b128 v[182:185], v130 offset:4704
	v_mfma_f32_32x32x16_bf16 v[16:31], v[154:157], v[162:165], v[16:31]
	s_waitcnt lgkmcnt(4)
	v_mfma_f32_32x32x16_bf16 v[112:127], v[134:137], v[138:141], v[112:127]
	s_waitcnt lgkmcnt(1)
	v_mfma_f32_32x32x16_bf16 v[48:63], v[146:149], v[138:141], v[48:63]
	ds_read_b128 v[138:141], v128 offset:23104
	ds_read_b128 v[158:161], v128 offset:23136
	s_waitcnt lgkmcnt(1)
	v_mfma_f32_32x32x16_bf16 v[96:111], v[134:137], v[138:141], v[96:111]
	v_mfma_f32_32x32x16_bf16 v[32:47], v[146:149], v[138:141], v[32:47]
	ds_read_b128 v[138:141], v128 offset:27712
	ds_read_b128 v[178:181], v128 offset:27744
	s_waitcnt lgkmcnt(1)
	v_mfma_f32_32x32x16_bf16 v[80:95], v[134:137], v[138:141], v[80:95]
	v_mfma_f32_32x32x16_bf16 v[16:31], v[146:149], v[138:141], v[16:31]
	ds_read_b128 v[138:141], v128 offset:32320
	ds_read_b128 v[186:189], v128 offset:32352
	v_mfma_f32_32x32x16_bf16 v[0:15], v[154:157], v[166:169], v[0:15]
	s_waitcnt lgkmcnt(1)
	v_mfma_f32_32x32x16_bf16 v[64:79], v[134:137], v[138:141], v[64:79]
	v_ashrrev_i32_e32 v134, 3, v133
	v_ashrrev_i32_e32 v135, 31, v134
	v_lshlrev_b64 v[134:135], 12, v[134:135]
	v_and_b32_e32 v133, 7, v133
	v_lshl_or_b32 v134, v133, 4, v134
	v_lshl_add_u64 v[150:151], s[4:5], 0, v[134:135]
	v_lshl_add_u64 v[192:193], s[44:45], 0, v[150:151]
	v_mfma_f32_32x32x16_bf16 v[0:15], v[146:149], v[138:141], v[0:15]
	v_lshl_add_u64 v[146:147], s[42:43], 0, v[150:151]
	v_add_co_u32_e32 v138, vcc, s72, v146
	s_add_u32 s4, s4, 0x80
	s_nop 0
	v_addc_co_u32_e32 v139, vcc, 0, v147, vcc
	global_load_dwordx4 v[134:137], v[146:147], off offset:128
	s_nop 0
	global_load_dwordx4 v[138:141], v[138:139], off offset:128
	v_mfma_f32_32x32x16_bf16 v[112:127], v[174:177], v[142:145], v[112:127]
	s_addc_u32 s5, s5, 0
	s_cmpk_lg_i32 s4, 0xf80
	v_mfma_f32_32x32x16_bf16 v[48:63], v[182:185], v[142:145], v[48:63]
	v_add_co_u32_e32 v142, vcc, s86, v146
	s_nop 1
	v_addc_co_u32_e32 v143, vcc, 0, v147, vcc
	v_add_co_u32_e32 v146, vcc, s64, v146
	v_mfma_f32_32x32x16_bf16 v[96:111], v[174:177], v[158:161], v[96:111]
	s_nop 0
	v_addc_co_u32_e32 v147, vcc, 0, v147, vcc
	v_add_co_u32_e32 v154, vcc, s72, v192
	global_load_dwordx4 v[142:145], v[142:143], off offset:128
	s_nop 0
	global_load_dwordx4 v[146:149], v[146:147], off offset:128
	v_addc_co_u32_e32 v155, vcc, 0, v193, vcc
	v_mfma_f32_32x32x16_bf16 v[32:47], v[182:185], v[158:161], v[32:47]
	v_add_co_u32_e32 v158, vcc, s86, v192
	global_load_dwordx4 v[150:153], v[192:193], off offset:128
	s_nop 0
	global_load_dwordx4 v[154:157], v[154:155], off offset:128
	v_addc_co_u32_e32 v159, vcc, 0, v193, vcc
	v_add_co_u32_e32 v162, vcc, s64, v192
	v_mfma_f32_32x32x16_bf16 v[80:95], v[174:177], v[178:181], v[80:95]
	s_nop 0
	v_addc_co_u32_e32 v163, vcc, 0, v193, vcc
	v_add_co_u32_e32 v166, vcc, s65, v192
	global_load_dwordx4 v[158:161], v[158:159], off offset:128
	s_nop 0
	global_load_dwordx4 v[162:165], v[162:163], off offset:128
	v_addc_co_u32_e32 v167, vcc, 0, v193, vcc
	v_add_co_u32_e32 v170, vcc, s66, v192
	v_mfma_f32_32x32x16_bf16 v[16:31], v[182:185], v[178:181], v[16:31]
	s_nop 0
	v_addc_co_u32_e32 v171, vcc, 0, v193, vcc
	v_add_co_u32_e32 v178, vcc, s67, v192
	global_load_dwordx4 v[166:169], v[166:167], off offset:128
	s_nop 0
	global_load_dwordx4 v[170:173], v[170:171], off offset:128
	v_addc_co_u32_e32 v179, vcc, 0, v193, vcc
	v_add_co_u32_e32 v180, vcc, s61, v192
	s_waitcnt lgkmcnt(0)
	v_mfma_f32_32x32x16_bf16 v[64:79], v[174:177], v[186:189], v[64:79]
	v_addc_co_u32_e32 v181, vcc, 0, v193, vcc
	global_load_dwordx4 v[174:177], v[178:179], off offset:128
	s_nop 0
	global_load_dwordx4 v[178:181], v[180:181], off offset:128
	v_mfma_f32_32x32x16_bf16 v[0:15], v[182:185], v[186:189], v[0:15]
	s_cbranch_scc1 .LBB0_928
; #define MFMA(a, b, c) __builtin_amdgcn_mfma_f32_32x32x16_bf16((a), (b), (c), 0, 0, 0)
; DI int TID() { int t = threadIdx.x; asm volatile("" : "+v"(t)); return t; }
; DI void gemm_main2(const bfu* __restrict__ A, const bfu* __restrict__ Bt, int K, char* smem, f32x16 (&acc)[2][4], bf16x8 (&ra)[4], bf16x8 (&rb)[8]) {
;     ...
;   for (int kt = 0; kt < nk; ++kt) {
;     __syncthreads();
; #pragma unroll
;     for (int i = 0; i < 4; ++i) st8(As + (sr + 32 * i) * LDT + sc, ra[i]);
; #pragma unroll
;     for (int i = 0; i < 8; ++i) st8(Bs + (sr + 32 * i) * LDT + sc, rb[i]);
;     __syncthreads();
;     if (kt + 1 < nk) gemm_preload(A, Bt, K, kt + 1, ra, rb);
; #pragma unroll
;     for (int ks = 0; ks < 4; ++ks) {
;       const bf16x8 a0 = ld8(as + ks * 16), a1 = ld8(as + 32 * LDT + ks * 16);
; #pragma unroll
;       for (int j = 0; j < 4; ++j) {
;         const bf16x8 b = ld8(bs + j * 32 * LDT + ks * 16);
;         acc[0][j] = MFMA(a0, b, acc[0][j]); acc[1][j] = MFMA(a1, b, acc[1][j]);
;       }
;     }
; DI void phase_gemm(const Params& p, int g, int kind, char* smem, float* rsl, int* s_item, int vlo, int vhi, int cslot) {
;     ...
;   auto fetch = [&](TD& d) {
;     for (;;) {
;       __syncthreads();
;       if (TID() == 0) *s_item = atomicAdd(qctr, 1);
;       __syncthreads();
;       const int kq = *s_item;
;       const int tile = ((kq >> 6) * 8 + xcd) * 64 + (kq & 63);
	s_barrier
	s_waitcnt vmcnt(0)
	ds_write_b128 v131, v[134:137]
	ds_write_b128 v131, v[138:141] offset:4608
	ds_write_b128 v131, v[142:145] offset:9216
	ds_write_b128 v131, v[146:149] offset:13824
	ds_write_b128 v131, v[150:153] offset:18432
	ds_write_b128 v131, v[154:157] offset:23040
	ds_write_b128 v131, v[158:161] offset:27648
	ds_write_b128 v131, v[162:165] offset:32256
	ds_write_b128 v131, v[166:169] offset:36864
	ds_write_b128 v131, v[170:173] offset:41472
	ds_write_b128 v131, v[174:177] offset:46080
	ds_write_b128 v131, v[178:181] offset:50688
	s_waitcnt lgkmcnt(0)
	s_barrier
	ds_read_b128 v[182:185], v130
	ds_read_b128 v[186:189], v128 offset:18432
	ds_read_b128 v[192:195], v130 offset:4608
	s_waitcnt lgkmcnt(1)
	v_mfma_f32_32x32x16_bf16 v[112:127], v[182:185], v[186:189], v[112:127]
	s_waitcnt lgkmcnt(0)
	v_mfma_f32_32x32x16_bf16 v[48:63], v[192:195], v[186:189], v[48:63]
	ds_read_b128 v[186:189], v128 offset:23040
	s_waitcnt lgkmcnt(0)
	v_mfma_f32_32x32x16_bf16 v[96:111], v[182:185], v[186:189], v[96:111]
	v_mfma_f32_32x32x16_bf16 v[32:47], v[192:195], v[186:189], v[32:47]
	ds_read_b128 v[186:189], v128 offset:27648
	s_waitcnt lgkmcnt(0)
	v_mfma_f32_32x32x16_bf16 v[80:95], v[182:185], v[186:189], v[80:95]
	v_mfma_f32_32x32x16_bf16 v[16:31], v[192:195], v[186:189], v[16:31]
	ds_read_b128 v[186:189], v128 offset:32256
	s_waitcnt lgkmcnt(0)
	v_mfma_f32_32x32x16_bf16 v[64:79], v[182:185], v[186:189], v[64:79]
	v_mfma_f32_32x32x16_bf16 v[0:15], v[192:195], v[186:189], v[0:15]
	ds_read_b128 v[182:185], v130 offset:32
	ds_read_b128 v[186:189], v128 offset:18464
	ds_read_b128 v[192:195], v130 offset:4640
	s_waitcnt lgkmcnt(1)
	v_mfma_f32_32x32x16_bf16 v[112:127], v[182:185], v[186:189], v[112:127]
	s_waitcnt lgkmcnt(0)
	v_mfma_f32_32x32x16_bf16 v[48:63], v[192:195], v[186:189], v[48:63]
	ds_read_b128 v[186:189], v128 offset:23072
	s_waitcnt lgkmcnt(0)
	v_mfma_f32_32x32x16_bf16 v[96:111], v[182:185], v[186:189], v[96:111]
	v_mfma_f32_32x32x16_bf16 v[32:47], v[192:195], v[186:189], v[32:47]
	ds_read_b128 v[186:189], v128 offset:27680
	s_waitcnt lgkmcnt(0)
	v_mfma_f32_32x32x16_bf16 v[80:95], v[182:185], v[186:189], v[80:95]
	v_mfma_f32_32x32x16_bf16 v[16:31], v[192:195], v[186:189], v[16:31]
	ds_read_b128 v[186:189], v128 offset:32288
	s_waitcnt lgkmcnt(0)
	v_mfma_f32_32x32x16_bf16 v[64:79], v[182:185], v[186:189], v[64:79]
	v_mfma_f32_32x32x16_bf16 v[0:15], v[192:195], v[186:189], v[0:15]
	ds_read_b128 v[182:185], v130 offset:64
	ds_read_b128 v[186:189], v128 offset:18496
	ds_read_b128 v[192:195], v130 offset:4672
	s_waitcnt lgkmcnt(1)
	v_mfma_f32_32x32x16_bf16 v[112:127], v[182:185], v[186:189], v[112:127]
	s_waitcnt lgkmcnt(0)
	v_mfma_f32_32x32x16_bf16 v[48:63], v[192:195], v[186:189], v[48:63]
	ds_read_b128 v[186:189], v128 offset:23104
	s_waitcnt lgkmcnt(0)
	v_mfma_f32_32x32x16_bf16 v[96:111], v[182:185], v[186:189], v[96:111]
	v_mfma_f32_32x32x16_bf16 v[32:47], v[192:195], v[186:189], v[32:47]
	ds_read_b128 v[186:189], v128 offset:27712
	s_waitcnt lgkmcnt(0)
	v_mfma_f32_32x32x16_bf16 v[80:95], v[182:185], v[186:189], v[80:95]
	v_mfma_f32_32x32x16_bf16 v[16:31], v[192:195], v[186:189], v[16:31]
	ds_read_b128 v[186:189], v128 offset:32320
	s_waitcnt lgkmcnt(0)
	v_mfma_f32_32x32x16_bf16 v[64:79], v[182:185], v[186:189], v[64:79]
	v_mfma_f32_32x32x16_bf16 v[0:15], v[192:195], v[186:189], v[0:15]
	ds_read_b128 v[182:185], v130 offset:96
	ds_read_b128 v[186:189], v128 offset:18528
	ds_read_b128 v[192:195], v130 offset:4704
	s_waitcnt lgkmcnt(1)
	v_mfma_f32_32x32x16_bf16 v[112:127], v[182:185], v[186:189], v[112:127]
	s_waitcnt lgkmcnt(0)
	v_mfma_f32_32x32x16_bf16 v[48:63], v[192:195], v[186:189], v[48:63]
	ds_read_b128 v[186:189], v128 offset:23136
	s_waitcnt lgkmcnt(0)
	v_mfma_f32_32x32x16_bf16 v[96:111], v[182:185], v[186:189], v[96:111]
	v_mfma_f32_32x32x16_bf16 v[32:47], v[192:195], v[186:189], v[32:47]
	ds_read_b128 v[186:189], v128 offset:27744
	s_waitcnt lgkmcnt(0)
	v_mfma_f32_32x32x16_bf16 v[80:95], v[182:185], v[186:189], v[80:95]
	v_mfma_f32_32x32x16_bf16 v[16:31], v[192:195], v[186:189], v[16:31]
	ds_read_b128 v[186:189], v128 offset:32352
	v_mov_b32_e32 v128, v202
	s_waitcnt lgkmcnt(0)
	s_barrier
	v_mfma_f32_32x32x16_bf16 v[64:79], v[182:185], v[186:189], v[64:79]
	v_cmp_eq_u32_e32 vcc, 0, v128
	v_mfma_f32_32x32x16_bf16 v[0:15], v[192:195], v[186:189], v[0:15]
	s_and_saveexec_b64 s[2:3], vcc
	s_movk_i32 s23, 0xff
	s_movk_i32 s24, 0xe80
	s_mov_b32 s25, 0xfff70000
	s_mov_b32 s26, 0x3db504f3
	s_movk_i32 s27, 0x190
	s_movk_i32 s28, 0x2ff
	s_cbranch_execz .LBB0_933
	s_mov_b64 s[6:7], exec
	v_mbcnt_lo_u32_b32 v128, s6, 0
	v_mbcnt_hi_u32_b32 v128, s7, v128
	v_cmp_eq_u32_e32 vcc, 0, v128
	s_and_saveexec_b64 s[4:5], vcc
	s_cbranch_execz .LBB0_932
	s_bcnt1_i32_b64 s1, s[6:7]
	v_mov_b32_e32 v130, s1
	global_atomic_add v130, v129, v130, s[36:37] sc0

; DI int TID() { int t = threadIdx.x; asm volatile("" : "+v"(t)); return t; }
; DI void gemm_preload(const bfu* __restrict__ A, const bfu* __restrict__ Bt, int K, int kt, bf16x8 (&ra)[4], bf16x8 (&rb)[8]) {
;   const int tid = TID(), sr = tid >> 3, sc = (tid & 7) * 8;
;   const bfu* Ag = A + (long)sr * K + sc + kt * BK; const bfu* Bg = Bt + (long)sr * K + sc + kt * BK;
; #pragma unroll
;   for (int i = 0; i < 4; ++i) ra[i] = ld8(Ag + (long)(32 * i) * K);
; #pragma unroll
;   for (int i = 0; i < 8; ++i) rb[i] = ld8(Bg + (long)(32 * i) * K);
; }
; DI void phase_gemm(const Params& p, int g, int kind, char* smem, float* rsl, int* s_item, int vlo, int vhi, int cslot) {
;     ...
;     if (nxt.ok) gemm_preload(nxt.A, nxt.Bt, nxt.K, 0, ra, rb);
.LBB0_935:
	s_andn2_b64 vcc, exec, s[2:3]
	s_cbranch_vccnz .LBB0_937
	v_mov_b32_e32 v128, v202
	s_nop 0
	v_ashrrev_i32_e32 v130, 3, v128
	v_ashrrev_i32_e32 v131, 31, v130
	v_lshlrev_b64 v[130:131], 12, v[130:131]
	v_lshlrev_b32_e32 v128, 4, v128
	v_lshl_add_u64 v[134:135], s[42:43], 0, v[130:131]
	v_and_b32_e32 v128, 0x70, v128
	v_lshl_add_u64 v[146:147], v[134:135], 0, v[128:129]
	v_add_co_u32_e32 v138, vcc, 0x20000, v146
	v_lshl_add_u64 v[130:131], s[44:45], 0, v[130:131]
	s_nop 0
	v_addc_co_u32_e32 v139, vcc, 0, v147, vcc
	v_add_co_u32_e32 v142, vcc, 0x40000, v146
	global_load_dwordx4 v[134:137], v[146:147], off
	s_nop 0
	v_addc_co_u32_e32 v143, vcc, 0, v147, vcc
	v_add_co_u32_e32 v146, vcc, 0x60000, v146
	v_lshl_add_u64 v[130:131], v[130:131], 0, v[128:129]
	s_nop 0
	v_addc_co_u32_e32 v147, vcc, 0, v147, vcc
	v_add_co_u32_e32 v154, vcc, s72, v130
	global_load_dwordx4 v[138:141], v[138:139], off
	s_nop 0
	global_load_dwordx4 v[142:145], v[142:143], off
	v_addc_co_u32_e32 v155, vcc, 0, v131, vcc
	v_add_co_u32_e32 v158, vcc, 0x40000, v130
	global_load_dwordx4 v[146:149], v[146:147], off
	s_nop 0
	global_load_dwordx4 v[150:153], v[130:131], off
	v_addc_co_u32_e32 v159, vcc, 0, v131, vcc
	v_add_co_u32_e32 v162, vcc, 0x60000, v130
	global_load_dwordx4 v[154:157], v[154:155], off
	s_nop 0
	global_load_dwordx4 v[158:161], v[158:159], off
	v_addc_co_u32_e32 v163, vcc, 0, v131, vcc
	v_add_co_u32_e32 v166, vcc, 0x80000, v130
	s_nop 1
	v_addc_co_u32_e32 v167, vcc, 0, v131, vcc
	v_add_co_u32_e32 v170, vcc, 0xa0000, v130
	global_load_dwordx4 v[162:165], v[162:163], off
	s_nop 0
	global_load_dwordx4 v[166:169], v[166:167], off
	v_addc_co_u32_e32 v171, vcc, 0, v131, vcc
	v_add_co_u32_e32 v174, vcc, 0xc0000, v130
	s_nop 1
	v_addc_co_u32_e32 v175, vcc, 0, v131, vcc
	v_add_co_u32_e32 v130, vcc, 0xe0000, v130
	global_load_dwordx4 v[170:173], v[170:171], off
	s_nop 0
	global_load_dwordx4 v[174:177], v[174:175], off
	v_addc_co_u32_e32 v131, vcc, 0, v131, vcc
	global_load_dwordx4 v[178:181], v[130:131], off

;   DI const float* ab_b_if() const { return (const float*)sp[9]; }
; DI float logsig(float v) { return fminf(v, 0.f) - log1pf(__expf(-fabsf(v))); }
; DI void epi_in0(const Params& p, float* Cs, int m0, int n0) {
;     ...
;     for (int sidx = w; sidx < 32; sidx += 4) {
;       const int ch = sidx & 1, dh = sidx >> 1, dir = dh >> 3, head = dh & 7, row = ch * 64 + lane;
;       const float ig = Cs[row * CLD + dir * 8 + head] + p.ab_b_if()[dir * 8 + head];
;       const float f = logsig(Cs[row * CLD + 16 + dir * 8 + head] + p.ab_b_if()[16 + dir * 8 + head]);
;       float bc = f;
;       for (int off = 1; off < 64; off <<= 1) {
;         const float yu = __shfl_up(bc, off), yd = __shfl_down(bc, off);
;         const bool ok = dir == 0 ? lane >= off : lane + off < 64;
.LBB0_960:
	v_ashrrev_i32_e32 v227, 4, v188
	v_bfe_u32 v226, v188, 1, 3
	v_and_or_b32 v128, v199, 64, v133
	v_lshlrev_b32_e32 v201, 3, v227
	v_mul_u32_u24_e32 v182, 0x210, v128
	v_lshlrev_b32_e32 v183, 5, v227
	v_lshlrev_b32_e32 v204, 2, v226
	v_add3_u32 v182, v182, v183, v204
	v_or_b32_e32 v204, v201, v226
	v_ashrrev_i32_e32 v205, 31, v204
	s_waitcnt lgkmcnt(0)
	v_lshl_add_u64 v[206:207], v[204:205], 2, v[130:131]
	v_ashrrev_i32_e32 v205, 31, v201
	v_lshl_add_u64 v[204:205], v[204:205], 2, v[130:131]
	global_load_dword v228, v[206:207], off
	global_load_dword v201, v[204:205], off offset:64
	ds_read2_b32 v[182:183], v182 offset1:16
	v_add_u32_e32 v199, 0x100, v199
	s_waitcnt vmcnt(0) lgkmcnt(0)
	v_add_f32_e32 v182, v182, v228
	v_add_f32_e32 v183, v183, v201
	v_min_f32_e32 v201, 0, v183
	v_mul_f32_e64 v183, |v183|, s22
	v_exp_f32_e32 v183, v183
	s_nop 0
	v_add_f32_e32 v206, 1.0, v183
	v_add_f32_e32 v204, -1.0, v206
	v_sub_f32_e32 v205, v204, v206
	v_add_f32_e32 v205, 1.0, v205
	v_sub_f32_e32 v204, v183, v204
	v_add_f32_e32 v207, v204, v205
	v_frexp_mant_f32_e32 v204, v206
	v_cmp_gt_f32_e64 s[0:1], s23, v204
	v_cvt_f64_f32_e32 v[204:205], v206
	v_frexp_exp_i32_f64_e32 v204, v[204:205]
	v_subbrev_co_u32_e64 v204, s[0:1], 0, v204, s[0:1]
	v_sub_u32_e32 v205, 0, v204
	v_ldexp_f32 v206, v206, v205
	v_ldexp_f32 v205, v207, v205
	v_add_f32_e32 v207, -1.0, v206
	v_add_f32_e32 v209, 1.0, v207
	v_sub_f32_e32 v209, v206, v209
	v_add_f32_e32 v209, v205, v209
	v_add_f32_e32 v210, v207, v209
	v_sub_f32_e32 v207, v210, v207
	v_sub_f32_e32 v207, v209, v207
	v_add_f32_e32 v209, 1.0, v206
	v_add_f32_e32 v211, -1.0, v209
	v_sub_f32_e32 v206, v206, v211
	v_add_f32_e32 v205, v205, v206
	v_add_f32_e32 v206, v209, v205
	v_sub_f32_e32 v209, v206, v209
	v_sub_f32_e32 v205, v205, v209
	v_rcp_f32_e32 v209, v206
	v_cvt_f32_i32_e32 v204, v204
	v_cmp_neq_f32_e64 s[0:1], s25, v183
	v_cmp_gt_u32_e64 s[22:23], 16, v188
	v_mul_f32_e32 v211, v210, v209
	v_mul_f32_e32 v214, v206, v211
	v_fma_f32 v229, v211, v206, -v214
	v_fmac_f32_e32 v229, v211, v205
	v_add_f32_e32 v230, v214, v229
	v_sub_f32_e32 v231, v210, v230
	v_sub_f32_e32 v210, v210, v231
	v_sub_f32_e32 v214, v230, v214
	v_sub_f32_e32 v210, v210, v230
	v_add_f32_e32 v207, v207, v210
	v_sub_f32_e32 v210, v214, v229
	v_add_f32_e32 v207, v210, v207
	v_add_f32_e32 v210, v231, v207
	v_mul_f32_e32 v214, v209, v210
	v_mul_f32_e32 v229, v206, v214
	v_fma_f32 v206, v214, v206, -v229
	v_fmac_f32_e32 v206, v214, v205
	v_sub_f32_e32 v205, v231, v210
	v_add_f32_e32 v205, v207, v205
	v_add_f32_e32 v207, v229, v206
	v_sub_f32_e32 v230, v210, v207
	v_sub_f32_e32 v210, v210, v230
	v_sub_f32_e32 v229, v207, v229
	v_sub_f32_e32 v207, v210, v207
	v_add_f32_e32 v205, v205, v207
	v_sub_f32_e32 v206, v229, v206
	v_add_f32_e32 v205, v206, v205
	v_add_f32_e32 v206, v211, v214
	v_add_f32_e32 v205, v230, v205
	v_sub_f32_e32 v207, v206, v211
	v_mul_f32_e32 v205, v209, v205
	v_sub_f32_e32 v207, v214, v207
	v_add_f32_e32 v205, v207, v205
	v_mul_f32_e32 v211, 0x3f317218, v204
	v_add_f32_e32 v207, v206, v205
	v_fma_f32 v214, v204, s24, -v211
	v_mul_f32_e32 v209, v207, v207
	v_fmac_f32_e32 v214, 0xb102e308, v204
	v_sub_f32_e32 v204, v207, v206
	v_fmamk_f32 v210, v209, 0x3e9b6dac, v232
	v_sub_f32_e32 v204, v205, v204
	v_add_f32_e32 v205, v211, v214
	v_fmaak_f32 v210, v209, v210, 0x3f2aaada
	v_sub_f32_e32 v206, v205, v211
	v_ldexp_f32 v211, v207, 1
	v_mul_f32_e32 v207, v207, v209
	v_mul_f32_e32 v207, v207, v210
	v_add_f32_e32 v209, v211, v207
	v_sub_f32_e32 v210, v209, v211
	v_ldexp_f32 v204, v204, 1
	v_sub_f32_e32 v207, v207, v210
	v_add_f32_e32 v204, v204, v207
	v_add_f32_e32 v207, v209, v204
	v_sub_f32_e32 v209, v207, v209
	v_sub_f32_e32 v204, v204, v209
	v_add_f32_e32 v209, v205, v207
	v_sub_f32_e32 v210, v209, v205
	v_sub_f32_e32 v211, v209, v210
	v_sub_f32_e32 v206, v214, v206
	v_sub_f32_e32 v205, v205, v211
	v_sub_f32_e32 v207, v207, v210
	v_add_f32_e32 v205, v207, v205
	v_add_f32_e32 v207, v206, v204
	v_sub_f32_e32 v210, v207, v206
	v_sub_f32_e32 v211, v207, v210
	v_sub_f32_e32 v206, v206, v211
	v_sub_f32_e32 v204, v204, v210
	v_add_f32_e32 v205, v207, v205
	v_add_f32_e32 v204, v204, v206
	v_add_f32_e32 v206, v209, v205
	v_sub_f32_e32 v207, v206, v209
	v_sub_f32_e32 v205, v205, v207
	v_add_f32_e32 v204, v204, v205
	v_add_f32_e32 v204, v206, v204
	v_cndmask_b32_e64 v204, v233, v204, s[0:1]
	v_cmp_ngt_f32_e64 s[0:1], -1.0, v183
	v_cndmask_b32_e64 v205, 63, 0, s[22:23]
	v_cmp_eq_u32_e64 s[24:25], v133, v205
	v_cndmask_b32_e64 v204, v234, v204, s[0:1]
	v_cmp_neq_f32_e64 s[0:1], -1.0, v183
	s_xor_b64 s[34:35], s[20:21], s[22:23]
	s_nop 0
	v_cndmask_b32_e64 v204, v242, v204, s[0:1]
	v_cmp_lt_f32_e64 s[0:1], |v183|, s17
	s_nop 1
	v_cndmask_b32_e64 v183, v204, v183, s[0:1]
	v_sub_f32_e32 v183, v201, v183
	ds_bpermute_b32 v201, v184, v183
	ds_bpermute_b32 v204, v185, v183
	v_readlane_b32 s0, v254, 29
	v_readlane_b32 s1, v254, 30
	s_waitcnt lgkmcnt(0)
; DI void epi_in0(const Params& p, float* Cs, int m0, int n0) {
;     ...
;       float bc = f;
;       for (int off = 1; off < 64; off <<= 1) {
;         const float yu = __shfl_up(bc, off), yd = __shfl_down(bc, off);
;         const bool ok = dir == 0 ? lane >= off : lane + off < 64;
;         if (ok) bc += dir == 0 ? yu : yd;
;       }
;       const float gs = ig - bc;
;       float cm = gs;
;       for (int off = 1; off < 64; off <<= 1) {
;         const float yu = __shfl_up(cm, off), yd = __shfl_down(cm, off);
;         const bool ok = dir == 0 ? lane >= off : lane + off < 64;
;         if (ok) cm = fmaxf(cm, dir == 0 ? yu : yd);
;       }
;       const long o = ((long)(dir * GB + bg) * 8 + head) * T + t0 + row;
;       gb[o] = bc; gsv[o] = gs; gc[o] = cm;
	v_cndmask_b32_e64 v201, v204, v201, s[22:23]
	v_add_f32_e32 v201, v183, v201
	v_cndmask_b32_e64 v183, v201, v183, s[24:25]
	ds_bpermute_b32 v201, v186, v183
	ds_bpermute_b32 v204, v187, v183
	v_cndmask_b32_e64 v205, 0, 1, s[0:1]
	v_readlane_b32 s0, v255, 5
	v_readlane_b32 s1, v255, 6
	s_waitcnt lgkmcnt(0)
	v_cndmask_b32_e64 v201, v204, v201, s[22:23]
	v_cndmask_b32_e64 v206, 0, 1, s[0:1]
	v_cndmask_b32_e64 v205, v206, v205, s[22:23]
	v_and_b32_e32 v205, 1, v205
	v_cmp_eq_u32_e64 s[26:27], 1, v205
	v_add_f32_e32 v201, v183, v201
	v_readlane_b32 s0, v255, 3
	v_cndmask_b32_e64 v183, v183, v201, s[26:27]
	ds_bpermute_b32 v201, v189, v183
	ds_bpermute_b32 v204, v192, v183
	v_readlane_b32 s1, v255, 4
	s_waitcnt lgkmcnt(0)
	v_cndmask_b32_e64 v201, v204, v201, s[22:23]
	v_cndmask_b32_e64 v205, 0, 1, s[0:1]
	v_readlane_b32 s0, v255, 9
	v_readlane_b32 s1, v255, 10
	v_add_f32_e32 v201, v183, v201
	s_nop 0
	v_cndmask_b32_e64 v206, 0, 1, s[0:1]
	v_cndmask_b32_e64 v205, v206, v205, s[22:23]
	v_and_b32_e32 v205, 1, v205
	v_cmp_eq_u32_e64 s[28:29], 1, v205
	v_cndmask_b32_e64 v205, 0, 1, s[6:7]
	v_cndmask_b32_e64 v206, 0, 1, s[2:3]
	v_cndmask_b32_e64 v183, v183, v201, s[28:29]
	ds_bpermute_b32 v201, v193, v183
	ds_bpermute_b32 v204, v194, v183
	v_cndmask_b32_e64 v205, v206, v205, s[22:23]
	v_and_b32_e32 v205, 1, v205
	v_cmp_eq_u32_e64 s[0:1], 1, v205
	v_cndmask_b32_e64 v205, 0, 1, vcc
	s_waitcnt lgkmcnt(0)
	v_cndmask_b32_e64 v201, v204, v201, s[22:23]
	v_add_f32_e32 v201, v183, v201
	v_cndmask_b32_e64 v183, v183, v201, s[0:1]
	ds_bpermute_b32 v201, v195, v183
	ds_bpermute_b32 v204, v196, v183
	v_cndmask_b32_e64 v206, 0, 1, s[18:19]
	v_cndmask_b32_e64 v205, v206, v205, s[22:23]
	v_and_b32_e32 v205, 1, v205
	v_cmp_eq_u32_e64 s[30:31], 1, v205
	s_waitcnt lgkmcnt(0)
	v_cndmask_b32_e64 v201, v204, v201, s[22:23]
	v_add_f32_e32 v201, v183, v201
	v_cndmask_b32_e64 v183, v183, v201, s[30:31]
	ds_bpermute_b32 v201, v197, v183
	ds_bpermute_b32 v204, v198, v183
	s_waitcnt lgkmcnt(0)
	v_cndmask_b32_e64 v201, v204, v201, s[22:23]
	v_add_f32_e32 v201, v183, v201
	v_cndmask_b32_e64 v201, v183, v201, s[34:35]
	v_sub_f32_e32 v206, v182, v201
	ds_bpermute_b32 v182, v184, v206
	ds_bpermute_b32 v183, v185, v206
	s_waitcnt lgkmcnt(0)
	v_cndmask_b32_e64 v182, v183, v182, s[22:23]
	v_max_f32_e32 v182, v182, v182
	v_max_f32_e32 v182, v206, v182
	v_cndmask_b32_e64 v182, v182, v206, s[24:25]
	ds_bpermute_b32 v183, v186, v182
	ds_bpermute_b32 v204, v187, v182
	s_mov_b32 s25, 0x7f800000
	s_mov_b32 s24, 0x3f317218
	s_waitcnt lgkmcnt(0)
	v_cndmask_b32_e64 v183, v204, v183, s[22:23]
	v_max_f32_e32 v183, v183, v183
	v_max_f32_e32 v183, v182, v183
	v_cndmask_b32_e64 v182, v182, v183, s[26:27]
	ds_bpermute_b32 v183, v189, v182
	ds_bpermute_b32 v204, v192, v182
	s_waitcnt lgkmcnt(0)
	v_cndmask_b32_e64 v183, v204, v183, s[22:23]
	v_max_f32_e32 v183, v183, v183
	v_max_f32_e32 v183, v182, v183
	v_cndmask_b32_e64 v182, v182, v183, s[28:29]
	ds_bpermute_b32 v183, v193, v182
	ds_bpermute_b32 v204, v194, v182
	s_waitcnt lgkmcnt(0)
	v_cndmask_b32_e64 v183, v204, v183, s[22:23]
	v_max_f32_e32 v183, v183, v183
	v_max_f32_e32 v183, v182, v183
	v_cndmask_b32_e64 v182, v182, v183, s[0:1]
	ds_bpermute_b32 v183, v195, v182
	ds_bpermute_b32 v204, v196, v182
	s_waitcnt lgkmcnt(0)
	v_cndmask_b32_e64 v183, v204, v183, s[22:23]
	v_max_f32_e32 v183, v183, v183
	v_max_f32_e32 v183, v182, v183
	v_cndmask_b32_e64 v182, v182, v183, s[30:31]
	ds_bpermute_b32 v183, v197, v182
	ds_bpermute_b32 v204, v198, v182
	s_waitcnt lgkmcnt(0)
	v_cndmask_b32_e64 v183, v204, v183, s[22:23]
	v_max_f32_e32 v183, v183, v183
	v_max_f32_e32 v204, v182, v182
	v_max_f32_e32 v183, v204, v183
	v_cndmask_b32_e64 v207, v182, v183, s[34:35]
	v_lshl_add_u32 v182, v227, 1, s13
	v_ashrrev_i32_e32 v204, 31, v182
	v_lshl_or_b32 v205, v182, 3, v226
	v_lshl_add_u64 v[182:183], v[128:129], 0, s[48:49]
	v_mad_u64_u32 v[182:183], s[0:1], v205, s60, v[182:183]
	v_mad_i32_i24 v183, v204, s60, v183
	v_lshlrev_b64 v[182:183], 2, v[182:183]
	v_lshl_add_u64 v[204:205], s[74:75], 0, v[182:183]
	v_add_u32_e32 v128, 4, v188
	v_cmp_lt_i32_e64 s[0:1], 27, v188
	s_mov_b32 s23, 0x3f2aaaab
	s_mov_b32 s22, 0xbfb8aa3b
	global_store_dword v[204:205], v201, off
	v_lshl_add_u64 v[204:205], s[78:79], 0, v[182:183]
	v_lshl_add_u64 v[182:183], s[80:81], 0, v[182:183]
	s_or_b64 s[94:95], s[0:1], s[94:95]
	v_mov_b32_e32 v188, v128
	global_store_dword v[204:205], v206, off
	global_store_dword v[182:183], v207, off
	s_andn2_b64 exec, exec, s[94:95]
	s_cbranch_execnz .LBB0_960

;   DI const float* c() const { return (const float*)sp[1]; }
; DI int TID() { int t = threadIdx.x; asm volatile("" : "+v"(t)); return t; }
; DI bf16x8 pack8f(const float* v) { u32x4 w = {cvtpk(v[0], v[1]), cvtpk(v[2], v[3]), cvtpk(v[4], v[5]), cvtpk(v[6], v[7])}; return __builtin_bit_cast(bf16x8, w); }
; DI void store_T(const float* Cs, int cb, int nc, bfu* dst, long ldT, float scale, const float* rs = nullptr) {
;   for (int u = TID(); u < nc * 16; u += NT) {
;     int c = u % nc, rc = (u / nc) * 8; float v[8];
;     for (int j = 0; j < 8; ++j) v[j] = Cs[(rc + j) * CLD + cb + c] * (rs ? scale * rs[rc + j] : scale);
;     st8(dst + c * ldT + rc, pack8f(v));
;   }
.LBB0_977:
	v_ashrrev_i32_e32 v133, 31, v131
	v_lshrrev_b32_e32 v133, 25, v133
	v_add_u32_e32 v182, 0x100, v131
	v_add_u32_e32 v133, v131, v133
	v_cmp_lt_i32_e32 vcc, s87, v131
	v_mov_b32_e32 v131, v182
	v_ashrrev_i32_e32 v133, 7, v133
	v_mad_u64_u32 v[184:185], s[18:19], v133, s24, v[130:131]
	v_lshlrev_b32_e32 v182, 3, v133
	v_mad_u64_u32 v[186:187], s[18:19], v133, s25, v[128:129]
	v_add_u32_e32 v133, 0x400, v184
	v_add_u32_e32 v192, 0x800, v184
	v_add_u32_e32 v194, 0xc00, v184
	ds_read2_b32 v[188:189], v184 offset1:132
	ds_read2_b32 v[184:185], v133 offset0:8 offset1:140
	ds_read2_b32 v[192:193], v192 offset0:16 offset1:148
	ds_read2_b32 v[194:195], v194 offset0:24 offset1:156
	v_ashrrev_i32_e32 v187, 31, v186
	v_ashrrev_i32_e32 v183, 31, v182
	v_lshl_add_u64 v[186:187], s[2:3], 0, v[186:187]
	s_or_b64 s[6:7], vcc, s[6:7]
	v_add_u32_e32 v128, 0x120000, v128
	v_add_u32_e32 v130, 0x400, v130
	v_lshl_add_u64 v[186:187], v[182:183], 1, v[186:187]
	s_waitcnt lgkmcnt(0)
	v_cvt_pk_bf16_f32 v182, v188, v189
	v_cvt_pk_bf16_f32 v183, v184, v185
	v_cvt_pk_bf16_f32 v184, v192, v193
	v_cvt_pk_bf16_f32 v185, v194, v195
	global_store_dwordx4 v[186:187], v[182:185], off
	s_andn2_b64 exec, exec, s[6:7]
	s_cbranch_execnz .LBB0_977

; DI int TID() { int t = threadIdx.x; asm volatile("" : "+v"(t)); return t; }
; DI bf16x8 pack8f(const float* v) { u32x4 w = {cvtpk(v[0], v[1]), cvtpk(v[2], v[3]), cvtpk(v[4], v[5]), cvtpk(v[6], v[7])}; return __builtin_bit_cast(bf16x8, w); }
; DI void store_R(const float* Cs, int cb, int nc, bfu* dst, long ld, float scale, const float* rs = nullptr) {
;   const int cpr = nc >> 3;
;   for (int u = TID(); u < 128 * cpr; u += NT) {
;     int row = u / cpr, c8 = (u % cpr) * 8; float v[8]; ldrow8(Cs, row, cb + c8, v);
;     float s = rs ? scale * rs[row] : scale;
;     for (int j = 0; j < 8; ++j) v[j] *= s;
;     st8(dst + row * ld + c8, pack8f(v));
;   }
; }
; DI void epi_in0(const Params& p, float* Cs, int m0, int n0) {
;     ...
;     store_R(Cs, 0, 128, (bfu*)(G + L0_MQ) + ((long)(bg * 8 + head) * T + t0) * 128, 128, 0.08838834764831845f);
.LBB0_992:
	v_ashrrev_i32_e32 v133, 31, v128
	v_lshrrev_b32_e32 v133, 28, v133
	v_add_u32_e32 v133, v128, v133
	v_add_u32_e32 v182, 0x100, v128
	v_ashrrev_i32_e32 v192, 4, v133
	v_and_b32_e32 v133, -16, v133
	v_cmp_lt_i32_e32 vcc, s87, v128
	v_mov_b32_e32 v128, v182
	v_lshlrev_b32_e32 v182, 7, v192
	v_add_u32_e32 v133, v131, v133
	v_sub_u32_e32 v194, v130, v182
	ds_read_b128 v[182:185], v133
	ds_read_b128 v[186:189], v133 offset:16
	v_ashrrev_i32_e32 v193, 31, v192
	v_lshlrev_b64 v[192:193], 8, v[192:193]
	v_lshl_add_u64 v[192:193], s[2:3], 0, v[192:193]
	v_ashrrev_i32_e32 v195, 31, v194
	s_waitcnt lgkmcnt(0)
	v_pk_mul_f32 v[182:183], v[182:183], s[26:27] op_sel_hi:[1,0]
	v_pk_mul_f32 v[184:185], v[184:185], s[26:27] op_sel_hi:[1,0]
	v_pk_mul_f32 v[186:187], v[186:187], s[26:27] op_sel_hi:[1,0]
	v_pk_mul_f32 v[188:189], v[188:189], s[26:27] op_sel_hi:[1,0]
	s_or_b64 s[6:7], vcc, s[6:7]
	v_add_u32_e32 v131, 0x2000, v131
	v_add_u32_e32 v130, 0x800, v130
	v_lshl_add_u64 v[192:193], v[194:195], 1, v[192:193]
	v_cvt_pk_bf16_f32 v182, v182, v183
	v_cvt_pk_bf16_f32 v183, v184, v185
	v_cvt_pk_bf16_f32 v184, v186, v187
	v_cvt_pk_bf16_f32 v185, v188, v189
	global_store_dwordx4 v[192:193], v[182:185], off
	s_andn2_b64 exec, exec, s[6:7]
	s_cbranch_execnz .LBB0_992

; DI int TID() { int t = threadIdx.x; asm volatile("" : "+v"(t)); return t; }
; DI bf16x8 pack8f(const float* v) { u32x4 w = {cvtpk(v[0], v[1]), cvtpk(v[2], v[3]), cvtpk(v[4], v[5]), cvtpk(v[6], v[7])}; return __builtin_bit_cast(bf16x8, w); }
; DI void store_R(const float* Cs, int cb, int nc, bfu* dst, long ld, float scale, const float* rs = nullptr) {
;   const int cpr = nc >> 3;
;   for (int u = TID(); u < 128 * cpr; u += NT) {
;     int row = u / cpr, c8 = (u % cpr) * 8; float v[8]; ldrow8(Cs, row, cb + c8, v);
;     float s = rs ? scale * rs[row] : scale;
;     for (int j = 0; j < 8; ++j) v[j] *= s;
;     st8(dst + row * ld + c8, pack8f(v));
;   }
; }
; DI void epi_in0(const Params& p, float* Cs, int m0, int n0) {
;     ...
;     for (int m = 0; m < 2; ++m) store_R(Cs, m * 64, 64, dst + ((long)(bg * 32 + head * 2 + m) * T + t0) * 64, 64, isq ? 0.125f * LOG2E : 1.f);
.LBB0_1012:
	v_ashrrev_i32_e32 v183, 31, v133
	v_lshrrev_b32_e32 v183, 29, v183
	v_add_u32_e32 v183, v133, v183
	v_ashrrev_i32_e32 v188, 3, v183
	v_add_u32_e32 v184, 0x100, v133
	v_mad_u64_u32 v[192:193], s[20:21], v188, s22, v[128:129]
	v_cmp_lt_i32_e32 vcc, s28, v133
	v_mov_b32_e32 v133, v184
	ds_read_b128 v[184:187], v192
	ds_read_b128 v[192:195], v192 offset:16
	v_lshlrev_b32_e32 v183, 6, v188
	v_ashrrev_i32_e32 v189, 31, v188
	v_sub_u32_e32 v196, v182, v183
	v_lshlrev_b64 v[188:189], 7, v[188:189]
	v_lshl_add_u64 v[188:189], s[2:3], 0, v[188:189]
	v_ashrrev_i32_e32 v197, 31, v196
	s_waitcnt lgkmcnt(0)
	v_pk_mul_f32 v[184:185], v[130:131], v[184:185]
	v_pk_mul_f32 v[186:187], v[130:131], v[186:187]
	v_pk_mul_f32 v[192:193], v[130:131], v[192:193]
	v_pk_mul_f32 v[194:195], v[130:131], v[194:195]
	s_or_b64 s[6:7], vcc, s[6:7]
	v_add_u32_e32 v128, 0x2000, v128
	v_add_u32_e32 v182, 0x800, v182
	v_lshl_add_u64 v[188:189], v[196:197], 1, v[188:189]
	v_cvt_pk_bf16_f32 v184, v184, v185
	v_cvt_pk_bf16_f32 v185, v186, v187
	v_cvt_pk_bf16_f32 v186, v192, v193
	v_cvt_pk_bf16_f32 v187, v194, v195
	global_store_dwordx4 v[188:189], v[184:187], off
	s_andn2_b64 exec, exec, s[6:7]
	s_cbranch_execnz .LBB0_1012

; DI int TID() { int t = threadIdx.x; asm volatile("" : "+v"(t)); return t; }
; DI bf16x8 pack8f(const float* v) { u32x4 w = {cvtpk(v[0], v[1]), cvtpk(v[2], v[3]), cvtpk(v[4], v[5]), cvtpk(v[6], v[7])}; return __builtin_bit_cast(bf16x8, w); }
; DI void store_R(const float* Cs, int cb, int nc, bfu* dst, long ld, float scale, const float* rs = nullptr) {
;   const int cpr = nc >> 3;
;   for (int u = TID(); u < 128 * cpr; u += NT) {
;     int row = u / cpr, c8 = (u % cpr) * 8; float v[8]; ldrow8(Cs, row, cb + c8, v);
;     float s = rs ? scale * rs[row] : scale;
;     for (int j = 0; j < 8; ++j) v[j] *= s;
;     st8(dst + row * ld + c8, pack8f(v));
;   }
; }
; DI void epi_in0(const Params& p, float* Cs, int m0, int n0) {
;     ...
;     for (int m = 0; m < 2; ++m) store_R(Cs, m * 64, 64, dst + ((long)(bg * 32 + head * 2 + m) * T + t0) * 64, 64, isq ? 0.125f * LOG2E : 1.f);
.LBB0_1015:
	v_ashrrev_i32_e32 v183, 31, v133
	v_lshrrev_b32_e32 v183, 29, v183
	v_add_u32_e32 v183, v133, v183
	v_ashrrev_i32_e32 v188, 3, v183
	v_add_u32_e32 v184, 0x100, v133
	v_mad_u64_u32 v[192:193], s[18:19], v188, s20, v[128:129]
	v_cmp_lt_i32_e32 vcc, s28, v133
	v_mov_b32_e32 v133, v184
	ds_read_b128 v[184:187], v192
	ds_read_b128 v[192:195], v192 offset:16
	v_lshlrev_b32_e32 v183, 6, v188
	v_ashrrev_i32_e32 v189, 31, v188
	v_sub_u32_e32 v196, v182, v183
	v_lshlrev_b64 v[188:189], 7, v[188:189]
	v_lshl_add_u64 v[188:189], s[2:3], 0, v[188:189]
	v_ashrrev_i32_e32 v197, 31, v196
	s_waitcnt lgkmcnt(0)
	v_pk_mul_f32 v[184:185], v[130:131], v[184:185]
	v_pk_mul_f32 v[186:187], v[130:131], v[186:187]
	v_pk_mul_f32 v[192:193], v[130:131], v[192:193]
	v_pk_mul_f32 v[194:195], v[130:131], v[194:195]
	s_or_b64 s[6:7], vcc, s[6:7]
	v_add_u32_e32 v128, 0x2000, v128
	v_add_u32_e32 v182, 0x800, v182
	v_lshl_add_u64 v[188:189], v[196:197], 1, v[188:189]
	v_cvt_pk_bf16_f32 v184, v184, v185
	v_cvt_pk_bf16_f32 v185, v186, v187
	v_cvt_pk_bf16_f32 v186, v192, v193
	v_cvt_pk_bf16_f32 v187, v194, v195
	global_store_dwordx4 v[188:189], v[184:187], off
	s_andn2_b64 exec, exec, s[6:7]
	s_cbranch_execnz .LBB0_1015

;   DI const float* ab_b_if() const { return (const float*)sp[9]; }
; DI float logsig(float v) { return fminf(v, 0.f) - log1pf(__expf(-fabsf(v))); }
; DI void epi_in0(const Params& p, float* Cs, int m0, int n0) {
;     ...
;     for (int sidx = w; sidx < 32; sidx += 4) {
;       const int ch = sidx & 1, dh = sidx >> 1, dir = dh >> 3, head = dh & 7, row = ch * 64 + lane;
;       const float ig = Cs[row * CLD + dir * 8 + head] + p.ab_b_if()[dir * 8 + head];
;       const float f = logsig(Cs[row * CLD + 16 + dir * 8 + head] + p.ab_b_if()[16 + dir * 8 + head]);
;       float bc = f;
;       for (int off = 1; off < 64; off <<= 1) {
;         const float yu = __shfl_up(bc, off), yd = __shfl_down(bc, off);
;         const bool ok = dir == 0 ? lane >= off : lane + off < 64;
.LBB0_1040:
	v_ashrrev_i32_e32 v20, 4, v9
	v_bfe_u32 v19, v9, 1, 3
	v_lshlrev_b32_e32 v26, 3, v20
	v_or_b32_e32 v22, v26, v19
	v_ashrrev_i32_e32 v23, 31, v22
	v_and_or_b32 v128, v18, 64, v4
	s_waitcnt lgkmcnt(0)
	v_lshl_add_u64 v[24:25], v[22:23], 2, v[0:1]
	v_ashrrev_i32_e32 v23, 31, v26
	v_mul_u32_u24_e32 v2, 0x210, v128
	v_lshlrev_b32_e32 v3, 5, v20
	v_lshlrev_b32_e32 v21, 2, v19
	v_lshl_add_u64 v[22:23], v[22:23], 2, v[0:1]
	v_add3_u32 v2, v2, v3, v21
	global_load_dword v21, v[24:25], off
	ds_read2_b32 v[2:3], v2 offset1:16
	global_load_dword v22, v[22:23], off offset:64
	v_add_u32_e32 v18, 0x100, v18
	s_waitcnt vmcnt(0) lgkmcnt(0)
	v_add_f32_e32 v2, v2, v21
	v_add_f32_e32 v3, v3, v22
	v_min_f32_e32 v24, 0, v3
	v_mul_f32_e64 v3, |v3|, s22
	v_exp_f32_e32 v3, v3
	s_nop 0
	v_add_f32_e32 v25, 1.0, v3
	v_add_f32_e32 v22, -1.0, v25
	v_sub_f32_e32 v23, v22, v25
	v_add_f32_e32 v23, 1.0, v23
	v_sub_f32_e32 v22, v3, v22
	v_add_f32_e32 v26, v22, v23
	v_frexp_mant_f32_e32 v22, v25
	v_cmp_gt_f32_e64 s[0:1], s23, v22
	v_cvt_f64_f32_e32 v[22:23], v25
	v_frexp_exp_i32_f64_e32 v22, v[22:23]
	v_subbrev_co_u32_e64 v22, s[0:1], 0, v22, s[0:1]
	v_sub_u32_e32 v23, 0, v22
	v_ldexp_f32 v25, v25, v23
	v_ldexp_f32 v23, v26, v23
	v_add_f32_e32 v26, -1.0, v25
	v_add_f32_e32 v27, 1.0, v26
	v_sub_f32_e32 v27, v25, v27
	v_add_f32_e32 v27, v23, v27
	v_add_f32_e32 v28, v26, v27
	v_sub_f32_e32 v26, v28, v26
	v_sub_f32_e32 v26, v27, v26
	v_add_f32_e32 v27, 1.0, v25
	v_add_f32_e32 v29, -1.0, v27
	v_sub_f32_e32 v25, v25, v29
	v_add_f32_e32 v23, v23, v25
	v_add_f32_e32 v25, v27, v23
	v_sub_f32_e32 v27, v25, v27
	v_sub_f32_e32 v23, v23, v27
	v_rcp_f32_e32 v27, v25
	v_cvt_f32_i32_e32 v22, v22
	v_cmp_neq_f32_e64 s[0:1], s15, v3
	v_cmp_gt_u32_e64 s[22:23], 16, v9
	v_mul_f32_e32 v29, v28, v27
	v_mul_f32_e32 v30, v25, v29
	v_fma_f32 v31, v29, v25, -v30
	v_fmac_f32_e32 v31, v29, v23
	v_add_f32_e32 v32, v30, v31
	v_sub_f32_e32 v33, v28, v32
	v_sub_f32_e32 v28, v28, v33
	v_sub_f32_e32 v30, v32, v30
	v_sub_f32_e32 v28, v28, v32
	v_add_f32_e32 v26, v26, v28
	v_sub_f32_e32 v28, v30, v31
	v_add_f32_e32 v26, v28, v26
	v_add_f32_e32 v28, v33, v26
	v_mul_f32_e32 v30, v27, v28
	v_mul_f32_e32 v31, v25, v30
	v_fma_f32 v25, v30, v25, -v31
	v_fmac_f32_e32 v25, v30, v23
	v_sub_f32_e32 v23, v33, v28
	v_add_f32_e32 v23, v26, v23
	v_add_f32_e32 v26, v31, v25
	v_sub_f32_e32 v32, v28, v26
	v_sub_f32_e32 v28, v28, v32
	v_sub_f32_e32 v31, v26, v31
	v_sub_f32_e32 v26, v28, v26
	v_add_f32_e32 v23, v23, v26
	v_sub_f32_e32 v25, v31, v25
	v_add_f32_e32 v23, v25, v23
	v_add_f32_e32 v25, v29, v30
	v_add_f32_e32 v23, v32, v23
	v_sub_f32_e32 v26, v25, v29
	v_mul_f32_e32 v23, v27, v23
	v_sub_f32_e32 v26, v30, v26
	v_add_f32_e32 v23, v26, v23
	v_mul_f32_e32 v29, 0x3f317218, v22
	v_add_f32_e32 v26, v25, v23
	v_fma_f32 v30, v22, s71, -v29
	v_mul_f32_e32 v27, v26, v26
	v_fmac_f32_e32 v30, 0xb102e308, v22
	v_sub_f32_e32 v22, v26, v25
	v_fmamk_f32 v28, v27, 0x3e9b6dac, v201
	v_sub_f32_e32 v22, v23, v22
	v_add_f32_e32 v23, v29, v30
	v_fmaak_f32 v28, v27, v28, 0x3f2aaada
	v_sub_f32_e32 v25, v23, v29
	v_ldexp_f32 v29, v26, 1
	v_mul_f32_e32 v26, v26, v27
	v_mul_f32_e32 v26, v26, v28
	v_add_f32_e32 v27, v29, v26
	v_sub_f32_e32 v28, v27, v29
	v_ldexp_f32 v22, v22, 1
	v_sub_f32_e32 v26, v26, v28
	v_add_f32_e32 v22, v22, v26
	v_add_f32_e32 v26, v27, v22
	v_sub_f32_e32 v27, v26, v27
	v_sub_f32_e32 v22, v22, v27
	v_add_f32_e32 v27, v23, v26
	v_sub_f32_e32 v28, v27, v23
	v_sub_f32_e32 v29, v27, v28
	v_sub_f32_e32 v25, v30, v25
	v_sub_f32_e32 v23, v23, v29
	v_sub_f32_e32 v26, v26, v28
	v_add_f32_e32 v23, v26, v23
	v_add_f32_e32 v26, v25, v22
	v_sub_f32_e32 v28, v26, v25
	v_sub_f32_e32 v29, v26, v28
	v_sub_f32_e32 v25, v25, v29
	v_sub_f32_e32 v22, v22, v28
	v_add_f32_e32 v23, v26, v23
	v_add_f32_e32 v22, v22, v25
	v_add_f32_e32 v25, v27, v23
	v_sub_f32_e32 v26, v25, v27
	v_sub_f32_e32 v23, v23, v26
	v_add_f32_e32 v22, v22, v23
	v_add_f32_e32 v22, v25, v22
	v_cndmask_b32_e64 v22, v209, v22, s[0:1]
	v_cmp_ngt_f32_e64 s[0:1], -1.0, v3
	s_xor_b64 s[34:35], s[20:21], s[22:23]
	s_nop 0
	v_cndmask_b32_e64 v22, v214, v22, s[0:1]
	v_cmp_neq_f32_e64 s[0:1], -1.0, v3
	s_nop 1
	v_cndmask_b32_e64 v22, v242, v22, s[0:1]
	v_cmp_lt_f32_e64 s[0:1], |v3|, s62
	s_nop 1
	v_cndmask_b32_e64 v3, v22, v3, s[0:1]
	v_sub_f32_e32 v3, v24, v3
	ds_bpermute_b32 v22, v5, v3
	ds_bpermute_b32 v23, v6, v3
	v_cndmask_b32_e64 v24, 63, 0, s[22:23]
	v_cmp_eq_u32_e64 s[24:25], v4, v24
	v_readlane_b32 s0, v254, 29
	v_readlane_b32 s1, v254, 30
	s_waitcnt lgkmcnt(0)
; DI void epi_in0(const Params& p, float* Cs, int m0, int n0) {
;     ...
;       float bc = f;
;       for (int off = 1; off < 64; off <<= 1) {
;         const float yu = __shfl_up(bc, off), yd = __shfl_down(bc, off);
;         const bool ok = dir == 0 ? lane >= off : lane + off < 64;
;         if (ok) bc += dir == 0 ? yu : yd;
;       }
;       const float gs = ig - bc;
;       float cm = gs;
;       for (int off = 1; off < 64; off <<= 1) {
;         const float yu = __shfl_up(cm, off), yd = __shfl_down(cm, off);
;         const bool ok = dir == 0 ? lane >= off : lane + off < 64;
;         if (ok) cm = fmaxf(cm, dir == 0 ? yu : yd);
;       }
;       const long o = ((long)(dir * GB + bg) * 8 + head) * T + t0 + row;
;       gb[o] = bc; gsv[o] = gs; gc[o] = cm;
	v_cndmask_b32_e64 v22, v23, v22, s[22:23]
	v_add_f32_e32 v22, v3, v22
	v_cndmask_b32_e64 v3, v22, v3, s[24:25]
	ds_bpermute_b32 v22, v7, v3
	ds_bpermute_b32 v23, v8, v3
	v_cndmask_b32_e64 v24, 0, 1, s[0:1]
	v_readlane_b32 s0, v255, 5
	v_readlane_b32 s1, v255, 6
	s_waitcnt lgkmcnt(0)
	v_cndmask_b32_e64 v22, v23, v22, s[22:23]
	v_cndmask_b32_e64 v25, 0, 1, s[0:1]
	v_cndmask_b32_e64 v24, v25, v24, s[22:23]
	v_and_b32_e32 v24, 1, v24
	v_cmp_eq_u32_e64 s[26:27], 1, v24
	v_add_f32_e32 v22, v3, v22
	v_readlane_b32 s0, v255, 3
	v_cndmask_b32_e64 v3, v3, v22, s[26:27]
	ds_bpermute_b32 v22, v10, v3
	ds_bpermute_b32 v23, v11, v3
	v_readlane_b32 s1, v255, 4
	v_cndmask_b32_e64 v25, 0, 1, s[6:7]
	s_waitcnt lgkmcnt(0)
	v_cndmask_b32_e64 v22, v23, v22, s[22:23]
	v_cndmask_b32_e64 v24, 0, 1, s[0:1]
	v_cndmask_b32_e64 v24, v25, v24, s[22:23]
	v_and_b32_e32 v24, 1, v24
	v_cmp_eq_u32_e64 s[28:29], 1, v24
	v_add_f32_e32 v22, v3, v22
	v_cndmask_b32_e64 v24, 0, 1, s[2:3]
	v_cndmask_b32_e64 v3, v3, v22, s[28:29]
	ds_bpermute_b32 v22, v12, v3
	ds_bpermute_b32 v23, v13, v3
	v_cndmask_b32_e64 v25, 0, 1, vcc
	v_cndmask_b32_e64 v24, v25, v24, s[22:23]
	v_and_b32_e32 v24, 1, v24
	v_cmp_eq_u32_e64 s[0:1], 1, v24
	s_waitcnt lgkmcnt(0)
	v_cndmask_b32_e64 v22, v23, v22, s[22:23]
	v_add_f32_e32 v22, v3, v22
	v_cndmask_b32_e64 v3, v3, v22, s[0:1]
	ds_bpermute_b32 v22, v14, v3
	ds_bpermute_b32 v23, v15, v3
	v_cndmask_b32_e64 v24, 0, 1, s[16:17]
	v_cndmask_b32_e64 v25, 0, 1, s[18:19]
	v_cndmask_b32_e64 v24, v25, v24, s[22:23]
	v_and_b32_e32 v24, 1, v24
	s_waitcnt lgkmcnt(0)
	v_cndmask_b32_e64 v22, v23, v22, s[22:23]
	v_cmp_eq_u32_e64 s[30:31], 1, v24
	v_add_f32_e32 v22, v3, v22
	s_nop 0
	v_cndmask_b32_e64 v3, v3, v22, s[30:31]
	ds_bpermute_b32 v22, v16, v3
	ds_bpermute_b32 v23, v17, v3
	s_waitcnt lgkmcnt(0)
	v_cndmask_b32_e64 v22, v23, v22, s[22:23]
	v_add_f32_e32 v22, v3, v22
	v_cndmask_b32_e64 v22, v3, v22, s[34:35]
	v_sub_f32_e32 v23, v2, v22
	ds_bpermute_b32 v2, v5, v23
	ds_bpermute_b32 v3, v6, v23
	s_waitcnt lgkmcnt(0)
	v_cndmask_b32_e64 v2, v3, v2, s[22:23]
	v_max_f32_e32 v2, v2, v2
	v_max_f32_e32 v2, v23, v2
	v_cndmask_b32_e64 v2, v2, v23, s[24:25]
	ds_bpermute_b32 v3, v7, v2
	ds_bpermute_b32 v21, v8, v2
	s_waitcnt lgkmcnt(0)
	v_cndmask_b32_e64 v3, v21, v3, s[22:23]
	v_max_f32_e32 v3, v3, v3
	v_max_f32_e32 v3, v2, v3
	v_cndmask_b32_e64 v2, v2, v3, s[26:27]
	ds_bpermute_b32 v3, v10, v2
	ds_bpermute_b32 v21, v11, v2
	s_waitcnt lgkmcnt(0)
	v_cndmask_b32_e64 v3, v21, v3, s[22:23]
	v_max_f32_e32 v3, v3, v3
	v_max_f32_e32 v3, v2, v3
	v_cndmask_b32_e64 v2, v2, v3, s[28:29]
	ds_bpermute_b32 v3, v12, v2
	ds_bpermute_b32 v21, v13, v2
	s_waitcnt lgkmcnt(0)
	v_cndmask_b32_e64 v3, v21, v3, s[22:23]
	v_max_f32_e32 v3, v3, v3
	v_max_f32_e32 v3, v2, v3
	v_cndmask_b32_e64 v2, v2, v3, s[0:1]
	ds_bpermute_b32 v3, v14, v2
	ds_bpermute_b32 v21, v15, v2
	s_waitcnt lgkmcnt(0)
	v_cndmask_b32_e64 v3, v21, v3, s[22:23]
	v_max_f32_e32 v3, v3, v3
	v_max_f32_e32 v3, v2, v3
	v_cndmask_b32_e64 v2, v2, v3, s[30:31]
	ds_bpermute_b32 v3, v16, v2
	ds_bpermute_b32 v21, v17, v2
	s_waitcnt lgkmcnt(0)
	v_cndmask_b32_e64 v3, v21, v3, s[22:23]
	v_max_f32_e32 v3, v3, v3
	v_max_f32_e32 v21, v2, v2
	v_max_f32_e32 v3, v21, v3
	v_cndmask_b32_e64 v24, v2, v3, s[34:35]
	v_lshl_add_u32 v2, v20, 1, s13
	v_ashrrev_i32_e32 v20, 31, v2
	v_lshl_or_b32 v19, v2, 3, v19
	v_lshl_add_u64 v[2:3], v[128:129], 0, s[48:49]
	v_mad_u64_u32 v[2:3], s[0:1], v19, s60, v[2:3]
	v_mad_i32_i24 v3, v20, s60, v3
	v_lshlrev_b64 v[2:3], 2, v[2:3]
	v_lshl_add_u64 v[20:21], s[78:79], 0, v[2:3]
	global_store_dword v[20:21], v22, off
	v_lshl_add_u64 v[20:21], s[80:81], 0, v[2:3]
	v_lshl_add_u64 v[2:3], s[94:95], 0, v[2:3]
	global_store_dword v[2:3], v24, off
	v_add_u32_e32 v2, 4, v9
	v_cmp_lt_i32_e64 s[0:1], 27, v9
	s_mov_b32 s23, 0x3f2aaaab
	s_mov_b32 s22, 0xbfb8aa3b
	s_or_b64 s[96:97], s[0:1], s[96:97]
	v_mov_b32_e32 v9, v2
	global_store_dword v[20:21], v23, off
	s_andn2_b64 exec, exec, s[96:97]
	s_cbranch_execnz .LBB0_1040

;   DI const float* c() const { return (const float*)sp[1]; }
; DI int TID() { int t = threadIdx.x; asm volatile("" : "+v"(t)); return t; }
; DI bf16x8 pack8f(const float* v) { u32x4 w = {cvtpk(v[0], v[1]), cvtpk(v[2], v[3]), cvtpk(v[4], v[5]), cvtpk(v[6], v[7])}; return __builtin_bit_cast(bf16x8, w); }
; DI void store_T(const float* Cs, int cb, int nc, bfu* dst, long ldT, float scale, const float* rs = nullptr) {
;   for (int u = TID(); u < nc * 16; u += NT) {
;     int c = u % nc, rc = (u / nc) * 8; float v[8];
;     for (int j = 0; j < 8; ++j) v[j] = Cs[(rc + j) * CLD + cb + c] * (rs ? scale * rs[rc + j] : scale);
;     st8(dst + c * ldT + rc, pack8f(v));
;   }
.LBB0_1057:
	v_ashrrev_i32_e32 v3, 31, v1
	v_lshrrev_b32_e32 v3, 25, v3
	v_add_u32_e32 v3, v1, v3
	v_add_u32_e32 v4, 0x100, v1
	v_ashrrev_i32_e32 v3, 7, v3
	v_cmp_lt_i32_e32 vcc, s87, v1
	v_mov_b32_e32 v1, v4
	v_mad_u64_u32 v[6:7], s[6:7], v3, s24, v[2:3]
	v_lshlrev_b32_e32 v4, 3, v3
	v_mad_u64_u32 v[8:9], s[6:7], v3, s25, v[0:1]
	v_add_u32_e32 v3, 0x400, v6
	v_add_u32_e32 v12, 0x800, v6
	v_add_u32_e32 v14, 0xc00, v6
	ds_read2_b32 v[10:11], v6 offset1:132
	ds_read2_b32 v[6:7], v3 offset0:8 offset1:140
	ds_read2_b32 v[12:13], v12 offset0:16 offset1:148
	ds_read2_b32 v[14:15], v14 offset0:24 offset1:156
	v_ashrrev_i32_e32 v9, 31, v8
	v_ashrrev_i32_e32 v5, 31, v4
	v_lshl_add_u64 v[8:9], s[2:3], 0, v[8:9]
	s_or_b64 s[4:5], vcc, s[4:5]
	v_add_u32_e32 v0, 0x120000, v0
	v_add_u32_e32 v2, 0x400, v2
	v_lshl_add_u64 v[8:9], v[4:5], 1, v[8:9]
	s_waitcnt lgkmcnt(0)
	v_cvt_pk_bf16_f32 v4, v10, v11
	v_cvt_pk_bf16_f32 v5, v6, v7
	v_cvt_pk_bf16_f32 v6, v12, v13
	v_cvt_pk_bf16_f32 v7, v14, v15
	global_store_dwordx4 v[8:9], v[4:7], off
	s_andn2_b64 exec, exec, s[4:5]
	s_cbranch_execnz .LBB0_1057

; DI int TID() { int t = threadIdx.x; asm volatile("" : "+v"(t)); return t; }
; DI bf16x8 pack8f(const float* v) { u32x4 w = {cvtpk(v[0], v[1]), cvtpk(v[2], v[3]), cvtpk(v[4], v[5]), cvtpk(v[6], v[7])}; return __builtin_bit_cast(bf16x8, w); }
; DI void store_R(const float* Cs, int cb, int nc, bfu* dst, long ld, float scale, const float* rs = nullptr) {
;   const int cpr = nc >> 3;
;   for (int u = TID(); u < 128 * cpr; u += NT) {
;     int row = u / cpr, c8 = (u % cpr) * 8; float v[8]; ldrow8(Cs, row, cb + c8, v);
;     float s = rs ? scale * rs[row] : scale;
;     for (int j = 0; j < 8; ++j) v[j] *= s;
;     st8(dst + row * ld + c8, pack8f(v));
;   }
; }
.LBB0_1072:
	v_ashrrev_i32_e32 v3, 31, v0
	v_lshrrev_b32_e32 v3, 28, v3
	v_add_u32_e32 v3, v0, v3
	v_add_u32_e32 v4, 0x100, v0
	v_ashrrev_i32_e32 v12, 4, v3
	v_and_b32_e32 v3, -16, v3
	v_cmp_lt_i32_e32 vcc, s87, v0
	v_mov_b32_e32 v0, v4
	v_lshlrev_b32_e32 v4, 7, v12
	v_add_u32_e32 v3, v2, v3
	v_sub_u32_e32 v14, v1, v4
	ds_read_b128 v[4:7], v3
	ds_read_b128 v[8:11], v3 offset:16
	v_ashrrev_i32_e32 v13, 31, v12
	v_lshlrev_b64 v[12:13], 8, v[12:13]
	v_lshl_add_u64 v[12:13], s[2:3], 0, v[12:13]
	v_ashrrev_i32_e32 v15, 31, v14
	s_waitcnt lgkmcnt(0)
	v_pk_mul_f32 v[4:5], v[4:5], s[26:27] op_sel_hi:[1,0]
	v_pk_mul_f32 v[6:7], v[6:7], s[26:27] op_sel_hi:[1,0]
	v_pk_mul_f32 v[8:9], v[8:9], s[26:27] op_sel_hi:[1,0]
	v_pk_mul_f32 v[10:11], v[10:11], s[26:27] op_sel_hi:[1,0]
	s_or_b64 s[4:5], vcc, s[4:5]
	v_add_u32_e32 v2, 0x2000, v2
	v_add_u32_e32 v1, 0x800, v1
	v_lshl_add_u64 v[12:13], v[14:15], 1, v[12:13]
	v_cvt_pk_bf16_f32 v4, v4, v5
	v_cvt_pk_bf16_f32 v5, v6, v7
	v_cvt_pk_bf16_f32 v6, v8, v9
	v_cvt_pk_bf16_f32 v7, v10, v11
	global_store_dwordx4 v[12:13], v[4:7], off
	s_andn2_b64 exec, exec, s[4:5]
	s_cbranch_execnz .LBB0_1072

; DI int TID() { int t = threadIdx.x; asm volatile("" : "+v"(t)); return t; }
; DI bf16x8 pack8f(const float* v) { u32x4 w = {cvtpk(v[0], v[1]), cvtpk(v[2], v[3]), cvtpk(v[4], v[5]), cvtpk(v[6], v[7])}; return __builtin_bit_cast(bf16x8, w); }
; DI void store_R(const float* Cs, int cb, int nc, bfu* dst, long ld, float scale, const float* rs = nullptr) {
;   const int cpr = nc >> 3;
;   for (int u = TID(); u < 128 * cpr; u += NT) {
;     int row = u / cpr, c8 = (u % cpr) * 8; float v[8]; ldrow8(Cs, row, cb + c8, v);
;     float s = rs ? scale * rs[row] : scale;
;     for (int j = 0; j < 8; ++j) v[j] *= s;
;     st8(dst + row * ld + c8, pack8f(v));
;   }
; }
.LBB0_1092:
	v_ashrrev_i32_e32 v5, 31, v3
	v_lshrrev_b32_e32 v5, 29, v5
	v_add_u32_e32 v6, 0x100, v3
	v_add_u32_e32 v5, v3, v5
	v_cmp_lt_i32_e32 vcc, s28, v3
	v_mov_b32_e32 v3, v6
	v_ashrrev_i32_e32 v14, 3, v5
	v_mad_u64_u32 v[10:11], s[12:13], v14, s15, v[2:3]
	ds_read_b128 v[6:9], v10
	ds_read_b128 v[10:13], v10 offset:16
	v_lshlrev_b32_e32 v5, 6, v14
	v_ashrrev_i32_e32 v15, 31, v14
	v_sub_u32_e32 v16, v4, v5
	v_lshlrev_b64 v[14:15], 7, v[14:15]
	v_lshl_add_u64 v[14:15], s[2:3], 0, v[14:15]
	v_ashrrev_i32_e32 v17, 31, v16
	s_waitcnt lgkmcnt(0)
	v_pk_mul_f32 v[6:7], v[0:1], v[6:7]
	v_pk_mul_f32 v[8:9], v[0:1], v[8:9]
	v_pk_mul_f32 v[10:11], v[0:1], v[10:11]
	v_pk_mul_f32 v[12:13], v[0:1], v[12:13]
	s_or_b64 s[4:5], vcc, s[4:5]
	v_add_u32_e32 v2, 0x2000, v2
	v_add_u32_e32 v4, 0x800, v4
	v_lshl_add_u64 v[14:15], v[16:17], 1, v[14:15]
	v_cvt_pk_bf16_f32 v6, v6, v7
	v_cvt_pk_bf16_f32 v7, v8, v9
	v_cvt_pk_bf16_f32 v8, v10, v11
	v_cvt_pk_bf16_f32 v9, v12, v13
	global_store_dwordx4 v[14:15], v[6:9], off
	s_andn2_b64 exec, exec, s[4:5]
	s_cbranch_execnz .LBB0_1092

; DI int TID() { int t = threadIdx.x; asm volatile("" : "+v"(t)); return t; }
; DI bf16x8 pack8f(const float* v) { u32x4 w = {cvtpk(v[0], v[1]), cvtpk(v[2], v[3]), cvtpk(v[4], v[5]), cvtpk(v[6], v[7])}; return __builtin_bit_cast(bf16x8, w); }
; DI void store_R(const float* Cs, int cb, int nc, bfu* dst, long ld, float scale, const float* rs = nullptr) {
;   const int cpr = nc >> 3;
;   for (int u = TID(); u < 128 * cpr; u += NT) {
;     int row = u / cpr, c8 = (u % cpr) * 8; float v[8]; ldrow8(Cs, row, cb + c8, v);
;     float s = rs ? scale * rs[row] : scale;
;     for (int j = 0; j < 8; ++j) v[j] *= s;
;     st8(dst + row * ld + c8, pack8f(v));
;   }
; }
.LBB0_1095:
	v_ashrrev_i32_e32 v5, 31, v3
	v_lshrrev_b32_e32 v5, 29, v5
	v_add_u32_e32 v6, 0x100, v3
	v_add_u32_e32 v5, v3, v5
	v_cmp_lt_i32_e32 vcc, s28, v3
	v_mov_b32_e32 v3, v6
	v_ashrrev_i32_e32 v14, 3, v5
	v_mad_u64_u32 v[10:11], s[6:7], v14, s12, v[2:3]
	ds_read_b128 v[6:9], v10
	ds_read_b128 v[10:13], v10 offset:16
	v_lshlrev_b32_e32 v5, 6, v14
	v_ashrrev_i32_e32 v15, 31, v14
	v_sub_u32_e32 v16, v4, v5
	v_lshlrev_b64 v[14:15], 7, v[14:15]
	v_lshl_add_u64 v[14:15], s[2:3], 0, v[14:15]
	v_ashrrev_i32_e32 v17, 31, v16
	s_waitcnt lgkmcnt(0)
	v_pk_mul_f32 v[6:7], v[0:1], v[6:7]
	v_pk_mul_f32 v[8:9], v[0:1], v[8:9]
	v_pk_mul_f32 v[10:11], v[0:1], v[10:11]
	v_pk_mul_f32 v[12:13], v[0:1], v[12:13]
	s_or_b64 s[4:5], vcc, s[4:5]
	v_add_u32_e32 v2, 0x2000, v2
	v_add_u32_e32 v4, 0x800, v4
	v_lshl_add_u64 v[14:15], v[16:17], 1, v[14:15]
	v_cvt_pk_bf16_f32 v6, v6, v7
	v_cvt_pk_bf16_f32 v7, v8, v9
	v_cvt_pk_bf16_f32 v8, v10, v11
	v_cvt_pk_bf16_f32 v9, v12, v13
	global_store_dwordx4 v[14:15], v[6:9], off
	s_andn2_b64 exec, exec, s[4:5]
	s_cbranch_execnz .LBB0_1095
	s_branch .LBB0_925

;   DI const float* x() const { return (const float*)sp[0]; }
;   DI const float* kv_norm_g() const { return (const float*)sp[19]; }
;   DI const float* w_ukv() const { return (const float*)sp[20]; }
; DI int TID() { int t = threadIdx.x; asm volatile("" : "+v"(t)); return t; }
; DI void tr_load(const float* __restrict__ src, int ld, int K, int mapid, const float* __restrict__ ks, int tile, f32x4 (&v)[4]) {
;   const int tid = TID();
;   const int kT = K >> 6, nt = tile / kT, kt = tile % kT, n0 = nt * 64, k0 = kt * 64;
;   const int n4 = (tid & 15) * 4, kr = tid >> 4;
;   const int n = n0 + n4;
;   const int sc = mapid == 1 ? srccol1(n) : (mapid == 2 ? srccol2(n) : n);
; #pragma unroll
;   for (int i = 0; i < 4; ++i) {
;     const int k = i * 16 + kr;
;     f32x4 x = {0.f, 0.f, 0.f, 0.f};
;     if (sc >= 0) x = *reinterpret_cast<const f32x4*>(src + (long)(k0 + k) * ld + sc);
;     if (ks) { const float g_ = ks[k0 + k]; x *= g_; }
;     v[i] = x;
;   }
; }
; DI void phase_prep1(const Params& p, char* smem) {
;     ...
;       else tr_load(p.w_ukv(), 4096, 256, 0, p.kv_norm_g(), it - t1 - t2 - t3, v);
.LBB0_1097:
	s_and_b64 vcc, exec, s[0:1]
	s_cbranch_vccz .LBB0_1187
	v_readlane_b32 s0, v254, 5
	v_readlane_b32 s1, v254, 6
	v_mov_b32_e32 v15, 0
	s_andn2_b64 vcc, exec, s[0:1]
	v_cndmask_b32_e64 v0, 0, 1, s[0:1]
	v_cmp_ne_u32_e64 s[6:7], 1, v0
	v_mov_b32_e32 v14, 0
	v_mov_b32_e32 v13, 0
	v_mov_b32_e32 v12, 0
	v_mov_b32_e32 v11, 0
	v_mov_b32_e32 v10, 0
	v_mov_b32_e32 v9, 0
	v_mov_b32_e32 v8, 0
	v_mov_b32_e32 v7, 0
	v_mov_b32_e32 v6, 0
	v_mov_b32_e32 v5, 0
	v_mov_b32_e32 v4, 0
	v_mov_b32_e32 v3, 0
	v_mov_b32_e32 v2, 0
	v_mov_b32_e32 v1, 0
	v_mov_b32_e32 v0, 0
	s_cbranch_vccnz .LBB0_1132
	v_readlane_b32 s2, v254, 38
	v_readlane_b32 s3, v254, 39
	s_mov_b64 s[0:1], -1
	s_and_b64 vcc, exec, s[2:3]
	s_cbranch_vccz .LBB0_1124
	v_readlane_b32 s2, v254, 40
	v_readlane_b32 s3, v254, 41
	s_and_b64 vcc, exec, s[2:3]
	s_cbranch_vccz .LBB0_1121
	v_readlane_b32 s2, v254, 42
	v_readlane_b32 s3, v254, 43
	s_and_b64 vcc, exec, s[2:3]
	s_cbranch_vccz .LBB0_1111
	v_mov_b32_e32 v0, 0x12298
	ds_read2_b64 v[4:7], v0 offset1:1
	v_mov_b32_e32 v0, v202
	v_readlane_b32 s0, v254, 45
	v_lshlrev_b32_e32 v1, 2, v0
	v_ashrrev_i32_e32 v2, 4, v0
	v_and_or_b32 v0, v1, 60, s0
	v_lshlrev_b32_e32 v128, 2, v0
	v_readlane_b32 s0, v254, 46
	s_waitcnt lgkmcnt(0)
	v_lshl_add_u64 v[0:1], v[6:7], 0, v[128:129]
	v_cmp_eq_u64_e32 vcc, 0, v[4:5]
	v_add_u32_e32 v6, s0, v2
	v_ashrrev_i32_e32 v7, 31, v6
	v_lshlrev_b64 v[2:3], 14, v[6:7]
	v_lshl_add_u64 v[12:13], v[0:1], 0, v[2:3]
	global_load_dwordx4 v[0:3], v[12:13], off
	v_cmp_ne_u64_e64 s[0:1], 0, v[4:5]
	v_lshl_add_u64 v[16:17], v[6:7], 2, v[4:5]
	s_cbranch_vccnz .LBB0_1104
	global_load_dword v4, v[16:17], off
	s_waitcnt vmcnt(0) lgkmcnt(0)
	v_pk_mul_f32 v[2:3], v[2:3], v[4:5] op_sel_hi:[1,0]
	v_pk_mul_f32 v[0:1], v[0:1], v[4:5] op_sel_hi:[1,0]
.LBB0_1104:
	v_add_co_u32_e32 v4, vcc, 0x40000, v12
	v_cndmask_b32_e64 v8, 0, 1, s[0:1]
	s_nop 0
	v_addc_co_u32_e32 v5, vcc, 0, v13, vcc
	global_load_dwordx4 v[4:7], v[4:5], off
	v_cmp_ne_u32_e64 s[8:9], 1, v8
	s_andn2_b64 vcc, exec, s[0:1]
	s_cbranch_vccnz .LBB0_1106
	global_load_dword v8, v[16:17], off offset:64
	s_waitcnt vmcnt(0) lgkmcnt(0)
	v_pk_mul_f32 v[6:7], v[6:7], v[8:9] op_sel_hi:[1,0]
	v_pk_mul_f32 v[4:5], v[4:5], v[8:9] op_sel_hi:[1,0]
.LBB0_1106:
	v_add_co_u32_e32 v8, vcc, 0x80000, v12
	s_nop 1
	v_addc_co_u32_e32 v9, vcc, 0, v13, vcc
	global_load_dwordx4 v[8:11], v[8:9], off
	s_and_b64 vcc, exec, s[8:9]
	s_cbranch_vccnz .LBB0_1108
	global_load_dword v14, v[16:17], off offset:128
	s_waitcnt vmcnt(0) lgkmcnt(0)
	v_pk_mul_f32 v[10:11], v[10:11], v[14:15] op_sel_hi:[1,0]
	v_pk_mul_f32 v[8:9], v[8:9], v[14:15] op_sel_hi:[1,0]
.LBB0_1108:
	v_add_co_u32_e32 v12, vcc, 0xc0000, v12
	s_nop 1
	v_addc_co_u32_e32 v13, vcc, 0, v13, vcc
	global_load_dwordx4 v[12:15], v[12:13], off
	s_and_b64 vcc, exec, s[8:9]
	s_cbranch_vccnz .LBB0_1110
	global_load_dword v16, v[16:17], off offset:192
	s_waitcnt vmcnt(0) lgkmcnt(0)
	v_pk_mul_f32 v[14:15], v[14:15], v[16:17] op_sel_hi:[1,0]
	v_pk_mul_f32 v[12:13], v[12:13], v[16:17] op_sel_hi:[1,0]

;   DI const float* x() const { return (const float*)sp[0]; }
;   DI const float* q_norm_g() const { return (const float*)sp[17]; }
;   DI const float* w_uq() const { return (const float*)sp[18]; }
; DI int TID() { int t = threadIdx.x; asm volatile("" : "+v"(t)); return t; }
; DI void tr_load(const float* __restrict__ src, int ld, int K, int mapid, const float* __restrict__ ks, int tile, f32x4 (&v)[4]) {
;   const int tid = TID();
;   const int kT = K >> 6, nt = tile / kT, kt = tile % kT, n0 = nt * 64, k0 = kt * 64;
;   const int n4 = (tid & 15) * 4, kr = tid >> 4;
;   const int n = n0 + n4;
;   const int sc = mapid == 1 ? srccol1(n) : (mapid == 2 ? srccol2(n) : n);
; #pragma unroll
;   for (int i = 0; i < 4; ++i) {
;     const int k = i * 16 + kr;
;     f32x4 x = {0.f, 0.f, 0.f, 0.f};
;     if (sc >= 0) x = *reinterpret_cast<const f32x4*>(src + (long)(k0 + k) * ld + sc);
;     if (ks) { const float g_ = ks[k0 + k]; x *= g_; }
;     v[i] = x;
;   }
; }
; DI void phase_prep1(const Params& p, char* smem) {
;     ...
;       else if (it < t1 + t2 + t3) tr_load(p.w_uq(), 3072, 512, 0, p.q_norm_g(), it - t1 - t2, v);
.LBB0_1111:
	s_and_b64 vcc, exec, s[0:1]
	s_cbranch_vccz .LBB0_1120
	s_waitcnt vmcnt(0) lgkmcnt(0)
	v_mov_b32_e32 v0, 0x12288
	ds_read2_b64 v[4:7], v0 offset1:1
	v_mov_b32_e32 v0, v202
	v_readlane_b32 s0, v254, 48
	v_lshlrev_b32_e32 v1, 2, v0
	v_ashrrev_i32_e32 v0, 4, v0
	v_and_or_b32 v1, v1, 60, s0
	v_lshlrev_b32_e32 v128, 2, v1
	v_readlane_b32 s0, v254, 49
	s_waitcnt lgkmcnt(0)
	v_lshl_add_u64 v[12:13], v[6:7], 0, v[128:129]
	v_cmp_eq_u64_e32 vcc, 0, v[4:5]
	v_add_u32_e32 v14, s0, v0
	s_movk_i32 s0, 0x3000
	v_mad_i64_i32 v[0:1], s[0:1], v14, s0, v[12:13]
	global_load_dwordx4 v[0:3], v[0:1], off
	v_ashrrev_i32_e32 v15, 31, v14
	v_cmp_ne_u64_e64 s[0:1], 0, v[4:5]
	v_lshl_add_u64 v[16:17], v[14:15], 2, v[4:5]
	s_cbranch_vccnz .LBB0_1114
	global_load_dword v4, v[16:17], off
	s_waitcnt vmcnt(0) lgkmcnt(0)
	v_pk_mul_f32 v[2:3], v[2:3], v[4:5] op_sel_hi:[1,0]
	v_pk_mul_f32 v[0:1], v[0:1], v[4:5] op_sel_hi:[1,0]
.LBB0_1114:
	v_add_u32_e32 v4, 16, v14
	s_movk_i32 s2, 0x3000
	v_mad_i64_i32 v[4:5], s[2:3], v4, s2, v[12:13]
	global_load_dwordx4 v[4:7], v[4:5], off
	v_cndmask_b32_e64 v8, 0, 1, s[0:1]
	v_cmp_ne_u32_e64 s[8:9], 1, v8
	s_andn2_b64 vcc, exec, s[0:1]
	s_cbranch_vccnz .LBB0_1116
	global_load_dword v8, v[16:17], off offset:64
	s_waitcnt vmcnt(0) lgkmcnt(0)
	v_pk_mul_f32 v[6:7], v[6:7], v[8:9] op_sel_hi:[1,0]
	v_pk_mul_f32 v[4:5], v[4:5], v[8:9] op_sel_hi:[1,0]
.LBB0_1116:
	v_add_u32_e32 v8, 32, v14
	s_movk_i32 s0, 0x3000
	v_mad_i64_i32 v[8:9], s[0:1], v8, s0, v[12:13]
	global_load_dwordx4 v[8:11], v[8:9], off
	s_and_b64 vcc, exec, s[8:9]
	s_cbranch_vccnz .LBB0_1118
	global_load_dword v18, v[16:17], off offset:128
	s_waitcnt vmcnt(0) lgkmcnt(0)
	v_pk_mul_f32 v[10:11], v[10:11], v[18:19] op_sel_hi:[1,0]
	v_pk_mul_f32 v[8:9], v[8:9], v[18:19] op_sel_hi:[1,0]
.LBB0_1118:
	v_add_u32_e32 v14, 48, v14
	s_movk_i32 s0, 0x3000
	v_mad_i64_i32 v[12:13], s[0:1], v14, s0, v[12:13]
	global_load_dwordx4 v[12:15], v[12:13], off
	s_and_b64 vcc, exec, s[8:9]
	s_cbranch_vccnz .LBB0_1120
	global_load_dword v16, v[16:17], off offset:192
	s_mov_b64 s[0:1], 0
	s_waitcnt vmcnt(0) lgkmcnt(0)
	v_pk_mul_f32 v[14:15], v[14:15], v[16:17] op_sel_hi:[1,0]
	v_pk_mul_f32 v[12:13], v[12:13], v[16:17] op_sel_hi:[1,0]
	s_branch .LBB0_1121

;   DI const float* x() const { return (const float*)sp[0]; }
;   DI const float* cd_w_out() const { return (const float*)sp[21]; }
; DI int TID() { int t = threadIdx.x; asm volatile("" : "+v"(t)); return t; }
; DI void tr_load(const float* __restrict__ src, int ld, int K, int mapid, const float* __restrict__ ks, int tile, f32x4 (&v)[4]) {
;   const int tid = TID();
;   const int kT = K >> 6, nt = tile / kT, kt = tile % kT, n0 = nt * 64, k0 = kt * 64;
;   const int n4 = (tid & 15) * 4, kr = tid >> 4;
;   const int n = n0 + n4;
;   const int sc = mapid == 1 ? srccol1(n) : (mapid == 2 ? srccol2(n) : n);
; #pragma unroll
;   for (int i = 0; i < 4; ++i) {
;     const int k = i * 16 + kr;
;     f32x4 x = {0.f, 0.f, 0.f, 0.f};
;     if (sc >= 0) x = *reinterpret_cast<const f32x4*>(src + (long)(k0 + k) * ld + sc);
;     if (ks) { const float g_ = ks[k0 + k]; x *= g_; }
;     v[i] = x;
;   }
; }
; DI void phase_prep1(const Params& p, char* smem) {
;     ...
;       else if (it < t1 + t2) tr_load(p.cd_w_out(), 2048, 4096, 0, nullptr, it - t1, v);
.LBB0_1121:
	s_andn2_b64 vcc, exec, s[0:1]
	s_cbranch_vccnz .LBB0_1123
	s_waitcnt vmcnt(0) lgkmcnt(0)
	v_mov_b32_e32 v0, 0x122a8
	ds_read_b64 v[0:1], v0
	v_mov_b32_e32 v2, v202
	v_readlane_b32 s0, v254, 50
	v_lshlrev_b32_e32 v3, 2, v2
	v_ashrrev_i32_e32 v2, 4, v2
	v_and_or_b32 v3, v3, 60, s0
	v_readlane_b32 s0, v254, 8
	v_lshlrev_b32_e32 v128, 2, v3
	s_waitcnt lgkmcnt(0)
	v_lshl_add_u64 v[0:1], v[0:1], 0, v[128:129]
	v_add_u32_e32 v2, s0, v2
	v_ashrrev_i32_e32 v3, 31, v2
	v_lshlrev_b64 v[2:3], 13, v[2:3]
	v_lshl_add_u64 v[8:9], v[0:1], 0, v[2:3]
	v_add_co_u32_e32 v4, vcc, 0x20000, v8
	s_nop 1
	v_addc_co_u32_e32 v5, vcc, 0, v9, vcc
	v_add_co_u32_e32 v10, vcc, 0x40000, v8
	global_load_dwordx4 v[0:3], v[8:9], off
	s_nop 0
	global_load_dwordx4 v[4:7], v[4:5], off
	v_addc_co_u32_e32 v11, vcc, 0, v9, vcc
	v_add_co_u32_e32 v12, vcc, 0x60000, v8
	s_nop 1
	v_addc_co_u32_e32 v13, vcc, 0, v9, vcc
	global_load_dwordx4 v[8:11], v[10:11], off
	s_nop 0
	global_load_dwordx4 v[12:15], v[12:13], off

;   DI const float* x() const { return (const float*)sp[0]; }
;   DI const float* cd_w_in() const { return (const float*)sp[14]; }
; DI int TID() { int t = threadIdx.x; asm volatile("" : "+v"(t)); return t; }
; DI void tr_load(const float* __restrict__ src, int ld, int K, int mapid, const float* __restrict__ ks, int tile, f32x4 (&v)[4]) {
;   const int tid = TID();
;   const int kT = K >> 6, nt = tile / kT, kt = tile % kT, n0 = nt * 64, k0 = kt * 64;
;   const int n4 = (tid & 15) * 4, kr = tid >> 4;
;   const int n = n0 + n4;
;   const int sc = mapid == 1 ? srccol1(n) : (mapid == 2 ? srccol2(n) : n);
; #pragma unroll
;   for (int i = 0; i < 4; ++i) {
;     const int k = i * 16 + kr;
;     f32x4 x = {0.f, 0.f, 0.f, 0.f};
;     if (sc >= 0) x = *reinterpret_cast<const f32x4*>(src + (long)(k0 + k) * ld + sc);
; DI void phase_prep1(const Params& p, char* smem) {
;     ...
;       if (it < t1) tr_load(p.cd_w_in(), 11072, 2048, 2, nullptr, it, v);
.LBB0_1129:
	s_or_b64 exec, exec, s[0:1]
	v_mov_b32_e32 v128, v129
	v_mov_b32_e32 v130, v129
	v_mov_b32_e32 v131, v129
	v_mov_b64_e32 v[12:13], v[128:129]
	v_cmp_lt_i32_e32 vcc, -1, v18
	v_mov_b32_e32 v0, 0
	v_mov_b64_e32 v[14:15], v[130:131]
	v_mov_b32_e32 v1, 0
	v_mov_b32_e32 v2, 0
	v_mov_b32_e32 v3, 0
	v_mov_b32_e32 v4, 0
	v_mov_b32_e32 v5, 0
	v_mov_b32_e32 v6, 0
	v_mov_b32_e32 v7, 0
	v_mov_b32_e32 v8, 0
	v_mov_b32_e32 v9, 0
	v_mov_b32_e32 v10, 0
	v_mov_b32_e32 v11, 0
	s_and_saveexec_b64 s[0:1], vcc
	s_cbranch_execz .LBB0_1131
	v_ashrrev_i32_e32 v0, 4, v19
	v_mov_b32_e32 v19, v129
	v_readlane_b32 s2, v254, 10
	v_lshl_add_u64 v[8:9], v[18:19], 2, v[16:17]
	s_mov_b32 s4, 0xad00
	v_add_u32_e32 v12, s2, v0
	v_mad_i64_i32 v[0:1], s[2:3], v12, s4, v[8:9]
	v_add_u32_e32 v2, 16, v12
	v_add_u32_e32 v10, 32, v12
	v_add_u32_e32 v12, 48, v12
	v_mad_i64_i32 v[4:5], s[2:3], v2, s4, v[8:9]
	v_mad_i64_i32 v[10:11], s[2:3], v10, s4, v[8:9]
	v_mad_i64_i32 v[12:13], s[2:3], v12, s4, v[8:9]
	global_load_dwordx4 v[0:3], v[0:1], off
	s_nop 0
	global_load_dwordx4 v[4:7], v[4:5], off
	s_nop 0
	global_load_dwordx4 v[8:11], v[10:11], off
	s_nop 0
	global_load_dwordx4 v[12:15], v[12:13], off

;   DI const float* x() const { return (const float*)sp[0]; }
;   DI const float* cd_w_in() const { return (const float*)sp[14]; }
;   DI const float* q_norm_g() const { return (const float*)sp[17]; }
;   DI const float* w_uq() const { return (const float*)sp[18]; }
;   DI const float* kv_norm_g() const { return (const float*)sp[19]; }
;   DI const float* w_ukv() const { return (const float*)sp[20]; }
;   DI const float* cd_w_out() const { return (const float*)sp[21]; }
; DI int TID() { int t = threadIdx.x; asm volatile("" : "+v"(t)); return t; }
; DI void tr_load(const float* __restrict__ src, int ld, int K, int mapid, const float* __restrict__ ks, int tile, f32x4 (&v)[4]) {
;   const int tid = TID();
;   const int kT = K >> 6, nt = tile / kT, kt = tile % kT, n0 = nt * 64, k0 = kt * 64;
;   const int n4 = (tid & 15) * 4, kr = tid >> 4;
;   const int n = n0 + n4;
;   const int sc = mapid == 1 ? srccol1(n) : (mapid == 2 ? srccol2(n) : n);
; #pragma unroll
;   for (int i = 0; i < 4; ++i) {
;     const int k = i * 16 + kr;
;     f32x4 x = {0.f, 0.f, 0.f, 0.f};
;     if (sc >= 0) x = *reinterpret_cast<const f32x4*>(src + (long)(k0 + k) * ld + sc);
;     if (ks) { const float g_ = ks[k0 + k]; x *= g_; }
;     v[i] = x;
;   }
; }
; DI void phase_prep1(const Params& p, char* smem) {
;     ...
;     const int tot = t1 + t2 + t3 + t4;
;     auto ld_ = [&](int it, f32x4 (&v)[4]) {
;       if (it < t1) tr_load(p.cd_w_in(), 11072, 2048, 2, nullptr, it, v);
;       else if (it < t1 + t2) tr_load(p.cd_w_out(), 2048, 4096, 0, nullptr, it - t1, v);
;       else if (it < t1 + t2 + t3) tr_load(p.w_uq(), 3072, 512, 0, p.q_norm_g(), it - t1 - t2, v);
;       else tr_load(p.w_ukv(), 4096, 256, 0, p.kv_norm_g(), it - t1 - t2 - t3, v);
;     };
;     auto fin_ = [&](int it, const f32x4 (&v)[4]) {
;       if (it < t1) tr_finish(2048, (bfu*)((char*)wa + WA_W2), it, v, tl);
;       else if (it < t1 + t2) tr_finish(4096, (bfu*)((char*)wa + WA_WO2), it - t1, v, tl);
;       else if (it < t1 + t2 + t3) tr_finish(512, (bfu*)((char*)wa + WA_UQ), it - t1 - t2, v, tl);
;       else tr_finish(256, (bfu*)((char*)wa + WA_UKV), it - t1 - t2 - t3, v, tl);
;     };
;     f32x4 va[4], vb[4];
;     int it = b;
;     if (it < tot) ld_(it, va);
;     while (it < tot) {
;       const int nx = it + G_;
;       if (nx < tot) ld_(nx, vb);
.LBB0_1136:
	v_readlane_b32 s0, v254, 21
	s_add_i32 s14, s15, s0
	s_cmpk_gt_i32 s14, 0x203f
	s_cselect_b64 s[4:5], -1, 0
	s_and_b64 vcc, exec, s[4:5]
	v_readlane_b32 s1, v254, 22
	s_cbranch_vccnz .LBB0_1172
	s_cmpk_gt_i32 s14, 0x15bf
	s_mov_b64 s[0:1], -1
	s_cbranch_scc0 .LBB0_1162
	s_cmpk_gt_u32 s14, 0x1dbf
	s_cbranch_scc0 .LBB0_1159
	s_add_i32 s2, s8, s13
	s_cmpk_gt_u32 s14, 0x1f3f
	s_cbranch_scc0 .LBB0_1149
	v_mov_b32_e32 v16, 0x12298
	ds_read2_b64 v[20:23], v16 offset1:1
	v_mov_b32_e32 v16, v202
	s_add_i32 s0, s9, s12
	s_and_b32 s0, s0, 0xfc0
	v_lshlrev_b32_e32 v17, 2, v16
	v_ashrrev_i32_e32 v18, 4, v16
	v_and_or_b32 v16, v17, 60, s0
	s_and_b32 s1, s2, 0xc0
	v_lshlrev_b32_e32 v128, 2, v16
	s_waitcnt lgkmcnt(0)
	v_lshl_add_u64 v[16:17], v[22:23], 0, v[128:129]
	v_add_u32_e32 v22, s1, v18
	v_ashrrev_i32_e32 v23, 31, v22
	v_lshlrev_b64 v[18:19], 14, v[22:23]
	v_lshl_add_u64 v[28:29], v[16:17], 0, v[18:19]
	global_load_dwordx4 v[16:19], v[28:29], off
	v_cmp_eq_u64_e32 vcc, 0, v[20:21]
	v_cmp_ne_u64_e64 s[0:1], 0, v[20:21]
	v_lshl_add_u64 v[32:33], v[22:23], 2, v[20:21]
	s_cbranch_vccnz .LBB0_1142
	global_load_dword v20, v[32:33], off
	s_waitcnt vmcnt(0) lgkmcnt(0)
	v_pk_mul_f32 v[18:19], v[18:19], v[20:21] op_sel_hi:[1,0]
	v_pk_mul_f32 v[16:17], v[16:17], v[20:21] op_sel_hi:[1,0]
.LBB0_1142:
	v_add_co_u32_e32 v20, vcc, 0x40000, v28
	v_cndmask_b32_e64 v24, 0, 1, s[0:1]
	s_nop 0
	v_addc_co_u32_e32 v21, vcc, 0, v29, vcc
	global_load_dwordx4 v[20:23], v[20:21], off
	v_cmp_ne_u32_e64 s[6:7], 1, v24
	s_andn2_b64 vcc, exec, s[0:1]
	s_cbranch_vccnz .LBB0_1144
	global_load_dword v24, v[32:33], off offset:64
	s_waitcnt vmcnt(0) lgkmcnt(0)
	v_pk_mul_f32 v[22:23], v[22:23], v[24:25] op_sel_hi:[1,0]
	v_pk_mul_f32 v[20:21], v[20:21], v[24:25] op_sel_hi:[1,0]
.LBB0_1144:
	v_add_co_u32_e32 v24, vcc, 0x80000, v28
	s_nop 1
	v_addc_co_u32_e32 v25, vcc, 0, v29, vcc
	global_load_dwordx4 v[24:27], v[24:25], off
	s_and_b64 vcc, exec, s[6:7]
	s_cbranch_vccnz .LBB0_1146
	global_load_dword v30, v[32:33], off offset:128
	s_waitcnt vmcnt(0) lgkmcnt(0)
	v_pk_mul_f32 v[26:27], v[26:27], v[30:31] op_sel_hi:[1,0]
	v_pk_mul_f32 v[24:25], v[24:25], v[30:31] op_sel_hi:[1,0]
.LBB0_1146:
	v_add_co_u32_e32 v28, vcc, 0xc0000, v28
	s_nop 1
	v_addc_co_u32_e32 v29, vcc, 0, v29, vcc
	global_load_dwordx4 v[28:31], v[28:29], off
	s_and_b64 vcc, exec, s[6:7]
	s_cbranch_vccnz .LBB0_1148
	global_load_dword v32, v[32:33], off offset:192
	s_waitcnt vmcnt(0) lgkmcnt(0)
	v_pk_mul_f32 v[30:31], v[30:31], v[32:33] op_sel_hi:[1,0]
	v_pk_mul_f32 v[28:29], v[28:29], v[32:33] op_sel_hi:[1,0]

;   DI const float* x() const { return (const float*)sp[0]; }
;   DI const float* q_norm_g() const { return (const float*)sp[17]; }
;   DI const float* w_uq() const { return (const float*)sp[18]; }
; DI int TID() { int t = threadIdx.x; asm volatile("" : "+v"(t)); return t; }
; DI void tr_load(const float* __restrict__ src, int ld, int K, int mapid, const float* __restrict__ ks, int tile, f32x4 (&v)[4]) {
;   const int tid = TID();
;   const int kT = K >> 6, nt = tile / kT, kt = tile % kT, n0 = nt * 64, k0 = kt * 64;
;   const int n4 = (tid & 15) * 4, kr = tid >> 4;
;   const int n = n0 + n4;
;   const int sc = mapid == 1 ? srccol1(n) : (mapid == 2 ? srccol2(n) : n);
; #pragma unroll
;   for (int i = 0; i < 4; ++i) {
;     const int k = i * 16 + kr;
;     f32x4 x = {0.f, 0.f, 0.f, 0.f};
;     if (sc >= 0) x = *reinterpret_cast<const f32x4*>(src + (long)(k0 + k) * ld + sc);
;     if (ks) { const float g_ = ks[k0 + k]; x *= g_; }
;     v[i] = x;
;   }
; }
; DI void phase_prep1(const Params& p, char* smem) {
;     ...
;       else if (it < t1 + t2 + t3) tr_load(p.w_uq(), 3072, 512, 0, p.q_norm_g(), it - t1 - t2, v);
.LBB0_1149:
	s_and_b64 vcc, exec, s[0:1]
	s_cbranch_vccz .LBB0_1158
	s_waitcnt vmcnt(0) lgkmcnt(0)
	v_mov_b32_e32 v16, 0x12288
	ds_read2_b64 v[20:23], v16 offset1:1
	v_mov_b32_e32 v16, v202
	s_add_i32 s0, s10, s11
	s_and_b32 s0, s0, 0x7ffc0
	v_lshlrev_b32_e32 v17, 2, v16
	v_and_or_b32 v17, v17, 60, s0
	s_and_b32 s1, s2, 0x1c0
	v_ashrrev_i32_e32 v16, 4, v16
	v_lshlrev_b32_e32 v128, 2, v17
	s_waitcnt lgkmcnt(0)
	v_lshl_add_u64 v[28:29], v[22:23], 0, v[128:129]
	v_add_u32_e32 v30, s1, v16
	s_movk_i32 s0, 0x3000
	v_mad_i64_i32 v[16:17], s[0:1], v30, s0, v[28:29]
	global_load_dwordx4 v[16:19], v[16:17], off
	v_cmp_eq_u64_e32 vcc, 0, v[20:21]
	v_ashrrev_i32_e32 v31, 31, v30
	v_cmp_ne_u64_e64 s[0:1], 0, v[20:21]
	v_lshl_add_u64 v[32:33], v[30:31], 2, v[20:21]
	s_cbranch_vccnz .LBB0_1152
	global_load_dword v20, v[32:33], off
	s_waitcnt vmcnt(0) lgkmcnt(0)
	v_pk_mul_f32 v[18:19], v[18:19], v[20:21] op_sel_hi:[1,0]
	v_pk_mul_f32 v[16:17], v[16:17], v[20:21] op_sel_hi:[1,0]
.LBB0_1152:
	v_add_u32_e32 v20, 16, v30
	s_movk_i32 s2, 0x3000
	v_mad_i64_i32 v[20:21], s[2:3], v20, s2, v[28:29]
	global_load_dwordx4 v[20:23], v[20:21], off
	v_cndmask_b32_e64 v24, 0, 1, s[0:1]
	v_cmp_ne_u32_e64 s[6:7], 1, v24
	s_andn2_b64 vcc, exec, s[0:1]
	s_cbranch_vccnz .LBB0_1154
	global_load_dword v24, v[32:33], off offset:64
	s_waitcnt vmcnt(0) lgkmcnt(0)
	v_pk_mul_f32 v[22:23], v[22:23], v[24:25] op_sel_hi:[1,0]
	v_pk_mul_f32 v[20:21], v[20:21], v[24:25] op_sel_hi:[1,0]
.LBB0_1154:
	v_add_u32_e32 v24, 32, v30
	s_movk_i32 s0, 0x3000
	v_mad_i64_i32 v[24:25], s[0:1], v24, s0, v[28:29]
	global_load_dwordx4 v[24:27], v[24:25], off
	s_and_b64 vcc, exec, s[6:7]
	s_cbranch_vccnz .LBB0_1156
	global_load_dword v34, v[32:33], off offset:128
	s_waitcnt vmcnt(0) lgkmcnt(0)
	v_pk_mul_f32 v[26:27], v[26:27], v[34:35] op_sel_hi:[1,0]
	v_pk_mul_f32 v[24:25], v[24:25], v[34:35] op_sel_hi:[1,0]
.LBB0_1156:
	v_add_u32_e32 v30, 48, v30
	s_movk_i32 s0, 0x3000
	v_mad_i64_i32 v[28:29], s[0:1], v30, s0, v[28:29]
	global_load_dwordx4 v[28:31], v[28:29], off
	s_and_b64 vcc, exec, s[6:7]
	s_cbranch_vccnz .LBB0_1158
	global_load_dword v32, v[32:33], off offset:192
	s_mov_b64 s[0:1], 0
	s_waitcnt vmcnt(0) lgkmcnt(0)
	v_pk_mul_f32 v[30:31], v[30:31], v[32:33] op_sel_hi:[1,0]
	v_pk_mul_f32 v[28:29], v[28:29], v[32:33] op_sel_hi:[1,0]
	s_branch .LBB0_1159

;   DI const float* x() const { return (const float*)sp[0]; }
;   DI const float* cd_w_out() const { return (const float*)sp[21]; }
; DI int TID() { int t = threadIdx.x; asm volatile("" : "+v"(t)); return t; }
; DI void tr_load(const float* __restrict__ src, int ld, int K, int mapid, const float* __restrict__ ks, int tile, f32x4 (&v)[4]) {
;   const int tid = TID();
;   const int kT = K >> 6, nt = tile / kT, kt = tile % kT, n0 = nt * 64, k0 = kt * 64;
;   const int n4 = (tid & 15) * 4, kr = tid >> 4;
;   const int n = n0 + n4;
;   const int sc = mapid == 1 ? srccol1(n) : (mapid == 2 ? srccol2(n) : n);
; #pragma unroll
;   for (int i = 0; i < 4; ++i) {
;     const int k = i * 16 + kr;
;     f32x4 x = {0.f, 0.f, 0.f, 0.f};
;     if (sc >= 0) x = *reinterpret_cast<const f32x4*>(src + (long)(k0 + k) * ld + sc);
;     if (ks) { const float g_ = ks[k0 + k]; x *= g_; }
;     v[i] = x;
;   }
; }
; DI void phase_prep1(const Params& p, char* smem) {
;     ...
;       else if (it < t1 + t2) tr_load(p.cd_w_out(), 2048, 4096, 0, nullptr, it - t1, v);
.LBB0_1159:
	s_andn2_b64 vcc, exec, s[0:1]
	s_cbranch_vccnz .LBB0_1161
	s_waitcnt vmcnt(0) lgkmcnt(0)
	v_mov_b32_e32 v16, 0x122a8
	ds_read_b64 v[16:17], v16
	v_mov_b32_e32 v18, v202
	s_add_i32 s0, s14, 0xea40
	s_add_i32 s1, s8, s13
	s_and_b32 s0, s0, 0xffc0
	s_and_b32 s1, s1, 0xfc0
	v_lshlrev_b32_e32 v19, 2, v18
	v_ashrrev_i32_e32 v18, 4, v18
	v_and_or_b32 v19, v19, 60, s0
	v_add_u32_e32 v18, s1, v18
	v_lshlrev_b32_e32 v128, 2, v19
	v_ashrrev_i32_e32 v19, 31, v18
	s_waitcnt lgkmcnt(0)
	v_lshl_add_u64 v[16:17], v[16:17], 0, v[128:129]
	v_lshlrev_b64 v[18:19], 13, v[18:19]
	v_lshl_add_u64 v[24:25], v[16:17], 0, v[18:19]
	v_add_co_u32_e32 v20, vcc, s72, v24
	s_nop 1
	v_addc_co_u32_e32 v21, vcc, 0, v25, vcc
	v_add_co_u32_e32 v26, vcc, s86, v24
	global_load_dwordx4 v[16:19], v[24:25], off
	s_nop 0
	global_load_dwordx4 v[20:23], v[20:21], off
	v_addc_co_u32_e32 v27, vcc, 0, v25, vcc
	v_add_co_u32_e32 v28, vcc, s64, v24
	s_nop 1
	v_addc_co_u32_e32 v29, vcc, 0, v25, vcc
	global_load_dwordx4 v[24:27], v[26:27], off
	s_nop 0
	global_load_dwordx4 v[28:31], v[28:29], off

;   DI const float* x() const { return (const float*)sp[0]; }
;   DI const float* cd_w_in() const { return (const float*)sp[14]; }
; DI int TID() { int t = threadIdx.x; asm volatile("" : "+v"(t)); return t; }
; DI int srccol2(int n) {
;   if (n < 4096) { int base = n & ~255, j = n & 255, grp = j >> 6, w = j & 63; return base + (grp & 1) * 128 + (grp >> 1) * 64 + w; }
;   if (n < 6976) return n;
;   if (n < 7040) return -1;
;   return n - 64;
; }
; DI void tr_load(const float* __restrict__ src, int ld, int K, int mapid, const float* __restrict__ ks, int tile, f32x4 (&v)[4]) {
;   const int tid = TID();
;   const int kT = K >> 6, nt = tile / kT, kt = tile % kT, n0 = nt * 64, k0 = kt * 64;
;   const int n4 = (tid & 15) * 4, kr = tid >> 4;
;   const int n = n0 + n4;
;   const int sc = mapid == 1 ? srccol1(n) : (mapid == 2 ? srccol2(n) : n);
; #pragma unroll
;   for (int i = 0; i < 4; ++i) {
;     const int k = i * 16 + kr;
;     f32x4 x = {0.f, 0.f, 0.f, 0.f};
;     if (sc >= 0) x = *reinterpret_cast<const f32x4*>(src + (long)(k0 + k) * ld + sc);
; DI void phase_prep1(const Params& p, char* smem) {
;     ...
;       if (it < t1) tr_load(p.cd_w_in(), 11072, 2048, 2, nullptr, it, v);
.LBB0_1162:
	s_andn2_b64 vcc, exec, s[0:1]
	s_cbranch_vccnz .LBB0_1172
	s_ashr_i32 s0, s14, 31
	s_lshr_b32 s0, s0, 27
	ds_read_b64 v[32:33], v212
	s_add_i32 s0, s14, s0
	v_mov_b32_e32 v35, v202
	s_ashr_i32 s6, s0, 5
	s_lshl_b32 s0, s6, 6
	s_waitcnt vmcnt(0) lgkmcnt(0)
	v_lshlrev_b32_e32 v16, 2, v35
	v_and_or_b32 v16, v16, 60, s0
	s_movk_i32 s1, 0xfff
	v_cmp_lt_i32_e32 vcc, s1, v16
	s_and_saveexec_b64 s[2:3], vcc
	s_xor_b64 s[2:3], exec, s[2:3]
	s_cmpk_lt_u32 s0, 0x1b40
	s_cselect_b64 vcc, -1, 0
	s_cmpk_gt_u32 s0, 0x1b7f
	v_subrev_u32_e32 v17, 64, v16
	s_cselect_b64 s[0:1], -1, 0
	v_cndmask_b32_e64 v17, -1, v17, s[0:1]
	v_cndmask_b32_e32 v34, v17, v16, vcc
	s_andn2_saveexec_b64 s[0:1], s[2:3]
	s_and_b32 s2, s6, 3
	s_brev_b32 s2, s2
	v_and_b32_e32 v16, 0xffffff3c, v16
	s_lshr_b32 s2, s2, 24
	v_or_b32_e32 v34, s2, v16
	s_or_b64 exec, exec, s[0:1]
	v_cmp_gt_i32_e32 vcc, 0, v34
	s_and_saveexec_b64 s[0:1], vcc
	s_xor_b64 s[0:1], exec, s[0:1]
	s_or_saveexec_b64 s[0:1], s[0:1]
	v_mov_b32_e32 v128, v129
	v_mov_b32_e32 v130, v129
	v_mov_b32_e32 v131, v129
	v_mov_b64_e32 v[28:29], v[128:129]
	v_mov_b32_e32 v16, 0
	v_mov_b64_e32 v[30:31], v[130:131]
	v_mov_b32_e32 v17, 0
	v_mov_b32_e32 v18, 0
	v_mov_b32_e32 v19, 0
	v_mov_b32_e32 v20, 0
	v_mov_b32_e32 v21, 0
	v_mov_b32_e32 v22, 0
	v_mov_b32_e32 v23, 0
	v_mov_b32_e32 v24, 0
	v_mov_b32_e32 v25, 0
	v_mov_b32_e32 v26, 0
	v_mov_b32_e32 v27, 0
	s_xor_b64 exec, exec, s[0:1]
	s_cbranch_execz .LBB0_1171
	v_ashrrev_i32_e32 v16, 4, v35
	s_lshl_b32 s2, s6, 11
	v_mov_b32_e32 v35, v129
	v_subrev_u32_e32 v16, s2, v16
	s_add_i32 s2, s8, s13
	v_lshl_add_u64 v[24:25], v[34:35], 2, v[32:33]
	v_add_u32_e32 v28, s2, v16
	s_mov_b32 s6, 0xad00
	v_mad_i64_i32 v[16:17], s[2:3], v28, s6, v[24:25]
	v_add_u32_e32 v18, 16, v28
	v_add_u32_e32 v26, 32, v28
	v_add_u32_e32 v28, 48, v28
	v_mad_i64_i32 v[20:21], s[2:3], v18, s6, v[24:25]
	v_mad_i64_i32 v[26:27], s[2:3], v26, s6, v[24:25]
	v_mad_i64_i32 v[28:29], s[2:3], v28, s6, v[24:25]
	global_load_dwordx4 v[16:19], v[16:17], off
	s_nop 0
	global_load_dwordx4 v[20:23], v[20:21], off
	s_nop 0
	global_load_dwordx4 v[24:27], v[26:27], off
	s_nop 0
	global_load_dwordx4 v[28:31], v[28:29], off

;   DI const float* ln_g() const { return (const float*)sp[6]; }
;   DI const float* ln_b() const { return (const float*)sp[7]; }
; DI float wsum(float v) { for (int o = 32; o > 0; o >>= 1) v += __shfl_xor(v, o); return v; }
; DI void row_ln(float (&v)[32], const float* __restrict__ g, const float* __restrict__ bta, int lane) {
;   float sm = 0.f;
; #pragma unroll
;   for (int i = 0; i < 32; ++i) sm += v[i];
;   const float mean = wsum(sm) * (1.f / DM);
;   float sq = 0.f;
; #pragma unroll
;   for (int i = 0; i < 32; ++i) { v[i] -= mean; sq += v[i] * v[i]; }
;   const float rstd = rsqrtf(wsum(sq) * (1.f / DM) + EPS);
; DI void phase_mod(const Params& p, int g, int layer, char* smem) {
;     ...
;       float* s = P_ZX + r * DM;
; #pragma unroll
;       for (int j = 0; j < 8; ++j) { const f32x4 a = *(const f32x4*)(s + lane * 4 + 256 * j); v[4 * j] = a[0]; v[4 * j + 1] = a[1]; v[4 * j + 2] = a[2]; v[4 * j + 3] = a[3]; }
;       row_ln(v, p.ln_g(), p.ln_b(), lane);
.LBB0_1185:
	v_mul_hi_i32 v0, v80, s73
	v_lshrrev_b32_e32 v1, 31, v0
	v_ashrrev_i32_e32 v0, 9, v0
	v_add_u32_e32 v126, v0, v1
	v_ashrrev_i32_e32 v81, 31, v80
	v_mul_i32_i24_e32 v0, 0x900, v126
	v_sub_u32_e32 v125, v80, v0
	v_lshlrev_b64 v[0:1], 13, v[80:81]
	v_lshl_add_u64 v[86:87], v[84:85], 0, v[0:1]
	global_load_dwordx4 v[32:35], v[86:87], off
	global_load_dwordx4 v[40:43], v[86:87], off offset:1024
	global_load_dwordx4 v[28:31], v[86:87], off offset:2048
	global_load_dwordx4 v[20:23], v[86:87], off offset:3072
	v_add_co_u32_e32 v88, vcc, s9, v86
	v_mov_b32_e32 v16, 0x12230
	s_nop 0
	v_addc_co_u32_e32 v89, vcc, 0, v87, vcc
	global_load_dwordx4 v[12:15], v[88:89], off
	global_load_dwordx4 v[8:11], v[88:89], off offset:1024
	global_load_dwordx4 v[4:7], v[88:89], off offset:2048
	global_load_dwordx4 v[0:3], v[88:89], off offset:3072
	ds_read_b128 v[16:19], v16
	s_waitcnt lgkmcnt(0)
	v_lshl_add_u64 v[56:57], v[16:17], 0, v[128:129]
	v_lshl_add_u64 v[60:61], v[18:19], 0, v[128:129]
	v_add_co_u32_e32 v130, vcc, s9, v56
	s_waitcnt vmcnt(0)
	v_add_f32_e32 v24, 0, v32
	v_add_f32_e32 v24, v33, v24
	v_add_f32_e32 v24, v34, v24
	v_add_f32_e32 v24, v35, v24
	s_waitcnt vmcnt(6)
	v_add_f32_e32 v24, v40, v24
	v_add_f32_e32 v24, v41, v24
	v_add_f32_e32 v24, v42, v24
	v_add_f32_e32 v24, v43, v24
	s_waitcnt vmcnt(5)
	v_add_f32_e32 v24, v28, v24
	v_add_f32_e32 v24, v29, v24
	v_add_f32_e32 v24, v30, v24
	v_add_f32_e32 v24, v31, v24
	s_waitcnt vmcnt(4)
	v_add_f32_e32 v24, v20, v24
	v_add_f32_e32 v24, v21, v24
	v_add_f32_e32 v24, v22, v24
	v_add_f32_e32 v24, v23, v24
	s_waitcnt vmcnt(3)
	v_add_f32_e32 v24, v12, v24
	v_add_f32_e32 v24, v13, v24
	v_add_f32_e32 v24, v14, v24
	v_add_f32_e32 v24, v15, v24
	s_waitcnt vmcnt(2)
	v_add_f32_e32 v24, v8, v24
	v_add_f32_e32 v24, v9, v24
	v_add_f32_e32 v24, v10, v24
	v_add_f32_e32 v24, v11, v24
	s_waitcnt vmcnt(1)
	v_add_f32_e32 v24, v4, v24
	v_add_f32_e32 v24, v5, v24
	v_add_f32_e32 v24, v6, v24
	v_add_f32_e32 v24, v7, v24
	s_waitcnt vmcnt(0)
	v_add_f32_e32 v24, v0, v24
	v_add_f32_e32 v24, v1, v24
	v_add_f32_e32 v24, v2, v24
	v_add_f32_e32 v24, v3, v24
	ds_bpermute_b32 v25, v91, v24
	v_addc_co_u32_e32 v131, vcc, 0, v57, vcc
	v_add_co_u32_e32 v138, vcc, s9, v60
	s_waitcnt lgkmcnt(0)
	v_add_f32_e32 v24, v24, v25
	ds_bpermute_b32 v25, v120, v24
	v_addc_co_u32_e32 v139, vcc, 0, v61, vcc
	s_waitcnt lgkmcnt(0)
	v_add_f32_e32 v24, v24, v25
	ds_bpermute_b32 v25, v121, v24
	s_waitcnt lgkmcnt(0)
	v_add_f32_e32 v24, v24, v25
	ds_bpermute_b32 v25, v122, v24
	s_waitcnt lgkmcnt(0)
	v_add_f32_e32 v24, v24, v25
	ds_bpermute_b32 v25, v123, v24
	s_waitcnt lgkmcnt(0)
	v_add_f32_e32 v24, v24, v25
	ds_bpermute_b32 v25, v124, v24
	s_waitcnt lgkmcnt(0)
	v_add_f32_e32 v24, v24, v25
	v_mul_f32_e32 v90, 0x3a000000, v24
	global_load_dwordx4 v[16:19], v[56:57], off
	global_load_dwordx4 v[24:27], v[60:61], off
	v_pk_add_f32 v[92:93], v[32:33], v[90:91] op_sel_hi:[1,0] neg_lo:[0,1] neg_hi:[0,1]
	v_pk_add_f32 v[94:95], v[34:35], v[90:91] op_sel_hi:[1,0] neg_lo:[0,1] neg_hi:[0,1]
	v_pk_mul_f32 v[104:105], v[92:93], v[92:93]
	global_load_dwordx4 v[32:35], v[56:57], off offset:1024
	global_load_dwordx4 v[36:39], v[60:61], off offset:1024
	v_pk_mul_f32 v[106:107], v[94:95], v[94:95]
	v_pk_add_f32 v[96:97], v[40:41], v[90:91] op_sel_hi:[1,0] neg_lo:[0,1] neg_hi:[0,1]
	v_pk_add_f32 v[98:99], v[42:43], v[90:91] op_sel_hi:[1,0] neg_lo:[0,1] neg_hi:[0,1]
	v_pk_add_f32 v[100:101], v[28:29], v[90:91] op_sel_hi:[1,0] neg_lo:[0,1] neg_hi:[0,1]
	v_pk_add_f32 v[102:103], v[30:31], v[90:91] op_sel_hi:[1,0] neg_lo:[0,1] neg_hi:[0,1]
	v_pk_add_f32 v[108:109], v[20:21], v[90:91] op_sel_hi:[1,0] neg_lo:[0,1] neg_hi:[0,1]
	v_pk_add_f32 v[110:111], v[22:23], v[90:91] op_sel_hi:[1,0] neg_lo:[0,1] neg_hi:[0,1]
	v_pk_add_f32 v[12:13], v[12:13], v[90:91] op_sel_hi:[1,0] neg_lo:[0,1] neg_hi:[0,1]
	v_pk_add_f32 v[14:15], v[14:15], v[90:91] op_sel_hi:[1,0] neg_lo:[0,1] neg_hi:[0,1]
	v_pk_add_f32 v[8:9], v[8:9], v[90:91] op_sel_hi:[1,0] neg_lo:[0,1] neg_hi:[0,1]
	v_pk_add_f32 v[10:11], v[10:11], v[90:91] op_sel_hi:[1,0] neg_lo:[0,1] neg_hi:[0,1]
	v_pk_add_f32 v[4:5], v[4:5], v[90:91] op_sel_hi:[1,0] neg_lo:[0,1] neg_hi:[0,1]
	v_pk_add_f32 v[6:7], v[6:7], v[90:91] op_sel_hi:[1,0] neg_lo:[0,1] neg_hi:[0,1]
	v_pk_add_f32 v[0:1], v[0:1], v[90:91] op_sel_hi:[1,0] neg_lo:[0,1] neg_hi:[0,1]
	v_pk_add_f32 v[2:3], v[2:3], v[90:91] op_sel_hi:[1,0] neg_lo:[0,1] neg_hi:[0,1]
	v_add_f32_e32 v90, v104, v105
	v_add_f32_e32 v90, v106, v90
	v_pk_mul_f32 v[112:113], v[96:97], v[96:97]
	v_add_f32_e32 v90, v107, v90
	global_load_dwordx4 v[40:43], v[56:57], off offset:2048
	global_load_dwordx4 v[44:47], v[60:61], off offset:2048
	v_add_f32_e32 v90, v112, v90
	v_pk_mul_f32 v[114:115], v[98:99], v[98:99]
	v_add_f32_e32 v90, v113, v90
	global_load_dwordx4 v[48:51], v[56:57], off offset:3072
	global_load_dwordx4 v[52:55], v[60:61], off offset:3072
	v_add_f32_e32 v90, v114, v90
	global_load_dwordx4 v[56:59], v[130:131], off
	global_load_dwordx4 v[60:63], v[138:139], off
	global_load_dwordx4 v[64:67], v[130:131], off offset:1024
	global_load_dwordx4 v[68:71], v[138:139], off offset:1024
	global_load_dwordx4 v[72:75], v[130:131], off offset:2048
	global_load_dwordx4 v[76:79], v[138:139], off offset:2048
	global_load_dwordx4 v[134:137], v[130:131], off offset:3072
	s_nop 0
	global_load_dwordx4 v[138:141], v[138:139], off offset:3072
	v_pk_mul_f32 v[28:29], v[100:101], v[100:101]
	v_add_f32_e32 v90, v115, v90
	v_add_f32_e32 v28, v28, v90
	v_pk_mul_f32 v[30:31], v[102:103], v[102:103]
	v_add_f32_e32 v28, v29, v28
	v_add_f32_e32 v28, v30, v28
	v_pk_mul_f32 v[20:21], v[108:109], v[108:109]
	v_add_f32_e32 v28, v31, v28
	v_add_f32_e32 v20, v20, v28
	v_pk_mul_f32 v[22:23], v[110:111], v[110:111]
	v_add_f32_e32 v20, v21, v20
	v_add_f32_e32 v20, v22, v20
	v_pk_mul_f32 v[116:117], v[12:13], v[12:13]
	v_add_f32_e32 v20, v23, v20
	v_add_f32_e32 v20, v116, v20
	v_pk_mul_f32 v[118:119], v[14:15], v[14:15]
	v_add_f32_e32 v20, v117, v20
	v_add_f32_e32 v20, v118, v20
	v_pk_mul_f32 v[142:143], v[8:9], v[8:9]
	v_add_f32_e32 v20, v119, v20
	v_add_f32_e32 v20, v142, v20
	v_pk_mul_f32 v[144:145], v[10:11], v[10:11]
	v_add_f32_e32 v20, v143, v20
	v_add_f32_e32 v20, v144, v20
	v_pk_mul_f32 v[146:147], v[4:5], v[4:5]
	v_add_f32_e32 v20, v145, v20
	v_add_f32_e32 v20, v146, v20
	v_pk_mul_f32 v[148:149], v[6:7], v[6:7]
	v_add_f32_e32 v20, v147, v20
	v_add_f32_e32 v20, v148, v20
	v_pk_mul_f32 v[130:131], v[0:1], v[0:1]
	v_add_f32_e32 v20, v149, v20
	v_add_f32_e32 v20, v130, v20
	v_pk_mul_f32 v[150:151], v[2:3], v[2:3]
	v_add_f32_e32 v20, v131, v20
	v_add_f32_e32 v20, v150, v20
	v_add_f32_e32 v20, v151, v20
	ds_bpermute_b32 v21, v91, v20
	s_waitcnt lgkmcnt(0)
;   DI const float* x() const { return (const float*)sp[0]; }
;   DI const float* ctx() const { return (const float*)sp[2]; }
;   DI const float* ln_g() const { return (const float*)sp[6]; }
;   DI const float* ln_b() const { return (const float*)sp[7]; }
; DI void row_ln(float (&v)[32], const float* __restrict__ g, const float* __restrict__ bta, int lane) {
;     ...
;   for (int i = 0; i < 32; ++i) { v[i] -= mean; sq += v[i] * v[i]; }
;   const float rstd = rsqrtf(wsum(sq) * (1.f / DM) + EPS);
; #pragma unroll
;   for (int j = 0; j < 8; ++j) {
;     const f32x4 gg = *(const f32x4*)(g + lane * 4 + 256 * j), bb = *(const f32x4*)(bta + lane * 4 + 256 * j);
; #pragma unroll
;     for (int e = 0; e < 4; ++e) v[4 * j + e] = v[4 * j + e] * rstd * gg[e] + bb[e];
;   }
; }
; DI void phase_mod(const Params& p, int g, int layer, char* smem) {
;   (void)smem;
;   const int tid = TID(), lane = tid & 63, w = tid >> 6;
;   bfu* h = (bfu*)(OPQ(p.ws + WS_G) + (layer == 0 ? L0_H : L1_H));
;   for (int i = blockIdx.x * 4 + w; i < MG; i += gridDim.x * 4) {
;     const long r = (long)g * MG + i; const int b = (int)(r / T), t = (int)(r % T);
;     float v[32];
;     if (layer == 0) {
;       const float* s = t < CTX ? p.ctx() + ((long)b * CTX + t) * DM : p.x() + ((long)b * SEQ + (t - CTX)) * DM;
; #pragma unroll
;       for (int j = 0; j < 8; ++j) { const f32x4 a = *(const f32x4*)(s + lane * 4 + 256 * j); v[4 * j] = a[0]; v[4 * j + 1] = a[1]; v[4 * j + 2] = a[2]; v[4 * j + 3] = a[3]; }
;     } else {
;       float* s = P_ZX + r * DM;
; #pragma unroll
;       for (int j = 0; j < 8; ++j) { const f32x4 a = *(const f32x4*)(s + lane * 4 + 256 * j); v[4 * j] = a[0]; v[4 * j + 1] = a[1]; v[4 * j + 2] = a[2]; v[4 * j + 3] = a[3]; }
;       row_ln(v, p.ln_g(), p.ln_b(), lane);
; #pragma unroll
;       for (int j = 0; j < 8; ++j) { const f32x4 o = {v[4 * j], v[4 * j + 1], v[4 * j + 2], v[4 * j + 3]}; *(f32x4*)(s + lane * 4 + 256 * j) = o; }
;     }
;     const float* md = P_MOD + ((long)layer * 9 + (t < CTX ? 8 : b)) * 6144;
; #pragma unroll
;     for (int j = 0; j < 8; ++j) {
;       const f32x4 sh = *(const f32x4*)(md + lane * 4 + 256 * j), sc = *(const f32x4*)(md + 2048 + lane * 4 + 256 * j);
;       u32x2 o = {cvtpk(v[4 * j] * (1.f + sc[0]) + sh[0], v[4 * j + 1] * (1.f + sc[1]) + sh[1]), cvtpk(v[4 * j + 2] * (1.f + sc[2]) + sh[2], v[4 * j + 3] * (1.f + sc[3]) + sh[3])};
	v_add_f32_e32 v20, v20, v21
	ds_bpermute_b32 v21, v120, v20
	s_waitcnt lgkmcnt(0)
	v_add_f32_e32 v20, v20, v21
	ds_bpermute_b32 v21, v121, v20
	s_waitcnt lgkmcnt(0)
	v_add_f32_e32 v20, v20, v21
	ds_bpermute_b32 v21, v122, v20
	s_waitcnt lgkmcnt(0)
	v_add_f32_e32 v20, v20, v21
	ds_bpermute_b32 v21, v123, v20
	s_waitcnt lgkmcnt(0)
	v_add_f32_e32 v20, v20, v21
	ds_bpermute_b32 v21, v124, v20
	s_waitcnt lgkmcnt(0)
	v_add_f32_e32 v20, v20, v21
	v_fmamk_f32 v20, v20, 0x3a000000, v190
	v_cmp_gt_f32_e32 vcc, s11, v20
	v_mul_f32_e32 v21, 0x4b800000, v20
	s_nop 0
	v_cndmask_b32_e32 v20, v20, v21, vcc
	v_rsq_f32_e32 v20, v20
	s_nop 0
	v_mul_f32_e32 v21, 0x45800000, v20
	v_cndmask_b32_e32 v90, v20, v21, vcc
	v_pk_mul_f32 v[20:21], v[92:93], v[90:91] op_sel_hi:[1,0]
	v_cmp_lt_i32_e32 vcc, s8, v125
	s_waitcnt vmcnt(0)
	v_pk_fma_f32 v[28:29], v[16:17], v[20:21], v[24:25]
	v_pk_mul_f32 v[16:17], v[94:95], v[90:91] op_sel_hi:[1,0]
	v_pk_mul_f32 v[12:13], v[12:13], v[90:91] op_sel_hi:[1,0]
	v_pk_fma_f32 v[30:31], v[18:19], v[16:17], v[26:27]
	v_pk_mul_f32 v[16:17], v[96:97], v[90:91] op_sel_hi:[1,0]
	v_pk_mul_f32 v[18:19], v[110:111], v[90:91] op_sel_hi:[1,0]
	v_pk_fma_f32 v[24:25], v[32:33], v[16:17], v[36:37]
	v_add_u32_e32 v32, 9, v126
	v_cndmask_b32_e32 v32, 17, v32, vcc
	v_pk_mul_f32 v[16:17], v[98:99], v[90:91] op_sel_hi:[1,0]
	v_mul_hi_i32_i24_e32 v33, 0x6000, v32
	v_mul_i32_i24_e32 v32, 0x6000, v32
	v_pk_fma_f32 v[26:27], v[34:35], v[16:17], v[38:39]
	v_pk_mul_f32 v[16:17], v[100:101], v[90:91] op_sel_hi:[1,0]
	v_lshl_add_u64 v[32:33], s[6:7], 0, v[32:33]
	v_pk_fma_f32 v[20:21], v[40:41], v[16:17], v[44:45]
	v_pk_mul_f32 v[16:17], v[102:103], v[90:91] op_sel_hi:[1,0]
	v_lshl_add_u64 v[36:37], v[32:33], 0, v[128:129]
	v_pk_fma_f32 v[22:23], v[42:43], v[16:17], v[46:47]
	v_pk_mul_f32 v[16:17], v[108:109], v[90:91] op_sel_hi:[1,0]
	v_pk_mul_f32 v[14:15], v[14:15], v[90:91] op_sel_hi:[1,0]
	v_pk_mul_f32 v[8:9], v[8:9], v[90:91] op_sel_hi:[1,0]
	v_pk_mul_f32 v[10:11], v[10:11], v[90:91] op_sel_hi:[1,0]
	v_pk_mul_f32 v[4:5], v[4:5], v[90:91] op_sel_hi:[1,0]
	v_pk_mul_f32 v[6:7], v[6:7], v[90:91] op_sel_hi:[1,0]
	v_pk_mul_f32 v[0:1], v[0:1], v[90:91] op_sel_hi:[1,0]
	v_pk_mul_f32 v[2:3], v[2:3], v[90:91] op_sel_hi:[1,0]
	v_add_co_u32_e32 v34, vcc, s10, v36
	v_pk_fma_f32 v[16:17], v[48:49], v[16:17], v[52:53]
	v_pk_fma_f32 v[18:19], v[50:51], v[18:19], v[54:55]
	v_pk_fma_f32 v[12:13], v[56:57], v[12:13], v[60:61]
	v_pk_fma_f32 v[14:15], v[58:59], v[14:15], v[62:63]
	v_pk_fma_f32 v[8:9], v[64:65], v[8:9], v[68:69]
	v_pk_fma_f32 v[10:11], v[66:67], v[10:11], v[70:71]
	v_pk_fma_f32 v[4:5], v[72:73], v[4:5], v[76:77]
	v_pk_fma_f32 v[6:7], v[74:75], v[6:7], v[78:79]
	v_pk_fma_f32 v[0:1], v[134:135], v[0:1], v[138:139]
	v_pk_fma_f32 v[2:3], v[136:137], v[2:3], v[140:141]
	global_store_dwordx4 v[86:87], v[28:31], off
	global_store_dwordx4 v[86:87], v[24:27], off offset:1024
	global_store_dwordx4 v[86:87], v[20:23], off offset:2048
	global_store_dwordx4 v[86:87], v[16:19], off offset:3072
	global_store_dwordx4 v[88:89], v[12:15], off
	global_store_dwordx4 v[88:89], v[8:11], off offset:1024
	global_store_dwordx4 v[88:89], v[4:7], off offset:2048
	global_store_dwordx4 v[88:89], v[0:3], off offset:3072
	v_addc_co_u32_e32 v35, vcc, 0, v37, vcc
	global_load_dwordx4 v[40:43], v[36:37], off
	global_load_dwordx4 v[44:47], v[34:35], off offset:-4096
	v_lshlrev_b64 v[32:33], 12, v[80:81]
	v_lshl_add_u64 v[32:33], v[82:83], 0, v[32:33]
	v_lshl_add_u64 v[38:39], v[36:37], 0, s[90:91]
	v_add_u32_e32 v80, s80, v80
	s_waitcnt vmcnt(0)
; DI unsigned cvtpk(float lo, float hi) { f32x2_t v = {lo, hi}; bf16x2_t b = __builtin_convertvector(v, bf16x2_t); return __builtin_bit_cast(unsigned, b); }
; DI void phase_mod(const Params& p, int g, int layer, char* smem) {
;     ...
;     const float* md = P_MOD + ((long)layer * 9 + (t < CTX ? 8 : b)) * 6144;
; #pragma unroll
;     for (int j = 0; j < 8; ++j) {
;       const f32x4 sh = *(const f32x4*)(md + lane * 4 + 256 * j), sc = *(const f32x4*)(md + 2048 + lane * 4 + 256 * j);
;       u32x2 o = {cvtpk(v[4 * j] * (1.f + sc[0]) + sh[0], v[4 * j + 1] * (1.f + sc[1]) + sh[1]), cvtpk(v[4 * j + 2] * (1.f + sc[2]) + sh[2], v[4 * j + 3] * (1.f + sc[3]) + sh[3])};
;       *reinterpret_cast<u32x2*>(h + (long)i * DM + lane * 4 + 256 * j) = o;
;     }
	v_pk_add_f32 v[44:45], v[44:45], 1.0 op_sel_hi:[1,0]
	s_nop 0
	v_pk_fma_f32 v[28:29], v[44:45], v[28:29], v[40:41]
	v_pk_add_f32 v[40:41], v[46:47], 1.0 op_sel_hi:[1,0]
	v_cvt_pk_bf16_f32 v28, v28, v29
	v_pk_fma_f32 v[30:31], v[40:41], v[30:31], v[42:43]
	s_nop 0
	v_cvt_pk_bf16_f32 v29, v30, v31
	global_store_dwordx2 v[32:33], v[28:29], off
	global_load_dwordx4 v[28:31], v[36:37], off offset:1024
	s_nop 0
	global_load_dwordx4 v[40:43], v[38:39], off offset:1024
	s_waitcnt vmcnt(0)
	v_pk_add_f32 v[40:41], v[40:41], 1.0 op_sel_hi:[1,0]
	s_nop 0
	v_pk_fma_f32 v[24:25], v[40:41], v[24:25], v[28:29]
	v_pk_add_f32 v[28:29], v[42:43], 1.0 op_sel_hi:[1,0]
	v_cvt_pk_bf16_f32 v24, v24, v25
	v_pk_fma_f32 v[26:27], v[28:29], v[26:27], v[30:31]
	s_nop 0
	v_cvt_pk_bf16_f32 v25, v26, v27
	global_store_dwordx2 v[32:33], v[24:25], off offset:512
	global_load_dwordx4 v[24:27], v[36:37], off offset:2048
	s_nop 0
	global_load_dwordx4 v[28:31], v[38:39], off offset:2048
	s_waitcnt vmcnt(0)
	v_pk_add_f32 v[28:29], v[28:29], 1.0 op_sel_hi:[1,0]
	s_nop 0
	v_pk_fma_f32 v[20:21], v[28:29], v[20:21], v[24:25]
	v_pk_add_f32 v[24:25], v[30:31], 1.0 op_sel_hi:[1,0]
	v_cvt_pk_bf16_f32 v20, v20, v21
	v_pk_fma_f32 v[22:23], v[24:25], v[22:23], v[26:27]
	s_nop 0
	v_cvt_pk_bf16_f32 v21, v22, v23
	global_store_dwordx2 v[32:33], v[20:21], off offset:1024
	global_load_dwordx4 v[20:23], v[36:37], off offset:3072
	s_nop 0
	global_load_dwordx4 v[24:27], v[38:39], off offset:3072
	s_waitcnt vmcnt(0)
	v_pk_add_f32 v[24:25], v[24:25], 1.0 op_sel_hi:[1,0]
	s_nop 0
	v_pk_fma_f32 v[16:17], v[24:25], v[16:17], v[20:21]
	v_pk_add_f32 v[20:21], v[26:27], 1.0 op_sel_hi:[1,0]
	v_cvt_pk_bf16_f32 v16, v16, v17
	v_pk_fma_f32 v[18:19], v[20:21], v[18:19], v[22:23]
	v_add_co_u32_e32 v24, vcc, s9, v36
	v_cvt_pk_bf16_f32 v17, v18, v19
	global_store_dwordx2 v[32:33], v[16:17], off offset:1536
	v_addc_co_u32_e32 v25, vcc, 0, v37, vcc
	global_load_dwordx4 v[16:19], v[24:25], off
	global_load_dwordx4 v[20:23], v[34:35], off
	v_cmp_lt_i32_e32 vcc, s12, v80
	s_or_b64 s[4:5], vcc, s[4:5]
	s_waitcnt vmcnt(0)
	v_pk_add_f32 v[20:21], v[20:21], 1.0 op_sel_hi:[1,0]
	s_nop 0
	v_pk_fma_f32 v[12:13], v[20:21], v[12:13], v[16:17]
	v_pk_add_f32 v[16:17], v[22:23], 1.0 op_sel_hi:[1,0]
	v_cvt_pk_bf16_f32 v12, v12, v13
	v_pk_fma_f32 v[14:15], v[16:17], v[14:15], v[18:19]
	s_nop 0
	v_cvt_pk_bf16_f32 v13, v14, v15
	global_store_dwordx2 v[32:33], v[12:13], off offset:2048
	global_load_dwordx4 v[12:15], v[24:25], off offset:1024
	s_nop 0
	global_load_dwordx4 v[16:19], v[34:35], off offset:1024
	s_waitcnt vmcnt(0)
	v_pk_add_f32 v[16:17], v[16:17], 1.0 op_sel_hi:[1,0]
	s_nop 0
	v_pk_fma_f32 v[8:9], v[16:17], v[8:9], v[12:13]
	v_pk_add_f32 v[12:13], v[18:19], 1.0 op_sel_hi:[1,0]
	v_cvt_pk_bf16_f32 v8, v8, v9
	v_pk_fma_f32 v[10:11], v[12:13], v[10:11], v[14:15]
	s_nop 0
	v_cvt_pk_bf16_f32 v9, v10, v11
	global_store_dwordx2 v[32:33], v[8:9], off offset:2560
	global_load_dwordx4 v[8:11], v[24:25], off offset:2048
	s_nop 0
	global_load_dwordx4 v[12:15], v[34:35], off offset:2048
	s_waitcnt vmcnt(0)
	v_pk_add_f32 v[12:13], v[12:13], 1.0 op_sel_hi:[1,0]
	s_nop 0
	v_pk_fma_f32 v[4:5], v[12:13], v[4:5], v[8:9]
	v_pk_add_f32 v[8:9], v[14:15], 1.0 op_sel_hi:[1,0]
	v_cvt_pk_bf16_f32 v4, v4, v5
	v_pk_fma_f32 v[6:7], v[8:9], v[6:7], v[10:11]
	s_nop 0
	v_cvt_pk_bf16_f32 v5, v6, v7
	global_store_dwordx2 v[32:33], v[4:5], off offset:3072
	global_load_dwordx4 v[4:7], v[24:25], off offset:3072
	s_nop 0
	global_load_dwordx4 v[8:11], v[34:35], off offset:3072
	s_waitcnt vmcnt(0)
	v_pk_add_f32 v[8:9], v[8:9], 1.0 op_sel_hi:[1,0]
	s_nop 0
	v_pk_fma_f32 v[0:1], v[8:9], v[0:1], v[4:5]
	v_pk_add_f32 v[4:5], v[10:11], 1.0 op_sel_hi:[1,0]
	v_cvt_pk_bf16_f32 v0, v0, v1
	v_pk_fma_f32 v[2:3], v[4:5], v[2:3], v[6:7]
	s_nop 0
	v_cvt_pk_bf16_f32 v1, v2, v3
	global_store_dwordx2 v[32:33], v[0:1], off offset:3584
	s_andn2_b64 exec, exec, s[4:5]
	s_cbranch_execnz .LBB0_1185

;   DI const float* x() const { return (const float*)sp[0]; }
;   DI const float* c() const { return (const float*)sp[1]; }
; __device__ __forceinline__ unsigned xb_ld(unsigned* p)              { return __hip_atomic_load(p, __ATOMIC_RELAXED, __HIP_MEMORY_SCOPE_AGENT); }
; __device__ __forceinline__ void xcd_barrier_complete(unsigned* bar, unsigned x, unsigned& nloc, unsigned& nx) {
;     const unsigned G = gridDim.x * gridDim.y * gridDim.z;
;     unsigned sum, cnt, mine, sp = 0u;
;     for (;;) {
;         sum = 0u; cnt = 0u; mine = 0u;
; #pragma unroll
;         for (unsigned j = 0; j < 16; ++j) { const unsigned c = xb_ld(&bar[XB_XCNT(j)]); sum += c; cnt += (c > 0u) ? 1u : 0u; mine = (j == x) ? c : mine; }
;         if (sum == G) break;
;         __builtin_amdgcn_s_sleep(1);
;         if ((++sp & 255u) == 0u) { if (xb_ld(&bar[XB_TMO])) break; if (sp > XB_SPIN_CAP) { atomicAdd(&bar[XB_TMO], 1u); break; } }
;     }
;     nloc = mine > 0u ? mine : 1u; nx = cnt > 0u ? cnt : 1u;
; }
.LBB0_1192:
	s_waitcnt lgkmcnt(0)
	v_mov_b64_e32 v[0:1], s[6:7]
	v_mov_b64_e32 v[2:3], s[8:9]
	global_load_dword v0, v[0:1], off sc1
	v_readlane_b32 s2, v254, 15
	global_load_dword v1, v[2:3], off sc1
	v_mov_b64_e32 v[2:3], s[10:11]
	global_load_dword v2, v[2:3], off sc1
	s_or_b64 s[48:49], s[48:49], exec
	s_or_b64 s[46:47], s[46:47], exec
	s_waitcnt vmcnt(0) lgkmcnt(0)
	v_add_u32_e32 v4, v1, v0
	v_add_u32_e32 v6, v4, v2
	v_mov_b64_e32 v[4:5], s[12:13]
	global_load_dword v3, v[4:5], off sc1
	v_mov_b64_e32 v[4:5], s[14:15]
	global_load_dword v4, v[4:5], off sc1
	s_waitcnt vmcnt(0) lgkmcnt(0)
	v_add_u32_e32 v6, v6, v3
	v_add_u32_e32 v8, v6, v4
	v_mov_b64_e32 v[6:7], s[16:17]
	global_load_dword v5, v[6:7], off sc1
	v_mov_b64_e32 v[6:7], s[18:19]
	global_load_dword v6, v[6:7], off sc1
	s_waitcnt vmcnt(0) lgkmcnt(0)
	v_add_u32_e32 v8, v8, v5
	v_add_u32_e32 v10, v8, v6
	v_mov_b64_e32 v[8:9], s[20:21]
	global_load_dword v7, v[8:9], off sc1
	v_mov_b64_e32 v[8:9], s[22:23]
	global_load_dword v8, v[8:9], off sc1
	s_waitcnt vmcnt(0) lgkmcnt(0)
	v_add_u32_e32 v10, v10, v7
	v_add_u32_e32 v12, v10, v8
	v_mov_b64_e32 v[10:11], s[24:25]
	global_load_dword v9, v[10:11], off sc1
	v_mov_b64_e32 v[10:11], s[26:27]
	global_load_dword v10, v[10:11], off sc1
	s_waitcnt vmcnt(0) lgkmcnt(0)
	v_add_u32_e32 v12, v12, v9
	v_add_u32_e32 v14, v12, v10
	v_mov_b64_e32 v[12:13], s[28:29]
	global_load_dword v11, v[12:13], off sc1
	v_mov_b64_e32 v[12:13], s[30:31]
	global_load_dword v12, v[12:13], off sc1
	s_waitcnt vmcnt(0) lgkmcnt(0)
	v_add_u32_e32 v14, v14, v11
	v_add_u32_e32 v16, v14, v12
	v_mov_b64_e32 v[14:15], s[34:35]
	global_load_dword v13, v[14:15], off sc1
	v_mov_b64_e32 v[14:15], s[38:39]
	global_load_dword v14, v[14:15], off sc1
	s_waitcnt vmcnt(0) lgkmcnt(0)
	v_add_u32_e32 v16, v16, v13
	v_add_u32_e32 v18, v16, v14
	v_mov_b64_e32 v[16:17], s[40:41]
	global_load_dword v15, v[16:17], off sc1
	s_waitcnt vmcnt(0) lgkmcnt(0)
	v_add_u32_e32 v16, v18, v15
	v_cmp_ne_u32_e32 vcc, s2, v16
	s_and_saveexec_b64 s[2:3], vcc
	s_cbranch_execz .LBB0_1191
	s_and_b32 s52, s71, 0xff
	s_mov_b64 s[50:51], -1
	s_cmp_eq_u32 s52, 0
	s_mov_b64 s[54:55], -1
	s_mov_b64 s[52:53], -1
	s_sleep 1
	s_cbranch_scc1 .LBB0_1195
	s_and_saveexec_b64 s[62:63], s[54:55]
	s_cbranch_execz .LBB0_1190
	s_branch .LBB0_1198
.LBB0_1195:
	v_mov_b64_e32 v[16:17], s[0:1]
	global_load_dword v16, v[16:17], off sc1
	s_mov_b64 s[54:55], 0
	s_waitcnt vmcnt(0) lgkmcnt(0)
	v_cmp_eq_u32_e32 vcc, 0, v16
	s_and_saveexec_b64 s[68:69], vcc
	s_cmp_lt_u32 s71, 0x40001
	s_cselect_b64 s[54:55], -1, 0
	s_xor_b64 s[52:53], exec, -1
	s_and_b64 s[54:55], s[54:55], exec
	s_or_b64 exec, exec, s[68:69]
	s_and_saveexec_b64 s[62:63], s[54:55]
	s_cbranch_execz .LBB0_1190

; __device__ __forceinline__ unsigned xb_ld(unsigned* p)              { return __hip_atomic_load(p, __ATOMIC_RELAXED, __HIP_MEMORY_SCOPE_AGENT); }
; __device__ __forceinline__ void xcd_barrier_complete(unsigned* bar, unsigned x, unsigned& nloc, unsigned& nx) {
;     ...
;         if ((++sp & 255u) == 0u) { if (xb_ld(&bar[XB_TMO])) break; if (sp > XB_SPIN_CAP) { atomicAdd(&bar[XB_TMO], 1u); break; } }
.LBB0_1199:
	s_or_b64 exec, exec, s[42:43]
	s_xor_b64 s[2:3], s[44:45], -1
	s_and_saveexec_b64 s[6:7], s[2:3]
	s_xor_b64 s[2:3], exec, s[6:7]
	s_cbranch_execz .LBB0_1201
	v_mov_b64_e32 v[16:17], s[0:1]
	global_atomic_add v[16:17], v208, off

;   DI const float* x() const { return (const float*)sp[0]; }
; __device__ __forceinline__ unsigned xb_ld(unsigned* p)              { return __hip_atomic_load(p, __ATOMIC_RELAXED, __HIP_MEMORY_SCOPE_AGENT); }
; __device__ __forceinline__ unsigned xb_add(unsigned* p, unsigned v) { return __hip_atomic_fetch_add(p, v, __ATOMIC_RELAXED, __HIP_MEMORY_SCOPE_AGENT); }
; #define XB_SPIN(cond, bar) do { unsigned _sp = 0; while (cond) { __builtin_amdgcn_s_sleep(1); \
;     if ((++_sp & 255u) == 0u) { if (xb_ld(&(bar)[XB_TMO])) break; if (_sp > XB_SPIN_CAP) { atomicAdd(&(bar)[XB_TMO], 1u); break; } } } } while (0)
; __device__ __forceinline__ void xcd_barrier(const XcdBarrier& b) {
;     asm volatile("s_waitcnt vmcnt(0)" ::: "memory");
;     __syncthreads();
;     if (threadIdx.x == 0) {
;         unsigned* bar = b.bar;
;         __builtin_amdgcn_s_waitcnt(0);
;         unsigned nloc = b.st[0], nx = b.st[1];
;         if (nloc == 0u) { xcd_barrier_complete(bar, b.x, nloc, nx); b.st[0] = nloc; b.st[1] = nx; }
;         const unsigned old = xb_add(&bar[XB_XSUB(b.x)], 1u);
;         const unsigned gen = old / nloc;
;         if (old + 1u == (gen + 1u) * nloc) {
;             __builtin_amdgcn_fence(__ATOMIC_RELEASE, "agent");
;             asm volatile("s_waitcnt vmcnt(0)" ::: "memory");
;             const unsigned og = xb_add(&bar[XB_TOP], 1u);
;             const unsigned tg = og / nx;
;             if (og + 1u == (tg + 1u) * nx) xb_add(&bar[XB_TOPGEN], 1u);
;             else XB_SPIN(xb_ld(&bar[XB_TOPGEN]) == tg, bar);
;             __builtin_amdgcn_fence(__ATOMIC_ACQUIRE, "agent");
;             xb_add(&bar[XB_XGEN(b.x)], 1u);
;             asm volatile("s_waitcnt vmcnt(0)" ::: "memory");
;         } else {
;             XB_SPIN(xb_ld(&bar[XB_XGEN(b.x)]) == gen, bar);
;             __builtin_amdgcn_fence(__ATOMIC_ACQUIRE, "agent");
;             asm volatile("s_waitcnt vmcnt(0)" ::: "memory");
;         }
.LBB0_1202:
	s_add_u32 s24, s36, 0xe36d000
	s_addc_u32 s25, s37, 0
	s_lshl_b32 s26, s70, 6
	s_add_i32 s76, s26, 0x500
	s_lshl_b64 s[0:1], s[76:77], 2
	s_add_u32 s0, s24, s0
	s_addc_u32 s1, s25, s1
	v_mov_b64_e32 v[4:5], s[0:1]
	global_atomic_add v3, v[4:5], v208, off sc0
	v_cvt_f32_u32_e32 v1, v2
	v_sub_u32_e32 v4, 0, v2
	v_rcp_iflag_f32_e32 v1, v1
	s_nop 0
	v_mul_f32_e32 v1, 0x4f7ffffe, v1
	v_cvt_u32_f32_e32 v1, v1
	v_mul_lo_u32 v4, v4, v1
	v_mul_hi_u32 v4, v1, v4
	v_add_u32_e32 v1, v1, v4
	s_waitcnt vmcnt(0) lgkmcnt(0)
	v_mul_hi_u32 v1, v3, v1
	v_mul_lo_u32 v4, v1, v2
	v_sub_u32_e32 v4, v3, v4
	v_cmp_ge_u32_e32 vcc, v4, v2
	v_add_u32_e32 v5, 1, v1
	s_nop 0
	v_cndmask_b32_e32 v1, v1, v5, vcc
	v_sub_u32_e32 v5, v4, v2
	v_cndmask_b32_e32 v4, v4, v5, vcc
	v_cmp_ge_u32_e32 vcc, v4, v2
	v_add_u32_e32 v4, 1, v1
	s_nop 0
	v_cndmask_b32_e32 v1, v1, v4, vcc
	v_add_u32_e32 v4, 1, v3
	v_mad_u64_u32 v[2:3], s[0:1], v2, v1, v[2:3]
	v_cmp_ne_u32_e32 vcc, v4, v2
	s_and_saveexec_b64 s[0:1], vcc
	s_xor_b64 s[0:1], exec, s[0:1]
	s_cbranch_execz .LBB0_1215
	s_add_i32 s76, s26, 0x900
	s_lshl_b64 s[2:3], s[76:77], 2
	s_add_u32 s6, s24, s2
	s_addc_u32 s7, s25, s3
	v_mov_b64_e32 v[2:3], s[6:7]
	global_load_dword v0, v[2:3], off sc1
	s_waitcnt vmcnt(0) lgkmcnt(0)
	v_cmp_eq_u32_e32 vcc, v0, v1
	s_and_saveexec_b64 s[2:3], vcc
	s_cbranch_execz .LBB0_1214
	s_add_u32 s8, s36, 0xe36d200
	s_addc_u32 s9, s37, 0
	s_mov_b32 s27, 1
	s_mov_b64 s[10:11], 0
	s_branch .LBB0_1206

; __device__ __forceinline__ unsigned xb_ld(unsigned* p)              { return __hip_atomic_load(p, __ATOMIC_RELAXED, __HIP_MEMORY_SCOPE_AGENT); }
; __device__ __forceinline__ unsigned xb_add(unsigned* p, unsigned v) { return __hip_atomic_fetch_add(p, v, __ATOMIC_RELAXED, __HIP_MEMORY_SCOPE_AGENT); }
; #define XB_SPIN(cond, bar) do { unsigned _sp = 0; while (cond) { __builtin_amdgcn_s_sleep(1); \
;     if ((++_sp & 255u) == 0u) { if (xb_ld(&(bar)[XB_TMO])) break; if (_sp > XB_SPIN_CAP) { atomicAdd(&(bar)[XB_TMO], 1u); break; } } } } while (0)
; __device__ __forceinline__ void xcd_barrier(const XcdBarrier& b) {
;     ...
;         if (old + 1u == (gen + 1u) * nloc) {
;             __builtin_amdgcn_fence(__ATOMIC_RELEASE, "agent");
;             asm volatile("s_waitcnt vmcnt(0)" ::: "memory");
;             const unsigned og = xb_add(&bar[XB_TOP], 1u);
;             const unsigned tg = og / nx;
;             if (og + 1u == (tg + 1u) * nx) xb_add(&bar[XB_TOPGEN], 1u);
;             else XB_SPIN(xb_ld(&bar[XB_TOPGEN]) == tg, bar);
.LBB0_1215:
	s_andn2_saveexec_b64 s[0:1], s[0:1]
	s_cbranch_execz .LBB0_410
	v_mov_b32_e32 v1, s36
	v_add_co_u32_e32 v2, vcc, 0xe370000, v1
	v_mov_b32_e32 v1, s37
	buffer_wbl2 sc1
	s_waitcnt vmcnt(0)
	v_addc_co_u32_e32 v3, vcc, 0, v1, vcc
	global_atomic_add v1, v[2:3], v208, off offset:1024 sc0
	v_cvt_f32_u32_e32 v2, v0
	v_sub_u32_e32 v3, 0, v0
	s_mov_b64 s[6:7], -1
	v_rcp_iflag_f32_e32 v2, v2
	s_nop 0
	v_mul_f32_e32 v2, 0x4f7ffffe, v2
	v_cvt_u32_f32_e32 v2, v2
	v_mul_lo_u32 v3, v3, v2
	v_mul_hi_u32 v3, v2, v3
	v_add_u32_e32 v2, v2, v3
	s_waitcnt vmcnt(0) lgkmcnt(0)
	v_mul_hi_u32 v2, v1, v2
	v_mul_lo_u32 v3, v2, v0
	v_sub_u32_e32 v3, v1, v3
	v_cmp_ge_u32_e32 vcc, v3, v0
	v_add_u32_e32 v4, 1, v2
	s_nop 0
	v_cndmask_b32_e32 v2, v2, v4, vcc
	v_sub_u32_e32 v4, v3, v0
	v_cndmask_b32_e32 v3, v3, v4, vcc
	v_cmp_ge_u32_e32 vcc, v3, v0
	v_add_u32_e32 v3, 1, v2
	s_nop 0
	v_cndmask_b32_e32 v2, v2, v3, vcc
	v_add_u32_e32 v3, 1, v1
	v_mad_u64_u32 v[0:1], s[0:1], v0, v2, v[0:1]
	s_add_u32 s0, s36, 0xe370500
	s_addc_u32 s1, s37, 0
	v_cmp_ne_u32_e32 vcc, v3, v0
	v_mov_b64_e32 v[0:1], s[0:1]
	s_and_saveexec_b64 s[2:3], vcc
	s_cbranch_execz .LBB0_1228
	v_mov_b64_e32 v[0:1], s[0:1]
	global_load_dword v0, v[0:1], off sc1
	s_mov_b64 s[10:11], 0
	s_waitcnt vmcnt(0) lgkmcnt(0)
	v_cmp_eq_u32_e32 vcc, v0, v2
	s_and_saveexec_b64 s[8:9], vcc
	s_cbranch_execz .LBB0_1227
	s_add_u32 s6, s36, 0xe36d200
	s_addc_u32 s7, s37, 0
	s_mov_b32 s22, 1
	s_branch .LBB0_1220

;   DI const float* x() const { return (const float*)sp[0]; }
; __device__ __forceinline__ unsigned xb_ld(unsigned* p)              { return __hip_atomic_load(p, __ATOMIC_RELAXED, __HIP_MEMORY_SCOPE_AGENT); }
; __device__ __forceinline__ unsigned xb_add(unsigned* p, unsigned v) { return __hip_atomic_fetch_add(p, v, __ATOMIC_RELAXED, __HIP_MEMORY_SCOPE_AGENT); }
; #define XB_SPIN(cond, bar) do { unsigned _sp = 0; while (cond) { __builtin_amdgcn_s_sleep(1); \
;     if ((++_sp & 255u) == 0u) { if (xb_ld(&(bar)[XB_TMO])) break; if (_sp > XB_SPIN_CAP) { atomicAdd(&(bar)[XB_TMO], 1u); break; } } } } while (0)
; __device__ __forceinline__ void xcd_barrier(const XcdBarrier& b) {
;     ...
;             const unsigned og = xb_add(&bar[XB_TOP], 1u);
;             const unsigned tg = og / nx;
;             if (og + 1u == (tg + 1u) * nx) xb_add(&bar[XB_TOPGEN], 1u);
;             else XB_SPIN(xb_ld(&bar[XB_TOPGEN]) == tg, bar);
;             __builtin_amdgcn_fence(__ATOMIC_ACQUIRE, "agent");
;             xb_add(&bar[XB_XGEN(b.x)], 1u);
.LBB0_1228:
	s_or_b64 exec, exec, s[2:3]
	s_and_saveexec_b64 s[0:1], s[6:7]
	s_cbranch_execz .LBB0_409
	global_atomic_add v[0:1], v208, off
	s_branch .LBB0_409

;   DI const float* x() const { return (const float*)sp[0]; }
; __device__ __forceinline__ unsigned xb_add(unsigned* p, unsigned v) { return __hip_atomic_fetch_add(p, v, __ATOMIC_RELAXED, __HIP_MEMORY_SCOPE_AGENT); }
; __device__ __forceinline__ void xcd_barrier(const XcdBarrier& b) {
;     ...
;             __builtin_amdgcn_fence(__ATOMIC_ACQUIRE, "agent");
;             xb_add(&bar[XB_XGEN(b.x)], 1u);
;             asm volatile("s_waitcnt vmcnt(0)" ::: "memory");
.LBB0_1231:
	s_or_b64 exec, exec, s[0:1]
	s_add_i32 s42, s24, 0x900
	s_lshl_b64 s[0:1], s[42:43], 2
	s_add_u32 s0, s22, s0
	s_addc_u32 s1, s23, s1
	v_mov_b64_e32 v[0:1], s[0:1]
	v_mov_b32_e32 v2, 1
	s_waitcnt vmcnt(0) lgkmcnt(0)
	buffer_inv sc1
	global_atomic_add v[0:1], v2, off
	s_waitcnt vmcnt(0)

; DI int TID() { int t = threadIdx.x; asm volatile("" : "+v"(t)); return t; }
; DI void gemm_preload(const bfu* __restrict__ A, const bfu* __restrict__ Bt, int K, int kt, bf16x8 (&ra)[4], bf16x8 (&rb)[8]) {
;   const int tid = TID(), sr = tid >> 3, sc = (tid & 7) * 8;
;   const bfu* Ag = A + (long)sr * K + sc + kt * BK; const bfu* Bg = Bt + (long)sr * K + sc + kt * BK;
; #pragma unroll
;   for (int i = 0; i < 4; ++i) ra[i] = ld8(Ag + (long)(32 * i) * K);
; #pragma unroll
;   for (int i = 0; i < 8; ++i) rb[i] = ld8(Bg + (long)(32 * i) * K);
; }
.LBB0_1239:
	v_cndmask_b32_e64 v0, 0, 1, s[12:13]
	v_cmp_ne_u32_e64 s[2:3], 1, v0
	s_andn2_b64 vcc, exec, s[12:13]
	s_cbranch_vccnz .LBB0_1241
	v_mov_b32_e32 v4, v202
	s_nop 0
	v_ashrrev_i32_e32 v0, 3, v4
	v_ashrrev_i32_e32 v1, 31, v0
	v_lshlrev_b64 v[0:1], 12, v[0:1]
	v_lshlrev_b32_e32 v4, 4, v4
	v_lshl_add_u64 v[2:3], s[8:9], 0, v[0:1]
	v_and_b32_e32 v184, 0x70, v4
	v_lshl_add_u64 v[2:3], v[2:3], 0, v[184:185]
	v_add_co_u32_e32 v4, vcc, 0x20000, v2
	v_lshl_add_u64 v[0:1], s[10:11], 0, v[0:1]
	s_nop 0
	v_addc_co_u32_e32 v5, vcc, 0, v3, vcc
	v_add_co_u32_e32 v6, vcc, 0x40000, v2
	global_load_dwordx4 v[128:131], v[2:3], off
	s_nop 0
	v_addc_co_u32_e32 v7, vcc, 0, v3, vcc
	v_add_co_u32_e32 v2, vcc, 0x60000, v2
	v_lshl_add_u64 v[0:1], v[0:1], 0, v[184:185]
	s_nop 0
	v_addc_co_u32_e32 v3, vcc, 0, v3, vcc
	s_waitcnt vmcnt(0)
	global_load_dwordx4 v[132:135], v[4:5], off
	global_load_dwordx4 v[136:139], v[6:7], off
	global_load_dwordx4 v[140:143], v[2:3], off
	global_load_dwordx4 v[144:147], v[0:1], off
	v_add_co_u32_e32 v2, vcc, s64, v0
	s_nop 1
	v_addc_co_u32_e32 v3, vcc, 0, v1, vcc
	v_add_co_u32_e32 v4, vcc, 0x40000, v0
	s_nop 1
	v_addc_co_u32_e32 v5, vcc, 0, v1, vcc
	global_load_dwordx4 v[148:151], v[2:3], off
	global_load_dwordx4 v[152:155], v[4:5], off
	v_add_co_u32_e32 v2, vcc, 0x60000, v0
	s_nop 1
	v_addc_co_u32_e32 v3, vcc, 0, v1, vcc
	v_add_co_u32_e32 v4, vcc, 0x80000, v0
	s_nop 1
	v_addc_co_u32_e32 v5, vcc, 0, v1, vcc
	global_load_dwordx4 v[156:159], v[2:3], off
	global_load_dwordx4 v[160:163], v[4:5], off
	v_add_co_u32_e32 v2, vcc, 0xa0000, v0
	s_nop 1
	v_addc_co_u32_e32 v3, vcc, 0, v1, vcc
	v_add_co_u32_e32 v4, vcc, 0xc0000, v0
	s_nop 1
	v_addc_co_u32_e32 v5, vcc, 0, v1, vcc
	v_add_co_u32_e32 v0, vcc, 0xe0000, v0
	global_load_dwordx4 v[164:167], v[2:3], off
	global_load_dwordx4 v[168:171], v[4:5], off
	v_addc_co_u32_e32 v1, vcc, 0, v1, vcc
	global_load_dwordx4 v[172:175], v[0:1], off
	s_and_b64 vcc, exec, s[2:3]
	s_cbranch_vccnz .LBB0_1402
	s_branch .LBB0_1242

; #define MFMA(a, b, c) __builtin_amdgcn_mfma_f32_32x32x16_bf16((a), (b), (c), 0, 0, 0)
; DI int TID() { int t = threadIdx.x; asm volatile("" : "+v"(t)); return t; }
; DI void gemm_preload(const bfu* __restrict__ A, const bfu* __restrict__ Bt, int K, int kt, bf16x8 (&ra)[4], bf16x8 (&rb)[8]) {
;   const int tid = TID(), sr = tid >> 3, sc = (tid & 7) * 8;
;   const bfu* Ag = A + (long)sr * K + sc + kt * BK; const bfu* Bg = Bt + (long)sr * K + sc + kt * BK;
; #pragma unroll
;   for (int i = 0; i < 4; ++i) ra[i] = ld8(Ag + (long)(32 * i) * K);
; #pragma unroll
;   for (int i = 0; i < 8; ++i) rb[i] = ld8(Bg + (long)(32 * i) * K);
; }
; DI void gemm_main2(const bfu* __restrict__ A, const bfu* __restrict__ Bt, int K, char* smem, f32x16 (&acc)[2][4], bf16x8 (&ra)[4], bf16x8 (&rb)[8]) {
;     ...
;   for (int kt = 0; kt < nk; ++kt) {
;     __syncthreads();
; #pragma unroll
;     for (int i = 0; i < 4; ++i) st8(As + (sr + 32 * i) * LDT + sc, ra[i]);
; #pragma unroll
;     for (int i = 0; i < 8; ++i) st8(Bs + (sr + 32 * i) * LDT + sc, rb[i]);
;     __syncthreads();
;     if (kt + 1 < nk) gemm_preload(A, Bt, K, kt + 1, ra, rb);
; #pragma unroll
;     for (int ks = 0; ks < 4; ++ks) {
;       const bf16x8 a0 = ld8(as + ks * 16), a1 = ld8(as + 32 * LDT + ks * 16);
; #pragma unroll
;       for (int j = 0; j < 4; ++j) {
;         const bf16x8 b = ld8(bs + j * 32 * LDT + ks * 16);
;         acc[0][j] = MFMA(a0, b, acc[0][j]); acc[1][j] = MFMA(a1, b, acc[1][j]);
;       }
;     }
;   }
.LBB0_1246:
	s_waitcnt lgkmcnt(0)
	s_barrier
	s_waitcnt vmcnt(0)
	ds_write_b128 v178, v[128:131]
	ds_write_b128 v178, v[132:135] offset:4608
	ds_write_b128 v178, v[136:139] offset:9216
	ds_write_b128 v178, v[140:143] offset:13824
	ds_write_b128 v178, v[144:147] offset:18432
	ds_write_b128 v178, v[148:151] offset:23040
	ds_write_b128 v178, v[152:155] offset:27648
	ds_write_b128 v178, v[156:159] offset:32256
	ds_write_b128 v178, v[160:163] offset:36864
	ds_write_b128 v178, v[164:167] offset:41472
	ds_write_b128 v178, v[168:171] offset:46080
	ds_write_b128 v178, v[172:175] offset:50688
	v_mov_b32_e32 v164, v202
	s_waitcnt lgkmcnt(0)
	s_barrier
	ds_read_b128 v[128:131], v176
	ds_read_b128 v[132:135], v177 offset:18432
	ds_read_b128 v[136:139], v176 offset:32
	ds_read_b128 v[140:143], v177 offset:18464
	ds_read_b128 v[144:147], v176 offset:4608
	ds_read_b128 v[148:151], v176 offset:4640
	s_waitcnt lgkmcnt(4)
	v_mfma_f32_32x32x16_bf16 v[112:127], v[128:131], v[132:135], v[112:127]
	s_waitcnt lgkmcnt(1)
	v_mfma_f32_32x32x16_bf16 v[48:63], v[144:147], v[132:135], v[48:63]
	ds_read_b128 v[132:135], v177 offset:23040
	ds_read_b128 v[152:155], v177 offset:23072
	s_waitcnt lgkmcnt(1)
	v_mfma_f32_32x32x16_bf16 v[96:111], v[128:131], v[132:135], v[96:111]
	v_mfma_f32_32x32x16_bf16 v[32:47], v[144:147], v[132:135], v[32:47]
	ds_read_b128 v[132:135], v177 offset:27648
	ds_read_b128 v[156:159], v177 offset:27680
	s_waitcnt lgkmcnt(1)
	v_mfma_f32_32x32x16_bf16 v[80:95], v[128:131], v[132:135], v[80:95]
	v_mfma_f32_32x32x16_bf16 v[16:31], v[144:147], v[132:135], v[16:31]
	ds_read_b128 v[132:135], v177 offset:32256
	ds_read_b128 v[160:163], v177 offset:32288
	s_waitcnt lgkmcnt(1)
	v_mfma_f32_32x32x16_bf16 v[64:79], v[128:131], v[132:135], v[64:79]
	v_mfma_f32_32x32x16_bf16 v[112:127], v[136:139], v[140:143], v[112:127]
	v_mfma_f32_32x32x16_bf16 v[48:63], v[148:151], v[140:143], v[48:63]
	v_mfma_f32_32x32x16_bf16 v[0:15], v[144:147], v[132:135], v[0:15]
	v_mfma_f32_32x32x16_bf16 v[96:111], v[136:139], v[152:155], v[96:111]
	v_mfma_f32_32x32x16_bf16 v[32:47], v[148:151], v[152:155], v[32:47]
	v_mfma_f32_32x32x16_bf16 v[80:95], v[136:139], v[156:159], v[80:95]
	s_waitcnt lgkmcnt(0)
	v_mfma_f32_32x32x16_bf16 v[64:79], v[136:139], v[160:163], v[64:79]
	ds_read_b128 v[128:131], v176 offset:64
	ds_read_b128 v[132:135], v177 offset:18496
	ds_read_b128 v[168:171], v176 offset:96
	ds_read_b128 v[136:139], v177 offset:18528
	ds_read_b128 v[140:143], v176 offset:4672
	ds_read_b128 v[180:183], v176 offset:4704
	v_mfma_f32_32x32x16_bf16 v[16:31], v[148:151], v[156:159], v[16:31]
	s_waitcnt lgkmcnt(4)
	v_mfma_f32_32x32x16_bf16 v[112:127], v[128:131], v[132:135], v[112:127]
	s_waitcnt lgkmcnt(1)
	v_mfma_f32_32x32x16_bf16 v[48:63], v[140:143], v[132:135], v[48:63]
	ds_read_b128 v[132:135], v177 offset:23104
	ds_read_b128 v[152:155], v177 offset:23136
	s_waitcnt lgkmcnt(1)
	v_mfma_f32_32x32x16_bf16 v[96:111], v[128:131], v[132:135], v[96:111]
	v_mfma_f32_32x32x16_bf16 v[32:47], v[140:143], v[132:135], v[32:47]
	ds_read_b128 v[132:135], v177 offset:27712
	ds_read_b128 v[172:175], v177 offset:27744
	s_waitcnt lgkmcnt(1)
	v_mfma_f32_32x32x16_bf16 v[80:95], v[128:131], v[132:135], v[80:95]
	v_mfma_f32_32x32x16_bf16 v[16:31], v[140:143], v[132:135], v[16:31]
	ds_read_b128 v[132:135], v177 offset:32320
	ds_read_b128 v[188:191], v177 offset:32352
	v_mfma_f32_32x32x16_bf16 v[0:15], v[148:151], v[160:163], v[0:15]
	s_waitcnt lgkmcnt(1)
	v_mfma_f32_32x32x16_bf16 v[64:79], v[128:131], v[132:135], v[64:79]
	v_ashrrev_i32_e32 v128, 3, v164
	v_ashrrev_i32_e32 v129, 31, v128
	v_lshlrev_b64 v[128:129], 12, v[128:129]
	v_and_b32_e32 v130, 7, v164
	v_lshl_or_b32 v128, v130, 4, v128
	v_lshl_add_u64 v[144:145], s[0:1], 0, v[128:129]
	v_lshl_add_u64 v[192:193], s[10:11], 0, v[144:145]
	v_mfma_f32_32x32x16_bf16 v[0:15], v[140:143], v[132:135], v[0:15]
	v_lshl_add_u64 v[140:141], s[8:9], 0, v[144:145]
	v_add_co_u32_e32 v132, vcc, s64, v140
	s_add_u32 s0, s0, 0x80
	s_nop 0
	v_addc_co_u32_e32 v133, vcc, 0, v141, vcc
	global_load_dwordx4 v[128:131], v[140:141], off offset:128
	s_nop 0
	global_load_dwordx4 v[132:135], v[132:133], off offset:128
	v_mfma_f32_32x32x16_bf16 v[112:127], v[168:171], v[136:139], v[112:127]
	s_addc_u32 s1, s1, 0
	s_cmpk_lg_i32 s0, 0xf80
	v_mfma_f32_32x32x16_bf16 v[48:63], v[180:183], v[136:139], v[48:63]
	v_add_co_u32_e32 v136, vcc, s65, v140
	s_nop 1
	v_addc_co_u32_e32 v137, vcc, 0, v141, vcc
	v_add_co_u32_e32 v140, vcc, s66, v140
	v_mfma_f32_32x32x16_bf16 v[96:111], v[168:171], v[152:155], v[96:111]
	s_nop 0
	v_addc_co_u32_e32 v141, vcc, 0, v141, vcc
	v_add_co_u32_e32 v148, vcc, s64, v192
	global_load_dwordx4 v[136:139], v[136:137], off offset:128
	s_nop 0
	global_load_dwordx4 v[140:143], v[140:141], off offset:128
	v_addc_co_u32_e32 v149, vcc, 0, v193, vcc
	v_mfma_f32_32x32x16_bf16 v[32:47], v[180:183], v[152:155], v[32:47]
	v_add_co_u32_e32 v152, vcc, s65, v192
	global_load_dwordx4 v[144:147], v[192:193], off offset:128
	s_nop 0
	global_load_dwordx4 v[148:151], v[148:149], off offset:128
	v_addc_co_u32_e32 v153, vcc, 0, v193, vcc
	v_add_co_u32_e32 v156, vcc, s66, v192
	v_mfma_f32_32x32x16_bf16 v[80:95], v[168:171], v[172:175], v[80:95]
	s_nop 0
	v_addc_co_u32_e32 v157, vcc, 0, v193, vcc
	v_add_co_u32_e32 v160, vcc, s67, v192
	global_load_dwordx4 v[152:155], v[152:153], off offset:128
	s_nop 0
	global_load_dwordx4 v[156:159], v[156:157], off offset:128
	v_addc_co_u32_e32 v161, vcc, 0, v193, vcc
	v_add_co_u32_e32 v164, vcc, s72, v192
	v_mfma_f32_32x32x16_bf16 v[16:31], v[180:183], v[172:175], v[16:31]
	s_nop 0
	v_addc_co_u32_e32 v165, vcc, 0, v193, vcc
	v_add_co_u32_e32 v172, vcc, s73, v192
	global_load_dwordx4 v[160:163], v[160:161], off offset:128
	s_nop 0
	global_load_dwordx4 v[164:167], v[164:165], off offset:128
	v_addc_co_u32_e32 v173, vcc, 0, v193, vcc
	v_add_co_u32_e32 v174, vcc, s77, v192
	s_waitcnt lgkmcnt(0)
	v_mfma_f32_32x32x16_bf16 v[64:79], v[168:171], v[188:191], v[64:79]
	v_addc_co_u32_e32 v175, vcc, 0, v193, vcc
	global_load_dwordx4 v[168:171], v[172:173], off offset:128
	s_nop 0
	global_load_dwordx4 v[172:175], v[174:175], off offset:128
	v_mfma_f32_32x32x16_bf16 v[0:15], v[180:183], v[188:191], v[0:15]
	s_cbranch_scc1 .LBB0_1246
; #define MFMA(a, b, c) __builtin_amdgcn_mfma_f32_32x32x16_bf16((a), (b), (c), 0, 0, 0)
; DI int TID() { int t = threadIdx.x; asm volatile("" : "+v"(t)); return t; }
; DI void gemm_main2(const bfu* __restrict__ A, const bfu* __restrict__ Bt, int K, char* smem, f32x16 (&acc)[2][4], bf16x8 (&ra)[4], bf16x8 (&rb)[8]) {
;     ...
;   for (int kt = 0; kt < nk; ++kt) {
;     __syncthreads();
; #pragma unroll
;     for (int i = 0; i < 4; ++i) st8(As + (sr + 32 * i) * LDT + sc, ra[i]);
; #pragma unroll
;     for (int i = 0; i < 8; ++i) st8(Bs + (sr + 32 * i) * LDT + sc, rb[i]);
;     __syncthreads();
;     if (kt + 1 < nk) gemm_preload(A, Bt, K, kt + 1, ra, rb);
; #pragma unroll
;     for (int ks = 0; ks < 4; ++ks) {
;       const bf16x8 a0 = ld8(as + ks * 16), a1 = ld8(as + 32 * LDT + ks * 16);
; #pragma unroll
;       for (int j = 0; j < 4; ++j) {
;         const bf16x8 b = ld8(bs + j * 32 * LDT + ks * 16);
;         acc[0][j] = MFMA(a0, b, acc[0][j]); acc[1][j] = MFMA(a1, b, acc[1][j]);
;       }
;     }
;   }
; DI void phase_gemm(const Params& p, int g, int kind, char* smem, float* rsl, int* s_item, int vlo, int vhi, int cslot) {
;     ...
;   auto fetch = [&](TD& d) {
;     for (;;) {
;       __syncthreads();
;       if (TID() == 0) *s_item = atomicAdd(qctr, 1);
;       __syncthreads();
	s_barrier
	s_waitcnt vmcnt(0)
	ds_write_b128 v178, v[128:131]
	ds_write_b128 v178, v[132:135] offset:4608
	ds_write_b128 v178, v[136:139] offset:9216
	ds_write_b128 v178, v[140:143] offset:13824
	ds_write_b128 v178, v[144:147] offset:18432
	ds_write_b128 v178, v[148:151] offset:23040
	ds_write_b128 v178, v[152:155] offset:27648
	ds_write_b128 v178, v[156:159] offset:32256
	ds_write_b128 v178, v[160:163] offset:36864
	ds_write_b128 v178, v[164:167] offset:41472
	ds_write_b128 v178, v[168:171] offset:46080
	ds_write_b128 v178, v[172:175] offset:50688
	s_waitcnt lgkmcnt(0)
	s_barrier
	ds_read_b128 v[178:181], v176
	ds_read_b128 v[188:191], v177 offset:18432
	ds_read_b128 v[192:195], v176 offset:4608
	s_waitcnt lgkmcnt(1)
	v_mfma_f32_32x32x16_bf16 v[112:127], v[178:181], v[188:191], v[112:127]
	s_waitcnt lgkmcnt(0)
	v_mfma_f32_32x32x16_bf16 v[48:63], v[192:195], v[188:191], v[48:63]
	ds_read_b128 v[188:191], v177 offset:23040
	s_waitcnt lgkmcnt(0)
	v_mfma_f32_32x32x16_bf16 v[96:111], v[178:181], v[188:191], v[96:111]
	v_mfma_f32_32x32x16_bf16 v[32:47], v[192:195], v[188:191], v[32:47]
	ds_read_b128 v[188:191], v177 offset:27648
	s_waitcnt lgkmcnt(0)
	v_mfma_f32_32x32x16_bf16 v[80:95], v[178:181], v[188:191], v[80:95]
	v_mfma_f32_32x32x16_bf16 v[16:31], v[192:195], v[188:191], v[16:31]
	ds_read_b128 v[188:191], v177 offset:32256
	s_waitcnt lgkmcnt(0)
	v_mfma_f32_32x32x16_bf16 v[64:79], v[178:181], v[188:191], v[64:79]
	v_mfma_f32_32x32x16_bf16 v[0:15], v[192:195], v[188:191], v[0:15]
	ds_read_b128 v[178:181], v176 offset:32
	ds_read_b128 v[188:191], v177 offset:18464
	ds_read_b128 v[192:195], v176 offset:4640
	s_waitcnt lgkmcnt(1)
	v_mfma_f32_32x32x16_bf16 v[112:127], v[178:181], v[188:191], v[112:127]
	s_waitcnt lgkmcnt(0)
	v_mfma_f32_32x32x16_bf16 v[48:63], v[192:195], v[188:191], v[48:63]
	ds_read_b128 v[188:191], v177 offset:23072
	s_waitcnt lgkmcnt(0)
	v_mfma_f32_32x32x16_bf16 v[96:111], v[178:181], v[188:191], v[96:111]
	v_mfma_f32_32x32x16_bf16 v[32:47], v[192:195], v[188:191], v[32:47]
	ds_read_b128 v[188:191], v177 offset:27680
	s_waitcnt lgkmcnt(0)
	v_mfma_f32_32x32x16_bf16 v[80:95], v[178:181], v[188:191], v[80:95]
	v_mfma_f32_32x32x16_bf16 v[16:31], v[192:195], v[188:191], v[16:31]
	ds_read_b128 v[188:191], v177 offset:32288
	s_waitcnt lgkmcnt(0)
	v_mfma_f32_32x32x16_bf16 v[64:79], v[178:181], v[188:191], v[64:79]
	v_mfma_f32_32x32x16_bf16 v[0:15], v[192:195], v[188:191], v[0:15]
	ds_read_b128 v[178:181], v176 offset:64
	ds_read_b128 v[188:191], v177 offset:18496
	ds_read_b128 v[192:195], v176 offset:4672
	s_waitcnt lgkmcnt(1)
	v_mfma_f32_32x32x16_bf16 v[112:127], v[178:181], v[188:191], v[112:127]
	s_waitcnt lgkmcnt(0)
	v_mfma_f32_32x32x16_bf16 v[48:63], v[192:195], v[188:191], v[48:63]
	ds_read_b128 v[188:191], v177 offset:23104
	s_waitcnt lgkmcnt(0)
	v_mfma_f32_32x32x16_bf16 v[96:111], v[178:181], v[188:191], v[96:111]
	v_mfma_f32_32x32x16_bf16 v[32:47], v[192:195], v[188:191], v[32:47]
	ds_read_b128 v[188:191], v177 offset:27712
	s_waitcnt lgkmcnt(0)
	v_mfma_f32_32x32x16_bf16 v[80:95], v[178:181], v[188:191], v[80:95]
	v_mfma_f32_32x32x16_bf16 v[16:31], v[192:195], v[188:191], v[16:31]
	ds_read_b128 v[188:191], v177 offset:32320
	s_waitcnt lgkmcnt(0)
	v_mfma_f32_32x32x16_bf16 v[64:79], v[178:181], v[188:191], v[64:79]
	v_mfma_f32_32x32x16_bf16 v[0:15], v[192:195], v[188:191], v[0:15]
	ds_read_b128 v[178:181], v176 offset:96
	ds_read_b128 v[188:191], v177 offset:18528
	ds_read_b128 v[192:195], v176 offset:4704
	v_mov_b32_e32 v176, v202
	s_waitcnt lgkmcnt(1)
	v_mfma_f32_32x32x16_bf16 v[112:127], v[178:181], v[188:191], v[112:127]
	s_waitcnt lgkmcnt(0)
	v_mfma_f32_32x32x16_bf16 v[48:63], v[192:195], v[188:191], v[48:63]
	ds_read_b128 v[188:191], v177 offset:23136
	s_waitcnt lgkmcnt(0)
	v_mfma_f32_32x32x16_bf16 v[96:111], v[178:181], v[188:191], v[96:111]
	v_mfma_f32_32x32x16_bf16 v[32:47], v[192:195], v[188:191], v[32:47]
	ds_read_b128 v[188:191], v177 offset:27744
	s_waitcnt lgkmcnt(0)
	v_mfma_f32_32x32x16_bf16 v[80:95], v[178:181], v[188:191], v[80:95]
	v_mfma_f32_32x32x16_bf16 v[16:31], v[192:195], v[188:191], v[16:31]
	ds_read_b128 v[188:191], v177 offset:32352
	s_waitcnt lgkmcnt(0)
	s_barrier
	s_nop 0
	v_cmp_eq_u32_e32 vcc, 0, v176
	v_mfma_f32_32x32x16_bf16 v[64:79], v[178:181], v[188:191], v[64:79]
	v_mfma_f32_32x32x16_bf16 v[0:15], v[192:195], v[188:191], v[0:15]
	s_and_saveexec_b64 s[0:1], vcc
	s_cbranch_execz .LBB0_1251
	s_mov_b64 s[16:17], exec
	v_mbcnt_lo_u32_b32 v176, s16, 0
	v_mbcnt_hi_u32_b32 v176, s17, v176
	v_cmp_eq_u32_e32 vcc, 0, v176
	s_and_saveexec_b64 s[2:3], vcc
	s_cbranch_execz .LBB0_1250
	s_bcnt1_i32_b64 s5, s[16:17]
	v_mov_b32_e32 v177, s5
	global_atomic_add v177, v185, v177, s[88:89] offset:96 sc0

; DI int TID() { int t = threadIdx.x; asm volatile("" : "+v"(t)); return t; }
; DI void gemm_preload(const bfu* __restrict__ A, const bfu* __restrict__ Bt, int K, int kt, bf16x8 (&ra)[4], bf16x8 (&rb)[8]) {
;   const int tid = TID(), sr = tid >> 3, sc = (tid & 7) * 8;
;   const bfu* Ag = A + (long)sr * K + sc + kt * BK; const bfu* Bg = Bt + (long)sr * K + sc + kt * BK;
; #pragma unroll
;   for (int i = 0; i < 4; ++i) ra[i] = ld8(Ag + (long)(32 * i) * K);
; #pragma unroll
;   for (int i = 0; i < 8; ++i) rb[i] = ld8(Bg + (long)(32 * i) * K);
; }
; DI void phase_gemm(const Params& p, int g, int kind, char* smem, float* rsl, int* s_item, int vlo, int vhi, int cslot) {
;     ...
;     TD nxt; fetch(nxt);
;     if (nxt.ok) gemm_preload(nxt.A, nxt.Bt, nxt.K, 0, ra, rb);
.LBB0_1253:
	s_andn2_b64 vcc, exec, s[0:1]
	s_cbranch_vccnz .LBB0_1255
	v_mov_b32_e32 v132, v202
	s_nop 0
	v_ashrrev_i32_e32 v128, 3, v132
	v_ashrrev_i32_e32 v129, 31, v128
	v_lshlrev_b64 v[128:129], 12, v[128:129]
	v_lshlrev_b32_e32 v132, 4, v132
	v_lshl_add_u64 v[130:131], s[8:9], 0, v[128:129]
	v_and_b32_e32 v184, 0x70, v132
	v_lshl_add_u64 v[140:141], v[130:131], 0, v[184:185]
	v_add_co_u32_e32 v132, vcc, 0x20000, v140
	v_lshl_add_u64 v[128:129], s[10:11], 0, v[128:129]
	s_nop 0
	v_addc_co_u32_e32 v133, vcc, 0, v141, vcc
	v_add_co_u32_e32 v136, vcc, 0x40000, v140
	v_lshl_add_u64 v[172:173], v[128:129], 0, v[184:185]
	s_nop 0
	v_addc_co_u32_e32 v137, vcc, 0, v141, vcc
	global_load_dwordx4 v[128:131], v[140:141], off
	v_add_co_u32_e32 v140, vcc, 0x60000, v140
	global_load_dwordx4 v[132:135], v[132:133], off
	s_nop 0
	global_load_dwordx4 v[136:139], v[136:137], off
	v_addc_co_u32_e32 v141, vcc, 0, v141, vcc
	v_add_co_u32_e32 v148, vcc, s64, v172
	global_load_dwordx4 v[140:143], v[140:141], off
	s_nop 0
	global_load_dwordx4 v[144:147], v[172:173], off
	v_addc_co_u32_e32 v149, vcc, 0, v173, vcc
	v_add_co_u32_e32 v152, vcc, 0x40000, v172
	s_nop 1
	v_addc_co_u32_e32 v153, vcc, 0, v173, vcc
	v_add_co_u32_e32 v156, vcc, 0x60000, v172
	global_load_dwordx4 v[148:151], v[148:149], off
	s_nop 0
	global_load_dwordx4 v[152:155], v[152:153], off
	v_addc_co_u32_e32 v157, vcc, 0, v173, vcc
	v_add_co_u32_e32 v160, vcc, 0x80000, v172
	s_nop 1
	v_addc_co_u32_e32 v161, vcc, 0, v173, vcc
	v_add_co_u32_e32 v164, vcc, 0xa0000, v172
	global_load_dwordx4 v[156:159], v[156:157], off
	s_nop 0
	global_load_dwordx4 v[160:163], v[160:161], off
	v_addc_co_u32_e32 v165, vcc, 0, v173, vcc
	v_add_co_u32_e32 v168, vcc, 0xc0000, v172
	s_nop 1
	v_addc_co_u32_e32 v169, vcc, 0, v173, vcc
	v_add_co_u32_e32 v172, vcc, 0xe0000, v172
	global_load_dwordx4 v[164:167], v[164:165], off
	s_nop 0
	global_load_dwordx4 v[168:171], v[168:169], off
	v_addc_co_u32_e32 v173, vcc, 0, v173, vcc
	global_load_dwordx4 v[172:175], v[172:173], off

; DI int TID() { int t = threadIdx.x; asm volatile("" : "+v"(t)); return t; }
; DI unsigned cvtpk(float lo, float hi) { f32x2_t v = {lo, hi}; bf16x2_t b = __builtin_convertvector(v, bf16x2_t); return __builtin_bit_cast(unsigned, b); }
; DI void store_T_regs(const f32x16 (&acc)[2][4], int h, bfu* dst, const float* rs) {
;   const int tid = TID(), lane = tid & 63, w = tid >> 6, wm = w >> 1, wn = w & 1, l32 = lane & 31, hi = lane >> 5;
;   if (wn != h) return;
; #pragma unroll
;   for (int mi = 0; mi < 2; ++mi)
; #pragma unroll
;     for (int ni = 0; ni < 4; ++ni)
; #pragma unroll
;       for (int rg = 0; rg < 4; ++rg) {
;         const int row = wm * 64 + mi * 32 + 8 * rg + 4 * hi;
;         float s0 = 1.f, s1 = 1.f, s2 = 1.f, s3 = 1.f;
;         if (rs) { s0 = rs[row]; s1 = rs[row + 1]; s2 = rs[row + 2]; s3 = rs[row + 3]; }
;         const u32x2 v = {cvtpk(acc[mi][ni][4 * rg] * s0, acc[mi][ni][4 * rg + 1] * s1), cvtpk(acc[mi][ni][4 * rg + 2] * s2, acc[mi][ni][4 * rg + 3] * s3)};
;         *reinterpret_cast<u32x2*>(dst + (long)(ni * 32 + l32) * T + row) = v;
;       }
; }
.LBB0_1257:
	s_cmpk_gt_i32 s20, 0xff
	s_cselect_b64 s[22:23], -1, 0
	s_cmp_eq_u64 s[2:3], 0
	s_cbranch_scc1 .LBB0_1261
	v_mov_b32_e32 v176, v202
	s_nop 0
	v_and_b32_e32 v177, 64, v176
	v_cmp_eq_u32_e32 vcc, 0, v177
	s_and_saveexec_b64 s[0:1], vcc
	s_cbranch_execz .LBB0_1260
	v_and_b32_e32 v177, 31, v176
	v_ashrrev_i32_e32 v178, 1, v176
	v_lshrrev_b32_e32 v176, 3, v176
	v_and_b32_e32 v176, 4, v176
	s_movk_i32 s13, 0xffc0
	v_and_or_b32 v176, v178, s13, v176
	v_mul_u32_u24_e32 v177, 0x900, v177
	v_lshlrev_b32_e32 v184, 1, v177
	v_ashrrev_i32_e32 v177, 31, v176
	v_lshl_add_u64 v[178:179], s[2:3], 0, v[184:185]
	v_lshlrev_b64 v[182:183], 1, v[176:177]
	v_cvt_pk_bf16_f32 v180, v112, v113
	v_cvt_pk_bf16_f32 v181, v114, v115
	v_lshl_add_u64 v[188:189], v[178:179], 0, v[182:183]
	global_store_dwordx2 v[188:189], v[180:181], off
	v_or_b32_e32 v180, 8, v176
	v_cvt_pk_bf16_f32 v190, v116, v117
	v_cvt_pk_bf16_f32 v191, v118, v119
	v_cvt_pk_bf16_f32 v194, v124, v125
	v_cvt_pk_bf16_f32 v195, v126, v127
	s_mov_b64 s[2:3], 0x24000
	v_ashrrev_i32_e32 v181, 31, v180
	global_store_dwordx2 v[188:189], v[190:191], off offset:16
	v_or_b32_e32 v190, 16, v176
	v_cvt_pk_bf16_f32 v192, v120, v121
	v_cvt_pk_bf16_f32 v193, v122, v123
	global_store_dwordx2 v[188:189], v[194:195], off offset:48
	v_lshl_add_u64 v[194:195], v[178:179], 0, s[2:3]
	v_ashrrev_i32_e32 v191, 31, v190
	global_store_dwordx2 v[188:189], v[192:193], off offset:32
	v_or_b32_e32 v192, 24, v176
	v_cvt_pk_bf16_f32 v196, v96, v97
	v_cvt_pk_bf16_f32 v197, v98, v99
	v_lshl_add_u64 v[198:199], v[194:195], 0, v[182:183]
	v_lshlrev_b64 v[180:181], 1, v[180:181]
	v_ashrrev_i32_e32 v193, 31, v192
	global_store_dwordx2 v[198:199], v[196:197], off
	v_cvt_pk_bf16_f32 v196, v100, v101
	v_cvt_pk_bf16_f32 v197, v102, v103
	v_lshl_add_u64 v[198:199], v[194:195], 0, v[180:181]
	v_lshlrev_b64 v[190:191], 1, v[190:191]
	global_store_dwordx2 v[198:199], v[196:197], off
	v_cvt_pk_bf16_f32 v196, v104, v105
	v_cvt_pk_bf16_f32 v197, v106, v107
	v_lshl_add_u64 v[198:199], v[194:195], 0, v[190:191]
	v_lshlrev_b64 v[192:193], 1, v[192:193]
	global_store_dwordx2 v[198:199], v[196:197], off
	v_cvt_pk_bf16_f32 v196, v108, v109
	v_cvt_pk_bf16_f32 v197, v110, v111
	v_lshl_add_u64 v[198:199], v[194:195], 0, v[192:193]
	s_mov_b64 s[2:3], 0x48000
	global_store_dwordx2 v[198:199], v[196:197], off
	v_lshl_add_u64 v[196:197], v[178:179], 0, s[2:3]
	v_cvt_pk_bf16_f32 v198, v80, v81
	v_cvt_pk_bf16_f32 v199, v82, v83
	v_lshl_add_u64 v[200:201], v[196:197], 0, v[182:183]
	global_store_dwordx2 v[200:201], v[198:199], off
	v_cvt_pk_bf16_f32 v198, v84, v85
	v_cvt_pk_bf16_f32 v199, v86, v87
	v_lshl_add_u64 v[200:201], v[196:197], 0, v[180:181]
	global_store_dwordx2 v[200:201], v[198:199], off
	v_cvt_pk_bf16_f32 v198, v88, v89
	v_cvt_pk_bf16_f32 v199, v90, v91
	v_lshl_add_u64 v[200:201], v[196:197], 0, v[190:191]
	s_mov_b64 s[2:3], 0x6c000
	global_store_dwordx2 v[200:201], v[198:199], off
	v_cvt_pk_bf16_f32 v198, v92, v93
	v_cvt_pk_bf16_f32 v199, v94, v95
	v_lshl_add_u64 v[200:201], v[196:197], 0, v[192:193]
	v_lshl_add_u64 v[178:179], v[178:179], 0, s[2:3]
	global_store_dwordx2 v[200:201], v[198:199], off
	v_cvt_pk_bf16_f32 v198, v64, v65
	v_cvt_pk_bf16_f32 v199, v66, v67
	v_lshl_add_u64 v[182:183], v[178:179], 0, v[182:183]
	global_store_dwordx2 v[182:183], v[198:199], off
	v_cvt_pk_bf16_f32 v182, v68, v69
	v_cvt_pk_bf16_f32 v183, v70, v71
	v_lshl_add_u64 v[180:181], v[178:179], 0, v[180:181]
	global_store_dwordx2 v[180:181], v[182:183], off
	v_cvt_pk_bf16_f32 v180, v72, v73
	v_cvt_pk_bf16_f32 v181, v74, v75
	v_lshl_add_u64 v[182:183], v[178:179], 0, v[190:191]
	global_store_dwordx2 v[182:183], v[180:181], off
	v_cvt_pk_bf16_f32 v180, v76, v77
	v_cvt_pk_bf16_f32 v181, v78, v79
	v_lshl_add_u64 v[182:183], v[178:179], 0, v[192:193]
	global_store_dwordx2 v[182:183], v[180:181], off
	v_or_b32_e32 v180, 32, v176
	v_cvt_pk_bf16_f32 v182, v48, v49
	v_cvt_pk_bf16_f32 v183, v50, v51
	v_ashrrev_i32_e32 v181, 31, v180
	global_store_dwordx2 v[188:189], v[182:183], off offset:64
	v_or_b32_e32 v182, 40, v176
	v_cvt_pk_bf16_f32 v190, v52, v53
	v_cvt_pk_bf16_f32 v191, v54, v55
	v_cvt_pk_bf16_f32 v192, v56, v57
	v_cvt_pk_bf16_f32 v193, v58, v59
	v_ashrrev_i32_e32 v183, 31, v182
	global_store_dwordx2 v[188:189], v[190:191], off offset:80
	v_or_b32_e32 v190, 48, v176
	global_store_dwordx2 v[188:189], v[192:193], off offset:96
	v_cvt_pk_bf16_f32 v192, v60, v61
	v_cvt_pk_bf16_f32 v193, v62, v63
	v_lshlrev_b64 v[180:181], 1, v[180:181]
	v_ashrrev_i32_e32 v191, 31, v190
	v_or_b32_e32 v176, 56, v176
	global_store_dwordx2 v[188:189], v[192:193], off offset:112
	v_cvt_pk_bf16_f32 v188, v32, v33
	v_cvt_pk_bf16_f32 v189, v34, v35
	v_lshl_add_u64 v[192:193], v[194:195], 0, v[180:181]
	v_lshlrev_b64 v[182:183], 1, v[182:183]
	v_ashrrev_i32_e32 v177, 31, v176
	global_store_dwordx2 v[192:193], v[188:189], off
	v_cvt_pk_bf16_f32 v188, v36, v37
	v_cvt_pk_bf16_f32 v189, v38, v39
	v_lshl_add_u64 v[192:193], v[194:195], 0, v[182:183]
	v_lshlrev_b64 v[190:191], 1, v[190:191]
	global_store_dwordx2 v[192:193], v[188:189], off
	v_cvt_pk_bf16_f32 v188, v40, v41
	v_cvt_pk_bf16_f32 v189, v42, v43
	v_lshl_add_u64 v[192:193], v[194:195], 0, v[190:191]
	v_lshlrev_b64 v[176:177], 1, v[176:177]
	global_store_dwordx2 v[192:193], v[188:189], off
	v_cvt_pk_bf16_f32 v188, v44, v45
	v_cvt_pk_bf16_f32 v189, v46, v47
	v_lshl_add_u64 v[192:193], v[194:195], 0, v[176:177]
	global_store_dwordx2 v[192:193], v[188:189], off
	v_cvt_pk_bf16_f32 v188, v16, v17
	v_cvt_pk_bf16_f32 v189, v18, v19
	v_lshl_add_u64 v[192:193], v[196:197], 0, v[180:181]
	global_store_dwordx2 v[192:193], v[188:189], off
	v_cvt_pk_bf16_f32 v188, v20, v21
	v_cvt_pk_bf16_f32 v189, v22, v23
	v_lshl_add_u64 v[192:193], v[196:197], 0, v[182:183]
	global_store_dwordx2 v[192:193], v[188:189], off
	v_cvt_pk_bf16_f32 v188, v24, v25
	v_cvt_pk_bf16_f32 v189, v26, v27
	v_lshl_add_u64 v[192:193], v[196:197], 0, v[190:191]
	global_store_dwordx2 v[192:193], v[188:189], off
	v_cvt_pk_bf16_f32 v188, v28, v29
	v_cvt_pk_bf16_f32 v189, v30, v31
	v_lshl_add_u64 v[192:193], v[196:197], 0, v[176:177]
	global_store_dwordx2 v[192:193], v[188:189], off
	v_cvt_pk_bf16_f32 v188, v0, v1
	v_cvt_pk_bf16_f32 v189, v2, v3
	v_lshl_add_u64 v[180:181], v[178:179], 0, v[180:181]
	global_store_dwordx2 v[180:181], v[188:189], off
	v_cvt_pk_bf16_f32 v180, v4, v5
	v_cvt_pk_bf16_f32 v181, v6, v7
	v_lshl_add_u64 v[182:183], v[178:179], 0, v[182:183]
	global_store_dwordx2 v[182:183], v[180:181], off
	v_cvt_pk_bf16_f32 v180, v8, v9
	v_cvt_pk_bf16_f32 v181, v10, v11
	v_lshl_add_u64 v[182:183], v[178:179], 0, v[190:191]
	global_store_dwordx2 v[182:183], v[180:181], off
	v_cvt_pk_bf16_f32 v180, v12, v13
	v_cvt_pk_bf16_f32 v181, v14, v15
	v_lshl_add_u64 v[176:177], v[178:179], 0, v[176:177]
	global_store_dwordx2 v[176:177], v[180:181], off

; DI int TID() { int t = threadIdx.x; asm volatile("" : "+v"(t)); return t; }
; DI bf16x8 pack8f(const float* v) { u32x4 w = {cvtpk(v[0], v[1]), cvtpk(v[2], v[3]), cvtpk(v[4], v[5]), cvtpk(v[6], v[7])}; return __builtin_bit_cast(bf16x8, w); }
; DI void store_R(const float* Cs, int cb, int nc, bfu* dst, long ld, float scale, const float* rs = nullptr) {
;   const int cpr = nc >> 3;
;   for (int u = TID(); u < 128 * cpr; u += NT) {
;     int row = u / cpr, c8 = (u % cpr) * 8; float v[8]; ldrow8(Cs, row, cb + c8, v);
;     float s = rs ? scale * rs[row] : scale;
;     for (int j = 0; j < 8; ++j) v[j] *= s;
;     st8(dst + row * ld + c8, pack8f(v));
;   }
; }
.LBB0_1271:
	v_ashrrev_i32_e32 v179, 31, v176
	v_lshrrev_b32_e32 v179, 28, v179
	v_add_u32_e32 v179, v176, v179
	v_add_u32_e32 v180, 0x100, v176
	v_ashrrev_i32_e32 v192, 4, v179
	v_and_b32_e32 v179, -16, v179
	v_cmp_lt_i32_e32 vcc, s53, v176
	v_mov_b32_e32 v176, v180
	v_lshlrev_b32_e32 v180, 7, v192
	v_add_u32_e32 v179, v178, v179
	v_sub_u32_e32 v194, v177, v180
	ds_read_b128 v[180:183], v179
	ds_read_b128 v[188:191], v179 offset:16
	v_ashrrev_i32_e32 v193, 31, v192
	v_lshlrev_b64 v[192:193], 13, v[192:193]
	v_lshl_add_u64 v[192:193], s[2:3], 0, v[192:193]
	v_ashrrev_i32_e32 v195, 31, v194
	s_or_b64 s[34:35], vcc, s[34:35]
	v_add_u32_e32 v178, 0x2000, v178
	v_add_u32_e32 v177, 0x800, v177
	v_lshl_add_u64 v[192:193], v[194:195], 1, v[192:193]
	s_waitcnt lgkmcnt(0)
	v_cvt_pk_bf16_f32 v180, v180, v181
	v_cvt_pk_bf16_f32 v181, v182, v183
	v_cvt_pk_bf16_f32 v182, v188, v189
	v_cvt_pk_bf16_f32 v183, v190, v191
	global_store_dwordx4 v[192:193], v[180:183], off
	s_andn2_b64 exec, exec, s[34:35]
	s_cbranch_execnz .LBB0_1271

; DI int TID() { int t = threadIdx.x; asm volatile("" : "+v"(t)); return t; }
; DI bf16x8 pack8f(const float* v) { u32x4 w = {cvtpk(v[0], v[1]), cvtpk(v[2], v[3]), cvtpk(v[4], v[5]), cvtpk(v[6], v[7])}; return __builtin_bit_cast(bf16x8, w); }
; DI void store_R(const float* Cs, int cb, int nc, bfu* dst, long ld, float scale, const float* rs = nullptr) {
;   const int cpr = nc >> 3;
;   for (int u = TID(); u < 128 * cpr; u += NT) {
;     int row = u / cpr, c8 = (u % cpr) * 8; float v[8]; ldrow8(Cs, row, cb + c8, v);
;     float s = rs ? scale * rs[row] : scale;
;     for (int j = 0; j < 8; ++j) v[j] *= s;
;     st8(dst + row * ld + c8, pack8f(v));
;   }
; }
.LBB0_1283:
	v_ashrrev_i32_e32 v179, 31, v177
	v_lshrrev_b32_e32 v179, 29, v179
	v_add_u32_e32 v182, 0x100, v177
	v_add_u32_e32 v179, v177, v179
	v_cmp_lt_i32_e32 vcc, s87, v177
	v_mov_b32_e32 v177, v182
	v_ashrrev_i32_e32 v179, 3, v179
	v_mov_b64_e32 v[180:181], s[2:3]
	v_lshlrev_b32_e32 v182, 6, v179
	v_mad_u64_u32 v[188:189], s[36:37], v179, s60, v[176:177]
	v_mad_i64_i32 v[192:193], s[36:37], v179, s74, v[180:181]
	v_sub_u32_e32 v194, v178, v182
	ds_read_b128 v[180:183], v188
	ds_read_b128 v[188:191], v188 offset:16
	v_ashrrev_i32_e32 v195, 31, v194
	s_or_b64 s[34:35], vcc, s[34:35]
	v_add_u32_e32 v176, 0x2000, v176
	v_add_u32_e32 v178, 0x800, v178
	v_lshl_add_u64 v[192:193], v[194:195], 1, v[192:193]
	s_waitcnt lgkmcnt(0)
	v_cvt_pk_bf16_f32 v180, v180, v181
	v_cvt_pk_bf16_f32 v181, v182, v183
	v_cvt_pk_bf16_f32 v182, v188, v189
	v_cvt_pk_bf16_f32 v183, v190, v191
	global_store_dwordx4 v[192:193], v[180:183], off
	s_andn2_b64 exec, exec, s[34:35]
	s_cbranch_execnz .LBB0_1283
	s_branch .LBB0_1280

; DI int TID() { int t = threadIdx.x; asm volatile("" : "+v"(t)); return t; }
; DI bf16x8 pack8f(const float* v) { u32x4 w = {cvtpk(v[0], v[1]), cvtpk(v[2], v[3]), cvtpk(v[4], v[5]), cvtpk(v[6], v[7])}; return __builtin_bit_cast(bf16x8, w); }
; DI void store_R(const float* Cs, int cb, int nc, bfu* dst, long ld, float scale, const float* rs = nullptr) {
;   const int cpr = nc >> 3;
;   for (int u = TID(); u < 128 * cpr; u += NT) {
;     int row = u / cpr, c8 = (u % cpr) * 8; float v[8]; ldrow8(Cs, row, cb + c8, v);
;     float s = rs ? scale * rs[row] : scale;
;     for (int j = 0; j < 8; ++j) v[j] *= s;
;     st8(dst + row * ld + c8, pack8f(v));
;   }
; }
; DI void epi_in1(const Params& p, float* Cs, int m0, int n0) {
;     ...
;     if (isq) store_R(Cs, 0, 128, (bfu*)(G + L1_QL) + (long)m0 * 512 + j * 128, 512, 1.f);
;     else store_R(Cs, 0, 128, (bfu*)(G + L1_KVL) + (long)m0 * 256 + j * 128, 256, 1.f);
.LBB0_1289:
	v_ashrrev_i32_e32 v179, 31, v176
	v_lshrrev_b32_e32 v179, 28, v179
	v_add_u32_e32 v179, v176, v179
	v_add_u32_e32 v180, 0x100, v176
	v_ashrrev_i32_e32 v192, 4, v179
	v_and_b32_e32 v179, -16, v179
	v_cmp_lt_i32_e32 vcc, s53, v176
	v_mov_b32_e32 v176, v180
	v_lshlrev_b32_e32 v180, 7, v192
	v_add_u32_e32 v179, v178, v179
	v_sub_u32_e32 v194, v177, v180
	ds_read_b128 v[180:183], v179
	ds_read_b128 v[188:191], v179 offset:16
	v_ashrrev_i32_e32 v193, 31, v192
	v_lshlrev_b64 v[192:193], 9, v[192:193]
	v_lshl_add_u64 v[192:193], s[34:35], 0, v[192:193]
	v_ashrrev_i32_e32 v195, 31, v194
	s_or_b64 s[36:37], vcc, s[36:37]
	v_add_u32_e32 v178, 0x2000, v178
	v_add_u32_e32 v177, 0x800, v177
	v_lshl_add_u64 v[192:193], v[194:195], 1, v[192:193]
	s_waitcnt lgkmcnt(0)
	v_cvt_pk_bf16_f32 v180, v180, v181
	v_cvt_pk_bf16_f32 v181, v182, v183
	v_cvt_pk_bf16_f32 v182, v188, v189
	v_cvt_pk_bf16_f32 v183, v190, v191
	global_store_dwordx4 v[192:193], v[180:183], off
	s_andn2_b64 exec, exec, s[36:37]
	s_cbranch_execnz .LBB0_1289

; DI int TID() { int t = threadIdx.x; asm volatile("" : "+v"(t)); return t; }
; DI bf16x8 pack8f(const float* v) { u32x4 w = {cvtpk(v[0], v[1]), cvtpk(v[2], v[3]), cvtpk(v[4], v[5]), cvtpk(v[6], v[7])}; return __builtin_bit_cast(bf16x8, w); }
; DI void store_R(const float* Cs, int cb, int nc, bfu* dst, long ld, float scale, const float* rs = nullptr) {
;   const int cpr = nc >> 3;
;   for (int u = TID(); u < 128 * cpr; u += NT) {
;     int row = u / cpr, c8 = (u % cpr) * 8; float v[8]; ldrow8(Cs, row, cb + c8, v);
;     float s = rs ? scale * rs[row] : scale;
;     for (int j = 0; j < 8; ++j) v[j] *= s;
;     st8(dst + row * ld + c8, pack8f(v));
;   }
; }
; DI void epi_in1(const Params& p, float* Cs, int m0, int n0) {
;     ...
;     if (isq) store_R(Cs, 0, 128, (bfu*)(G + L1_QL) + (long)m0 * 512 + j * 128, 512, 1.f);
;     else store_R(Cs, 0, 128, (bfu*)(G + L1_KVL) + (long)m0 * 256 + j * 128, 256, 1.f);
.LBB0_1294:
	v_ashrrev_i32_e32 v179, 31, v176
	v_lshrrev_b32_e32 v179, 28, v179
	v_add_u32_e32 v179, v176, v179
	v_add_u32_e32 v180, 0x100, v176
	v_ashrrev_i32_e32 v192, 4, v179
	v_and_b32_e32 v179, -16, v179
	v_cmp_lt_i32_e32 vcc, s53, v176
	v_mov_b32_e32 v176, v180
	v_lshlrev_b32_e32 v180, 7, v192
	v_add_u32_e32 v179, v178, v179
	v_sub_u32_e32 v194, v177, v180
	ds_read_b128 v[180:183], v179
	ds_read_b128 v[188:191], v179 offset:16
	v_ashrrev_i32_e32 v193, 31, v192
	v_lshlrev_b64 v[192:193], 10, v[192:193]
	v_lshl_add_u64 v[192:193], s[34:35], 0, v[192:193]
	v_ashrrev_i32_e32 v195, 31, v194
	s_or_b64 s[36:37], vcc, s[36:37]
	v_add_u32_e32 v178, 0x2000, v178
	v_add_u32_e32 v177, 0x800, v177
	v_lshl_add_u64 v[192:193], v[194:195], 1, v[192:193]
	s_waitcnt lgkmcnt(0)
	v_cvt_pk_bf16_f32 v180, v180, v181
	v_cvt_pk_bf16_f32 v181, v182, v183
	v_cvt_pk_bf16_f32 v182, v188, v189
	v_cvt_pk_bf16_f32 v183, v190, v191
	global_store_dwordx4 v[192:193], v[180:183], off
	s_andn2_b64 exec, exec, s[36:37]
	s_cbranch_execnz .LBB0_1294

; DI int TID() { int t = threadIdx.x; asm volatile("" : "+v"(t)); return t; }
; DI void epi_in1(const Params& p, float* Cs, int m0, int n0) {
;     ...
;     float* ss = (float*)(G + L1_SM + (isq ? SM_SSQ : SM_SSK));
;     for (int u = TID(); u < 2048; u += NT) {
;       int row = u >> 4, c8 = (u & 15) * 8; float v[8]; ldrow8(Cs, row, c8, v);
;       float s = 0; for (int jj = 0; jj < 8; ++jj) s += v[jj] * v[jj];
;       s += __shfl_xor(s, 1); s += __shfl_xor(s, 2); s += __shfl_xor(s, 4); s += __shfl_xor(s, 8);
;       if ((u & 15) == 0) ss[(long)(m0 + row) * (isq ? 4 : 2) + j] = s;
;     }
.LBB0_1299:
	v_ashrrev_i32_e32 v182, 4, v177
	v_mad_u64_u32 v[192:193], s[0:1], v182, s78, v[176:177]
	ds_read_b128 v[188:191], v192
	ds_read_b128 v[192:195], v192 offset:16
	s_waitcnt lgkmcnt(0)
	v_mul_f32_e32 v183, v189, v189
	v_fmac_f32_e32 v183, v188, v188
	v_fmac_f32_e32 v183, v190, v190
	v_fmac_f32_e32 v183, v191, v191
	v_fmac_f32_e32 v183, v192, v192
	v_fmac_f32_e32 v183, v193, v193
	v_fmac_f32_e32 v183, v194, v194
	v_fmac_f32_e32 v183, v195, v195
	ds_bpermute_b32 v184, v178, v183
	s_waitcnt lgkmcnt(0)
	v_add_f32_e32 v183, v183, v184
	ds_bpermute_b32 v184, v179, v183
	s_waitcnt lgkmcnt(0)
	v_add_f32_e32 v183, v183, v184
	ds_bpermute_b32 v184, v180, v183
	s_waitcnt lgkmcnt(0)
	v_add_f32_e32 v183, v183, v184
	ds_bpermute_b32 v184, v181, v183
	s_and_saveexec_b64 s[0:1], vcc
	s_cbranch_execz .LBB0_1298
	v_add_u32_e32 v188, s14, v182
	v_ashrrev_i32_e32 v189, 31, v188
	v_lshlrev_b64 v[188:189], s13, v[188:189]
	v_lshl_add_u64 v[188:189], v[188:189], 2, s[2:3]
	s_waitcnt lgkmcnt(0)
	v_add_f32_e32 v182, v183, v184
	global_store_dword v[188:189], v182, off
	s_branch .LBB0_1298

;   DI const float* c() const { return (const float*)sp[1]; }
; DI int TID() { int t = threadIdx.x; asm volatile("" : "+v"(t)); return t; }
; DI bf16x8 pack8f(const float* v) { u32x4 w = {cvtpk(v[0], v[1]), cvtpk(v[2], v[3]), cvtpk(v[4], v[5]), cvtpk(v[6], v[7])}; return __builtin_bit_cast(bf16x8, w); }
; DI void store_T(const float* Cs, int cb, int nc, bfu* dst, long ldT, float scale, const float* rs = nullptr) {
;   for (int u = TID(); u < nc * 16; u += NT) {
;     int c = u % nc, rc = (u / nc) * 8; float v[8];
;     for (int j = 0; j < 8; ++j) v[j] = Cs[(rc + j) * CLD + cb + c] * (rs ? scale * rs[rc + j] : scale);
;     st8(dst + c * ldT + rc, pack8f(v));
;   }
; }
.LBB0_1306:
	v_ashrrev_i32_e32 v179, 31, v177
	v_lshrrev_b32_e32 v179, 25, v179
	v_add_u32_e32 v179, v177, v179
	v_add_u32_e32 v180, 0x100, v177
	v_ashrrev_i32_e32 v179, 7, v179
	v_cmp_lt_i32_e32 vcc, s53, v177
	v_mov_b32_e32 v177, v180
	v_mad_u64_u32 v[182:183], s[36:37], v179, s15, v[178:179]
	v_lshlrev_b32_e32 v180, 3, v179
	v_mad_u64_u32 v[188:189], s[36:37], v179, s42, v[176:177]
	v_add_u32_e32 v179, 0x400, v182
	v_add_u32_e32 v194, 0xc00, v182
	ds_read2_b32 v[190:191], v182 offset1:132
	s_waitcnt lgkmcnt(0)
	v_add_u32_e32 v184, 0x800, v182
	ds_read2_b32 v[182:183], v179 offset0:8 offset1:140
	ds_read2_b32 v[192:193], v184 offset0:16 offset1:148
	ds_read2_b32 v[194:195], v194 offset0:24 offset1:156
	v_ashrrev_i32_e32 v189, 31, v188
	v_ashrrev_i32_e32 v181, 31, v180
	v_lshl_add_u64 v[188:189], s[2:3], 0, v[188:189]
	s_or_b64 s[34:35], vcc, s[34:35]
	v_add_u32_e32 v176, 0x120000, v176
	v_add_u32_e32 v178, 0x400, v178
	v_lshl_add_u64 v[188:189], v[180:181], 1, v[188:189]
	v_cvt_pk_bf16_f32 v180, v190, v191
	s_waitcnt lgkmcnt(0)
	v_cvt_pk_bf16_f32 v181, v182, v183
	v_cvt_pk_bf16_f32 v182, v192, v193
	v_cvt_pk_bf16_f32 v183, v194, v195
	global_store_dwordx4 v[188:189], v[180:183], off
	s_andn2_b64 exec, exec, s[34:35]
	s_cbranch_execnz .LBB0_1306

; DI int TID() { int t = threadIdx.x; asm volatile("" : "+v"(t)); return t; }
; DI bf16x8 pack8f(const float* v) { u32x4 w = {cvtpk(v[0], v[1]), cvtpk(v[2], v[3]), cvtpk(v[4], v[5]), cvtpk(v[6], v[7])}; return __builtin_bit_cast(bf16x8, w); }
; DI void store_R(const float* Cs, int cb, int nc, bfu* dst, long ld, float scale, const float* rs = nullptr) {
;   const int cpr = nc >> 3;
;   for (int u = TID(); u < 128 * cpr; u += NT) {
;     int row = u / cpr, c8 = (u % cpr) * 8; float v[8]; ldrow8(Cs, row, cb + c8, v);
;     float s = rs ? scale * rs[row] : scale;
;     for (int j = 0; j < 8; ++j) v[j] *= s;
;     st8(dst + row * ld + c8, pack8f(v));
;   }
; }
; DI void epi_in1(const Params& p, float* Cs, int m0, int n0) {
;     ...
;     bfu* dst = (bfu*)(G + (isq ? L1_RQ : L1_RK)) + ((long)(bg * 8 + head) * T + t0) * 256;
;     const float sc = isq ? 1.f : 0.0625f;
;     store_R(Cs, 0, 64, dst + par * 64, 256, sc); store_R(Cs, 64, 64, dst + 128 + par * 64, 256, sc);
.LBB0_1317:
	v_ashrrev_i32_e32 v181, 31, v179
	v_lshrrev_b32_e32 v181, 29, v181
	v_add_u32_e32 v182, 0x100, v179
	v_add_u32_e32 v181, v179, v181
	v_cmp_lt_i32_e32 vcc, s87, v179
	v_mov_b32_e32 v179, v182
	v_ashrrev_i32_e32 v182, 3, v181
	v_mad_u64_u32 v[192:193], s[62:63], v182, s60, v[178:179]
	ds_read_b128 v[188:191], v192
	ds_read_b128 v[192:195], v192 offset:16
	v_lshlrev_b32_e32 v181, 6, v182
	v_ashrrev_i32_e32 v183, 31, v182
	v_sub_u32_e32 v196, v180, v181
	v_lshlrev_b64 v[182:183], 9, v[182:183]
	v_lshl_add_u64 v[182:183], s[2:3], 0, v[182:183]
	v_ashrrev_i32_e32 v197, 31, v196
	s_waitcnt lgkmcnt(0)
	v_pk_mul_f32 v[188:189], v[176:177], v[188:189]
	v_pk_mul_f32 v[190:191], v[176:177], v[190:191]
	v_pk_mul_f32 v[192:193], v[176:177], v[192:193]
	v_pk_mul_f32 v[194:195], v[176:177], v[194:195]
	s_or_b64 s[36:37], vcc, s[36:37]
	v_add_u32_e32 v178, 0x2000, v178
	v_add_u32_e32 v180, 0x800, v180
	v_lshl_add_u64 v[182:183], v[196:197], 1, v[182:183]
	v_cvt_pk_bf16_f32 v188, v188, v189
	v_cvt_pk_bf16_f32 v189, v190, v191
	v_cvt_pk_bf16_f32 v190, v192, v193
	v_cvt_pk_bf16_f32 v191, v194, v195
	global_store_dwordx4 v[182:183], v[188:191], off
	s_andn2_b64 exec, exec, s[36:37]
	s_cbranch_execnz .LBB0_1317

; DI int TID() { int t = threadIdx.x; asm volatile("" : "+v"(t)); return t; }
; DI bf16x8 pack8f(const float* v) { u32x4 w = {cvtpk(v[0], v[1]), cvtpk(v[2], v[3]), cvtpk(v[4], v[5]), cvtpk(v[6], v[7])}; return __builtin_bit_cast(bf16x8, w); }
; DI void store_R(const float* Cs, int cb, int nc, bfu* dst, long ld, float scale, const float* rs = nullptr) {
;   const int cpr = nc >> 3;
;   for (int u = TID(); u < 128 * cpr; u += NT) {
;     int row = u / cpr, c8 = (u % cpr) * 8; float v[8]; ldrow8(Cs, row, cb + c8, v);
;     float s = rs ? scale * rs[row] : scale;
;     for (int j = 0; j < 8; ++j) v[j] *= s;
;     st8(dst + row * ld + c8, pack8f(v));
;   }
; }
; DI void epi_in1(const Params& p, float* Cs, int m0, int n0) {
;     ...
;     bfu* dst = (bfu*)(G + (isq ? L1_RQ : L1_RK)) + ((long)(bg * 8 + head) * T + t0) * 256;
;     const float sc = isq ? 1.f : 0.0625f;
;     store_R(Cs, 0, 64, dst + par * 64, 256, sc); store_R(Cs, 64, 64, dst + 128 + par * 64, 256, sc);
.LBB0_1320:
	v_ashrrev_i32_e32 v181, 31, v179
	v_lshrrev_b32_e32 v181, 29, v181
	v_add_u32_e32 v182, 0x100, v179
	v_add_u32_e32 v181, v179, v181
	v_cmp_lt_i32_e32 vcc, s87, v179
	v_mov_b32_e32 v179, v182
	v_ashrrev_i32_e32 v182, 3, v181
	v_mad_u64_u32 v[192:193], s[62:63], v182, s60, v[178:179]
	ds_read_b128 v[188:191], v192
	ds_read_b128 v[192:195], v192 offset:16
	v_lshlrev_b32_e32 v181, 6, v182
	v_ashrrev_i32_e32 v183, 31, v182
	v_sub_u32_e32 v196, v180, v181
	v_lshlrev_b64 v[182:183], 9, v[182:183]
	v_lshl_add_u64 v[182:183], s[2:3], 0, v[182:183]
	v_ashrrev_i32_e32 v197, 31, v196
	s_waitcnt lgkmcnt(0)
	v_pk_mul_f32 v[188:189], v[176:177], v[188:189]
	v_pk_mul_f32 v[190:191], v[176:177], v[190:191]
	v_pk_mul_f32 v[192:193], v[176:177], v[192:193]
	v_pk_mul_f32 v[194:195], v[176:177], v[194:195]
	s_or_b64 s[36:37], vcc, s[36:37]
	v_add_u32_e32 v178, 0x2000, v178
	v_add_u32_e32 v180, 0x800, v180
	v_lshl_add_u64 v[182:183], v[196:197], 1, v[182:183]
	v_cvt_pk_bf16_f32 v188, v188, v189
	v_cvt_pk_bf16_f32 v189, v190, v191
	v_cvt_pk_bf16_f32 v190, v192, v193
	v_cvt_pk_bf16_f32 v191, v194, v195
	global_store_dwordx4 v[182:183], v[188:191], off offset:256
	s_andn2_b64 exec, exec, s[36:37]
	s_cbranch_execnz .LBB0_1320

;   DI const float* c() const { return (const float*)sp[1]; }
; DI int TID() { int t = threadIdx.x; asm volatile("" : "+v"(t)); return t; }
; DI bf16x8 pack8f(const float* v) { u32x4 w = {cvtpk(v[0], v[1]), cvtpk(v[2], v[3]), cvtpk(v[4], v[5]), cvtpk(v[6], v[7])}; return __builtin_bit_cast(bf16x8, w); }
; DI void store_T(const float* Cs, int cb, int nc, bfu* dst, long ldT, float scale, const float* rs = nullptr) {
;   for (int u = TID(); u < nc * 16; u += NT) {
;     int c = u % nc, rc = (u / nc) * 8; float v[8];
;     for (int j = 0; j < 8; ++j) v[j] = Cs[(rc + j) * CLD + cb + c] * (rs ? scale * rs[rc + j] : scale);
;     st8(dst + c * ldT + rc, pack8f(v));
;   }
; }
; DI void epi_in1(const Params& p, float* Cs, int m0, int n0) {
;     ...
;     if (!isq) {
;       bfu* dT = (bfu*)(G + L1_RKT) + ((long)(bg * 8 + head) * 256) * T + t0;
;       store_T(Cs, 0, 64, dT + (long)(par * 64) * T, T, sc); store_T(Cs, 64, 64, dT + (long)(128 + par * 64) * T, T, sc);
;     }
.LBB0_1324:
	v_ashrrev_i32_e32 v179, 31, v177
	v_lshrrev_b32_e32 v179, 26, v179
	v_add_u32_e32 v179, v177, v179
	v_add_u32_e32 v180, 0x100, v177
	v_ashrrev_i32_e32 v179, 6, v179
	v_cmp_lt_i32_e32 vcc, s87, v177
	v_mov_b32_e32 v177, v180
	v_mad_u64_u32 v[182:183], s[36:37], v179, s35, v[178:179]
	v_lshlrev_b32_e32 v180, 3, v179
	v_mad_u64_u32 v[188:189], s[36:37], v179, s55, v[176:177]
	v_add_u32_e32 v179, 0x400, v182
	v_add_u32_e32 v194, 0xc00, v182
	ds_read2_b32 v[190:191], v182 offset1:132
	s_waitcnt lgkmcnt(0)
	v_add_u32_e32 v184, 0x800, v182
	ds_read2_b32 v[182:183], v179 offset0:8 offset1:140
	ds_read2_b32 v[192:193], v184 offset0:16 offset1:148
	ds_read2_b32 v[194:195], v194 offset0:24 offset1:156
	v_ashrrev_i32_e32 v189, 31, v188
	v_ashrrev_i32_e32 v181, 31, v180
	v_lshl_add_u64 v[188:189], s[2:3], 0, v[188:189]
	v_lshl_add_u64 v[188:189], v[180:181], 1, v[188:189]
	v_pk_mul_f32 v[180:181], v[190:191], s[76:77] op_sel_hi:[1,0]
	s_waitcnt lgkmcnt(0)
	v_pk_mul_f32 v[182:183], v[182:183], s[76:77] op_sel_hi:[1,0]
	v_pk_mul_f32 v[190:191], v[192:193], s[76:77] op_sel_hi:[1,0]
	v_pk_mul_f32 v[192:193], v[194:195], s[76:77] op_sel_hi:[1,0]
	s_or_b64 s[30:31], vcc, s[30:31]
	v_add_u32_e32 v176, 0x120000, v176
	v_add_u32_e32 v178, 0x400, v178
	v_cvt_pk_bf16_f32 v180, v180, v181
	v_cvt_pk_bf16_f32 v181, v182, v183
	v_cvt_pk_bf16_f32 v182, v190, v191
	v_cvt_pk_bf16_f32 v183, v192, v193
	global_store_dwordx4 v[188:189], v[180:183], off
	s_andn2_b64 exec, exec, s[30:31]
	s_cbranch_execnz .LBB0_1324

;   DI const float* c() const { return (const float*)sp[1]; }
; DI int TID() { int t = threadIdx.x; asm volatile("" : "+v"(t)); return t; }
; DI bf16x8 pack8f(const float* v) { u32x4 w = {cvtpk(v[0], v[1]), cvtpk(v[2], v[3]), cvtpk(v[4], v[5]), cvtpk(v[6], v[7])}; return __builtin_bit_cast(bf16x8, w); }
; DI void store_T(const float* Cs, int cb, int nc, bfu* dst, long ldT, float scale, const float* rs = nullptr) {
;   for (int u = TID(); u < nc * 16; u += NT) {
;     int c = u % nc, rc = (u / nc) * 8; float v[8];
;     for (int j = 0; j < 8; ++j) v[j] = Cs[(rc + j) * CLD + cb + c] * (rs ? scale * rs[rc + j] : scale);
;     st8(dst + c * ldT + rc, pack8f(v));
;   }
; }
; DI void epi_in1(const Params& p, float* Cs, int m0, int n0) {
;     ...
;     if (!isq) {
;       bfu* dT = (bfu*)(G + L1_RKT) + ((long)(bg * 8 + head) * 256) * T + t0;
;       store_T(Cs, 0, 64, dT + (long)(par * 64) * T, T, sc); store_T(Cs, 64, 64, dT + (long)(128 + par * 64) * T, T, sc);
;     }
.LBB0_1327:
	v_ashrrev_i32_e32 v179, 31, v177
	v_lshrrev_b32_e32 v179, 26, v179
	v_add_u32_e32 v179, v177, v179
	v_add_u32_e32 v180, 0x100, v177
	v_ashrrev_i32_e32 v179, 6, v179
	v_cmp_lt_i32_e32 vcc, s87, v177
	v_mov_b32_e32 v177, v180
	v_mad_u64_u32 v[182:183], s[34:35], v179, s36, v[178:179]
	v_lshlrev_b32_e32 v180, 3, v179
	v_mad_u64_u32 v[188:189], s[34:35], v179, s37, v[176:177]
	v_add_u32_e32 v179, 0x400, v182
	v_add_u32_e32 v194, 0xc00, v182
	ds_read2_b32 v[190:191], v182 offset0:64 offset1:196
	s_waitcnt lgkmcnt(0)
	v_add_u32_e32 v184, 0x800, v182
	ds_read2_b32 v[182:183], v179 offset0:72 offset1:204
	ds_read2_b32 v[192:193], v184 offset0:80 offset1:212
	ds_read2_b32 v[194:195], v194 offset0:88 offset1:220
	v_ashrrev_i32_e32 v189, 31, v188
	v_ashrrev_i32_e32 v181, 31, v180
	v_lshl_add_u64 v[188:189], s[2:3], 0, v[188:189]
	v_lshl_add_u64 v[188:189], v[180:181], 1, v[188:189]
	v_pk_mul_f32 v[180:181], v[190:191], s[76:77] op_sel_hi:[1,0]
	s_waitcnt lgkmcnt(0)
	v_pk_mul_f32 v[182:183], v[182:183], s[76:77] op_sel_hi:[1,0]
	v_pk_mul_f32 v[190:191], v[192:193], s[76:77] op_sel_hi:[1,0]
	v_pk_mul_f32 v[192:193], v[194:195], s[76:77] op_sel_hi:[1,0]
	s_or_b64 s[30:31], vcc, s[30:31]
	v_add_u32_e32 v176, 0x120000, v176
	v_add_u32_e32 v178, 0x400, v178
	v_cvt_pk_bf16_f32 v180, v180, v181
	v_cvt_pk_bf16_f32 v181, v182, v183
	v_cvt_pk_bf16_f32 v182, v190, v191
	v_cvt_pk_bf16_f32 v183, v192, v193
	global_store_dwordx4 v[188:189], v[180:183], off
	s_andn2_b64 exec, exec, s[30:31]
	s_cbranch_execnz .LBB0_1327

; DI int TID() { int t = threadIdx.x; asm volatile("" : "+v"(t)); return t; }
; DI unsigned cvtpk(float lo, float hi) { f32x2_t v = {lo, hi}; bf16x2_t b = __builtin_convertvector(v, bf16x2_t); return __builtin_bit_cast(unsigned, b); }
; DI void store_T_regs(const f32x16 (&acc)[2][4], int h, bfu* dst, const float* rs) {
;   const int tid = TID(), lane = tid & 63, w = tid >> 6, wm = w >> 1, wn = w & 1, l32 = lane & 31, hi = lane >> 5;
;   if (wn != h) return;
; #pragma unroll
;   for (int mi = 0; mi < 2; ++mi)
; #pragma unroll
;     for (int ni = 0; ni < 4; ++ni)
; #pragma unroll
;       for (int rg = 0; rg < 4; ++rg) {
;         const int row = wm * 64 + mi * 32 + 8 * rg + 4 * hi;
;         float s0 = 1.f, s1 = 1.f, s2 = 1.f, s3 = 1.f;
;         if (rs) { s0 = rs[row]; s1 = rs[row + 1]; s2 = rs[row + 2]; s3 = rs[row + 3]; }
;         const u32x2 v = {cvtpk(acc[mi][ni][4 * rg] * s0, acc[mi][ni][4 * rg + 1] * s1), cvtpk(acc[mi][ni][4 * rg + 2] * s2, acc[mi][ni][4 * rg + 3] * s3)};
;         *reinterpret_cast<u32x2*>(dst + (long)(ni * 32 + l32) * T + row) = v;
;       }
; }
.LBB0_1331:
	s_cmp_eq_u64 s[2:3], 0
	s_cbranch_scc1 .LBB0_1335
	v_mov_b32_e32 v176, v202
	s_nop 0
	v_and_b32_e32 v177, 64, v176
	v_cmp_ne_u32_e32 vcc, 0, v177
	s_and_saveexec_b64 s[0:1], vcc
	s_cbranch_execz .LBB0_1334
	v_and_b32_e32 v177, 31, v176
	v_ashrrev_i32_e32 v178, 1, v176
	v_lshrrev_b32_e32 v176, 3, v176
	v_and_b32_e32 v176, 4, v176
	s_movk_i32 s13, 0xffc0
	v_and_or_b32 v176, v178, s13, v176
	v_mul_u32_u24_e32 v177, 0x900, v177
	s_waitcnt lgkmcnt(0)
	v_lshlrev_b32_e32 v184, 1, v177
	v_ashrrev_i32_e32 v177, 31, v176
	v_lshl_add_u64 v[178:179], s[2:3], 0, v[184:185]
	v_lshlrev_b64 v[182:183], 1, v[176:177]
	v_cvt_pk_bf16_f32 v180, v112, v113
	v_cvt_pk_bf16_f32 v181, v114, v115
	v_lshl_add_u64 v[188:189], v[178:179], 0, v[182:183]
	global_store_dwordx2 v[188:189], v[180:181], off
	v_or_b32_e32 v180, 8, v176
	v_cvt_pk_bf16_f32 v190, v116, v117
	v_cvt_pk_bf16_f32 v191, v118, v119
	v_cvt_pk_bf16_f32 v194, v124, v125
	v_cvt_pk_bf16_f32 v195, v126, v127
	s_mov_b64 s[2:3], 0x24000
	v_ashrrev_i32_e32 v181, 31, v180
	global_store_dwordx2 v[188:189], v[190:191], off offset:16
	v_or_b32_e32 v190, 16, v176
	v_cvt_pk_bf16_f32 v192, v120, v121
	v_cvt_pk_bf16_f32 v193, v122, v123
	global_store_dwordx2 v[188:189], v[194:195], off offset:48
	v_lshl_add_u64 v[194:195], v[178:179], 0, s[2:3]
	v_ashrrev_i32_e32 v191, 31, v190
	global_store_dwordx2 v[188:189], v[192:193], off offset:32
	v_or_b32_e32 v192, 24, v176
	v_cvt_pk_bf16_f32 v196, v96, v97
	v_cvt_pk_bf16_f32 v197, v98, v99
	v_lshl_add_u64 v[198:199], v[194:195], 0, v[182:183]
	v_lshlrev_b64 v[180:181], 1, v[180:181]
	v_ashrrev_i32_e32 v193, 31, v192
	global_store_dwordx2 v[198:199], v[196:197], off
	v_cvt_pk_bf16_f32 v196, v100, v101
	v_cvt_pk_bf16_f32 v197, v102, v103
	v_lshl_add_u64 v[198:199], v[194:195], 0, v[180:181]
	v_lshlrev_b64 v[190:191], 1, v[190:191]
	global_store_dwordx2 v[198:199], v[196:197], off
	v_cvt_pk_bf16_f32 v196, v104, v105
	v_cvt_pk_bf16_f32 v197, v106, v107
	v_lshl_add_u64 v[198:199], v[194:195], 0, v[190:191]
	v_lshlrev_b64 v[192:193], 1, v[192:193]
	global_store_dwordx2 v[198:199], v[196:197], off
	v_cvt_pk_bf16_f32 v196, v108, v109
	v_cvt_pk_bf16_f32 v197, v110, v111
	v_lshl_add_u64 v[198:199], v[194:195], 0, v[192:193]
	s_mov_b64 s[2:3], 0x48000
	global_store_dwordx2 v[198:199], v[196:197], off
	v_lshl_add_u64 v[196:197], v[178:179], 0, s[2:3]
	v_cvt_pk_bf16_f32 v198, v80, v81
	v_cvt_pk_bf16_f32 v199, v82, v83
	v_lshl_add_u64 v[200:201], v[196:197], 0, v[182:183]
	global_store_dwordx2 v[200:201], v[198:199], off
	v_cvt_pk_bf16_f32 v198, v84, v85
	v_cvt_pk_bf16_f32 v199, v86, v87
	v_lshl_add_u64 v[200:201], v[196:197], 0, v[180:181]
	global_store_dwordx2 v[200:201], v[198:199], off
	v_cvt_pk_bf16_f32 v198, v88, v89
	v_cvt_pk_bf16_f32 v199, v90, v91
	v_lshl_add_u64 v[200:201], v[196:197], 0, v[190:191]
	s_mov_b64 s[2:3], 0x6c000
	global_store_dwordx2 v[200:201], v[198:199], off
	v_cvt_pk_bf16_f32 v198, v92, v93
	v_cvt_pk_bf16_f32 v199, v94, v95
	v_lshl_add_u64 v[200:201], v[196:197], 0, v[192:193]
	v_lshl_add_u64 v[178:179], v[178:179], 0, s[2:3]
	global_store_dwordx2 v[200:201], v[198:199], off
	v_cvt_pk_bf16_f32 v198, v64, v65
	v_cvt_pk_bf16_f32 v199, v66, v67
	v_lshl_add_u64 v[182:183], v[178:179], 0, v[182:183]
	global_store_dwordx2 v[182:183], v[198:199], off
	v_cvt_pk_bf16_f32 v182, v68, v69
	v_cvt_pk_bf16_f32 v183, v70, v71
	v_lshl_add_u64 v[180:181], v[178:179], 0, v[180:181]
	global_store_dwordx2 v[180:181], v[182:183], off
	v_cvt_pk_bf16_f32 v180, v72, v73
	v_cvt_pk_bf16_f32 v181, v74, v75
	v_lshl_add_u64 v[182:183], v[178:179], 0, v[190:191]
	global_store_dwordx2 v[182:183], v[180:181], off
	v_cvt_pk_bf16_f32 v180, v76, v77
	v_cvt_pk_bf16_f32 v181, v78, v79
	v_lshl_add_u64 v[182:183], v[178:179], 0, v[192:193]
	global_store_dwordx2 v[182:183], v[180:181], off
	v_or_b32_e32 v180, 32, v176
	v_cvt_pk_bf16_f32 v182, v48, v49
	v_cvt_pk_bf16_f32 v183, v50, v51
	v_ashrrev_i32_e32 v181, 31, v180
	global_store_dwordx2 v[188:189], v[182:183], off offset:64
	v_or_b32_e32 v182, 40, v176
	v_cvt_pk_bf16_f32 v190, v52, v53
	v_cvt_pk_bf16_f32 v191, v54, v55
	v_cvt_pk_bf16_f32 v192, v56, v57
	v_cvt_pk_bf16_f32 v193, v58, v59
	v_ashrrev_i32_e32 v183, 31, v182
	global_store_dwordx2 v[188:189], v[190:191], off offset:80
	v_or_b32_e32 v190, 48, v176
	global_store_dwordx2 v[188:189], v[192:193], off offset:96
	v_cvt_pk_bf16_f32 v192, v60, v61
	v_cvt_pk_bf16_f32 v193, v62, v63
	v_lshlrev_b64 v[180:181], 1, v[180:181]
	v_ashrrev_i32_e32 v191, 31, v190
	v_or_b32_e32 v176, 56, v176
	global_store_dwordx2 v[188:189], v[192:193], off offset:112
	v_cvt_pk_bf16_f32 v188, v32, v33
	v_cvt_pk_bf16_f32 v189, v34, v35
	v_lshl_add_u64 v[192:193], v[194:195], 0, v[180:181]
	v_lshlrev_b64 v[182:183], 1, v[182:183]
	v_ashrrev_i32_e32 v177, 31, v176
	global_store_dwordx2 v[192:193], v[188:189], off
	v_cvt_pk_bf16_f32 v188, v36, v37
	v_cvt_pk_bf16_f32 v189, v38, v39
	v_lshl_add_u64 v[192:193], v[194:195], 0, v[182:183]
	v_lshlrev_b64 v[190:191], 1, v[190:191]
	global_store_dwordx2 v[192:193], v[188:189], off
	v_cvt_pk_bf16_f32 v188, v40, v41
	v_cvt_pk_bf16_f32 v189, v42, v43
	v_lshl_add_u64 v[192:193], v[194:195], 0, v[190:191]
	v_lshlrev_b64 v[176:177], 1, v[176:177]
	global_store_dwordx2 v[192:193], v[188:189], off
	v_cvt_pk_bf16_f32 v188, v44, v45
	v_cvt_pk_bf16_f32 v189, v46, v47
	v_lshl_add_u64 v[192:193], v[194:195], 0, v[176:177]
	global_store_dwordx2 v[192:193], v[188:189], off
	v_cvt_pk_bf16_f32 v188, v16, v17
	v_cvt_pk_bf16_f32 v189, v18, v19
	v_lshl_add_u64 v[192:193], v[196:197], 0, v[180:181]
	global_store_dwordx2 v[192:193], v[188:189], off
	v_cvt_pk_bf16_f32 v188, v20, v21
	v_cvt_pk_bf16_f32 v189, v22, v23
	v_lshl_add_u64 v[192:193], v[196:197], 0, v[182:183]
	global_store_dwordx2 v[192:193], v[188:189], off
	v_cvt_pk_bf16_f32 v188, v24, v25
	v_cvt_pk_bf16_f32 v189, v26, v27
	v_lshl_add_u64 v[192:193], v[196:197], 0, v[190:191]
	global_store_dwordx2 v[192:193], v[188:189], off
	v_cvt_pk_bf16_f32 v188, v28, v29
	v_cvt_pk_bf16_f32 v189, v30, v31
	v_lshl_add_u64 v[192:193], v[196:197], 0, v[176:177]
	global_store_dwordx2 v[192:193], v[188:189], off
	v_cvt_pk_bf16_f32 v188, v0, v1
	v_cvt_pk_bf16_f32 v189, v2, v3
	v_lshl_add_u64 v[180:181], v[178:179], 0, v[180:181]
	global_store_dwordx2 v[180:181], v[188:189], off
	v_cvt_pk_bf16_f32 v180, v4, v5
	v_cvt_pk_bf16_f32 v181, v6, v7
	v_lshl_add_u64 v[182:183], v[178:179], 0, v[182:183]
	global_store_dwordx2 v[182:183], v[180:181], off
	v_cvt_pk_bf16_f32 v180, v8, v9
	v_cvt_pk_bf16_f32 v181, v10, v11
	v_lshl_add_u64 v[182:183], v[178:179], 0, v[190:191]
	global_store_dwordx2 v[182:183], v[180:181], off
	v_cvt_pk_bf16_f32 v180, v12, v13
	v_cvt_pk_bf16_f32 v181, v14, v15
	v_lshl_add_u64 v[176:177], v[178:179], 0, v[176:177]
	global_store_dwordx2 v[176:177], v[180:181], off

; DI int TID() { int t = threadIdx.x; asm volatile("" : "+v"(t)); return t; }
; DI bf16x8 pack8f(const float* v) { u32x4 w = {cvtpk(v[0], v[1]), cvtpk(v[2], v[3]), cvtpk(v[4], v[5]), cvtpk(v[6], v[7])}; return __builtin_bit_cast(bf16x8, w); }
; DI void store_R(const float* Cs, int cb, int nc, bfu* dst, long ld, float scale, const float* rs = nullptr) {
;   const int cpr = nc >> 3;
;   for (int u = TID(); u < 128 * cpr; u += NT) {
;     int row = u / cpr, c8 = (u % cpr) * 8; float v[8]; ldrow8(Cs, row, cb + c8, v);
;     float s = rs ? scale * rs[row] : scale;
;     for (int j = 0; j < 8; ++j) v[j] *= s;
;     st8(dst + row * ld + c8, pack8f(v));
;   }
; }
.LBB0_1344:
	v_ashrrev_i32_e32 v3, 31, v0
	v_lshrrev_b32_e32 v3, 28, v3
	v_add_u32_e32 v3, v0, v3
	v_add_u32_e32 v4, 0x100, v0
	v_ashrrev_i32_e32 v12, 4, v3
	v_and_b32_e32 v3, -16, v3
	v_cmp_lt_i32_e32 vcc, s53, v0
	v_mov_b32_e32 v0, v4
	v_lshlrev_b32_e32 v4, 7, v12
	v_add_u32_e32 v3, v2, v3
	v_sub_u32_e32 v14, v1, v4
	ds_read_b128 v[4:7], v3
	ds_read_b128 v[8:11], v3 offset:16
	v_ashrrev_i32_e32 v13, 31, v12
	v_lshlrev_b64 v[12:13], 13, v[12:13]
	v_lshl_add_u64 v[12:13], s[28:29], 0, v[12:13]
	v_ashrrev_i32_e32 v15, 31, v14
	s_or_b64 s[30:31], vcc, s[30:31]
	v_add_u32_e32 v2, 0x2000, v2
	v_add_u32_e32 v1, 0x800, v1
	v_lshl_add_u64 v[12:13], v[14:15], 1, v[12:13]
	s_waitcnt lgkmcnt(0)
	v_cvt_pk_bf16_f32 v4, v4, v5
	v_cvt_pk_bf16_f32 v5, v6, v7
	v_cvt_pk_bf16_f32 v6, v8, v9
	v_cvt_pk_bf16_f32 v7, v10, v11
	global_store_dwordx4 v[12:13], v[4:7], off
	s_andn2_b64 exec, exec, s[30:31]
	s_cbranch_execnz .LBB0_1344

; DI int TID() { int t = threadIdx.x; asm volatile("" : "+v"(t)); return t; }
; DI bf16x8 pack8f(const float* v) { u32x4 w = {cvtpk(v[0], v[1]), cvtpk(v[2], v[3]), cvtpk(v[4], v[5]), cvtpk(v[6], v[7])}; return __builtin_bit_cast(bf16x8, w); }
; DI void store_R(const float* Cs, int cb, int nc, bfu* dst, long ld, float scale, const float* rs = nullptr) {
;   const int cpr = nc >> 3;
;   for (int u = TID(); u < 128 * cpr; u += NT) {
;     int row = u / cpr, c8 = (u % cpr) * 8; float v[8]; ldrow8(Cs, row, cb + c8, v);
;     float s = rs ? scale * rs[row] : scale;
;     for (int j = 0; j < 8; ++j) v[j] *= s;
;     st8(dst + row * ld + c8, pack8f(v));
;   }
; }
.LBB0_1356:
	v_ashrrev_i32_e32 v3, 31, v1
	v_lshrrev_b32_e32 v3, 29, v3
	v_add_u32_e32 v6, 0x100, v1
	v_add_u32_e32 v3, v1, v3
	v_cmp_lt_i32_e32 vcc, s87, v1
	v_mov_b32_e32 v1, v6
	v_ashrrev_i32_e32 v3, 3, v3
	v_mov_b64_e32 v[4:5], s[28:29]
	v_lshlrev_b32_e32 v6, 6, v3
	v_mad_u64_u32 v[8:9], s[34:35], v3, s60, v[0:1]
	v_mad_i64_i32 v[12:13], s[34:35], v3, s74, v[4:5]
	v_sub_u32_e32 v14, v2, v6
	ds_read_b128 v[4:7], v8
	ds_read_b128 v[8:11], v8 offset:16
	v_ashrrev_i32_e32 v15, 31, v14
	s_or_b64 s[30:31], vcc, s[30:31]
	v_add_u32_e32 v0, 0x2000, v0
	v_add_u32_e32 v2, 0x800, v2
	v_lshl_add_u64 v[12:13], v[14:15], 1, v[12:13]
	s_waitcnt lgkmcnt(0)
	v_cvt_pk_bf16_f32 v4, v4, v5
	v_cvt_pk_bf16_f32 v5, v6, v7
	v_cvt_pk_bf16_f32 v6, v8, v9
	v_cvt_pk_bf16_f32 v7, v10, v11
	global_store_dwordx4 v[12:13], v[4:7], off
	s_andn2_b64 exec, exec, s[30:31]
	s_cbranch_execnz .LBB0_1356
	s_branch .LBB0_1353

; DI int TID() { int t = threadIdx.x; asm volatile("" : "+v"(t)); return t; }
; DI bf16x8 pack8f(const float* v) { u32x4 w = {cvtpk(v[0], v[1]), cvtpk(v[2], v[3]), cvtpk(v[4], v[5]), cvtpk(v[6], v[7])}; return __builtin_bit_cast(bf16x8, w); }
; DI void store_R(const float* Cs, int cb, int nc, bfu* dst, long ld, float scale, const float* rs = nullptr) {
;   const int cpr = nc >> 3;
;   for (int u = TID(); u < 128 * cpr; u += NT) {
;     int row = u / cpr, c8 = (u % cpr) * 8; float v[8]; ldrow8(Cs, row, cb + c8, v);
;     float s = rs ? scale * rs[row] : scale;
;     for (int j = 0; j < 8; ++j) v[j] *= s;
;     st8(dst + row * ld + c8, pack8f(v));
;   }
; }
; DI void epi_in1(const Params& p, float* Cs, int m0, int n0) {
;     ...
;     if (isq) store_R(Cs, 0, 128, (bfu*)(G + L1_QL) + (long)m0 * 512 + j * 128, 512, 1.f);
;     else store_R(Cs, 0, 128, (bfu*)(G + L1_KVL) + (long)m0 * 256 + j * 128, 256, 1.f);
.LBB0_1362:
	v_ashrrev_i32_e32 v3, 31, v0
	v_lshrrev_b32_e32 v3, 28, v3
	v_add_u32_e32 v3, v0, v3
	v_add_u32_e32 v4, 0x100, v0
	v_ashrrev_i32_e32 v12, 4, v3
	v_and_b32_e32 v3, -16, v3
	v_cmp_lt_i32_e32 vcc, s53, v0
	v_mov_b32_e32 v0, v4
	v_lshlrev_b32_e32 v4, 7, v12
	v_add_u32_e32 v3, v2, v3
	v_sub_u32_e32 v14, v1, v4
	ds_read_b128 v[4:7], v3
	ds_read_b128 v[8:11], v3 offset:16
	v_ashrrev_i32_e32 v13, 31, v12
	v_lshlrev_b64 v[12:13], 9, v[12:13]
	v_lshl_add_u64 v[12:13], s[26:27], 0, v[12:13]
	v_ashrrev_i32_e32 v15, 31, v14
	s_or_b64 s[30:31], vcc, s[30:31]
	v_add_u32_e32 v2, 0x2000, v2
	v_add_u32_e32 v1, 0x800, v1
	v_lshl_add_u64 v[12:13], v[14:15], 1, v[12:13]
	s_waitcnt lgkmcnt(0)
	v_cvt_pk_bf16_f32 v4, v4, v5
	v_cvt_pk_bf16_f32 v5, v6, v7
	v_cvt_pk_bf16_f32 v6, v8, v9
	v_cvt_pk_bf16_f32 v7, v10, v11
	global_store_dwordx4 v[12:13], v[4:7], off
	s_andn2_b64 exec, exec, s[30:31]
	s_cbranch_execnz .LBB0_1362

; DI int TID() { int t = threadIdx.x; asm volatile("" : "+v"(t)); return t; }
; DI bf16x8 pack8f(const float* v) { u32x4 w = {cvtpk(v[0], v[1]), cvtpk(v[2], v[3]), cvtpk(v[4], v[5]), cvtpk(v[6], v[7])}; return __builtin_bit_cast(bf16x8, w); }
; DI void store_R(const float* Cs, int cb, int nc, bfu* dst, long ld, float scale, const float* rs = nullptr) {
;   const int cpr = nc >> 3;
;   for (int u = TID(); u < 128 * cpr; u += NT) {
;     int row = u / cpr, c8 = (u % cpr) * 8; float v[8]; ldrow8(Cs, row, cb + c8, v);
;     float s = rs ? scale * rs[row] : scale;
;     for (int j = 0; j < 8; ++j) v[j] *= s;
;     st8(dst + row * ld + c8, pack8f(v));
;   }
; }
; DI void epi_in1(const Params& p, float* Cs, int m0, int n0) {
;     ...
;     if (isq) store_R(Cs, 0, 128, (bfu*)(G + L1_QL) + (long)m0 * 512 + j * 128, 512, 1.f);
;     else store_R(Cs, 0, 128, (bfu*)(G + L1_KVL) + (long)m0 * 256 + j * 128, 256, 1.f);
.LBB0_1367:
	v_ashrrev_i32_e32 v3, 31, v0
	v_lshrrev_b32_e32 v3, 28, v3
	v_add_u32_e32 v3, v0, v3
	v_add_u32_e32 v4, 0x100, v0
	v_ashrrev_i32_e32 v12, 4, v3
	v_and_b32_e32 v3, -16, v3
	v_cmp_lt_i32_e32 vcc, s53, v0
	v_mov_b32_e32 v0, v4
	v_lshlrev_b32_e32 v4, 7, v12
	v_add_u32_e32 v3, v2, v3
	v_sub_u32_e32 v14, v1, v4
	ds_read_b128 v[4:7], v3
	ds_read_b128 v[8:11], v3 offset:16
	v_ashrrev_i32_e32 v13, 31, v12
	v_lshlrev_b64 v[12:13], 10, v[12:13]
	v_lshl_add_u64 v[12:13], s[24:25], 0, v[12:13]
	v_ashrrev_i32_e32 v15, 31, v14
	s_or_b64 s[28:29], vcc, s[28:29]
	v_add_u32_e32 v2, 0x2000, v2
	v_add_u32_e32 v1, 0x800, v1
	v_lshl_add_u64 v[12:13], v[14:15], 1, v[12:13]
	s_waitcnt lgkmcnt(0)
	v_cvt_pk_bf16_f32 v4, v4, v5
	v_cvt_pk_bf16_f32 v5, v6, v7
	v_cvt_pk_bf16_f32 v6, v8, v9
	v_cvt_pk_bf16_f32 v7, v10, v11
	global_store_dwordx4 v[12:13], v[4:7], off
	s_andn2_b64 exec, exec, s[28:29]
	s_cbranch_execnz .LBB0_1367

; DI int TID() { int t = threadIdx.x; asm volatile("" : "+v"(t)); return t; }
; DI void epi_in1(const Params& p, float* Cs, int m0, int n0) {
;     ...
;     float* ss = (float*)(G + L1_SM + (isq ? SM_SSQ : SM_SSK));
;     for (int u = TID(); u < 2048; u += NT) {
;       int row = u >> 4, c8 = (u & 15) * 8; float v[8]; ldrow8(Cs, row, c8, v);
;       float s = 0; for (int jj = 0; jj < 8; ++jj) s += v[jj] * v[jj];
;       s += __shfl_xor(s, 1); s += __shfl_xor(s, 2); s += __shfl_xor(s, 4); s += __shfl_xor(s, 8);
;       if ((u & 15) == 0) ss[(long)(m0 + row) * (isq ? 4 : 2) + j] = s;
;     }
.LBB0_1372:
	v_ashrrev_i32_e32 v6, 4, v1
	v_mad_u64_u32 v[12:13], s[0:1], v6, s78, v[0:1]
	s_waitcnt lgkmcnt(0)
	ds_read_b128 v[8:11], v12
	ds_read_b128 v[12:15], v12 offset:16
	s_waitcnt lgkmcnt(0)
	v_mul_f32_e32 v7, v9, v9
	v_fmac_f32_e32 v7, v8, v8
	v_fmac_f32_e32 v7, v10, v10
	v_fmac_f32_e32 v7, v11, v11
	v_fmac_f32_e32 v7, v12, v12
	v_fmac_f32_e32 v7, v13, v13
	v_fmac_f32_e32 v7, v14, v14
	v_fmac_f32_e32 v7, v15, v15
	ds_bpermute_b32 v8, v2, v7
	s_waitcnt lgkmcnt(0)
	v_add_f32_e32 v7, v7, v8
	ds_bpermute_b32 v8, v3, v7
	s_waitcnt lgkmcnt(0)
	v_add_f32_e32 v7, v7, v8
	ds_bpermute_b32 v8, v4, v7
	s_waitcnt lgkmcnt(0)
	v_add_f32_e32 v7, v7, v8
	ds_bpermute_b32 v8, v5, v7
	s_and_saveexec_b64 s[0:1], vcc
	s_cbranch_execz .LBB0_1371
	v_add_u32_e32 v10, s14, v6
	v_ashrrev_i32_e32 v11, 31, v10
	v_lshlrev_b64 v[10:11], s13, v[10:11]
	v_lshl_add_u64 v[10:11], v[10:11], 2, s[26:27]
	s_waitcnt lgkmcnt(0)
	v_add_f32_e32 v6, v7, v8
	global_store_dword v[10:11], v6, off
	s_branch .LBB0_1371

;   DI const float* c() const { return (const float*)sp[1]; }
; DI int TID() { int t = threadIdx.x; asm volatile("" : "+v"(t)); return t; }
; DI bf16x8 pack8f(const float* v) { u32x4 w = {cvtpk(v[0], v[1]), cvtpk(v[2], v[3]), cvtpk(v[4], v[5]), cvtpk(v[6], v[7])}; return __builtin_bit_cast(bf16x8, w); }
; DI void store_T(const float* Cs, int cb, int nc, bfu* dst, long ldT, float scale, const float* rs = nullptr) {
;   for (int u = TID(); u < nc * 16; u += NT) {
;     int c = u % nc, rc = (u / nc) * 8; float v[8];
;     for (int j = 0; j < 8; ++j) v[j] = Cs[(rc + j) * CLD + cb + c] * (rs ? scale * rs[rc + j] : scale);
;     st8(dst + c * ldT + rc, pack8f(v));
;   }
; }
.LBB0_1379:
	v_ashrrev_i32_e32 v3, 31, v1
	v_lshrrev_b32_e32 v3, 25, v3
	v_add_u32_e32 v3, v1, v3
	v_add_u32_e32 v4, 0x100, v1
	v_ashrrev_i32_e32 v3, 7, v3
	v_cmp_lt_i32_e32 vcc, s53, v1
	v_mov_b32_e32 v1, v4
	v_mad_u64_u32 v[6:7], s[26:27], v3, s28, v[2:3]
	v_lshlrev_b32_e32 v4, 3, v3
	s_waitcnt lgkmcnt(0)
	v_mad_u64_u32 v[8:9], s[26:27], v3, s29, v[0:1]
	v_add_u32_e32 v3, 0x400, v6
	v_add_u32_e32 v12, 0x800, v6
	v_add_u32_e32 v14, 0xc00, v6
	ds_read2_b32 v[10:11], v6 offset1:132
	ds_read2_b32 v[6:7], v3 offset0:8 offset1:140
	ds_read2_b32 v[12:13], v12 offset0:16 offset1:148
	ds_read2_b32 v[14:15], v14 offset0:24 offset1:156
	v_ashrrev_i32_e32 v9, 31, v8
	v_ashrrev_i32_e32 v5, 31, v4
	v_lshl_add_u64 v[8:9], s[14:15], 0, v[8:9]
	s_or_b64 s[24:25], vcc, s[24:25]
	v_add_u32_e32 v0, 0x120000, v0
	v_add_u32_e32 v2, 0x400, v2
	v_lshl_add_u64 v[8:9], v[4:5], 1, v[8:9]
	s_waitcnt lgkmcnt(0)
	v_cvt_pk_bf16_f32 v4, v10, v11
	v_cvt_pk_bf16_f32 v5, v6, v7
	v_cvt_pk_bf16_f32 v6, v12, v13
	v_cvt_pk_bf16_f32 v7, v14, v15
	global_store_dwordx4 v[8:9], v[4:7], off
	s_andn2_b64 exec, exec, s[24:25]
	s_cbranch_execnz .LBB0_1379

; DI int TID() { int t = threadIdx.x; asm volatile("" : "+v"(t)); return t; }
; DI bf16x8 pack8f(const float* v) { u32x4 w = {cvtpk(v[0], v[1]), cvtpk(v[2], v[3]), cvtpk(v[4], v[5]), cvtpk(v[6], v[7])}; return __builtin_bit_cast(bf16x8, w); }
; DI void store_R(const float* Cs, int cb, int nc, bfu* dst, long ld, float scale, const float* rs = nullptr) {
;   const int cpr = nc >> 3;
;   for (int u = TID(); u < 128 * cpr; u += NT) {
;     int row = u / cpr, c8 = (u % cpr) * 8; float v[8]; ldrow8(Cs, row, cb + c8, v);
;     float s = rs ? scale * rs[row] : scale;
;     for (int j = 0; j < 8; ++j) v[j] *= s;
;     st8(dst + row * ld + c8, pack8f(v));
;   }
; }
; DI void epi_in1(const Params& p, float* Cs, int m0, int n0) {
;     ...
;     bfu* dst = (bfu*)(G + (isq ? L1_RQ : L1_RK)) + ((long)(bg * 8 + head) * T + t0) * 256;
;     const float sc = isq ? 1.f : 0.0625f;
;     store_R(Cs, 0, 64, dst + par * 64, 256, sc); store_R(Cs, 64, 64, dst + 128 + par * 64, 256, sc);
.LBB0_1390:
	v_ashrrev_i32_e32 v5, 31, v3
	v_lshrrev_b32_e32 v5, 29, v5
	v_add_u32_e32 v6, 0x100, v3
	v_add_u32_e32 v5, v3, v5
	v_cmp_lt_i32_e32 vcc, s87, v3
	v_mov_b32_e32 v3, v6
	v_ashrrev_i32_e32 v14, 3, v5
	v_mad_u64_u32 v[10:11], s[24:25], v14, s60, v[2:3]
	s_waitcnt lgkmcnt(0)
	ds_read_b128 v[6:9], v10
	ds_read_b128 v[10:13], v10 offset:16
	v_lshlrev_b32_e32 v5, 6, v14
	v_ashrrev_i32_e32 v15, 31, v14
	v_sub_u32_e32 v16, v4, v5
	v_lshlrev_b64 v[14:15], 9, v[14:15]
	v_lshl_add_u64 v[14:15], s[12:13], 0, v[14:15]
	v_ashrrev_i32_e32 v17, 31, v16
	s_waitcnt lgkmcnt(0)
	v_pk_mul_f32 v[6:7], v[0:1], v[6:7]
	v_pk_mul_f32 v[8:9], v[0:1], v[8:9]
	v_pk_mul_f32 v[10:11], v[0:1], v[10:11]
	v_pk_mul_f32 v[12:13], v[0:1], v[12:13]
	s_or_b64 s[20:21], vcc, s[20:21]
	v_add_u32_e32 v2, 0x2000, v2
	v_add_u32_e32 v4, 0x800, v4
	v_lshl_add_u64 v[14:15], v[16:17], 1, v[14:15]
	v_cvt_pk_bf16_f32 v6, v6, v7
	v_cvt_pk_bf16_f32 v7, v8, v9
	v_cvt_pk_bf16_f32 v8, v10, v11
	v_cvt_pk_bf16_f32 v9, v12, v13
	global_store_dwordx4 v[14:15], v[6:9], off
	s_andn2_b64 exec, exec, s[20:21]
	s_cbranch_execnz .LBB0_1390

; DI int TID() { int t = threadIdx.x; asm volatile("" : "+v"(t)); return t; }
; DI bf16x8 pack8f(const float* v) { u32x4 w = {cvtpk(v[0], v[1]), cvtpk(v[2], v[3]), cvtpk(v[4], v[5]), cvtpk(v[6], v[7])}; return __builtin_bit_cast(bf16x8, w); }
; DI void store_R(const float* Cs, int cb, int nc, bfu* dst, long ld, float scale, const float* rs = nullptr) {
;   const int cpr = nc >> 3;
;   for (int u = TID(); u < 128 * cpr; u += NT) {
;     int row = u / cpr, c8 = (u % cpr) * 8; float v[8]; ldrow8(Cs, row, cb + c8, v);
;     float s = rs ? scale * rs[row] : scale;
;     for (int j = 0; j < 8; ++j) v[j] *= s;
;     st8(dst + row * ld + c8, pack8f(v));
;   }
; }
; DI void epi_in1(const Params& p, float* Cs, int m0, int n0) {
;     ...
;     bfu* dst = (bfu*)(G + (isq ? L1_RQ : L1_RK)) + ((long)(bg * 8 + head) * T + t0) * 256;
;     const float sc = isq ? 1.f : 0.0625f;
;     store_R(Cs, 0, 64, dst + par * 64, 256, sc); store_R(Cs, 64, 64, dst + 128 + par * 64, 256, sc);
.LBB0_1393:
	v_ashrrev_i32_e32 v5, 31, v3
	v_lshrrev_b32_e32 v5, 29, v5
	v_add_u32_e32 v6, 0x100, v3
	v_add_u32_e32 v5, v3, v5
	v_cmp_lt_i32_e32 vcc, s87, v3
	v_mov_b32_e32 v3, v6
	v_ashrrev_i32_e32 v14, 3, v5
	v_mad_u64_u32 v[10:11], s[24:25], v14, s60, v[2:3]
	s_waitcnt lgkmcnt(0)
	ds_read_b128 v[6:9], v10
	ds_read_b128 v[10:13], v10 offset:16
	v_lshlrev_b32_e32 v5, 6, v14
	v_ashrrev_i32_e32 v15, 31, v14
	v_sub_u32_e32 v16, v4, v5
	v_lshlrev_b64 v[14:15], 9, v[14:15]
	v_lshl_add_u64 v[14:15], s[12:13], 0, v[14:15]
	v_ashrrev_i32_e32 v17, 31, v16
	s_waitcnt lgkmcnt(0)
	v_pk_mul_f32 v[6:7], v[0:1], v[6:7]
	v_pk_mul_f32 v[8:9], v[0:1], v[8:9]
	v_pk_mul_f32 v[10:11], v[0:1], v[10:11]
	v_pk_mul_f32 v[12:13], v[0:1], v[12:13]
	s_or_b64 s[20:21], vcc, s[20:21]
	v_add_u32_e32 v2, 0x2000, v2
	v_add_u32_e32 v4, 0x800, v4
	v_lshl_add_u64 v[14:15], v[16:17], 1, v[14:15]
	v_cvt_pk_bf16_f32 v6, v6, v7
	v_cvt_pk_bf16_f32 v7, v8, v9
	v_cvt_pk_bf16_f32 v8, v10, v11
	v_cvt_pk_bf16_f32 v9, v12, v13
	global_store_dwordx4 v[14:15], v[6:9], off offset:256
	s_andn2_b64 exec, exec, s[20:21]
	s_cbranch_execnz .LBB0_1393

;   DI const float* c() const { return (const float*)sp[1]; }
; DI int TID() { int t = threadIdx.x; asm volatile("" : "+v"(t)); return t; }
; DI bf16x8 pack8f(const float* v) { u32x4 w = {cvtpk(v[0], v[1]), cvtpk(v[2], v[3]), cvtpk(v[4], v[5]), cvtpk(v[6], v[7])}; return __builtin_bit_cast(bf16x8, w); }
; DI void store_T(const float* Cs, int cb, int nc, bfu* dst, long ldT, float scale, const float* rs = nullptr) {
;   for (int u = TID(); u < nc * 16; u += NT) {
;     int c = u % nc, rc = (u / nc) * 8; float v[8];
;     for (int j = 0; j < 8; ++j) v[j] = Cs[(rc + j) * CLD + cb + c] * (rs ? scale * rs[rc + j] : scale);
;     st8(dst + c * ldT + rc, pack8f(v));
;   }
; }
; DI void epi_in1(const Params& p, float* Cs, int m0, int n0) {
;     ...
;     if (!isq) {
;       bfu* dT = (bfu*)(G + L1_RKT) + ((long)(bg * 8 + head) * 256) * T + t0;
;       store_T(Cs, 0, 64, dT + (long)(par * 64) * T, T, sc); store_T(Cs, 64, 64, dT + (long)(128 + par * 64) * T, T, sc);
;     }
.LBB0_1397:
	v_ashrrev_i32_e32 v3, 31, v1
	v_lshrrev_b32_e32 v3, 26, v3
	v_add_u32_e32 v3, v1, v3
	v_add_u32_e32 v4, 0x100, v1
	v_ashrrev_i32_e32 v3, 6, v3
	v_cmp_lt_i32_e32 vcc, s87, v1
	v_mov_b32_e32 v1, v4
	v_mad_u64_u32 v[6:7], s[14:15], v3, s18, v[2:3]
	v_lshlrev_b32_e32 v4, 3, v3
	s_waitcnt lgkmcnt(0)
	v_mad_u64_u32 v[8:9], s[14:15], v3, s19, v[0:1]
	v_add_u32_e32 v3, 0x400, v6
	v_add_u32_e32 v12, 0x800, v6
	v_add_u32_e32 v14, 0xc00, v6
	ds_read2_b32 v[10:11], v6 offset1:132
	ds_read2_b32 v[6:7], v3 offset0:8 offset1:140
	ds_read2_b32 v[12:13], v12 offset0:16 offset1:148
	ds_read2_b32 v[14:15], v14 offset0:24 offset1:156
	v_ashrrev_i32_e32 v9, 31, v8
	v_ashrrev_i32_e32 v5, 31, v4
	v_lshl_add_u64 v[8:9], s[2:3], 0, v[8:9]
	v_lshl_add_u64 v[8:9], v[4:5], 1, v[8:9]
	s_waitcnt lgkmcnt(0)
	v_pk_mul_f32 v[4:5], v[10:11], s[76:77] op_sel_hi:[1,0]
	v_pk_mul_f32 v[6:7], v[6:7], s[76:77] op_sel_hi:[1,0]
	v_pk_mul_f32 v[10:11], v[12:13], s[76:77] op_sel_hi:[1,0]
	v_pk_mul_f32 v[12:13], v[14:15], s[76:77] op_sel_hi:[1,0]
	s_or_b64 s[12:13], vcc, s[12:13]
	v_add_u32_e32 v0, 0x120000, v0
	v_add_u32_e32 v2, 0x400, v2
	v_cvt_pk_bf16_f32 v4, v4, v5
	v_cvt_pk_bf16_f32 v5, v6, v7
	v_cvt_pk_bf16_f32 v6, v10, v11
	v_cvt_pk_bf16_f32 v7, v12, v13
	global_store_dwordx4 v[8:9], v[4:7], off
	s_andn2_b64 exec, exec, s[12:13]
	s_cbranch_execnz .LBB0_1397

;   DI const float* c() const { return (const float*)sp[1]; }
; DI int TID() { int t = threadIdx.x; asm volatile("" : "+v"(t)); return t; }
; DI bf16x8 pack8f(const float* v) { u32x4 w = {cvtpk(v[0], v[1]), cvtpk(v[2], v[3]), cvtpk(v[4], v[5]), cvtpk(v[6], v[7])}; return __builtin_bit_cast(bf16x8, w); }
; DI void store_T(const float* Cs, int cb, int nc, bfu* dst, long ldT, float scale, const float* rs = nullptr) {
;   for (int u = TID(); u < nc * 16; u += NT) {
;     int c = u % nc, rc = (u / nc) * 8; float v[8];
;     for (int j = 0; j < 8; ++j) v[j] = Cs[(rc + j) * CLD + cb + c] * (rs ? scale * rs[rc + j] : scale);
;     st8(dst + c * ldT + rc, pack8f(v));
;   }
; }
; DI void epi_in1(const Params& p, float* Cs, int m0, int n0) {
;     ...
;     if (!isq) {
;       bfu* dT = (bfu*)(G + L1_RKT) + ((long)(bg * 8 + head) * 256) * T + t0;
;       store_T(Cs, 0, 64, dT + (long)(par * 64) * T, T, sc); store_T(Cs, 64, 64, dT + (long)(128 + par * 64) * T, T, sc);
;     }
.LBB0_1400:
	v_ashrrev_i32_e32 v3, 31, v1
	v_lshrrev_b32_e32 v3, 26, v3
	v_add_u32_e32 v3, v1, v3
	v_add_u32_e32 v4, 0x100, v1
	v_ashrrev_i32_e32 v3, 6, v3
	v_cmp_lt_i32_e32 vcc, s87, v1
	v_mov_b32_e32 v1, v4
	v_mad_u64_u32 v[6:7], s[14:15], v3, s18, v[2:3]
	v_lshlrev_b32_e32 v4, 3, v3
	s_waitcnt lgkmcnt(0)
	v_mad_u64_u32 v[8:9], s[14:15], v3, s19, v[0:1]
	v_add_u32_e32 v3, 0x400, v6
	v_add_u32_e32 v12, 0x800, v6
	v_add_u32_e32 v14, 0xc00, v6
	ds_read2_b32 v[10:11], v6 offset0:64 offset1:196
	ds_read2_b32 v[6:7], v3 offset0:72 offset1:204
	ds_read2_b32 v[12:13], v12 offset0:80 offset1:212
	ds_read2_b32 v[14:15], v14 offset0:88 offset1:220
	v_ashrrev_i32_e32 v9, 31, v8
	v_ashrrev_i32_e32 v5, 31, v4
	v_lshl_add_u64 v[8:9], s[2:3], 0, v[8:9]
	v_lshl_add_u64 v[8:9], v[4:5], 1, v[8:9]
	s_waitcnt lgkmcnt(0)
	v_pk_mul_f32 v[4:5], v[10:11], s[76:77] op_sel_hi:[1,0]
	v_pk_mul_f32 v[6:7], v[6:7], s[76:77] op_sel_hi:[1,0]
	v_pk_mul_f32 v[10:11], v[12:13], s[76:77] op_sel_hi:[1,0]
	v_pk_mul_f32 v[12:13], v[14:15], s[76:77] op_sel_hi:[1,0]
	s_or_b64 s[12:13], vcc, s[12:13]
	v_add_u32_e32 v0, 0x120000, v0
	v_add_u32_e32 v2, 0x400, v2
	v_cvt_pk_bf16_f32 v4, v4, v5
	v_cvt_pk_bf16_f32 v5, v6, v7
	v_cvt_pk_bf16_f32 v6, v10, v11
	v_cvt_pk_bf16_f32 v7, v12, v13
	global_store_dwordx4 v[8:9], v[4:7], off
	s_andn2_b64 exec, exec, s[12:13]
	s_cbranch_execnz .LBB0_1400
	s_branch .LBB0_1243

;   DI const float* x() const { return (const float*)sp[0]; }
;   DI const float* c() const { return (const float*)sp[1]; }
; __device__ __forceinline__ unsigned xb_ld(unsigned* p)              { return __hip_atomic_load(p, __ATOMIC_RELAXED, __HIP_MEMORY_SCOPE_AGENT); }
; __device__ __forceinline__ void xcd_barrier_complete(unsigned* bar, unsigned x, unsigned& nloc, unsigned& nx) {
;     const unsigned G = gridDim.x * gridDim.y * gridDim.z;
;     unsigned sum, cnt, mine, sp = 0u;
;     for (;;) {
;         sum = 0u; cnt = 0u; mine = 0u;
; #pragma unroll
;         for (unsigned j = 0; j < 16; ++j) { const unsigned c = xb_ld(&bar[XB_XCNT(j)]); sum += c; cnt += (c > 0u) ? 1u : 0u; mine = (j == x) ? c : mine; }
;         if (sum == G) break;
;         __builtin_amdgcn_s_sleep(1);
;         if ((++sp & 255u) == 0u) { if (xb_ld(&bar[XB_TMO])) break; if (sp > XB_SPIN_CAP) { atomicAdd(&bar[XB_TMO], 1u); break; } }
;     }
;     nloc = mine > 0u ? mine : 1u; nx = cnt > 0u ? cnt : 1u;
; }
.LBB0_1407:
	s_waitcnt lgkmcnt(0)
	v_mov_b64_e32 v[0:1], s[2:3]
	v_mov_b64_e32 v[2:3], s[4:5]
	global_load_dword v0, v[0:1], off sc1
	v_readlane_b32 s40, v254, 15
	global_load_dword v1, v[2:3], off sc1
	v_mov_b64_e32 v[2:3], s[6:7]
	global_load_dword v2, v[2:3], off sc1
	s_or_b64 s[90:91], s[90:91], exec
	s_or_b64 s[70:71], s[70:71], exec
	s_waitcnt vmcnt(0) lgkmcnt(0)
	v_add_u32_e32 v4, v1, v0
	v_add_u32_e32 v6, v4, v2
	v_mov_b64_e32 v[4:5], s[8:9]
	global_load_dword v3, v[4:5], off sc1
	v_mov_b64_e32 v[4:5], s[10:11]
	global_load_dword v4, v[4:5], off sc1
	s_waitcnt vmcnt(0) lgkmcnt(0)
	v_add_u32_e32 v6, v6, v3
	v_add_u32_e32 v8, v6, v4
	v_mov_b64_e32 v[6:7], s[12:13]
	global_load_dword v5, v[6:7], off sc1
	v_mov_b64_e32 v[6:7], s[14:15]
	global_load_dword v6, v[6:7], off sc1
	s_waitcnt vmcnt(0) lgkmcnt(0)
	v_add_u32_e32 v8, v8, v5
	v_add_u32_e32 v10, v8, v6
	v_mov_b64_e32 v[8:9], s[16:17]
	global_load_dword v7, v[8:9], off sc1
	v_mov_b64_e32 v[8:9], s[18:19]
	global_load_dword v8, v[8:9], off sc1
	s_waitcnt vmcnt(0) lgkmcnt(0)
	v_add_u32_e32 v10, v10, v7
	v_add_u32_e32 v12, v10, v8
	v_mov_b64_e32 v[10:11], s[20:21]
	global_load_dword v9, v[10:11], off sc1
	v_mov_b64_e32 v[10:11], s[22:23]
	global_load_dword v10, v[10:11], off sc1
	s_waitcnt vmcnt(0) lgkmcnt(0)
	v_add_u32_e32 v12, v12, v9
	v_add_u32_e32 v14, v12, v10
	v_mov_b64_e32 v[12:13], s[24:25]
	global_load_dword v11, v[12:13], off sc1
	v_mov_b64_e32 v[12:13], s[26:27]
	global_load_dword v12, v[12:13], off sc1
	s_waitcnt vmcnt(0) lgkmcnt(0)
	v_add_u32_e32 v14, v14, v11
	v_add_u32_e32 v16, v14, v12
	v_mov_b64_e32 v[14:15], s[28:29]
	global_load_dword v13, v[14:15], off sc1
	v_mov_b64_e32 v[14:15], s[36:37]
	global_load_dword v14, v[14:15], off sc1
	s_waitcnt vmcnt(0) lgkmcnt(0)
	v_add_u32_e32 v16, v16, v13
	v_add_u32_e32 v18, v16, v14
	v_mov_b64_e32 v[16:17], s[38:39]
	global_load_dword v15, v[16:17], off sc1
	s_waitcnt vmcnt(0) lgkmcnt(0)
	v_add_u32_e32 v16, v18, v15
	v_cmp_ne_u32_e32 vcc, s40, v16
	s_and_saveexec_b64 s[92:93], vcc
	s_cbranch_execz .LBB0_1406
	s_and_b32 s40, s62, 0xff
	s_mov_b64 s[94:95], -1
	s_cmp_eq_u32 s40, 0
	s_mov_b64 s[46:47], -1
	s_mov_b64 s[96:97], -1
	s_sleep 1
	s_cbranch_scc1 .LBB0_1410
	s_and_saveexec_b64 s[40:41], s[46:47]
	s_cbranch_execz .LBB0_1405
	s_branch .LBB0_1413
.LBB0_1410:
	v_mov_b64_e32 v[16:17], s[0:1]
	global_load_dword v16, v[16:17], off sc1
	s_mov_b64 s[46:47], 0
	s_waitcnt vmcnt(0) lgkmcnt(0)
	v_cmp_eq_u32_e32 vcc, 0, v16
	s_and_saveexec_b64 s[40:41], vcc
	s_cmp_lt_u32 s62, 0x40001
	s_cselect_b64 s[46:47], -1, 0
	s_xor_b64 s[96:97], exec, -1
	s_and_b64 s[46:47], s[46:47], exec
	s_or_b64 exec, exec, s[40:41]
	s_and_saveexec_b64 s[40:41], s[46:47]
	s_cbranch_execz .LBB0_1405

; __device__ __forceinline__ unsigned xb_ld(unsigned* p)              { return __hip_atomic_load(p, __ATOMIC_RELAXED, __HIP_MEMORY_SCOPE_AGENT); }
; __device__ __forceinline__ void xcd_barrier_complete(unsigned* bar, unsigned x, unsigned& nloc, unsigned& nx) {
;     ...
;         if ((++sp & 255u) == 0u) { if (xb_ld(&bar[XB_TMO])) break; if (sp > XB_SPIN_CAP) { atomicAdd(&bar[XB_TMO], 1u); break; } }
.LBB0_1414:
	s_or_b64 exec, exec, s[54:55]
	s_xor_b64 s[2:3], s[68:69], -1
	s_and_saveexec_b64 s[4:5], s[2:3]
	s_xor_b64 s[2:3], exec, s[4:5]
	s_cbranch_execz .LBB0_1416
	v_mov_b64_e32 v[16:17], s[0:1]
	v_mov_b32_e32 v18, 1
	global_atomic_add v[16:17], v18, off

;   DI const float* x() const { return (const float*)sp[0]; }
; __device__ __forceinline__ unsigned xb_ld(unsigned* p)              { return __hip_atomic_load(p, __ATOMIC_RELAXED, __HIP_MEMORY_SCOPE_AGENT); }
; __device__ __forceinline__ unsigned xb_add(unsigned* p, unsigned v) { return __hip_atomic_fetch_add(p, v, __ATOMIC_RELAXED, __HIP_MEMORY_SCOPE_AGENT); }
; #define XB_SPIN(cond, bar) do { unsigned _sp = 0; while (cond) { __builtin_amdgcn_s_sleep(1); \
;     if ((++_sp & 255u) == 0u) { if (xb_ld(&(bar)[XB_TMO])) break; if (_sp > XB_SPIN_CAP) { atomicAdd(&(bar)[XB_TMO], 1u); break; } } } } while (0)
; __device__ __forceinline__ void xcd_barrier(const XcdBarrier& b) {
;     asm volatile("s_waitcnt vmcnt(0)" ::: "memory");
;     __syncthreads();
;     if (threadIdx.x == 0) {
;         unsigned* bar = b.bar;
;         __builtin_amdgcn_s_waitcnt(0);
;         unsigned nloc = b.st[0], nx = b.st[1];
;         if (nloc == 0u) { xcd_barrier_complete(bar, b.x, nloc, nx); b.st[0] = nloc; b.st[1] = nx; }
;         const unsigned old = xb_add(&bar[XB_XSUB(b.x)], 1u);
;         const unsigned gen = old / nloc;
;         if (old + 1u == (gen + 1u) * nloc) {
;             __builtin_amdgcn_fence(__ATOMIC_RELEASE, "agent");
;             asm volatile("s_waitcnt vmcnt(0)" ::: "memory");
;             const unsigned og = xb_add(&bar[XB_TOP], 1u);
;             const unsigned tg = og / nx;
;             if (og + 1u == (tg + 1u) * nx) xb_add(&bar[XB_TOPGEN], 1u);
;             else XB_SPIN(xb_ld(&bar[XB_TOPGEN]) == tg, bar);
;             __builtin_amdgcn_fence(__ATOMIC_ACQUIRE, "agent");
;             xb_add(&bar[XB_XGEN(b.x)], 1u);
;             asm volatile("s_waitcnt vmcnt(0)" ::: "memory");
;         } else {
;             XB_SPIN(xb_ld(&bar[XB_XGEN(b.x)]) == gen, bar);
;             __builtin_amdgcn_fence(__ATOMIC_ACQUIRE, "agent");
;             asm volatile("s_waitcnt vmcnt(0)" ::: "memory");
;         }
.LBB0_1417:
	s_add_u32 s22, s34, 0xe36d000
	s_addc_u32 s23, s35, 0
	s_lshl_b32 s24, s42, 6
	s_add_i32 s42, s24, 0x500
	s_lshl_b64 s[0:1], s[42:43], 2
	s_add_u32 s0, s22, s0
	s_addc_u32 s1, s23, s1
	v_mov_b64_e32 v[4:5], s[0:1]
	v_mov_b32_e32 v1, 1
	global_atomic_add v3, v[4:5], v1, off sc0
	v_cvt_f32_u32_e32 v1, v2
	v_sub_u32_e32 v4, 0, v2
	v_rcp_iflag_f32_e32 v1, v1
	s_nop 0
	v_mul_f32_e32 v1, 0x4f7ffffe, v1
	v_cvt_u32_f32_e32 v1, v1
	v_mul_lo_u32 v4, v4, v1
	v_mul_hi_u32 v4, v1, v4
	v_add_u32_e32 v1, v1, v4
	s_waitcnt vmcnt(0) lgkmcnt(0)
	v_mul_hi_u32 v1, v3, v1
	v_mul_lo_u32 v4, v1, v2
	v_sub_u32_e32 v4, v3, v4
	v_cmp_ge_u32_e32 vcc, v4, v2
	v_add_u32_e32 v5, 1, v1
	s_nop 0
	v_cndmask_b32_e32 v1, v1, v5, vcc
	v_sub_u32_e32 v5, v4, v2
	v_cndmask_b32_e32 v4, v4, v5, vcc
	v_cmp_ge_u32_e32 vcc, v4, v2
	v_add_u32_e32 v4, 1, v1
	s_nop 0
	v_cndmask_b32_e32 v1, v1, v4, vcc
	v_add_u32_e32 v4, 1, v3
	v_mad_u64_u32 v[2:3], s[0:1], v2, v1, v[2:3]
	v_cmp_ne_u32_e32 vcc, v4, v2
	s_and_saveexec_b64 s[0:1], vcc
	s_xor_b64 s[0:1], exec, s[0:1]
	s_cbranch_execz .LBB0_1430
	s_add_i32 s42, s24, 0x900
	s_lshl_b64 s[2:3], s[42:43], 2
	s_add_u32 s4, s22, s2
	s_addc_u32 s5, s23, s3
	v_mov_b64_e32 v[2:3], s[4:5]
	global_load_dword v0, v[2:3], off sc1
	s_waitcnt vmcnt(0) lgkmcnt(0)
	v_cmp_eq_u32_e32 vcc, v0, v1
	s_and_saveexec_b64 s[2:3], vcc
	s_cbranch_execz .LBB0_1429
	s_add_u32 s6, s34, 0xe36d200
	s_addc_u32 s7, s35, 0
	s_mov_b32 s25, 1
	s_mov_b64 s[8:9], 0
	s_branch .LBB0_1421

;   DI const float* x() const { return (const float*)sp[0]; }
; __device__ __forceinline__ unsigned xb_ld(unsigned* p)              { return __hip_atomic_load(p, __ATOMIC_RELAXED, __HIP_MEMORY_SCOPE_AGENT); }
; #define XB_SPIN(cond, bar) do { unsigned _sp = 0; while (cond) { __builtin_amdgcn_s_sleep(1); \
;     if ((++_sp & 255u) == 0u) { if (xb_ld(&(bar)[XB_TMO])) break; if (_sp > XB_SPIN_CAP) { atomicAdd(&(bar)[XB_TMO], 1u); break; } } } } while (0)
; __device__ __forceinline__ void xcd_barrier(const XcdBarrier& b) {
;     ...
;             XB_SPIN(xb_ld(&bar[XB_XGEN(b.x)]) == gen, bar);
.LBB0_1427:
	s_or_b64 exec, exec, s[8:9]
	s_xor_b64 s[4:5], s[10:11], -1
	s_and_saveexec_b64 s[8:9], s[4:5]
	s_xor_b64 s[8:9], exec, s[8:9]
	s_cbranch_execz .LBB0_1429
	v_mov_b64_e32 v[0:1], s[6:7]
	v_mov_b32_e32 v2, 1
	global_atomic_add v[0:1], v2, off

; __device__ __forceinline__ unsigned xb_ld(unsigned* p)              { return __hip_atomic_load(p, __ATOMIC_RELAXED, __HIP_MEMORY_SCOPE_AGENT); }
; __device__ __forceinline__ unsigned xb_add(unsigned* p, unsigned v) { return __hip_atomic_fetch_add(p, v, __ATOMIC_RELAXED, __HIP_MEMORY_SCOPE_AGENT); }
; #define XB_SPIN(cond, bar) do { unsigned _sp = 0; while (cond) { __builtin_amdgcn_s_sleep(1); \
;     if ((++_sp & 255u) == 0u) { if (xb_ld(&(bar)[XB_TMO])) break; if (_sp > XB_SPIN_CAP) { atomicAdd(&(bar)[XB_TMO], 1u); break; } } } } while (0)
; __device__ __forceinline__ void xcd_barrier(const XcdBarrier& b) {
;     ...
;         if (old + 1u == (gen + 1u) * nloc) {
;             __builtin_amdgcn_fence(__ATOMIC_RELEASE, "agent");
;             asm volatile("s_waitcnt vmcnt(0)" ::: "memory");
;             const unsigned og = xb_add(&bar[XB_TOP], 1u);
;             const unsigned tg = og / nx;
;             if (og + 1u == (tg + 1u) * nx) xb_add(&bar[XB_TOPGEN], 1u);
;             else XB_SPIN(xb_ld(&bar[XB_TOPGEN]) == tg, bar);
.LBB0_1430:
	s_andn2_saveexec_b64 s[0:1], s[0:1]
	s_cbranch_execz .LBB0_1446
	v_mov_b32_e32 v1, s34
	v_add_co_u32_e32 v2, vcc, 0xe370000, v1
	v_mov_b32_e32 v1, s35
	buffer_wbl2 sc1
	s_waitcnt vmcnt(0)
	v_addc_co_u32_e32 v3, vcc, 0, v1, vcc
	v_mov_b32_e32 v1, 1
	global_atomic_add v1, v[2:3], v1, off offset:1024 sc0
	v_cvt_f32_u32_e32 v2, v0
	v_sub_u32_e32 v3, 0, v0
	s_mov_b64 s[4:5], -1
	v_rcp_iflag_f32_e32 v2, v2
	s_nop 0
	v_mul_f32_e32 v2, 0x4f7ffffe, v2
	v_cvt_u32_f32_e32 v2, v2
	v_mul_lo_u32 v3, v3, v2
	v_mul_hi_u32 v3, v2, v3
	v_add_u32_e32 v2, v2, v3
	s_waitcnt vmcnt(0) lgkmcnt(0)
	v_mul_hi_u32 v2, v1, v2
	v_mul_lo_u32 v3, v2, v0
	v_sub_u32_e32 v3, v1, v3
	v_cmp_ge_u32_e32 vcc, v3, v0
	v_add_u32_e32 v4, 1, v2
	s_nop 0
	v_cndmask_b32_e32 v2, v2, v4, vcc
	v_sub_u32_e32 v4, v3, v0
	v_cndmask_b32_e32 v3, v3, v4, vcc
	v_cmp_ge_u32_e32 vcc, v3, v0
	v_add_u32_e32 v3, 1, v2
	s_nop 0
	v_cndmask_b32_e32 v2, v2, v3, vcc
	v_add_u32_e32 v3, 1, v1
	v_mad_u64_u32 v[0:1], s[0:1], v0, v2, v[0:1]
	s_add_u32 s0, s34, 0xe370500
	s_addc_u32 s1, s35, 0
	v_cmp_ne_u32_e32 vcc, v3, v0
	v_mov_b64_e32 v[0:1], s[0:1]
	s_and_saveexec_b64 s[2:3], vcc
	s_cbranch_execz .LBB0_1443
	v_mov_b64_e32 v[0:1], s[0:1]
	global_load_dword v0, v[0:1], off sc1
	s_mov_b64 s[8:9], 0
	s_waitcnt vmcnt(0) lgkmcnt(0)
	v_cmp_eq_u32_e32 vcc, v0, v2
	s_and_saveexec_b64 s[6:7], vcc
	s_cbranch_execz .LBB0_1442
	s_add_u32 s4, s34, 0xe36d200
	s_addc_u32 s5, s35, 0
	s_mov_b32 s20, 1
	s_branch .LBB0_1435

; __device__ __forceinline__ unsigned xb_ld(unsigned* p)              { return __hip_atomic_load(p, __ATOMIC_RELAXED, __HIP_MEMORY_SCOPE_AGENT); }
; #define XB_SPIN(cond, bar) do { unsigned _sp = 0; while (cond) { __builtin_amdgcn_s_sleep(1); \
;     if ((++_sp & 255u) == 0u) { if (xb_ld(&(bar)[XB_TMO])) break; if (_sp > XB_SPIN_CAP) { atomicAdd(&(bar)[XB_TMO], 1u); break; } } } } while (0)
; __device__ __forceinline__ void xcd_barrier(const XcdBarrier& b) {
;     ...
;             else XB_SPIN(xb_ld(&bar[XB_TOPGEN]) == tg, bar);
.LBB0_1437:
	v_mov_b64_e32 v[0:1], s[4:5]
	global_load_dword v0, v[0:1], off sc1
	s_mov_b64 s[16:17], 0
	s_mov_b64 s[14:15], -1
	s_waitcnt vmcnt(0) lgkmcnt(0)
	v_cmp_eq_u32_e32 vcc, 0, v0
	s_and_saveexec_b64 s[18:19], vcc
	s_cmp_lt_u32 s20, 0x40001
	s_cselect_b64 s[16:17], -1, 0
	s_xor_b64 s[14:15], exec, -1
	s_and_b64 s[16:17], s[16:17], exec
	s_or_b64 exec, exec, s[18:19]
	s_and_saveexec_b64 s[18:19], s[16:17]
	s_cbranch_execz .LBB0_1434
.LBB0_1440:
	v_mov_b64_e32 v[0:1], s[0:1]
	global_load_dword v0, v[0:1], off sc1
	s_add_i32 s20, s20, 1
	s_or_b64 s[14:15], s[14:15], exec
	s_waitcnt vmcnt(0) lgkmcnt(0)
	v_cmp_ne_u32_e32 vcc, v0, v2
	s_orn2_b64 s[12:13], vcc, exec
	s_branch .LBB0_1434

;   DI const float* ret_decay() const { return (const float*)sp[15]; }
; DI float logsig(float v) { return fminf(v, 0.f) - log1pf(__expf(-fabsf(v))); }
; template <bool ML>
; DI void scan_block(const Params& p, int sitem, char* smem) {
;     ...
;   bfu* qS = (bfu*)smem; bfu* kS = qS + 64 * LQ; bfu* kTS = kS + 64 * LQ; bfu* vTS = kTS + 128 * LT; float* wsm = (float*)(vTS + 128 * LT);
;   float lg2 = 0.f;
;   if (!ML) lg2 = logsig(p.ret_decay()[dir * 8 + head]) * LOG2E;
;   const bf16x8 ones = {0x3F80, 0x3F80, 0x3F80, 0x3F80, 0x3F80, 0x3F80, 0x3F80, 0x3F80};
;   const bool active = !isden || w == 0;
;   const int r16 = tid >> 4, c16 = (tid & 15) * 8, r8 = tid >> 3, c8 = (tid & 7) * 8;
;   bf16x8 ra[4], rb[4];
;   float bN = 0.f, gsN = 0.f, cmN = 0.f;
;     ...
;   __syncthreads();
;   if (!ML && tid < 64) {
;     wsm[128 + tid] = __builtin_amdgcn_exp2f(lg2 * (dir == 0 ? (float)(tid + 1) : (float)(64 - tid)));
;     wsm[192 + tid] = __builtin_amdgcn_exp2f(lg2 * (dir == 0 ? (float)(63 - tid) : (float)tid));
;     wsm[tid] = __builtin_amdgcn_exp2f(lg2 * (dir == 0 ? (float)tid : -(float)tid));
;     wsm[64 + tid] = __builtin_amdgcn_exp2f(lg2 * (dir == 0 ? -(float)tid : (float)tid));
;     if (tid == 0) wsm[320] = __builtin_amdgcn_exp2f(lg2 * 64.f);
;   }
; template <int layer, int part>
; DI void phase_mix(const Params& p, int cidx, char* smem, int* s_item) {
;     ...
;   while (scanner && item < nscan) {
;     const int sib = layer == 0 ? 3 : 4;
;     const int sitem = (xcd + 8 * (item / sib)) * sib + item % sib;
;     __builtin_amdgcn_s_setprio(3);
.LBB0_1456:
	s_ashr_i32 s0, s4, 31
	s_lshr_b32 s0, s0, 30
	s_add_i32 s0, s4, s0
	s_lshl_b32 s1, s0, 3
	s_and_b32 s0, s0, -4
	s_sub_i32 s9, s4, s0
	v_readlane_b32 s0, v254, 31
	s_andn2_b32 s1, s1, 31
	s_add_i32 s4, s9, s0
	s_add_i32 s6, s4, s1
	s_setprio 3
	v_readlane_b32 s0, v254, 16
	v_readlane_b32 s1, v254, 17
	v_mov_b32_e32 v0, v202
	v_mov_b32_e32 v1, 0x12278
	ds_read_b64 v[2:3], v1
	s_bfe_u32 s10, s4, 0x10002
	s_bfe_u32 s8, s6, 0x30003
	s_lshl_b32 s4, s8, 2
	s_lshl_b32 s11, s10, 5
	s_or_b32 s42, s11, s4
	s_waitcnt lgkmcnt(0)
	v_lshl_add_u64 v[2:3], v[2:3], 0, s[42:43]
	global_load_dword v1, v[2:3], off
	v_cmp_gt_i32_e32 vcc, 64, v0
	s_waitcnt lgkmcnt(0)
	s_barrier
	s_and_saveexec_b64 s[4:5], vcc
	s_cbranch_execz .LBB0_1459
	s_mov_b32 s7, 0xbfb8aa3b
	s_waitcnt vmcnt(0)
	v_mul_f32_e64 v2, |v1|, s7
	v_exp_f32_e32 v4, v2
	s_mov_b32 s7, 0x3f2aaaab
	v_max_f32_e32 v1, v1, v1
	v_min_f32_e32 v1, 0, v1
	v_add_f32_e32 v5, 1.0, v4
	v_cvt_f64_f32_e32 v[2:3], v5
	v_frexp_mant_f32_e32 v6, v5
	v_frexp_exp_i32_f64_e32 v2, v[2:3]
	v_cmp_gt_f32_e32 vcc, s7, v6
	v_add_f32_e32 v10, -1.0, v5
	v_sub_f32_e32 v11, v4, v10
	v_subbrev_co_u32_e32 v2, vcc, 0, v2, vcc
	v_cvt_f32_i32_e32 v3, v2
	v_sub_u32_e32 v2, 0, v2
	v_ldexp_f32 v8, v5, v2
	v_sub_f32_e32 v5, v10, v5
	v_add_f32_e32 v5, 1.0, v5
	v_add_f32_e32 v10, 1.0, v8
	v_add_f32_e32 v5, v11, v5
	v_add_f32_e32 v11, -1.0, v10
	v_ldexp_f32 v2, v5, v2
	v_sub_f32_e32 v11, v8, v11
	v_add_f32_e32 v11, v2, v11
	v_add_f32_e32 v9, -1.0, v8
	v_add_f32_e32 v12, v10, v11
	v_add_f32_e32 v5, 1.0, v9
	v_rcp_f32_e32 v13, v12
	v_sub_f32_e32 v5, v8, v5
	v_add_f32_e32 v2, v2, v5
	v_add_f32_e32 v5, v9, v2
	v_mul_f32_e32 v8, v5, v13
	v_mul_f32_e32 v14, v12, v8
	v_sub_f32_e32 v10, v12, v10
	v_sub_f32_e32 v10, v11, v10
	v_fma_f32 v11, v8, v12, -v14
	v_fmac_f32_e32 v11, v8, v10
	v_add_f32_e32 v15, v14, v11
	v_sub_f32_e32 v16, v5, v15
	v_sub_f32_e32 v9, v5, v9
	v_sub_f32_e32 v5, v5, v16
	v_sub_f32_e32 v14, v15, v14
	v_sub_f32_e32 v2, v2, v9
	v_sub_f32_e32 v5, v5, v15
	v_sub_f32_e32 v11, v14, v11
	v_add_f32_e32 v2, v2, v5
	v_add_f32_e32 v2, v11, v2
	v_add_f32_e32 v5, v16, v2
	v_mul_f32_e32 v9, v13, v5
	v_mul_f32_e32 v14, v12, v9
	v_add_f32_e32 v11, v8, v9
	v_fma_f32 v12, v9, v12, -v14
	v_sub_f32_e32 v8, v11, v8
	v_fmac_f32_e32 v12, v9, v10
	v_sub_f32_e32 v8, v9, v8
	v_add_f32_e32 v9, v14, v12
	v_sub_f32_e32 v10, v5, v9
	v_sub_f32_e32 v14, v9, v14
	v_sub_f32_e32 v12, v14, v12
	v_sub_f32_e32 v14, v16, v5
	v_sub_f32_e32 v5, v5, v10
	v_add_f32_e32 v2, v2, v14
	v_sub_f32_e32 v5, v5, v9
	v_add_f32_e32 v2, v2, v5
	v_add_f32_e32 v2, v12, v2
	v_add_f32_e32 v2, v10, v2
	v_mul_f32_e32 v2, v13, v2
	v_add_f32_e32 v2, v8, v2
	v_add_f32_e32 v5, v11, v2
	v_mul_f32_e32 v9, v5, v5
	v_mov_b32_e32 v12, 0x3ecc95a3
	v_fmamk_f32 v12, v9, 0x3e9b6dac, v12
	v_mul_f32_e32 v10, v5, v9
	v_fmaak_f32 v9, v9, v12, 0x3f2aaada
	v_ldexp_f32 v8, v5, 1
	v_mul_f32_e32 v9, v10, v9
	v_add_f32_e32 v10, v8, v9
	v_sub_f32_e32 v5, v5, v11
	v_mul_f32_e32 v6, 0x3f317218, v3
	s_mov_b32 s7, 0x3f317218
	v_sub_f32_e32 v2, v2, v5
	v_sub_f32_e32 v5, v10, v8
	v_fma_f32 v7, v3, s7, -v6
	v_ldexp_f32 v2, v2, 1
	v_sub_f32_e32 v5, v9, v5
	v_fmac_f32_e32 v7, 0xb102e308, v3
	v_add_f32_e32 v2, v2, v5
	v_add_f32_e32 v3, v6, v7
	v_add_f32_e32 v5, v10, v2
	v_add_f32_e32 v8, v3, v5
	v_sub_f32_e32 v6, v3, v6
	v_sub_f32_e32 v6, v7, v6
	v_sub_f32_e32 v7, v5, v10
	v_sub_f32_e32 v9, v8, v3
	v_sub_f32_e32 v2, v2, v7
	v_sub_f32_e32 v5, v5, v9
	v_sub_f32_e32 v9, v8, v9
	v_add_f32_e32 v7, v6, v2
	v_sub_f32_e32 v3, v3, v9
	v_add_f32_e32 v3, v5, v3
	v_sub_f32_e32 v9, v7, v6
	v_add_f32_e32 v3, v7, v3
	v_sub_f32_e32 v7, v7, v9
	v_add_f32_e32 v5, v8, v3
	v_sub_f32_e32 v2, v2, v9
	v_sub_f32_e32 v6, v6, v7
	v_add_f32_e32 v2, v2, v6
	v_sub_f32_e32 v6, v5, v8
	v_sub_f32_e32 v3, v3, v6
	v_add_f32_e32 v2, v2, v3
	s_mov_b32 s7, 0x7f800000
	v_add_f32_e32 v2, v5, v2
	v_cmp_neq_f32_e32 vcc, s7, v4
	v_mov_b32_e32 v3, 0x7f800000
	s_mov_b32 s7, 0x33800000
	v_cndmask_b32_e32 v2, v3, v2, vcc
	v_cmp_ngt_f32_e32 vcc, -1.0, v4
	v_mov_b32_e32 v3, 0x7fc00000
	v_cvt_f32_i32_e32 v5, v0
	v_cndmask_b32_e32 v2, v3, v2, vcc
	v_cmp_neq_f32_e32 vcc, -1.0, v4
	v_mov_b32_e32 v3, 0xff800000
	s_cmp_eq_u32 s10, 0
	v_cndmask_b32_e32 v2, v3, v2, vcc
	v_cmp_lt_f32_e64 vcc, |v4|, s7
	v_sub_u32_e32 v3, 64, v0
	v_cvt_f32_u32_e32 v3, v3
	v_cndmask_b32_e32 v2, v2, v4, vcc
	v_sub_f32_e32 v1, v1, v2
	v_add_u32_e32 v2, 1, v0
	v_sub_u32_e32 v4, 63, v0
	v_cvt_f32_i32_e32 v2, v2
	v_cvt_f32_u32_e32 v4, v4
	s_cselect_b64 vcc, -1, 0
	v_mul_f32_e32 v1, 0x3fb8aa3b, v1
	v_cndmask_b32_e32 v2, v3, v2, vcc
	v_cndmask_b32_e32 v3, v5, v4, vcc
	v_mul_f32_e32 v2, v2, v1
	v_mul_f32_e32 v3, v3, v1
	v_cndmask_b32_e64 v4, -v5, v5, vcc
	v_cndmask_b32_e64 v5, v5, -v5, vcc
	v_exp_f32_e32 v2, v2
	v_exp_f32_e32 v3, v3
	v_mul_f32_e32 v4, v4, v1
	v_mul_f32_e32 v5, v5, v1
	v_exp_f32_e32 v4, v4
	v_exp_f32_e32 v5, v5
	v_lshl_add_u32 v6, v0, 2, v214
	v_cmp_eq_u32_e32 vcc, 0, v0
	ds_write2st64_b32 v6, v2, v3 offset0:2 offset1:3
	ds_write2st64_b32 v6, v4, v5 offset1:1
	s_and_b64 exec, exec, vcc
	s_cbranch_execz .LBB0_1459
	v_mul_f32_e32 v1, 0x42800000, v1
	v_exp_f32_e32 v1, v1
	ds_write_b32 v209, v1
;   DI const float* ret_decay() const { return (const float*)sp[15]; }
; template <bool ML>
; DI void scan_block(const Params& p, int sitem, char* smem) {
;   constexpr int DKS = ML ? 128 : 256, LQ = 136, LT = 72;
;   char* G = OPQ(p.ws + WS_G);
;   const int tid = TID(), lane = tid & 63, w = tid >> 6, l32 = lane & 31, hi = lane >> 5;
;   int half = 0, dvg = 0, dir, head, bg; bool isden = false;
;   if (ML) { const int which = sitem % 3, rest = sitem / 3; dir = rest & 1; head = (rest >> 1) & 7; bg = rest >> 4; isden = which == 2; dvg = isden ? 0 : which; }
;   else { half = sitem & 1; dvg = (sitem >> 1) & 1; const int rest = sitem >> 2; dir = rest & 1; head = (rest >> 1) & 7; bg = rest >> 4; }
;   const long hb = (long)(bg * 8 + head);
;   const bfu* q = (const bfu*)(G + (ML ? L0_MQ : L1_RQ)) + hb * T * DKS + half * 128;
;   const bfu* k = (const bfu*)(G + (ML ? L0_MK : L1_RK)) + hb * T * DKS + half * 128;
;   const bfu* kT = (const bfu*)(G + (ML ? L0_MKT : L1_RKT)) + (hb * DKS + half * 128) * T;
;   const bfu* vT = (const bfu*)(G + (ML ? L0_MVT : L1_RVT)) + (hb * 256 + dvg * 128) * T;
;   const float* gbp = (const float*)(G + L0_SM + SM_GI) + ((long)(dir * GB + bg) * 8 + head) * T;
;   const float* gsp = (const float*)(G + L0_SM + SM_GF) + ((long)(dir * GB + bg) * 8 + head) * T;
;   const float* gcp = (const float*)(G + L0_SM + SM_GC) + ((long)(dir * GB + bg) * 8 + head) * T;
;   float* dnp = (float*)(G + L0_SM + SM_DN) + ((long)(dir * GB + bg) * 8 + head) * T;
;   bfu* outp = ML ? (bfu*)(G + L0_HN) + ((long)dir * MG + (long)bg * T) * 2048 + head * 256 + dvg * 128 + w * 32
;                  : (bfu*)(G + L1_R) + ((long)(dir * 2 + half) * MG + (long)bg * T) * 2048 + head * 256 + dvg * 128 + w * 32;
;   bfu* qS = (bfu*)smem; bfu* kS = qS + 64 * LQ; bfu* kTS = kS + 64 * LQ; bfu* vTS = kTS + 128 * LT; float* wsm = (float*)(vTS + 128 * LT);
;   float lg2 = 0.f;
;   if (!ML) lg2 = logsig(p.ret_decay()[dir * 8 + head]) * LOG2E;
;   const bf16x8 ones = {0x3F80, 0x3F80, 0x3F80, 0x3F80, 0x3F80, 0x3F80, 0x3F80, 0x3F80};
;   const bool active = !isden || w == 0;
;   const int r16 = tid >> 4, c16 = (tid & 15) * 8, r8 = tid >> 3, c8 = (tid & 7) * 8;
;   bf16x8 ra[4], rb[4];
;   float bN = 0.f, gsN = 0.f, cmN = 0.f;
;     ...
;   __syncthreads();
;   if (!ML && tid < 64) {
;     wsm[128 + tid] = __builtin_amdgcn_exp2f(lg2 * (dir == 0 ? (float)(tid + 1) : (float)(64 - tid)));
.LBB0_1459:
	s_or_b64 exec, exec, s[4:5]
	s_ashr_i32 s13, s6, 6
	s_lshl_b32 s4, s13, 3
	s_or_b32 s4, s4, s8
	s_and_b32 s12, s9, 1
	s_ashr_i32 s5, s4, 31
	s_mul_i32 s7, s4, 0x120000
	s_mul_hi_i32 s6, s4, 0x120000
	s_add_u32 s7, s0, s7
	s_addc_u32 s14, s1, s6
	s_lshl_b32 s15, s12, 7
	s_lshl_b32 s6, s12, 8
	s_add_u32 s6, s7, s6
	s_addc_u32 s7, s14, 0
	s_lshl_b64 s[4:5], s[4:5], 8
	s_or_b32 s14, s4, s15
	s_mul_hi_u32 s15, s14, 0x1200
	s_mulk_i32 s5, 0x1200
	s_add_i32 s15, s15, s5
	s_mulk_i32 s14, 0x1200
	s_add_u32 s14, s0, s14
	s_addc_u32 s15, s1, s15
	s_add_u32 s54, s14, 0x2400000
	s_addc_u32 s55, s15, 0
	s_lshl_b32 s9, s9, 6
	s_and_b32 s9, s9, 0x80
	s_or_b32 s4, s4, s9
	s_mul_hi_u32 s14, s4, 0x1200
	s_add_i32 s14, s14, s5
	s_mulk_i32 s4, 0x1200
	s_add_u32 s4, s0, s4
	s_addc_u32 s5, s1, s14
	s_add_u32 s68, s4, 0x3600000
	s_addc_u32 s69, s5, 0
	s_lshl_b32 s4, s10, 1
	s_or_b32 s4, s4, s12
	s_mulk_i32 s4, 0x1200
	s_mul_hi_i32 s5, s13, 0x900
	s_mulk_i32 s13, 0x900
	s_add_u32 s4, s13, s4
	s_addc_u32 s5, s5, 0
	s_lshl_b64 s[4:5], s[4:5], 12
	s_add_u32 s0, s0, s4
	s_addc_u32 s1, s1, s5
	s_lshl_b32 s4, s8, 9
	s_add_u32 s0, s0, s4
	s_addc_u32 s1, s1, 0
	s_lshl_b32 s4, s9, 1
	s_add_u32 s8, s0, s4
	s_waitcnt vmcnt(0)
	v_bfe_u32 v1, v0, 5, 1
	s_addc_u32 s9, s1, 0
	v_and_b32_e32 v194, 31, v0
	s_cmp_eq_u32 s10, 0
	v_lshlrev_b32_e32 v2, 2, v1
	v_cmp_le_u32_e32 vcc, v2, v194
	s_cselect_b64 s[4:5], -1, 0
	s_cmp_lg_u32 s10, 0
	v_cndmask_b32_e64 v3, 0, 1, vcc
	v_cmp_ge_u32_e32 vcc, v2, v194
	s_cselect_b64 s[0:1], -1, 0
	s_and_b64 s[12:13], s[4:5], exec
	v_ashrrev_i32_e32 v195, 4, v0
	v_cndmask_b32_e64 v4, 0, 1, vcc
	s_cselect_b32 s12, 0, 0xc0
	v_lshlrev_b32_e32 v38, 4, v0
	v_cndmask_b32_e64 v3, v4, v3, s[4:5]
	v_add_u32_e32 v4, s12, v195
	v_and_b32_e32 v184, 0xf0, v38
	v_lshl_add_u64 v[160:161], s[6:7], 0, v[184:185]
	s_mov_b64 s[6:7], 0x1200000
	v_ashrrev_i32_e32 v5, 31, v4
	v_lshl_add_u64 v[162:163], v[160:161], 0, s[6:7]
	v_lshlrev_b64 v[28:29], 9, v[4:5]
	s_mov_b64 s[6:7], 0x2000
	v_lshl_add_u64 v[12:13], v[28:29], 0, s[6:7]
	s_mov_b64 s[6:7], 0x4000
	v_lshl_add_u64 v[4:5], v[160:161], 0, v[28:29]
	v_lshl_add_u64 v[8:9], v[162:163], 0, v[28:29]
	v_lshl_add_u64 v[20:21], v[28:29], 0, s[6:7]
	v_lshl_add_u64 v[28:29], v[28:29], 0, s[80:81]
	v_lshl_add_u64 v[14:15], v[160:161], 0, v[12:13]
	v_lshl_add_u64 v[16:17], v[162:163], 0, v[12:13]
	v_lshl_add_u64 v[22:23], v[160:161], 0, v[20:21]
	v_lshl_add_u64 v[24:25], v[162:163], 0, v[20:21]
	v_lshl_add_u64 v[30:31], v[160:161], 0, v[28:29]
	v_lshl_add_u64 v[32:33], v[162:163], 0, v[28:29]
	global_load_dwordx4 v[4:7], v[4:5], off
	s_nop 0
	global_load_dwordx4 v[8:11], v[8:9], off
	s_nop 0
	global_load_dwordx4 v[12:15], v[14:15], off
	s_nop 0
	global_load_dwordx4 v[16:19], v[16:17], off
	s_nop 0
	global_load_dwordx4 v[20:23], v[22:23], off
	s_nop 0
	global_load_dwordx4 v[24:27], v[24:25], off
	s_nop 0
	global_load_dwordx4 v[28:31], v[30:31], off
	s_nop 0
	global_load_dwordx4 v[32:35], v[32:33], off
	v_ashrrev_i32_e32 v46, 1, v0
	v_and_b32_e32 v36, 0xffffffe0, v46
	v_ashrrev_i32_e32 v37, 31, v36
	v_mad_u64_u32 v[164:165], s[6:7], v195, s60, v[184:185]
	v_lshl_add_u64 v[36:37], v[36:37], 1, s[8:9]
	s_mov_b64 s[6:7], 0xc600000
	s_cselect_b32 s8, 0, 0x180
	v_lshl_add_u64 v[166:167], v[36:37], 0, s[6:7]
	s_add_u32 s6, s54, s8
	v_and_b32_e32 v184, 0x70, v38
	s_addc_u32 s7, s55, 0
	v_lshl_add_u64 v[36:37], s[6:7], 0, v[184:185]
	s_add_u32 s6, s68, s8
	v_ashrrev_i32_e32 v47, 3, v0
	s_addc_u32 s7, s69, 0
	v_add_u32_e32 v48, 32, v47
	v_lshl_add_u64 v[42:43], s[6:7], 0, v[184:185]
	v_mad_i64_i32 v[38:39], s[8:9], v47, s75, v[36:37]
	v_mad_i64_i32 v[40:41], s[8:9], v48, s75, v[36:37]
	v_mad_i64_i32 v[44:45], s[6:7], v47, s75, v[42:43]
	v_bfi_b32 v0, s39, v46, v0
	v_lshlrev_b32_e32 v165, 3, v1
	v_mul_lo_u32 v0, v0, s50
	v_or_b32_e32 v198, v0, v165
	v_and_b32_e32 v0, 1, v3
	v_cmp_lt_u32_e32 vcc, v2, v194
	v_lshl_or_b32 v201, v1, 5, v214
	s_mul_i32 s46, s10, 0x2200
	s_xor_b32 s47, s11, 32
	s_mov_b32 s42, 0
	v_lshl_or_b32 v197, v194, 2, v214
	s_waitcnt vmcnt(0) lgkmcnt(0)
	ds_write_b128 v164, v[4:7]
	ds_write_b128 v164, v[8:11] offset:17408
	ds_write_b128 v164, v[12:15] offset:4352
	ds_write_b128 v164, v[16:19] offset:21760
	ds_write_b128 v164, v[20:23] offset:8704
	ds_write_b128 v164, v[24:27] offset:26112
	ds_write_b128 v164, v[28:31] offset:13056
	ds_write_b128 v164, v[32:35] offset:30464
	v_mad_i64_i32 v[4:5], s[6:7], v48, s75, v[42:43]
	v_add_u32_e32 v8, 64, v47
	global_load_dwordx4 v[128:131], v[38:39], off
	global_load_dwordx4 v[132:135], v[44:45], off
	global_load_dwordx4 v[136:139], v[40:41], off
	global_load_dwordx4 v[140:143], v[4:5], off
	v_mad_i64_i32 v[4:5], s[6:7], v8, s75, v[36:37]
	v_add_u32_e32 v9, 0x60, v47
	v_mad_i64_i32 v[6:7], s[6:7], v8, s75, v[42:43]
	global_load_dwordx4 v[144:147], v[4:5], off
	global_load_dwordx4 v[148:151], v[6:7], off
	v_mad_i64_i32 v[4:5], s[6:7], v9, s75, v[36:37]
	v_mad_i64_i32 v[6:7], s[6:7], v9, s75, v[42:43]
	global_load_dwordx4 v[152:155], v[4:5], off
	global_load_dwordx4 v[156:159], v[6:7], off
	v_mul_u32_u24_e32 v4, 0x88, v194
	v_lshlrev_b32_e32 v4, 1, v4
	v_lshlrev_b32_e32 v11, 4, v1
	s_movk_i32 s6, 0x2200
	v_add3_u32 v200, v4, v11, s6
	v_mad_u64_u32 v[168:169], s[6:7], v47, s50, v[184:185]
	v_cmp_eq_u32_e64 s[6:7], 1, v0
	v_or_b32_e32 v0, 1, v2
	v_cndmask_b32_e64 v1, 0, 1, vcc
	v_cmp_ge_u32_e32 vcc, v0, v194
	v_lshl_or_b32 v225, v0, 2, v214
	v_or_b32_e32 v0, 2, v2
	v_cndmask_b32_e64 v3, 0, 1, vcc
	v_cndmask_b32_e64 v1, v3, v1, s[4:5]
	v_and_b32_e32 v1, 1, v1
	v_cmp_le_u32_e32 vcc, v0, v194
	v_cmp_eq_u32_e64 s[8:9], 1, v1
	v_lshl_or_b32 v226, v0, 2, v214
	v_cndmask_b32_e64 v1, 0, 1, vcc
; DI int crow(int r, int hi) { return (r & 3) + 8 * (r >> 2) + 4 * hi; }
; template <bool ML>
; DI void scan_block(const Params& p, int sitem, char* smem) {
;     ...
;   f32x16 C[4];
; #pragma unroll
;   for (int i = 0; i < 4; ++i)
; #pragma unroll
;     for (int r = 0; r < 16; ++r) C[i][r] = 0.f;
;   float mst = 0.f;
;     ...
;         const float sBx = tbx ? sB1 : sB0;
; #pragma unroll
;         for (int r = 0; r < 16; ++r) {
;           const int sl = crow(r, hi);
;           const bool valid = dir == 0 ? sl <= l32 : sl >= l32;
;           float w0, wx;
;           if (ML) { w0 = __expf(sB0 + wsm[64 + sl]); wx = __expf(sBx + wsm[64 + sbx * 32 + sl]); }
;           else { w0 = sB0 * wsm[64 + sl]; wx = sBx * wsm[64 + sbx * 32 + sl]; }
;           sd0[r] = valid ? sd0[r] * w0 : 0.f; sx[r] *= wx;
;         }
	v_cmp_ge_u32_e32 vcc, v0, v194
	v_or_b32_e32 v0, 3, v2
	v_or_b32_e32 v169, 0x11800, v11
	v_cndmask_b32_e64 v3, 0, 1, vcc
	v_cndmask_b32_e64 v1, v3, v1, s[4:5]
	v_and_b32_e32 v1, 1, v1
	v_cmp_le_u32_e32 vcc, v0, v194
	v_lshl_or_b32 v224, s10, 7, v169
	v_cmp_eq_u32_e64 s[10:11], 1, v1
	v_cndmask_b32_e64 v1, 0, 1, vcc
	v_cmp_ge_u32_e32 vcc, v0, v194
	v_lshl_or_b32 v227, v0, 2, v214
	v_or_b32_e32 v0, 8, v2
	v_cndmask_b32_e64 v3, 0, 1, vcc
	v_cndmask_b32_e64 v1, v3, v1, s[4:5]
	v_and_b32_e32 v1, 1, v1
	v_cmp_le_u32_e32 vcc, v0, v194
	v_cmp_eq_u32_e64 s[12:13], 1, v1
	v_lshl_or_b32 v228, v0, 2, v214
	v_cndmask_b32_e64 v1, 0, 1, vcc
	v_cmp_ge_u32_e32 vcc, v0, v194
	v_or_b32_e32 v0, 9, v2
	v_lshl_or_b32 v229, v0, 2, v214
	v_cndmask_b32_e64 v3, 0, 1, vcc
	v_cndmask_b32_e64 v1, v3, v1, s[4:5]
	v_and_b32_e32 v1, 1, v1
	v_cmp_le_u32_e32 vcc, v0, v194
	v_cmp_eq_u32_e64 s[14:15], 1, v1
	v_or_b32_e32 v196, v4, v165
	v_cndmask_b32_e64 v1, 0, 1, vcc
	v_cmp_ge_u32_e32 vcc, v0, v194
	v_or_b32_e32 v0, 10, v2
	v_lshl_or_b32 v230, v0, 2, v214
	v_cndmask_b32_e64 v3, 0, 1, vcc
	v_cndmask_b32_e64 v1, v3, v1, s[4:5]
	v_and_b32_e32 v1, 1, v1
	v_cmp_le_u32_e32 vcc, v0, v194
	v_cmp_eq_u32_e64 s[16:17], 1, v1
	v_or_b32_e32 v10, 32, v194
	v_cndmask_b32_e64 v1, 0, 1, vcc
	v_cmp_ge_u32_e32 vcc, v0, v194
	v_or_b32_e32 v0, 11, v2
	v_lshl_or_b32 v231, v0, 2, v214
	v_cndmask_b32_e64 v3, 0, 1, vcc
	v_cndmask_b32_e64 v1, v3, v1, s[4:5]
	v_and_b32_e32 v1, 1, v1
	v_cmp_le_u32_e32 vcc, v0, v194
	v_cmp_eq_u32_e64 s[18:19], 1, v1
	v_mul_u32_u24_e32 v12, 0x90, v194
	v_cndmask_b32_e64 v1, 0, 1, vcc
	v_cmp_ge_u32_e32 vcc, v0, v194
	v_or_b32_e32 v0, 16, v2
	v_lshl_or_b32 v232, v0, 2, v214
	v_cndmask_b32_e64 v3, 0, 1, vcc
	v_cndmask_b32_e64 v1, v3, v1, s[4:5]
	v_and_b32_e32 v1, 1, v1
	v_cmp_le_u32_e32 vcc, v0, v194
	v_cmp_eq_u32_e64 s[20:21], 1, v1
	v_lshl_or_b32 v199, v10, 2, v214
	v_cndmask_b32_e64 v1, 0, 1, vcc
	v_cmp_ge_u32_e32 vcc, v0, v194
	v_or_b32_e32 v0, 17, v2
	v_lshl_or_b32 v233, v0, 2, v214
	v_cndmask_b32_e64 v3, 0, 1, vcc
	v_cndmask_b32_e64 v1, v3, v1, s[4:5]
	v_and_b32_e32 v1, 1, v1
	v_cmp_le_u32_e32 vcc, v0, v194
	v_cmp_eq_u32_e64 s[22:23], 1, v1
	s_mulk_i32 s47, 0x110
	v_cndmask_b32_e64 v1, 0, 1, vcc
	v_cmp_ge_u32_e32 vcc, v0, v194
	v_or_b32_e32 v0, 18, v2
	v_lshl_or_b32 v234, v0, 2, v214
	v_cndmask_b32_e64 v3, 0, 1, vcc
	v_cndmask_b32_e64 v1, v3, v1, s[4:5]
	v_and_b32_e32 v1, 1, v1
	v_cmp_le_u32_e32 vcc, v0, v194
	v_cmp_eq_u32_e64 s[24:25], 1, v1
	v_add_u32_e32 v240, v11, v12
	v_cndmask_b32_e64 v1, 0, 1, vcc
	v_cmp_ge_u32_e32 vcc, v0, v194
	v_or_b32_e32 v0, 19, v2
	v_lshl_or_b32 v235, v0, 2, v214
	v_cndmask_b32_e64 v3, 0, 1, vcc
	v_cndmask_b32_e64 v1, v3, v1, s[4:5]
	v_and_b32_e32 v1, 1, v1
	v_cmp_le_u32_e32 vcc, v0, v194
	v_cmp_eq_u32_e64 s[26:27], 1, v1
	s_nop 0
	v_cndmask_b32_e64 v1, 0, 1, vcc
	v_cmp_ge_u32_e32 vcc, v0, v194
	v_or_b32_e32 v0, 24, v2
	v_lshl_or_b32 v236, v0, 2, v214
	v_cndmask_b32_e64 v3, 0, 1, vcc
	v_cndmask_b32_e64 v1, v3, v1, s[4:5]
	v_and_b32_e32 v1, 1, v1
	v_cmp_le_u32_e32 vcc, v0, v194
	v_cmp_eq_u32_e64 s[28:29], 1, v1
	s_nop 0
	v_cndmask_b32_e64 v1, 0, 1, vcc
	v_cmp_ge_u32_e32 vcc, v0, v194
	v_or_b32_e32 v0, 25, v2
	v_lshl_or_b32 v237, v0, 2, v214
	v_cndmask_b32_e64 v3, 0, 1, vcc
	v_cndmask_b32_e64 v1, v3, v1, s[4:5]
	v_and_b32_e32 v1, 1, v1
	v_cmp_le_u32_e32 vcc, v0, v194
	v_cmp_eq_u32_e64 s[30:31], 1, v1
	s_nop 0
	v_cndmask_b32_e64 v1, 0, 1, vcc
	v_cmp_ge_u32_e32 vcc, v0, v194
	v_or_b32_e32 v0, 26, v2
	v_lshl_or_b32 v238, v0, 2, v214
	v_cndmask_b32_e64 v3, 0, 1, vcc
	v_cndmask_b32_e64 v1, v3, v1, s[4:5]
	v_and_b32_e32 v1, 1, v1
	v_cmp_le_u32_e32 vcc, v0, v194
	v_cmp_eq_u32_e64 s[34:35], 1, v1
	s_nop 0
	v_cndmask_b32_e64 v1, 0, 1, vcc
	v_cmp_ge_u32_e32 vcc, v0, v194
	v_or_b32_e32 v0, 27, v2
	v_lshl_or_b32 v239, v0, 2, v214
	v_cndmask_b32_e64 v3, 0, 1, vcc
	v_cndmask_b32_e64 v1, v3, v1, s[4:5]
	v_and_b32_e32 v1, 1, v1
	v_cmp_le_u32_e32 vcc, v0, v194
	v_cmp_eq_u32_e64 s[36:37], 1, v1
	s_nop 0
	v_cndmask_b32_e64 v1, 0, 1, vcc
	v_cmp_ge_u32_e32 vcc, v0, v194
	s_nop 1
	v_cndmask_b32_e64 v3, 0, 1, vcc
	v_cndmask_b32_e64 v1, v3, v1, s[4:5]
	v_and_b32_e32 v1, 1, v1
	v_cmp_eq_u32_e64 s[38:39], 1, v1
	v_mov_b64_e32 v[0:1], s[54:55]
	v_mad_i64_i32 v[4:5], s[40:41], v47, s75, v[0:1]
	v_lshl_add_u64 v[170:171], v[4:5], 0, v[184:185]
	v_mov_b64_e32 v[4:5], s[68:69]
	v_mad_i64_i32 v[6:7], s[40:41], v47, s75, v[4:5]
	v_lshl_add_u64 v[172:173], v[6:7], 0, v[184:185]
	v_mad_i64_i32 v[6:7], s[40:41], v48, s75, v[0:1]
	v_lshl_add_u64 v[174:175], v[6:7], 0, v[184:185]
	v_mad_i64_i32 v[6:7], s[40:41], v48, s75, v[4:5]
	v_lshl_add_u64 v[176:177], v[6:7], 0, v[184:185]
	v_mad_i64_i32 v[6:7], s[40:41], v8, s75, v[0:1]
	v_mad_i64_i32 v[0:1], s[40:41], v9, s75, v[0:1]
	v_lshl_add_u64 v[182:183], v[0:1], 0, v[184:185]
	v_mad_i64_i32 v[0:1], s[40:41], v9, s75, v[4:5]
	v_lshl_add_u64 v[178:179], v[6:7], 0, v[184:185]
	v_mad_i64_i32 v[6:7], s[40:41], v8, s75, v[4:5]
	v_lshl_add_u64 v[188:189], v[0:1], 0, v[184:185]
	v_mul_u32_u24_e32 v1, 0x90, v10
	v_mov_b32_e32 v0, 0
	v_lshl_add_u64 v[180:181], v[6:7], 0, v[184:185]
	v_lshlrev_b32_e32 v184, 1, v2
	v_add_u32_e32 v241, v11, v1
	v_mov_b32_e32 v1, v0
	v_mov_b32_e32 v2, v0
	v_mov_b32_e32 v3, v0
	v_mov_b32_e32 v4, v0
	v_mov_b32_e32 v5, v0
	v_mov_b32_e32 v6, v0
	v_mov_b32_e32 v7, v0
	v_mov_b32_e32 v8, v0
	v_mov_b32_e32 v9, v0
	v_mov_b32_e32 v10, v0
	v_mov_b32_e32 v11, v0
	v_mov_b32_e32 v12, v0
	v_mov_b32_e32 v13, v0
	v_mov_b32_e32 v14, v0
	v_mov_b32_e32 v15, v0
	v_mov_b32_e32 v16, v0
	v_mov_b32_e32 v17, v0
	v_mov_b32_e32 v18, v0
	v_mov_b32_e32 v19, v0
	v_mov_b32_e32 v20, v0
	v_mov_b32_e32 v21, v0
	v_mov_b32_e32 v22, v0
	v_mov_b32_e32 v23, v0
	v_mov_b32_e32 v24, v0
	v_mov_b32_e32 v25, v0
	v_mov_b32_e32 v26, v0
	v_mov_b32_e32 v27, v0
	v_mov_b32_e32 v28, v0
	v_mov_b32_e32 v29, v0
	v_mov_b32_e32 v30, v0
	v_mov_b32_e32 v31, v0
	v_mov_b32_e32 v32, v0
	v_mov_b32_e32 v33, v0
	v_mov_b32_e32 v34, v0
	v_mov_b32_e32 v35, v0
	v_mov_b32_e32 v36, v0
	v_mov_b32_e32 v37, v0
	v_mov_b32_e32 v38, v0
	v_mov_b32_e32 v39, v0
	v_mov_b32_e32 v40, v0
	v_mov_b32_e32 v41, v0
	v_mov_b32_e32 v42, v0
	v_mov_b32_e32 v43, v0
	v_mov_b32_e32 v44, v0
	v_mov_b32_e32 v45, v0
	v_mov_b32_e32 v46, v0
	v_mov_b32_e32 v47, v0
	v_mov_b32_e32 v48, v0
	v_mov_b32_e32 v49, v0
	v_mov_b32_e32 v50, v0
	v_mov_b32_e32 v51, v0
	v_mov_b32_e32 v52, v0
	v_mov_b32_e32 v53, v0
	v_mov_b32_e32 v54, v0
	v_mov_b32_e32 v55, v0
	v_mov_b32_e32 v56, v0
	v_mov_b32_e32 v57, v0
	v_mov_b32_e32 v58, v0
	v_mov_b32_e32 v59, v0
	v_mov_b32_e32 v60, v0
	v_mov_b32_e32 v61, v0
	v_mov_b32_e32 v62, v0
	v_mov_b32_e32 v63, v0
	s_branch .LBB0_1461

; #define SC_STORE_QK()                                                                                     \
;   _Pragma("unroll") for (int i = 0; i < 4; ++i) { st8(qS + (r16 + 16 * i) * LQ + c16, ra[i]); st8(kS + (r16 + 16 * i) * LQ + c16, rb[i]); }
; #define SC_STORE_T()                                                                                      \
;   _Pragma("unroll") for (int i = 0; i < 4; ++i) { st8(kTS + (r8 + 32 * i) * LT + c8, ra[i]); st8(vTS + (r8 + 32 * i) * LT + c8, rb[i]); }
; template <bool ML>
; DI void scan_block(const Params& p, int sitem, char* smem) {
;     ...
;   __syncthreads();
;   if (!ML && tid < 64) {
;     wsm[128 + tid] = __builtin_amdgcn_exp2f(lg2 * (dir == 0 ? (float)(tid + 1) : (float)(64 - tid)));
;     wsm[192 + tid] = __builtin_amdgcn_exp2f(lg2 * (dir == 0 ? (float)(63 - tid) : (float)tid));
;     wsm[tid] = __builtin_amdgcn_exp2f(lg2 * (dir == 0 ? (float)tid : -(float)tid));
;     wsm[64 + tid] = __builtin_amdgcn_exp2f(lg2 * (dir == 0 ? -(float)tid : (float)tid));
;     if (tid == 0) wsm[320] = __builtin_amdgcn_exp2f(lg2 * 64.f);
;   }
;   SC_LOAD_QK(SC_CHUNK(0) * 64);
;   SC_STORE_QK();
;   SC_LOAD_T(SC_CHUNK(0) * 64);
;   f32x16 C[4];
; #pragma unroll
;   for (int i = 0; i < 4; ++i)
; #pragma unroll
;     for (int r = 0; r < 16; ++r) C[i][r] = 0.f;
;   float mst = 0.f;
;   for (int ci = 0; ci < 36; ++ci) {
;     const int p0 = SC_CHUNK(ci) * 64;
;     __syncthreads();
;     SC_STORE_T();
;     const float b = bN, gs = gsN, cm = cmN;
;     if (ci + 1 < 36) SC_LOAD_QK(SC_CHUNK(ci + 1) * 64);
;     if (ML && w == 0) {
;       const float bend = __uint_as_float(dir == 0 ? __builtin_amdgcn_readlane(__float_as_uint(b), 63) : __builtin_amdgcn_readlane(__float_as_uint(b), 0));
.LBB0_1461:
	s_add_i32 s62, s42, 1
	s_cmp_lg_u32 s42, 35
	s_cselect_b64 s[54:55], -1, 0
	s_cmp_eq_u32 s42, 35
	v_add_u32_e32 v64, 0x1200, v168
	s_waitcnt lgkmcnt(0)
	s_barrier
	s_waitcnt vmcnt(0)
	ds_write_b128 v168, v[128:131] offset:34816
	ds_write_b128 v168, v[132:135] offset:53248
	ds_write_b128 v168, v[136:139] offset:39424
	ds_write_b128 v168, v[140:143] offset:57856
	ds_write_b128 v168, v[144:147] offset:44032
	ds_write_b128 v168, v[148:151] offset:62464
	ds_write_b128 v168, v[152:155] offset:48640
	ds_write_b128 v64, v[156:159] offset:62464
	s_cbranch_scc1 .LBB0_1463
	s_cmp_gt_u32 s42, 2
	s_cselect_b32 s40, 38, 2
	s_sub_i32 s63, s40, s42
	s_and_b64 s[40:41], s[4:5], exec
	s_cselect_b32 s40, s62, s63
	v_lshl_add_u32 v64, s40, 6, v195
	v_ashrrev_i32_e32 v65, 31, v64
	v_lshlrev_b64 v[66:67], 9, v[64:65]
	v_lshl_add_u64 v[68:69], v[160:161], 0, v[66:67]
	v_lshl_add_u64 v[66:67], v[162:163], 0, v[66:67]
	global_load_dwordx4 v[128:131], v[68:69], off
	global_load_dwordx4 v[132:135], v[66:67], off
	v_add_u32_e32 v66, 16, v64
	v_ashrrev_i32_e32 v67, 31, v66
	v_lshlrev_b64 v[66:67], 9, v[66:67]
	v_lshl_add_u64 v[68:69], v[160:161], 0, v[66:67]
	v_lshl_add_u64 v[66:67], v[162:163], 0, v[66:67]
	global_load_dwordx4 v[136:139], v[68:69], off
	global_load_dwordx4 v[140:143], v[66:67], off
	v_add_u32_e32 v66, 32, v64
	v_ashrrev_i32_e32 v67, 31, v66
	v_add_u32_e32 v64, 48, v64
	v_lshlrev_b64 v[66:67], 9, v[66:67]
	v_ashrrev_i32_e32 v65, 31, v64
	v_lshl_add_u64 v[68:69], v[160:161], 0, v[66:67]
	v_lshl_add_u64 v[66:67], v[162:163], 0, v[66:67]
	v_lshlrev_b64 v[64:65], 9, v[64:65]
	global_load_dwordx4 v[144:147], v[68:69], off
	global_load_dwordx4 v[148:151], v[66:67], off
	v_lshl_add_u64 v[66:67], v[160:161], 0, v[64:65]
	v_lshl_add_u64 v[64:65], v[162:163], 0, v[64:65]
	global_load_dwordx4 v[152:155], v[66:67], off
	global_load_dwordx4 v[156:159], v[64:65], off

; #define MFMA(a, b, c) __builtin_amdgcn_mfma_f32_32x32x16_bf16((a), (b), (c), 0, 0, 0)
; DI int crow(int r, int hi) { return (r & 3) + 8 * (r >> 2) + 4 * hi; }
; DI unsigned cvtpk(float lo, float hi) { f32x2_t v = {lo, hi}; bf16x2_t b = __builtin_convertvector(v, bf16x2_t); return __builtin_bit_cast(unsigned, b); }
; #define SC_STORE_QK()                                                                                     \
;   _Pragma("unroll") for (int i = 0; i < 4; ++i) { st8(qS + (r16 + 16 * i) * LQ + c16, ra[i]); st8(kS + (r16 + 16 * i) * LQ + c16, rb[i]); }
; template <bool ML>
; DI void scan_block(const Params& p, int sitem, char* smem) {
;     ...
;         for (int r = 0; r < 16; ++r) {
;           const int sl = crow(r, hi);
;           const bool valid = dir == 0 ? sl <= l32 : sl >= l32;
;           float w1;
;           if (ML) w1 = __expf(sB1 + wsm[96 + sl]);
;           else w1 = sB1 * wsm[96 + sl];
;           sa[r] = valid ? (sa[r] + sb_[r]) * w1 : 0.f;
;         }
; #pragma unroll
;         for (int s2 = 0; s2 < 2; ++s2) out1 = MFMA(ld44(v1 + 16 * s2), packacc(sa, s2), out1);
;       }
;       if (!isden) {
;         bfu* orow0 = outp + (long)(p0 + l32) * 2048; bfu* orow1 = orow0 + 32 * 2048;
; #pragma unroll
;         for (int rg = 0; rg < 4; ++rg) {
;           u32x2 va = {cvtpk(out0[4 * rg], out0[4 * rg + 1]), cvtpk(out0[4 * rg + 2], out0[4 * rg + 3])};
;           u32x2 vb = {cvtpk(out1[4 * rg], out1[4 * rg + 1]), cvtpk(out1[4 * rg + 2], out1[4 * rg + 3])};
;           *reinterpret_cast<u32x2*>(orow0 + 8 * rg + 4 * hi) = va;
;           *reinterpret_cast<u32x2*>(orow1 + 8 * rg + 4 * hi) = vb;
;         }
;       } else if (hi == 0) {
;         dnp[p0 + l32] = fmaxf(fabsf(out0[0]), wsm[256 + l32]);
;         dnp[p0 + 32 + l32] = fmaxf(fabsf(out1[0]), wsm[288 + l32]);
;       }
;     }
;     __syncthreads();
;     if (ci + 1 < 36) { SC_STORE_QK(); SC_LOAD_T(SC_CHUNK(ci + 1) * 64); }
.LBB0_1535:
	s_or_b64 exec, exec, s[40:41]
	ds_read2_b64 v[110:113], v192 offset0:8 offset1:10
	ds_read2_b64 v[114:117], v192 offset0:12 offset1:14
	v_cvt_pk_bf16_f32 v118, v193, v190
	v_cvt_pk_bf16_f32 v119, v97, v96
	v_cvt_pk_bf16_f32 v120, v99, v98
	v_cvt_pk_bf16_f32 v121, v101, v100
	s_cmp_gt_u32 s42, 3
	s_cselect_b32 s40, 39, 3
	s_waitcnt lgkmcnt(0)
	v_mfma_f32_32x32x16_bf16 v[64:79], v[110:113], v[118:121], v[64:79]
	v_cvt_pk_bf16_f32 v96, v103, v102
	v_cvt_pk_bf16_f32 v97, v105, v104
	v_cvt_pk_bf16_f32 v98, v107, v106
	v_cvt_pk_bf16_f32 v99, v109, v108
	s_sub_i32 s63, s40, s42
	s_and_b64 s[40:41], s[4:5], exec
	s_cselect_b32 s40, s42, s63
	v_mfma_f32_32x32x16_bf16 v[64:79], v[114:117], v[96:99], v[64:79]
	v_lshl_or_b32 v96, s40, 6, v194
	v_ashrrev_i32_e32 v97, 31, v96
	v_lshlrev_b64 v[96:97], 12, v[96:97]
	v_lshl_add_u64 v[96:97], v[166:167], 0, v[96:97]
	v_lshl_add_u64 v[96:97], v[96:97], 0, v[184:185]
	s_mov_b64 s[40:41], 0x20000
	v_cvt_pk_bf16_f32 v80, v80, v81
	s_nop 4
	v_cvt_pk_bf16_f32 v64, v64, v65
	v_cvt_pk_bf16_f32 v65, v66, v67
	v_add_co_u32_e32 v66, vcc, s64, v96
	v_cvt_pk_bf16_f32 v81, v82, v83
	s_nop 0
	v_addc_co_u32_e32 v67, vcc, 0, v97, vcc
	global_store_dwordx2 v[66:67], v[64:65], off
	v_cvt_pk_bf16_f32 v64, v84, v85
	v_cvt_pk_bf16_f32 v65, v86, v87
	v_lshl_add_u64 v[98:99], v[96:97], 0, s[40:41]
	global_store_dwordx2 v[96:97], v[80:81], off
	v_cvt_pk_bf16_f32 v66, v68, v69
	v_cvt_pk_bf16_f32 v67, v70, v71
	global_store_dwordx2 v[96:97], v[64:65], off offset:16
	global_store_dwordx2 v[98:99], v[66:67], off offset:16
	v_cvt_pk_bf16_f32 v64, v88, v89
	v_cvt_pk_bf16_f32 v65, v90, v91
	v_cvt_pk_bf16_f32 v66, v72, v73
	v_cvt_pk_bf16_f32 v67, v74, v75
	global_store_dwordx2 v[96:97], v[64:65], off offset:32
	global_store_dwordx2 v[98:99], v[66:67], off offset:32
	v_cvt_pk_bf16_f32 v64, v92, v93
	v_cvt_pk_bf16_f32 v65, v94, v95
	s_andn2_b64 vcc, exec, s[54:55]
	v_cvt_pk_bf16_f32 v66, v76, v77
	v_cvt_pk_bf16_f32 v67, v78, v79
	global_store_dwordx2 v[96:97], v[64:65], off offset:48
	global_store_dwordx2 v[98:99], v[66:67], off offset:48
	s_waitcnt lgkmcnt(0)
	s_barrier
	s_cbranch_vccnz .LBB0_1460
	s_cmp_gt_u32 s42, 2
	s_cselect_b32 s40, 38, 2
	s_sub_i32 s42, s40, s42
	s_and_b64 s[40:41], s[4:5], exec
	s_cselect_b32 s40, s62, s42
	s_lshl_b32 s42, s40, 6
	s_lshl_b64 s[40:41], s[42:43], 1
	s_waitcnt vmcnt(0)
	ds_write_b128 v164, v[128:131]
	ds_write_b128 v164, v[132:135] offset:17408
	ds_write_b128 v164, v[136:139] offset:4352
	ds_write_b128 v164, v[140:143] offset:21760
	ds_write_b128 v164, v[144:147] offset:8704
	ds_write_b128 v164, v[148:151] offset:26112
	ds_write_b128 v164, v[152:155] offset:13056
	ds_write_b128 v164, v[156:159] offset:30464
	v_lshl_add_u64 v[64:65], v[170:171], 0, s[40:41]
	v_lshl_add_u64 v[66:67], v[172:173], 0, s[40:41]
	global_load_dwordx4 v[128:131], v[64:65], off
	global_load_dwordx4 v[132:135], v[66:67], off
	v_lshl_add_u64 v[64:65], v[174:175], 0, s[40:41]
	v_lshl_add_u64 v[66:67], v[176:177], 0, s[40:41]
	global_load_dwordx4 v[136:139], v[64:65], off
	global_load_dwordx4 v[140:143], v[66:67], off
	v_lshl_add_u64 v[64:65], v[178:179], 0, s[40:41]
	v_lshl_add_u64 v[66:67], v[180:181], 0, s[40:41]
	global_load_dwordx4 v[144:147], v[64:65], off
	global_load_dwordx4 v[148:151], v[66:67], off
	v_lshl_add_u64 v[64:65], v[182:183], 0, s[40:41]
	v_lshl_add_u64 v[66:67], v[188:189], 0, s[40:41]
	global_load_dwordx4 v[152:155], v[64:65], off
	global_load_dwordx4 v[156:159], v[66:67], off
	s_branch .LBB0_1460

; DI int TID() { int t = threadIdx.x; asm volatile("" : "+v"(t)); return t; }
; #define ATT_LOADK(key0)                                                                                  \
;   do {                                                                                                   \
;     _Pragma("unroll") for (int i = 0; i < KCH; ++i) { int c = tid + NT * i; kr[i] = ld8(Kp + (long)((key0) + c / CPR) * DK + (c % CPR) * 8); } \
;   } while (0)
; #define ATT_LOADV(key0)                                                                                  \
;   do {                                                                                                   \
;     _Pragma("unroll") for (int i = 0; i < VCH; ++i) { int c = tid + NT * i; vr[i] = ld8(Vtp + (long)(c / VPR) * T + (key0) + (c % VPR) * 8); }  \
;   } while (0)
; template <int DK, int KT>
; DI void attn_item(const bfu* __restrict__ Qp, const bfu* __restrict__ Kp, const bfu* __restrict__ Vtp, int nkeys, bfu* __restrict__ Op, int ldo, char* smem) {
;   constexpr int LK = DK + 8, LV = KT + 8, NKS = DK / 16, CPR = DK / 8, KCH = KT * CPR / NT, VPR = KT / 8, VCH = 128 * VPR / NT, NBK = KT / 32;
;   bfu* Ks = (bfu*)smem; bfu* Vs = Ks + KT * LK;
;   const int tid = TID(), lane = tid & 63, w = tid >> 6, l32 = lane & 31, hi = lane >> 5;
;   bf16x8 qf[NKS];
;   {
;     const bfu* qrow = Qp + (long)(w * 32 + l32) * DK + hi * 8;
; #pragma unroll
;     for (int ks = 0; ks < NKS; ++ks) qf[ks] = ld8(qrow + ks * 16);
;   }
;   f32x16 o[4];
; #pragma unroll
;   for (int d = 0; d < 4; ++d)
; #pragma unroll
;     for (int r = 0; r < 16; ++r) o[d][r] = 0.f;
;   float m = -1e30f, lsum = 0.f;
;   bf16x8 kr[KCH], vr[VCH];
;     ...
;   ATT_LOADK(0); ATT_LOADV(0);
; template <int layer, int part>
; DI void phase_mix(const Params& p, int cidx, char* smem, int* s_item) {
;     ...
;       const int pl = a >> 4, t0 = CTX + (a & 15) * 128;
;       const int pair = pl * 8 + xcd, bg = pair >> 4, h = pair & 15;
;       attn_item<192, 64>((const bfu*)(G + L1_Q) + ((long)(bg * 16 + h) * T + t0) * 192, (const bfu*)(G + L1_K) + (long)(bg * 16 + h) * T * 192,
;                      (const bfu*)(G + L1_VT) + (long)(bg * 16 + h) * 128 * T, T, (bfu*)(G + L1_OA) + ((long)bg * T + t0) * 2048 + h * 128, 2048, smem);
.LBB0_1544:
	s_lshl_b32 s1, s4, 7
	s_add_i32 s0, s4, -16
	s_and_b32 s1, s1, 0x780
	s_add_i32 s7, s1, 0x100
	s_lshr_b32 s1, s0, 1
	s_and_b32 s4, s1, 8
	s_ashr_i32 s16, s0, 5
	s_or_b32 s6, s4, s33
	s_lshl_b32 s5, s16, 4
	s_or_b32 s0, s6, s5
	s_mul_i32 s17, s0, 0x900
	s_mul_hi_i32 s1, s0, 0x900
	s_add_u32 s17, s17, s7
	s_addc_u32 s1, s1, 0
	s_mulk_i32 s1, 0x180
	s_mul_hi_u32 s18, s17, 0x180
	s_add_i32 s1, s18, s1
	s_mulk_i32 s17, 0x180
	s_add_u32 s18, s8, s17
	v_mov_b32_e32 v18, v202
	s_addc_u32 s19, s9, s1
	s_mul_i32 s17, s0, 0xd8000
	v_ashrrev_i32_e32 v0, 1, v18
	v_bfe_u32 v2, v18, 5, 1
	s_waitcnt vmcnt(0)
	v_bfi_b32 v168, s39, v0, v18
	v_mov_b64_e32 v[0:1], s[18:19]
	v_mad_i64_i32 v[0:1], s[18:19], v168, s74, v[0:1]
	v_lshlrev_b32_e32 v184, 3, v2
	v_lshlrev_b32_e32 v2, 4, v2
	v_mov_b32_e32 v3, v185
	s_add_u32 s20, s10, s17
	v_lshl_add_u64 v[0:1], v[0:1], 0, v[2:3]
	s_mov_b32 s17, 0x2aaaaaab
	global_load_dwordx4 v[140:143], v[0:1], off
	global_load_dwordx4 v[136:139], v[0:1], off offset:32
	global_load_dwordx4 v[132:135], v[0:1], off offset:64
	global_load_dwordx4 v[128:131], v[0:1], off offset:96
	global_load_dwordx4 v[124:127], v[0:1], off offset:128
	global_load_dwordx4 v[120:123], v[0:1], off offset:160
	global_load_dwordx4 v[116:119], v[0:1], off offset:192
	global_load_dwordx4 v[112:115], v[0:1], off offset:224
	global_load_dwordx4 v[108:111], v[0:1], off offset:256
	global_load_dwordx4 v[104:107], v[0:1], off offset:288
	global_load_dwordx4 v[100:103], v[0:1], off offset:320
	global_load_dwordx4 v[96:99], v[0:1], off offset:352
	v_mul_hi_i32 v0, v18, s17
	v_add_u32_e32 v22, 0x100, v18
	v_lshrrev_b32_e32 v1, 31, v0
	v_ashrrev_i32_e32 v0, 2, v0
	v_mul_hi_i32 v8, v22, s17
	v_add_u32_e32 v27, v0, v1
	v_lshrrev_b32_e32 v9, 31, v8
	v_ashrrev_i32_e32 v8, 2, v8
	v_mul_lo_u32 v3, v27, 24
	v_add_u32_e32 v28, v8, v9
	s_mul_hi_i32 s1, s0, 0xd8000
	v_sub_u32_e32 v3, v18, v3
	v_mul_lo_u32 v10, v28, 24
	s_addc_u32 s21, s11, s1
	v_lshlrev_b32_e32 v6, 3, v3
	v_sub_u32_e32 v29, v22, v10
	v_mov_b64_e32 v[0:1], s[20:21]
	v_ashrrev_i32_e32 v7, 31, v6
	v_lshlrev_b32_e32 v10, 3, v29
	v_mad_i64_i32 v[4:5], s[18:19], v27, s74, v[0:1]
	v_lshlrev_b64 v[6:7], 1, v[6:7]
	v_ashrrev_i32_e32 v11, 31, v10
	v_lshl_add_u64 v[4:5], v[4:5], 0, v[6:7]
	v_mad_i64_i32 v[8:9], s[18:19], v28, s74, v[0:1]
	v_lshlrev_b64 v[10:11], 1, v[10:11]
	v_add_u32_e32 v24, 0x200, v18
	v_add_u32_e32 v25, 0x300, v18
	v_lshl_add_u64 v[8:9], v[8:9], 0, v[10:11]
	global_load_dwordx4 v[144:147], v[4:5], off
	global_load_dwordx4 v[148:151], v[8:9], off
	v_mul_hi_i32 v4, v24, s17
	v_mul_hi_i32 v12, v25, s17
	v_lshrrev_b32_e32 v5, 31, v4
	v_ashrrev_i32_e32 v4, 2, v4
	v_lshrrev_b32_e32 v13, 31, v12
	v_ashrrev_i32_e32 v12, 2, v12
	v_add_u32_e32 v30, v4, v5
	v_add_u32_e32 v32, v12, v13
	v_mul_lo_u32 v8, v30, 24
	v_mul_lo_u32 v14, v32, 24
	v_sub_u32_e32 v31, v24, v8
	v_sub_u32_e32 v33, v25, v14
	v_lshlrev_b32_e32 v8, 3, v31
	v_lshlrev_b32_e32 v14, 3, v33
	v_ashrrev_i32_e32 v9, 31, v8
	v_ashrrev_i32_e32 v15, 31, v14
	v_mad_i64_i32 v[4:5], s[18:19], v30, s74, v[0:1]
	v_lshlrev_b64 v[8:9], 1, v[8:9]
	v_mad_i64_i32 v[12:13], s[18:19], v32, s74, v[0:1]
	v_lshlrev_b64 v[14:15], 1, v[14:15]
	v_lshl_add_u64 v[4:5], v[4:5], 0, v[8:9]
	v_lshl_add_u64 v[12:13], v[12:13], 0, v[14:15]
	global_load_dwordx4 v[152:155], v[4:5], off
	global_load_dwordx4 v[156:159], v[12:13], off
	v_add_u32_e32 v12, 0x400, v18
	v_add_u32_e32 v16, 0x500, v18
	v_mul_hi_i32 v4, v12, s17
	v_mul_hi_i32 v17, v16, s17
	v_lshrrev_b32_e32 v5, 31, v4
	v_ashrrev_i32_e32 v4, 2, v4
	v_lshrrev_b32_e32 v19, 31, v17
	v_ashrrev_i32_e32 v17, 2, v17
	v_add_u32_e32 v34, v4, v5
	v_add_u32_e32 v36, v17, v19
	v_mul_lo_u32 v13, v34, 24
	v_mul_lo_u32 v17, v36, 24
	v_sub_u32_e32 v35, v12, v13
	v_sub_u32_e32 v37, v16, v17
	v_lshlrev_b32_e32 v12, 3, v35
	v_lshlrev_b32_e32 v16, 3, v37
	v_ashrrev_i32_e32 v13, 31, v12
	v_ashrrev_i32_e32 v17, 31, v16
	v_mad_i64_i32 v[4:5], s[18:19], v34, s74, v[0:1]
	v_lshlrev_b64 v[12:13], 1, v[12:13]
	v_mad_i64_i32 v[0:1], s[18:19], v36, s74, v[0:1]
	v_lshlrev_b64 v[16:17], 1, v[16:17]
	v_lshl_add_u64 v[4:5], v[4:5], 0, v[12:13]
	v_lshl_add_u64 v[0:1], v[0:1], 0, v[16:17]
	global_load_dwordx4 v[160:163], v[4:5], off
	global_load_dwordx4 v[164:167], v[0:1], off
	v_ashrrev_i32_e32 v0, 31, v18
	v_lshrrev_b32_e32 v0, 29, v0
	v_ashrrev_i32_e32 v20, 31, v22
	v_add_u32_e32 v19, v18, v0
	v_lshrrev_b32_e32 v20, 29, v20
	s_mul_hi_i32 s1, s0, 0x90000
	s_mul_i32 s0, s0, 0x90000
	v_ashrrev_i32_e32 v38, 3, v19
	v_and_b32_e32 v19, -8, v19
	v_add_u32_e32 v23, v22, v20
	s_add_u32 s0, s12, s0
	v_sub_u32_e32 v39, v18, v19
	v_ashrrev_i32_e32 v40, 3, v23
	v_and_b32_e32 v23, -8, v23
	s_addc_u32 s1, s13, s1
	v_and_b32_e32 v26, 31, v18
	v_lshlrev_b32_e32 v18, 3, v39
	v_sub_u32_e32 v41, v22, v23
	v_mov_b64_e32 v[0:1], s[0:1]
	v_ashrrev_i32_e32 v19, 31, v18
	v_lshlrev_b32_e32 v22, 3, v41
	v_mad_i64_i32 v[4:5], s[0:1], v38, s75, v[0:1]
	v_lshlrev_b64 v[18:19], 1, v[18:19]
	v_ashrrev_i32_e32 v23, 31, v22
	v_lshl_add_u64 v[4:5], v[4:5], 0, v[18:19]
	v_mad_i64_i32 v[20:21], s[0:1], v40, s75, v[0:1]
	v_lshlrev_b64 v[22:23], 1, v[22:23]
	v_lshl_add_u64 v[20:21], v[20:21], 0, v[22:23]
	global_load_dwordx4 v[64:67], v[4:5], off
	global_load_dwordx4 v[68:71], v[20:21], off
	v_ashrrev_i32_e32 v4, 31, v24
	v_lshrrev_b32_e32 v4, 29, v4
	v_add_u32_e32 v20, v24, v4
	v_ashrrev_i32_e32 v42, 3, v20
	v_and_b32_e32 v20, -8, v20
	v_sub_u32_e32 v43, v24, v20
	v_ashrrev_i32_e32 v24, 31, v25
	v_lshrrev_b32_e32 v24, 29, v24
	v_add_u32_e32 v24, v25, v24
	v_ashrrev_i32_e32 v44, 3, v24
	v_and_b32_e32 v24, -8, v24
	v_lshlrev_b32_e32 v20, 3, v43
	v_sub_u32_e32 v45, v25, v24
;   DI const float* c() const { return (const float*)sp[1]; }
; #define ATT_LOADK(key0)                                                                                  \
;   do {                                                                                                   \
;     _Pragma("unroll") for (int i = 0; i < KCH; ++i) { int c = tid + NT * i; kr[i] = ld8(Kp + (long)((key0) + c / CPR) * DK + (c % CPR) * 8); } \
;   } while (0)
; #define ATT_LOADV(key0)                                                                                  \
;   do {                                                                                                   \
;     _Pragma("unroll") for (int i = 0; i < VCH; ++i) { int c = tid + NT * i; vr[i] = ld8(Vtp + (long)(c / VPR) * T + (key0) + (c % VPR) * 8); }  \
;   } while (0)
; template <int DK, int KT>
; DI void attn_item(const bfu* __restrict__ Qp, const bfu* __restrict__ Kp, const bfu* __restrict__ Vtp, int nkeys, bfu* __restrict__ Op, int ldo, char* smem) {
;     ...
;   f32x16 o[4];
; #pragma unroll
;   for (int d = 0; d < 4; ++d)
; #pragma unroll
;     for (int r = 0; r < 16; ++r) o[d][r] = 0.f;
;   float m = -1e30f, lsum = 0.f;
;   bf16x8 kr[KCH], vr[VCH];
;     ...
;   ATT_LOADK(0); ATT_LOADV(0);
;   const int NTL = nkeys / KT;
;   for (int j = 0; j < NTL; ++j) {
;     __syncthreads();
; #pragma unroll
;     for (int i = 0; i < KCH; ++i) { int c = tid + NT * i; st8(Ks + (c / CPR) * LK + (c % CPR) * 8, kr[i]); }
; #pragma unroll
;     for (int i = 0; i < VCH; ++i) { int c = tid + NT * i; st8(Vs + (c / VPR) * LV + (c % VPR) * 8, vr[i]); }
;     __syncthreads();
	v_ashrrev_i32_e32 v21, 31, v20
	v_lshlrev_b32_e32 v24, 3, v45
	v_mad_i64_i32 v[4:5], s[0:1], v42, s75, v[0:1]
	v_lshlrev_b64 v[20:21], 1, v[20:21]
	v_ashrrev_i32_e32 v25, 31, v24
	v_lshl_add_u64 v[4:5], v[4:5], 0, v[20:21]
	v_mad_i64_i32 v[0:1], s[0:1], v44, s75, v[0:1]
	v_lshlrev_b64 v[24:25], 1, v[24:25]
	v_lshl_add_u64 v[0:1], v[0:1], 0, v[24:25]
	global_load_dwordx4 v[72:75], v[4:5], off
	global_load_dwordx4 v[76:79], v[0:1], off
	s_movk_i32 s0, 0x190
	v_mad_u32_u24 v197, v26, s0, v2
	v_mul_lo_u32 v46, v27, s0
	v_mul_lo_u32 v48, v28, s0
	v_mul_lo_u32 v49, v30, s0
	v_mul_lo_u32 v50, v32, s0
	v_mul_lo_u32 v51, v34, s0
	v_mul_lo_u32 v52, v36, s0
	s_or_b32 s0, s33, s5
	v_and_b32_e32 v1, 64, v203
	s_or_b32 s4, s0, s4
	v_xor_b32_e32 v0, 32, v203
	v_add_u32_e32 v1, 64, v1
	s_mul_i32 s0, s4, 0x90000
	v_cmp_lt_i32_e32 vcc, v0, v1
	s_mul_hi_i32 s1, s4, 0x90000
	s_add_u32 s0, s0, 0xa200080
	v_cndmask_b32_e32 v0, v203, v0, vcc
	s_addc_u32 s1, s1, 0
	v_lshlrev_b32_e32 v195, 2, v0
	v_mov_b64_e32 v[0:1], s[0:1]
	v_lshlrev_b32_e32 v47, 4, v3
	v_mad_i64_i32 v[2:3], s[0:1], v44, s75, v[0:1]
	v_lshl_add_u64 v[170:171], v[2:3], 0, v[24:25]
	v_mad_i64_i32 v[2:3], s[0:1], v42, s75, v[0:1]
	v_lshl_add_u64 v[172:173], v[2:3], 0, v[20:21]
	v_mad_i64_i32 v[2:3], s[0:1], v40, s75, v[0:1]
	v_mad_i64_i32 v[0:1], s[0:1], v38, s75, v[0:1]
	s_mul_hi_i32 s1, s4, 0xd8000
	s_mul_i32 s4, s4, 0xd8000
	s_add_u32 s0, s4, 0x8706000
	s_addc_u32 s1, s1, 0
	v_lshl_add_u64 v[176:177], v[0:1], 0, v[18:19]
	v_mov_b64_e32 v[0:1], s[0:1]
	v_lshl_add_u64 v[174:175], v[2:3], 0, v[22:23]
	v_mad_i64_i32 v[2:3], s[0:1], v36, s74, v[0:1]
	v_lshl_add_u64 v[178:179], v[2:3], 0, v[16:17]
	v_mad_i64_i32 v[2:3], s[0:1], v34, s74, v[0:1]
	v_lshl_add_u64 v[180:181], v[2:3], 0, v[12:13]
	v_mad_i64_i32 v[2:3], s[0:1], v32, s74, v[0:1]
	v_lshl_add_u64 v[182:183], v[2:3], 0, v[14:15]
	v_mad_i64_i32 v[2:3], s[0:1], v30, s74, v[0:1]
	v_mul_u32_u24_e32 v26, 0x90, v26
	v_lshlrev_b32_e32 v29, 4, v29
	v_lshlrev_b32_e32 v31, 4, v31
	v_lshlrev_b32_e32 v33, 4, v33
	v_lshlrev_b32_e32 v35, 4, v35
	v_lshlrev_b32_e32 v37, 4, v37
	v_mul_lo_u32 v53, v38, s50
	v_lshlrev_b32_e32 v39, 4, v39
	v_mul_lo_u32 v54, v40, s50
	v_lshlrev_b32_e32 v41, 4, v41
	v_mul_lo_u32 v55, v42, s50
	v_lshlrev_b32_e32 v43, 4, v43
	v_mul_lo_u32 v56, v44, s50
	v_lshlrev_b32_e32 v45, 4, v45
	v_lshl_add_u64 v[188:189], v[2:3], 0, v[8:9]
	v_mad_i64_i32 v[2:3], s[0:1], v28, s74, v[0:1]
	v_mad_i64_i32 v[0:1], s[0:1], v27, s74, v[0:1]
	v_mov_b32_e32 v14, v185
	v_mov_b32_e32 v15, v185
	v_lshl_add_u64 v[190:191], v[2:3], 0, v[10:11]
	v_lshl_add_u64 v[192:193], v[0:1], 0, v[6:7]
	v_mov_b32_e32 v0, v185
	v_mov_b32_e32 v1, v185
	v_mov_b32_e32 v2, v185
	v_mov_b32_e32 v3, v185
	v_mov_b32_e32 v4, v185
	v_mov_b32_e32 v5, v185
	v_mov_b32_e32 v6, v185
	v_mov_b32_e32 v7, v185
	v_mov_b32_e32 v8, v185
	v_mov_b32_e32 v9, v185
	v_mov_b32_e32 v10, v185
	v_mov_b32_e32 v11, v185
	v_mov_b32_e32 v12, v185
	v_mov_b32_e32 v13, v185
	v_add_u32_e32 v224, v46, v47
	v_add_u32_e32 v225, v48, v29
	v_add_u32_e32 v226, v49, v31
	v_add_u32_e32 v227, v50, v33
	v_add_u32_e32 v228, v51, v35
	v_add_u32_e32 v229, v52, v37
	v_add_u32_e32 v230, v53, v39
	v_add_u32_e32 v231, v54, v41
	v_add_u32_e32 v232, v55, v43
	v_add_u32_e32 v233, v56, v45
	v_add_u32_e32 v234, v184, v26
	v_mov_b64_e32 v[30:31], v[14:15]
	v_mov_b64_e32 v[46:47], v[14:15]
	v_mov_b64_e32 v[62:63], v[14:15]
	v_ashrrev_i32_e32 v169, 31, v168
	v_mov_b32_e32 v196, 0xf149f2ca
	v_mov_b32_e32 v198, 0
	s_mov_b32 s0, 35
	v_mov_b64_e32 v[28:29], v[12:13]
	v_mov_b64_e32 v[26:27], v[10:11]
	v_mov_b64_e32 v[24:25], v[8:9]
	v_mov_b64_e32 v[22:23], v[6:7]
	v_mov_b64_e32 v[20:21], v[4:5]
	v_mov_b64_e32 v[18:19], v[2:3]
	v_mov_b64_e32 v[16:17], v[0:1]
	v_mov_b64_e32 v[44:45], v[12:13]
	v_mov_b64_e32 v[42:43], v[10:11]
	v_mov_b64_e32 v[40:41], v[8:9]
	v_mov_b64_e32 v[38:39], v[6:7]
	v_mov_b64_e32 v[36:37], v[4:5]
	v_mov_b64_e32 v[34:35], v[2:3]
	v_mov_b64_e32 v[32:33], v[0:1]
	v_mov_b64_e32 v[60:61], v[12:13]
	v_mov_b64_e32 v[58:59], v[10:11]
	v_mov_b64_e32 v[56:57], v[8:9]
	v_mov_b64_e32 v[54:55], v[6:7]
	v_mov_b64_e32 v[52:53], v[4:5]
	v_mov_b64_e32 v[50:51], v[2:3]
	v_mov_b64_e32 v[48:49], v[0:1]
.LBB0_1545:
	s_waitcnt lgkmcnt(0)
	s_barrier
	s_waitcnt vmcnt(0)
	ds_write_b128 v224, v[144:147]
	ds_write_b128 v225, v[148:151]
	ds_write_b128 v226, v[152:155]
	ds_write_b128 v227, v[156:159]
	ds_write_b128 v228, v[160:163]
	ds_write_b128 v229, v[164:167]
	ds_write_b128 v230, v[64:67] offset:25600
	ds_write_b128 v231, v[68:71] offset:25600
	ds_write_b128 v232, v[72:75] offset:25600
	ds_write_b128 v233, v[76:79] offset:25600
	v_lshl_add_u64 v[64:65], s[92:93], 0, v[192:193]
	s_waitcnt lgkmcnt(0)
	s_barrier
; #define MFMA(a, b, c) __builtin_amdgcn_mfma_f32_32x32x16_bf16((a), (b), (c), 0, 0, 0)
; #define ATT_LOADK(key0)                                                                                  \
;   do {                                                                                                   \
;     _Pragma("unroll") for (int i = 0; i < KCH; ++i) { int c = tid + NT * i; kr[i] = ld8(Kp + (long)((key0) + c / CPR) * DK + (c % CPR) * 8); } \
;   } while (0)
; template <int DK, int KT>
; DI void attn_item(const bfu* __restrict__ Qp, const bfu* __restrict__ Kp, const bfu* __restrict__ Vtp, int nkeys, bfu* __restrict__ Op, int ldo, char* smem) {
;     ...
;     if (j + 1 < NTL) ATT_LOADK((j + 1) * KT);
;     f32x16 sv[NBK];
; #pragma unroll
;     for (int bk = 0; bk < NBK; ++bk)
; #pragma unroll
;       for (int r = 0; r < 16; ++r) sv[bk][r] = 0.f;
;     const bfu* k0p = Ks + l32 * LK + hi * 8;
; #pragma unroll
;     for (int ks = 0; ks < NKS; ++ks)
; #pragma unroll
;       for (int bk = 0; bk < NBK; ++bk) sv[bk] = MFMA(ld8(k0p + bk * 32 * LK + ks * 16), qf[ks], sv[bk]);
;     float mx = sv[0][0];
; #pragma unroll
;     for (int bk = 0; bk < NBK; ++bk)
; #pragma unroll
;       for (int r = 0; r < 16; ++r) mx = fmaxf(mx, sv[bk][r]);
;     mx = fmaxf(mx, __shfl_xor(mx, 32));
;     float mn = m, alpha = 1.f;
;     const bool moved = __builtin_amdgcn_ballot_w64(mx > m + 8.f) != 0ull;
;     if (moved) { mn = fmaxf(m, mx); alpha = __builtin_amdgcn_exp2f(m - mn); m = mn; }
;     float rs = 0.f;
; #pragma unroll
;     for (int bk = 0; bk < NBK; ++bk)
; #pragma unroll
;       for (int r = 0; r < 16; ++r) { sv[bk][r] = __builtin_amdgcn_exp2f(sv[bk][r] - mn); rs += sv[bk][r]; }
;     lsum = lsum * alpha + rs;
;     if (moved) {
; #pragma unroll
;       for (int d = 0; d < 4; ++d)
; #pragma unroll
;         for (int r = 0; r < 16; ++r) o[d][r] *= alpha;
;     }
	global_load_dwordx4 v[144:147], v[64:65], off
	v_lshl_add_u64 v[64:65], s[92:93], 0, v[190:191]
	global_load_dwordx4 v[148:151], v[64:65], off
	v_lshl_add_u64 v[64:65], s[92:93], 0, v[188:189]
	global_load_dwordx4 v[152:155], v[64:65], off
	v_lshl_add_u64 v[64:65], s[92:93], 0, v[182:183]
	global_load_dwordx4 v[156:159], v[64:65], off
	v_lshl_add_u64 v[64:65], s[92:93], 0, v[180:181]
	global_load_dwordx4 v[160:163], v[64:65], off
	v_lshl_add_u64 v[64:65], s[92:93], 0, v[178:179]
	global_load_dwordx4 v[164:167], v[64:65], off
	ds_read_b128 v[64:67], v197
	ds_read_b128 v[236:239], v197 offset:32
	s_waitcnt lgkmcnt(0)
	v_mfma_f32_32x32x16_bf16 v[80:95], v[64:67], v[140:143], 0
	ds_read_b128 v[64:67], v197 offset:12800
	v_mfma_f32_32x32x16_bf16 v[80:95], v[236:239], v[136:139], v[80:95]
	ds_read_b128 v[236:239], v197 offset:12832
	s_waitcnt lgkmcnt(0)
	v_mfma_f32_32x32x16_bf16 v[64:79], v[64:67], v[140:143], 0
	v_mfma_f32_32x32x16_bf16 v[64:79], v[236:239], v[136:139], v[64:79]
	ds_read_b128 v[236:239], v197 offset:64
	s_waitcnt lgkmcnt(0)
	v_mfma_f32_32x32x16_bf16 v[80:95], v[236:239], v[132:135], v[80:95]
	ds_read_b128 v[236:239], v197 offset:12864
	s_waitcnt lgkmcnt(0)
	v_mfma_f32_32x32x16_bf16 v[64:79], v[236:239], v[132:135], v[64:79]
	ds_read_b128 v[236:239], v197 offset:96
	s_waitcnt lgkmcnt(0)
	v_mfma_f32_32x32x16_bf16 v[80:95], v[236:239], v[128:131], v[80:95]
	ds_read_b128 v[236:239], v197 offset:12896
	s_waitcnt lgkmcnt(0)
	v_mfma_f32_32x32x16_bf16 v[64:79], v[236:239], v[128:131], v[64:79]
	ds_read_b128 v[236:239], v197 offset:128
	s_waitcnt lgkmcnt(0)
	v_mfma_f32_32x32x16_bf16 v[80:95], v[236:239], v[124:127], v[80:95]
	ds_read_b128 v[236:239], v197 offset:12928
	s_waitcnt lgkmcnt(0)
	v_mfma_f32_32x32x16_bf16 v[64:79], v[236:239], v[124:127], v[64:79]
	ds_read_b128 v[236:239], v197 offset:160
	s_waitcnt lgkmcnt(0)
	v_mfma_f32_32x32x16_bf16 v[80:95], v[236:239], v[120:123], v[80:95]
	ds_read_b128 v[236:239], v197 offset:12960
	s_waitcnt lgkmcnt(0)
	v_mfma_f32_32x32x16_bf16 v[64:79], v[236:239], v[120:123], v[64:79]
	ds_read_b128 v[236:239], v197 offset:192
	s_waitcnt lgkmcnt(0)
	v_mfma_f32_32x32x16_bf16 v[80:95], v[236:239], v[116:119], v[80:95]
	ds_read_b128 v[236:239], v197 offset:12992
	s_waitcnt lgkmcnt(0)
	v_mfma_f32_32x32x16_bf16 v[64:79], v[236:239], v[116:119], v[64:79]
	ds_read_b128 v[236:239], v197 offset:224
	s_waitcnt lgkmcnt(0)
	v_mfma_f32_32x32x16_bf16 v[80:95], v[236:239], v[112:115], v[80:95]
	ds_read_b128 v[236:239], v197 offset:13024
	s_waitcnt lgkmcnt(0)
	v_mfma_f32_32x32x16_bf16 v[64:79], v[236:239], v[112:115], v[64:79]
	ds_read_b128 v[236:239], v197 offset:256
	s_waitcnt lgkmcnt(0)
	v_mfma_f32_32x32x16_bf16 v[80:95], v[236:239], v[108:111], v[80:95]
	ds_read_b128 v[236:239], v197 offset:13056
	s_waitcnt lgkmcnt(0)
	v_mfma_f32_32x32x16_bf16 v[64:79], v[236:239], v[108:111], v[64:79]
	ds_read_b128 v[236:239], v197 offset:288
	s_waitcnt lgkmcnt(0)
	v_mfma_f32_32x32x16_bf16 v[80:95], v[236:239], v[104:107], v[80:95]
	ds_read_b128 v[236:239], v197 offset:13088
	s_waitcnt lgkmcnt(0)
	v_mfma_f32_32x32x16_bf16 v[64:79], v[236:239], v[104:107], v[64:79]
	ds_read_b128 v[236:239], v197 offset:320
	s_waitcnt lgkmcnt(0)
	v_mfma_f32_32x32x16_bf16 v[80:95], v[236:239], v[100:103], v[80:95]
	ds_read_b128 v[236:239], v197 offset:13120
	s_waitcnt lgkmcnt(0)
	v_mfma_f32_32x32x16_bf16 v[64:79], v[236:239], v[100:103], v[64:79]
	ds_read_b128 v[236:239], v197 offset:352
	s_waitcnt lgkmcnt(0)
	v_mfma_f32_32x32x16_bf16 v[80:95], v[236:239], v[96:99], v[80:95]
	ds_read_b128 v[236:239], v197 offset:13152
	s_waitcnt lgkmcnt(0)
	v_mfma_f32_32x32x16_bf16 v[64:79], v[236:239], v[96:99], v[64:79]
	s_nop 8
	v_max_f32_e32 v194, v81, v81
	v_max_f32_e32 v199, v80, v80
	v_max_f32_e32 v194, v199, v194
	v_max3_f32 v194, v194, v82, v83
	v_max3_f32 v194, v194, v84, v85
	v_max3_f32 v194, v194, v86, v87
	v_max3_f32 v194, v194, v88, v89
	v_max3_f32 v194, v194, v90, v91
	v_max3_f32 v194, v194, v92, v93
	v_max3_f32 v194, v194, v94, v95
	v_max3_f32 v194, v194, v64, v65
	v_max3_f32 v194, v194, v66, v67
	v_max3_f32 v194, v194, v68, v69
	v_max3_f32 v194, v194, v70, v71
	v_max3_f32 v194, v194, v72, v73
	v_max3_f32 v194, v194, v74, v75
	v_max3_f32 v194, v194, v76, v77
	v_max3_f32 v194, v194, v78, v79
	ds_bpermute_b32 v199, v195, v194
	s_waitcnt lgkmcnt(0)
	v_max_f32_e32 v199, v199, v199
	v_max_f32_e32 v194, v194, v199
	v_add_f32_e32 v199, 0x41000000, v196
	v_cmp_gt_f32_e32 vcc, v194, v199
	v_max_f32_e32 v199, v196, v196
	v_max_f32_e32 v199, v199, v194
	v_sub_f32_e32 v194, v196, v199
	v_exp_f32_e32 v194, v194
	s_cmp_eq_u64 vcc, 0
	s_cselect_b64 s[4:5], -1, 0
	s_and_b64 vcc, exec, s[4:5]
	s_cbranch_vccnz .LBB0_1547
	v_pk_mul_f32 v[62:63], v[62:63], v[194:195] op_sel_hi:[1,0]
	v_pk_mul_f32 v[60:61], v[60:61], v[194:195] op_sel_hi:[1,0]
	v_pk_mul_f32 v[58:59], v[58:59], v[194:195] op_sel_hi:[1,0]
	v_pk_mul_f32 v[56:57], v[56:57], v[194:195] op_sel_hi:[1,0]
	v_pk_mul_f32 v[54:55], v[54:55], v[194:195] op_sel_hi:[1,0]
	v_pk_mul_f32 v[52:53], v[52:53], v[194:195] op_sel_hi:[1,0]
	v_pk_mul_f32 v[50:51], v[50:51], v[194:195] op_sel_hi:[1,0]
	v_pk_mul_f32 v[48:49], v[48:49], v[194:195] op_sel_hi:[1,0]
	v_pk_mul_f32 v[46:47], v[46:47], v[194:195] op_sel_hi:[1,0]
	v_pk_mul_f32 v[44:45], v[44:45], v[194:195] op_sel_hi:[1,0]
	v_pk_mul_f32 v[42:43], v[42:43], v[194:195] op_sel_hi:[1,0]
	v_pk_mul_f32 v[40:41], v[40:41], v[194:195] op_sel_hi:[1,0]
	v_pk_mul_f32 v[38:39], v[38:39], v[194:195] op_sel_hi:[1,0]
	v_pk_mul_f32 v[36:37], v[36:37], v[194:195] op_sel_hi:[1,0]
	v_pk_mul_f32 v[34:35], v[34:35], v[194:195] op_sel_hi:[1,0]
	v_pk_mul_f32 v[32:33], v[32:33], v[194:195] op_sel_hi:[1,0]
	v_pk_mul_f32 v[30:31], v[30:31], v[194:195] op_sel_hi:[1,0]
	v_pk_mul_f32 v[28:29], v[28:29], v[194:195] op_sel_hi:[1,0]
	v_pk_mul_f32 v[26:27], v[26:27], v[194:195] op_sel_hi:[1,0]
	v_pk_mul_f32 v[24:25], v[24:25], v[194:195] op_sel_hi:[1,0]
	v_pk_mul_f32 v[22:23], v[22:23], v[194:195] op_sel_hi:[1,0]
	v_pk_mul_f32 v[20:21], v[20:21], v[194:195] op_sel_hi:[1,0]
	v_pk_mul_f32 v[18:19], v[18:19], v[194:195] op_sel_hi:[1,0]
	v_pk_mul_f32 v[16:17], v[16:17], v[194:195] op_sel_hi:[1,0]
	v_pk_mul_f32 v[14:15], v[14:15], v[194:195] op_sel_hi:[1,0]
	v_pk_mul_f32 v[12:13], v[12:13], v[194:195] op_sel_hi:[1,0]
	v_pk_mul_f32 v[10:11], v[10:11], v[194:195] op_sel_hi:[1,0]
	v_pk_mul_f32 v[8:9], v[8:9], v[194:195] op_sel_hi:[1,0]
	v_pk_mul_f32 v[6:7], v[6:7], v[194:195] op_sel_hi:[1,0]
	v_pk_mul_f32 v[4:5], v[4:5], v[194:195] op_sel_hi:[1,0]
	v_pk_mul_f32 v[2:3], v[2:3], v[194:195] op_sel_hi:[1,0]
	v_pk_mul_f32 v[0:1], v[0:1], v[194:195] op_sel_hi:[1,0]
; #define MFMA(a, b, c) __builtin_amdgcn_mfma_f32_32x32x16_bf16((a), (b), (c), 0, 0, 0)
; #define ATT_LOADV(key0)                                                                                  \
;   do {                                                                                                   \
;     _Pragma("unroll") for (int i = 0; i < VCH; ++i) { int c = tid + NT * i; vr[i] = ld8(Vtp + (long)(c / VPR) * T + (key0) + (c % VPR) * 8); }  \
;   } while (0)
; template <int DK, int KT>
; DI void attn_item(const bfu* __restrict__ Qp, const bfu* __restrict__ Kp, const bfu* __restrict__ Vtp, int nkeys, bfu* __restrict__ Op, int ldo, char* smem) {
;     ...
;     if (moved) { mn = fmaxf(m, mx); alpha = __builtin_amdgcn_exp2f(m - mn); m = mn; }
;     float rs = 0.f;
; #pragma unroll
;     for (int bk = 0; bk < NBK; ++bk)
; #pragma unroll
;       for (int r = 0; r < 16; ++r) { sv[bk][r] = __builtin_amdgcn_exp2f(sv[bk][r] - mn); rs += sv[bk][r]; }
;     lsum = lsum * alpha + rs;
;     if (moved) {
; #pragma unroll
;       for (int d = 0; d < 4; ++d)
; #pragma unroll
;         for (int r = 0; r < 16; ++r) o[d][r] *= alpha;
;     }
;     bf16x8 pf[2 * NBK];
; #pragma unroll
;     for (int bk = 0; bk < NBK; ++bk) { pf[2 * bk] = packacc(sv[bk], 0); pf[2 * bk + 1] = packacc(sv[bk], 1); }
;     if (j + 1 < NTL) ATT_LOADV((j + 1) * KT);
; #pragma unroll
;     for (int kk = 0; kk < 2 * NBK; ++kk)
; #pragma unroll
;       for (int d = 0; d < 4; ++d) o[d] = MFMA(ld44(Vs + (d * 32 + l32) * LV + kk * 16 + 4 * hi), pf[kk], o[d]);
;   }
.LBB0_1547:
	v_cndmask_b32_e64 v196, v199, v196, s[4:5]
	v_sub_f32_e32 v80, v80, v196
	v_exp_f32_e32 v80, v80
	v_sub_f32_e32 v81, v81, v196
	v_exp_f32_e32 v81, v81
	v_sub_f32_e32 v82, v82, v196
	v_exp_f32_e32 v82, v82
	v_sub_f32_e32 v83, v83, v196
	v_exp_f32_e32 v83, v83
	v_sub_f32_e32 v84, v84, v196
	v_add_f32_e32 v199, 0, v80
	v_exp_f32_e32 v84, v84
	v_sub_f32_e32 v85, v85, v196
	v_add_f32_e32 v199, v81, v199
	v_exp_f32_e32 v85, v85
	v_sub_f32_e32 v86, v86, v196
	v_add_f32_e32 v199, v82, v199
	v_exp_f32_e32 v86, v86
	v_sub_f32_e32 v87, v87, v196
	v_add_f32_e32 v199, v83, v199
	v_exp_f32_e32 v87, v87
	v_sub_f32_e32 v88, v88, v196
	v_add_f32_e32 v199, v84, v199
	v_exp_f32_e32 v88, v88
	v_sub_f32_e32 v89, v89, v196
	v_add_f32_e32 v199, v85, v199
	v_exp_f32_e32 v89, v89
	v_sub_f32_e32 v90, v90, v196
	v_add_f32_e32 v199, v86, v199
	v_exp_f32_e32 v90, v90
	v_sub_f32_e32 v91, v91, v196
	v_add_f32_e32 v199, v87, v199
	v_exp_f32_e32 v91, v91
	v_sub_f32_e32 v92, v92, v196
	v_add_f32_e32 v199, v88, v199
	v_exp_f32_e32 v200, v92
	v_add_f32_e32 v199, v89, v199
	v_add_f32_e32 v199, v90, v199
	v_add_f32_e32 v199, v91, v199
	v_sub_f32_e32 v93, v93, v196
	v_add_f32_e32 v92, v200, v199
	v_exp_f32_e32 v199, v93
	v_sub_f32_e32 v93, v94, v196
	v_exp_f32_e32 v205, v93
	v_sub_f32_e32 v93, v95, v196
	v_exp_f32_e32 v206, v93
	v_sub_f32_e32 v64, v64, v196
	v_exp_f32_e32 v64, v64
	v_sub_f32_e32 v65, v65, v196
	v_add_f32_e32 v92, v199, v92
	v_exp_f32_e32 v65, v65
	v_sub_f32_e32 v66, v66, v196
	v_add_f32_e32 v92, v205, v92
	v_exp_f32_e32 v66, v66
	v_sub_f32_e32 v67, v67, v196
	v_add_f32_e32 v92, v206, v92
	v_exp_f32_e32 v67, v67
	v_sub_f32_e32 v68, v68, v196
	v_add_f32_e32 v92, v64, v92
	v_exp_f32_e32 v68, v68
	v_sub_f32_e32 v69, v69, v196
	v_add_f32_e32 v92, v65, v92
	v_exp_f32_e32 v69, v69
	v_sub_f32_e32 v70, v70, v196
	v_add_f32_e32 v92, v66, v92
	v_exp_f32_e32 v70, v70
	v_sub_f32_e32 v71, v71, v196
	v_add_f32_e32 v92, v67, v92
	v_exp_f32_e32 v71, v71
	v_sub_f32_e32 v72, v72, v196
	v_add_f32_e32 v92, v68, v92
	v_exp_f32_e32 v72, v72
	v_sub_f32_e32 v73, v73, v196
	v_add_f32_e32 v92, v69, v92
	v_exp_f32_e32 v73, v73
	v_sub_f32_e32 v74, v74, v196
	v_add_f32_e32 v92, v70, v92
	v_exp_f32_e32 v74, v74
	v_sub_f32_e32 v75, v75, v196
	v_add_f32_e32 v92, v71, v92
	v_exp_f32_e32 v75, v75
	v_sub_f32_e32 v76, v76, v196
	v_add_f32_e32 v92, v72, v92
	v_exp_f32_e32 v76, v76
	v_sub_f32_e32 v77, v77, v196
	v_add_f32_e32 v92, v73, v92
	v_exp_f32_e32 v77, v77
	v_sub_f32_e32 v78, v78, v196
	v_add_f32_e32 v92, v74, v92
	v_exp_f32_e32 v78, v78
	v_sub_f32_e32 v79, v79, v196
	v_add_f32_e32 v92, v75, v92
	v_exp_f32_e32 v79, v79
	v_add_f32_e32 v92, v76, v92
	v_add_f32_e32 v92, v77, v92
	v_add_f32_e32 v92, v78, v92
	v_add_f32_e32 v201, v79, v92
	v_cndmask_b32_e64 v92, v194, 1.0, s[4:5]
	v_fmac_f32_e32 v201, v198, v92
	v_cvt_pk_bf16_f32 v92, v80, v81
	v_cvt_pk_bf16_f32 v93, v82, v83
	v_cvt_pk_bf16_f32 v94, v84, v85
	v_cvt_pk_bf16_f32 v95, v86, v87
	v_cvt_pk_bf16_f32 v84, v64, v65
	v_cvt_pk_bf16_f32 v86, v68, v69
	v_cvt_pk_bf16_f32 v80, v72, v73
	v_cvt_pk_bf16_f32 v82, v76, v77
	v_lshl_add_u64 v[64:65], s[92:93], 0, v[176:177]
	v_lshl_add_u64 v[68:69], s[92:93], 0, v[174:175]
	v_lshl_add_u64 v[72:73], s[92:93], 0, v[172:173]
	v_lshl_add_u64 v[76:77], s[92:93], 0, v[170:171]
	v_add_u32_e32 v194, 0x6000, v234
	v_cvt_pk_bf16_f32 v85, v66, v67
	v_cvt_pk_bf16_f32 v87, v70, v71
	v_cvt_pk_bf16_f32 v81, v74, v75
	v_cvt_pk_bf16_f32 v83, v78, v79
	global_load_dwordx4 v[64:67], v[64:65], off
	v_cvt_pk_bf16_f32 v88, v88, v89
	global_load_dwordx4 v[68:71], v[68:69], off
	v_cvt_pk_bf16_f32 v89, v90, v91
	global_load_dwordx4 v[72:75], v[72:73], off
	v_cvt_pk_bf16_f32 v90, v200, v199
	global_load_dwordx4 v[76:79], v[76:77], off
	ds_read2_b64 v[236:239], v194 offset0:128 offset1:130
	ds_read2_b64 v[240:243], v194 offset0:132 offset1:134
	v_add_u32_e32 v199, 0x7000, v234
	s_waitcnt lgkmcnt(0)
	v_mfma_f32_32x32x16_bf16 v[48:63], v[236:239], v[92:95], v[48:63]
	ds_read2_b64 v[236:239], v199 offset0:192 offset1:194
	v_add_u32_e32 v198, 0x8800, v234
	v_add_u32_e32 v200, 0x9800, v234
	v_cvt_pk_bf16_f32 v91, v205, v206
	s_add_i32 s0, s0, -1
	v_lshl_add_u64 v[170:171], v[170:171], 0, s[48:49]
	v_lshl_add_u64 v[172:173], v[172:173], 0, s[48:49]
	s_waitcnt lgkmcnt(0)
	v_mfma_f32_32x32x16_bf16 v[32:47], v[236:239], v[92:95], v[32:47]
	ds_read2_b64 v[236:239], v198 offset1:2
	v_lshl_add_u64 v[174:175], v[174:175], 0, s[48:49]
	v_lshl_add_u64 v[176:177], v[176:177], 0, s[48:49]
	v_lshl_add_u64 v[178:179], v[178:179], 0, s[80:81]
	v_lshl_add_u64 v[180:181], v[180:181], 0, s[80:81]
	v_lshl_add_u64 v[182:183], v[182:183], 0, s[80:81]
	v_lshl_add_u64 v[188:189], v[188:189], 0, s[80:81]
	s_waitcnt lgkmcnt(0)
	v_mfma_f32_32x32x16_bf16 v[16:31], v[236:239], v[92:95], v[16:31]
	ds_read2_b64 v[236:239], v200 offset0:64 offset1:66
	v_lshl_add_u64 v[190:191], v[190:191], 0, s[80:81]
	v_lshl_add_u64 v[192:193], v[192:193], 0, s[80:81]
	s_cmp_eq_u32 s0, 0
	s_waitcnt lgkmcnt(0)
	v_mfma_f32_32x32x16_bf16 v[0:15], v[236:239], v[92:95], v[0:15]
	ds_read2_b64 v[92:95], v199 offset0:196 offset1:198
	s_waitcnt lgkmcnt(0)
	v_mfma_f32_32x32x16_bf16 v[32:47], v[92:95], v[88:91], v[32:47]
	ds_read2_b64 v[92:95], v198 offset0:4 offset1:6
	s_waitcnt lgkmcnt(0)
	v_mfma_f32_32x32x16_bf16 v[16:31], v[92:95], v[88:91], v[16:31]
	ds_read2_b64 v[92:95], v200 offset0:68 offset1:70
	v_mfma_f32_32x32x16_bf16 v[48:63], v[240:243], v[88:91], v[48:63]
	s_waitcnt lgkmcnt(0)
	v_mfma_f32_32x32x16_bf16 v[0:15], v[92:95], v[88:91], v[0:15]
	ds_read2_b64 v[88:91], v194 offset0:136 offset1:138
	s_waitcnt lgkmcnt(0)
	v_mfma_f32_32x32x16_bf16 v[48:63], v[88:91], v[84:87], v[48:63]
	ds_read2_b64 v[88:91], v199 offset0:200 offset1:202
	s_waitcnt lgkmcnt(0)
	v_mfma_f32_32x32x16_bf16 v[32:47], v[88:91], v[84:87], v[32:47]
	ds_read2_b64 v[88:91], v198 offset0:8 offset1:10
	s_waitcnt lgkmcnt(0)
	v_mfma_f32_32x32x16_bf16 v[16:31], v[88:91], v[84:87], v[16:31]
	ds_read2_b64 v[88:91], v200 offset0:72 offset1:74
	s_waitcnt lgkmcnt(0)
	v_mfma_f32_32x32x16_bf16 v[0:15], v[88:91], v[84:87], v[0:15]
	ds_read2_b64 v[84:87], v194 offset0:140 offset1:142
	s_waitcnt lgkmcnt(0)
	v_mfma_f32_32x32x16_bf16 v[48:63], v[84:87], v[80:83], v[48:63]
	ds_read2_b64 v[84:87], v199 offset0:204 offset1:206
	s_waitcnt lgkmcnt(0)
	v_mfma_f32_32x32x16_bf16 v[32:47], v[84:87], v[80:83], v[32:47]
	ds_read2_b64 v[84:87], v198 offset0:12 offset1:14
	s_waitcnt lgkmcnt(0)
	v_mfma_f32_32x32x16_bf16 v[16:31], v[84:87], v[80:83], v[16:31]
	ds_read2_b64 v[84:87], v200 offset0:76 offset1:78
	s_waitcnt lgkmcnt(0)
	v_mfma_f32_32x32x16_bf16 v[0:15], v[84:87], v[80:83], v[0:15]
	s_cbranch_scc1 .LBB0_1549
	v_mov_b32_e32 v198, v201
	s_branch .LBB0_1545

; #define MFMA(a, b, c) __builtin_amdgcn_mfma_f32_32x32x16_bf16((a), (b), (c), 0, 0, 0)
; #define ATT_LOADV(key0)                                                                                  \
;   do {                                                                                                   \
;     _Pragma("unroll") for (int i = 0; i < VCH; ++i) { int c = tid + NT * i; vr[i] = ld8(Vtp + (long)(c / VPR) * T + (key0) + (c % VPR) * 8); }  \
;   } while (0)
; template <int DK, int KT>
; DI void attn_item(const bfu* __restrict__ Qp, const bfu* __restrict__ Kp, const bfu* __restrict__ Vtp, int nkeys, bfu* __restrict__ Op, int ldo, char* smem) {
;     ...
;     float rs = 0.f;
; #pragma unroll
;     for (int bk = 0; bk < NBK; ++bk)
; #pragma unroll
;       for (int r = 0; r < 16; ++r) { sv[bk][r] = __builtin_amdgcn_exp2f(sv[bk][r] - mn); rs += sv[bk][r]; }
;     lsum = lsum * alpha + rs;
;     if (moved) {
; #pragma unroll
;       for (int d = 0; d < 4; ++d)
; #pragma unroll
;         for (int r = 0; r < 16; ++r) o[d][r] *= alpha;
;     }
;     bf16x8 pf[2 * NBK];
; #pragma unroll
;     for (int bk = 0; bk < NBK; ++bk) { pf[2 * bk] = packacc(sv[bk], 0); pf[2 * bk + 1] = packacc(sv[bk], 1); }
;     if (j + 1 < NTL) ATT_LOADV((j + 1) * KT);
; #pragma unroll
;     for (int kk = 0; kk < 2 * NBK; ++kk)
; #pragma unroll
;       for (int d = 0; d < 4; ++d) o[d] = MFMA(ld44(Vs + (d * 32 + l32) * LV + kk * 16 + 4 * hi), pf[kk], o[d]);
.LBB0_1552:
	v_sub_f32_e32 v64, v64, v196
	v_exp_f32_e32 v109, v64
	v_sub_f32_e32 v64, v65, v196
	v_exp_f32_e32 v110, v64
	v_sub_f32_e32 v65, v66, v196
	v_exp_f32_e32 v111, v65
	v_sub_f32_e32 v65, v67, v196
	v_sub_f32_e32 v66, v68, v196
	v_exp_f32_e32 v112, v65
	v_exp_f32_e32 v68, v66
	v_sub_f32_e32 v66, v69, v196
	v_cvt_pk_bf16_f32 v64, v109, v110
	v_exp_f32_e32 v69, v66
	v_add_f32_e32 v109, 0, v109
	v_sub_f32_e32 v67, v70, v196
	v_add_f32_e32 v109, v110, v109
	v_exp_f32_e32 v70, v67
	v_sub_f32_e32 v67, v71, v196
	v_add_f32_e32 v109, v111, v109
	v_sub_f32_e32 v72, v72, v196
	v_exp_f32_e32 v71, v67
	v_add_f32_e32 v109, v112, v109
	v_exp_f32_e32 v105, v72
	v_sub_f32_e32 v72, v73, v196
	v_cvt_pk_bf16_f32 v66, v68, v69
	v_add_f32_e32 v68, v68, v109
	v_exp_f32_e32 v106, v72
	v_sub_f32_e32 v73, v74, v196
	v_add_f32_e32 v68, v69, v68
	v_exp_f32_e32 v107, v73
	v_sub_f32_e32 v73, v75, v196
	v_add_f32_e32 v68, v70, v68
	v_exp_f32_e32 v108, v73
	v_sub_f32_e32 v74, v76, v196
	v_add_f32_e32 v68, v71, v68
	v_exp_f32_e32 v76, v74
	v_sub_f32_e32 v74, v77, v196
	v_add_f32_e32 v68, v105, v68
	v_exp_f32_e32 v77, v74
	v_sub_f32_e32 v75, v78, v196
	v_add_f32_e32 v68, v106, v68
	v_exp_f32_e32 v78, v75
	v_sub_f32_e32 v75, v79, v196
	v_add_f32_e32 v68, v107, v68
	v_sub_f32_e32 v80, v80, v196
	v_exp_f32_e32 v79, v75
	v_add_f32_e32 v68, v108, v68
	v_exp_f32_e32 v101, v80
	v_sub_f32_e32 v80, v81, v196
	v_add_f32_e32 v68, v76, v68
	v_exp_f32_e32 v102, v80
	v_sub_f32_e32 v81, v82, v196
	v_add_f32_e32 v68, v77, v68
	v_exp_f32_e32 v103, v81
	v_sub_f32_e32 v81, v83, v196
	v_add_f32_e32 v68, v78, v68
	v_exp_f32_e32 v104, v81
	v_sub_f32_e32 v82, v84, v196
	v_add_f32_e32 v68, v79, v68
	v_exp_f32_e32 v84, v82
	v_sub_f32_e32 v82, v85, v196
	v_add_f32_e32 v68, v101, v68
	v_exp_f32_e32 v85, v82
	v_sub_f32_e32 v83, v86, v196
	v_add_f32_e32 v68, v102, v68
	v_exp_f32_e32 v86, v83
	v_sub_f32_e32 v83, v87, v196
	v_add_f32_e32 v68, v103, v68
	v_exp_f32_e32 v87, v83
	v_add_f32_e32 v68, v104, v68
	v_add_f32_e32 v68, v84, v68
	v_add_f32_e32 v68, v85, v68
	v_add_f32_e32 v68, v86, v68
	v_cvt_pk_bf16_f32 v82, v84, v85
	v_cvt_pk_bf16_f32 v83, v86, v87
	v_cvt_pk_bf16_f32 v74, v76, v77
	v_cvt_pk_bf16_f32 v75, v78, v79
	v_add_f32_e32 v68, v87, v68
	ds_read2_b64 v[76:79], v194 offset0:128 offset1:130
	ds_read2_b64 v[84:87], v194 offset0:132 offset1:134
	v_cvt_pk_bf16_f32 v65, v111, v112
	v_cvt_pk_bf16_f32 v67, v70, v71
	v_cvt_pk_bf16_f32 v72, v105, v106
	v_cvt_pk_bf16_f32 v73, v107, v108
	s_waitcnt lgkmcnt(1)
	v_mfma_f32_32x32x16_bf16 v[48:63], v[76:79], v[64:67], v[48:63]
	ds_read2_b64 v[76:79], v199 offset0:192 offset1:194
	v_cvt_pk_bf16_f32 v80, v101, v102
	v_cvt_pk_bf16_f32 v81, v103, v104
	v_sub_f32_e32 v88, v88, v196
	v_exp_f32_e32 v97, v88
	v_sub_f32_e32 v88, v89, v196
	v_sub_f32_e32 v89, v90, v196
	s_waitcnt lgkmcnt(0)
	v_mfma_f32_32x32x16_bf16 v[32:47], v[76:79], v[64:67], v[32:47]
	ds_read2_b64 v[76:79], v198 offset1:2
	v_exp_f32_e32 v99, v89
	v_sub_f32_e32 v89, v91, v196
	v_sub_f32_e32 v90, v92, v196
	v_sub_f32_e32 v91, v94, v196
	v_exp_f32_e32 v92, v90
	v_sub_f32_e32 v90, v93, v196
	s_waitcnt lgkmcnt(0)
	v_mfma_f32_32x32x16_bf16 v[16:31], v[76:79], v[64:67], v[16:31]
	ds_read2_b64 v[76:79], v200 offset0:64 offset1:66
	v_exp_f32_e32 v94, v91
	v_sub_f32_e32 v91, v95, v196
	v_exp_f32_e32 v98, v88
	v_exp_f32_e32 v100, v89
	v_exp_f32_e32 v93, v90
	v_exp_f32_e32 v95, v91
	s_waitcnt lgkmcnt(0)
	v_mfma_f32_32x32x16_bf16 v[0:15], v[76:79], v[64:67], v[0:15]
	ds_read2_b64 v[64:67], v199 offset0:196 offset1:198
	v_cvt_pk_bf16_f32 v88, v97, v98
	v_cvt_pk_bf16_f32 v89, v99, v100
	v_cvt_pk_bf16_f32 v90, v92, v93
	v_cvt_pk_bf16_f32 v91, v94, v95
	v_add_f32_e32 v68, v97, v68
	v_add_f32_e32 v68, v98, v68
	s_waitcnt lgkmcnt(0)
	v_mfma_f32_32x32x16_bf16 v[32:47], v[64:67], v[72:75], v[32:47]
	ds_read2_b64 v[64:67], v198 offset0:4 offset1:6
	v_add_f32_e32 v68, v99, v68
	v_add_f32_e32 v68, v100, v68
	v_add_f32_e32 v68, v92, v68
	v_add_f32_e32 v68, v93, v68
	v_add_f32_e32 v68, v94, v68
	v_add_f32_e32 v68, v95, v68
	s_waitcnt lgkmcnt(0)
	v_mfma_f32_32x32x16_bf16 v[16:31], v[64:67], v[72:75], v[16:31]
	ds_read2_b64 v[64:67], v200 offset0:68 offset1:70
	v_fmac_f32_e32 v68, v201, v96
	s_mul_hi_i32 s1, s16, 0x900
	s_mulk_i32 s16, 0x900
	s_add_u32 s0, s16, s7
	s_addc_u32 s1, s1, 0
	s_lshl_b64 s[0:1], s[0:1], 12
	s_waitcnt lgkmcnt(0)
	v_mfma_f32_32x32x16_bf16 v[0:15], v[64:67], v[72:75], v[0:15]
	ds_read2_b64 v[64:67], v194 offset0:136 offset1:138
	s_add_u32 s0, s14, s0
	s_addc_u32 s1, s15, s1
	s_lshl_b32 s4, s6, 8
	s_add_u32 s0, s0, s4
	s_addc_u32 s1, s1, 0
	v_mfma_f32_32x32x16_bf16 v[48:63], v[84:87], v[72:75], v[48:63]
	s_waitcnt lgkmcnt(0)
	v_mfma_f32_32x32x16_bf16 v[48:63], v[64:67], v[80:83], v[48:63]
	ds_read2_b64 v[64:67], v199 offset0:200 offset1:202
	s_waitcnt lgkmcnt(0)
	v_mfma_f32_32x32x16_bf16 v[32:47], v[64:67], v[80:83], v[32:47]
	ds_read2_b64 v[64:67], v198 offset0:8 offset1:10
	s_waitcnt lgkmcnt(0)
	v_mfma_f32_32x32x16_bf16 v[16:31], v[64:67], v[80:83], v[16:31]
	ds_read2_b64 v[64:67], v200 offset0:72 offset1:74
	s_waitcnt lgkmcnt(0)
	v_mfma_f32_32x32x16_bf16 v[0:15], v[64:67], v[80:83], v[0:15]
	ds_read2_b64 v[64:67], v194 offset0:140 offset1:142
	s_waitcnt lgkmcnt(0)
; #define MFMA(a, b, c) __builtin_amdgcn_mfma_f32_32x32x16_bf16((a), (b), (c), 0, 0, 0)
; DI unsigned cvtpk(float lo, float hi) { f32x2_t v = {lo, hi}; bf16x2_t b = __builtin_convertvector(v, bf16x2_t); return __builtin_bit_cast(unsigned, b); }
; template <int DK, int KT>
; DI void attn_item(const bfu* __restrict__ Qp, const bfu* __restrict__ Kp, const bfu* __restrict__ Vtp, int nkeys, bfu* __restrict__ Op, int ldo, char* smem) {
;     ...
;       for (int d = 0; d < 4; ++d) o[d] = MFMA(ld44(Vs + (d * 32 + l32) * LV + kk * 16 + 4 * hi), pf[kk], o[d]);
;   }
;     ...
;   const float inv = 1.f / (lsum + __shfl_xor(lsum, 32));
;   bfu* orow = Op + (long)(w * 32 + l32) * ldo;
; #pragma unroll
;   for (int d = 0; d < 4; ++d)
; #pragma unroll
;     for (int rg = 0; rg < 4; ++rg) {
;       u32x2 v = {cvtpk(o[d][4 * rg] * inv, o[d][4 * rg + 1] * inv), cvtpk(o[d][4 * rg + 2] * inv, o[d][4 * rg + 3] * inv)};
;       *reinterpret_cast<u32x2*>(orow + d * 32 + 8 * rg + 4 * hi) = v;
;     }
	v_mfma_f32_32x32x16_bf16 v[48:63], v[64:67], v[88:91], v[48:63]
	ds_read2_b64 v[64:67], v199 offset0:204 offset1:206
	s_waitcnt lgkmcnt(0)
	v_mfma_f32_32x32x16_bf16 v[32:47], v[64:67], v[88:91], v[32:47]
	ds_read2_b64 v[64:67], v198 offset0:12 offset1:14
	s_waitcnt lgkmcnt(0)
	v_mfma_f32_32x32x16_bf16 v[16:31], v[64:67], v[88:91], v[16:31]
	ds_read2_b64 v[64:67], v200 offset0:76 offset1:78
	s_waitcnt lgkmcnt(0)
	v_mfma_f32_32x32x16_bf16 v[0:15], v[64:67], v[88:91], v[0:15]
	ds_bpermute_b32 v64, v195, v68
	s_waitcnt lgkmcnt(0)
	v_add_f32_e32 v64, v68, v64
	v_div_scale_f32 v65, s[4:5], v64, v64, 1.0
	v_rcp_f32_e32 v66, v65
	s_nop 0
	v_fma_f32 v67, -v65, v66, 1.0
	v_fmac_f32_e32 v66, v67, v66
	v_div_scale_f32 v67, vcc, 1.0, v64, 1.0
	v_mul_f32_e32 v68, v67, v66
	v_fma_f32 v69, -v65, v68, v67
	v_fmac_f32_e32 v68, v69, v66
	v_fma_f32 v65, -v65, v68, v67
	v_div_fmas_f32 v65, v65, v66, v68
	v_div_fixup_f32 v64, v65, v64, 1.0
	v_lshlrev_b64 v[66:67], 12, v[168:169]
	v_lshl_add_u64 v[66:67], s[0:1], 0, v[66:67]
	v_pk_mul_f32 v[48:49], v[48:49], v[64:65] op_sel_hi:[1,0]
	v_pk_mul_f32 v[50:51], v[50:51], v[64:65] op_sel_hi:[1,0]
	v_pk_mul_f32 v[32:33], v[32:33], v[64:65] op_sel_hi:[1,0]
	v_pk_mul_f32 v[34:35], v[34:35], v[64:65] op_sel_hi:[1,0]
	v_pk_mul_f32 v[16:17], v[16:17], v[64:65] op_sel_hi:[1,0]
	v_pk_mul_f32 v[18:19], v[18:19], v[64:65] op_sel_hi:[1,0]
	v_pk_mul_f32 v[0:1], v[0:1], v[64:65] op_sel_hi:[1,0]
	v_pk_mul_f32 v[2:3], v[2:3], v[64:65] op_sel_hi:[1,0]
	v_lshl_add_u64 v[66:67], v[66:67], 0, v[184:185]
	v_cvt_pk_bf16_f32 v48, v48, v49
	v_cvt_pk_bf16_f32 v49, v50, v51
	v_cvt_pk_bf16_f32 v32, v32, v33
	v_cvt_pk_bf16_f32 v33, v34, v35
	v_cvt_pk_bf16_f32 v16, v16, v17
	v_cvt_pk_bf16_f32 v17, v18, v19
	v_cvt_pk_bf16_f32 v0, v0, v1
	v_cvt_pk_bf16_f32 v1, v2, v3
	global_store_dwordx2 v[66:67], v[48:49], off
	v_pk_mul_f32 v[48:49], v[52:53], v[64:65] op_sel_hi:[1,0]
	v_pk_mul_f32 v[50:51], v[54:55], v[64:65] op_sel_hi:[1,0]
	global_store_dwordx2 v[66:67], v[32:33], off offset:64
	v_pk_mul_f32 v[32:33], v[36:37], v[64:65] op_sel_hi:[1,0]
	v_pk_mul_f32 v[34:35], v[38:39], v[64:65] op_sel_hi:[1,0]
	global_store_dwordx2 v[66:67], v[16:17], off offset:128
	v_pk_mul_f32 v[16:17], v[20:21], v[64:65] op_sel_hi:[1,0]
	v_pk_mul_f32 v[18:19], v[22:23], v[64:65] op_sel_hi:[1,0]
	global_store_dwordx2 v[66:67], v[0:1], off offset:192
	v_pk_mul_f32 v[0:1], v[4:5], v[64:65] op_sel_hi:[1,0]
	v_pk_mul_f32 v[2:3], v[6:7], v[64:65] op_sel_hi:[1,0]
	v_cvt_pk_bf16_f32 v48, v48, v49
	v_cvt_pk_bf16_f32 v49, v50, v51
	v_cvt_pk_bf16_f32 v32, v32, v33
	v_cvt_pk_bf16_f32 v33, v34, v35
	v_cvt_pk_bf16_f32 v16, v16, v17
	v_cvt_pk_bf16_f32 v17, v18, v19
	v_cvt_pk_bf16_f32 v0, v0, v1
	v_cvt_pk_bf16_f32 v1, v2, v3
	global_store_dwordx2 v[66:67], v[48:49], off offset:16
	v_pk_mul_f32 v[48:49], v[56:57], v[64:65] op_sel_hi:[1,0]
	v_pk_mul_f32 v[50:51], v[58:59], v[64:65] op_sel_hi:[1,0]
	global_store_dwordx2 v[66:67], v[32:33], off offset:80
	v_pk_mul_f32 v[32:33], v[40:41], v[64:65] op_sel_hi:[1,0]
	v_pk_mul_f32 v[34:35], v[42:43], v[64:65] op_sel_hi:[1,0]
	global_store_dwordx2 v[66:67], v[16:17], off offset:144
	v_pk_mul_f32 v[16:17], v[24:25], v[64:65] op_sel_hi:[1,0]
	v_pk_mul_f32 v[18:19], v[26:27], v[64:65] op_sel_hi:[1,0]
	global_store_dwordx2 v[66:67], v[0:1], off offset:208
	v_pk_mul_f32 v[0:1], v[8:9], v[64:65] op_sel_hi:[1,0]
	v_pk_mul_f32 v[2:3], v[10:11], v[64:65] op_sel_hi:[1,0]
	v_cvt_pk_bf16_f32 v48, v48, v49
	v_cvt_pk_bf16_f32 v49, v50, v51
	v_cvt_pk_bf16_f32 v32, v32, v33
	v_cvt_pk_bf16_f32 v33, v34, v35
	v_cvt_pk_bf16_f32 v16, v16, v17
	v_cvt_pk_bf16_f32 v17, v18, v19
	v_cvt_pk_bf16_f32 v0, v0, v1
	v_cvt_pk_bf16_f32 v1, v2, v3
	global_store_dwordx2 v[66:67], v[48:49], off offset:32
	v_pk_mul_f32 v[48:49], v[60:61], v[64:65] op_sel_hi:[1,0]
	v_pk_mul_f32 v[50:51], v[62:63], v[64:65] op_sel_hi:[1,0]
	global_store_dwordx2 v[66:67], v[32:33], off offset:96
	v_pk_mul_f32 v[32:33], v[44:45], v[64:65] op_sel_hi:[1,0]
	v_pk_mul_f32 v[34:35], v[46:47], v[64:65] op_sel_hi:[1,0]
	global_store_dwordx2 v[66:67], v[16:17], off offset:160
	v_pk_mul_f32 v[16:17], v[28:29], v[64:65] op_sel_hi:[1,0]
	v_pk_mul_f32 v[18:19], v[30:31], v[64:65] op_sel_hi:[1,0]
	global_store_dwordx2 v[66:67], v[0:1], off offset:224
	v_pk_mul_f32 v[0:1], v[12:13], v[64:65] op_sel_hi:[1,0]
	v_pk_mul_f32 v[2:3], v[14:15], v[64:65] op_sel_hi:[1,0]
	v_cvt_pk_bf16_f32 v48, v48, v49
	v_cvt_pk_bf16_f32 v49, v50, v51
	v_cvt_pk_bf16_f32 v32, v32, v33
	v_cvt_pk_bf16_f32 v33, v34, v35
	v_cvt_pk_bf16_f32 v16, v16, v17
	v_cvt_pk_bf16_f32 v17, v18, v19
	v_cvt_pk_bf16_f32 v0, v0, v1
	v_cvt_pk_bf16_f32 v1, v2, v3
	global_store_dwordx2 v[66:67], v[48:49], off offset:48
	global_store_dwordx2 v[66:67], v[32:33], off offset:112
	global_store_dwordx2 v[66:67], v[16:17], off offset:176
	global_store_dwordx2 v[66:67], v[0:1], off offset:240
	s_waitcnt lgkmcnt(0)
	s_barrier
	s_and_saveexec_b64 s[0:1], s[2:3]
	s_cbranch_execz .LBB0_1543
	s_mov_b64 s[6:7], exec
	v_mbcnt_lo_u32_b32 v0, s6, 0
	v_mbcnt_hi_u32_b32 v0, s7, v0
	v_cmp_eq_u32_e32 vcc, 0, v0
	s_and_saveexec_b64 s[4:5], vcc
	s_cbranch_execz .LBB0_1542
	s_bcnt1_i32_b64 s6, s[6:7]
	v_mov_b32_e32 v1, s6
	v_readlane_b32 s6, v254, 27
	v_readlane_b32 s7, v254, 28
	s_nop 4
	global_atomic_add v1, v185, v1, s[6:7] offset:256 sc0
	s_branch .LBB0_1542

; DI int TID() { int t = threadIdx.x; asm volatile("" : "+v"(t)); return t; }
; DI void gemm_preload(const bfu* __restrict__ A, const bfu* __restrict__ Bt, int K, int kt, bf16x8 (&ra)[4], bf16x8 (&rb)[8]) {
;   const int tid = TID(), sr = tid >> 3, sc = (tid & 7) * 8;
;   const bfu* Ag = A + (long)sr * K + sc + kt * BK; const bfu* Bg = Bt + (long)sr * K + sc + kt * BK;
; #pragma unroll
;   for (int i = 0; i < 4; ++i) ra[i] = ld8(Ag + (long)(32 * i) * K);
; #pragma unroll
;   for (int i = 0; i < 8; ++i) rb[i] = ld8(Bg + (long)(32 * i) * K);
; }
; DI void phase_gemm(const Params& p, int g, int kind, char* smem, float* rsl, int* s_item, int vlo, int vhi, int cslot) {
;     ...
;   TD cur; fetch(cur);
;   bf16x8 ra[4], rb[8];
;   if (cur.ok) gemm_preload(cur.A, cur.Bt, cur.K, 0, ra, rb);
.LBB0_1561:
	v_cndmask_b32_e64 v0, 0, 1, s[12:13]
	v_cmp_ne_u32_e64 s[2:3], 1, v0
	s_andn2_b64 vcc, exec, s[12:13]
	s_cbranch_vccnz .LBB0_1563
	v_mov_b32_e32 v4, v202
	s_nop 0
	v_ashrrev_i32_e32 v0, 3, v4
	v_ashrrev_i32_e32 v1, 31, v0
	v_lshlrev_b64 v[0:1], 12, v[0:1]
	v_lshlrev_b32_e32 v4, 4, v4
	v_lshl_add_u64 v[2:3], s[8:9], 0, v[0:1]
	v_and_b32_e32 v184, 0x70, v4
	v_lshl_add_u64 v[2:3], v[2:3], 0, v[184:185]
	v_add_co_u32_e32 v4, vcc, 0x20000, v2
	v_lshl_add_u64 v[0:1], s[10:11], 0, v[0:1]
	s_nop 0
	v_addc_co_u32_e32 v5, vcc, 0, v3, vcc
	v_add_co_u32_e32 v6, vcc, 0x40000, v2
	s_waitcnt vmcnt(0)
	global_load_dwordx4 v[128:131], v[2:3], off
	v_addc_co_u32_e32 v7, vcc, 0, v3, vcc
	v_add_co_u32_e32 v2, vcc, 0x60000, v2
	v_lshl_add_u64 v[0:1], v[0:1], 0, v[184:185]
	s_nop 0
	v_addc_co_u32_e32 v3, vcc, 0, v3, vcc
	global_load_dwordx4 v[132:135], v[4:5], off
	global_load_dwordx4 v[136:139], v[6:7], off
	global_load_dwordx4 v[140:143], v[2:3], off
	global_load_dwordx4 v[144:147], v[0:1], off
	v_add_co_u32_e32 v2, vcc, s64, v0
	s_nop 1
	v_addc_co_u32_e32 v3, vcc, 0, v1, vcc
	v_add_co_u32_e32 v4, vcc, 0x40000, v0
	s_nop 1
	v_addc_co_u32_e32 v5, vcc, 0, v1, vcc
	global_load_dwordx4 v[148:151], v[2:3], off
	global_load_dwordx4 v[152:155], v[4:5], off
	v_add_co_u32_e32 v2, vcc, 0x60000, v0
	s_nop 1
	v_addc_co_u32_e32 v3, vcc, 0, v1, vcc
	v_add_co_u32_e32 v4, vcc, 0x80000, v0
	s_nop 1
	v_addc_co_u32_e32 v5, vcc, 0, v1, vcc
	global_load_dwordx4 v[156:159], v[2:3], off
	global_load_dwordx4 v[160:163], v[4:5], off
	v_add_co_u32_e32 v2, vcc, 0xa0000, v0
	s_nop 1
	v_addc_co_u32_e32 v3, vcc, 0, v1, vcc
	v_add_co_u32_e32 v4, vcc, 0xc0000, v0
	s_nop 1
	v_addc_co_u32_e32 v5, vcc, 0, v1, vcc
	v_add_co_u32_e32 v0, vcc, 0xe0000, v0
	global_load_dwordx4 v[164:167], v[2:3], off
	global_load_dwordx4 v[168:171], v[4:5], off
	v_addc_co_u32_e32 v1, vcc, 0, v1, vcc
	global_load_dwordx4 v[172:175], v[0:1], off
	s_and_b64 vcc, exec, s[2:3]
	s_cbranch_vccnz .LBB0_1725
	s_branch .LBB0_1564

; #define MFMA(a, b, c) __builtin_amdgcn_mfma_f32_32x32x16_bf16((a), (b), (c), 0, 0, 0)
; DI int TID() { int t = threadIdx.x; asm volatile("" : "+v"(t)); return t; }
; DI void gemm_main2(const bfu* __restrict__ A, const bfu* __restrict__ Bt, int K, char* smem, f32x16 (&acc)[2][4], bf16x8 (&ra)[4], bf16x8 (&rb)[8]) {
;   const int tid = TID(), lane = tid & 63, w = tid >> 6, wm = w >> 1, wn = w & 1, l32 = lane & 31, hi = lane >> 5;
;   bfu* As = (bfu*)smem; bfu* Bs = As + 128 * LDT;
;   const int sr = tid >> 3, sc = (tid & 7) * 8;
; #pragma unroll
;   for (int i = 0; i < 2; ++i)
; #pragma unroll
;     for (int j = 0; j < 4; ++j)
; #pragma unroll
;       for (int r = 0; r < 16; ++r) acc[i][j][r] = 0.f;
;   const int nk = K / BK;
;   const bfu* as = As + (wm * 64 + l32) * LDT + hi * 8;
;   const bfu* bs = Bs + (wn * 128 + l32) * LDT + hi * 8;
;   for (int kt = 0; kt < nk; ++kt) {
;     __syncthreads();
; #pragma unroll
;     for (int i = 0; i < 4; ++i) st8(As + (sr + 32 * i) * LDT + sc, ra[i]);
; #pragma unroll
;     for (int i = 0; i < 8; ++i) st8(Bs + (sr + 32 * i) * LDT + sc, rb[i]);
;     __syncthreads();
;     if (kt + 1 < nk) gemm_preload(A, Bt, K, kt + 1, ra, rb);
; #pragma unroll
;     for (int ks = 0; ks < 4; ++ks) {
;       const bf16x8 a0 = ld8(as + ks * 16), a1 = ld8(as + 32 * LDT + ks * 16);
; #pragma unroll
;       for (int j = 0; j < 4; ++j) {
;         const bf16x8 b = ld8(bs + j * 32 * LDT + ks * 16);
;         acc[0][j] = MFMA(a0, b, acc[0][j]); acc[1][j] = MFMA(a1, b, acc[1][j]);
;       }
;     }
;   }
.LBB0_1568:
	s_waitcnt lgkmcnt(0)
	s_barrier
	s_waitcnt vmcnt(0)
	ds_write_b128 v178, v[128:131]
	ds_write_b128 v178, v[132:135] offset:4608
	ds_write_b128 v178, v[136:139] offset:9216
	ds_write_b128 v178, v[140:143] offset:13824
	ds_write_b128 v178, v[144:147] offset:18432
	ds_write_b128 v178, v[148:151] offset:23040
	ds_write_b128 v178, v[152:155] offset:27648
	ds_write_b128 v178, v[156:159] offset:32256
	ds_write_b128 v178, v[160:163] offset:36864
	ds_write_b128 v178, v[164:167] offset:41472
	ds_write_b128 v178, v[168:171] offset:46080
	ds_write_b128 v178, v[172:175] offset:50688
	v_mov_b32_e32 v164, v202
	s_waitcnt lgkmcnt(0)
	s_barrier
	ds_read_b128 v[128:131], v176
	ds_read_b128 v[132:135], v177 offset:18432
	ds_read_b128 v[136:139], v176 offset:32
	ds_read_b128 v[140:143], v177 offset:18464
	ds_read_b128 v[144:147], v176 offset:4608
	ds_read_b128 v[148:151], v176 offset:4640
	s_waitcnt lgkmcnt(4)
	v_mfma_f32_32x32x16_bf16 v[112:127], v[128:131], v[132:135], v[112:127]
	s_waitcnt lgkmcnt(1)
	v_mfma_f32_32x32x16_bf16 v[48:63], v[144:147], v[132:135], v[48:63]
	ds_read_b128 v[132:135], v177 offset:23040
	ds_read_b128 v[152:155], v177 offset:23072
	s_waitcnt lgkmcnt(1)
	v_mfma_f32_32x32x16_bf16 v[96:111], v[128:131], v[132:135], v[96:111]
	v_mfma_f32_32x32x16_bf16 v[32:47], v[144:147], v[132:135], v[32:47]
	ds_read_b128 v[132:135], v177 offset:27648
	ds_read_b128 v[156:159], v177 offset:27680
	s_waitcnt lgkmcnt(1)
	v_mfma_f32_32x32x16_bf16 v[80:95], v[128:131], v[132:135], v[80:95]
	v_mfma_f32_32x32x16_bf16 v[16:31], v[144:147], v[132:135], v[16:31]
	ds_read_b128 v[132:135], v177 offset:32256
	ds_read_b128 v[160:163], v177 offset:32288
	s_waitcnt lgkmcnt(1)
	v_mfma_f32_32x32x16_bf16 v[64:79], v[128:131], v[132:135], v[64:79]
	v_mfma_f32_32x32x16_bf16 v[112:127], v[136:139], v[140:143], v[112:127]
	v_mfma_f32_32x32x16_bf16 v[48:63], v[148:151], v[140:143], v[48:63]
	v_mfma_f32_32x32x16_bf16 v[0:15], v[144:147], v[132:135], v[0:15]
	v_mfma_f32_32x32x16_bf16 v[96:111], v[136:139], v[152:155], v[96:111]
	v_mfma_f32_32x32x16_bf16 v[32:47], v[148:151], v[152:155], v[32:47]
	v_mfma_f32_32x32x16_bf16 v[80:95], v[136:139], v[156:159], v[80:95]
	s_waitcnt lgkmcnt(0)
	v_mfma_f32_32x32x16_bf16 v[64:79], v[136:139], v[160:163], v[64:79]
	ds_read_b128 v[128:131], v176 offset:64
	ds_read_b128 v[132:135], v177 offset:18496
	ds_read_b128 v[168:171], v176 offset:96
	ds_read_b128 v[136:139], v177 offset:18528
	ds_read_b128 v[140:143], v176 offset:4672
	ds_read_b128 v[180:183], v176 offset:4704
	v_mfma_f32_32x32x16_bf16 v[16:31], v[148:151], v[156:159], v[16:31]
	s_waitcnt lgkmcnt(4)
	v_mfma_f32_32x32x16_bf16 v[112:127], v[128:131], v[132:135], v[112:127]
	s_waitcnt lgkmcnt(1)
	v_mfma_f32_32x32x16_bf16 v[48:63], v[140:143], v[132:135], v[48:63]
	ds_read_b128 v[132:135], v177 offset:23104
	ds_read_b128 v[152:155], v177 offset:23136
	s_waitcnt lgkmcnt(1)
	v_mfma_f32_32x32x16_bf16 v[96:111], v[128:131], v[132:135], v[96:111]
	v_mfma_f32_32x32x16_bf16 v[32:47], v[140:143], v[132:135], v[32:47]
	ds_read_b128 v[132:135], v177 offset:27712
	ds_read_b128 v[172:175], v177 offset:27744
	s_waitcnt lgkmcnt(1)
	v_mfma_f32_32x32x16_bf16 v[80:95], v[128:131], v[132:135], v[80:95]
	v_mfma_f32_32x32x16_bf16 v[16:31], v[140:143], v[132:135], v[16:31]
	ds_read_b128 v[132:135], v177 offset:32320
	ds_read_b128 v[188:191], v177 offset:32352
	v_mfma_f32_32x32x16_bf16 v[0:15], v[148:151], v[160:163], v[0:15]
	s_waitcnt lgkmcnt(1)
	v_mfma_f32_32x32x16_bf16 v[64:79], v[128:131], v[132:135], v[64:79]
	v_ashrrev_i32_e32 v128, 3, v164
	v_ashrrev_i32_e32 v129, 31, v128
	v_lshlrev_b64 v[128:129], 12, v[128:129]
	v_and_b32_e32 v130, 7, v164
	v_lshl_or_b32 v128, v130, 4, v128
	v_lshl_add_u64 v[144:145], s[0:1], 0, v[128:129]
	v_lshl_add_u64 v[192:193], s[10:11], 0, v[144:145]
	v_mfma_f32_32x32x16_bf16 v[0:15], v[140:143], v[132:135], v[0:15]
	v_lshl_add_u64 v[140:141], s[8:9], 0, v[144:145]
	v_add_co_u32_e32 v132, vcc, s64, v140
	s_add_u32 s0, s0, 0x80
	s_nop 0
	v_addc_co_u32_e32 v133, vcc, 0, v141, vcc
	global_load_dwordx4 v[128:131], v[140:141], off offset:128
	s_nop 0
	global_load_dwordx4 v[132:135], v[132:133], off offset:128
	v_mfma_f32_32x32x16_bf16 v[112:127], v[168:171], v[136:139], v[112:127]
	s_addc_u32 s1, s1, 0
	s_cmpk_lg_i32 s0, 0xf80
	v_mfma_f32_32x32x16_bf16 v[48:63], v[180:183], v[136:139], v[48:63]
	v_add_co_u32_e32 v136, vcc, s65, v140
	s_nop 1
	v_addc_co_u32_e32 v137, vcc, 0, v141, vcc
	v_add_co_u32_e32 v140, vcc, s66, v140
	v_mfma_f32_32x32x16_bf16 v[96:111], v[168:171], v[152:155], v[96:111]
	s_nop 0
	v_addc_co_u32_e32 v141, vcc, 0, v141, vcc
	v_add_co_u32_e32 v148, vcc, s64, v192
	global_load_dwordx4 v[136:139], v[136:137], off offset:128
	s_nop 0
	global_load_dwordx4 v[140:143], v[140:141], off offset:128
	v_addc_co_u32_e32 v149, vcc, 0, v193, vcc
	v_mfma_f32_32x32x16_bf16 v[32:47], v[180:183], v[152:155], v[32:47]
	v_add_co_u32_e32 v152, vcc, s65, v192
	global_load_dwordx4 v[144:147], v[192:193], off offset:128
	s_nop 0
	global_load_dwordx4 v[148:151], v[148:149], off offset:128
	v_addc_co_u32_e32 v153, vcc, 0, v193, vcc
	v_add_co_u32_e32 v156, vcc, s66, v192
	v_mfma_f32_32x32x16_bf16 v[80:95], v[168:171], v[172:175], v[80:95]
	s_nop 0
	v_addc_co_u32_e32 v157, vcc, 0, v193, vcc
	v_add_co_u32_e32 v160, vcc, s67, v192
	global_load_dwordx4 v[152:155], v[152:153], off offset:128
	s_nop 0
	global_load_dwordx4 v[156:159], v[156:157], off offset:128
	v_addc_co_u32_e32 v161, vcc, 0, v193, vcc
	v_add_co_u32_e32 v164, vcc, s72, v192
	v_mfma_f32_32x32x16_bf16 v[16:31], v[180:183], v[172:175], v[16:31]
	s_nop 0
	v_addc_co_u32_e32 v165, vcc, 0, v193, vcc
	v_add_co_u32_e32 v172, vcc, s73, v192
	global_load_dwordx4 v[160:163], v[160:161], off offset:128
	s_nop 0
	global_load_dwordx4 v[164:167], v[164:165], off offset:128
	v_addc_co_u32_e32 v173, vcc, 0, v193, vcc
	v_add_co_u32_e32 v174, vcc, s77, v192
	s_waitcnt lgkmcnt(0)
	v_mfma_f32_32x32x16_bf16 v[64:79], v[168:171], v[188:191], v[64:79]
	v_addc_co_u32_e32 v175, vcc, 0, v193, vcc
	global_load_dwordx4 v[168:171], v[172:173], off offset:128
	s_nop 0
	global_load_dwordx4 v[172:175], v[174:175], off offset:128
	v_mfma_f32_32x32x16_bf16 v[0:15], v[180:183], v[188:191], v[0:15]
	s_cbranch_scc1 .LBB0_1568
; #define MFMA(a, b, c) __builtin_amdgcn_mfma_f32_32x32x16_bf16((a), (b), (c), 0, 0, 0)
; DI int TID() { int t = threadIdx.x; asm volatile("" : "+v"(t)); return t; }
; DI void gemm_main2(const bfu* __restrict__ A, const bfu* __restrict__ Bt, int K, char* smem, f32x16 (&acc)[2][4], bf16x8 (&ra)[4], bf16x8 (&rb)[8]) {
;     ...
;   for (int kt = 0; kt < nk; ++kt) {
;     __syncthreads();
; #pragma unroll
;     for (int i = 0; i < 4; ++i) st8(As + (sr + 32 * i) * LDT + sc, ra[i]);
; #pragma unroll
;     for (int i = 0; i < 8; ++i) st8(Bs + (sr + 32 * i) * LDT + sc, rb[i]);
;     __syncthreads();
;     if (kt + 1 < nk) gemm_preload(A, Bt, K, kt + 1, ra, rb);
; #pragma unroll
;     for (int ks = 0; ks < 4; ++ks) {
;       const bf16x8 a0 = ld8(as + ks * 16), a1 = ld8(as + 32 * LDT + ks * 16);
; #pragma unroll
;       for (int j = 0; j < 4; ++j) {
;         const bf16x8 b = ld8(bs + j * 32 * LDT + ks * 16);
;         acc[0][j] = MFMA(a0, b, acc[0][j]); acc[1][j] = MFMA(a1, b, acc[1][j]);
;       }
;     }
; DI void phase_gemm(const Params& p, int g, int kind, char* smem, float* rsl, int* s_item, int vlo, int vhi, int cslot) {
;     ...
;   auto fetch = [&](TD& d) {
;     for (;;) {
;       __syncthreads();
;       if (TID() == 0) *s_item = atomicAdd(qctr, 1);
;       __syncthreads();
	s_barrier
	s_waitcnt vmcnt(0)
	ds_write_b128 v178, v[128:131]
	ds_write_b128 v178, v[132:135] offset:4608
	ds_write_b128 v178, v[136:139] offset:9216
	ds_write_b128 v178, v[140:143] offset:13824
	ds_write_b128 v178, v[144:147] offset:18432
	ds_write_b128 v178, v[148:151] offset:23040
	ds_write_b128 v178, v[152:155] offset:27648
	ds_write_b128 v178, v[156:159] offset:32256
	ds_write_b128 v178, v[160:163] offset:36864
	ds_write_b128 v178, v[164:167] offset:41472
	ds_write_b128 v178, v[168:171] offset:46080
	ds_write_b128 v178, v[172:175] offset:50688
	s_waitcnt lgkmcnt(0)
	s_barrier
	ds_read_b128 v[178:181], v176
	ds_read_b128 v[188:191], v177 offset:18432
	ds_read_b128 v[192:195], v176 offset:4608
	s_waitcnt lgkmcnt(1)
	v_mfma_f32_32x32x16_bf16 v[112:127], v[178:181], v[188:191], v[112:127]
	s_waitcnt lgkmcnt(0)
	v_mfma_f32_32x32x16_bf16 v[48:63], v[192:195], v[188:191], v[48:63]
	ds_read_b128 v[188:191], v177 offset:23040
	s_waitcnt lgkmcnt(0)
	v_mfma_f32_32x32x16_bf16 v[96:111], v[178:181], v[188:191], v[96:111]
	v_mfma_f32_32x32x16_bf16 v[32:47], v[192:195], v[188:191], v[32:47]
	ds_read_b128 v[188:191], v177 offset:27648
	s_waitcnt lgkmcnt(0)
	v_mfma_f32_32x32x16_bf16 v[80:95], v[178:181], v[188:191], v[80:95]
	v_mfma_f32_32x32x16_bf16 v[16:31], v[192:195], v[188:191], v[16:31]
	ds_read_b128 v[188:191], v177 offset:32256
	s_waitcnt lgkmcnt(0)
	v_mfma_f32_32x32x16_bf16 v[64:79], v[178:181], v[188:191], v[64:79]
	v_mfma_f32_32x32x16_bf16 v[0:15], v[192:195], v[188:191], v[0:15]
	ds_read_b128 v[178:181], v176 offset:32
	ds_read_b128 v[188:191], v177 offset:18464
	ds_read_b128 v[192:195], v176 offset:4640
	s_waitcnt lgkmcnt(1)
	v_mfma_f32_32x32x16_bf16 v[112:127], v[178:181], v[188:191], v[112:127]
	s_waitcnt lgkmcnt(0)
	v_mfma_f32_32x32x16_bf16 v[48:63], v[192:195], v[188:191], v[48:63]
	ds_read_b128 v[188:191], v177 offset:23072
	s_waitcnt lgkmcnt(0)
	v_mfma_f32_32x32x16_bf16 v[96:111], v[178:181], v[188:191], v[96:111]
	v_mfma_f32_32x32x16_bf16 v[32:47], v[192:195], v[188:191], v[32:47]
	ds_read_b128 v[188:191], v177 offset:27680
	s_waitcnt lgkmcnt(0)
	v_mfma_f32_32x32x16_bf16 v[80:95], v[178:181], v[188:191], v[80:95]
	v_mfma_f32_32x32x16_bf16 v[16:31], v[192:195], v[188:191], v[16:31]
	ds_read_b128 v[188:191], v177 offset:32288
	s_waitcnt lgkmcnt(0)
	v_mfma_f32_32x32x16_bf16 v[64:79], v[178:181], v[188:191], v[64:79]
	v_mfma_f32_32x32x16_bf16 v[0:15], v[192:195], v[188:191], v[0:15]
	ds_read_b128 v[178:181], v176 offset:64
	ds_read_b128 v[188:191], v177 offset:18496
	ds_read_b128 v[192:195], v176 offset:4672
	s_waitcnt lgkmcnt(1)
	v_mfma_f32_32x32x16_bf16 v[112:127], v[178:181], v[188:191], v[112:127]
	s_waitcnt lgkmcnt(0)
	v_mfma_f32_32x32x16_bf16 v[48:63], v[192:195], v[188:191], v[48:63]
	ds_read_b128 v[188:191], v177 offset:23104
	s_waitcnt lgkmcnt(0)
	v_mfma_f32_32x32x16_bf16 v[96:111], v[178:181], v[188:191], v[96:111]
	v_mfma_f32_32x32x16_bf16 v[32:47], v[192:195], v[188:191], v[32:47]
	ds_read_b128 v[188:191], v177 offset:27712
	s_waitcnt lgkmcnt(0)
	v_mfma_f32_32x32x16_bf16 v[80:95], v[178:181], v[188:191], v[80:95]
	v_mfma_f32_32x32x16_bf16 v[16:31], v[192:195], v[188:191], v[16:31]
	ds_read_b128 v[188:191], v177 offset:32320
	s_waitcnt lgkmcnt(0)
	v_mfma_f32_32x32x16_bf16 v[64:79], v[178:181], v[188:191], v[64:79]
	v_mfma_f32_32x32x16_bf16 v[0:15], v[192:195], v[188:191], v[0:15]
	ds_read_b128 v[178:181], v176 offset:96
	ds_read_b128 v[188:191], v177 offset:18528
	ds_read_b128 v[192:195], v176 offset:4704
	v_mov_b32_e32 v176, v202
	s_waitcnt lgkmcnt(1)
	v_mfma_f32_32x32x16_bf16 v[112:127], v[178:181], v[188:191], v[112:127]
	s_waitcnt lgkmcnt(0)
	v_mfma_f32_32x32x16_bf16 v[48:63], v[192:195], v[188:191], v[48:63]
	ds_read_b128 v[188:191], v177 offset:23136
	s_waitcnt lgkmcnt(0)
	v_mfma_f32_32x32x16_bf16 v[96:111], v[178:181], v[188:191], v[96:111]
	v_mfma_f32_32x32x16_bf16 v[32:47], v[192:195], v[188:191], v[32:47]
	ds_read_b128 v[188:191], v177 offset:27744
	s_waitcnt lgkmcnt(0)
	v_mfma_f32_32x32x16_bf16 v[80:95], v[178:181], v[188:191], v[80:95]
	v_mfma_f32_32x32x16_bf16 v[16:31], v[192:195], v[188:191], v[16:31]
	ds_read_b128 v[188:191], v177 offset:32352
	s_waitcnt lgkmcnt(0)
	s_barrier
	s_nop 0
	v_cmp_eq_u32_e32 vcc, 0, v176
	v_mfma_f32_32x32x16_bf16 v[64:79], v[178:181], v[188:191], v[64:79]
	v_mfma_f32_32x32x16_bf16 v[0:15], v[192:195], v[188:191], v[0:15]
	s_and_saveexec_b64 s[0:1], vcc
	s_cbranch_execz .LBB0_1573
	s_mov_b64 s[16:17], exec
	v_mbcnt_lo_u32_b32 v176, s16, 0
	v_mbcnt_hi_u32_b32 v176, s17, v176
	v_cmp_eq_u32_e32 vcc, 0, v176
	s_and_saveexec_b64 s[2:3], vcc
	s_cbranch_execz .LBB0_1572
	s_bcnt1_i32_b64 s5, s[16:17]
	v_mov_b32_e32 v177, s5
	global_atomic_add v177, v185, v177, s[88:89] offset:128 sc0

; DI int TID() { int t = threadIdx.x; asm volatile("" : "+v"(t)); return t; }
; DI bf16x8 pack8f(const float* v) { u32x4 w = {cvtpk(v[0], v[1]), cvtpk(v[2], v[3]), cvtpk(v[4], v[5]), cvtpk(v[6], v[7])}; return __builtin_bit_cast(bf16x8, w); }
; DI void store_R(const float* Cs, int cb, int nc, bfu* dst, long ld, float scale, const float* rs = nullptr) {
;   const int cpr = nc >> 3;
;   for (int u = TID(); u < 128 * cpr; u += NT) {
;     int row = u / cpr, c8 = (u % cpr) * 8; float v[8]; ldrow8(Cs, row, cb + c8, v);
;     float s = rs ? scale * rs[row] : scale;
;     for (int j = 0; j < 8; ++j) v[j] *= s;
;     st8(dst + row * ld + c8, pack8f(v));
;   }
; }
; DI void epi_in1(const Params& p, float* Cs, int m0, int n0) {
;     ...
;     store_R(Cs, 0, 64, dst + par * 64, 256, sc); store_R(Cs, 64, 64, dst + 128 + par * 64, 256, sc);
.LBB0_1639:
	v_ashrrev_i32_e32 v181, 31, v179
	v_lshrrev_b32_e32 v181, 29, v181
	v_add_u32_e32 v182, 0x100, v179
	v_add_u32_e32 v181, v179, v181
	v_cmp_lt_i32_e32 vcc, s87, v179
	v_mov_b32_e32 v179, v182
	v_ashrrev_i32_e32 v182, 3, v181
	v_mad_u64_u32 v[192:193], s[68:69], v182, s60, v[178:179]
	ds_read_b128 v[188:191], v192
	ds_read_b128 v[192:195], v192 offset:16
	v_lshlrev_b32_e32 v181, 6, v182
	v_ashrrev_i32_e32 v183, 31, v182
	v_sub_u32_e32 v196, v180, v181
	v_lshlrev_b64 v[182:183], 9, v[182:183]
	v_lshl_add_u64 v[182:183], s[2:3], 0, v[182:183]
	v_ashrrev_i32_e32 v197, 31, v196
	s_waitcnt lgkmcnt(0)
	v_pk_mul_f32 v[188:189], v[176:177], v[188:189]
	v_pk_mul_f32 v[190:191], v[176:177], v[190:191]
	v_pk_mul_f32 v[192:193], v[176:177], v[192:193]
	v_pk_mul_f32 v[194:195], v[176:177], v[194:195]
	s_or_b64 s[36:37], vcc, s[36:37]
	v_add_u32_e32 v178, 0x2000, v178
	v_add_u32_e32 v180, 0x800, v180
	v_lshl_add_u64 v[182:183], v[196:197], 1, v[182:183]
	v_cvt_pk_bf16_f32 v188, v188, v189
	v_cvt_pk_bf16_f32 v189, v190, v191
	v_cvt_pk_bf16_f32 v190, v192, v193
	v_cvt_pk_bf16_f32 v191, v194, v195
	global_store_dwordx4 v[182:183], v[188:191], off
	s_andn2_b64 exec, exec, s[36:37]
	s_cbranch_execnz .LBB0_1639

; DI int TID() { int t = threadIdx.x; asm volatile("" : "+v"(t)); return t; }
; DI bf16x8 pack8f(const float* v) { u32x4 w = {cvtpk(v[0], v[1]), cvtpk(v[2], v[3]), cvtpk(v[4], v[5]), cvtpk(v[6], v[7])}; return __builtin_bit_cast(bf16x8, w); }
; DI void store_R(const float* Cs, int cb, int nc, bfu* dst, long ld, float scale, const float* rs = nullptr) {
;   const int cpr = nc >> 3;
;   for (int u = TID(); u < 128 * cpr; u += NT) {
;     int row = u / cpr, c8 = (u % cpr) * 8; float v[8]; ldrow8(Cs, row, cb + c8, v);
;     float s = rs ? scale * rs[row] : scale;
;     for (int j = 0; j < 8; ++j) v[j] *= s;
;     st8(dst + row * ld + c8, pack8f(v));
;   }
; }
; DI void epi_in1(const Params& p, float* Cs, int m0, int n0) {
;     ...
;     store_R(Cs, 0, 64, dst + par * 64, 256, sc); store_R(Cs, 64, 64, dst + 128 + par * 64, 256, sc);
.LBB0_1642:
	v_ashrrev_i32_e32 v181, 31, v179
	v_lshrrev_b32_e32 v181, 29, v181
	v_add_u32_e32 v182, 0x100, v179
	v_add_u32_e32 v181, v179, v181
	v_cmp_lt_i32_e32 vcc, s87, v179
	v_mov_b32_e32 v179, v182
	v_ashrrev_i32_e32 v182, 3, v181
	v_mad_u64_u32 v[192:193], s[68:69], v182, s60, v[178:179]
	ds_read_b128 v[188:191], v192
	ds_read_b128 v[192:195], v192 offset:16
	v_lshlrev_b32_e32 v181, 6, v182
	v_ashrrev_i32_e32 v183, 31, v182
	v_sub_u32_e32 v196, v180, v181
	v_lshlrev_b64 v[182:183], 9, v[182:183]
	v_lshl_add_u64 v[182:183], s[2:3], 0, v[182:183]
	v_ashrrev_i32_e32 v197, 31, v196
	s_waitcnt lgkmcnt(0)
	v_pk_mul_f32 v[188:189], v[176:177], v[188:189]
	v_pk_mul_f32 v[190:191], v[176:177], v[190:191]
	v_pk_mul_f32 v[192:193], v[176:177], v[192:193]
	v_pk_mul_f32 v[194:195], v[176:177], v[194:195]
	s_or_b64 s[36:37], vcc, s[36:37]
	v_add_u32_e32 v178, 0x2000, v178
	v_add_u32_e32 v180, 0x800, v180
	v_lshl_add_u64 v[182:183], v[196:197], 1, v[182:183]
	v_cvt_pk_bf16_f32 v188, v188, v189
	v_cvt_pk_bf16_f32 v189, v190, v191
	v_cvt_pk_bf16_f32 v190, v192, v193
	v_cvt_pk_bf16_f32 v191, v194, v195
	global_store_dwordx4 v[182:183], v[188:191], off offset:256
	s_andn2_b64 exec, exec, s[36:37]
	s_cbranch_execnz .LBB0_1642

;   DI const float* c() const { return (const float*)sp[1]; }
; DI int TID() { int t = threadIdx.x; asm volatile("" : "+v"(t)); return t; }
; DI bf16x8 pack8f(const float* v) { u32x4 w = {cvtpk(v[0], v[1]), cvtpk(v[2], v[3]), cvtpk(v[4], v[5]), cvtpk(v[6], v[7])}; return __builtin_bit_cast(bf16x8, w); }
; DI void store_T(const float* Cs, int cb, int nc, bfu* dst, long ldT, float scale, const float* rs = nullptr) {
;   for (int u = TID(); u < nc * 16; u += NT) {
;     int c = u % nc, rc = (u / nc) * 8; float v[8];
;     for (int j = 0; j < 8; ++j) v[j] = Cs[(rc + j) * CLD + cb + c] * (rs ? scale * rs[rc + j] : scale);
;     st8(dst + c * ldT + rc, pack8f(v));
;   }
; }
; DI void epi_in1(const Params& p, float* Cs, int m0, int n0) {
;     ...
;       store_T(Cs, 0, 64, dT + (long)(par * 64) * T, T, sc); store_T(Cs, 64, 64, dT + (long)(128 + par * 64) * T, T, sc);
.LBB0_1646:
	v_ashrrev_i32_e32 v179, 31, v177
	v_lshrrev_b32_e32 v179, 26, v179
	v_add_u32_e32 v179, v177, v179
	v_add_u32_e32 v180, 0x100, v177
	v_ashrrev_i32_e32 v179, 6, v179
	v_cmp_lt_i32_e32 vcc, s87, v177
	v_mov_b32_e32 v177, v180
	v_mad_u64_u32 v[182:183], s[36:37], v179, s35, v[178:179]
	v_lshlrev_b32_e32 v180, 3, v179
	v_mad_u64_u32 v[188:189], s[36:37], v179, s63, v[176:177]
	v_add_u32_e32 v179, 0x400, v182
	v_add_u32_e32 v194, 0xc00, v182
	ds_read2_b32 v[190:191], v182 offset1:132
	s_waitcnt lgkmcnt(0)
	v_add_u32_e32 v184, 0x800, v182
	ds_read2_b32 v[182:183], v179 offset0:8 offset1:140
	ds_read2_b32 v[192:193], v184 offset0:16 offset1:148
	ds_read2_b32 v[194:195], v194 offset0:24 offset1:156
	v_ashrrev_i32_e32 v189, 31, v188
	v_ashrrev_i32_e32 v181, 31, v180
	v_lshl_add_u64 v[188:189], s[2:3], 0, v[188:189]
	v_lshl_add_u64 v[188:189], v[180:181], 1, v[188:189]
	v_pk_mul_f32 v[180:181], v[190:191], s[76:77] op_sel_hi:[1,0]
	s_waitcnt lgkmcnt(0)
	v_pk_mul_f32 v[182:183], v[182:183], s[76:77] op_sel_hi:[1,0]
	v_pk_mul_f32 v[190:191], v[192:193], s[76:77] op_sel_hi:[1,0]
	v_pk_mul_f32 v[192:193], v[194:195], s[76:77] op_sel_hi:[1,0]
	s_or_b64 s[30:31], vcc, s[30:31]
	v_add_u32_e32 v176, 0x120000, v176
	v_add_u32_e32 v178, 0x400, v178
	v_cvt_pk_bf16_f32 v180, v180, v181
	v_cvt_pk_bf16_f32 v181, v182, v183
	v_cvt_pk_bf16_f32 v182, v190, v191
	v_cvt_pk_bf16_f32 v183, v192, v193
	global_store_dwordx4 v[188:189], v[180:183], off
	s_andn2_b64 exec, exec, s[30:31]
	s_cbranch_execnz .LBB0_1646

; DI int TID() { int t = threadIdx.x; asm volatile("" : "+v"(t)); return t; }
; DI void gemm_preload(const bfu* __restrict__ A, const bfu* __restrict__ Bt, int K, int kt, bf16x8 (&ra)[4], bf16x8 (&rb)[8]) {
;   const int tid = TID(), sr = tid >> 3, sc = (tid & 7) * 8;
;   const bfu* Ag = A + (long)sr * K + sc + kt * BK; const bfu* Bg = Bt + (long)sr * K + sc + kt * BK;
; #pragma unroll
;   for (int i = 0; i < 4; ++i) ra[i] = ld8(Ag + (long)(32 * i) * K);
; #pragma unroll
;   for (int i = 0; i < 8; ++i) rb[i] = ld8(Bg + (long)(32 * i) * K);
; }
; DI void phase_gemm(const Params& p, int g, int kind, char* smem, float* rsl, int* s_item, int vlo, int vhi, int cslot) {
;     ...
;   TD cur; fetch(cur);
;   bf16x8 ra[4], rb[8];
;   if (cur.ok) gemm_preload(cur.A, cur.Bt, cur.K, 0, ra, rb);
.LBB0_1734:
	v_cndmask_b32_e64 v0, 0, 1, s[14:15]
	v_cmp_ne_u32_e64 s[2:3], 1, v0
	s_andn2_b64 vcc, exec, s[14:15]
	s_cbranch_vccnz .LBB0_1736
	v_mov_b32_e32 v4, v202
	s_ashr_i32 s7, s6, 31
	v_ashrrev_i32_e32 v0, 3, v4
	v_mad_i64_i32 v[0:1], s[14:15], v0, s6, 0
	v_lshlrev_b64 v[0:1], 1, v[0:1]
	v_lshlrev_b32_e32 v4, 4, v4
	v_lshl_add_u64 v[2:3], s[10:11], 0, v[0:1]
	v_and_b32_e32 v184, 0x70, v4
	v_lshl_add_u64 v[2:3], v[2:3], 0, v[184:185]
	s_lshl_b64 s[14:15], s[6:7], 6
	s_waitcnt vmcnt(0)
	global_load_dwordx4 v[128:131], v[2:3], off
	v_lshl_add_u64 v[2:3], v[2:3], 0, s[14:15]
	v_lshl_add_u64 v[0:1], s[12:13], 0, v[0:1]
	v_lshl_add_u64 v[4:5], v[2:3], 0, s[14:15]
	v_lshl_add_u64 v[0:1], v[0:1], 0, v[184:185]
	global_load_dwordx4 v[132:135], v[2:3], off
	global_load_dwordx4 v[136:139], v[4:5], off
	v_lshl_add_u64 v[2:3], v[4:5], 0, s[14:15]
	global_load_dwordx4 v[140:143], v[2:3], off
	global_load_dwordx4 v[144:147], v[0:1], off
	v_lshl_add_u64 v[0:1], v[0:1], 0, s[14:15]
	v_lshl_add_u64 v[2:3], v[0:1], 0, s[14:15]
	global_load_dwordx4 v[148:151], v[0:1], off
	global_load_dwordx4 v[152:155], v[2:3], off
	v_lshl_add_u64 v[0:1], v[2:3], 0, s[14:15]
	v_lshl_add_u64 v[2:3], v[0:1], 0, s[14:15]
	global_load_dwordx4 v[156:159], v[0:1], off
	global_load_dwordx4 v[160:163], v[2:3], off
	v_lshl_add_u64 v[0:1], v[2:3], 0, s[14:15]
	v_lshl_add_u64 v[2:3], v[0:1], 0, s[14:15]
	global_load_dwordx4 v[164:167], v[0:1], off
	global_load_dwordx4 v[168:171], v[2:3], off
	v_lshl_add_u64 v[0:1], v[2:3], 0, s[14:15]
	global_load_dwordx4 v[172:175], v[0:1], off
	s_and_b64 vcc, exec, s[2:3]
	s_cbranch_vccnz .LBB0_2018
	s_branch .LBB0_1737

; DI int TID() { int t = threadIdx.x; asm volatile("" : "+v"(t)); return t; }
; DI void phase_gemm(const Params& p, int g, int kind, char* smem, float* rsl, int* s_item, int vlo, int vhi, int cslot) {
;     ...
;     if (kind == 2) {
;       const bool uq = nt < 12;
;       __syncthreads();
;       if (TID() < 128) {
;         float s;
;         if (uq) { const float* q = (const float*)(G + L1_SM + SM_SSQ) + (long)(m0 + TID()) * 4; s = (q[0] + q[1] + q[2] + q[3]) * (1.f / 512.f); }
;         else { const float* q = (const float*)(G + L1_SM + SM_SSK) + (long)(m0 + TID()) * 2; s = (q[0] + q[1]) * (1.f / 256.f); }
;         rsl[TID()] = rsqrtf(s + EPS);
;       }
.LBB0_1740:
	v_mov_b32_e32 v0, v202
	s_mov_b32 s22, s40
	s_mov_b32 s47, s4
	s_mov_b32 s23, s8
	s_waitcnt lgkmcnt(0)
	s_barrier
	s_nop 0
	v_cmp_gt_i32_e32 vcc, s70, v0
	s_and_saveexec_b64 s[2:3], vcc
	s_cbranch_execz .LBB0_1746
	s_cmp_gt_i32 s22, 11
	s_mov_b64 s[18:19], -1
	s_cbranch_scc0 .LBB0_1743
	v_mov_b32_e32 v0, v202
	s_mov_b64 s[18:19], 0
	v_add_u32_e32 v0, s23, v0
	v_ashrrev_i32_e32 v1, 31, v0
	v_lshl_add_u64 v[0:1], v[0:1], 3, s[14:15]
	global_load_dwordx2 v[0:1], v[0:1], off
	s_waitcnt vmcnt(0) lgkmcnt(0)
	v_add_f32_e32 v0, v0, v1
	v_mul_f32_e32 v0, 0x3b800000, v0
.LBB0_1743:
	s_andn2_b64 vcc, exec, s[18:19]
	s_cbranch_vccnz .LBB0_1745
	v_mov_b32_e32 v0, v202
	s_nop 0
	v_add_u32_e32 v0, s23, v0
	v_ashrrev_i32_e32 v1, 31, v0
	v_lshl_add_u64 v[0:1], v[0:1], 4, s[16:17]
	global_load_dwordx4 v[0:3], v[0:1], off
	s_waitcnt vmcnt(0) lgkmcnt(0)
	v_add_f32_e32 v0, v0, v1
	v_add_f32_e32 v0, v0, v2
	v_add_f32_e32 v0, v0, v3
	v_mul_f32_e32 v0, 0x3b000000, v0

; DI int TID() { int t = threadIdx.x; asm volatile("" : "+v"(t)); return t; }
; DI void gemm_preload(const bfu* __restrict__ A, const bfu* __restrict__ Bt, int K, int kt, bf16x8 (&ra)[4], bf16x8 (&rb)[8]) {
;   const int tid = TID(), sr = tid >> 3, sc = (tid & 7) * 8;
;   const bfu* Ag = A + (long)sr * K + sc + kt * BK; const bfu* Bg = Bt + (long)sr * K + sc + kt * BK;
; #pragma unroll
;   for (int i = 0; i < 4; ++i) ra[i] = ld8(Ag + (long)(32 * i) * K);
; #pragma unroll
;   for (int i = 0; i < 8; ++i) rb[i] = ld8(Bg + (long)(32 * i) * K);
; }
; DI void gemm_main2(const bfu* __restrict__ A, const bfu* __restrict__ Bt, int K, char* smem, f32x16 (&acc)[2][4], bf16x8 (&ra)[4], bf16x8 (&rb)[8]) {
;     ...
;   for (int kt = 0; kt < nk; ++kt) {
;     __syncthreads();
; #pragma unroll
;     for (int i = 0; i < 4; ++i) st8(As + (sr + 32 * i) * LDT + sc, ra[i]);
; #pragma unroll
;     for (int i = 0; i < 8; ++i) st8(Bs + (sr + 32 * i) * LDT + sc, rb[i]);
;     __syncthreads();
;     if (kt + 1 < nk) gemm_preload(A, Bt, K, kt + 1, ra, rb);
.LBB0_1748:
	s_add_i32 s7, s7, 1
	s_cmp_ge_i32 s7, s5
	s_waitcnt lgkmcnt(0)
	s_barrier
	s_waitcnt vmcnt(0)
	ds_write_b128 v178, v[128:131]
	ds_write_b128 v178, v[132:135] offset:4608
	ds_write_b128 v178, v[136:139] offset:9216
	ds_write_b128 v178, v[140:143] offset:13824
	ds_write_b128 v178, v[144:147] offset:18432
	ds_write_b128 v178, v[148:151] offset:23040
	ds_write_b128 v178, v[152:155] offset:27648
	ds_write_b128 v178, v[156:159] offset:32256
	ds_write_b128 v178, v[160:163] offset:36864
	ds_write_b128 v178, v[164:167] offset:41472
	ds_write_b128 v178, v[168:171] offset:46080
	ds_write_b128 v178, v[172:175] offset:50688
	s_waitcnt lgkmcnt(0)
	s_barrier
	s_cbranch_scc1 .LBB0_1747
	v_mov_b32_e32 v132, v202
	s_nop 0
	v_ashrrev_i32_e32 v128, 3, v132
	v_ashrrev_i32_e32 v131, 31, v128
	v_mad_u64_u32 v[128:129], s[20:21], v128, s6, 0
	v_mov_b32_e32 v130, v129
	v_mad_u64_u32 v[130:131], s[20:21], v131, s6, v[130:131]
	v_mov_b32_e32 v129, v130
	v_lshlrev_b64 v[128:129], 1, v[128:129]
	v_lshlrev_b32_e32 v132, 4, v132
	v_lshl_add_u64 v[130:131], s[10:11], 0, v[128:129]
	v_and_b32_e32 v184, 0x70, v132
	v_lshl_add_u64 v[130:131], v[130:131], 0, v[184:185]
	s_lshl_b64 s[20:21], s[42:43], 1
	v_lshl_add_u64 v[130:131], v[130:131], 0, s[20:21]
	v_lshl_add_u64 v[128:129], s[12:13], 0, v[128:129]
	v_lshl_add_u64 v[144:145], v[128:129], 0, v[184:185]
	v_lshl_add_u64 v[136:137], v[130:131], 0, s[18:19]
	global_load_dwordx4 v[128:131], v[130:131], off
	s_nop 0
	global_load_dwordx4 v[132:135], v[136:137], off
	v_lshl_add_u64 v[136:137], v[136:137], 0, s[2:3]
	v_lshl_add_u64 v[144:145], v[144:145], 0, s[20:21]
	v_lshl_add_u64 v[140:141], v[136:137], 0, s[2:3]
	v_lshl_add_u64 v[152:153], v[144:145], 0, s[18:19]
	global_load_dwordx4 v[136:139], v[136:137], off
	s_nop 0
	global_load_dwordx4 v[140:143], v[140:141], off
	s_nop 0
	global_load_dwordx4 v[144:147], v[144:145], off
	s_nop 0
	global_load_dwordx4 v[148:151], v[152:153], off
	v_lshl_add_u64 v[152:153], v[152:153], 0, s[2:3]
	v_lshl_add_u64 v[160:161], v[152:153], 0, s[2:3]
	global_load_dwordx4 v[152:155], v[152:153], off
	s_nop 0
	global_load_dwordx4 v[156:159], v[160:161], off
	v_lshl_add_u64 v[160:161], v[160:161], 0, s[2:3]
	v_lshl_add_u64 v[168:169], v[160:161], 0, s[2:3]
	global_load_dwordx4 v[160:163], v[160:161], off
	s_nop 0
	global_load_dwordx4 v[164:167], v[168:169], off
	v_lshl_add_u64 v[168:169], v[168:169], 0, s[2:3]
	v_lshl_add_u64 v[172:173], v[168:169], 0, s[2:3]
	global_load_dwordx4 v[168:171], v[168:169], off
	s_nop 0
	global_load_dwordx4 v[172:175], v[172:173], off
	s_branch .LBB0_1747

; DI int TID() { int t = threadIdx.x; asm volatile("" : "+v"(t)); return t; }
; DI void gemm_preload(const bfu* __restrict__ A, const bfu* __restrict__ Bt, int K, int kt, bf16x8 (&ra)[4], bf16x8 (&rb)[8]) {
;   const int tid = TID(), sr = tid >> 3, sc = (tid & 7) * 8;
;   const bfu* Ag = A + (long)sr * K + sc + kt * BK; const bfu* Bg = Bt + (long)sr * K + sc + kt * BK;
; #pragma unroll
;   for (int i = 0; i < 4; ++i) ra[i] = ld8(Ag + (long)(32 * i) * K);
; #pragma unroll
;   for (int i = 0; i < 8; ++i) rb[i] = ld8(Bg + (long)(32 * i) * K);
; }
; DI void phase_gemm(const Params& p, int g, int kind, char* smem, float* rsl, int* s_item, int vlo, int vhi, int cslot) {
;     ...
;     TD nxt; fetch(nxt);
;     if (nxt.ok) gemm_preload(nxt.A, nxt.Bt, nxt.K, 0, ra, rb);
; #pragma unroll
;     for (int h = 0; h < 2; ++h) {
;       if (nt * 2 + h >= nvalid) break;
.LBB0_1758:
	s_waitcnt vmcnt(0)
	v_mov_b32_e32 v132, v202
	s_ashr_i32 s7, s6, 31
	v_ashrrev_i32_e32 v128, 3, v132
	v_mad_i64_i32 v[128:129], s[2:3], v128, s6, 0
	v_lshlrev_b64 v[128:129], 1, v[128:129]
	v_lshlrev_b32_e32 v132, 4, v132
	v_lshl_add_u64 v[130:131], s[10:11], 0, v[128:129]
	v_and_b32_e32 v184, 0x70, v132
	v_lshl_add_u64 v[132:133], v[130:131], 0, v[184:185]
	v_lshl_add_u64 v[128:129], s[12:13], 0, v[128:129]
	s_lshl_b64 s[2:3], s[6:7], 6
	v_lshl_add_u64 v[148:149], v[128:129], 0, v[184:185]
	global_load_dwordx4 v[128:131], v[132:133], off
	v_lshl_add_u64 v[132:133], v[132:133], 0, s[2:3]
	v_lshl_add_u64 v[140:141], v[132:133], 0, s[2:3]
	global_load_dwordx4 v[132:135], v[132:133], off
	s_nop 0
	global_load_dwordx4 v[136:139], v[140:141], off
	v_lshl_add_u64 v[140:141], v[140:141], 0, s[2:3]
	global_load_dwordx4 v[140:143], v[140:141], off
	s_nop 0
	global_load_dwordx4 v[144:147], v[148:149], off
	v_lshl_add_u64 v[148:149], v[148:149], 0, s[2:3]
	v_lshl_add_u64 v[156:157], v[148:149], 0, s[2:3]
	global_load_dwordx4 v[148:151], v[148:149], off
	s_nop 0
	global_load_dwordx4 v[152:155], v[156:157], off
	v_lshl_add_u64 v[156:157], v[156:157], 0, s[2:3]
	v_lshl_add_u64 v[164:165], v[156:157], 0, s[2:3]
	global_load_dwordx4 v[156:159], v[156:157], off
	s_nop 0
	global_load_dwordx4 v[160:163], v[164:165], off
	v_lshl_add_u64 v[164:165], v[164:165], 0, s[2:3]
	v_lshl_add_u64 v[172:173], v[164:165], 0, s[2:3]
	global_load_dwordx4 v[164:167], v[164:165], off
	s_nop 0
	global_load_dwordx4 v[168:171], v[172:173], off
	v_lshl_add_u64 v[172:173], v[172:173], 0, s[2:3]
	global_load_dwordx4 v[172:175], v[172:173], off
	s_cmp_gt_i32 s22, 27
	s_cbranch_scc1 .LBB0_1739
	s_branch .LBB0_1762

; DI int TID() { int t = threadIdx.x; asm volatile("" : "+v"(t)); return t; }
; DI unsigned cvtpk(float lo, float hi) { f32x2_t v = {lo, hi}; bf16x2_t b = __builtin_convertvector(v, bf16x2_t); return __builtin_bit_cast(unsigned, b); }
; DI void store_T_regs(const f32x16 (&acc)[2][4], int h, bfu* dst, const float* rs) {
;   const int tid = TID(), lane = tid & 63, w = tid >> 6, wm = w >> 1, wn = w & 1, l32 = lane & 31, hi = lane >> 5;
;   if (wn != h) return;
; #pragma unroll
;   for (int mi = 0; mi < 2; ++mi)
; #pragma unroll
;     for (int ni = 0; ni < 4; ++ni)
; #pragma unroll
;       for (int rg = 0; rg < 4; ++rg) {
;         const int row = wm * 64 + mi * 32 + 8 * rg + 4 * hi;
;         float s0 = 1.f, s1 = 1.f, s2 = 1.f, s3 = 1.f;
;         if (rs) { s0 = rs[row]; s1 = rs[row + 1]; s2 = rs[row + 2]; s3 = rs[row + 3]; }
;         const u32x2 v = {cvtpk(acc[mi][ni][4 * rg] * s0, acc[mi][ni][4 * rg + 1] * s1), cvtpk(acc[mi][ni][4 * rg + 2] * s2, acc[mi][ni][4 * rg + 3] * s3)};
;         *reinterpret_cast<u32x2*>(dst + (long)(ni * 32 + l32) * T + row) = v;
;       }
; }
; DI void phase_gemm(const Params& p, int g, int kind, char* smem, float* rsl, int* s_item, int vlo, int vhi, int cslot) {
;     ...
;         else if (kind == 2 && nt >= 12 && (nh & 255) == 128) { td = (bfu*)(G + L1_VT) + ((long)(bgq * 16 + (nh >> 8)) * 128) * T + t0q; trs = rsl; }
;         if (td) { store_T_regs(acc, h, td, trs); continue; }
.LBB0_1769:
	v_and_b32_e32 v179, 31, v179
	v_mul_u32_u24_e32 v179, 0x900, v179
	v_lshlrev_b32_e32 v184, 1, v179
	v_lshl_add_u64 v[182:183], s[2:3], 0, v[184:185]
	s_waitcnt lgkmcnt(0)
	v_pk_mul_f32 v[188:189], v[112:113], v[188:189]
	v_pk_mul_f32 v[180:181], v[114:115], v[180:181]
	v_cndmask_b32_e64 v179, 0, 1, s[34:35]
	v_cvt_pk_bf16_f32 v190, v188, v189
	v_cvt_pk_bf16_f32 v191, v180, v181
	v_lshl_add_u64 v[188:189], v[176:177], 1, v[182:183]
	v_cmp_ne_u32_e64 s[2:3], 1, v179
	s_andn2_b64 vcc, exec, s[34:35]
	v_mov_b32_e32 v179, 1.0
	v_mov_b32_e32 v180, 1.0
	v_mov_b32_e32 v181, 1.0
	global_store_dwordx2 v[188:189], v[190:191], off
	s_cbranch_vccnz .LBB0_1771
	ds_read2_b32 v[178:179], v224 offset0:8 offset1:9
	ds_read2_b32 v[180:181], v224 offset0:10 offset1:11
.LBB0_1771:
	s_waitcnt lgkmcnt(0)
	v_pk_mul_f32 v[178:179], v[116:117], v[178:179]
	v_pk_mul_f32 v[180:181], v[118:119], v[180:181]
	v_cvt_pk_bf16_f32 v178, v178, v179
	v_cvt_pk_bf16_f32 v179, v180, v181
	global_store_dwordx2 v[188:189], v[178:179], off offset:16
	v_mov_b32_e32 v178, 1.0
	s_and_b64 vcc, exec, s[2:3]
	v_mov_b32_e32 v190, 1.0
	v_mov_b32_e32 v191, 1.0
	v_mov_b32_e32 v180, 1.0
	v_mov_b32_e32 v181, 1.0
	s_cbranch_vccnz .LBB0_1773
	ds_read2_b32 v[190:191], v224 offset0:16 offset1:17
	ds_read2_b32 v[180:181], v224 offset0:18 offset1:19
.LBB0_1773:
	s_waitcnt lgkmcnt(0)
	v_pk_mul_f32 v[190:191], v[120:121], v[190:191]
	v_pk_mul_f32 v[180:181], v[122:123], v[180:181]
	v_cvt_pk_bf16_f32 v190, v190, v191
	v_cvt_pk_bf16_f32 v191, v180, v181
	s_and_b64 vcc, exec, s[2:3]
	v_mov_b32_e32 v179, 1.0
	v_mov_b32_e32 v180, 1.0
	v_mov_b32_e32 v181, 1.0
	global_store_dwordx2 v[188:189], v[190:191], off offset:32
	s_cbranch_vccnz .LBB0_1775
	ds_read2_b32 v[178:179], v224 offset0:24 offset1:25
	ds_read2_b32 v[180:181], v224 offset0:26 offset1:27
.LBB0_1775:
	s_waitcnt lgkmcnt(0)
	v_pk_mul_f32 v[178:179], v[124:125], v[178:179]
	v_pk_mul_f32 v[180:181], v[126:127], v[180:181]
	v_cvt_pk_bf16_f32 v178, v178, v179
	v_cvt_pk_bf16_f32 v179, v180, v181
	v_mov_b32_e32 v180, 1.0
	s_and_b64 vcc, exec, s[2:3]
	v_mov_b32_e32 v192, 1.0
	v_mov_b32_e32 v193, 1.0
	v_mov_b32_e32 v190, 1.0
	v_mov_b32_e32 v191, 1.0
	global_store_dwordx2 v[188:189], v[178:179], off offset:48
	s_cbranch_vccnz .LBB0_1777
	ds_read2_b32 v[192:193], v224 offset1:1
	ds_read2_b32 v[190:191], v224 offset0:2 offset1:3
.LBB0_1777:
	s_mov_b64 s[34:35], 0x24000
	v_lshl_add_u64 v[178:179], v[182:183], 0, s[34:35]
	s_waitcnt lgkmcnt(0)
	v_pk_mul_f32 v[192:193], v[96:97], v[192:193]
	v_pk_mul_f32 v[190:191], v[98:99], v[190:191]
	v_cvt_pk_bf16_f32 v192, v192, v193
	v_cvt_pk_bf16_f32 v193, v190, v191
	v_lshl_add_u64 v[190:191], v[176:177], 1, v[178:179]
	global_store_dwordx2 v[190:191], v[192:193], off
	s_and_b64 vcc, exec, s[2:3]
	v_mov_b32_e32 v181, 1.0
	v_mov_b32_e32 v192, 1.0
	v_mov_b32_e32 v193, 1.0
	s_cbranch_vccnz .LBB0_1779
	ds_read2_b32 v[180:181], v224 offset0:8 offset1:9
	ds_read2_b32 v[192:193], v224 offset0:10 offset1:11
.LBB0_1779:
	v_or_b32_e32 v190, 8, v176
	v_ashrrev_i32_e32 v191, 31, v190
	s_waitcnt lgkmcnt(0)
	v_pk_mul_f32 v[180:181], v[100:101], v[180:181]
	v_pk_mul_f32 v[192:193], v[102:103], v[192:193]
	v_cvt_pk_bf16_f32 v180, v180, v181
	v_cvt_pk_bf16_f32 v181, v192, v193
	v_lshl_add_u64 v[192:193], v[190:191], 1, v[178:179]
	global_store_dwordx2 v[192:193], v[180:181], off
	v_mov_b32_e32 v180, 1.0
	s_and_b64 vcc, exec, s[2:3]
	v_mov_b32_e32 v196, 1.0
	v_mov_b32_e32 v197, 1.0
	v_mov_b32_e32 v194, 1.0
	v_mov_b32_e32 v195, 1.0
	s_cbranch_vccnz .LBB0_1781
	ds_read2_b32 v[196:197], v224 offset0:16 offset1:17
	ds_read2_b32 v[194:195], v224 offset0:18 offset1:19
.LBB0_1781:
	v_or_b32_e32 v192, 16, v176
	v_ashrrev_i32_e32 v193, 31, v192
	s_waitcnt lgkmcnt(0)
	v_pk_mul_f32 v[196:197], v[104:105], v[196:197]
	v_pk_mul_f32 v[194:195], v[106:107], v[194:195]
	v_cvt_pk_bf16_f32 v196, v196, v197
	v_cvt_pk_bf16_f32 v197, v194, v195
	v_lshl_add_u64 v[194:195], v[192:193], 1, v[178:179]
	global_store_dwordx2 v[194:195], v[196:197], off
	s_and_b64 vcc, exec, s[2:3]
	v_mov_b32_e32 v181, 1.0
	v_mov_b32_e32 v196, 1.0
	v_mov_b32_e32 v197, 1.0
	s_cbranch_vccnz .LBB0_1783
	ds_read2_b32 v[180:181], v224 offset0:24 offset1:25
	ds_read2_b32 v[196:197], v224 offset0:26 offset1:27
.LBB0_1783:
	v_or_b32_e32 v194, 24, v176
	v_ashrrev_i32_e32 v195, 31, v194
	s_waitcnt lgkmcnt(0)
	v_pk_mul_f32 v[180:181], v[108:109], v[180:181]
	v_pk_mul_f32 v[196:197], v[110:111], v[196:197]
	v_cvt_pk_bf16_f32 v180, v180, v181
	v_cvt_pk_bf16_f32 v181, v196, v197
	v_lshl_add_u64 v[196:197], v[194:195], 1, v[178:179]
	global_store_dwordx2 v[196:197], v[180:181], off
	v_mov_b32_e32 v196, 1.0
	s_and_b64 vcc, exec, s[2:3]
	v_mov_b32_e32 v200, 1.0
	v_mov_b32_e32 v201, 1.0
	v_mov_b32_e32 v198, 1.0
	v_mov_b32_e32 v199, 1.0
	s_cbranch_vccnz .LBB0_1785
	ds_read2_b32 v[200:201], v224 offset1:1
	ds_read2_b32 v[198:199], v224 offset0:2 offset1:3
.LBB0_1785:
	s_mov_b64 s[34:35], 0x48000
	v_lshl_add_u64 v[180:181], v[182:183], 0, s[34:35]
	s_waitcnt lgkmcnt(0)
	v_pk_mul_f32 v[200:201], v[80:81], v[200:201]
	v_pk_mul_f32 v[198:199], v[82:83], v[198:199]
	v_cvt_pk_bf16_f32 v200, v200, v201
	v_cvt_pk_bf16_f32 v201, v198, v199
	v_lshl_add_u64 v[198:199], v[176:177], 1, v[180:181]
	global_store_dwordx2 v[198:199], v[200:201], off
	s_and_b64 vcc, exec, s[2:3]
	v_mov_b32_e32 v197, 1.0
	v_mov_b32_e32 v198, 1.0
	v_mov_b32_e32 v199, 1.0
	s_cbranch_vccnz .LBB0_1787
	ds_read2_b32 v[196:197], v224 offset0:8 offset1:9
	ds_read2_b32 v[198:199], v224 offset0:10 offset1:11
; DI int TID() { int t = threadIdx.x; asm volatile("" : "+v"(t)); return t; }
; DI unsigned cvtpk(float lo, float hi) { f32x2_t v = {lo, hi}; bf16x2_t b = __builtin_convertvector(v, bf16x2_t); return __builtin_bit_cast(unsigned, b); }
; DI void store_T_regs(const f32x16 (&acc)[2][4], int h, bfu* dst, const float* rs) {
;   const int tid = TID(), lane = tid & 63, w = tid >> 6, wm = w >> 1, wn = w & 1, l32 = lane & 31, hi = lane >> 5;
;   if (wn != h) return;
; #pragma unroll
;   for (int mi = 0; mi < 2; ++mi)
; #pragma unroll
;     for (int ni = 0; ni < 4; ++ni)
; #pragma unroll
;       for (int rg = 0; rg < 4; ++rg) {
;         const int row = wm * 64 + mi * 32 + 8 * rg + 4 * hi;
;         float s0 = 1.f, s1 = 1.f, s2 = 1.f, s3 = 1.f;
;         if (rs) { s0 = rs[row]; s1 = rs[row + 1]; s2 = rs[row + 2]; s3 = rs[row + 3]; }
;         const u32x2 v = {cvtpk(acc[mi][ni][4 * rg] * s0, acc[mi][ni][4 * rg + 1] * s1), cvtpk(acc[mi][ni][4 * rg + 2] * s2, acc[mi][ni][4 * rg + 3] * s3)};
;         *reinterpret_cast<u32x2*>(dst + (long)(ni * 32 + l32) * T + row) = v;
;       }
; }
.LBB0_1787:
	s_waitcnt lgkmcnt(0)
	v_pk_mul_f32 v[196:197], v[84:85], v[196:197]
	v_pk_mul_f32 v[198:199], v[86:87], v[198:199]
	v_cvt_pk_bf16_f32 v196, v196, v197
	v_cvt_pk_bf16_f32 v197, v198, v199
	v_lshl_add_u64 v[198:199], v[190:191], 1, v[180:181]
	global_store_dwordx2 v[198:199], v[196:197], off
	v_mov_b32_e32 v196, 1.0
	s_and_b64 vcc, exec, s[2:3]
	v_mov_b32_e32 v200, 1.0
	v_mov_b32_e32 v201, 1.0
	v_mov_b32_e32 v198, 1.0
	v_mov_b32_e32 v199, 1.0
	s_cbranch_vccnz .LBB0_1789
	ds_read2_b32 v[200:201], v224 offset0:16 offset1:17
	ds_read2_b32 v[198:199], v224 offset0:18 offset1:19
.LBB0_1789:
	s_waitcnt lgkmcnt(0)
	v_pk_mul_f32 v[200:201], v[88:89], v[200:201]
	v_pk_mul_f32 v[198:199], v[90:91], v[198:199]
	v_cvt_pk_bf16_f32 v200, v200, v201
	v_cvt_pk_bf16_f32 v201, v198, v199
	v_lshl_add_u64 v[198:199], v[192:193], 1, v[180:181]
	global_store_dwordx2 v[198:199], v[200:201], off
	s_and_b64 vcc, exec, s[2:3]
	v_mov_b32_e32 v197, 1.0
	v_mov_b32_e32 v198, 1.0
	v_mov_b32_e32 v199, 1.0
	s_cbranch_vccnz .LBB0_1791
	ds_read2_b32 v[196:197], v224 offset0:24 offset1:25
	ds_read2_b32 v[198:199], v224 offset0:26 offset1:27
.LBB0_1791:
	s_waitcnt lgkmcnt(0)
	v_pk_mul_f32 v[196:197], v[92:93], v[196:197]
	v_pk_mul_f32 v[198:199], v[94:95], v[198:199]
	v_cvt_pk_bf16_f32 v196, v196, v197
	v_cvt_pk_bf16_f32 v197, v198, v199
	v_lshl_add_u64 v[198:199], v[194:195], 1, v[180:181]
	global_store_dwordx2 v[198:199], v[196:197], off
	v_mov_b32_e32 v196, 1.0
	s_and_b64 vcc, exec, s[2:3]
	v_mov_b32_e32 v200, 1.0
	v_mov_b32_e32 v201, 1.0
	v_mov_b32_e32 v198, 1.0
	v_mov_b32_e32 v199, 1.0
	s_cbranch_vccnz .LBB0_1793
	ds_read2_b32 v[200:201], v224 offset1:1
	ds_read2_b32 v[198:199], v224 offset0:2 offset1:3
.LBB0_1793:
	s_mov_b64 s[34:35], 0x6c000
	v_lshl_add_u64 v[182:183], v[182:183], 0, s[34:35]
	s_waitcnt lgkmcnt(0)
	v_pk_mul_f32 v[200:201], v[64:65], v[200:201]
	v_pk_mul_f32 v[198:199], v[66:67], v[198:199]
	v_cvt_pk_bf16_f32 v200, v200, v201
	v_cvt_pk_bf16_f32 v201, v198, v199
	v_lshl_add_u64 v[198:199], v[176:177], 1, v[182:183]
	global_store_dwordx2 v[198:199], v[200:201], off
	s_and_b64 vcc, exec, s[2:3]
	v_mov_b32_e32 v197, 1.0
	v_mov_b32_e32 v198, 1.0
	v_mov_b32_e32 v199, 1.0
	s_cbranch_vccnz .LBB0_1795
	ds_read2_b32 v[196:197], v224 offset0:8 offset1:9
	ds_read2_b32 v[198:199], v224 offset0:10 offset1:11
.LBB0_1795:
	s_waitcnt lgkmcnt(0)
	v_pk_mul_f32 v[196:197], v[68:69], v[196:197]
	v_pk_mul_f32 v[198:199], v[70:71], v[198:199]
	v_cvt_pk_bf16_f32 v196, v196, v197
	v_cvt_pk_bf16_f32 v197, v198, v199
	v_lshl_add_u64 v[190:191], v[190:191], 1, v[182:183]
	global_store_dwordx2 v[190:191], v[196:197], off
	v_mov_b32_e32 v190, 1.0
	s_and_b64 vcc, exec, s[2:3]
	v_mov_b32_e32 v198, 1.0
	v_mov_b32_e32 v199, 1.0
	v_mov_b32_e32 v196, 1.0
	v_mov_b32_e32 v197, 1.0
	s_cbranch_vccnz .LBB0_1797
	ds_read2_b32 v[198:199], v224 offset0:16 offset1:17
	ds_read2_b32 v[196:197], v224 offset0:18 offset1:19
.LBB0_1797:
	s_waitcnt lgkmcnt(0)
	v_pk_mul_f32 v[198:199], v[72:73], v[198:199]
	v_pk_mul_f32 v[196:197], v[74:75], v[196:197]
	v_cvt_pk_bf16_f32 v198, v198, v199
	v_cvt_pk_bf16_f32 v199, v196, v197
	v_lshl_add_u64 v[192:193], v[192:193], 1, v[182:183]
	global_store_dwordx2 v[192:193], v[198:199], off
	s_and_b64 vcc, exec, s[2:3]
	v_mov_b32_e32 v191, 1.0
	v_mov_b32_e32 v192, 1.0
	v_mov_b32_e32 v193, 1.0
	s_cbranch_vccnz .LBB0_1799
	ds_read2_b32 v[190:191], v224 offset0:24 offset1:25
	ds_read2_b32 v[192:193], v224 offset0:26 offset1:27
.LBB0_1799:
	s_waitcnt lgkmcnt(0)
	v_pk_mul_f32 v[190:191], v[76:77], v[190:191]
	v_pk_mul_f32 v[192:193], v[78:79], v[192:193]
	v_cvt_pk_bf16_f32 v190, v190, v191
	v_cvt_pk_bf16_f32 v191, v192, v193
	v_lshl_add_u64 v[192:193], v[194:195], 1, v[182:183]
	global_store_dwordx2 v[192:193], v[190:191], off
	v_mov_b32_e32 v190, 1.0
	s_and_b64 vcc, exec, s[2:3]
	v_mov_b32_e32 v194, 1.0
	v_mov_b32_e32 v195, 1.0
	v_mov_b32_e32 v192, 1.0
	v_mov_b32_e32 v193, 1.0
	s_cbranch_vccnz .LBB0_1801
	ds_read2_b32 v[194:195], v224 offset0:32 offset1:33
	ds_read2_b32 v[192:193], v224 offset0:34 offset1:35
.LBB0_1801:
	s_waitcnt lgkmcnt(0)
	v_pk_mul_f32 v[194:195], v[48:49], v[194:195]
	v_pk_mul_f32 v[192:193], v[50:51], v[192:193]
	v_cvt_pk_bf16_f32 v194, v194, v195
	v_cvt_pk_bf16_f32 v195, v192, v193
	s_and_b64 vcc, exec, s[2:3]
	v_mov_b32_e32 v191, 1.0
	v_mov_b32_e32 v192, 1.0
	v_mov_b32_e32 v193, 1.0
	global_store_dwordx2 v[188:189], v[194:195], off offset:64
	s_cbranch_vccnz .LBB0_1803
	ds_read2_b32 v[190:191], v224 offset0:40 offset1:41
	ds_read2_b32 v[192:193], v224 offset0:42 offset1:43
.LBB0_1803:
	s_waitcnt lgkmcnt(0)
	v_pk_mul_f32 v[190:191], v[52:53], v[190:191]
	v_pk_mul_f32 v[192:193], v[54:55], v[192:193]
	v_cvt_pk_bf16_f32 v190, v190, v191
	v_cvt_pk_bf16_f32 v191, v192, v193
	global_store_dwordx2 v[188:189], v[190:191], off offset:80
	v_mov_b32_e32 v190, 1.0
	s_and_b64 vcc, exec, s[2:3]
	v_mov_b32_e32 v194, 1.0
	v_mov_b32_e32 v195, 1.0
	v_mov_b32_e32 v192, 1.0
	v_mov_b32_e32 v193, 1.0
	s_cbranch_vccnz .LBB0_1805
	ds_read2_b32 v[194:195], v224 offset0:48 offset1:49
	ds_read2_b32 v[192:193], v224 offset0:50 offset1:51
.LBB0_1805:
	s_waitcnt lgkmcnt(0)
	v_pk_mul_f32 v[194:195], v[56:57], v[194:195]
	v_pk_mul_f32 v[192:193], v[58:59], v[192:193]
	v_cvt_pk_bf16_f32 v194, v194, v195
	v_cvt_pk_bf16_f32 v195, v192, v193
	s_and_b64 vcc, exec, s[2:3]
	v_mov_b32_e32 v191, 1.0
	v_mov_b32_e32 v192, 1.0
	v_mov_b32_e32 v193, 1.0
	global_store_dwordx2 v[188:189], v[194:195], off offset:96
	s_cbranch_vccnz .LBB0_1807
	ds_read2_b32 v[190:191], v224 offset0:56 offset1:57
	ds_read2_b32 v[192:193], v224 offset0:58 offset1:59
; DI int TID() { int t = threadIdx.x; asm volatile("" : "+v"(t)); return t; }
; DI unsigned cvtpk(float lo, float hi) { f32x2_t v = {lo, hi}; bf16x2_t b = __builtin_convertvector(v, bf16x2_t); return __builtin_bit_cast(unsigned, b); }
; DI void store_T_regs(const f32x16 (&acc)[2][4], int h, bfu* dst, const float* rs) {
;   const int tid = TID(), lane = tid & 63, w = tid >> 6, wm = w >> 1, wn = w & 1, l32 = lane & 31, hi = lane >> 5;
;   if (wn != h) return;
; #pragma unroll
;   for (int mi = 0; mi < 2; ++mi)
; #pragma unroll
;     for (int ni = 0; ni < 4; ++ni)
; #pragma unroll
;       for (int rg = 0; rg < 4; ++rg) {
;         const int row = wm * 64 + mi * 32 + 8 * rg + 4 * hi;
;         float s0 = 1.f, s1 = 1.f, s2 = 1.f, s3 = 1.f;
;         if (rs) { s0 = rs[row]; s1 = rs[row + 1]; s2 = rs[row + 2]; s3 = rs[row + 3]; }
;         const u32x2 v = {cvtpk(acc[mi][ni][4 * rg] * s0, acc[mi][ni][4 * rg + 1] * s1), cvtpk(acc[mi][ni][4 * rg + 2] * s2, acc[mi][ni][4 * rg + 3] * s3)};
;         *reinterpret_cast<u32x2*>(dst + (long)(ni * 32 + l32) * T + row) = v;
;       }
; }
.LBB0_1807:
	s_waitcnt lgkmcnt(0)
	v_pk_mul_f32 v[190:191], v[60:61], v[190:191]
	v_pk_mul_f32 v[192:193], v[62:63], v[192:193]
	v_cvt_pk_bf16_f32 v190, v190, v191
	v_cvt_pk_bf16_f32 v191, v192, v193
	global_store_dwordx2 v[188:189], v[190:191], off offset:112
	v_mov_b32_e32 v192, 1.0
	s_and_b64 vcc, exec, s[2:3]
	v_mov_b32_e32 v194, 1.0
	v_mov_b32_e32 v195, 1.0
	v_mov_b32_e32 v190, 1.0
	v_mov_b32_e32 v191, 1.0
	s_cbranch_vccnz .LBB0_1809
	ds_read2_b32 v[194:195], v224 offset0:32 offset1:33
	ds_read2_b32 v[190:191], v224 offset0:34 offset1:35
.LBB0_1809:
	v_or_b32_e32 v188, 32, v176
	v_ashrrev_i32_e32 v189, 31, v188
	s_waitcnt lgkmcnt(0)
	v_pk_mul_f32 v[194:195], v[32:33], v[194:195]
	v_pk_mul_f32 v[190:191], v[34:35], v[190:191]
	v_cvt_pk_bf16_f32 v194, v194, v195
	v_cvt_pk_bf16_f32 v195, v190, v191
	v_lshl_add_u64 v[190:191], v[188:189], 1, v[178:179]
	global_store_dwordx2 v[190:191], v[194:195], off
	s_and_b64 vcc, exec, s[2:3]
	v_mov_b32_e32 v193, 1.0
	v_mov_b32_e32 v194, 1.0
	v_mov_b32_e32 v195, 1.0
	s_cbranch_vccnz .LBB0_1811
	ds_read2_b32 v[192:193], v224 offset0:40 offset1:41
	ds_read2_b32 v[194:195], v224 offset0:42 offset1:43
.LBB0_1811:
	v_or_b32_e32 v190, 40, v176
	v_ashrrev_i32_e32 v191, 31, v190
	s_waitcnt lgkmcnt(0)
	v_pk_mul_f32 v[192:193], v[36:37], v[192:193]
	v_pk_mul_f32 v[194:195], v[38:39], v[194:195]
	v_cvt_pk_bf16_f32 v192, v192, v193
	v_cvt_pk_bf16_f32 v193, v194, v195
	v_lshl_add_u64 v[194:195], v[190:191], 1, v[178:179]
	global_store_dwordx2 v[194:195], v[192:193], off
	v_mov_b32_e32 v194, 1.0
	s_and_b64 vcc, exec, s[2:3]
	v_mov_b32_e32 v198, 1.0
	v_mov_b32_e32 v199, 1.0
	v_mov_b32_e32 v196, 1.0
	v_mov_b32_e32 v197, 1.0
	s_cbranch_vccnz .LBB0_1813
	ds_read2_b32 v[198:199], v224 offset0:48 offset1:49
	ds_read2_b32 v[196:197], v224 offset0:50 offset1:51
.LBB0_1813:
	v_or_b32_e32 v192, 48, v176
	v_ashrrev_i32_e32 v193, 31, v192
	s_waitcnt lgkmcnt(0)
	v_pk_mul_f32 v[198:199], v[40:41], v[198:199]
	v_pk_mul_f32 v[196:197], v[42:43], v[196:197]
	v_cvt_pk_bf16_f32 v198, v198, v199
	v_cvt_pk_bf16_f32 v199, v196, v197
	v_lshl_add_u64 v[196:197], v[192:193], 1, v[178:179]
	global_store_dwordx2 v[196:197], v[198:199], off
	s_and_b64 vcc, exec, s[2:3]
	v_mov_b32_e32 v195, 1.0
	v_mov_b32_e32 v196, 1.0
	v_mov_b32_e32 v197, 1.0
	s_cbranch_vccnz .LBB0_1815
	ds_read2_b32 v[194:195], v224 offset0:56 offset1:57
	ds_read2_b32 v[196:197], v224 offset0:58 offset1:59
.LBB0_1815:
	v_or_b32_e32 v176, 56, v176
	v_ashrrev_i32_e32 v177, 31, v176
	s_waitcnt lgkmcnt(0)
	v_pk_mul_f32 v[194:195], v[44:45], v[194:195]
	v_pk_mul_f32 v[196:197], v[46:47], v[196:197]
	v_cvt_pk_bf16_f32 v194, v194, v195
	v_cvt_pk_bf16_f32 v195, v196, v197
	v_lshl_add_u64 v[178:179], v[176:177], 1, v[178:179]
	global_store_dwordx2 v[178:179], v[194:195], off
	v_mov_b32_e32 v178, 1.0
	s_and_b64 vcc, exec, s[2:3]
	v_mov_b32_e32 v196, 1.0
	v_mov_b32_e32 v197, 1.0
	v_mov_b32_e32 v194, 1.0
	v_mov_b32_e32 v195, 1.0
	s_cbranch_vccnz .LBB0_1817
	ds_read2_b32 v[196:197], v224 offset0:32 offset1:33
	ds_read2_b32 v[194:195], v224 offset0:34 offset1:35
.LBB0_1817:
	s_waitcnt lgkmcnt(0)
	v_pk_mul_f32 v[196:197], v[16:17], v[196:197]
	v_pk_mul_f32 v[194:195], v[18:19], v[194:195]
	v_cvt_pk_bf16_f32 v196, v196, v197
	v_cvt_pk_bf16_f32 v197, v194, v195
	v_lshl_add_u64 v[194:195], v[188:189], 1, v[180:181]
	global_store_dwordx2 v[194:195], v[196:197], off
	s_and_b64 vcc, exec, s[2:3]
	v_mov_b32_e32 v179, 1.0
	v_mov_b32_e32 v194, 1.0
	v_mov_b32_e32 v195, 1.0
	s_cbranch_vccnz .LBB0_1819
	ds_read2_b32 v[178:179], v224 offset0:40 offset1:41
	ds_read2_b32 v[194:195], v224 offset0:42 offset1:43
; DI int TID() { int t = threadIdx.x; asm volatile("" : "+v"(t)); return t; }
; DI unsigned cvtpk(float lo, float hi) { f32x2_t v = {lo, hi}; bf16x2_t b = __builtin_convertvector(v, bf16x2_t); return __builtin_bit_cast(unsigned, b); }
; DI void store_T_regs(const f32x16 (&acc)[2][4], int h, bfu* dst, const float* rs) {
;   const int tid = TID(), lane = tid & 63, w = tid >> 6, wm = w >> 1, wn = w & 1, l32 = lane & 31, hi = lane >> 5;
;   if (wn != h) return;
; #pragma unroll
;   for (int mi = 0; mi < 2; ++mi)
; #pragma unroll
;     for (int ni = 0; ni < 4; ++ni)
; #pragma unroll
;       for (int rg = 0; rg < 4; ++rg) {
;         const int row = wm * 64 + mi * 32 + 8 * rg + 4 * hi;
;         float s0 = 1.f, s1 = 1.f, s2 = 1.f, s3 = 1.f;
;         if (rs) { s0 = rs[row]; s1 = rs[row + 1]; s2 = rs[row + 2]; s3 = rs[row + 3]; }
;         const u32x2 v = {cvtpk(acc[mi][ni][4 * rg] * s0, acc[mi][ni][4 * rg + 1] * s1), cvtpk(acc[mi][ni][4 * rg + 2] * s2, acc[mi][ni][4 * rg + 3] * s3)};
;         *reinterpret_cast<u32x2*>(dst + (long)(ni * 32 + l32) * T + row) = v;
;       }
; }
.LBB0_1819:
	s_waitcnt lgkmcnt(0)
	v_pk_mul_f32 v[178:179], v[20:21], v[178:179]
	v_pk_mul_f32 v[194:195], v[22:23], v[194:195]
	v_cvt_pk_bf16_f32 v178, v178, v179
	v_cvt_pk_bf16_f32 v179, v194, v195
	v_lshl_add_u64 v[194:195], v[190:191], 1, v[180:181]
	global_store_dwordx2 v[194:195], v[178:179], off
	v_mov_b32_e32 v178, 1.0
	s_and_b64 vcc, exec, s[2:3]
	v_mov_b32_e32 v196, 1.0
	v_mov_b32_e32 v197, 1.0
	v_mov_b32_e32 v194, 1.0
	v_mov_b32_e32 v195, 1.0
	s_cbranch_vccnz .LBB0_1821
	ds_read2_b32 v[196:197], v224 offset0:48 offset1:49
	ds_read2_b32 v[194:195], v224 offset0:50 offset1:51
.LBB0_1821:
	s_waitcnt lgkmcnt(0)
	v_pk_mul_f32 v[196:197], v[24:25], v[196:197]
	v_pk_mul_f32 v[194:195], v[26:27], v[194:195]
	v_cvt_pk_bf16_f32 v196, v196, v197
	v_cvt_pk_bf16_f32 v197, v194, v195
	v_lshl_add_u64 v[194:195], v[192:193], 1, v[180:181]
	global_store_dwordx2 v[194:195], v[196:197], off
	s_and_b64 vcc, exec, s[2:3]
	v_mov_b32_e32 v179, 1.0
	v_mov_b32_e32 v194, 1.0
	v_mov_b32_e32 v195, 1.0
	s_cbranch_vccnz .LBB0_1823
	ds_read2_b32 v[178:179], v224 offset0:56 offset1:57
	ds_read2_b32 v[194:195], v224 offset0:58 offset1:59
.LBB0_1823:
	s_waitcnt lgkmcnt(0)
	v_pk_mul_f32 v[178:179], v[28:29], v[178:179]
	v_pk_mul_f32 v[194:195], v[30:31], v[194:195]
	v_cvt_pk_bf16_f32 v178, v178, v179
	v_cvt_pk_bf16_f32 v179, v194, v195
	v_lshl_add_u64 v[180:181], v[176:177], 1, v[180:181]
	global_store_dwordx2 v[180:181], v[178:179], off
	v_mov_b32_e32 v178, 1.0
	s_and_b64 vcc, exec, s[2:3]
	v_mov_b32_e32 v194, 1.0
	v_mov_b32_e32 v195, 1.0
	v_mov_b32_e32 v180, 1.0
	v_mov_b32_e32 v181, 1.0
	s_cbranch_vccnz .LBB0_1825
	ds_read2_b32 v[194:195], v224 offset0:32 offset1:33
	ds_read2_b32 v[180:181], v224 offset0:34 offset1:35
.LBB0_1825:
	s_waitcnt lgkmcnt(0)
	v_pk_mul_f32 v[194:195], v[0:1], v[194:195]
	v_pk_mul_f32 v[180:181], v[2:3], v[180:181]
	v_cvt_pk_bf16_f32 v194, v194, v195
	v_cvt_pk_bf16_f32 v195, v180, v181
	v_lshl_add_u64 v[180:181], v[188:189], 1, v[182:183]
	global_store_dwordx2 v[180:181], v[194:195], off
	s_and_b64 vcc, exec, s[2:3]
	v_mov_b32_e32 v179, 1.0
	v_mov_b32_e32 v180, 1.0
	v_mov_b32_e32 v181, 1.0
	s_cbranch_vccnz .LBB0_1827
	ds_read2_b32 v[178:179], v224 offset0:40 offset1:41
	ds_read2_b32 v[180:181], v224 offset0:42 offset1:43
.LBB0_1827:
	s_waitcnt lgkmcnt(0)
	v_pk_mul_f32 v[178:179], v[4:5], v[178:179]
	v_pk_mul_f32 v[180:181], v[6:7], v[180:181]
	v_cvt_pk_bf16_f32 v178, v178, v179
	v_cvt_pk_bf16_f32 v179, v180, v181
	v_lshl_add_u64 v[180:181], v[190:191], 1, v[182:183]
	global_store_dwordx2 v[180:181], v[178:179], off
	v_mov_b32_e32 v178, 1.0
	s_and_b64 vcc, exec, s[2:3]
	v_mov_b32_e32 v188, 1.0
	v_mov_b32_e32 v189, 1.0
	v_mov_b32_e32 v180, 1.0
	v_mov_b32_e32 v181, 1.0
	s_cbranch_vccnz .LBB0_1829
	ds_read2_b32 v[188:189], v224 offset0:48 offset1:49
	ds_read2_b32 v[180:181], v224 offset0:50 offset1:51
.LBB0_1829:
	s_waitcnt lgkmcnt(0)
	v_pk_mul_f32 v[188:189], v[8:9], v[188:189]
	v_pk_mul_f32 v[180:181], v[10:11], v[180:181]
	v_cvt_pk_bf16_f32 v188, v188, v189
	v_cvt_pk_bf16_f32 v189, v180, v181
	v_lshl_add_u64 v[180:181], v[192:193], 1, v[182:183]
	global_store_dwordx2 v[180:181], v[188:189], off
	s_and_b64 vcc, exec, s[2:3]
	v_mov_b32_e32 v179, 1.0
	v_mov_b32_e32 v180, 1.0
	v_mov_b32_e32 v181, 1.0
	s_cbranch_vccnz .LBB0_1831
	ds_read2_b32 v[178:179], v224 offset0:56 offset1:57
	ds_read2_b32 v[180:181], v224 offset0:58 offset1:59
.LBB0_1831:
	s_waitcnt lgkmcnt(0)
	v_pk_mul_f32 v[178:179], v[12:13], v[178:179]
	v_pk_mul_f32 v[180:181], v[14:15], v[180:181]
	v_cvt_pk_bf16_f32 v178, v178, v179
	v_cvt_pk_bf16_f32 v179, v180, v181
	v_lshl_add_u64 v[176:177], v[176:177], 1, v[182:183]
	global_store_dwordx2 v[176:177], v[178:179], off

;   DI const float* c() const { return (const float*)sp[1]; }
; DI int TID() { int t = threadIdx.x; asm volatile("" : "+v"(t)); return t; }
; DI bf16x8 pack8f(const float* v) { u32x4 w = {cvtpk(v[0], v[1]), cvtpk(v[2], v[3]), cvtpk(v[4], v[5]), cvtpk(v[6], v[7])}; return __builtin_bit_cast(bf16x8, w); }
; DI void store_T(const float* Cs, int cb, int nc, bfu* dst, long ldT, float scale, const float* rs = nullptr) {
;   for (int u = TID(); u < nc * 16; u += NT) {
;     int c = u % nc, rc = (u / nc) * 8; float v[8];
;     for (int j = 0; j < 8; ++j) v[j] = Cs[(rc + j) * CLD + cb + c] * (rs ? scale * rs[rc + j] : scale);
;     st8(dst + c * ldT + rc, pack8f(v));
;   }
; }
; DI void epi_ukv(const Params& p, float* Cs, int m0, int n0, const float* rsl) {
;     ...
;   else store_T(Cs, 0, 128, (bfu*)(G + L1_VT) + ((long)(bg * 16 + head) * 128) * T + t0, T, 1.f, rsl);
.LBB0_1840:
	s_mov_b32 s2, 0xfff70000
	s_waitcnt lgkmcnt(0)
	v_mul_f32_e32 v181, v181, v183
	v_mul_f32_e32 v188, v188, v182
	v_mad_u64_u32 v[182:183], s[2:3], v179, s2, v[176:177]
	v_ashrrev_i32_e32 v183, 31, v182
	v_mul_f32_e32 v198, v198, v199
	v_mul_f32_e32 v193, v193, v195
	v_mul_f32_e32 v194, v196, v194
	v_mul_f32_e32 v189, v189, v191
	v_mul_f32_e32 v190, v192, v190
	v_mul_f32_e32 v184, v184, v197
	v_lshl_add_u64 v[182:183], s[36:37], 0, v[182:183]
	v_ashrrev_i32_e32 v179, 31, v178
	v_lshl_add_u64 v[178:179], v[178:179], 1, v[182:183]
	v_cvt_pk_bf16_f32 v188, v181, v188
	v_cvt_pk_bf16_f32 v189, v189, v190
	v_cvt_pk_bf16_f32 v190, v193, v194
	v_cvt_pk_bf16_f32 v191, v198, v184
	global_store_dwordx4 v[178:179], v[188:191], off
	v_add_u32_e32 v178, 0x100, v177
	v_cmp_lt_i32_e32 vcc, s53, v177
	v_add_u32_e32 v176, 0x120000, v176
	v_add_u32_e32 v180, 0x400, v180
	s_or_b64 s[38:39], vcc, s[38:39]
	v_mov_b32_e32 v177, v178
	s_andn2_b64 exec, exec, s[38:39]
	s_cbranch_execz .LBB0_1857

; DI int TID() { int t = threadIdx.x; asm volatile("" : "+v"(t)); return t; }
; DI bf16x8 pack8f(const float* v) { u32x4 w = {cvtpk(v[0], v[1]), cvtpk(v[2], v[3]), cvtpk(v[4], v[5]), cvtpk(v[6], v[7])}; return __builtin_bit_cast(bf16x8, w); }
; DI void store_R(const float* Cs, int cb, int nc, bfu* dst, long ld, float scale, const float* rs = nullptr) {
;   const int cpr = nc >> 3;
;   for (int u = TID(); u < 128 * cpr; u += NT) {
;     int row = u / cpr, c8 = (u % cpr) * 8; float v[8]; ldrow8(Cs, row, cb + c8, v);
;     float s = rs ? scale * rs[row] : scale;
;     for (int j = 0; j < 8; ++j) v[j] *= s;
;     st8(dst + row * ld + c8, pack8f(v));
;   }
; }
; DI void epi_ukv(const Params& p, float* Cs, int m0, int n0, const float* rsl) {
;     ...
;   if ((n0 & 255) == 0) store_R(Cs, 0, 128, (bfu*)(G + L1_K) + ((long)(bg * 16 + head) * T + t0) * 192, 192, 1.f, rsl);
.LBB0_1862:
	v_lshlrev_b32_e32 v192, 7, v191
	v_sub_u32_e32 v192, v189, v192
	s_waitcnt lgkmcnt(0)
	v_pk_mul_f32 v[194:195], v[176:177], v[184:185] op_sel_hi:[1,0]
	v_mov_b64_e32 v[176:177], s[30:31]
	v_pk_mul_f32 v[180:181], v[180:181], v[184:185] op_sel_hi:[1,0]
	v_pk_mul_f32 v[182:183], v[182:183], v[184:185] op_sel_hi:[1,0]
	v_pk_mul_f32 v[196:197], v[178:179], v[184:185] op_sel_hi:[1,0]
	v_mad_i64_i32 v[176:177], s[36:37], v191, s74, v[176:177]
	v_ashrrev_i32_e32 v193, 31, v192
	v_lshl_add_u64 v[192:193], v[192:193], 1, v[176:177]
	v_cvt_pk_bf16_f32 v176, v180, v181
	v_cvt_pk_bf16_f32 v177, v182, v183
	v_cvt_pk_bf16_f32 v178, v194, v195
	v_cvt_pk_bf16_f32 v179, v196, v197
	global_store_dwordx4 v[192:193], v[176:179], off
	v_cmp_lt_i32_e32 vcc, s53, v188
	v_add_u32_e32 v189, 0x800, v189
	v_add_u32_e32 v176, 0x100, v188
	v_add_u32_e32 v190, 0x2000, v190
	s_or_b64 s[34:35], vcc, s[34:35]
	v_mov_b32_e32 v188, v176
	s_andn2_b64 exec, exec, s[34:35]
	s_cbranch_execz .LBB0_1865

; DI int TID() { int t = threadIdx.x; asm volatile("" : "+v"(t)); return t; }
; DI bf16x8 pack8f(const float* v) { u32x4 w = {cvtpk(v[0], v[1]), cvtpk(v[2], v[3]), cvtpk(v[4], v[5]), cvtpk(v[6], v[7])}; return __builtin_bit_cast(bf16x8, w); }
; DI void store_R(const float* Cs, int cb, int nc, bfu* dst, long ld, float scale, const float* rs = nullptr) {
;   const int cpr = nc >> 3;
;   for (int u = TID(); u < 128 * cpr; u += NT) {
;     int row = u / cpr, c8 = (u % cpr) * 8; float v[8]; ldrow8(Cs, row, cb + c8, v);
;     float s = rs ? scale * rs[row] : scale;
;     for (int j = 0; j < 8; ++j) v[j] *= s;
;     st8(dst + row * ld + c8, pack8f(v));
;   }
; }
; DI void epi_uq(const Params& p, float* Cs, int m0, int n0, const float* rsl) {
;     ...
;     store_R(Cs, gq * 64, 64, (bfu*)(G + L1_Q) + ((long)(bg * 16 + head) * T + t0) * 192 + part * 64, 192, 0.07216878364870323f * LOG2E, rsl);
.LBB0_1876:
	v_lshlrev_b32_e32 v192, 6, v191
	v_sub_u32_e32 v192, v190, v192
	s_waitcnt lgkmcnt(0)
	v_pk_mul_f32 v[194:195], v[176:177], v[188:189] op_sel_hi:[1,0]
	v_mov_b64_e32 v[176:177], s[34:35]
	v_pk_mul_f32 v[180:181], v[180:181], v[188:189] op_sel_hi:[1,0]
	v_pk_mul_f32 v[182:183], v[182:183], v[188:189] op_sel_hi:[1,0]
	v_pk_mul_f32 v[196:197], v[178:179], v[188:189] op_sel_hi:[1,0]
	v_mad_i64_i32 v[176:177], s[62:63], v191, s74, v[176:177]
	v_ashrrev_i32_e32 v193, 31, v192
	v_lshl_add_u64 v[192:193], v[192:193], 1, v[176:177]
	v_cvt_pk_bf16_f32 v176, v180, v181
	v_cvt_pk_bf16_f32 v177, v182, v183
	v_cvt_pk_bf16_f32 v178, v194, v195
	v_cvt_pk_bf16_f32 v179, v196, v197
	global_store_dwordx4 v[192:193], v[176:179], off
	v_cmp_lt_i32_e32 vcc, s87, v189
	v_add_u32_e32 v190, 0x800, v190
	v_add_u32_e32 v176, 0x100, v189
	v_add_u32_e32 v184, 0x2000, v184
	s_or_b64 s[36:37], vcc, s[36:37]
	v_mov_b32_e32 v189, v176
	s_andn2_b64 exec, exec, s[36:37]
	s_cbranch_execz .LBB0_1879

; DI int TID() { int t = threadIdx.x; asm volatile("" : "+v"(t)); return t; }
; DI bf16x8 pack8f(const float* v) { u32x4 w = {cvtpk(v[0], v[1]), cvtpk(v[2], v[3]), cvtpk(v[4], v[5]), cvtpk(v[6], v[7])}; return __builtin_bit_cast(bf16x8, w); }
; DI void store_R(const float* Cs, int cb, int nc, bfu* dst, long ld, float scale, const float* rs = nullptr) {
;   const int cpr = nc >> 3;
;   for (int u = TID(); u < 128 * cpr; u += NT) {
;     int row = u / cpr, c8 = (u % cpr) * 8; float v[8]; ldrow8(Cs, row, cb + c8, v);
;     float s = rs ? scale * rs[row] : scale;
;     for (int j = 0; j < 8; ++j) v[j] *= s;
;     st8(dst + row * ld + c8, pack8f(v));
;   }
; }
; DI void epi_uq(const Params& p, float* Cs, int m0, int n0, const float* rsl) {
;     ...
;     store_R(Cs, gq * 64, 64, (bfu*)(G + L1_Q) + ((long)(bg * 16 + head) * T + t0) * 192 + part * 64, 192, 0.07216878364870323f * LOG2E, rsl);
.LBB0_1887:
	v_lshlrev_b32_e32 v192, 6, v191
	v_sub_u32_e32 v192, v190, v192
	s_waitcnt lgkmcnt(0)
	v_pk_mul_f32 v[194:195], v[176:177], v[188:189] op_sel_hi:[1,0]
	v_mov_b64_e32 v[176:177], s[30:31]
	v_pk_mul_f32 v[180:181], v[180:181], v[188:189] op_sel_hi:[1,0]
	v_pk_mul_f32 v[182:183], v[182:183], v[188:189] op_sel_hi:[1,0]
	v_pk_mul_f32 v[196:197], v[178:179], v[188:189] op_sel_hi:[1,0]
	v_mad_i64_i32 v[176:177], s[36:37], v191, s74, v[176:177]
	v_ashrrev_i32_e32 v193, 31, v192
	v_lshl_add_u64 v[192:193], v[192:193], 1, v[176:177]
	v_cvt_pk_bf16_f32 v176, v180, v181
	v_cvt_pk_bf16_f32 v177, v182, v183
	v_cvt_pk_bf16_f32 v178, v194, v195
	v_cvt_pk_bf16_f32 v179, v196, v197
	global_store_dwordx4 v[192:193], v[176:179], off
	v_cmp_lt_i32_e32 vcc, s87, v189
	v_add_u32_e32 v184, 0x2000, v184
	v_add_u32_e32 v176, 0x100, v189
	v_add_u32_e32 v190, 0x800, v190
	s_or_b64 s[34:35], vcc, s[34:35]
	v_mov_b32_e32 v189, v176
	s_andn2_b64 exec, exec, s[34:35]
	s_cbranch_execz .LBB0_1890

; DI int TID() { int t = threadIdx.x; asm volatile("" : "+v"(t)); return t; }
; DI unsigned cvtpk(float lo, float hi) { f32x2_t v = {lo, hi}; bf16x2_t b = __builtin_convertvector(v, bf16x2_t); return __builtin_bit_cast(unsigned, b); }
; DI void store_T_regs(const f32x16 (&acc)[2][4], int h, bfu* dst, const float* rs) {
;   const int tid = TID(), lane = tid & 63, w = tid >> 6, wm = w >> 1, wn = w & 1, l32 = lane & 31, hi = lane >> 5;
;   if (wn != h) return;
; #pragma unroll
;   for (int mi = 0; mi < 2; ++mi)
; #pragma unroll
;     for (int ni = 0; ni < 4; ++ni)
; #pragma unroll
;       for (int rg = 0; rg < 4; ++rg) {
;         const int row = wm * 64 + mi * 32 + 8 * rg + 4 * hi;
;         float s0 = 1.f, s1 = 1.f, s2 = 1.f, s3 = 1.f;
;         if (rs) { s0 = rs[row]; s1 = rs[row + 1]; s2 = rs[row + 2]; s3 = rs[row + 3]; }
;         const u32x2 v = {cvtpk(acc[mi][ni][4 * rg] * s0, acc[mi][ni][4 * rg + 1] * s1), cvtpk(acc[mi][ni][4 * rg + 2] * s2, acc[mi][ni][4 * rg + 3] * s3)};
;         *reinterpret_cast<u32x2*>(dst + (long)(ni * 32 + l32) * T + row) = v;
;       }
; }
.LBB0_1898:
	v_and_b32_e32 v179, 31, v179
	v_mul_u32_u24_e32 v179, 0x900, v179
	v_lshlrev_b32_e32 v184, 1, v179
	v_lshl_add_u64 v[182:183], s[2:3], 0, v[184:185]
	s_waitcnt lgkmcnt(0)
	v_pk_mul_f32 v[188:189], v[112:113], v[188:189]
	v_pk_mul_f32 v[180:181], v[114:115], v[180:181]
	v_cndmask_b32_e64 v179, 0, 1, s[30:31]
	v_cvt_pk_bf16_f32 v190, v188, v189
	v_cvt_pk_bf16_f32 v191, v180, v181
	v_lshl_add_u64 v[188:189], v[176:177], 1, v[182:183]
	v_cmp_ne_u32_e64 s[2:3], 1, v179
	s_andn2_b64 vcc, exec, s[30:31]
	v_mov_b32_e32 v179, 1.0
	v_mov_b32_e32 v180, 1.0
	v_mov_b32_e32 v181, 1.0
	global_store_dwordx2 v[188:189], v[190:191], off
	s_cbranch_vccnz .LBB0_1900
	ds_read2_b32 v[178:179], v224 offset0:8 offset1:9
	ds_read2_b32 v[180:181], v224 offset0:10 offset1:11

; DI int TID() { int t = threadIdx.x; asm volatile("" : "+v"(t)); return t; }
; DI unsigned cvtpk(float lo, float hi) { f32x2_t v = {lo, hi}; bf16x2_t b = __builtin_convertvector(v, bf16x2_t); return __builtin_bit_cast(unsigned, b); }
; DI void store_T_regs(const f32x16 (&acc)[2][4], int h, bfu* dst, const float* rs) {
;   const int tid = TID(), lane = tid & 63, w = tid >> 6, wm = w >> 1, wn = w & 1, l32 = lane & 31, hi = lane >> 5;
;   if (wn != h) return;
; #pragma unroll
;   for (int mi = 0; mi < 2; ++mi)
; #pragma unroll
;     for (int ni = 0; ni < 4; ++ni)
; #pragma unroll
;       for (int rg = 0; rg < 4; ++rg) {
;         const int row = wm * 64 + mi * 32 + 8 * rg + 4 * hi;
;         float s0 = 1.f, s1 = 1.f, s2 = 1.f, s3 = 1.f;
;         if (rs) { s0 = rs[row]; s1 = rs[row + 1]; s2 = rs[row + 2]; s3 = rs[row + 3]; }
;         const u32x2 v = {cvtpk(acc[mi][ni][4 * rg] * s0, acc[mi][ni][4 * rg + 1] * s1), cvtpk(acc[mi][ni][4 * rg + 2] * s2, acc[mi][ni][4 * rg + 3] * s3)};
;         *reinterpret_cast<u32x2*>(dst + (long)(ni * 32 + l32) * T + row) = v;
;       }
; }
.LBB0_1906:
	s_mov_b64 s[30:31], 0x24000
	v_lshl_add_u64 v[178:179], v[182:183], 0, s[30:31]
	s_waitcnt lgkmcnt(0)
	v_pk_mul_f32 v[192:193], v[96:97], v[192:193]
	v_pk_mul_f32 v[190:191], v[98:99], v[190:191]
	v_cvt_pk_bf16_f32 v192, v192, v193
	v_cvt_pk_bf16_f32 v193, v190, v191
	v_lshl_add_u64 v[190:191], v[176:177], 1, v[178:179]
	global_store_dwordx2 v[190:191], v[192:193], off
	s_and_b64 vcc, exec, s[2:3]
	v_mov_b32_e32 v181, 1.0
	v_mov_b32_e32 v192, 1.0
	v_mov_b32_e32 v193, 1.0
	s_cbranch_vccnz .LBB0_1908
	ds_read2_b32 v[180:181], v224 offset0:8 offset1:9
	ds_read2_b32 v[192:193], v224 offset0:10 offset1:11

; DI int TID() { int t = threadIdx.x; asm volatile("" : "+v"(t)); return t; }
; DI unsigned cvtpk(float lo, float hi) { f32x2_t v = {lo, hi}; bf16x2_t b = __builtin_convertvector(v, bf16x2_t); return __builtin_bit_cast(unsigned, b); }
; DI void store_T_regs(const f32x16 (&acc)[2][4], int h, bfu* dst, const float* rs) {
;   const int tid = TID(), lane = tid & 63, w = tid >> 6, wm = w >> 1, wn = w & 1, l32 = lane & 31, hi = lane >> 5;
;   if (wn != h) return;
; #pragma unroll
;   for (int mi = 0; mi < 2; ++mi)
; #pragma unroll
;     for (int ni = 0; ni < 4; ++ni)
; #pragma unroll
;       for (int rg = 0; rg < 4; ++rg) {
;         const int row = wm * 64 + mi * 32 + 8 * rg + 4 * hi;
;         float s0 = 1.f, s1 = 1.f, s2 = 1.f, s3 = 1.f;
;         if (rs) { s0 = rs[row]; s1 = rs[row + 1]; s2 = rs[row + 2]; s3 = rs[row + 3]; }
;         const u32x2 v = {cvtpk(acc[mi][ni][4 * rg] * s0, acc[mi][ni][4 * rg + 1] * s1), cvtpk(acc[mi][ni][4 * rg + 2] * s2, acc[mi][ni][4 * rg + 3] * s3)};
;         *reinterpret_cast<u32x2*>(dst + (long)(ni * 32 + l32) * T + row) = v;
;       }
; }
.LBB0_1914:
	s_mov_b64 s[30:31], 0x48000
	v_lshl_add_u64 v[180:181], v[182:183], 0, s[30:31]
	s_waitcnt lgkmcnt(0)
	v_pk_mul_f32 v[200:201], v[80:81], v[200:201]
	v_pk_mul_f32 v[198:199], v[82:83], v[198:199]
	v_cvt_pk_bf16_f32 v200, v200, v201
	v_cvt_pk_bf16_f32 v201, v198, v199
	v_lshl_add_u64 v[198:199], v[176:177], 1, v[180:181]
	global_store_dwordx2 v[198:199], v[200:201], off
	s_and_b64 vcc, exec, s[2:3]
	v_mov_b32_e32 v197, 1.0
	v_mov_b32_e32 v198, 1.0
	v_mov_b32_e32 v199, 1.0
	s_cbranch_vccnz .LBB0_1916
	ds_read2_b32 v[196:197], v224 offset0:8 offset1:9
	ds_read2_b32 v[198:199], v224 offset0:10 offset1:11

; DI int TID() { int t = threadIdx.x; asm volatile("" : "+v"(t)); return t; }
; DI unsigned cvtpk(float lo, float hi) { f32x2_t v = {lo, hi}; bf16x2_t b = __builtin_convertvector(v, bf16x2_t); return __builtin_bit_cast(unsigned, b); }
; DI void store_T_regs(const f32x16 (&acc)[2][4], int h, bfu* dst, const float* rs) {
;   const int tid = TID(), lane = tid & 63, w = tid >> 6, wm = w >> 1, wn = w & 1, l32 = lane & 31, hi = lane >> 5;
;   if (wn != h) return;
; #pragma unroll
;   for (int mi = 0; mi < 2; ++mi)
; #pragma unroll
;     for (int ni = 0; ni < 4; ++ni)
; #pragma unroll
;       for (int rg = 0; rg < 4; ++rg) {
;         const int row = wm * 64 + mi * 32 + 8 * rg + 4 * hi;
;         float s0 = 1.f, s1 = 1.f, s2 = 1.f, s3 = 1.f;
;         if (rs) { s0 = rs[row]; s1 = rs[row + 1]; s2 = rs[row + 2]; s3 = rs[row + 3]; }
;         const u32x2 v = {cvtpk(acc[mi][ni][4 * rg] * s0, acc[mi][ni][4 * rg + 1] * s1), cvtpk(acc[mi][ni][4 * rg + 2] * s2, acc[mi][ni][4 * rg + 3] * s3)};
;         *reinterpret_cast<u32x2*>(dst + (long)(ni * 32 + l32) * T + row) = v;
;       }
; }
.LBB0_1922:
	s_mov_b64 s[30:31], 0x6c000
	v_lshl_add_u64 v[182:183], v[182:183], 0, s[30:31]
	s_waitcnt lgkmcnt(0)
	v_pk_mul_f32 v[200:201], v[64:65], v[200:201]
	v_pk_mul_f32 v[198:199], v[66:67], v[198:199]
	v_cvt_pk_bf16_f32 v200, v200, v201
	v_cvt_pk_bf16_f32 v201, v198, v199
	v_lshl_add_u64 v[198:199], v[176:177], 1, v[182:183]
	global_store_dwordx2 v[198:199], v[200:201], off
	s_and_b64 vcc, exec, s[2:3]
	v_mov_b32_e32 v197, 1.0
	v_mov_b32_e32 v198, 1.0
	v_mov_b32_e32 v199, 1.0
	s_cbranch_vccnz .LBB0_1924
	ds_read2_b32 v[196:197], v224 offset0:8 offset1:9
	ds_read2_b32 v[198:199], v224 offset0:10 offset1:11

;   DI const float* c() const { return (const float*)sp[1]; }
; DI int TID() { int t = threadIdx.x; asm volatile("" : "+v"(t)); return t; }
; DI bf16x8 pack8f(const float* v) { u32x4 w = {cvtpk(v[0], v[1]), cvtpk(v[2], v[3]), cvtpk(v[4], v[5]), cvtpk(v[6], v[7])}; return __builtin_bit_cast(bf16x8, w); }
; DI void store_T(const float* Cs, int cb, int nc, bfu* dst, long ldT, float scale, const float* rs = nullptr) {
;   for (int u = TID(); u < nc * 16; u += NT) {
;     int c = u % nc, rc = (u / nc) * 8; float v[8];
;     for (int j = 0; j < 8; ++j) v[j] = Cs[(rc + j) * CLD + cb + c] * (rs ? scale * rs[rc + j] : scale);
;     st8(dst + c * ldT + rc, pack8f(v));
;   }
; }
; DI void epi_ukv(const Params& p, float* Cs, int m0, int n0, const float* rsl) {
;     ...
;   else store_T(Cs, 0, 128, (bfu*)(G + L1_VT) + ((long)(bg * 16 + head) * 128) * T + t0, T, 1.f, rsl);
.LBB0_1968:
	s_mov_b32 s2, 0xfff70000
	s_waitcnt lgkmcnt(0)
	v_mul_f32_e32 v5, v5, v7
	v_mul_f32_e32 v9, v9, v6
	v_mad_u64_u32 v[6:7], s[2:3], v3, s2, v[0:1]
	v_ashrrev_i32_e32 v7, 31, v6
	v_mul_f32_e32 v19, v19, v20
	v_mul_f32_e32 v14, v14, v16
	v_mul_f32_e32 v15, v17, v15
	v_mul_f32_e32 v10, v10, v12
	v_mul_f32_e32 v11, v13, v11
	v_mul_f32_e32 v12, v8, v18
	v_lshl_add_u64 v[6:7], s[24:25], 0, v[6:7]
	v_ashrrev_i32_e32 v3, 31, v2
	v_lshl_add_u64 v[2:3], v[2:3], 1, v[6:7]
	v_cvt_pk_bf16_f32 v6, v5, v9
	v_cvt_pk_bf16_f32 v7, v10, v11
	v_cvt_pk_bf16_f32 v8, v14, v15
	v_cvt_pk_bf16_f32 v9, v19, v12
	global_store_dwordx4 v[2:3], v[6:9], off
	v_add_u32_e32 v2, 0x100, v1
	v_cmp_lt_i32_e32 vcc, s53, v1
	v_add_u32_e32 v0, 0x120000, v0
	v_add_u32_e32 v4, 0x400, v4
	s_or_b64 s[30:31], vcc, s[30:31]
	v_mov_b32_e32 v1, v2
	s_andn2_b64 exec, exec, s[30:31]
	s_cbranch_execz .LBB0_1985

; DI int TID() { int t = threadIdx.x; asm volatile("" : "+v"(t)); return t; }
; DI bf16x8 pack8f(const float* v) { u32x4 w = {cvtpk(v[0], v[1]), cvtpk(v[2], v[3]), cvtpk(v[4], v[5]), cvtpk(v[6], v[7])}; return __builtin_bit_cast(bf16x8, w); }
; DI void store_R(const float* Cs, int cb, int nc, bfu* dst, long ld, float scale, const float* rs = nullptr) {
;   const int cpr = nc >> 3;
;   for (int u = TID(); u < 128 * cpr; u += NT) {
;     int row = u / cpr, c8 = (u % cpr) * 8; float v[8]; ldrow8(Cs, row, cb + c8, v);
;     float s = rs ? scale * rs[row] : scale;
;     for (int j = 0; j < 8; ++j) v[j] *= s;
;     st8(dst + row * ld + c8, pack8f(v));
;   }
; }
; DI void epi_ukv(const Params& p, float* Cs, int m0, int n0, const float* rsl) {
;     ...
;   if ((n0 & 255) == 0) store_R(Cs, 0, 128, (bfu*)(G + L1_K) + ((long)(bg * 16 + head) * T + t0) * 192, 192, 1.f, rsl);
.LBB0_1990:
	v_lshlrev_b32_e32 v13, 7, v12
	v_sub_u32_e32 v14, v10, v13
	s_waitcnt lgkmcnt(0)
	v_pk_mul_f32 v[16:17], v[0:1], v[8:9] op_sel_hi:[1,0]
	v_mov_b64_e32 v[0:1], s[24:25]
	v_pk_mul_f32 v[4:5], v[4:5], v[8:9] op_sel_hi:[1,0]
	v_pk_mul_f32 v[6:7], v[6:7], v[8:9] op_sel_hi:[1,0]
	v_pk_mul_f32 v[18:19], v[2:3], v[8:9] op_sel_hi:[1,0]
	v_mad_i64_i32 v[0:1], s[28:29], v12, s74, v[0:1]
	v_ashrrev_i32_e32 v15, 31, v14
	v_lshl_add_u64 v[12:13], v[14:15], 1, v[0:1]
	v_cvt_pk_bf16_f32 v0, v4, v5
	v_cvt_pk_bf16_f32 v1, v6, v7
	v_cvt_pk_bf16_f32 v2, v16, v17
	v_cvt_pk_bf16_f32 v3, v18, v19
	global_store_dwordx4 v[12:13], v[0:3], off
	v_cmp_lt_i32_e32 vcc, s53, v9
	v_add_u32_e32 v10, 0x800, v10
	v_add_u32_e32 v0, 0x100, v9
	v_add_u32_e32 v11, 0x2000, v11
	s_or_b64 s[26:27], vcc, s[26:27]
	v_mov_b32_e32 v9, v0
	s_andn2_b64 exec, exec, s[26:27]
	s_cbranch_execz .LBB0_1993

; DI int TID() { int t = threadIdx.x; asm volatile("" : "+v"(t)); return t; }
; DI bf16x8 pack8f(const float* v) { u32x4 w = {cvtpk(v[0], v[1]), cvtpk(v[2], v[3]), cvtpk(v[4], v[5]), cvtpk(v[6], v[7])}; return __builtin_bit_cast(bf16x8, w); }
; DI void store_R(const float* Cs, int cb, int nc, bfu* dst, long ld, float scale, const float* rs = nullptr) {
;   const int cpr = nc >> 3;
;   for (int u = TID(); u < 128 * cpr; u += NT) {
;     int row = u / cpr, c8 = (u % cpr) * 8; float v[8]; ldrow8(Cs, row, cb + c8, v);
;     float s = rs ? scale * rs[row] : scale;
;     for (int j = 0; j < 8; ++j) v[j] *= s;
;     st8(dst + row * ld + c8, pack8f(v));
;   }
; }
; DI void epi_uq(const Params& p, float* Cs, int m0, int n0, const float* rsl) {
;     ...
;     store_R(Cs, gq * 64, 64, (bfu*)(G + L1_Q) + ((long)(bg * 16 + head) * T + t0) * 192 + part * 64, 192, 0.07216878364870323f * LOG2E, rsl);
.LBB0_2004:
	v_lshlrev_b32_e32 v13, 6, v12
	v_sub_u32_e32 v14, v11, v13
	s_waitcnt lgkmcnt(0)
	v_pk_mul_f32 v[16:17], v[0:1], v[10:11] op_sel_hi:[1,0]
	v_mov_b64_e32 v[0:1], s[24:25]
	v_pk_mul_f32 v[4:5], v[4:5], v[10:11] op_sel_hi:[1,0]
	v_pk_mul_f32 v[6:7], v[6:7], v[10:11] op_sel_hi:[1,0]
	v_pk_mul_f32 v[18:19], v[2:3], v[10:11] op_sel_hi:[1,0]
	v_mad_i64_i32 v[0:1], s[30:31], v12, s74, v[0:1]
	v_ashrrev_i32_e32 v15, 31, v14
	v_lshl_add_u64 v[12:13], v[14:15], 1, v[0:1]
	v_cvt_pk_bf16_f32 v0, v4, v5
	v_cvt_pk_bf16_f32 v1, v6, v7
	v_cvt_pk_bf16_f32 v2, v16, v17
	v_cvt_pk_bf16_f32 v3, v18, v19
	global_store_dwordx4 v[12:13], v[0:3], off
	v_cmp_lt_i32_e32 vcc, s87, v9
	v_add_u32_e32 v11, 0x800, v11
	v_add_u32_e32 v0, 0x100, v9
	v_add_u32_e32 v8, 0x2000, v8
	s_or_b64 s[26:27], vcc, s[26:27]
	v_mov_b32_e32 v9, v0
	s_andn2_b64 exec, exec, s[26:27]
	s_cbranch_execz .LBB0_2007

; DI int TID() { int t = threadIdx.x; asm volatile("" : "+v"(t)); return t; }
; DI bf16x8 pack8f(const float* v) { u32x4 w = {cvtpk(v[0], v[1]), cvtpk(v[2], v[3]), cvtpk(v[4], v[5]), cvtpk(v[6], v[7])}; return __builtin_bit_cast(bf16x8, w); }
; DI void store_R(const float* Cs, int cb, int nc, bfu* dst, long ld, float scale, const float* rs = nullptr) {
;   const int cpr = nc >> 3;
;   for (int u = TID(); u < 128 * cpr; u += NT) {
;     int row = u / cpr, c8 = (u % cpr) * 8; float v[8]; ldrow8(Cs, row, cb + c8, v);
;     float s = rs ? scale * rs[row] : scale;
;     for (int j = 0; j < 8; ++j) v[j] *= s;
;     st8(dst + row * ld + c8, pack8f(v));
;   }
; }
; DI void epi_uq(const Params& p, float* Cs, int m0, int n0, const float* rsl) {
;     ...
;     store_R(Cs, gq * 64, 64, (bfu*)(G + L1_Q) + ((long)(bg * 16 + head) * T + t0) * 192 + part * 64, 192, 0.07216878364870323f * LOG2E, rsl);
.LBB0_2015:
	v_lshlrev_b32_e32 v13, 6, v12
	v_sub_u32_e32 v14, v11, v13
	s_waitcnt lgkmcnt(0)
	v_pk_mul_f32 v[16:17], v[0:1], v[10:11] op_sel_hi:[1,0]
	v_mov_b64_e32 v[0:1], s[20:21]
	v_pk_mul_f32 v[4:5], v[4:5], v[10:11] op_sel_hi:[1,0]
	v_pk_mul_f32 v[6:7], v[6:7], v[10:11] op_sel_hi:[1,0]
	v_pk_mul_f32 v[18:19], v[2:3], v[10:11] op_sel_hi:[1,0]
	v_mad_i64_i32 v[0:1], s[24:25], v12, s74, v[0:1]
	v_ashrrev_i32_e32 v15, 31, v14
	v_lshl_add_u64 v[12:13], v[14:15], 1, v[0:1]
	v_cvt_pk_bf16_f32 v0, v4, v5
	v_cvt_pk_bf16_f32 v1, v6, v7
	v_cvt_pk_bf16_f32 v2, v16, v17
	v_cvt_pk_bf16_f32 v3, v18, v19
	global_store_dwordx4 v[12:13], v[0:3], off
	v_cmp_lt_i32_e32 vcc, s87, v9
	v_add_u32_e32 v8, 0x2000, v8
	v_add_u32_e32 v0, 0x100, v9
	v_add_u32_e32 v11, 0x800, v11
	s_or_b64 s[22:23], vcc, s[22:23]
	v_mov_b32_e32 v9, v0
	s_andn2_b64 exec, exec, s[22:23]
	s_cbranch_execz .LBB0_1738

;   DI const float* x() const { return (const float*)sp[0]; }
;   DI const float* c() const { return (const float*)sp[1]; }
; __device__ __forceinline__ unsigned xb_ld(unsigned* p)              { return __hip_atomic_load(p, __ATOMIC_RELAXED, __HIP_MEMORY_SCOPE_AGENT); }
; __device__ __forceinline__ void xcd_barrier_complete(unsigned* bar, unsigned x, unsigned& nloc, unsigned& nx) {
;     const unsigned G = gridDim.x * gridDim.y * gridDim.z;
;     unsigned sum, cnt, mine, sp = 0u;
;     for (;;) {
;         sum = 0u; cnt = 0u; mine = 0u;
; #pragma unroll
;         for (unsigned j = 0; j < 16; ++j) { const unsigned c = xb_ld(&bar[XB_XCNT(j)]); sum += c; cnt += (c > 0u) ? 1u : 0u; mine = (j == x) ? c : mine; }
;         if (sum == G) break;
;         __builtin_amdgcn_s_sleep(1);
;         if ((++sp & 255u) == 0u) { if (xb_ld(&bar[XB_TMO])) break; if (sp > XB_SPIN_CAP) { atomicAdd(&bar[XB_TMO], 1u); break; } }
;     }
;     nloc = mine > 0u ? mine : 1u; nx = cnt > 0u ? cnt : 1u;
; }
.LBB0_2023:
	s_waitcnt lgkmcnt(0)
	v_mov_b64_e32 v[0:1], s[2:3]
	v_mov_b64_e32 v[2:3], s[4:5]
	global_load_dword v0, v[0:1], off sc1
	v_readlane_b32 s40, v254, 15
	global_load_dword v1, v[2:3], off sc1
	v_mov_b64_e32 v[2:3], s[6:7]
	global_load_dword v2, v[2:3], off sc1
	s_or_b64 s[92:93], s[92:93], exec
	s_or_b64 s[70:71], s[70:71], exec
	s_waitcnt vmcnt(0) lgkmcnt(0)
	v_add_u32_e32 v4, v1, v0
	v_add_u32_e32 v6, v4, v2
	v_mov_b64_e32 v[4:5], s[8:9]
	global_load_dword v3, v[4:5], off sc1
	v_mov_b64_e32 v[4:5], s[10:11]
	global_load_dword v4, v[4:5], off sc1
	s_waitcnt vmcnt(0) lgkmcnt(0)
	v_add_u32_e32 v6, v6, v3
	v_add_u32_e32 v8, v6, v4
	v_mov_b64_e32 v[6:7], s[12:13]
	global_load_dword v5, v[6:7], off sc1
	v_mov_b64_e32 v[6:7], s[14:15]
	global_load_dword v6, v[6:7], off sc1
	s_waitcnt vmcnt(0) lgkmcnt(0)
	v_add_u32_e32 v8, v8, v5
	v_add_u32_e32 v10, v8, v6
	v_mov_b64_e32 v[8:9], s[16:17]
	global_load_dword v7, v[8:9], off sc1
	v_mov_b64_e32 v[8:9], s[18:19]
	global_load_dword v8, v[8:9], off sc1
	s_waitcnt vmcnt(0) lgkmcnt(0)
	v_add_u32_e32 v10, v10, v7
	v_add_u32_e32 v12, v10, v8
	v_mov_b64_e32 v[10:11], s[20:21]
	global_load_dword v9, v[10:11], off sc1
	v_mov_b64_e32 v[10:11], s[22:23]
	global_load_dword v10, v[10:11], off sc1
	s_waitcnt vmcnt(0) lgkmcnt(0)
	v_add_u32_e32 v12, v12, v9
	v_add_u32_e32 v14, v12, v10
	v_mov_b64_e32 v[12:13], s[24:25]
	global_load_dword v11, v[12:13], off sc1
	v_mov_b64_e32 v[12:13], s[26:27]
	global_load_dword v12, v[12:13], off sc1
	s_waitcnt vmcnt(0) lgkmcnt(0)
	v_add_u32_e32 v14, v14, v11
	v_add_u32_e32 v16, v14, v12
	v_mov_b64_e32 v[14:15], s[28:29]
	global_load_dword v13, v[14:15], off sc1
	v_mov_b64_e32 v[14:15], s[36:37]
	global_load_dword v14, v[14:15], off sc1
	s_waitcnt vmcnt(0) lgkmcnt(0)
	v_add_u32_e32 v16, v16, v13
	v_add_u32_e32 v18, v16, v14
	v_mov_b64_e32 v[16:17], s[38:39]
	global_load_dword v15, v[16:17], off sc1
	s_waitcnt vmcnt(0) lgkmcnt(0)
	v_add_u32_e32 v16, v18, v15
	v_cmp_ne_u32_e32 vcc, s40, v16
	s_and_saveexec_b64 s[94:95], vcc
	s_cbranch_execz .LBB0_2022
	s_and_b32 s40, s90, 0xff
	s_mov_b64 s[96:97], -1
	s_cmp_eq_u32 s40, 0
	s_mov_b64 s[40:41], -1
	s_mov_b64 s[46:47], -1
	s_sleep 1
	s_cbranch_scc1 .LBB0_2026
	s_and_saveexec_b64 s[62:63], s[40:41]
	s_cbranch_execz .LBB0_2021
	s_branch .LBB0_2029
.LBB0_2026:
	v_mov_b64_e32 v[16:17], s[0:1]
	global_load_dword v16, v[16:17], off sc1
	s_mov_b64 s[40:41], 0
	s_waitcnt vmcnt(0) lgkmcnt(0)
	v_cmp_eq_u32_e32 vcc, 0, v16
	s_and_saveexec_b64 s[62:63], vcc
	s_cmp_lt_u32 s90, 0x40001
	s_cselect_b64 s[40:41], -1, 0
	s_xor_b64 s[46:47], exec, -1
	s_and_b64 s[40:41], s[40:41], exec
	s_or_b64 exec, exec, s[62:63]
	s_and_saveexec_b64 s[62:63], s[40:41]
	s_cbranch_execz .LBB0_2021

; DI int TID() { int t = threadIdx.x; asm volatile("" : "+v"(t)); return t; }
; #define ATT_LOADK(key0)                                                                                  \
;   do {                                                                                                   \
;     _Pragma("unroll") for (int i = 0; i < KCH; ++i) { int c = tid + NT * i; kr[i] = ld8(Kp + (long)((key0) + c / CPR) * DK + (c % CPR) * 8); } \
;   } while (0)
; #define ATT_LOADV(key0)                                                                                  \
;   do {                                                                                                   \
;     _Pragma("unroll") for (int i = 0; i < VCH; ++i) { int c = tid + NT * i; vr[i] = ld8(Vtp + (long)(c / VPR) * T + (key0) + (c % VPR) * 8); }  \
;   } while (0)
; template <int DK, int KT>
; DI void attn_item(const bfu* __restrict__ Qp, const bfu* __restrict__ Kp, const bfu* __restrict__ Vtp, int nkeys, bfu* __restrict__ Op, int ldo, char* smem) {
;   constexpr int LK = DK + 8, LV = KT + 8, NKS = DK / 16, CPR = DK / 8, KCH = KT * CPR / NT, VPR = KT / 8, VCH = 128 * VPR / NT, NBK = KT / 32;
;   bfu* Ks = (bfu*)smem; bfu* Vs = Ks + KT * LK;
;   const int tid = TID(), lane = tid & 63, w = tid >> 6, l32 = lane & 31, hi = lane >> 5;
;   bf16x8 qf[NKS];
;   {
;     const bfu* qrow = Qp + (long)(w * 32 + l32) * DK + hi * 8;
; #pragma unroll
;     for (int ks = 0; ks < NKS; ++ks) qf[ks] = ld8(qrow + ks * 16);
;   }
;   f32x16 o[4];
; #pragma unroll
;   for (int d = 0; d < 4; ++d)
; #pragma unroll
;     for (int r = 0; r < 16; ++r) o[d][r] = 0.f;
;   float m = -1e30f, lsum = 0.f;
;   bf16x8 kr[KCH], vr[VCH];
;     ...
;   ATT_LOADK(0); ATT_LOADV(0);
; template <int layer, int part>
; DI void phase_mix(const Params& p, int cidx, char* smem, int* s_item) {
;     ...
;       const int pl = a >> 4, t0 = CTX + (a & 15) * 128;
;       const int pair = pl * 8 + xcd, bg = pair >> 4, h = pair & 15;
;       attn_item<192, 64>((const bfu*)(G + L1_Q) + ((long)(bg * 16 + h) * T + t0) * 192, (const bfu*)(G + L1_K) + (long)(bg * 16 + h) * T * 192,
;                      (const bfu*)(G + L1_VT) + (long)(bg * 16 + h) * 128 * T, T, (bfu*)(G + L1_OA) + ((long)bg * T + t0) * 2048 + h * 128, 2048, smem);
.LBB0_2070:
	s_lshl_b32 s5, s4, 7
	s_and_b32 s5, s5, 0x780
	s_add_i32 s7, s5, 0x100
	s_lshr_b32 s5, s4, 1
	s_and_b32 s9, s5, 8
	s_ashr_i32 s8, s4, 5
	s_or_b32 s6, s9, s33
	s_lshl_b32 s18, s8, 4
	s_or_b32 s4, s6, s18
	s_mul_i32 s19, s4, 0x900
	s_mul_hi_i32 s5, s4, 0x900
	s_add_u32 s19, s19, s7
	s_addc_u32 s5, s5, 0
	s_mulk_i32 s5, 0x180
	s_mul_hi_u32 s20, s19, 0x180
	s_add_i32 s5, s20, s5
	s_mulk_i32 s19, 0x180
	s_add_u32 s20, s10, s19
	v_mov_b32_e32 v18, v202
	s_addc_u32 s21, s11, s5
	s_mul_i32 s19, s4, 0xd8000
	v_ashrrev_i32_e32 v0, 1, v18
	v_bfe_u32 v2, v18, 5, 1
	v_bfi_b32 v168, s39, v0, v18
	v_mov_b64_e32 v[0:1], s[20:21]
	v_mad_i64_i32 v[0:1], s[20:21], v168, s74, v[0:1]
	v_lshlrev_b32_e32 v184, 3, v2
	v_lshlrev_b32_e32 v2, 4, v2
	v_mov_b32_e32 v3, v185
	s_add_u32 s22, s12, s19
	v_lshl_add_u64 v[0:1], v[0:1], 0, v[2:3]
	s_mov_b32 s19, 0x2aaaaaab
	global_load_dwordx4 v[140:143], v[0:1], off
	global_load_dwordx4 v[136:139], v[0:1], off offset:32
	global_load_dwordx4 v[132:135], v[0:1], off offset:64
	global_load_dwordx4 v[128:131], v[0:1], off offset:96
	global_load_dwordx4 v[124:127], v[0:1], off offset:128
	global_load_dwordx4 v[120:123], v[0:1], off offset:160
	global_load_dwordx4 v[116:119], v[0:1], off offset:192
	global_load_dwordx4 v[112:115], v[0:1], off offset:224
	global_load_dwordx4 v[108:111], v[0:1], off offset:256
	global_load_dwordx4 v[104:107], v[0:1], off offset:288
	global_load_dwordx4 v[100:103], v[0:1], off offset:320
	global_load_dwordx4 v[96:99], v[0:1], off offset:352
	v_mul_hi_i32 v0, v18, s19
	v_add_u32_e32 v22, 0x100, v18
	v_lshrrev_b32_e32 v1, 31, v0
	v_ashrrev_i32_e32 v0, 2, v0
	v_mul_hi_i32 v8, v22, s19
	v_add_u32_e32 v27, v0, v1
	v_lshrrev_b32_e32 v9, 31, v8
	v_ashrrev_i32_e32 v8, 2, v8
	v_mul_lo_u32 v3, v27, 24
	v_add_u32_e32 v28, v8, v9
	s_mul_hi_i32 s5, s4, 0xd8000
	v_sub_u32_e32 v3, v18, v3
	v_mul_lo_u32 v10, v28, 24
	s_addc_u32 s23, s13, s5
	v_lshlrev_b32_e32 v6, 3, v3
	v_sub_u32_e32 v29, v22, v10
	v_mov_b64_e32 v[0:1], s[22:23]
	v_ashrrev_i32_e32 v7, 31, v6
	v_lshlrev_b32_e32 v10, 3, v29
	v_mad_i64_i32 v[4:5], s[20:21], v27, s74, v[0:1]
	v_lshlrev_b64 v[6:7], 1, v[6:7]
	v_ashrrev_i32_e32 v11, 31, v10
	v_lshl_add_u64 v[4:5], v[4:5], 0, v[6:7]
	v_mad_i64_i32 v[8:9], s[20:21], v28, s74, v[0:1]
	v_lshlrev_b64 v[10:11], 1, v[10:11]
	v_add_u32_e32 v24, 0x200, v18
	v_add_u32_e32 v25, 0x300, v18
	v_lshl_add_u64 v[8:9], v[8:9], 0, v[10:11]
	global_load_dwordx4 v[144:147], v[4:5], off
	global_load_dwordx4 v[148:151], v[8:9], off
	v_mul_hi_i32 v4, v24, s19
	v_mul_hi_i32 v12, v25, s19
	v_lshrrev_b32_e32 v5, 31, v4
	v_ashrrev_i32_e32 v4, 2, v4
	v_lshrrev_b32_e32 v13, 31, v12
	v_ashrrev_i32_e32 v12, 2, v12
	v_add_u32_e32 v30, v4, v5
	v_add_u32_e32 v32, v12, v13
	v_mul_lo_u32 v8, v30, 24
	v_mul_lo_u32 v14, v32, 24
	v_sub_u32_e32 v31, v24, v8
	v_sub_u32_e32 v33, v25, v14
	v_lshlrev_b32_e32 v8, 3, v31
	v_lshlrev_b32_e32 v14, 3, v33
	v_ashrrev_i32_e32 v9, 31, v8
	v_ashrrev_i32_e32 v15, 31, v14
	v_mad_i64_i32 v[4:5], s[20:21], v30, s74, v[0:1]
	v_lshlrev_b64 v[8:9], 1, v[8:9]
	v_mad_i64_i32 v[12:13], s[20:21], v32, s74, v[0:1]
	v_lshlrev_b64 v[14:15], 1, v[14:15]
	v_lshl_add_u64 v[4:5], v[4:5], 0, v[8:9]
	v_lshl_add_u64 v[12:13], v[12:13], 0, v[14:15]
	global_load_dwordx4 v[152:155], v[4:5], off
	global_load_dwordx4 v[156:159], v[12:13], off
	v_add_u32_e32 v12, 0x400, v18
	v_add_u32_e32 v16, 0x500, v18
	v_mul_hi_i32 v4, v12, s19
	v_mul_hi_i32 v17, v16, s19
	v_lshrrev_b32_e32 v5, 31, v4
	v_ashrrev_i32_e32 v4, 2, v4
	v_lshrrev_b32_e32 v19, 31, v17
	v_ashrrev_i32_e32 v17, 2, v17
	v_add_u32_e32 v34, v4, v5
	v_add_u32_e32 v36, v17, v19
	v_mul_lo_u32 v13, v34, 24
	v_mul_lo_u32 v17, v36, 24
	v_sub_u32_e32 v35, v12, v13
	v_sub_u32_e32 v37, v16, v17
	v_lshlrev_b32_e32 v12, 3, v35
	v_lshlrev_b32_e32 v16, 3, v37
	v_ashrrev_i32_e32 v13, 31, v12
	v_ashrrev_i32_e32 v17, 31, v16
	v_mad_i64_i32 v[4:5], s[20:21], v34, s74, v[0:1]
	v_lshlrev_b64 v[12:13], 1, v[12:13]
	v_mad_i64_i32 v[0:1], s[20:21], v36, s74, v[0:1]
	v_lshlrev_b64 v[16:17], 1, v[16:17]
	v_lshl_add_u64 v[4:5], v[4:5], 0, v[12:13]
	v_lshl_add_u64 v[0:1], v[0:1], 0, v[16:17]
	global_load_dwordx4 v[160:163], v[4:5], off
	global_load_dwordx4 v[164:167], v[0:1], off
	v_ashrrev_i32_e32 v0, 31, v18
	v_lshrrev_b32_e32 v0, 29, v0
	v_ashrrev_i32_e32 v20, 31, v22
	v_add_u32_e32 v19, v18, v0
	v_lshrrev_b32_e32 v20, 29, v20
	s_mul_hi_i32 s5, s4, 0x90000
	s_mul_i32 s4, s4, 0x90000
	v_ashrrev_i32_e32 v38, 3, v19
	v_and_b32_e32 v19, -8, v19
	v_add_u32_e32 v23, v22, v20
	s_add_u32 s4, s14, s4
	v_sub_u32_e32 v39, v18, v19
	v_ashrrev_i32_e32 v40, 3, v23
	v_and_b32_e32 v23, -8, v23
	s_addc_u32 s5, s15, s5
	v_and_b32_e32 v26, 31, v18
	v_lshlrev_b32_e32 v18, 3, v39
	v_sub_u32_e32 v41, v22, v23
	v_mov_b64_e32 v[0:1], s[4:5]
	v_ashrrev_i32_e32 v19, 31, v18
	v_lshlrev_b32_e32 v22, 3, v41
	v_mad_i64_i32 v[4:5], s[4:5], v38, s75, v[0:1]
	v_lshlrev_b64 v[18:19], 1, v[18:19]
	v_ashrrev_i32_e32 v23, 31, v22
	v_lshl_add_u64 v[4:5], v[4:5], 0, v[18:19]
	v_mad_i64_i32 v[20:21], s[4:5], v40, s75, v[0:1]
	v_lshlrev_b64 v[22:23], 1, v[22:23]
	v_lshl_add_u64 v[20:21], v[20:21], 0, v[22:23]
	global_load_dwordx4 v[64:67], v[4:5], off
	global_load_dwordx4 v[68:71], v[20:21], off
	v_ashrrev_i32_e32 v4, 31, v24
	v_lshrrev_b32_e32 v4, 29, v4
	v_add_u32_e32 v20, v24, v4
	v_ashrrev_i32_e32 v42, 3, v20
	v_and_b32_e32 v20, -8, v20
	v_sub_u32_e32 v43, v24, v20
	v_ashrrev_i32_e32 v24, 31, v25
	v_lshrrev_b32_e32 v24, 29, v24
	v_add_u32_e32 v24, v25, v24
	v_ashrrev_i32_e32 v44, 3, v24
	v_and_b32_e32 v24, -8, v24
	v_lshlrev_b32_e32 v20, 3, v43
	v_sub_u32_e32 v45, v25, v24
	v_ashrrev_i32_e32 v21, 31, v20
;   DI const float* c() const { return (const float*)sp[1]; }
; #define ATT_LOADK(key0)                                                                                  \
;   do {                                                                                                   \
;     _Pragma("unroll") for (int i = 0; i < KCH; ++i) { int c = tid + NT * i; kr[i] = ld8(Kp + (long)((key0) + c / CPR) * DK + (c % CPR) * 8); } \
;   } while (0)
; #define ATT_LOADV(key0)                                                                                  \
;   do {                                                                                                   \
;     _Pragma("unroll") for (int i = 0; i < VCH; ++i) { int c = tid + NT * i; vr[i] = ld8(Vtp + (long)(c / VPR) * T + (key0) + (c % VPR) * 8); }  \
;   } while (0)
; template <int DK, int KT>
; DI void attn_item(const bfu* __restrict__ Qp, const bfu* __restrict__ Kp, const bfu* __restrict__ Vtp, int nkeys, bfu* __restrict__ Op, int ldo, char* smem) {
;     ...
;   f32x16 o[4];
; #pragma unroll
;   for (int d = 0; d < 4; ++d)
; #pragma unroll
;     for (int r = 0; r < 16; ++r) o[d][r] = 0.f;
;   float m = -1e30f, lsum = 0.f;
;   bf16x8 kr[KCH], vr[VCH];
;     ...
;   ATT_LOADK(0); ATT_LOADV(0);
;   const int NTL = nkeys / KT;
;   for (int j = 0; j < NTL; ++j) {
;     __syncthreads();
; #pragma unroll
;     for (int i = 0; i < KCH; ++i) { int c = tid + NT * i; st8(Ks + (c / CPR) * LK + (c % CPR) * 8, kr[i]); }
; #pragma unroll
;     for (int i = 0; i < VCH; ++i) { int c = tid + NT * i; st8(Vs + (c / VPR) * LV + (c % VPR) * 8, vr[i]); }
;     __syncthreads();
	v_lshlrev_b32_e32 v24, 3, v45
	v_mad_i64_i32 v[4:5], s[4:5], v42, s75, v[0:1]
	v_lshlrev_b64 v[20:21], 1, v[20:21]
	v_ashrrev_i32_e32 v25, 31, v24
	v_lshl_add_u64 v[4:5], v[4:5], 0, v[20:21]
	v_mad_i64_i32 v[0:1], s[4:5], v44, s75, v[0:1]
	v_lshlrev_b64 v[24:25], 1, v[24:25]
	v_lshl_add_u64 v[0:1], v[0:1], 0, v[24:25]
	global_load_dwordx4 v[72:75], v[4:5], off
	global_load_dwordx4 v[76:79], v[0:1], off
	s_movk_i32 s4, 0x190
	v_mad_u32_u24 v197, v26, s4, v2
	v_mul_lo_u32 v46, v27, s4
	v_mul_lo_u32 v48, v28, s4
	v_mul_lo_u32 v49, v30, s4
	v_mul_lo_u32 v50, v32, s4
	v_mul_lo_u32 v51, v34, s4
	v_mul_lo_u32 v52, v36, s4
	s_or_b32 s4, s33, s18
	v_and_b32_e32 v1, 64, v203
	s_or_b32 s9, s4, s9
	v_xor_b32_e32 v0, 32, v203
	v_add_u32_e32 v1, 64, v1
	s_mul_i32 s4, s9, 0x90000
	v_cmp_lt_i32_e32 vcc, v0, v1
	s_mul_hi_i32 s5, s9, 0x90000
	s_add_u32 s4, s4, 0xa200080
	v_cndmask_b32_e32 v0, v203, v0, vcc
	s_addc_u32 s5, s5, 0
	v_lshlrev_b32_e32 v195, 2, v0
	v_mov_b64_e32 v[0:1], s[4:5]
	v_lshlrev_b32_e32 v47, 4, v3
	v_mad_i64_i32 v[2:3], s[4:5], v44, s75, v[0:1]
	v_lshl_add_u64 v[170:171], v[2:3], 0, v[24:25]
	v_mad_i64_i32 v[2:3], s[4:5], v42, s75, v[0:1]
	v_lshl_add_u64 v[172:173], v[2:3], 0, v[20:21]
	v_mad_i64_i32 v[2:3], s[4:5], v40, s75, v[0:1]
	v_mad_i64_i32 v[0:1], s[4:5], v38, s75, v[0:1]
	s_mul_hi_i32 s5, s9, 0xd8000
	s_mul_i32 s9, s9, 0xd8000
	s_add_u32 s4, s9, 0x8706000
	s_addc_u32 s5, s5, 0
	v_lshl_add_u64 v[176:177], v[0:1], 0, v[18:19]
	v_mov_b64_e32 v[0:1], s[4:5]
	v_lshl_add_u64 v[174:175], v[2:3], 0, v[22:23]
	v_mad_i64_i32 v[2:3], s[4:5], v36, s74, v[0:1]
	v_lshl_add_u64 v[178:179], v[2:3], 0, v[16:17]
	v_mad_i64_i32 v[2:3], s[4:5], v34, s74, v[0:1]
	v_lshl_add_u64 v[180:181], v[2:3], 0, v[12:13]
	v_mad_i64_i32 v[2:3], s[4:5], v32, s74, v[0:1]
	v_lshl_add_u64 v[182:183], v[2:3], 0, v[14:15]
	v_mad_i64_i32 v[2:3], s[4:5], v30, s74, v[0:1]
	v_mul_u32_u24_e32 v26, 0x90, v26
	v_lshlrev_b32_e32 v29, 4, v29
	v_lshlrev_b32_e32 v31, 4, v31
	v_lshlrev_b32_e32 v33, 4, v33
	v_lshlrev_b32_e32 v35, 4, v35
	v_lshlrev_b32_e32 v37, 4, v37
	v_mul_lo_u32 v53, v38, s50
	v_lshlrev_b32_e32 v39, 4, v39
	v_mul_lo_u32 v54, v40, s50
	v_lshlrev_b32_e32 v41, 4, v41
	v_mul_lo_u32 v55, v42, s50
	v_lshlrev_b32_e32 v43, 4, v43
	v_mul_lo_u32 v56, v44, s50
	v_lshlrev_b32_e32 v45, 4, v45
	v_lshl_add_u64 v[188:189], v[2:3], 0, v[8:9]
	v_mad_i64_i32 v[2:3], s[4:5], v28, s74, v[0:1]
	v_mad_i64_i32 v[0:1], s[4:5], v27, s74, v[0:1]
	v_mov_b32_e32 v14, v185
	v_mov_b32_e32 v15, v185
	v_lshl_add_u64 v[190:191], v[2:3], 0, v[10:11]
	v_lshl_add_u64 v[192:193], v[0:1], 0, v[6:7]
	v_mov_b32_e32 v0, v185
	v_mov_b32_e32 v1, v185
	v_mov_b32_e32 v2, v185
	v_mov_b32_e32 v3, v185
	v_mov_b32_e32 v4, v185
	v_mov_b32_e32 v5, v185
	v_mov_b32_e32 v6, v185
	v_mov_b32_e32 v7, v185
	v_mov_b32_e32 v8, v185
	v_mov_b32_e32 v9, v185
	v_mov_b32_e32 v10, v185
	v_mov_b32_e32 v11, v185
	v_mov_b32_e32 v12, v185
	v_mov_b32_e32 v13, v185
	v_add_u32_e32 v224, v46, v47
	v_add_u32_e32 v225, v48, v29
	v_add_u32_e32 v226, v49, v31
	v_add_u32_e32 v227, v50, v33
	v_add_u32_e32 v228, v51, v35
	v_add_u32_e32 v229, v52, v37
	v_add_u32_e32 v230, v53, v39
	v_add_u32_e32 v231, v54, v41
	v_add_u32_e32 v232, v55, v43
	v_add_u32_e32 v233, v56, v45
	v_add_u32_e32 v234, v184, v26
	v_mov_b64_e32 v[30:31], v[14:15]
	v_mov_b64_e32 v[46:47], v[14:15]
	v_mov_b64_e32 v[62:63], v[14:15]
	v_ashrrev_i32_e32 v169, 31, v168
	v_mov_b32_e32 v196, 0xf149f2ca
	v_mov_b32_e32 v198, 0
	s_mov_b32 s9, 35
	v_mov_b64_e32 v[28:29], v[12:13]
	v_mov_b64_e32 v[26:27], v[10:11]
	v_mov_b64_e32 v[24:25], v[8:9]
	v_mov_b64_e32 v[22:23], v[6:7]
	v_mov_b64_e32 v[20:21], v[4:5]
	v_mov_b64_e32 v[18:19], v[2:3]
	v_mov_b64_e32 v[16:17], v[0:1]
	v_mov_b64_e32 v[44:45], v[12:13]
	v_mov_b64_e32 v[42:43], v[10:11]
	v_mov_b64_e32 v[40:41], v[8:9]
	v_mov_b64_e32 v[38:39], v[6:7]
	v_mov_b64_e32 v[36:37], v[4:5]
	v_mov_b64_e32 v[34:35], v[2:3]
	v_mov_b64_e32 v[32:33], v[0:1]
	v_mov_b64_e32 v[60:61], v[12:13]
	v_mov_b64_e32 v[58:59], v[10:11]
	v_mov_b64_e32 v[56:57], v[8:9]
	v_mov_b64_e32 v[54:55], v[6:7]
	v_mov_b64_e32 v[52:53], v[4:5]
	v_mov_b64_e32 v[50:51], v[2:3]
	v_mov_b64_e32 v[48:49], v[0:1]
.LBB0_2071:
	s_waitcnt lgkmcnt(0)
	s_barrier
	s_waitcnt vmcnt(0)
	ds_write_b128 v224, v[144:147]
	ds_write_b128 v225, v[148:151]
	ds_write_b128 v226, v[152:155]
	ds_write_b128 v227, v[156:159]
	ds_write_b128 v228, v[160:163]
	ds_write_b128 v229, v[164:167]
	ds_write_b128 v230, v[64:67] offset:25600
	ds_write_b128 v231, v[68:71] offset:25600
	ds_write_b128 v232, v[72:75] offset:25600
	ds_write_b128 v233, v[76:79] offset:25600
	v_lshl_add_u64 v[64:65], s[0:1], 0, v[192:193]
	s_waitcnt lgkmcnt(0)
	s_barrier
; #define MFMA(a, b, c) __builtin_amdgcn_mfma_f32_32x32x16_bf16((a), (b), (c), 0, 0, 0)
; #define ATT_LOADK(key0)                                                                                  \
;   do {                                                                                                   \
;     _Pragma("unroll") for (int i = 0; i < KCH; ++i) { int c = tid + NT * i; kr[i] = ld8(Kp + (long)((key0) + c / CPR) * DK + (c % CPR) * 8); } \
;   } while (0)
; template <int DK, int KT>
; DI void attn_item(const bfu* __restrict__ Qp, const bfu* __restrict__ Kp, const bfu* __restrict__ Vtp, int nkeys, bfu* __restrict__ Op, int ldo, char* smem) {
;     ...
;     if (j + 1 < NTL) ATT_LOADK((j + 1) * KT);
;     f32x16 sv[NBK];
; #pragma unroll
;     for (int bk = 0; bk < NBK; ++bk)
; #pragma unroll
;       for (int r = 0; r < 16; ++r) sv[bk][r] = 0.f;
;     const bfu* k0p = Ks + l32 * LK + hi * 8;
; #pragma unroll
;     for (int ks = 0; ks < NKS; ++ks)
; #pragma unroll
;       for (int bk = 0; bk < NBK; ++bk) sv[bk] = MFMA(ld8(k0p + bk * 32 * LK + ks * 16), qf[ks], sv[bk]);
;     float mx = sv[0][0];
; #pragma unroll
;     for (int bk = 0; bk < NBK; ++bk)
; #pragma unroll
;       for (int r = 0; r < 16; ++r) mx = fmaxf(mx, sv[bk][r]);
;     mx = fmaxf(mx, __shfl_xor(mx, 32));
;     float mn = m, alpha = 1.f;
;     const bool moved = __builtin_amdgcn_ballot_w64(mx > m + 8.f) != 0ull;
;     if (moved) { mn = fmaxf(m, mx); alpha = __builtin_amdgcn_exp2f(m - mn); m = mn; }
;     float rs = 0.f;
; #pragma unroll
;     for (int bk = 0; bk < NBK; ++bk)
; #pragma unroll
;       for (int r = 0; r < 16; ++r) { sv[bk][r] = __builtin_amdgcn_exp2f(sv[bk][r] - mn); rs += sv[bk][r]; }
;     lsum = lsum * alpha + rs;
;     if (moved) {
; #pragma unroll
;       for (int d = 0; d < 4; ++d)
; #pragma unroll
;         for (int r = 0; r < 16; ++r) o[d][r] *= alpha;
;     }
	global_load_dwordx4 v[144:147], v[64:65], off
	v_lshl_add_u64 v[64:65], s[0:1], 0, v[190:191]
	global_load_dwordx4 v[148:151], v[64:65], off
	v_lshl_add_u64 v[64:65], s[0:1], 0, v[188:189]
	global_load_dwordx4 v[152:155], v[64:65], off
	v_lshl_add_u64 v[64:65], s[0:1], 0, v[182:183]
	global_load_dwordx4 v[156:159], v[64:65], off
	v_lshl_add_u64 v[64:65], s[0:1], 0, v[180:181]
	global_load_dwordx4 v[160:163], v[64:65], off
	v_lshl_add_u64 v[64:65], s[0:1], 0, v[178:179]
	global_load_dwordx4 v[164:167], v[64:65], off
	ds_read_b128 v[64:67], v197
	ds_read_b128 v[236:239], v197 offset:32
	s_waitcnt lgkmcnt(0)
	v_mfma_f32_32x32x16_bf16 v[80:95], v[64:67], v[140:143], 0
	ds_read_b128 v[64:67], v197 offset:12800
	v_mfma_f32_32x32x16_bf16 v[80:95], v[236:239], v[136:139], v[80:95]
	ds_read_b128 v[236:239], v197 offset:12832
	s_waitcnt lgkmcnt(0)
	v_mfma_f32_32x32x16_bf16 v[64:79], v[64:67], v[140:143], 0
	v_mfma_f32_32x32x16_bf16 v[64:79], v[236:239], v[136:139], v[64:79]
	ds_read_b128 v[236:239], v197 offset:64
	s_waitcnt lgkmcnt(0)
	v_mfma_f32_32x32x16_bf16 v[80:95], v[236:239], v[132:135], v[80:95]
	ds_read_b128 v[236:239], v197 offset:12864
	s_waitcnt lgkmcnt(0)
	v_mfma_f32_32x32x16_bf16 v[64:79], v[236:239], v[132:135], v[64:79]
	ds_read_b128 v[236:239], v197 offset:96
	s_waitcnt lgkmcnt(0)
	v_mfma_f32_32x32x16_bf16 v[80:95], v[236:239], v[128:131], v[80:95]
	ds_read_b128 v[236:239], v197 offset:12896
	s_waitcnt lgkmcnt(0)
	v_mfma_f32_32x32x16_bf16 v[64:79], v[236:239], v[128:131], v[64:79]
	ds_read_b128 v[236:239], v197 offset:128
	s_waitcnt lgkmcnt(0)
	v_mfma_f32_32x32x16_bf16 v[80:95], v[236:239], v[124:127], v[80:95]
	ds_read_b128 v[236:239], v197 offset:12928
	s_waitcnt lgkmcnt(0)
	v_mfma_f32_32x32x16_bf16 v[64:79], v[236:239], v[124:127], v[64:79]
	ds_read_b128 v[236:239], v197 offset:160
	s_waitcnt lgkmcnt(0)
	v_mfma_f32_32x32x16_bf16 v[80:95], v[236:239], v[120:123], v[80:95]
	ds_read_b128 v[236:239], v197 offset:12960
	s_waitcnt lgkmcnt(0)
	v_mfma_f32_32x32x16_bf16 v[64:79], v[236:239], v[120:123], v[64:79]
	ds_read_b128 v[236:239], v197 offset:192
	s_waitcnt lgkmcnt(0)
	v_mfma_f32_32x32x16_bf16 v[80:95], v[236:239], v[116:119], v[80:95]
	ds_read_b128 v[236:239], v197 offset:12992
	s_waitcnt lgkmcnt(0)
	v_mfma_f32_32x32x16_bf16 v[64:79], v[236:239], v[116:119], v[64:79]
	ds_read_b128 v[236:239], v197 offset:224
	s_waitcnt lgkmcnt(0)
	v_mfma_f32_32x32x16_bf16 v[80:95], v[236:239], v[112:115], v[80:95]
	ds_read_b128 v[236:239], v197 offset:13024
	s_waitcnt lgkmcnt(0)
	v_mfma_f32_32x32x16_bf16 v[64:79], v[236:239], v[112:115], v[64:79]
	ds_read_b128 v[236:239], v197 offset:256
	s_waitcnt lgkmcnt(0)
	v_mfma_f32_32x32x16_bf16 v[80:95], v[236:239], v[108:111], v[80:95]
	ds_read_b128 v[236:239], v197 offset:13056
	s_waitcnt lgkmcnt(0)
	v_mfma_f32_32x32x16_bf16 v[64:79], v[236:239], v[108:111], v[64:79]
	ds_read_b128 v[236:239], v197 offset:288
	s_waitcnt lgkmcnt(0)
	v_mfma_f32_32x32x16_bf16 v[80:95], v[236:239], v[104:107], v[80:95]
	ds_read_b128 v[236:239], v197 offset:13088
	s_waitcnt lgkmcnt(0)
	v_mfma_f32_32x32x16_bf16 v[64:79], v[236:239], v[104:107], v[64:79]
	ds_read_b128 v[236:239], v197 offset:320
	s_waitcnt lgkmcnt(0)
	v_mfma_f32_32x32x16_bf16 v[80:95], v[236:239], v[100:103], v[80:95]
	ds_read_b128 v[236:239], v197 offset:13120
	s_waitcnt lgkmcnt(0)
	v_mfma_f32_32x32x16_bf16 v[64:79], v[236:239], v[100:103], v[64:79]
	ds_read_b128 v[236:239], v197 offset:352
	s_waitcnt lgkmcnt(0)
	v_mfma_f32_32x32x16_bf16 v[80:95], v[236:239], v[96:99], v[80:95]
	ds_read_b128 v[236:239], v197 offset:13152
	s_waitcnt lgkmcnt(0)
	v_mfma_f32_32x32x16_bf16 v[64:79], v[236:239], v[96:99], v[64:79]
	s_nop 8
	v_max_f32_e32 v194, v81, v81
	v_max_f32_e32 v199, v80, v80
	v_max_f32_e32 v194, v199, v194
	v_max3_f32 v194, v194, v82, v83
	v_max3_f32 v194, v194, v84, v85
	v_max3_f32 v194, v194, v86, v87
	v_max3_f32 v194, v194, v88, v89
	v_max3_f32 v194, v194, v90, v91
	v_max3_f32 v194, v194, v92, v93
	v_max3_f32 v194, v194, v94, v95
	v_max3_f32 v194, v194, v64, v65
	v_max3_f32 v194, v194, v66, v67
	v_max3_f32 v194, v194, v68, v69
	v_max3_f32 v194, v194, v70, v71
	v_max3_f32 v194, v194, v72, v73
	v_max3_f32 v194, v194, v74, v75
	v_max3_f32 v194, v194, v76, v77
	v_max3_f32 v194, v194, v78, v79
	ds_bpermute_b32 v199, v195, v194
	s_waitcnt lgkmcnt(0)
	v_max_f32_e32 v199, v199, v199
	v_max_f32_e32 v194, v194, v199
	v_add_f32_e32 v199, 0x41000000, v196
	v_cmp_gt_f32_e32 vcc, v194, v199
	v_max_f32_e32 v199, v196, v196
	v_max_f32_e32 v199, v199, v194
	v_sub_f32_e32 v194, v196, v199
	v_exp_f32_e32 v194, v194
	s_cmp_eq_u64 vcc, 0
	s_cselect_b64 s[4:5], -1, 0
	s_and_b64 vcc, exec, s[4:5]
	s_cbranch_vccnz .LBB0_2073
	v_pk_mul_f32 v[62:63], v[62:63], v[194:195] op_sel_hi:[1,0]
	v_pk_mul_f32 v[60:61], v[60:61], v[194:195] op_sel_hi:[1,0]
	v_pk_mul_f32 v[58:59], v[58:59], v[194:195] op_sel_hi:[1,0]
	v_pk_mul_f32 v[56:57], v[56:57], v[194:195] op_sel_hi:[1,0]
	v_pk_mul_f32 v[54:55], v[54:55], v[194:195] op_sel_hi:[1,0]
	v_pk_mul_f32 v[52:53], v[52:53], v[194:195] op_sel_hi:[1,0]
	v_pk_mul_f32 v[50:51], v[50:51], v[194:195] op_sel_hi:[1,0]
	v_pk_mul_f32 v[48:49], v[48:49], v[194:195] op_sel_hi:[1,0]
	v_pk_mul_f32 v[46:47], v[46:47], v[194:195] op_sel_hi:[1,0]
	v_pk_mul_f32 v[44:45], v[44:45], v[194:195] op_sel_hi:[1,0]
	v_pk_mul_f32 v[42:43], v[42:43], v[194:195] op_sel_hi:[1,0]
	v_pk_mul_f32 v[40:41], v[40:41], v[194:195] op_sel_hi:[1,0]
	v_pk_mul_f32 v[38:39], v[38:39], v[194:195] op_sel_hi:[1,0]
	v_pk_mul_f32 v[36:37], v[36:37], v[194:195] op_sel_hi:[1,0]
	v_pk_mul_f32 v[34:35], v[34:35], v[194:195] op_sel_hi:[1,0]
	v_pk_mul_f32 v[32:33], v[32:33], v[194:195] op_sel_hi:[1,0]
	v_pk_mul_f32 v[30:31], v[30:31], v[194:195] op_sel_hi:[1,0]
	v_pk_mul_f32 v[28:29], v[28:29], v[194:195] op_sel_hi:[1,0]
	v_pk_mul_f32 v[26:27], v[26:27], v[194:195] op_sel_hi:[1,0]
	v_pk_mul_f32 v[24:25], v[24:25], v[194:195] op_sel_hi:[1,0]
	v_pk_mul_f32 v[22:23], v[22:23], v[194:195] op_sel_hi:[1,0]
	v_pk_mul_f32 v[20:21], v[20:21], v[194:195] op_sel_hi:[1,0]
	v_pk_mul_f32 v[18:19], v[18:19], v[194:195] op_sel_hi:[1,0]
	v_pk_mul_f32 v[16:17], v[16:17], v[194:195] op_sel_hi:[1,0]
	v_pk_mul_f32 v[14:15], v[14:15], v[194:195] op_sel_hi:[1,0]
	v_pk_mul_f32 v[12:13], v[12:13], v[194:195] op_sel_hi:[1,0]
	v_pk_mul_f32 v[10:11], v[10:11], v[194:195] op_sel_hi:[1,0]
	v_pk_mul_f32 v[8:9], v[8:9], v[194:195] op_sel_hi:[1,0]
	v_pk_mul_f32 v[6:7], v[6:7], v[194:195] op_sel_hi:[1,0]
	v_pk_mul_f32 v[4:5], v[4:5], v[194:195] op_sel_hi:[1,0]
	v_pk_mul_f32 v[2:3], v[2:3], v[194:195] op_sel_hi:[1,0]
	v_pk_mul_f32 v[0:1], v[0:1], v[194:195] op_sel_hi:[1,0]
; #define MFMA(a, b, c) __builtin_amdgcn_mfma_f32_32x32x16_bf16((a), (b), (c), 0, 0, 0)
; #define ATT_LOADV(key0)                                                                                  \
;   do {                                                                                                   \
;     _Pragma("unroll") for (int i = 0; i < VCH; ++i) { int c = tid + NT * i; vr[i] = ld8(Vtp + (long)(c / VPR) * T + (key0) + (c % VPR) * 8); }  \
;   } while (0)
; template <int DK, int KT>
; DI void attn_item(const bfu* __restrict__ Qp, const bfu* __restrict__ Kp, const bfu* __restrict__ Vtp, int nkeys, bfu* __restrict__ Op, int ldo, char* smem) {
;     ...
;     float mn = m, alpha = 1.f;
;     const bool moved = __builtin_amdgcn_ballot_w64(mx > m + 8.f) != 0ull;
;     if (moved) { mn = fmaxf(m, mx); alpha = __builtin_amdgcn_exp2f(m - mn); m = mn; }
;     float rs = 0.f;
; #pragma unroll
;     for (int bk = 0; bk < NBK; ++bk)
; #pragma unroll
;       for (int r = 0; r < 16; ++r) { sv[bk][r] = __builtin_amdgcn_exp2f(sv[bk][r] - mn); rs += sv[bk][r]; }
;     lsum = lsum * alpha + rs;
;     if (moved) {
; #pragma unroll
;       for (int d = 0; d < 4; ++d)
; #pragma unroll
;         for (int r = 0; r < 16; ++r) o[d][r] *= alpha;
;     }
;     bf16x8 pf[2 * NBK];
; #pragma unroll
;     for (int bk = 0; bk < NBK; ++bk) { pf[2 * bk] = packacc(sv[bk], 0); pf[2 * bk + 1] = packacc(sv[bk], 1); }
;     if (j + 1 < NTL) ATT_LOADV((j + 1) * KT);
; #pragma unroll
;     for (int kk = 0; kk < 2 * NBK; ++kk)
; #pragma unroll
;       for (int d = 0; d < 4; ++d) o[d] = MFMA(ld44(Vs + (d * 32 + l32) * LV + kk * 16 + 4 * hi), pf[kk], o[d]);
.LBB0_2073:
	v_cndmask_b32_e64 v196, v199, v196, s[4:5]
	v_sub_f32_e32 v80, v80, v196
	v_exp_f32_e32 v80, v80
	v_sub_f32_e32 v81, v81, v196
	v_exp_f32_e32 v81, v81
	v_sub_f32_e32 v82, v82, v196
	v_exp_f32_e32 v82, v82
	v_sub_f32_e32 v83, v83, v196
	v_exp_f32_e32 v83, v83
	v_sub_f32_e32 v84, v84, v196
	v_add_f32_e32 v199, 0, v80
	v_exp_f32_e32 v84, v84
	v_sub_f32_e32 v85, v85, v196
	v_add_f32_e32 v199, v81, v199
	v_exp_f32_e32 v85, v85
	v_sub_f32_e32 v86, v86, v196
	v_add_f32_e32 v199, v82, v199
	v_exp_f32_e32 v86, v86
	v_sub_f32_e32 v87, v87, v196
	v_add_f32_e32 v199, v83, v199
	v_exp_f32_e32 v87, v87
	v_sub_f32_e32 v88, v88, v196
	v_add_f32_e32 v199, v84, v199
	v_exp_f32_e32 v88, v88
	v_sub_f32_e32 v89, v89, v196
	v_add_f32_e32 v199, v85, v199
	v_exp_f32_e32 v89, v89
	v_sub_f32_e32 v90, v90, v196
	v_add_f32_e32 v199, v86, v199
	v_exp_f32_e32 v90, v90
	v_sub_f32_e32 v91, v91, v196
	v_add_f32_e32 v199, v87, v199
	v_exp_f32_e32 v91, v91
	v_sub_f32_e32 v92, v92, v196
	v_add_f32_e32 v199, v88, v199
	v_exp_f32_e32 v200, v92
	v_add_f32_e32 v199, v89, v199
	v_add_f32_e32 v199, v90, v199
	v_add_f32_e32 v199, v91, v199
	v_sub_f32_e32 v93, v93, v196
	v_add_f32_e32 v92, v200, v199
	v_exp_f32_e32 v199, v93
	v_sub_f32_e32 v93, v94, v196
	v_exp_f32_e32 v205, v93
	v_sub_f32_e32 v93, v95, v196
	v_exp_f32_e32 v206, v93
	v_sub_f32_e32 v64, v64, v196
	v_exp_f32_e32 v64, v64
	v_sub_f32_e32 v65, v65, v196
	v_add_f32_e32 v92, v199, v92
	v_exp_f32_e32 v65, v65
	v_sub_f32_e32 v66, v66, v196
	v_add_f32_e32 v92, v205, v92
	v_exp_f32_e32 v66, v66
	v_sub_f32_e32 v67, v67, v196
	v_add_f32_e32 v92, v206, v92
	v_exp_f32_e32 v67, v67
	v_sub_f32_e32 v68, v68, v196
	v_add_f32_e32 v92, v64, v92
	v_exp_f32_e32 v68, v68
	v_sub_f32_e32 v69, v69, v196
	v_add_f32_e32 v92, v65, v92
	v_exp_f32_e32 v69, v69
	v_sub_f32_e32 v70, v70, v196
	v_add_f32_e32 v92, v66, v92
	v_exp_f32_e32 v70, v70
	v_sub_f32_e32 v71, v71, v196
	v_add_f32_e32 v92, v67, v92
	v_exp_f32_e32 v71, v71
	v_sub_f32_e32 v72, v72, v196
	v_add_f32_e32 v92, v68, v92
	v_exp_f32_e32 v72, v72
	v_sub_f32_e32 v73, v73, v196
	v_add_f32_e32 v92, v69, v92
	v_exp_f32_e32 v73, v73
	v_sub_f32_e32 v74, v74, v196
	v_add_f32_e32 v92, v70, v92
	v_exp_f32_e32 v74, v74
	v_sub_f32_e32 v75, v75, v196
	v_add_f32_e32 v92, v71, v92
	v_exp_f32_e32 v75, v75
	v_sub_f32_e32 v76, v76, v196
	v_add_f32_e32 v92, v72, v92
	v_exp_f32_e32 v76, v76
	v_sub_f32_e32 v77, v77, v196
	v_add_f32_e32 v92, v73, v92
	v_exp_f32_e32 v77, v77
	v_sub_f32_e32 v78, v78, v196
	v_add_f32_e32 v92, v74, v92
	v_exp_f32_e32 v78, v78
	v_sub_f32_e32 v79, v79, v196
	v_add_f32_e32 v92, v75, v92
	v_exp_f32_e32 v79, v79
	v_add_f32_e32 v92, v76, v92
	v_add_f32_e32 v92, v77, v92
	v_add_f32_e32 v92, v78, v92
	v_add_f32_e32 v201, v79, v92
	v_cndmask_b32_e64 v92, v194, 1.0, s[4:5]
	v_fmac_f32_e32 v201, v198, v92
	v_cvt_pk_bf16_f32 v92, v80, v81
	v_cvt_pk_bf16_f32 v93, v82, v83
	v_cvt_pk_bf16_f32 v94, v84, v85
	v_cvt_pk_bf16_f32 v95, v86, v87
	v_cvt_pk_bf16_f32 v84, v64, v65
	v_cvt_pk_bf16_f32 v86, v68, v69
	v_cvt_pk_bf16_f32 v80, v72, v73
	v_cvt_pk_bf16_f32 v82, v76, v77
	v_lshl_add_u64 v[64:65], s[0:1], 0, v[176:177]
	v_lshl_add_u64 v[68:69], s[0:1], 0, v[174:175]
	v_lshl_add_u64 v[72:73], s[0:1], 0, v[172:173]
	v_lshl_add_u64 v[76:77], s[0:1], 0, v[170:171]
	v_add_u32_e32 v194, 0x6000, v234
	v_cvt_pk_bf16_f32 v85, v66, v67
	v_cvt_pk_bf16_f32 v87, v70, v71
	v_cvt_pk_bf16_f32 v81, v74, v75
	v_cvt_pk_bf16_f32 v83, v78, v79
	global_load_dwordx4 v[64:67], v[64:65], off
	v_cvt_pk_bf16_f32 v88, v88, v89
	global_load_dwordx4 v[68:71], v[68:69], off
	v_cvt_pk_bf16_f32 v89, v90, v91
	global_load_dwordx4 v[72:75], v[72:73], off
	v_cvt_pk_bf16_f32 v90, v200, v199
	global_load_dwordx4 v[76:79], v[76:77], off
	ds_read2_b64 v[236:239], v194 offset0:128 offset1:130
	ds_read2_b64 v[240:243], v194 offset0:132 offset1:134
	v_add_u32_e32 v199, 0x7000, v234
	s_waitcnt lgkmcnt(0)
	v_mfma_f32_32x32x16_bf16 v[48:63], v[236:239], v[92:95], v[48:63]
	ds_read2_b64 v[236:239], v199 offset0:192 offset1:194
	v_add_u32_e32 v198, 0x8800, v234
	v_add_u32_e32 v200, 0x9800, v234
	v_cvt_pk_bf16_f32 v91, v205, v206
	s_add_i32 s9, s9, -1
	v_lshl_add_u64 v[170:171], v[170:171], 0, s[48:49]
	v_lshl_add_u64 v[172:173], v[172:173], 0, s[48:49]
	s_waitcnt lgkmcnt(0)
	v_mfma_f32_32x32x16_bf16 v[32:47], v[236:239], v[92:95], v[32:47]
	ds_read2_b64 v[236:239], v198 offset1:2
	v_lshl_add_u64 v[174:175], v[174:175], 0, s[48:49]
	v_lshl_add_u64 v[176:177], v[176:177], 0, s[48:49]
	v_lshl_add_u64 v[178:179], v[178:179], 0, s[80:81]
	v_lshl_add_u64 v[180:181], v[180:181], 0, s[80:81]
	v_lshl_add_u64 v[182:183], v[182:183], 0, s[80:81]
	v_lshl_add_u64 v[188:189], v[188:189], 0, s[80:81]
	s_waitcnt lgkmcnt(0)
	v_mfma_f32_32x32x16_bf16 v[16:31], v[236:239], v[92:95], v[16:31]
	ds_read2_b64 v[236:239], v200 offset0:64 offset1:66
	v_lshl_add_u64 v[190:191], v[190:191], 0, s[80:81]
	v_lshl_add_u64 v[192:193], v[192:193], 0, s[80:81]
	s_cmp_eq_u32 s9, 0
	s_waitcnt lgkmcnt(0)
	v_mfma_f32_32x32x16_bf16 v[0:15], v[236:239], v[92:95], v[0:15]
	ds_read2_b64 v[92:95], v199 offset0:196 offset1:198
	s_waitcnt lgkmcnt(0)
	v_mfma_f32_32x32x16_bf16 v[32:47], v[92:95], v[88:91], v[32:47]
	ds_read2_b64 v[92:95], v198 offset0:4 offset1:6
	s_waitcnt lgkmcnt(0)
	v_mfma_f32_32x32x16_bf16 v[16:31], v[92:95], v[88:91], v[16:31]
	ds_read2_b64 v[92:95], v200 offset0:68 offset1:70
	v_mfma_f32_32x32x16_bf16 v[48:63], v[240:243], v[88:91], v[48:63]
	s_waitcnt lgkmcnt(0)
	v_mfma_f32_32x32x16_bf16 v[0:15], v[92:95], v[88:91], v[0:15]
	ds_read2_b64 v[88:91], v194 offset0:136 offset1:138
	s_waitcnt lgkmcnt(0)
	v_mfma_f32_32x32x16_bf16 v[48:63], v[88:91], v[84:87], v[48:63]
	ds_read2_b64 v[88:91], v199 offset0:200 offset1:202
	s_waitcnt lgkmcnt(0)
	v_mfma_f32_32x32x16_bf16 v[32:47], v[88:91], v[84:87], v[32:47]
	ds_read2_b64 v[88:91], v198 offset0:8 offset1:10
	s_waitcnt lgkmcnt(0)
	v_mfma_f32_32x32x16_bf16 v[16:31], v[88:91], v[84:87], v[16:31]
	ds_read2_b64 v[88:91], v200 offset0:72 offset1:74
	s_waitcnt lgkmcnt(0)
	v_mfma_f32_32x32x16_bf16 v[0:15], v[88:91], v[84:87], v[0:15]
	ds_read2_b64 v[84:87], v194 offset0:140 offset1:142
	s_waitcnt lgkmcnt(0)
	v_mfma_f32_32x32x16_bf16 v[48:63], v[84:87], v[80:83], v[48:63]
	ds_read2_b64 v[84:87], v199 offset0:204 offset1:206
	s_waitcnt lgkmcnt(0)
	v_mfma_f32_32x32x16_bf16 v[32:47], v[84:87], v[80:83], v[32:47]
	ds_read2_b64 v[84:87], v198 offset0:12 offset1:14
	s_waitcnt lgkmcnt(0)
	v_mfma_f32_32x32x16_bf16 v[16:31], v[84:87], v[80:83], v[16:31]
	ds_read2_b64 v[84:87], v200 offset0:76 offset1:78
	s_waitcnt lgkmcnt(0)
	v_mfma_f32_32x32x16_bf16 v[0:15], v[84:87], v[80:83], v[0:15]
	s_cbranch_scc1 .LBB0_2075
	v_mov_b32_e32 v198, v201
	s_branch .LBB0_2071

; #define MFMA(a, b, c) __builtin_amdgcn_mfma_f32_32x32x16_bf16((a), (b), (c), 0, 0, 0)
; #define ATT_LOADV(key0)                                                                                  \
;   do {                                                                                                   \
;     _Pragma("unroll") for (int i = 0; i < VCH; ++i) { int c = tid + NT * i; vr[i] = ld8(Vtp + (long)(c / VPR) * T + (key0) + (c % VPR) * 8); }  \
;   } while (0)
; template <int DK, int KT>
; DI void attn_item(const bfu* __restrict__ Qp, const bfu* __restrict__ Kp, const bfu* __restrict__ Vtp, int nkeys, bfu* __restrict__ Op, int ldo, char* smem) {
;     ...
;     float rs = 0.f;
; #pragma unroll
;     for (int bk = 0; bk < NBK; ++bk)
; #pragma unroll
;       for (int r = 0; r < 16; ++r) { sv[bk][r] = __builtin_amdgcn_exp2f(sv[bk][r] - mn); rs += sv[bk][r]; }
;     lsum = lsum * alpha + rs;
;     if (moved) {
; #pragma unroll
;       for (int d = 0; d < 4; ++d)
; #pragma unroll
;         for (int r = 0; r < 16; ++r) o[d][r] *= alpha;
;     }
;     bf16x8 pf[2 * NBK];
; #pragma unroll
;     for (int bk = 0; bk < NBK; ++bk) { pf[2 * bk] = packacc(sv[bk], 0); pf[2 * bk + 1] = packacc(sv[bk], 1); }
;     if (j + 1 < NTL) ATT_LOADV((j + 1) * KT);
; #pragma unroll
;     for (int kk = 0; kk < 2 * NBK; ++kk)
; #pragma unroll
;       for (int d = 0; d < 4; ++d) o[d] = MFMA(ld44(Vs + (d * 32 + l32) * LV + kk * 16 + 4 * hi), pf[kk], o[d]);
.LBB0_2078:
	v_sub_f32_e32 v64, v64, v196
	v_exp_f32_e32 v109, v64
	v_sub_f32_e32 v64, v65, v196
	v_exp_f32_e32 v110, v64
	v_sub_f32_e32 v65, v66, v196
	v_exp_f32_e32 v111, v65
	v_sub_f32_e32 v65, v67, v196
	v_sub_f32_e32 v66, v68, v196
	v_exp_f32_e32 v112, v65
	v_exp_f32_e32 v68, v66
	v_sub_f32_e32 v66, v69, v196
	v_cvt_pk_bf16_f32 v64, v109, v110
	v_exp_f32_e32 v69, v66
	v_add_f32_e32 v109, 0, v109
	v_sub_f32_e32 v67, v70, v196
	v_add_f32_e32 v109, v110, v109
	v_exp_f32_e32 v70, v67
	v_sub_f32_e32 v67, v71, v196
	v_add_f32_e32 v109, v111, v109
	v_sub_f32_e32 v72, v72, v196
	v_exp_f32_e32 v71, v67
	v_add_f32_e32 v109, v112, v109
	v_exp_f32_e32 v105, v72
	v_sub_f32_e32 v72, v73, v196
	v_cvt_pk_bf16_f32 v66, v68, v69
	v_add_f32_e32 v68, v68, v109
	v_exp_f32_e32 v106, v72
	v_sub_f32_e32 v73, v74, v196
	v_add_f32_e32 v68, v69, v68
	v_exp_f32_e32 v107, v73
	v_sub_f32_e32 v73, v75, v196
	v_add_f32_e32 v68, v70, v68
	v_exp_f32_e32 v108, v73
	v_sub_f32_e32 v74, v76, v196
	v_add_f32_e32 v68, v71, v68
	v_exp_f32_e32 v76, v74
	v_sub_f32_e32 v74, v77, v196
	v_add_f32_e32 v68, v105, v68
	v_exp_f32_e32 v77, v74
	v_sub_f32_e32 v75, v78, v196
	v_add_f32_e32 v68, v106, v68
	v_exp_f32_e32 v78, v75
	v_sub_f32_e32 v75, v79, v196
	v_add_f32_e32 v68, v107, v68
	v_sub_f32_e32 v80, v80, v196
	v_exp_f32_e32 v79, v75
	v_add_f32_e32 v68, v108, v68
	v_exp_f32_e32 v101, v80
	v_sub_f32_e32 v80, v81, v196
	v_add_f32_e32 v68, v76, v68
	v_exp_f32_e32 v102, v80
	v_sub_f32_e32 v81, v82, v196
	v_add_f32_e32 v68, v77, v68
	v_exp_f32_e32 v103, v81
	v_sub_f32_e32 v81, v83, v196
	v_add_f32_e32 v68, v78, v68
	v_exp_f32_e32 v104, v81
	v_sub_f32_e32 v82, v84, v196
	v_add_f32_e32 v68, v79, v68
	v_exp_f32_e32 v84, v82
	v_sub_f32_e32 v82, v85, v196
	v_add_f32_e32 v68, v101, v68
	v_exp_f32_e32 v85, v82
	v_sub_f32_e32 v83, v86, v196
	v_add_f32_e32 v68, v102, v68
	v_exp_f32_e32 v86, v83
	v_sub_f32_e32 v83, v87, v196
	v_add_f32_e32 v68, v103, v68
	v_exp_f32_e32 v87, v83
	v_add_f32_e32 v68, v104, v68
	v_add_f32_e32 v68, v84, v68
	v_add_f32_e32 v68, v85, v68
	v_add_f32_e32 v68, v86, v68
	v_cvt_pk_bf16_f32 v82, v84, v85
	v_cvt_pk_bf16_f32 v83, v86, v87
	v_cvt_pk_bf16_f32 v74, v76, v77
	v_cvt_pk_bf16_f32 v75, v78, v79
	v_add_f32_e32 v68, v87, v68
	ds_read2_b64 v[76:79], v194 offset0:128 offset1:130
	ds_read2_b64 v[84:87], v194 offset0:132 offset1:134
	v_cvt_pk_bf16_f32 v65, v111, v112
	v_cvt_pk_bf16_f32 v67, v70, v71
	v_cvt_pk_bf16_f32 v72, v105, v106
	v_cvt_pk_bf16_f32 v73, v107, v108
	s_waitcnt lgkmcnt(1)
	v_mfma_f32_32x32x16_bf16 v[48:63], v[76:79], v[64:67], v[48:63]
	ds_read2_b64 v[76:79], v199 offset0:192 offset1:194
	v_cvt_pk_bf16_f32 v80, v101, v102
	v_cvt_pk_bf16_f32 v81, v103, v104
	v_sub_f32_e32 v88, v88, v196
	v_exp_f32_e32 v97, v88
	v_sub_f32_e32 v88, v89, v196
	v_sub_f32_e32 v89, v90, v196
	s_waitcnt lgkmcnt(0)
	v_mfma_f32_32x32x16_bf16 v[32:47], v[76:79], v[64:67], v[32:47]
	ds_read2_b64 v[76:79], v198 offset1:2
	v_exp_f32_e32 v99, v89
	v_sub_f32_e32 v89, v91, v196
	v_sub_f32_e32 v90, v92, v196
	v_sub_f32_e32 v91, v94, v196
	v_exp_f32_e32 v92, v90
	v_sub_f32_e32 v90, v93, v196
	s_waitcnt lgkmcnt(0)
	v_mfma_f32_32x32x16_bf16 v[16:31], v[76:79], v[64:67], v[16:31]
	ds_read2_b64 v[76:79], v200 offset0:64 offset1:66
	v_exp_f32_e32 v94, v91
	v_sub_f32_e32 v91, v95, v196
	v_exp_f32_e32 v98, v88
	v_exp_f32_e32 v100, v89
	v_exp_f32_e32 v93, v90
	v_exp_f32_e32 v95, v91
	s_waitcnt lgkmcnt(0)
	v_mfma_f32_32x32x16_bf16 v[0:15], v[76:79], v[64:67], v[0:15]
	ds_read2_b64 v[64:67], v199 offset0:196 offset1:198
	v_cvt_pk_bf16_f32 v88, v97, v98
	v_cvt_pk_bf16_f32 v89, v99, v100
	v_cvt_pk_bf16_f32 v90, v92, v93
	v_cvt_pk_bf16_f32 v91, v94, v95
	v_add_f32_e32 v68, v97, v68
	v_add_f32_e32 v68, v98, v68
	s_waitcnt lgkmcnt(0)
	v_mfma_f32_32x32x16_bf16 v[32:47], v[64:67], v[72:75], v[32:47]
	ds_read2_b64 v[64:67], v198 offset0:4 offset1:6
	v_add_f32_e32 v68, v99, v68
	v_add_f32_e32 v68, v100, v68
	v_add_f32_e32 v68, v92, v68
	v_add_f32_e32 v68, v93, v68
	v_add_f32_e32 v68, v94, v68
	v_add_f32_e32 v68, v95, v68
	s_waitcnt lgkmcnt(0)
	v_mfma_f32_32x32x16_bf16 v[16:31], v[64:67], v[72:75], v[16:31]
	ds_read2_b64 v[64:67], v200 offset0:68 offset1:70
	v_fmac_f32_e32 v68, v201, v96
	s_mul_hi_i32 s5, s8, 0x900
	s_mulk_i32 s8, 0x900
	s_add_u32 s4, s8, s7
	s_addc_u32 s5, s5, 0
	s_lshl_b64 s[4:5], s[4:5], 12
	s_waitcnt lgkmcnt(0)
	v_mfma_f32_32x32x16_bf16 v[0:15], v[64:67], v[72:75], v[0:15]
	ds_read2_b64 v[64:67], v194 offset0:136 offset1:138
	s_add_u32 s4, s16, s4
	s_addc_u32 s5, s17, s5
	s_lshl_b32 s6, s6, 8
	s_add_u32 s4, s4, s6
	s_addc_u32 s5, s5, 0
	v_mfma_f32_32x32x16_bf16 v[48:63], v[84:87], v[72:75], v[48:63]
	s_waitcnt lgkmcnt(0)
	v_mfma_f32_32x32x16_bf16 v[48:63], v[64:67], v[80:83], v[48:63]
	ds_read2_b64 v[64:67], v199 offset0:200 offset1:202
	s_waitcnt lgkmcnt(0)
	v_mfma_f32_32x32x16_bf16 v[32:47], v[64:67], v[80:83], v[32:47]
	ds_read2_b64 v[64:67], v198 offset0:8 offset1:10
	s_waitcnt lgkmcnt(0)
	v_mfma_f32_32x32x16_bf16 v[16:31], v[64:67], v[80:83], v[16:31]
	ds_read2_b64 v[64:67], v200 offset0:72 offset1:74
	s_waitcnt lgkmcnt(0)
	v_mfma_f32_32x32x16_bf16 v[0:15], v[64:67], v[80:83], v[0:15]
	ds_read2_b64 v[64:67], v194 offset0:140 offset1:142
	s_waitcnt lgkmcnt(0)
; #define MFMA(a, b, c) __builtin_amdgcn_mfma_f32_32x32x16_bf16((a), (b), (c), 0, 0, 0)
; DI unsigned cvtpk(float lo, float hi) { f32x2_t v = {lo, hi}; bf16x2_t b = __builtin_convertvector(v, bf16x2_t); return __builtin_bit_cast(unsigned, b); }
; template <int DK, int KT>
; DI void attn_item(const bfu* __restrict__ Qp, const bfu* __restrict__ Kp, const bfu* __restrict__ Vtp, int nkeys, bfu* __restrict__ Op, int ldo, char* smem) {
;     ...
;       for (int d = 0; d < 4; ++d) o[d] = MFMA(ld44(Vs + (d * 32 + l32) * LV + kk * 16 + 4 * hi), pf[kk], o[d]);
;   }
;     ...
;   const float inv = 1.f / (lsum + __shfl_xor(lsum, 32));
;   bfu* orow = Op + (long)(w * 32 + l32) * ldo;
; #pragma unroll
;   for (int d = 0; d < 4; ++d)
; #pragma unroll
;     for (int rg = 0; rg < 4; ++rg) {
;       u32x2 v = {cvtpk(o[d][4 * rg] * inv, o[d][4 * rg + 1] * inv), cvtpk(o[d][4 * rg + 2] * inv, o[d][4 * rg + 3] * inv)};
;       *reinterpret_cast<u32x2*>(orow + d * 32 + 8 * rg + 4 * hi) = v;
;     }
	v_mfma_f32_32x32x16_bf16 v[48:63], v[64:67], v[88:91], v[48:63]
	ds_read2_b64 v[64:67], v199 offset0:204 offset1:206
	s_waitcnt lgkmcnt(0)
	v_mfma_f32_32x32x16_bf16 v[32:47], v[64:67], v[88:91], v[32:47]
	ds_read2_b64 v[64:67], v198 offset0:12 offset1:14
	s_waitcnt lgkmcnt(0)
	v_mfma_f32_32x32x16_bf16 v[16:31], v[64:67], v[88:91], v[16:31]
	ds_read2_b64 v[64:67], v200 offset0:76 offset1:78
	s_waitcnt lgkmcnt(0)
	v_mfma_f32_32x32x16_bf16 v[0:15], v[64:67], v[88:91], v[0:15]
	ds_bpermute_b32 v64, v195, v68
	s_waitcnt lgkmcnt(0)
	v_add_f32_e32 v64, v68, v64
	v_div_scale_f32 v65, s[6:7], v64, v64, 1.0
	v_rcp_f32_e32 v66, v65
	s_nop 0
	v_fma_f32 v67, -v65, v66, 1.0
	v_fmac_f32_e32 v66, v67, v66
	v_div_scale_f32 v67, vcc, 1.0, v64, 1.0
	v_mul_f32_e32 v68, v67, v66
	v_fma_f32 v69, -v65, v68, v67
	v_fmac_f32_e32 v68, v69, v66
	v_fma_f32 v65, -v65, v68, v67
	v_div_fmas_f32 v65, v65, v66, v68
	v_div_fixup_f32 v64, v65, v64, 1.0
	v_lshlrev_b64 v[66:67], 12, v[168:169]
	v_lshl_add_u64 v[66:67], s[4:5], 0, v[66:67]
	v_pk_mul_f32 v[48:49], v[48:49], v[64:65] op_sel_hi:[1,0]
	v_pk_mul_f32 v[50:51], v[50:51], v[64:65] op_sel_hi:[1,0]
	v_pk_mul_f32 v[32:33], v[32:33], v[64:65] op_sel_hi:[1,0]
	v_pk_mul_f32 v[34:35], v[34:35], v[64:65] op_sel_hi:[1,0]
	v_pk_mul_f32 v[16:17], v[16:17], v[64:65] op_sel_hi:[1,0]
	v_pk_mul_f32 v[18:19], v[18:19], v[64:65] op_sel_hi:[1,0]
	v_pk_mul_f32 v[0:1], v[0:1], v[64:65] op_sel_hi:[1,0]
	v_pk_mul_f32 v[2:3], v[2:3], v[64:65] op_sel_hi:[1,0]
	v_lshl_add_u64 v[66:67], v[66:67], 0, v[184:185]
	v_cvt_pk_bf16_f32 v48, v48, v49
	v_cvt_pk_bf16_f32 v49, v50, v51
	v_cvt_pk_bf16_f32 v32, v32, v33
	v_cvt_pk_bf16_f32 v33, v34, v35
	v_cvt_pk_bf16_f32 v16, v16, v17
	v_cvt_pk_bf16_f32 v17, v18, v19
	v_cvt_pk_bf16_f32 v0, v0, v1
	v_cvt_pk_bf16_f32 v1, v2, v3
	global_store_dwordx2 v[66:67], v[48:49], off
	v_pk_mul_f32 v[48:49], v[52:53], v[64:65] op_sel_hi:[1,0]
	v_pk_mul_f32 v[50:51], v[54:55], v[64:65] op_sel_hi:[1,0]
	global_store_dwordx2 v[66:67], v[32:33], off offset:64
	v_pk_mul_f32 v[32:33], v[36:37], v[64:65] op_sel_hi:[1,0]
	v_pk_mul_f32 v[34:35], v[38:39], v[64:65] op_sel_hi:[1,0]
	global_store_dwordx2 v[66:67], v[16:17], off offset:128
	v_pk_mul_f32 v[16:17], v[20:21], v[64:65] op_sel_hi:[1,0]
	v_pk_mul_f32 v[18:19], v[22:23], v[64:65] op_sel_hi:[1,0]
	global_store_dwordx2 v[66:67], v[0:1], off offset:192
	v_pk_mul_f32 v[0:1], v[4:5], v[64:65] op_sel_hi:[1,0]
	v_pk_mul_f32 v[2:3], v[6:7], v[64:65] op_sel_hi:[1,0]
	v_cvt_pk_bf16_f32 v48, v48, v49
	v_cvt_pk_bf16_f32 v49, v50, v51
	v_cvt_pk_bf16_f32 v32, v32, v33
	v_cvt_pk_bf16_f32 v33, v34, v35
	v_cvt_pk_bf16_f32 v16, v16, v17
	v_cvt_pk_bf16_f32 v17, v18, v19
	v_cvt_pk_bf16_f32 v0, v0, v1
	v_cvt_pk_bf16_f32 v1, v2, v3
	global_store_dwordx2 v[66:67], v[48:49], off offset:16
	v_pk_mul_f32 v[48:49], v[56:57], v[64:65] op_sel_hi:[1,0]
	v_pk_mul_f32 v[50:51], v[58:59], v[64:65] op_sel_hi:[1,0]
	global_store_dwordx2 v[66:67], v[32:33], off offset:80
	v_pk_mul_f32 v[32:33], v[40:41], v[64:65] op_sel_hi:[1,0]
	v_pk_mul_f32 v[34:35], v[42:43], v[64:65] op_sel_hi:[1,0]
	global_store_dwordx2 v[66:67], v[16:17], off offset:144
	v_pk_mul_f32 v[16:17], v[24:25], v[64:65] op_sel_hi:[1,0]
	v_pk_mul_f32 v[18:19], v[26:27], v[64:65] op_sel_hi:[1,0]
	global_store_dwordx2 v[66:67], v[0:1], off offset:208
	v_pk_mul_f32 v[0:1], v[8:9], v[64:65] op_sel_hi:[1,0]
	v_pk_mul_f32 v[2:3], v[10:11], v[64:65] op_sel_hi:[1,0]
	v_cvt_pk_bf16_f32 v48, v48, v49
	v_cvt_pk_bf16_f32 v49, v50, v51
	v_cvt_pk_bf16_f32 v32, v32, v33
	v_cvt_pk_bf16_f32 v33, v34, v35
	v_cvt_pk_bf16_f32 v16, v16, v17
	v_cvt_pk_bf16_f32 v17, v18, v19
	v_cvt_pk_bf16_f32 v0, v0, v1
	v_cvt_pk_bf16_f32 v1, v2, v3
	global_store_dwordx2 v[66:67], v[48:49], off offset:32
	v_pk_mul_f32 v[48:49], v[60:61], v[64:65] op_sel_hi:[1,0]
	v_pk_mul_f32 v[50:51], v[62:63], v[64:65] op_sel_hi:[1,0]
	global_store_dwordx2 v[66:67], v[32:33], off offset:96
	v_pk_mul_f32 v[32:33], v[44:45], v[64:65] op_sel_hi:[1,0]
	v_pk_mul_f32 v[34:35], v[46:47], v[64:65] op_sel_hi:[1,0]
	global_store_dwordx2 v[66:67], v[16:17], off offset:160
	v_pk_mul_f32 v[16:17], v[28:29], v[64:65] op_sel_hi:[1,0]
	v_pk_mul_f32 v[18:19], v[30:31], v[64:65] op_sel_hi:[1,0]
	global_store_dwordx2 v[66:67], v[0:1], off offset:224
	v_pk_mul_f32 v[0:1], v[12:13], v[64:65] op_sel_hi:[1,0]
	v_pk_mul_f32 v[2:3], v[14:15], v[64:65] op_sel_hi:[1,0]
	v_cvt_pk_bf16_f32 v48, v48, v49
	v_cvt_pk_bf16_f32 v49, v50, v51
	v_cvt_pk_bf16_f32 v32, v32, v33
	v_cvt_pk_bf16_f32 v33, v34, v35
	v_cvt_pk_bf16_f32 v16, v16, v17
	v_cvt_pk_bf16_f32 v17, v18, v19
	v_cvt_pk_bf16_f32 v0, v0, v1
	v_cvt_pk_bf16_f32 v1, v2, v3
	global_store_dwordx2 v[66:67], v[48:49], off offset:48
	global_store_dwordx2 v[66:67], v[32:33], off offset:112
	global_store_dwordx2 v[66:67], v[16:17], off offset:176
	global_store_dwordx2 v[66:67], v[0:1], off offset:240
	s_waitcnt lgkmcnt(0)
	s_barrier
	s_and_saveexec_b64 s[4:5], s[2:3]
	s_cbranch_execz .LBB0_2069
	s_mov_b64 s[8:9], exec
	v_mbcnt_lo_u32_b32 v0, s8, 0
	v_mbcnt_hi_u32_b32 v0, s9, v0
	v_cmp_eq_u32_e32 vcc, 0, v0
	s_and_saveexec_b64 s[6:7], vcc
	s_cbranch_execz .LBB0_2068
	s_bcnt1_i32_b64 s8, s[8:9]
	v_mov_b32_e32 v1, s8
	v_readlane_b32 s8, v254, 27
	v_readlane_b32 s9, v254, 28
	s_nop 4
	global_atomic_add v1, v185, v1, s[8:9] offset:768 sc0
	s_branch .LBB0_2068

;   DI const float* x() const { return (const float*)sp[0]; }
;   DI const float* c() const { return (const float*)sp[1]; }
; __device__ __forceinline__ unsigned xb_ld(unsigned* p)              { return __hip_atomic_load(p, __ATOMIC_RELAXED, __HIP_MEMORY_SCOPE_AGENT); }
; __device__ __forceinline__ void xcd_barrier_complete(unsigned* bar, unsigned x, unsigned& nloc, unsigned& nx) {
;     const unsigned G = gridDim.x * gridDim.y * gridDim.z;
;     unsigned sum, cnt, mine, sp = 0u;
;     for (;;) {
;         sum = 0u; cnt = 0u; mine = 0u;
; #pragma unroll
;         for (unsigned j = 0; j < 16; ++j) { const unsigned c = xb_ld(&bar[XB_XCNT(j)]); sum += c; cnt += (c > 0u) ? 1u : 0u; mine = (j == x) ? c : mine; }
;         if (sum == G) break;
;         __builtin_amdgcn_s_sleep(1);
;         if ((++sp & 255u) == 0u) { if (xb_ld(&bar[XB_TMO])) break; if (sp > XB_SPIN_CAP) { atomicAdd(&bar[XB_TMO], 1u); break; } }
;     }
;     nloc = mine > 0u ? mine : 1u; nx = cnt > 0u ? cnt : 1u;
; }
.LBB0_2087:
	s_waitcnt lgkmcnt(0)
	v_mov_b64_e32 v[0:1], s[2:3]
	v_mov_b64_e32 v[2:3], s[4:5]
	global_load_dword v0, v[0:1], off sc1
	v_readlane_b32 s40, v254, 15
	global_load_dword v1, v[2:3], off sc1
	v_mov_b64_e32 v[2:3], s[6:7]
	global_load_dword v2, v[2:3], off sc1
	s_or_b64 s[90:91], s[90:91], exec
	s_or_b64 s[70:71], s[70:71], exec
	s_waitcnt vmcnt(0) lgkmcnt(0)
	v_add_u32_e32 v4, v1, v0
	v_add_u32_e32 v6, v4, v2
	v_mov_b64_e32 v[4:5], s[8:9]
	global_load_dword v3, v[4:5], off sc1
	v_mov_b64_e32 v[4:5], s[10:11]
	global_load_dword v4, v[4:5], off sc1
	s_waitcnt vmcnt(0) lgkmcnt(0)
	v_add_u32_e32 v6, v6, v3
	v_add_u32_e32 v8, v6, v4
	v_mov_b64_e32 v[6:7], s[12:13]
	global_load_dword v5, v[6:7], off sc1
	v_mov_b64_e32 v[6:7], s[14:15]
	global_load_dword v6, v[6:7], off sc1
	s_waitcnt vmcnt(0) lgkmcnt(0)
	v_add_u32_e32 v8, v8, v5
	v_add_u32_e32 v10, v8, v6
	v_mov_b64_e32 v[8:9], s[16:17]
	global_load_dword v7, v[8:9], off sc1
	v_mov_b64_e32 v[8:9], s[18:19]
	global_load_dword v8, v[8:9], off sc1
	s_waitcnt vmcnt(0) lgkmcnt(0)
	v_add_u32_e32 v10, v10, v7
	v_add_u32_e32 v12, v10, v8
	v_mov_b64_e32 v[10:11], s[20:21]
	global_load_dword v9, v[10:11], off sc1
	v_mov_b64_e32 v[10:11], s[22:23]
	global_load_dword v10, v[10:11], off sc1
	s_waitcnt vmcnt(0) lgkmcnt(0)
	v_add_u32_e32 v12, v12, v9
	v_add_u32_e32 v14, v12, v10
	v_mov_b64_e32 v[12:13], s[24:25]
	global_load_dword v11, v[12:13], off sc1
	v_mov_b64_e32 v[12:13], s[26:27]
	global_load_dword v12, v[12:13], off sc1
	s_waitcnt vmcnt(0) lgkmcnt(0)
	v_add_u32_e32 v14, v14, v11
	v_add_u32_e32 v16, v14, v12
	v_mov_b64_e32 v[14:15], s[28:29]
	global_load_dword v13, v[14:15], off sc1
	v_mov_b64_e32 v[14:15], s[36:37]
	global_load_dword v14, v[14:15], off sc1
	s_waitcnt vmcnt(0) lgkmcnt(0)
	v_add_u32_e32 v16, v16, v13
	v_add_u32_e32 v18, v16, v14
	v_mov_b64_e32 v[16:17], s[38:39]
	global_load_dword v15, v[16:17], off sc1
	s_waitcnt vmcnt(0) lgkmcnt(0)
	v_add_u32_e32 v16, v18, v15
	v_cmp_ne_u32_e32 vcc, s40, v16
	s_and_saveexec_b64 s[92:93], vcc
	s_cbranch_execz .LBB0_2086
	s_and_b32 s40, s96, 0xff
	s_mov_b64 s[94:95], -1
	s_cmp_eq_u32 s40, 0
	s_mov_b64 s[40:41], -1
	s_mov_b64 s[46:47], -1
	s_sleep 1
	s_cbranch_scc1 .LBB0_2090
	s_and_saveexec_b64 s[62:63], s[40:41]
	s_cbranch_execz .LBB0_2085
	s_branch .LBB0_2093
.LBB0_2090:
	v_mov_b64_e32 v[16:17], s[0:1]
	global_load_dword v16, v[16:17], off sc1
	s_mov_b64 s[40:41], 0
	s_waitcnt vmcnt(0) lgkmcnt(0)
	v_cmp_eq_u32_e32 vcc, 0, v16
	s_and_saveexec_b64 s[62:63], vcc
	s_cmp_lt_u32 s96, 0x40001
	s_cselect_b64 s[40:41], -1, 0
	s_xor_b64 s[46:47], exec, -1
	s_and_b64 s[40:41], s[40:41], exec
	s_or_b64 exec, exec, s[62:63]
	s_and_saveexec_b64 s[62:63], s[40:41]
	s_cbranch_execz .LBB0_2085

;   DI const float* x() const { return (const float*)sp[0]; }
;   DI const float* ret_g() const { return (const float*)sp[16]; }
; DI int TID() { int t = threadIdx.x; asm volatile("" : "+v"(t)); return t; }
; DI char* OPQ(const void* ptr) { unsigned long long v = (unsigned long long)ptr; asm volatile("" : "+s"(v)); return (char*)v; }
; DI void phase_comb1(const Params& p) {
;   char* G = OPQ(p.ws + WS_G);
;   const int tid = TID(), c0 = tid * 8;
;   const bfu* Oa = (const bfu*)(G + L1_OA); const bfu* R = (const bfu*)(G + L1_R); const bfu* gate = (const bfu*)(G + L1_GATE); bfu* mix = (bfu*)(G + L1_MIX);
;   float gr[8];
;   for (int j = 0; j < 8; ++j) gr[j] = p.ret_g()[c0 + j];
;   for (int i = blockIdx.x; i < MG; i += gridDim.x) {
.LBB0_2126:
	s_or_b64 exec, exec, s[30:31]
	v_readlane_b32 s2, v254, 36
	v_readlane_b32 s0, v254, 16
	v_readlane_b32 s3, v254, 37
	v_readlane_b32 s1, v254, 17
	v_mov_b32_e32 v0, v202
	s_and_b64 vcc, exec, s[2:3]
	s_waitcnt lgkmcnt(0)
	s_barrier
	s_cbranch_vccz .LBB0_2131
	v_mov_b32_e32 v1, 0x12280
	ds_read_b64 v[2:3], v1
	v_lshlrev_b32_e32 v8, 3, v0
	v_ashrrev_i32_e32 v9, 31, v8
	s_add_u32 s2, s0, 0xc600000
	s_addc_u32 s3, s1, 0
	s_waitcnt lgkmcnt(0)
	v_lshl_add_u64 v[4:5], v[8:9], 2, v[2:3]
	global_load_dwordx4 v[0:3], v[4:5], off
	s_nop 0
	global_load_dwordx4 v[4:7], v[4:5], off offset:16
	v_lshlrev_b64 v[36:37], 1, v[8:9]
	s_add_u32 s8, s0, 0x4800000
	v_lshl_add_u64 v[8:9], s[0:1], 0, v[36:37]
	s_mov_b64 s[4:5], 0xb400000
	s_addc_u32 s9, s1, 0
	v_lshl_add_u64 v[38:39], s[2:3], 0, v[36:37]
	v_lshl_add_u64 v[40:41], v[8:9], 0, s[4:5]
	v_readlane_b32 s4, v254, 0
	s_branch .LBB0_2129

;   DI const float* x() const { return (const float*)sp[0]; }
; DI void unpack8(bf16x8 v, float* f) { u32x4 w = __builtin_bit_cast(u32x4, v); for (int i = 0; i < 4; ++i) { f[2 * i] = bflo(w[i]); f[2 * i + 1] = bfhi(w[i]); } }
; DI float silu(float v) { return v / (1.f + __expf(-v)); }
; DI void phase_comb1(const Params& p) {
;     ...
;   for (int i = blockIdx.x; i < MG; i += gridDim.x) {
;     if ((i % T) < CTX) continue;
;     const bf16x8 r0 = ld8(R + (long)i * 2048 + c0), r1 = ld8(R + ((long)MG + i) * 2048 + c0), r2 = ld8(R + ((long)2 * MG + i) * 2048 + c0), r3 = ld8(R + ((long)3 * MG + i) * 2048 + c0);
;     const bf16x8 rg0 = ld8(gate + (long)i * 4096 + c0), rg1 = ld8(gate + (long)i * 4096 + 2048 + c0), roa = ld8(Oa + (long)i * 2048 + c0);
;     float o[8];
;     {
;       float h0[8], h1[8], gt[8];
;       float h2[8], h3[8];
;       unpack8(r0, h0); unpack8(r1, h1);
;       unpack8(r2, h2); unpack8(r3, h3); unpack8(rg0, gt);
;       float sm = 0;
;       for (int j = 0; j < 8; ++j) { h0[j] = (h0[j] + h1[j]) + (h2[j] + h3[j]); sm += h0[j]; }
;       sm += __shfl_xor(sm, 1); sm += __shfl_xor(sm, 2); sm += __shfl_xor(sm, 4); sm += __shfl_xor(sm, 8); sm += __shfl_xor(sm, 16);
;       const float mean = sm * (1.f / 256.f);
;       float sq = 0;
;       for (int j = 0; j < 8; ++j) { h0[j] -= mean; sq += h0[j] * h0[j]; }
;       sq += __shfl_xor(sq, 1); sq += __shfl_xor(sq, 2); sq += __shfl_xor(sq, 4); sq += __shfl_xor(sq, 8); sq += __shfl_xor(sq, 16);
;       const float rstd = rsqrtf(sq * (1.f / 256.f) + EPS);
;       for (int j = 0; j < 8; ++j) o[j] = h0[j] * rstd * gr[j] * silu(gt[j]);
.LBB0_2129:
	s_mul_hi_i32 s5, s4, 0x38e38e39
	s_lshr_b32 s6, s5, 31
	s_ashr_i32 s5, s5, 9
	s_add_i32 s5, s5, s6
	s_mulk_i32 s5, 0x900
	s_sub_i32 s5, s4, s5
	s_cmpk_lt_i32 s5, 0x100
	s_cbranch_scc1 .LBB0_2128
	s_ashr_i32 s5, s4, 31
	s_lshl_b64 s[10:11], s[4:5], 12
	s_add_u32 s6, s2, s10
	v_lshl_add_u64 v[8:9], v[38:39], 0, s[10:11]
	s_addc_u32 s7, s3, s11
	global_load_dwordx4 v[16:19], v[8:9], off
	v_lshl_add_u64 v[8:9], s[6:7], 0, v[36:37]
	s_mov_b32 s6, 0x1200000
	v_add_co_u32_e32 v10, vcc, s6, v8
	s_mov_b32 s6, 0x2400000
	s_nop 0
	v_addc_co_u32_e32 v11, vcc, 0, v9, vcc
	global_load_dwordx4 v[20:23], v[10:11], off
	v_add_co_u32_e32 v10, vcc, s6, v8
	s_mov_b32 s6, 0x3600000
	s_nop 0
	v_addc_co_u32_e32 v11, vcc, 0, v9, vcc
	v_add_co_u32_e32 v8, vcc, s6, v8
	s_lshl_b64 s[6:7], s[4:5], 13
	s_nop 0
	v_addc_co_u32_e32 v9, vcc, 0, v9, vcc
	global_load_dwordx4 v[24:27], v[10:11], off
	global_load_dwordx4 v[28:31], v[8:9], off
	s_add_u32 s12, s8, s6
	s_addc_u32 s13, s9, s7
	v_lshl_add_u64 v[8:9], s[12:13], 0, v[36:37]
	global_load_dwordx4 v[32:35], v[8:9], off
	s_movk_i32 s5, 0x1000
	v_add_co_u32_e32 v8, vcc, s5, v8
	v_and_b32_e32 v43, 64, v203
	s_nop 0
	v_addc_co_u32_e32 v9, vcc, 0, v9, vcc
	v_xor_b32_e32 v42, 1, v203
	v_add_u32_e32 v43, 64, v43
	v_cmp_lt_i32_e32 vcc, v42, v43
	v_lshl_add_u64 v[12:13], v[40:41], 0, s[10:11]
	global_load_dwordx4 v[8:11], v[8:9], off
	v_cndmask_b32_e32 v42, v203, v42, vcc
	v_lshlrev_b32_e32 v45, 2, v42
	v_xor_b32_e32 v42, 2, v203
	v_cmp_lt_i32_e32 vcc, v42, v43
	global_load_dwordx4 v[12:15], v[12:13], off
	s_mov_b32 s5, 0x800000
	v_cndmask_b32_e32 v42, v203, v42, vcc
	v_lshlrev_b32_e32 v47, 2, v42
	v_xor_b32_e32 v42, 4, v203
	v_cmp_lt_i32_e32 vcc, v42, v43
	s_add_u32 s6, s0, s6
	s_addc_u32 s7, s1, s7
	v_cndmask_b32_e32 v42, v203, v42, vcc
	v_lshlrev_b32_e32 v46, 2, v42
	v_xor_b32_e32 v42, 8, v203
	v_cmp_lt_i32_e32 vcc, v42, v43
	s_waitcnt vmcnt(0) lgkmcnt(0)
	v_lshlrev_b32_e32 v50, 16, v23
	v_cndmask_b32_e32 v42, v203, v42, vcc
	v_lshlrev_b32_e32 v48, 2, v42
	v_xor_b32_e32 v42, 16, v203
	v_cmp_lt_i32_e32 vcc, v42, v43
	v_and_b32_e32 v43, 0xffff0000, v19
	v_and_b32_e32 v51, 0xffff0000, v23
	v_cndmask_b32_e32 v42, v203, v42, vcc
	v_lshlrev_b32_e32 v49, 2, v42
	v_lshlrev_b32_e32 v42, 16, v19
	v_pk_add_f32 v[42:43], v[42:43], v[50:51]
	v_lshlrev_b32_e32 v52, 16, v27
	v_and_b32_e32 v53, 0xffff0000, v27
	v_lshlrev_b32_e32 v54, 16, v31
	v_and_b32_e32 v55, 0xffff0000, v31
	v_pk_add_f32 v[50:51], v[52:53], v[54:55]
	v_and_b32_e32 v19, 0xffff0000, v22
	v_pk_add_f32 v[42:43], v[42:43], v[50:51]
	v_lshlrev_b32_e32 v50, 16, v18
	v_and_b32_e32 v51, 0xffff0000, v18
	v_lshlrev_b32_e32 v18, 16, v22
	v_lshlrev_b32_e32 v22, 16, v26
	v_and_b32_e32 v23, 0xffff0000, v26
	v_lshlrev_b32_e32 v26, 16, v30
	v_and_b32_e32 v27, 0xffff0000, v30
	v_lshlrev_b32_e32 v30, 16, v34
	v_and_b32_e32 v31, 0xffff0000, v34
	v_pk_add_f32 v[18:19], v[50:51], v[18:19]
	v_pk_add_f32 v[22:23], v[22:23], v[26:27]
	v_lshlrev_b32_e32 v52, 16, v29
	v_pk_add_f32 v[22:23], v[18:19], v[22:23]
	v_mul_f32_e32 v18, 0xbfb8aa3b, v30
	v_mul_f32_e32 v19, 0xbfb8aa3b, v31
	v_exp_f32_e32 v18, v18
	v_exp_f32_e32 v19, v19
	v_and_b32_e32 v53, 0xffff0000, v29
	v_lshlrev_b32_e32 v44, 16, v35
	v_and_b32_e32 v35, 0xffff0000, v35
	v_pk_add_f32 v[18:19], v[18:19], 1.0 op_sel_hi:[1,0]
	s_nop 0
	v_div_scale_f32 v26, s[10:11], v19, v19, v31
	v_rcp_f32_e32 v27, v26
	s_nop 0
	v_fma_f32 v34, -v26, v27, 1.0
	v_fmac_f32_e32 v27, v34, v27
	v_div_scale_f32 v34, vcc, v31, v19, v31
	v_mul_f32_e32 v50, v34, v27
	v_fma_f32 v51, -v26, v50, v34
	v_fmac_f32_e32 v50, v51, v27
	v_fma_f32 v26, -v26, v50, v34
	v_div_fmas_f32 v26, v26, v27, v50
	v_div_fixup_f32 v19, v26, v19, v31
	v_div_scale_f32 v26, s[10:11], v18, v18, v30
	v_rcp_f32_e32 v27, v26
	v_and_b32_e32 v51, 0xffff0000, v25
	v_fma_f32 v31, -v26, v27, 1.0
	v_fmac_f32_e32 v27, v31, v27
	v_div_scale_f32 v31, vcc, v30, v18, v30
	v_mul_f32_e32 v34, v31, v27
	v_fma_f32 v50, -v26, v34, v31
	v_fmac_f32_e32 v34, v50, v27
	v_fma_f32 v26, -v26, v34, v31
	v_div_fmas_f32 v26, v26, v27, v34
	v_div_fixup_f32 v18, v26, v18, v30
	v_lshlrev_b32_e32 v26, 16, v17
	v_and_b32_e32 v27, 0xffff0000, v17
	v_lshlrev_b32_e32 v30, 16, v21
	v_and_b32_e32 v31, 0xffff0000, v21
	v_lshlrev_b32_e32 v50, 16, v25
	v_lshlrev_b32_e32 v17, 16, v33
	v_and_b32_e32 v21, 0xffff0000, v33
	v_pk_add_f32 v[26:27], v[26:27], v[30:31]
	v_pk_add_f32 v[30:31], v[50:51], v[52:53]
	v_mul_f32_e32 v25, 0xbfb8aa3b, v17
	v_pk_add_f32 v[30:31], v[26:27], v[30:31]
	v_exp_f32_e32 v26, v25
	v_mul_f32_e32 v25, 0xbfb8aa3b, v21
	v_exp_f32_e32 v27, v25
	v_and_b32_e32 v51, 0xffff0000, v16
	v_pk_add_f32 v[26:27], v[26:27], 1.0 op_sel_hi:[1,0]
	s_nop 0
	v_div_scale_f32 v25, s[10:11], v27, v27, v21
	v_rcp_f32_e32 v29, v25
	s_nop 0
	v_fma_f32 v33, -v25, v29, 1.0
	v_fmac_f32_e32 v29, v33, v29
	v_div_scale_f32 v33, vcc, v21, v27, v21
	v_mul_f32_e32 v34, v33, v29
	v_fma_f32 v50, -v25, v34, v33
	v_fmac_f32_e32 v34, v50, v29
	v_fma_f32 v25, -v25, v34, v33
	v_div_fmas_f32 v25, v25, v29, v34
	v_div_fixup_f32 v27, v25, v27, v21
	v_div_scale_f32 v21, s[10:11], v26, v26, v17
	v_rcp_f32_e32 v25, v21
	v_lshlrev_b32_e32 v50, 16, v16
	v_lshlrev_b32_e32 v16, 16, v20
	v_fma_f32 v29, -v21, v25, 1.0
	v_fmac_f32_e32 v25, v29, v25
	v_div_scale_f32 v29, vcc, v17, v26, v17
	v_mul_f32_e32 v33, v29, v25
	v_fma_f32 v34, -v21, v33, v29
	v_fmac_f32_e32 v33, v34, v25
	v_fma_f32 v21, -v21, v33, v29
	v_div_fmas_f32 v21, v21, v25, v33
	v_div_fixup_f32 v26, v21, v26, v17
	v_and_b32_e32 v17, 0xffff0000, v20
	v_lshlrev_b32_e32 v20, 16, v24
	v_and_b32_e32 v21, 0xffff0000, v24
	v_lshlrev_b32_e32 v24, 16, v28
	v_and_b32_e32 v25, 0xffff0000, v28
	v_pk_add_f32 v[16:17], v[50:51], v[16:17]
	v_pk_add_f32 v[20:21], v[20:21], v[24:25]
	v_lshlrev_b32_e32 v28, 16, v32
	v_pk_add_f32 v[20:21], v[16:17], v[20:21]
	v_and_b32_e32 v29, 0xffff0000, v32
	v_add_f32_e32 v16, 0, v20
	v_add_f32_e32 v24, v21, v16
	v_mul_f32_e32 v16, 0xbfb8aa3b, v28
	v_mul_f32_e32 v17, 0xbfb8aa3b, v29
	v_exp_f32_e32 v16, v16
	v_exp_f32_e32 v17, v17
	v_add_f32_e32 v24, v30, v24
	v_add_f32_e32 v24, v31, v24
	v_add_f32_e32 v24, v22, v24
	v_pk_add_f32 v[16:17], v[16:17], 1.0 op_sel_hi:[1,0]
	v_add_f32_e32 v24, v23, v24
	v_div_scale_f32 v25, s[10:11], v17, v17, v29
	v_rcp_f32_e32 v32, v25
	v_add_f32_e32 v24, v42, v24
	v_add_f32_e32 v24, v43, v24
	v_fma_f32 v33, -v25, v32, 1.0
	v_fmac_f32_e32 v32, v33, v32
	v_div_scale_f32 v33, vcc, v29, v17, v29
	v_mul_f32_e32 v34, v33, v32
	v_fma_f32 v50, -v25, v34, v33
	v_fmac_f32_e32 v34, v50, v32
	v_fma_f32 v25, -v25, v34, v33
	v_div_fmas_f32 v25, v25, v32, v34
	v_div_fixup_f32 v17, v25, v17, v29
	v_div_scale_f32 v25, s[10:11], v16, v16, v28
	v_rcp_f32_e32 v29, v25
	s_nop 0
	v_fma_f32 v32, -v25, v29, 1.0
	v_fmac_f32_e32 v29, v32, v29
	v_div_scale_f32 v32, vcc, v28, v16, v28
	v_mul_f32_e32 v33, v32, v29
	v_fma_f32 v34, -v25, v33, v32
	v_fmac_f32_e32 v33, v34, v29
	v_fma_f32 v25, -v25, v33, v32
	v_div_fmas_f32 v25, v25, v29, v33
	v_div_fixup_f32 v16, v25, v16, v28
	ds_bpermute_b32 v25, v45, v24
	s_waitcnt lgkmcnt(0)
; DI void phase_comb1(const Params& p) {
;     ...
;       sm += __shfl_xor(sm, 1); sm += __shfl_xor(sm, 2); sm += __shfl_xor(sm, 4); sm += __shfl_xor(sm, 8); sm += __shfl_xor(sm, 16);
;       const float mean = sm * (1.f / 256.f);
;       float sq = 0;
;       for (int j = 0; j < 8; ++j) { h0[j] -= mean; sq += h0[j] * h0[j]; }
;       sq += __shfl_xor(sq, 1); sq += __shfl_xor(sq, 2); sq += __shfl_xor(sq, 4); sq += __shfl_xor(sq, 8); sq += __shfl_xor(sq, 16);
	v_add_f32_e32 v24, v24, v25
	ds_bpermute_b32 v25, v47, v24
	s_waitcnt lgkmcnt(0)
	v_add_f32_e32 v24, v24, v25
	ds_bpermute_b32 v25, v46, v24
	s_waitcnt lgkmcnt(0)
	v_add_f32_e32 v24, v24, v25
	ds_bpermute_b32 v25, v48, v24
	s_waitcnt lgkmcnt(0)
	v_add_f32_e32 v24, v24, v25
	ds_bpermute_b32 v25, v49, v24
	s_waitcnt lgkmcnt(0)
	v_add_f32_e32 v24, v24, v25
	v_mul_f32_e32 v24, 0x3b800000, v24
	v_pk_add_f32 v[20:21], v[20:21], v[24:25] op_sel_hi:[1,0] neg_lo:[0,1] neg_hi:[0,1]
	v_pk_add_f32 v[30:31], v[30:31], v[24:25] op_sel_hi:[1,0] neg_lo:[0,1] neg_hi:[0,1]
	v_pk_mul_f32 v[28:29], v[20:21], v[20:21]
	v_pk_mul_f32 v[32:33], v[30:31], v[30:31]
	v_add_f32_e32 v28, v28, v29
	v_pk_add_f32 v[22:23], v[22:23], v[24:25] op_sel_hi:[1,0] neg_lo:[0,1] neg_hi:[0,1]
	v_add_f32_e32 v28, v32, v28
	v_pk_mul_f32 v[50:51], v[22:23], v[22:23]
	v_add_f32_e32 v28, v33, v28
	v_pk_add_f32 v[24:25], v[42:43], v[24:25] op_sel_hi:[1,0] neg_lo:[0,1] neg_hi:[0,1]
	v_add_f32_e32 v28, v50, v28
	v_pk_mul_f32 v[42:43], v[24:25], v[24:25]
	v_add_f32_e32 v28, v51, v28
	v_add_f32_e32 v28, v42, v28
	v_add_f32_e32 v28, v43, v28
	ds_bpermute_b32 v29, v45, v28
	s_waitcnt lgkmcnt(0)
	v_add_f32_e32 v28, v28, v29
	ds_bpermute_b32 v29, v47, v28
	s_waitcnt lgkmcnt(0)
	v_add_f32_e32 v28, v28, v29
	ds_bpermute_b32 v29, v46, v28
	s_waitcnt lgkmcnt(0)
	v_add_f32_e32 v28, v28, v29
	ds_bpermute_b32 v29, v48, v28
	s_waitcnt lgkmcnt(0)
	v_add_f32_e32 v28, v28, v29
	ds_bpermute_b32 v29, v49, v28
	s_waitcnt lgkmcnt(0)
; DI bf16x8 pack8f(const float* v) { u32x4 w = {cvtpk(v[0], v[1]), cvtpk(v[2], v[3]), cvtpk(v[4], v[5]), cvtpk(v[6], v[7])}; return __builtin_bit_cast(bf16x8, w); }
; DI void unpack8(bf16x8 v, float* f) { u32x4 w = __builtin_bit_cast(u32x4, v); for (int i = 0; i < 4; ++i) { f[2 * i] = bflo(w[i]); f[2 * i + 1] = bfhi(w[i]); } }
; DI float silu(float v) { return v / (1.f + __expf(-v)); }
; DI void phase_comb1(const Params& p) {
;     ...
;       const float rstd = rsqrtf(sq * (1.f / 256.f) + EPS);
;       for (int j = 0; j < 8; ++j) o[j] = h0[j] * rstd * gr[j] * silu(gt[j]);
;       st8(mix + (long)i * 4096 + c0, pack8f(o));
;     }
;     {
;       float a[8], gt[8];
;       unpack8(roa, a); unpack8(rg1, gt);
;       for (int j = 0; j < 8; ++j) o[j] = a[j] * silu(gt[j]);
;       st8(mix + (long)i * 4096 + 2048 + c0, pack8f(o));
;     }
	v_add_f32_e32 v28, v28, v29
	v_fmamk_f32 v28, v28, 0x3b800000, v152
	v_cmp_gt_f32_e32 vcc, s5, v28
	v_mul_f32_e32 v29, 0x4b800000, v28
	s_nop 0
	v_cndmask_b32_e32 v28, v28, v29, vcc
	v_rsq_f32_e32 v28, v28
	s_nop 0
	v_mul_f32_e32 v29, 0x45800000, v28
	v_cndmask_b32_e32 v28, v28, v29, vcc
	v_pk_mul_f32 v[20:21], v[20:21], v[28:29] op_sel_hi:[1,0]
	s_nop 0
	v_pk_mul_f32 v[20:21], v[0:1], v[20:21]
	s_nop 0
	v_pk_mul_f32 v[20:21], v[16:17], v[20:21]
	v_pk_mul_f32 v[16:17], v[30:31], v[28:29] op_sel_hi:[1,0]
	s_nop 0
	v_pk_mul_f32 v[16:17], v[2:3], v[16:17]
	s_nop 0
	v_pk_mul_f32 v[26:27], v[26:27], v[16:17]
	v_pk_mul_f32 v[16:17], v[22:23], v[28:29] op_sel_hi:[1,0]
	s_nop 0
	v_pk_mul_f32 v[16:17], v[4:5], v[16:17]
	s_nop 0
	v_pk_mul_f32 v[22:23], v[18:19], v[16:17]
	v_mul_f32_e32 v16, 0xbfb8aa3b, v44
	v_mul_f32_e32 v17, 0xbfb8aa3b, v35
	v_exp_f32_e32 v16, v16
	v_exp_f32_e32 v17, v17
	v_pk_mul_f32 v[18:19], v[24:25], v[28:29] op_sel_hi:[1,0]
	v_pk_add_f32 v[16:17], v[16:17], 1.0 op_sel_hi:[1,0]
	s_nop 0
	v_div_scale_f32 v24, s[10:11], v17, v17, v35
	v_rcp_f32_e32 v25, v24
	v_pk_mul_f32 v[18:19], v[6:7], v[18:19]
	v_fma_f32 v28, -v24, v25, 1.0
	v_fmac_f32_e32 v25, v28, v25
	v_div_scale_f32 v28, vcc, v35, v17, v35
	v_mul_f32_e32 v29, v28, v25
	v_fma_f32 v30, -v24, v29, v28
	v_fmac_f32_e32 v29, v30, v25
	v_fma_f32 v24, -v24, v29, v28
	v_div_fmas_f32 v24, v24, v25, v29
	v_div_fixup_f32 v17, v24, v17, v35
	v_div_scale_f32 v24, s[10:11], v16, v16, v44
	v_rcp_f32_e32 v25, v24
	s_nop 0
	v_fma_f32 v28, -v24, v25, 1.0
	v_fmac_f32_e32 v25, v28, v25
	v_div_scale_f32 v28, vcc, v44, v16, v44
	v_mul_f32_e32 v29, v28, v25
	v_fma_f32 v30, -v24, v29, v28
	v_fmac_f32_e32 v29, v30, v25
	v_fma_f32 v24, -v24, v29, v28
	v_div_fmas_f32 v24, v24, v25, v29
	v_div_fixup_f32 v16, v24, v16, v44
	v_pk_mul_f32 v[24:25], v[16:17], v[18:19]
	v_lshl_add_u64 v[16:17], s[6:7], 0, v[36:37]
	v_cvt_pk_bf16_f32 v18, v20, v21
	v_cvt_pk_bf16_f32 v19, v26, v27
	v_cvt_pk_bf16_f32 v20, v22, v23
	v_cvt_pk_bf16_f32 v21, v24, v25
	global_store_dwordx4 v[16:17], v[18:21], off
	s_nop 1
	v_lshlrev_b32_e32 v18, 16, v12
	v_and_b32_e32 v19, 0xffff0000, v12
	v_lshlrev_b32_e32 v12, 16, v8
	v_and_b32_e32 v8, 0xffff0000, v8
	v_mul_f32_e32 v20, 0xbfb8aa3b, v12
	v_mul_f32_e32 v21, 0xbfb8aa3b, v8
	v_exp_f32_e32 v20, v20
	v_exp_f32_e32 v21, v21
	s_nop 0
	v_pk_add_f32 v[20:21], v[20:21], 1.0 op_sel_hi:[1,0]
	s_nop 0
	v_div_scale_f32 v22, s[6:7], v21, v21, v8
	v_rcp_f32_e32 v23, v22
	s_nop 0
	v_fma_f32 v24, -v22, v23, 1.0
	v_fmac_f32_e32 v23, v24, v23
	v_div_scale_f32 v24, vcc, v8, v21, v8
	v_mul_f32_e32 v25, v24, v23
	v_fma_f32 v26, -v22, v25, v24
	v_fmac_f32_e32 v25, v26, v23
	v_fma_f32 v22, -v22, v25, v24
	v_div_fmas_f32 v22, v22, v23, v25
	v_div_fixup_f32 v21, v22, v21, v8
	v_div_scale_f32 v8, s[6:7], v20, v20, v12
	v_rcp_f32_e32 v22, v8
	s_nop 0
	v_fma_f32 v23, -v8, v22, 1.0
	v_fmac_f32_e32 v22, v23, v22
	v_div_scale_f32 v23, vcc, v12, v20, v12
	v_mul_f32_e32 v24, v23, v22
	v_fma_f32 v25, -v8, v24, v23
	v_fmac_f32_e32 v24, v25, v22
	v_fma_f32 v8, -v8, v24, v23
	v_div_fmas_f32 v8, v8, v22, v24
	v_div_fixup_f32 v20, v8, v20, v12
	v_pk_mul_f32 v[18:19], v[20:21], v[18:19]
	v_lshlrev_b32_e32 v20, 16, v9
	v_and_b32_e32 v21, 0xffff0000, v9
	v_mul_f32_e32 v8, 0xbfb8aa3b, v20
	v_mul_f32_e32 v9, 0xbfb8aa3b, v21
	v_exp_f32_e32 v8, v8
	v_exp_f32_e32 v9, v9
	v_lshlrev_b32_e32 v12, 16, v13
	v_and_b32_e32 v13, 0xffff0000, v13
	v_pk_add_f32 v[8:9], v[8:9], 1.0 op_sel_hi:[1,0]
	s_nop 0
	v_div_scale_f32 v22, s[6:7], v9, v9, v21
	v_rcp_f32_e32 v23, v22
	s_nop 0
	v_fma_f32 v24, -v22, v23, 1.0
	v_fmac_f32_e32 v23, v24, v23
	v_div_scale_f32 v24, vcc, v21, v9, v21
	v_mul_f32_e32 v25, v24, v23
	v_fma_f32 v26, -v22, v25, v24
	v_fmac_f32_e32 v25, v26, v23
	v_fma_f32 v22, -v22, v25, v24
	v_div_fmas_f32 v22, v22, v23, v25
	v_div_fixup_f32 v9, v22, v9, v21
	v_div_scale_f32 v21, s[6:7], v8, v8, v20
	v_rcp_f32_e32 v22, v21
	s_nop 0
	v_fma_f32 v23, -v21, v22, 1.0
	v_fmac_f32_e32 v22, v23, v22
	v_div_scale_f32 v23, vcc, v20, v8, v20
	v_mul_f32_e32 v24, v23, v22
	v_fma_f32 v25, -v21, v24, v23
	v_fmac_f32_e32 v24, v25, v22
	v_fma_f32 v21, -v21, v24, v23
	v_div_fmas_f32 v21, v21, v22, v24
	v_div_fixup_f32 v8, v21, v8, v20
	v_pk_mul_f32 v[12:13], v[8:9], v[12:13]
	v_lshlrev_b32_e32 v8, 16, v14
	v_and_b32_e32 v9, 0xffff0000, v14
	v_lshlrev_b32_e32 v14, 16, v10
	v_and_b32_e32 v10, 0xffff0000, v10
	v_mul_f32_e32 v20, 0xbfb8aa3b, v14
	v_mul_f32_e32 v21, 0xbfb8aa3b, v10
	v_exp_f32_e32 v20, v20
	v_exp_f32_e32 v21, v21
	s_nop 0
	v_pk_add_f32 v[20:21], v[20:21], 1.0 op_sel_hi:[1,0]
	s_nop 0
	v_div_scale_f32 v22, s[6:7], v21, v21, v10
	v_rcp_f32_e32 v23, v22
	s_nop 0
	v_fma_f32 v24, -v22, v23, 1.0
	v_fmac_f32_e32 v23, v24, v23
	v_div_scale_f32 v24, vcc, v10, v21, v10
	v_mul_f32_e32 v25, v24, v23
	v_fma_f32 v26, -v22, v25, v24
	v_fmac_f32_e32 v25, v26, v23
	v_fma_f32 v22, -v22, v25, v24
	v_div_fmas_f32 v22, v22, v23, v25
	v_div_fixup_f32 v21, v22, v21, v10
	v_div_scale_f32 v10, s[6:7], v20, v20, v14
	v_rcp_f32_e32 v22, v10
	s_nop 0
	v_fma_f32 v23, -v10, v22, 1.0
	v_fmac_f32_e32 v22, v23, v22
	v_div_scale_f32 v23, vcc, v14, v20, v14
	v_mul_f32_e32 v24, v23, v22
	v_fma_f32 v25, -v10, v24, v23
	v_fmac_f32_e32 v24, v25, v22
	v_fma_f32 v10, -v10, v24, v23
	v_div_fmas_f32 v10, v10, v22, v24
	v_div_fixup_f32 v20, v10, v20, v14
	v_pk_mul_f32 v[20:21], v[20:21], v[8:9]
	v_lshlrev_b32_e32 v8, 16, v15
	v_and_b32_e32 v9, 0xffff0000, v15
	v_lshlrev_b32_e32 v14, 16, v11
	v_and_b32_e32 v15, 0xffff0000, v11
	v_mul_f32_e32 v10, 0xbfb8aa3b, v14
	v_mul_f32_e32 v11, 0xbfb8aa3b, v15
	v_exp_f32_e32 v10, v10
	v_exp_f32_e32 v11, v11
	s_nop 0
	v_pk_add_f32 v[10:11], v[10:11], 1.0 op_sel_hi:[1,0]
	s_nop 0
	v_div_scale_f32 v22, s[6:7], v11, v11, v15
	v_rcp_f32_e32 v23, v22
	s_nop 0
	v_fma_f32 v24, -v22, v23, 1.0
	v_fmac_f32_e32 v23, v24, v23
	v_div_scale_f32 v24, vcc, v15, v11, v15
	v_mul_f32_e32 v25, v24, v23
	v_fma_f32 v26, -v22, v25, v24
	v_fmac_f32_e32 v25, v26, v23
	v_fma_f32 v22, -v22, v25, v24
	v_div_fmas_f32 v22, v22, v23, v25
	v_div_fixup_f32 v11, v22, v11, v15
	v_div_scale_f32 v15, s[6:7], v10, v10, v14
	v_rcp_f32_e32 v22, v15
	s_nop 0
	v_fma_f32 v23, -v15, v22, 1.0
	v_fmac_f32_e32 v22, v23, v22
	v_div_scale_f32 v23, vcc, v14, v10, v14
	v_mul_f32_e32 v24, v23, v22
	v_fma_f32 v25, -v15, v24, v23
	v_fmac_f32_e32 v24, v25, v22
	v_fma_f32 v15, -v15, v24, v23
	v_div_fmas_f32 v15, v15, v22, v24
	v_div_fixup_f32 v10, v15, v10, v14
	v_pk_mul_f32 v[14:15], v[10:11], v[8:9]
	v_cvt_pk_bf16_f32 v9, v12, v13
	v_add_co_u32_e32 v12, vcc, 0x1000, v16
	v_cvt_pk_bf16_f32 v8, v18, v19
	v_cvt_pk_bf16_f32 v10, v20, v21
	v_cvt_pk_bf16_f32 v11, v14, v15
	v_addc_co_u32_e32 v13, vcc, 0, v17, vcc
	global_store_dwordx4 v[12:13], v[8:11], off
	s_branch .LBB0_2128

; DI int TID() { int t = threadIdx.x; asm volatile("" : "+v"(t)); return t; }
; DI void gemm_preload(const bfu* __restrict__ A, const bfu* __restrict__ Bt, int K, int kt, bf16x8 (&ra)[4], bf16x8 (&rb)[8]) {
;   const int tid = TID(), sr = tid >> 3, sc = (tid & 7) * 8;
;   const bfu* Ag = A + (long)sr * K + sc + kt * BK; const bfu* Bg = Bt + (long)sr * K + sc + kt * BK;
; #pragma unroll
;   for (int i = 0; i < 4; ++i) ra[i] = ld8(Ag + (long)(32 * i) * K);
; #pragma unroll
;   for (int i = 0; i < 8; ++i) rb[i] = ld8(Bg + (long)(32 * i) * K);
; }
; DI void phase_gemm(const Params& p, int g, int kind, char* smem, float* rsl, int* s_item, int vlo, int vhi, int cslot) {
;     ...
;   TD cur; fetch(cur);
;   bf16x8 ra[4], rb[8];
;   if (cur.ok) gemm_preload(cur.A, cur.Bt, cur.K, 0, ra, rb);
.LBB0_2183:
	s_andn2_b64 vcc, exec, s[2:3]
	s_cbranch_vccz .LBB0_2212
	s_lshl_b32 s2, s9, 3
	s_sub_i32 s2, s7, s2
	s_lshl_b32 s3, s6, 11
	s_lshl_b32 s2, s2, 8
	s_add_i32 s6, s3, s2
	s_ashr_i32 s7, s6, 31
	s_lshl_b64 s[2:3], s[6:7], 13
	v_readlane_b32 s4, v254, 60
	s_add_u32 s4, s4, s2
	v_readlane_b32 s2, v254, 61
	s_addc_u32 s5, s2, s3
	s_ashr_i32 s9, s8, 31
	v_mov_b32_e32 v4, v202
	s_lshl_b64 s[2:3], s[8:9], 13
	s_add_u32 s2, s0, s2
	v_ashrrev_i32_e32 v0, 3, v4
	v_ashrrev_i32_e32 v1, 31, v0
	s_addc_u32 s3, s1, s3
	v_lshlrev_b64 v[0:1], 13, v[0:1]
	v_lshlrev_b32_e32 v4, 4, v4
	v_lshl_add_u64 v[2:3], s[2:3], 0, v[0:1]
	v_and_b32_e32 v184, 0x70, v4
	v_lshl_add_u64 v[2:3], v[2:3], 0, v[184:185]
	v_add_co_u32_e32 v4, vcc, s65, v2
	v_lshl_add_u64 v[0:1], s[4:5], 0, v[0:1]
	s_nop 0
	v_addc_co_u32_e32 v5, vcc, 0, v3, vcc
	v_add_co_u32_e32 v6, vcc, s67, v2
	global_load_dwordx4 v[128:131], v[2:3], off
	s_nop 0
	v_addc_co_u32_e32 v7, vcc, 0, v3, vcc
	v_add_co_u32_e32 v2, vcc, s73, v2
	v_lshl_add_u64 v[0:1], v[0:1], 0, v[184:185]
	s_nop 0
	v_addc_co_u32_e32 v3, vcc, 0, v3, vcc
	global_load_dwordx4 v[132:135], v[4:5], off
	global_load_dwordx4 v[136:139], v[6:7], off
	global_load_dwordx4 v[140:143], v[2:3], off
	global_load_dwordx4 v[144:147], v[0:1], off
	v_add_co_u32_e32 v2, vcc, s65, v0
	s_nop 1
	v_addc_co_u32_e32 v3, vcc, 0, v1, vcc
	v_add_co_u32_e32 v4, vcc, s67, v0
	s_nop 1
	v_addc_co_u32_e32 v5, vcc, 0, v1, vcc
	global_load_dwordx4 v[148:151], v[2:3], off
	global_load_dwordx4 v[152:155], v[4:5], off
	v_add_co_u32_e32 v2, vcc, s73, v0
	s_nop 1
	v_addc_co_u32_e32 v3, vcc, 0, v1, vcc
	v_add_co_u32_e32 v4, vcc, s51, v0
	s_nop 1
	v_addc_co_u32_e32 v5, vcc, 0, v1, vcc
	global_load_dwordx4 v[156:159], v[2:3], off
	global_load_dwordx4 v[160:163], v[4:5], off
	v_add_co_u32_e32 v2, vcc, 0x140000, v0
	s_nop 1
	v_addc_co_u32_e32 v3, vcc, 0, v1, vcc
	v_add_co_u32_e32 v4, vcc, 0x180000, v0
	s_nop 1
	v_addc_co_u32_e32 v5, vcc, 0, v1, vcc
	v_add_co_u32_e32 v0, vcc, 0x1c0000, v0
	global_load_dwordx4 v[164:167], v[2:3], off
	global_load_dwordx4 v[168:171], v[4:5], off
	v_addc_co_u32_e32 v1, vcc, 0, v1, vcc
	global_load_dwordx4 v[172:175], v[0:1], off
	s_branch .LBB0_2186

; #define MFMA(a, b, c) __builtin_amdgcn_mfma_f32_32x32x16_bf16((a), (b), (c), 0, 0, 0)
; DI void gemm_main2(const bfu* __restrict__ A, const bfu* __restrict__ Bt, int K, char* smem, f32x16 (&acc)[2][4], bf16x8 (&ra)[4], bf16x8 (&rb)[8]) {
;     ...
;   for (int kt = 0; kt < nk; ++kt) {
;     __syncthreads();
; #pragma unroll
;     for (int i = 0; i < 4; ++i) st8(As + (sr + 32 * i) * LDT + sc, ra[i]);
; #pragma unroll
;     for (int i = 0; i < 8; ++i) st8(Bs + (sr + 32 * i) * LDT + sc, rb[i]);
;     __syncthreads();
;     if (kt + 1 < nk) gemm_preload(A, Bt, K, kt + 1, ra, rb);
; #pragma unroll
;     for (int ks = 0; ks < 4; ++ks) {
;       const bf16x8 a0 = ld8(as + ks * 16), a1 = ld8(as + 32 * LDT + ks * 16);
; #pragma unroll
;       for (int j = 0; j < 4; ++j) {
;         const bf16x8 b = ld8(bs + j * 32 * LDT + ks * 16);
;         acc[0][j] = MFMA(a0, b, acc[0][j]); acc[1][j] = MFMA(a1, b, acc[1][j]);
;       }
;     }
.LBB0_2187:
	s_waitcnt lgkmcnt(0)
	s_barrier
	s_waitcnt vmcnt(0)
	ds_write_b128 v178, v[128:131]
	ds_write_b128 v178, v[132:135] offset:4608
	ds_write_b128 v178, v[136:139] offset:9216
	ds_write_b128 v178, v[140:143] offset:13824
	ds_write_b128 v178, v[144:147] offset:18432
	ds_write_b128 v178, v[148:151] offset:23040
	ds_write_b128 v178, v[152:155] offset:27648
	ds_write_b128 v178, v[156:159] offset:32256
	ds_write_b128 v178, v[160:163] offset:36864
	ds_write_b128 v178, v[164:167] offset:41472
	ds_write_b128 v178, v[168:171] offset:46080
	ds_write_b128 v178, v[172:175] offset:50688
	v_mov_b32_e32 v164, v202
	s_waitcnt lgkmcnt(0)
	s_barrier
	ds_read_b128 v[128:131], v176
	ds_read_b128 v[132:135], v177 offset:18432
	ds_read_b128 v[136:139], v176 offset:32
	ds_read_b128 v[140:143], v177 offset:18464
	ds_read_b128 v[144:147], v176 offset:4608
	ds_read_b128 v[148:151], v176 offset:4640
	s_waitcnt lgkmcnt(4)
	v_mfma_f32_32x32x16_bf16 v[112:127], v[128:131], v[132:135], v[112:127]
	s_mov_b32 s7, 0x140000
	s_waitcnt lgkmcnt(1)
	v_mfma_f32_32x32x16_bf16 v[48:63], v[144:147], v[132:135], v[48:63]
	ds_read_b128 v[132:135], v177 offset:23040
	ds_read_b128 v[152:155], v177 offset:23072
	s_waitcnt lgkmcnt(1)
	v_mfma_f32_32x32x16_bf16 v[96:111], v[128:131], v[132:135], v[96:111]
	v_mfma_f32_32x32x16_bf16 v[32:47], v[144:147], v[132:135], v[32:47]
	ds_read_b128 v[132:135], v177 offset:27648
	ds_read_b128 v[156:159], v177 offset:27680
	s_waitcnt lgkmcnt(1)
	v_mfma_f32_32x32x16_bf16 v[80:95], v[128:131], v[132:135], v[80:95]
	v_mfma_f32_32x32x16_bf16 v[16:31], v[144:147], v[132:135], v[16:31]
	ds_read_b128 v[132:135], v177 offset:32256
	ds_read_b128 v[160:163], v177 offset:32288
	s_waitcnt lgkmcnt(1)
	v_mfma_f32_32x32x16_bf16 v[64:79], v[128:131], v[132:135], v[64:79]
	v_mfma_f32_32x32x16_bf16 v[112:127], v[136:139], v[140:143], v[112:127]
	v_mfma_f32_32x32x16_bf16 v[48:63], v[148:151], v[140:143], v[48:63]
	v_mfma_f32_32x32x16_bf16 v[0:15], v[144:147], v[132:135], v[0:15]
	v_mfma_f32_32x32x16_bf16 v[96:111], v[136:139], v[152:155], v[96:111]
	v_mfma_f32_32x32x16_bf16 v[32:47], v[148:151], v[152:155], v[32:47]
	v_mfma_f32_32x32x16_bf16 v[80:95], v[136:139], v[156:159], v[80:95]
	s_waitcnt lgkmcnt(0)
	v_mfma_f32_32x32x16_bf16 v[64:79], v[136:139], v[160:163], v[64:79]
	ds_read_b128 v[128:131], v176 offset:64
	ds_read_b128 v[132:135], v177 offset:18496
	ds_read_b128 v[168:171], v176 offset:96
	ds_read_b128 v[136:139], v177 offset:18528
	ds_read_b128 v[140:143], v176 offset:4672
	ds_read_b128 v[180:183], v176 offset:4704
	v_mfma_f32_32x32x16_bf16 v[16:31], v[148:151], v[156:159], v[16:31]
	s_waitcnt lgkmcnt(4)
	v_mfma_f32_32x32x16_bf16 v[112:127], v[128:131], v[132:135], v[112:127]
	s_waitcnt lgkmcnt(1)
	v_mfma_f32_32x32x16_bf16 v[48:63], v[140:143], v[132:135], v[48:63]
	ds_read_b128 v[132:135], v177 offset:23104
	ds_read_b128 v[152:155], v177 offset:23136
	s_waitcnt lgkmcnt(1)
	v_mfma_f32_32x32x16_bf16 v[96:111], v[128:131], v[132:135], v[96:111]
	v_mfma_f32_32x32x16_bf16 v[32:47], v[140:143], v[132:135], v[32:47]
	ds_read_b128 v[132:135], v177 offset:27712
	ds_read_b128 v[172:175], v177 offset:27744
	s_waitcnt lgkmcnt(1)
	v_mfma_f32_32x32x16_bf16 v[80:95], v[128:131], v[132:135], v[80:95]
	v_mfma_f32_32x32x16_bf16 v[16:31], v[140:143], v[132:135], v[16:31]
	ds_read_b128 v[132:135], v177 offset:32320
	ds_read_b128 v[188:191], v177 offset:32352
	v_mfma_f32_32x32x16_bf16 v[0:15], v[148:151], v[160:163], v[0:15]
	s_waitcnt lgkmcnt(1)
	v_mfma_f32_32x32x16_bf16 v[64:79], v[128:131], v[132:135], v[64:79]
	v_ashrrev_i32_e32 v128, 3, v164
	v_ashrrev_i32_e32 v129, 31, v128
	v_lshlrev_b64 v[128:129], 13, v[128:129]
	v_and_b32_e32 v130, 7, v164
	v_lshl_or_b32 v128, v130, 4, v128
	v_lshl_add_u64 v[144:145], s[10:11], 0, v[128:129]
	v_lshl_add_u64 v[192:193], s[4:5], 0, v[144:145]
	v_mfma_f32_32x32x16_bf16 v[0:15], v[140:143], v[132:135], v[0:15]
	v_lshl_add_u64 v[140:141], s[2:3], 0, v[144:145]
	v_add_co_u32_e32 v132, vcc, s65, v140
	s_add_u32 s10, s10, 0x80
	s_nop 0
	v_addc_co_u32_e32 v133, vcc, 0, v141, vcc
	global_load_dwordx4 v[128:131], v[140:141], off offset:128
	s_nop 0
	global_load_dwordx4 v[132:135], v[132:133], off offset:128
	v_mfma_f32_32x32x16_bf16 v[112:127], v[168:171], v[136:139], v[112:127]
	s_addc_u32 s11, s11, 0
	s_cmpk_lg_i32 s10, 0x1f80
	v_mfma_f32_32x32x16_bf16 v[48:63], v[180:183], v[136:139], v[48:63]
	v_add_co_u32_e32 v136, vcc, s67, v140
	s_nop 1
	v_addc_co_u32_e32 v137, vcc, 0, v141, vcc
	v_add_co_u32_e32 v140, vcc, s73, v140
	v_mfma_f32_32x32x16_bf16 v[96:111], v[168:171], v[152:155], v[96:111]
	s_nop 0
	v_addc_co_u32_e32 v141, vcc, 0, v141, vcc
	v_add_co_u32_e32 v148, vcc, s65, v192
	global_load_dwordx4 v[136:139], v[136:137], off offset:128
	s_nop 0
	global_load_dwordx4 v[140:143], v[140:141], off offset:128
	v_addc_co_u32_e32 v149, vcc, 0, v193, vcc
	v_mfma_f32_32x32x16_bf16 v[32:47], v[180:183], v[152:155], v[32:47]
	v_add_co_u32_e32 v152, vcc, s67, v192
	global_load_dwordx4 v[144:147], v[192:193], off offset:128
	s_nop 0
	global_load_dwordx4 v[148:151], v[148:149], off offset:128
	v_addc_co_u32_e32 v153, vcc, 0, v193, vcc
	v_add_co_u32_e32 v156, vcc, s73, v192
	v_mfma_f32_32x32x16_bf16 v[80:95], v[168:171], v[172:175], v[80:95]
	s_nop 0
	v_addc_co_u32_e32 v157, vcc, 0, v193, vcc
	v_add_co_u32_e32 v160, vcc, s51, v192
	global_load_dwordx4 v[152:155], v[152:153], off offset:128
	s_nop 0
	global_load_dwordx4 v[156:159], v[156:157], off offset:128
	v_addc_co_u32_e32 v161, vcc, 0, v193, vcc
	v_add_co_u32_e32 v164, vcc, s7, v192
	s_mov_b32 s7, 0x180000
	s_nop 0
	v_addc_co_u32_e32 v165, vcc, 0, v193, vcc
	v_mfma_f32_32x32x16_bf16 v[16:31], v[180:183], v[172:175], v[16:31]
	v_add_co_u32_e32 v172, vcc, s7, v192
	s_mov_b32 s7, 0x1c0000
	s_nop 0
	v_addc_co_u32_e32 v173, vcc, 0, v193, vcc
	v_add_co_u32_e32 v174, vcc, s7, v192
	global_load_dwordx4 v[160:163], v[160:161], off offset:128
	s_nop 0
	global_load_dwordx4 v[164:167], v[164:165], off offset:128
	v_addc_co_u32_e32 v175, vcc, 0, v193, vcc
	s_waitcnt lgkmcnt(0)
	v_mfma_f32_32x32x16_bf16 v[64:79], v[168:171], v[188:191], v[64:79]
	global_load_dwordx4 v[168:171], v[172:173], off offset:128
	s_nop 0
	global_load_dwordx4 v[172:175], v[174:175], off offset:128
	v_mfma_f32_32x32x16_bf16 v[0:15], v[180:183], v[188:191], v[0:15]
	s_cbranch_scc1 .LBB0_2187
; #define MFMA(a, b, c) __builtin_amdgcn_mfma_f32_32x32x16_bf16((a), (b), (c), 0, 0, 0)
; DI void gemm_main2(const bfu* __restrict__ A, const bfu* __restrict__ Bt, int K, char* smem, f32x16 (&acc)[2][4], bf16x8 (&ra)[4], bf16x8 (&rb)[8]) {
;     ...
;   for (int kt = 0; kt < nk; ++kt) {
;     __syncthreads();
; #pragma unroll
;     for (int i = 0; i < 4; ++i) st8(As + (sr + 32 * i) * LDT + sc, ra[i]);
; #pragma unroll
;     for (int i = 0; i < 8; ++i) st8(Bs + (sr + 32 * i) * LDT + sc, rb[i]);
;     __syncthreads();
;     if (kt + 1 < nk) gemm_preload(A, Bt, K, kt + 1, ra, rb);
; #pragma unroll
;     for (int ks = 0; ks < 4; ++ks) {
;       const bf16x8 a0 = ld8(as + ks * 16), a1 = ld8(as + 32 * LDT + ks * 16);
; #pragma unroll
;       for (int j = 0; j < 4; ++j) {
;         const bf16x8 b = ld8(bs + j * 32 * LDT + ks * 16);
;         acc[0][j] = MFMA(a0, b, acc[0][j]); acc[1][j] = MFMA(a1, b, acc[1][j]);
;       }
;     }
	s_barrier
	s_waitcnt vmcnt(0)
	ds_write_b128 v178, v[128:131]
	ds_write_b128 v178, v[132:135] offset:4608
	ds_write_b128 v178, v[136:139] offset:9216
	ds_write_b128 v178, v[140:143] offset:13824
	ds_write_b128 v178, v[144:147] offset:18432
	ds_write_b128 v178, v[148:151] offset:23040
	ds_write_b128 v178, v[152:155] offset:27648
	ds_write_b128 v178, v[156:159] offset:32256
	ds_write_b128 v178, v[160:163] offset:36864
	ds_write_b128 v178, v[164:167] offset:41472
	ds_write_b128 v178, v[168:171] offset:46080
	ds_write_b128 v178, v[172:175] offset:50688
	s_waitcnt lgkmcnt(0)
	s_barrier
	ds_read_b128 v[178:181], v176
	ds_read_b128 v[188:191], v177 offset:18432
	ds_read_b128 v[192:195], v176 offset:4608
	s_waitcnt lgkmcnt(1)
	v_mfma_f32_32x32x16_bf16 v[112:127], v[178:181], v[188:191], v[112:127]
	s_waitcnt lgkmcnt(0)
	v_mfma_f32_32x32x16_bf16 v[48:63], v[192:195], v[188:191], v[48:63]
	ds_read_b128 v[188:191], v177 offset:23040
	s_waitcnt lgkmcnt(0)
	v_mfma_f32_32x32x16_bf16 v[96:111], v[178:181], v[188:191], v[96:111]
	v_mfma_f32_32x32x16_bf16 v[32:47], v[192:195], v[188:191], v[32:47]
	ds_read_b128 v[188:191], v177 offset:27648
	s_waitcnt lgkmcnt(0)
	v_mfma_f32_32x32x16_bf16 v[80:95], v[178:181], v[188:191], v[80:95]
	v_mfma_f32_32x32x16_bf16 v[16:31], v[192:195], v[188:191], v[16:31]
	ds_read_b128 v[188:191], v177 offset:32256
	s_waitcnt lgkmcnt(0)
	v_mfma_f32_32x32x16_bf16 v[64:79], v[178:181], v[188:191], v[64:79]
	v_mfma_f32_32x32x16_bf16 v[0:15], v[192:195], v[188:191], v[0:15]
	ds_read_b128 v[178:181], v176 offset:32
	ds_read_b128 v[188:191], v177 offset:18464
	ds_read_b128 v[192:195], v176 offset:4640
	s_waitcnt lgkmcnt(1)
	v_mfma_f32_32x32x16_bf16 v[112:127], v[178:181], v[188:191], v[112:127]
	s_waitcnt lgkmcnt(0)
	v_mfma_f32_32x32x16_bf16 v[48:63], v[192:195], v[188:191], v[48:63]
	ds_read_b128 v[188:191], v177 offset:23072
	s_waitcnt lgkmcnt(0)
	v_mfma_f32_32x32x16_bf16 v[96:111], v[178:181], v[188:191], v[96:111]
	v_mfma_f32_32x32x16_bf16 v[32:47], v[192:195], v[188:191], v[32:47]
	ds_read_b128 v[188:191], v177 offset:27680
	s_waitcnt lgkmcnt(0)
	v_mfma_f32_32x32x16_bf16 v[80:95], v[178:181], v[188:191], v[80:95]
	v_mfma_f32_32x32x16_bf16 v[16:31], v[192:195], v[188:191], v[16:31]
	ds_read_b128 v[188:191], v177 offset:32288
	s_waitcnt lgkmcnt(0)
	v_mfma_f32_32x32x16_bf16 v[64:79], v[178:181], v[188:191], v[64:79]
	v_mfma_f32_32x32x16_bf16 v[0:15], v[192:195], v[188:191], v[0:15]
	ds_read_b128 v[178:181], v176 offset:64
	ds_read_b128 v[188:191], v177 offset:18496
	ds_read_b128 v[192:195], v176 offset:4672
	s_waitcnt lgkmcnt(1)
	v_mfma_f32_32x32x16_bf16 v[112:127], v[178:181], v[188:191], v[112:127]
	s_waitcnt lgkmcnt(0)
	v_mfma_f32_32x32x16_bf16 v[48:63], v[192:195], v[188:191], v[48:63]
	ds_read_b128 v[188:191], v177 offset:23104
	s_waitcnt lgkmcnt(0)
	v_mfma_f32_32x32x16_bf16 v[96:111], v[178:181], v[188:191], v[96:111]
	v_mfma_f32_32x32x16_bf16 v[32:47], v[192:195], v[188:191], v[32:47]
	ds_read_b128 v[188:191], v177 offset:27712
	s_waitcnt lgkmcnt(0)
	v_mfma_f32_32x32x16_bf16 v[80:95], v[178:181], v[188:191], v[80:95]
	v_mfma_f32_32x32x16_bf16 v[16:31], v[192:195], v[188:191], v[16:31]
	ds_read_b128 v[188:191], v177 offset:32320
	s_waitcnt lgkmcnt(0)
	v_mfma_f32_32x32x16_bf16 v[64:79], v[178:181], v[188:191], v[64:79]
	v_mfma_f32_32x32x16_bf16 v[0:15], v[192:195], v[188:191], v[0:15]
	ds_read_b128 v[178:181], v176 offset:96
	ds_read_b128 v[188:191], v177 offset:18528
	ds_read_b128 v[192:195], v176 offset:4704
	s_waitcnt lgkmcnt(1)
	v_mfma_f32_32x32x16_bf16 v[112:127], v[178:181], v[188:191], v[112:127]
	s_waitcnt lgkmcnt(0)
	v_mfma_f32_32x32x16_bf16 v[48:63], v[192:195], v[188:191], v[48:63]
	ds_read_b128 v[188:191], v177 offset:23136
	s_waitcnt lgkmcnt(0)
	v_mfma_f32_32x32x16_bf16 v[96:111], v[178:181], v[188:191], v[96:111]
	v_mfma_f32_32x32x16_bf16 v[32:47], v[192:195], v[188:191], v[32:47]
	ds_read_b128 v[188:191], v177 offset:27744
	s_waitcnt lgkmcnt(0)
	v_mfma_f32_32x32x16_bf16 v[80:95], v[178:181], v[188:191], v[80:95]
	v_mfma_f32_32x32x16_bf16 v[16:31], v[192:195], v[188:191], v[16:31]
	ds_read_b128 v[188:191], v177 offset:32352
	s_waitcnt lgkmcnt(0)
	v_mfma_f32_32x32x16_bf16 v[64:79], v[178:181], v[188:191], v[64:79]
	v_mfma_f32_32x32x16_bf16 v[0:15], v[192:195], v[188:191], v[0:15]

; DI int TID() { int t = threadIdx.x; asm volatile("" : "+v"(t)); return t; }
; DI void gemm_preload(const bfu* __restrict__ A, const bfu* __restrict__ Bt, int K, int kt, bf16x8 (&ra)[4], bf16x8 (&rb)[8]) {
;   const int tid = TID(), sr = tid >> 3, sc = (tid & 7) * 8;
;   const bfu* Ag = A + (long)sr * K + sc + kt * BK; const bfu* Bg = Bt + (long)sr * K + sc + kt * BK;
; #pragma unroll
;   for (int i = 0; i < 4; ++i) ra[i] = ld8(Ag + (long)(32 * i) * K);
; #pragma unroll
;   for (int i = 0; i < 8; ++i) rb[i] = ld8(Bg + (long)(32 * i) * K);
; }
; DI void phase_gemm(const Params& p, int g, int kind, char* smem, float* rsl, int* s_item, int vlo, int vhi, int cslot) {
;     ...
;     TD nxt; fetch(nxt);
;     if (nxt.ok) gemm_preload(nxt.A, nxt.Bt, nxt.K, 0, ra, rb);
.LBB0_2199:
	s_xor_b64 s[10:11], s[14:15], -1
	s_and_b64 vcc, exec, s[10:11]
	s_cbranch_vccnz .LBB0_2201
	v_mov_b32_e32 v132, v202
	s_nop 0
	v_ashrrev_i32_e32 v128, 3, v132
	v_ashrrev_i32_e32 v129, 31, v128
	v_lshlrev_b64 v[128:129], 13, v[128:129]
	v_lshlrev_b32_e32 v132, 4, v132
	v_lshl_add_u64 v[130:131], s[2:3], 0, v[128:129]
	v_and_b32_e32 v184, 0x70, v132
	v_lshl_add_u64 v[140:141], v[130:131], 0, v[184:185]
	v_add_co_u32_e32 v132, vcc, 0x40000, v140
	v_lshl_add_u64 v[128:129], s[4:5], 0, v[128:129]
	s_nop 0
	v_addc_co_u32_e32 v133, vcc, 0, v141, vcc
	v_add_co_u32_e32 v136, vcc, 0x80000, v140
	v_lshl_add_u64 v[172:173], v[128:129], 0, v[184:185]
	s_nop 0
	v_addc_co_u32_e32 v137, vcc, 0, v141, vcc
	global_load_dwordx4 v[128:131], v[140:141], off
	v_add_co_u32_e32 v140, vcc, 0xc0000, v140
	global_load_dwordx4 v[132:135], v[132:133], off
	s_nop 0
	global_load_dwordx4 v[136:139], v[136:137], off
	v_addc_co_u32_e32 v141, vcc, 0, v141, vcc
	v_add_co_u32_e32 v148, vcc, s65, v172
	global_load_dwordx4 v[140:143], v[140:141], off
	s_nop 0
	global_load_dwordx4 v[144:147], v[172:173], off
	v_addc_co_u32_e32 v149, vcc, 0, v173, vcc
	v_add_co_u32_e32 v152, vcc, 0x80000, v172
	s_nop 1
	v_addc_co_u32_e32 v153, vcc, 0, v173, vcc
	v_add_co_u32_e32 v156, vcc, 0xc0000, v172
	global_load_dwordx4 v[148:151], v[148:149], off
	s_nop 0
	global_load_dwordx4 v[152:155], v[152:153], off
	v_addc_co_u32_e32 v157, vcc, 0, v173, vcc
	v_add_co_u32_e32 v160, vcc, 0x100000, v172
	s_nop 1
	v_addc_co_u32_e32 v161, vcc, 0, v173, vcc
	v_add_co_u32_e32 v164, vcc, 0x140000, v172
	global_load_dwordx4 v[156:159], v[156:157], off
	s_nop 0
	global_load_dwordx4 v[160:163], v[160:161], off
	v_addc_co_u32_e32 v165, vcc, 0, v173, vcc
	v_add_co_u32_e32 v168, vcc, 0x180000, v172
	s_nop 1
	v_addc_co_u32_e32 v169, vcc, 0, v173, vcc
	v_add_co_u32_e32 v172, vcc, 0x1c0000, v172
	global_load_dwordx4 v[164:167], v[164:165], off
	s_nop 0
	global_load_dwordx4 v[168:171], v[168:169], off
	v_addc_co_u32_e32 v173, vcc, 0, v173, vcc
	global_load_dwordx4 v[172:175], v[172:173], off

;   DI const float* x() const { return (const float*)sp[0]; }
;   DI const float* ctx() const { return (const float*)sp[2]; }
;   DI const float* ln_g() const { return (const float*)sp[6]; }
;   DI const float* ln_b() const { return (const float*)sp[7]; }
; DI float wsum(float v) { for (int o = 32; o > 0; o >>= 1) v += __shfl_xor(v, o); return v; }
; DI void row_ln(float (&v)[32], const float* __restrict__ g, const float* __restrict__ bta, int lane) {
;   float sm = 0.f;
; #pragma unroll
;   for (int i = 0; i < 32; ++i) sm += v[i];
;   const float mean = wsum(sm) * (1.f / DM);
;   float sq = 0.f;
; #pragma unroll
;   for (int i = 0; i < 32; ++i) { v[i] -= mean; sq += v[i] * v[i]; }
;   const float rstd = rsqrtf(wsum(sq) * (1.f / DM) + EPS);
; DI void phase_mod(const Params& p, int g, int layer, char* smem) {
;     ...
;   for (int i = blockIdx.x * 4 + w; i < MG; i += gridDim.x * 4) {
;     const long r = (long)g * MG + i; const int b = (int)(r / T), t = (int)(r % T);
;     float v[32];
;     if (layer == 0) {
;       const float* s = t < CTX ? p.ctx() + ((long)b * CTX + t) * DM : p.x() + ((long)b * SEQ + (t - CTX)) * DM;
; #pragma unroll
;       for (int j = 0; j < 8; ++j) { const f32x4 a = *(const f32x4*)(s + lane * 4 + 256 * j); v[4 * j] = a[0]; v[4 * j + 1] = a[1]; v[4 * j + 2] = a[2]; v[4 * j + 3] = a[3]; }
;     } else {
;       float* s = P_ZX + r * DM;
; #pragma unroll
;       for (int j = 0; j < 8; ++j) { const f32x4 a = *(const f32x4*)(s + lane * 4 + 256 * j); v[4 * j] = a[0]; v[4 * j + 1] = a[1]; v[4 * j + 2] = a[2]; v[4 * j + 3] = a[3]; }
;       row_ln(v, p.ln_g(), p.ln_b(), lane);
.LBB0_2215:
	v_ashrrev_i32_e32 v81, 31, v80
	v_lshl_add_u64 v[0:1], v[80:81], 0, s[42:43]
	v_mul_hi_u32 v184, v0, s61
	v_mad_u64_u32 v[2:3], s[4:5], v1, s61, v[184:185]
	v_mov_b32_e32 v184, v3
	v_mov_b32_e32 v3, v185
	v_mad_u64_u32 v[2:3], s[4:5], v0, s44, v[2:3]
	v_mov_b32_e32 v2, v3
	v_mov_b32_e32 v3, v185
	v_lshl_add_u64 v[2:3], v[184:185], 0, v[2:3]
	v_mad_u64_u32 v[2:3], s[4:5], v1, s44, v[2:3]
	v_ashrrev_i32_e32 v4, 31, v1
	v_mad_u64_u32 v[2:3], s[4:5], v4, s61, v[2:3]
	v_mul_lo_u32 v5, v4, s44
	v_mul_lo_u32 v4, v4, s61
	v_add3_u32 v3, v4, v3, v5
	v_ashrrev_i64 v[4:5], 7, v[2:3]
	v_lshrrev_b32_e32 v184, 31, v3
	v_lshl_add_u64 v[88:89], v[4:5], 0, v[184:185]
	v_mad_u64_u32 v[2:3], s[4:5], v88, s52, 0
	v_mov_b32_e32 v4, v3
	v_mad_u64_u32 v[4:5], s[4:5], v89, s52, v[4:5]
	v_sub_co_u32_e32 v90, vcc, v0, v2
	v_mov_b32_e32 v12, 0x12230
	s_nop 0
	v_subb_co_u32_e32 v91, vcc, v1, v4, vcc
	v_lshlrev_b64 v[0:1], 13, v[0:1]
	v_lshl_add_u64 v[94:95], v[84:85], 0, v[0:1]
	global_load_dwordx4 v[20:23], v[94:95], off
	global_load_dwordx4 v[32:35], v[94:95], off offset:1024
	global_load_dwordx4 v[40:43], v[94:95], off offset:2048
	global_load_dwordx4 v[48:51], v[94:95], off offset:3072
	v_add_co_u32_e32 v92, vcc, s9, v94
	v_mov_b32_e32 v87, v185
	s_nop 0
	v_addc_co_u32_e32 v93, vcc, 0, v95, vcc
	global_load_dwordx4 v[24:27], v[92:93], off
	global_load_dwordx4 v[8:11], v[92:93], off offset:1024
	global_load_dwordx4 v[4:7], v[92:93], off offset:2048
	global_load_dwordx4 v[0:3], v[92:93], off offset:3072
	ds_read_b128 v[12:15], v12
	s_waitcnt lgkmcnt(0)
	v_lshl_add_u64 v[54:55], v[12:13], 0, v[86:87]
	v_add_co_u32_e32 v140, vcc, s9, v54
	v_lshl_add_u64 v[52:53], v[14:15], 0, v[86:87]
	s_nop 0
	v_addc_co_u32_e32 v141, vcc, 0, v55, vcc
	v_add_co_u32_e32 v142, vcc, s9, v52
	s_waitcnt vmcnt(0)
	v_add_f32_e32 v16, 0, v20
	v_add_f32_e32 v16, v21, v16
	v_add_f32_e32 v16, v22, v16
	v_add_f32_e32 v16, v23, v16
	v_add_f32_e32 v16, v32, v16
	v_add_f32_e32 v16, v33, v16
	v_add_f32_e32 v16, v34, v16
	v_add_f32_e32 v16, v35, v16
	v_add_f32_e32 v16, v40, v16
	v_add_f32_e32 v16, v41, v16
	v_add_f32_e32 v16, v42, v16
	v_add_f32_e32 v16, v43, v16
	v_add_f32_e32 v16, v48, v16
	v_add_f32_e32 v16, v49, v16
	v_add_f32_e32 v16, v50, v16
	v_add_f32_e32 v16, v51, v16
	v_add_f32_e32 v16, v24, v16
	v_add_f32_e32 v16, v25, v16
	v_add_f32_e32 v16, v26, v16
	v_add_f32_e32 v16, v27, v16
	v_add_f32_e32 v16, v8, v16
	v_add_f32_e32 v16, v9, v16
	v_add_f32_e32 v16, v10, v16
	v_add_f32_e32 v16, v11, v16
	v_add_f32_e32 v16, v4, v16
	v_add_f32_e32 v16, v5, v16
	v_add_f32_e32 v16, v6, v16
	v_add_f32_e32 v16, v7, v16
	v_add_f32_e32 v16, v0, v16
	v_add_f32_e32 v16, v1, v16
	v_add_f32_e32 v16, v2, v16
	v_add_f32_e32 v16, v3, v16
	ds_bpermute_b32 v17, v134, v16
	v_addc_co_u32_e32 v143, vcc, 0, v53, vcc
	s_waitcnt lgkmcnt(0)
	v_add_f32_e32 v16, v16, v17
	ds_bpermute_b32 v17, v135, v16
	s_waitcnt lgkmcnt(0)
	v_add_f32_e32 v16, v16, v17
	ds_bpermute_b32 v17, v136, v16
	s_waitcnt lgkmcnt(0)
	v_add_f32_e32 v16, v16, v17
	ds_bpermute_b32 v17, v137, v16
	s_waitcnt lgkmcnt(0)
	v_add_f32_e32 v16, v16, v17
	ds_bpermute_b32 v17, v138, v16
	s_waitcnt lgkmcnt(0)
	v_add_f32_e32 v16, v16, v17
	ds_bpermute_b32 v17, v139, v16
	s_waitcnt lgkmcnt(0)
	v_add_f32_e32 v16, v16, v17
	v_mul_f32_e32 v72, 0x3a000000, v16
	global_load_dwordx4 v[12:15], v[54:55], off
	global_load_dwordx4 v[16:19], v[52:53], off
	v_pk_add_f32 v[76:77], v[20:21], v[72:73] op_sel_hi:[1,0] neg_lo:[0,1] neg_hi:[0,1]
	v_pk_add_f32 v[74:75], v[22:23], v[72:73] op_sel_hi:[1,0] neg_lo:[0,1] neg_hi:[0,1]
	v_pk_mul_f32 v[78:79], v[76:77], v[76:77]
	global_load_dwordx4 v[20:23], v[54:55], off offset:1024
	global_load_dwordx4 v[28:31], v[52:53], off offset:1024
	v_pk_mul_f32 v[112:113], v[74:75], v[74:75]
	v_pk_add_f32 v[98:99], v[32:33], v[72:73] op_sel_hi:[1,0] neg_lo:[0,1] neg_hi:[0,1]
	v_pk_add_f32 v[96:97], v[34:35], v[72:73] op_sel_hi:[1,0] neg_lo:[0,1] neg_hi:[0,1]
	global_load_dwordx4 v[32:35], v[54:55], off offset:2048
	global_load_dwordx4 v[36:39], v[52:53], off offset:2048
	v_pk_add_f32 v[102:103], v[40:41], v[72:73] op_sel_hi:[1,0] neg_lo:[0,1] neg_hi:[0,1]
	v_pk_add_f32 v[100:101], v[42:43], v[72:73] op_sel_hi:[1,0] neg_lo:[0,1] neg_hi:[0,1]
	global_load_dwordx4 v[40:43], v[54:55], off offset:3072
	global_load_dwordx4 v[44:47], v[52:53], off offset:3072
	v_pk_add_f32 v[106:107], v[48:49], v[72:73] op_sel_hi:[1,0] neg_lo:[0,1] neg_hi:[0,1]
	v_pk_add_f32 v[104:105], v[50:51], v[72:73] op_sel_hi:[1,0] neg_lo:[0,1] neg_hi:[0,1]
	global_load_dwordx4 v[48:51], v[140:141], off
	global_load_dwordx4 v[52:55], v[142:143], off
	v_pk_add_f32 v[110:111], v[24:25], v[72:73] op_sel_hi:[1,0] neg_lo:[0,1] neg_hi:[0,1]
	v_pk_add_f32 v[108:109], v[26:27], v[72:73] op_sel_hi:[1,0] neg_lo:[0,1] neg_hi:[0,1]
	global_load_dwordx4 v[56:59], v[140:141], off offset:1024
	global_load_dwordx4 v[60:63], v[142:143], off offset:1024
	v_pk_add_f32 v[116:117], v[8:9], v[72:73] op_sel_hi:[1,0] neg_lo:[0,1] neg_hi:[0,1]
	v_pk_add_f32 v[114:115], v[10:11], v[72:73] op_sel_hi:[1,0] neg_lo:[0,1] neg_hi:[0,1]
	global_load_dwordx4 v[64:67], v[140:141], off offset:2048
	global_load_dwordx4 v[68:71], v[142:143], off offset:2048
	global_load_dwordx4 v[8:11], v[140:141], off offset:3072
	global_load_dwordx4 v[24:27], v[142:143], off offset:3072
	v_add_f32_e32 v78, v78, v79
	v_add_f32_e32 v78, v112, v78
	v_pk_mul_f32 v[118:119], v[98:99], v[98:99]
	v_add_f32_e32 v78, v113, v78
	v_add_f32_e32 v78, v118, v78
	v_pk_mul_f32 v[120:121], v[96:97], v[96:97]
	v_add_f32_e32 v78, v119, v78
	v_add_f32_e32 v78, v120, v78
	v_pk_mul_f32 v[122:123], v[102:103], v[102:103]
	v_add_f32_e32 v78, v121, v78
; DI float wsum(float v) { for (int o = 32; o > 0; o >>= 1) v += __shfl_xor(v, o); return v; }
; DI void row_ln(float (&v)[32], const float* __restrict__ g, const float* __restrict__ bta, int lane) {
;     ...
; #pragma unroll
;   for (int i = 0; i < 32; ++i) { v[i] -= mean; sq += v[i] * v[i]; }
;   const float rstd = rsqrtf(wsum(sq) * (1.f / DM) + EPS);
; #pragma unroll
;   for (int j = 0; j < 8; ++j) {
;     const f32x4 gg = *(const f32x4*)(g + lane * 4 + 256 * j), bb = *(const f32x4*)(bta + lane * 4 + 256 * j);
; #pragma unroll
;     for (int e = 0; e < 4; ++e) v[4 * j + e] = v[4 * j + e] * rstd * gg[e] + bb[e];
;   }
; DI void phase_mod(const Params& p, int g, int layer, char* smem) {
;     ...
;       for (int j = 0; j < 8; ++j) { const f32x4 o = {v[4 * j], v[4 * j + 1], v[4 * j + 2], v[4 * j + 3]}; *(f32x4*)(s + lane * 4 + 256 * j) = o; }
;     }
;     const float* md = P_MOD + ((long)layer * 9 + (t < CTX ? 8 : b)) * 6144;
; #pragma unroll
;     for (int j = 0; j < 8; ++j) {
;       const f32x4 sh = *(const f32x4*)(md + lane * 4 + 256 * j), sc = *(const f32x4*)(md + 2048 + lane * 4 + 256 * j);
	v_add_f32_e32 v78, v122, v78
	v_pk_mul_f32 v[124:125], v[100:101], v[100:101]
	v_add_f32_e32 v78, v123, v78
	v_add_f32_e32 v78, v124, v78
	v_pk_mul_f32 v[126:127], v[106:107], v[106:107]
	v_add_f32_e32 v78, v125, v78
	v_add_f32_e32 v78, v126, v78
	v_pk_mul_f32 v[128:129], v[104:105], v[104:105]
	v_add_f32_e32 v78, v127, v78
	v_add_f32_e32 v78, v128, v78
	v_pk_mul_f32 v[130:131], v[110:111], v[110:111]
	v_add_f32_e32 v78, v129, v78
	v_add_f32_e32 v78, v130, v78
	v_pk_mul_f32 v[132:133], v[108:109], v[108:109]
	v_add_f32_e32 v78, v131, v78
	v_add_f32_e32 v78, v132, v78
	v_pk_mul_f32 v[144:145], v[116:117], v[116:117]
	v_add_f32_e32 v78, v133, v78
	v_add_f32_e32 v78, v144, v78
	v_pk_mul_f32 v[146:147], v[114:115], v[114:115]
	v_add_f32_e32 v78, v145, v78
	v_pk_add_f32 v[4:5], v[4:5], v[72:73] op_sel_hi:[1,0] neg_lo:[0,1] neg_hi:[0,1]
	v_add_f32_e32 v78, v146, v78
	v_pk_mul_f32 v[148:149], v[4:5], v[4:5]
	v_add_f32_e32 v78, v147, v78
	v_pk_add_f32 v[6:7], v[6:7], v[72:73] op_sel_hi:[1,0] neg_lo:[0,1] neg_hi:[0,1]
	v_add_f32_e32 v78, v148, v78
	v_pk_mul_f32 v[150:151], v[6:7], v[6:7]
	v_add_f32_e32 v78, v149, v78
	v_pk_add_f32 v[0:1], v[0:1], v[72:73] op_sel_hi:[1,0] neg_lo:[0,1] neg_hi:[0,1]
	v_add_f32_e32 v78, v150, v78
	v_pk_mul_f32 v[140:141], v[0:1], v[0:1]
	v_add_f32_e32 v78, v151, v78
	v_pk_add_f32 v[2:3], v[2:3], v[72:73] op_sel_hi:[1,0] neg_lo:[0,1] neg_hi:[0,1]
	v_add_f32_e32 v78, v140, v78
	v_pk_mul_f32 v[72:73], v[2:3], v[2:3]
	v_add_f32_e32 v78, v141, v78
	v_add_f32_e32 v72, v72, v78
	v_add_f32_e32 v72, v73, v72
	ds_bpermute_b32 v73, v134, v72
	s_waitcnt lgkmcnt(0)
	v_add_f32_e32 v72, v72, v73
	ds_bpermute_b32 v73, v135, v72
	s_waitcnt lgkmcnt(0)
	v_add_f32_e32 v72, v72, v73
	ds_bpermute_b32 v73, v136, v72
	s_waitcnt lgkmcnt(0)
	v_add_f32_e32 v72, v72, v73
	ds_bpermute_b32 v73, v137, v72
	s_waitcnt lgkmcnt(0)
	v_add_f32_e32 v72, v72, v73
	ds_bpermute_b32 v73, v138, v72
	s_waitcnt lgkmcnt(0)
	v_add_f32_e32 v72, v72, v73
	ds_bpermute_b32 v73, v139, v72
	s_waitcnt lgkmcnt(0)
	v_add_f32_e32 v72, v72, v73
	v_fmamk_f32 v72, v72, 0x3a000000, v152
	v_cmp_gt_f32_e32 vcc, s12, v72
	v_mul_f32_e32 v73, 0x4b800000, v72
	s_nop 0
	v_cndmask_b32_e32 v72, v72, v73, vcc
	v_rsq_f32_e32 v72, v72
	s_nop 0
	v_mul_f32_e32 v73, 0x45800000, v72
	v_cndmask_b32_e32 v112, v72, v73, vcc
	v_pk_mul_f32 v[72:73], v[76:77], v[112:113] op_sel_hi:[1,0]
	v_pk_mul_f32 v[0:1], v[0:1], v[112:113] op_sel_hi:[1,0]
	s_waitcnt vmcnt(0)
	v_pk_fma_f32 v[76:77], v[12:13], v[72:73], v[16:17]
	v_pk_mul_f32 v[12:13], v[74:75], v[112:113] op_sel_hi:[1,0]
	v_pk_fma_f32 v[0:1], v[8:9], v[0:1], v[24:25]
	v_pk_fma_f32 v[78:79], v[14:15], v[12:13], v[18:19]
	v_pk_mul_f32 v[12:13], v[98:99], v[112:113] op_sel_hi:[1,0]
	v_pk_mul_f32 v[2:3], v[2:3], v[112:113] op_sel_hi:[1,0]
	v_pk_fma_f32 v[72:73], v[20:21], v[12:13], v[28:29]
	v_pk_mul_f32 v[12:13], v[96:97], v[112:113] op_sel_hi:[1,0]
	v_mad_u64_u32 v[8:9], s[4:5], v88, s45, v[186:187]
	v_pk_fma_f32 v[74:75], v[22:23], v[12:13], v[30:31]
	v_pk_mul_f32 v[12:13], v[102:103], v[112:113] op_sel_hi:[1,0]
	v_pk_fma_f32 v[2:3], v[10:11], v[2:3], v[26:27]
	v_pk_fma_f32 v[28:29], v[32:33], v[12:13], v[36:37]
	v_pk_mul_f32 v[12:13], v[100:101], v[112:113] op_sel_hi:[1,0]
	v_mov_b32_e32 v10, v9
	v_pk_fma_f32 v[30:31], v[34:35], v[12:13], v[38:39]
	v_pk_mul_f32 v[12:13], v[106:107], v[112:113] op_sel_hi:[1,0]
	v_mad_u64_u32 v[10:11], s[4:5], v89, s45, v[10:11]
	v_cmp_lt_i64_e32 vcc, s[82:83], v[90:91]
	v_pk_fma_f32 v[20:21], v[40:41], v[12:13], v[44:45]
	v_pk_mul_f32 v[12:13], v[104:105], v[112:113] op_sel_hi:[1,0]
	v_cndmask_b32_e32 v9, 0, v10, vcc
	v_cndmask_b32_e32 v8, v223, v8, vcc
	v_pk_fma_f32 v[22:23], v[42:43], v[12:13], v[46:47]
	v_pk_mul_f32 v[12:13], v[110:111], v[112:113] op_sel_hi:[1,0]
	v_lshl_add_u64 v[8:9], s[6:7], 0, v[8:9]
	v_pk_fma_f32 v[16:17], v[48:49], v[12:13], v[52:53]
	v_pk_mul_f32 v[12:13], v[108:109], v[112:113] op_sel_hi:[1,0]
	v_lshl_add_u64 v[36:37], v[8:9], 0, v[86:87]
	s_movk_i32 s4, 0x3000
	v_pk_fma_f32 v[18:19], v[50:51], v[12:13], v[54:55]
	v_pk_mul_f32 v[12:13], v[116:117], v[112:113] op_sel_hi:[1,0]
	v_pk_mul_f32 v[14:15], v[114:115], v[112:113] op_sel_hi:[1,0]
	v_pk_mul_f32 v[4:5], v[4:5], v[112:113] op_sel_hi:[1,0]
	v_pk_mul_f32 v[6:7], v[6:7], v[112:113] op_sel_hi:[1,0]
	v_add_co_u32_e32 v10, vcc, s4, v36
	v_pk_fma_f32 v[12:13], v[56:57], v[12:13], v[60:61]
	v_pk_fma_f32 v[14:15], v[58:59], v[14:15], v[62:63]
	v_pk_fma_f32 v[4:5], v[64:65], v[4:5], v[68:69]
	v_pk_fma_f32 v[6:7], v[66:67], v[6:7], v[70:71]
	global_store_dwordx4 v[94:95], v[76:79], off
	global_store_dwordx4 v[94:95], v[72:75], off offset:1024
	global_store_dwordx4 v[94:95], v[28:31], off offset:2048
	global_store_dwordx4 v[94:95], v[20:23], off offset:3072
	global_store_dwordx4 v[92:93], v[16:19], off
	global_store_dwordx4 v[92:93], v[12:15], off offset:1024
	global_store_dwordx4 v[92:93], v[4:7], off offset:2048
	global_store_dwordx4 v[92:93], v[0:3], off offset:3072
	v_addc_co_u32_e32 v11, vcc, 0, v37, vcc
	global_load_dwordx4 v[24:27], v[36:37], off
	global_load_dwordx4 v[32:35], v[10:11], off offset:-4096
	v_lshlrev_b64 v[8:9], 12, v[80:81]
	v_lshl_add_u64 v[8:9], v[82:83], 0, v[8:9]
	v_lshl_add_u64 v[38:39], v[36:37], 0, s[10:11]
	v_add_u32_e32 v80, s8, v80
	s_movk_i32 s4, 0x11ff
	s_waitcnt vmcnt(0)
; DI unsigned cvtpk(float lo, float hi) { f32x2_t v = {lo, hi}; bf16x2_t b = __builtin_convertvector(v, bf16x2_t); return __builtin_bit_cast(unsigned, b); }
; DI void phase_mod(const Params& p, int g, int layer, char* smem) {
;     ...
;     const float* md = P_MOD + ((long)layer * 9 + (t < CTX ? 8 : b)) * 6144;
; #pragma unroll
;     for (int j = 0; j < 8; ++j) {
;       const f32x4 sh = *(const f32x4*)(md + lane * 4 + 256 * j), sc = *(const f32x4*)(md + 2048 + lane * 4 + 256 * j);
;       u32x2 o = {cvtpk(v[4 * j] * (1.f + sc[0]) + sh[0], v[4 * j + 1] * (1.f + sc[1]) + sh[1]), cvtpk(v[4 * j + 2] * (1.f + sc[2]) + sh[2], v[4 * j + 3] * (1.f + sc[3]) + sh[3])};
;       *reinterpret_cast<u32x2*>(h + (long)i * DM + lane * 4 + 256 * j) = o;
;     }
	v_pk_add_f32 v[32:33], v[32:33], 1.0 op_sel_hi:[1,0]
	s_nop 0
	v_pk_fma_f32 v[24:25], v[32:33], v[76:77], v[24:25]
	v_pk_add_f32 v[32:33], v[34:35], 1.0 op_sel_hi:[1,0]
	v_cvt_pk_bf16_f32 v24, v24, v25
	v_pk_fma_f32 v[26:27], v[32:33], v[78:79], v[26:27]
	s_nop 0
	v_cvt_pk_bf16_f32 v25, v26, v27
	global_store_dwordx2 v[8:9], v[24:25], off
	global_load_dwordx4 v[24:27], v[36:37], off offset:1024
	s_nop 0
	global_load_dwordx4 v[32:35], v[38:39], off offset:1024
	s_waitcnt vmcnt(0)
	v_pk_add_f32 v[32:33], v[32:33], 1.0 op_sel_hi:[1,0]
	s_nop 0
	v_pk_fma_f32 v[24:25], v[32:33], v[72:73], v[24:25]
	v_pk_add_f32 v[32:33], v[34:35], 1.0 op_sel_hi:[1,0]
	v_cvt_pk_bf16_f32 v24, v24, v25
	v_pk_fma_f32 v[26:27], v[32:33], v[74:75], v[26:27]
	s_nop 0
	v_cvt_pk_bf16_f32 v25, v26, v27
	global_store_dwordx2 v[8:9], v[24:25], off offset:512
	global_load_dwordx4 v[24:27], v[36:37], off offset:2048
	s_nop 0
	global_load_dwordx4 v[32:35], v[38:39], off offset:2048
	s_waitcnt vmcnt(0)
	v_pk_add_f32 v[32:33], v[32:33], 1.0 op_sel_hi:[1,0]
	s_nop 0
	v_pk_fma_f32 v[24:25], v[32:33], v[28:29], v[24:25]
	v_pk_add_f32 v[28:29], v[34:35], 1.0 op_sel_hi:[1,0]
	v_cvt_pk_bf16_f32 v24, v24, v25
	v_pk_fma_f32 v[26:27], v[28:29], v[30:31], v[26:27]
	s_nop 0
	v_cvt_pk_bf16_f32 v25, v26, v27
	global_store_dwordx2 v[8:9], v[24:25], off offset:1024
	global_load_dwordx4 v[24:27], v[36:37], off offset:3072
	s_nop 0
	global_load_dwordx4 v[28:31], v[38:39], off offset:3072
	s_waitcnt vmcnt(0)
	v_pk_add_f32 v[28:29], v[28:29], 1.0 op_sel_hi:[1,0]
	s_nop 0
	v_pk_fma_f32 v[20:21], v[28:29], v[20:21], v[24:25]
	v_pk_add_f32 v[24:25], v[30:31], 1.0 op_sel_hi:[1,0]
	v_cvt_pk_bf16_f32 v20, v20, v21
	v_pk_fma_f32 v[22:23], v[24:25], v[22:23], v[26:27]
	v_add_co_u32_e32 v28, vcc, s9, v36
	v_cvt_pk_bf16_f32 v21, v22, v23
	global_store_dwordx2 v[8:9], v[20:21], off offset:1536
	v_addc_co_u32_e32 v29, vcc, 0, v37, vcc
	global_load_dwordx4 v[20:23], v[28:29], off
	global_load_dwordx4 v[24:27], v[10:11], off
	v_cmp_lt_i32_e32 vcc, s4, v80
	s_or_b64 s[2:3], vcc, s[2:3]
	s_waitcnt vmcnt(0)
	v_pk_add_f32 v[24:25], v[24:25], 1.0 op_sel_hi:[1,0]
	s_nop 0
	v_pk_fma_f32 v[16:17], v[24:25], v[16:17], v[20:21]
	v_pk_add_f32 v[20:21], v[26:27], 1.0 op_sel_hi:[1,0]
	v_cvt_pk_bf16_f32 v16, v16, v17
	v_pk_fma_f32 v[18:19], v[20:21], v[18:19], v[22:23]
	s_nop 0
	v_cvt_pk_bf16_f32 v17, v18, v19
	global_store_dwordx2 v[8:9], v[16:17], off offset:2048
	global_load_dwordx4 v[16:19], v[28:29], off offset:1024
	s_nop 0
	global_load_dwordx4 v[20:23], v[10:11], off offset:1024
	s_waitcnt vmcnt(0)
	v_pk_add_f32 v[20:21], v[20:21], 1.0 op_sel_hi:[1,0]
	s_nop 0
	v_pk_fma_f32 v[12:13], v[20:21], v[12:13], v[16:17]
	v_pk_add_f32 v[16:17], v[22:23], 1.0 op_sel_hi:[1,0]
	v_cvt_pk_bf16_f32 v12, v12, v13
	v_pk_fma_f32 v[14:15], v[16:17], v[14:15], v[18:19]
	s_nop 0
	v_cvt_pk_bf16_f32 v13, v14, v15
	global_store_dwordx2 v[8:9], v[12:13], off offset:2560
	global_load_dwordx4 v[12:15], v[28:29], off offset:2048
	s_nop 0
	global_load_dwordx4 v[16:19], v[10:11], off offset:2048
	s_waitcnt vmcnt(0)
	v_pk_add_f32 v[16:17], v[16:17], 1.0 op_sel_hi:[1,0]
	s_nop 0
	v_pk_fma_f32 v[4:5], v[16:17], v[4:5], v[12:13]
	v_pk_add_f32 v[12:13], v[18:19], 1.0 op_sel_hi:[1,0]
	v_cvt_pk_bf16_f32 v4, v4, v5
	v_pk_fma_f32 v[6:7], v[12:13], v[6:7], v[14:15]
	s_nop 0
	v_cvt_pk_bf16_f32 v5, v6, v7
	global_store_dwordx2 v[8:9], v[4:5], off offset:3072
	global_load_dwordx4 v[4:7], v[28:29], off offset:3072
	s_nop 0
	global_load_dwordx4 v[10:13], v[10:11], off offset:3072
	s_waitcnt vmcnt(0)
	v_pk_add_f32 v[10:11], v[10:11], 1.0 op_sel_hi:[1,0]
	s_nop 0
	v_pk_fma_f32 v[0:1], v[10:11], v[0:1], v[4:5]
	v_pk_add_f32 v[4:5], v[12:13], 1.0 op_sel_hi:[1,0]
	v_cvt_pk_bf16_f32 v0, v0, v1
	v_pk_fma_f32 v[2:3], v[4:5], v[2:3], v[6:7]
	s_nop 0
	v_cvt_pk_bf16_f32 v1, v2, v3
	global_store_dwordx2 v[8:9], v[0:1], off offset:3584
	s_andn2_b64 exec, exec, s[2:3]
	s_cbranch_execnz .LBB0_2215

;   DI const float* x() const { return (const float*)sp[0]; }
;   DI const float* c() const { return (const float*)sp[1]; }
; __device__ __forceinline__ unsigned xb_ld(unsigned* p)              { return __hip_atomic_load(p, __ATOMIC_RELAXED, __HIP_MEMORY_SCOPE_AGENT); }
; __device__ __forceinline__ void xcd_barrier_complete(unsigned* bar, unsigned x, unsigned& nloc, unsigned& nx) {
;     const unsigned G = gridDim.x * gridDim.y * gridDim.z;
;     unsigned sum, cnt, mine, sp = 0u;
;     for (;;) {
;         sum = 0u; cnt = 0u; mine = 0u;
; #pragma unroll
;         for (unsigned j = 0; j < 16; ++j) { const unsigned c = xb_ld(&bar[XB_XCNT(j)]); sum += c; cnt += (c > 0u) ? 1u : 0u; mine = (j == x) ? c : mine; }
;         if (sum == G) break;
;         __builtin_amdgcn_s_sleep(1);
;         if ((++sp & 255u) == 0u) { if (xb_ld(&bar[XB_TMO])) break; if (sp > XB_SPIN_CAP) { atomicAdd(&bar[XB_TMO], 1u); break; } }
;     }
;     nloc = mine > 0u ? mine : 1u; nx = cnt > 0u ? cnt : 1u;
; }
.LBB0_2222:
	s_waitcnt lgkmcnt(0)
	v_mov_b64_e32 v[0:1], s[2:3]
	v_mov_b64_e32 v[2:3], s[4:5]
	global_load_dword v0, v[0:1], off sc1
	v_readlane_b32 s40, v254, 15
	global_load_dword v1, v[2:3], off sc1
	v_mov_b64_e32 v[2:3], s[6:7]
	global_load_dword v2, v[2:3], off sc1
	s_or_b64 s[88:89], s[88:89], exec
	s_or_b64 s[70:71], s[70:71], exec
	s_waitcnt vmcnt(0) lgkmcnt(0)
	v_add_u32_e32 v4, v1, v0
	v_add_u32_e32 v6, v4, v2
	v_mov_b64_e32 v[4:5], s[8:9]
	global_load_dword v3, v[4:5], off sc1
	v_mov_b64_e32 v[4:5], s[10:11]
	global_load_dword v4, v[4:5], off sc1
	s_waitcnt vmcnt(0) lgkmcnt(0)
	v_add_u32_e32 v6, v6, v3
	v_add_u32_e32 v8, v6, v4
	v_mov_b64_e32 v[6:7], s[12:13]
	global_load_dword v5, v[6:7], off sc1
	v_mov_b64_e32 v[6:7], s[14:15]
	global_load_dword v6, v[6:7], off sc1
	s_waitcnt vmcnt(0) lgkmcnt(0)
	v_add_u32_e32 v8, v8, v5
	v_add_u32_e32 v10, v8, v6
	v_mov_b64_e32 v[8:9], s[16:17]
	global_load_dword v7, v[8:9], off sc1
	v_mov_b64_e32 v[8:9], s[18:19]
	global_load_dword v8, v[8:9], off sc1
	s_waitcnt vmcnt(0) lgkmcnt(0)
	v_add_u32_e32 v10, v10, v7
	v_add_u32_e32 v12, v10, v8
	v_mov_b64_e32 v[10:11], s[20:21]
	global_load_dword v9, v[10:11], off sc1
	v_mov_b64_e32 v[10:11], s[22:23]
	global_load_dword v10, v[10:11], off sc1
	s_waitcnt vmcnt(0) lgkmcnt(0)
	v_add_u32_e32 v12, v12, v9
	v_add_u32_e32 v14, v12, v10
	v_mov_b64_e32 v[12:13], s[24:25]
	global_load_dword v11, v[12:13], off sc1
	v_mov_b64_e32 v[12:13], s[26:27]
	global_load_dword v12, v[12:13], off sc1
	s_waitcnt vmcnt(0) lgkmcnt(0)
	v_add_u32_e32 v14, v14, v11
	v_add_u32_e32 v16, v14, v12
	v_mov_b64_e32 v[14:15], s[28:29]
	global_load_dword v13, v[14:15], off sc1
	v_mov_b64_e32 v[14:15], s[36:37]
	global_load_dword v14, v[14:15], off sc1
	s_waitcnt vmcnt(0) lgkmcnt(0)
	v_add_u32_e32 v16, v16, v13
	v_add_u32_e32 v18, v16, v14
	v_mov_b64_e32 v[16:17], s[38:39]
	global_load_dword v15, v[16:17], off sc1
	s_waitcnt vmcnt(0) lgkmcnt(0)
	v_add_u32_e32 v16, v18, v15
	v_cmp_ne_u32_e32 vcc, s40, v16
	s_and_saveexec_b64 s[90:91], vcc
	s_cbranch_execz .LBB0_2221
	s_and_b32 s40, s95, 0xff
	s_mov_b64 s[92:93], -1
	s_cmp_eq_u32 s40, 0
	s_mov_b64 s[40:41], -1
	s_mov_b64 s[46:47], -1
	s_sleep 1
	s_cbranch_scc1 .LBB0_2225
	s_and_saveexec_b64 s[62:63], s[40:41]
	s_cbranch_execz .LBB0_2220
	s_branch .LBB0_2228
.LBB0_2225:
	v_mov_b64_e32 v[16:17], s[0:1]
	global_load_dword v16, v[16:17], off sc1
	s_mov_b64 s[40:41], 0
	s_waitcnt vmcnt(0) lgkmcnt(0)
	v_cmp_eq_u32_e32 vcc, 0, v16
	s_and_saveexec_b64 s[62:63], vcc
	s_cmp_lt_u32 s95, 0x40001
	s_cselect_b64 s[40:41], -1, 0
	s_xor_b64 s[46:47], exec, -1
	s_and_b64 s[40:41], s[40:41], exec
	s_or_b64 exec, exec, s[62:63]
	s_and_saveexec_b64 s[62:63], s[40:41]
	s_cbranch_execz .LBB0_2220

;   DI const float* x() const { return (const float*)sp[0]; }
; __device__ __forceinline__ unsigned xb_ld(unsigned* p)              { return __hip_atomic_load(p, __ATOMIC_RELAXED, __HIP_MEMORY_SCOPE_AGENT); }
; __device__ __forceinline__ unsigned xb_add(unsigned* p, unsigned v) { return __hip_atomic_fetch_add(p, v, __ATOMIC_RELAXED, __HIP_MEMORY_SCOPE_AGENT); }
; #define XB_SPIN(cond, bar) do { unsigned _sp = 0; while (cond) { __builtin_amdgcn_s_sleep(1); \
;     if ((++_sp & 255u) == 0u) { if (xb_ld(&(bar)[XB_TMO])) break; if (_sp > XB_SPIN_CAP) { atomicAdd(&(bar)[XB_TMO], 1u); break; } } } } while (0)
; __device__ __forceinline__ void xcd_barrier(const XcdBarrier& b) {
;     ...
;         const unsigned old = xb_add(&bar[XB_XSUB(b.x)], 1u);
;         const unsigned gen = old / nloc;
;         if (old + 1u == (gen + 1u) * nloc) {
;             __builtin_amdgcn_fence(__ATOMIC_RELEASE, "agent");
;             asm volatile("s_waitcnt vmcnt(0)" ::: "memory");
;             const unsigned og = xb_add(&bar[XB_TOP], 1u);
;             const unsigned tg = og / nx;
;             if (og + 1u == (tg + 1u) * nx) xb_add(&bar[XB_TOPGEN], 1u);
;             else XB_SPIN(xb_ld(&bar[XB_TOPGEN]) == tg, bar);
;             __builtin_amdgcn_fence(__ATOMIC_ACQUIRE, "agent");
;             xb_add(&bar[XB_XGEN(b.x)], 1u);
.LBB0_2258:
	s_or_b64 exec, exec, s[2:3]
	s_and_saveexec_b64 s[0:1], s[4:5]
	s_cbranch_execz .LBB0_1231
	v_mov_b32_e32 v2, 1
	global_atomic_add v[0:1], v2, off
	s_branch .LBB0_1231

;   DI const float* x() const { return (const float*)sp[0]; }
;   DI const float* ln_g() const { return (const float*)sp[6]; }
;   DI const float* ln_b() const { return (const float*)sp[7]; }
; DI float wsum(float v) { for (int o = 32; o > 0; o >>= 1) v += __shfl_xor(v, o); return v; }
; DI void row_ln(float (&v)[32], const float* __restrict__ g, const float* __restrict__ bta, int lane) {
;   float sm = 0.f;
; #pragma unroll
;   for (int i = 0; i < 32; ++i) sm += v[i];
;   const float mean = wsum(sm) * (1.f / DM);
;   float sq = 0.f;
; #pragma unroll
;   for (int i = 0; i < 32; ++i) { v[i] -= mean; sq += v[i] * v[i]; }
;   const float rstd = rsqrtf(wsum(sq) * (1.f / DM) + EPS);
; DI void phase_final(const Params& p, char* smem) {
;     ...
;   for (int i = blockIdx.x * 4 + w; i < NB * SEQ; i += gridDim.x * 4) {
;     const int b = i / SEQ, pos = i % SEQ;
;     const float* s = P_ZX + ((long)b * T + CTX + pos) * DM;
;     float v[32];
; #pragma unroll
;     for (int j = 0; j < 8; ++j) { const f32x4 a = *(const f32x4*)(s + lane * 4 + 256 * j); v[4 * j] = a[0]; v[4 * j + 1] = a[1]; v[4 * j + 2] = a[2]; v[4 * j + 3] = a[3]; }
;     row_ln(v, p.ln_g() + DM, p.ln_b() + DM, lane);
.LBB0_2262:
	v_ashrrev_i32_e32 v49, 31, v48
	v_lshrrev_b32_e32 v0, 21, v49
	v_add_u32_e32 v0, v48, v0
	v_ashrrev_i32_e32 v0, 11, v0
	v_mul_i32_i24_e32 v2, 0x800, v0
	v_sub_u32_e32 v2, v48, v2
	v_add_u32_e32 v2, 0x100, v2
	v_mul_hi_i32_i24_e32 v1, 0x900, v0
	v_mul_i32_i24_e32 v0, 0x900, v0
	v_ashrrev_i32_e32 v3, 31, v2
	v_lshl_add_u64 v[0:1], v[0:1], 0, v[2:3]
	v_lshlrev_b64 v[0:1], 13, v[0:1]
	v_lshl_add_u64 v[0:1], v[50:51], 0, v[0:1]
	global_load_dwordx4 v[82:85], v[0:1], off
	global_load_dwordx4 v[86:89], v[0:1], off offset:1024
	global_load_dwordx4 v[90:93], v[0:1], off offset:2048
	global_load_dwordx4 v[94:97], v[0:1], off offset:3072
	v_add_co_u32_e32 v0, vcc, s4, v0
	s_nop 1
	v_addc_co_u32_e32 v1, vcc, 0, v1, vcc
	global_load_dwordx4 v[98:101], v[0:1], off
	global_load_dwordx4 v[102:105], v[0:1], off offset:1024
	global_load_dwordx4 v[106:109], v[0:1], off offset:2048
	global_load_dwordx4 v[110:113], v[0:1], off offset:3072
	s_waitcnt vmcnt(0)
	v_add_f32_e32 v0, 0, v82
	v_add_f32_e32 v0, v83, v0
	v_add_f32_e32 v0, v84, v0
	v_add_f32_e32 v0, v85, v0
	v_add_f32_e32 v0, v86, v0
	v_add_f32_e32 v0, v87, v0
	v_add_f32_e32 v0, v88, v0
	v_add_f32_e32 v0, v89, v0
	v_add_f32_e32 v0, v90, v0
	v_add_f32_e32 v0, v91, v0
	v_add_f32_e32 v0, v92, v0
	v_add_f32_e32 v0, v93, v0
	v_add_f32_e32 v0, v94, v0
	v_add_f32_e32 v0, v95, v0
	v_add_f32_e32 v0, v96, v0
	v_add_f32_e32 v0, v97, v0
	v_add_f32_e32 v0, v98, v0
	v_add_f32_e32 v0, v99, v0
	v_add_f32_e32 v0, v100, v0
	v_add_f32_e32 v0, v101, v0
	v_add_f32_e32 v0, v102, v0
	v_add_f32_e32 v0, v103, v0
	v_add_f32_e32 v0, v104, v0
	v_add_f32_e32 v0, v105, v0
	v_add_f32_e32 v0, v106, v0
	v_add_f32_e32 v0, v107, v0
	v_add_f32_e32 v0, v108, v0
	v_add_f32_e32 v0, v109, v0
	v_add_f32_e32 v0, v110, v0
	v_add_f32_e32 v0, v111, v0
	v_add_f32_e32 v0, v112, v0
	v_add_f32_e32 v0, v113, v0
	ds_bpermute_b32 v1, v74, v0
	s_waitcnt lgkmcnt(0)
	v_add_f32_e32 v0, v0, v1
	ds_bpermute_b32 v1, v75, v0
	s_waitcnt lgkmcnt(0)
	v_add_f32_e32 v16, v0, v1
	ds_bpermute_b32 v17, v76, v16
	global_load_dwordx4 v[0:3], v[54:55], off
	global_load_dwordx4 v[4:7], v[54:55], off offset:1024
	global_load_dwordx4 v[12:15], v[56:57], off
	global_load_dwordx4 v[8:11], v[56:57], off offset:1024
	s_waitcnt lgkmcnt(0)
	v_add_f32_e32 v32, v16, v17
	ds_bpermute_b32 v33, v77, v32
	global_load_dwordx4 v[16:19], v[54:55], off offset:2048
	global_load_dwordx4 v[20:23], v[54:55], off offset:3072
	global_load_dwordx4 v[28:31], v[56:57], off offset:2048
	global_load_dwordx4 v[24:27], v[56:57], off offset:3072
	s_waitcnt lgkmcnt(0)
	v_add_f32_e32 v81, v32, v33
	ds_bpermute_b32 v114, v78, v81
	global_load_dwordx4 v[32:35], v[58:59], off
	global_load_dwordx4 v[36:39], v[60:61], off
	global_load_dwordx4 v[40:43], v[62:63], off
	global_load_dwordx4 v[44:47], v[64:65], off
	s_waitcnt lgkmcnt(0)
	v_add_f32_e32 v81, v81, v114
	ds_bpermute_b32 v130, v79, v81
	global_load_dwordx4 v[114:117], v[66:67], off
	global_load_dwordx4 v[118:121], v[68:69], off
	global_load_dwordx4 v[122:125], v[70:71], off
	global_load_dwordx4 v[126:129], v[72:73], off
	s_waitcnt lgkmcnt(0)
	v_add_f32_e32 v81, v81, v130
	v_mul_f32_e32 v130, 0x3a000000, v81
	v_pk_add_f32 v[82:83], v[82:83], v[130:131] op_sel_hi:[1,0] neg_lo:[0,1] neg_hi:[0,1]
	v_pk_add_f32 v[84:85], v[84:85], v[130:131] op_sel_hi:[1,0] neg_lo:[0,1] neg_hi:[0,1]
	v_pk_add_f32 v[86:87], v[86:87], v[130:131] op_sel_hi:[1,0] neg_lo:[0,1] neg_hi:[0,1]
	v_pk_add_f32 v[88:89], v[88:89], v[130:131] op_sel_hi:[1,0] neg_lo:[0,1] neg_hi:[0,1]
	v_pk_add_f32 v[90:91], v[90:91], v[130:131] op_sel_hi:[1,0] neg_lo:[0,1] neg_hi:[0,1]
	v_pk_add_f32 v[92:93], v[92:93], v[130:131] op_sel_hi:[1,0] neg_lo:[0,1] neg_hi:[0,1]
	v_pk_add_f32 v[94:95], v[94:95], v[130:131] op_sel_hi:[1,0] neg_lo:[0,1] neg_hi:[0,1]
	v_pk_add_f32 v[96:97], v[96:97], v[130:131] op_sel_hi:[1,0] neg_lo:[0,1] neg_hi:[0,1]
	v_pk_add_f32 v[98:99], v[98:99], v[130:131] op_sel_hi:[1,0] neg_lo:[0,1] neg_hi:[0,1]
	v_pk_add_f32 v[100:101], v[100:101], v[130:131] op_sel_hi:[1,0] neg_lo:[0,1] neg_hi:[0,1]
	v_pk_add_f32 v[102:103], v[102:103], v[130:131] op_sel_hi:[1,0] neg_lo:[0,1] neg_hi:[0,1]
	v_pk_add_f32 v[104:105], v[104:105], v[130:131] op_sel_hi:[1,0] neg_lo:[0,1] neg_hi:[0,1]
	v_pk_add_f32 v[106:107], v[106:107], v[130:131] op_sel_hi:[1,0] neg_lo:[0,1] neg_hi:[0,1]
	v_pk_add_f32 v[108:109], v[108:109], v[130:131] op_sel_hi:[1,0] neg_lo:[0,1] neg_hi:[0,1]
	v_pk_add_f32 v[110:111], v[110:111], v[130:131] op_sel_hi:[1,0] neg_lo:[0,1] neg_hi:[0,1]
	v_pk_add_f32 v[112:113], v[112:113], v[130:131] op_sel_hi:[1,0] neg_lo:[0,1] neg_hi:[0,1]
	v_pk_mul_f32 v[130:131], v[82:83], v[82:83]
	v_pk_mul_f32 v[132:133], v[84:85], v[84:85]
	v_add_f32_e32 v81, v130, v131
	v_add_f32_e32 v81, v132, v81
	v_pk_mul_f32 v[134:135], v[86:87], v[86:87]
	v_add_f32_e32 v81, v133, v81
	v_add_f32_e32 v81, v134, v81
	v_pk_mul_f32 v[136:137], v[88:89], v[88:89]
	v_add_f32_e32 v81, v135, v81
	v_add_f32_e32 v81, v136, v81
	v_pk_mul_f32 v[138:139], v[90:91], v[90:91]
	v_add_f32_e32 v81, v137, v81
	v_add_f32_e32 v81, v138, v81
	v_pk_mul_f32 v[140:141], v[92:93], v[92:93]
	v_add_f32_e32 v81, v139, v81
	v_add_f32_e32 v81, v140, v81
	v_pk_mul_f32 v[142:143], v[94:95], v[94:95]
	v_add_f32_e32 v81, v141, v81
	v_add_f32_e32 v81, v142, v81
	v_pk_mul_f32 v[144:145], v[96:97], v[96:97]
	v_add_f32_e32 v81, v143, v81
	v_add_f32_e32 v81, v144, v81
	v_pk_mul_f32 v[146:147], v[98:99], v[98:99]
	v_add_f32_e32 v81, v145, v81
	v_add_f32_e32 v81, v146, v81
	v_pk_mul_f32 v[148:149], v[100:101], v[100:101]
	v_add_f32_e32 v81, v147, v81
	v_add_f32_e32 v81, v148, v81
	v_pk_mul_f32 v[150:151], v[102:103], v[102:103]
	v_add_f32_e32 v81, v149, v81
	v_add_f32_e32 v81, v150, v81
	v_pk_mul_f32 v[152:153], v[104:105], v[104:105]
	v_add_f32_e32 v81, v151, v81
	v_add_f32_e32 v81, v152, v81
	v_pk_mul_f32 v[154:155], v[106:107], v[106:107]
	v_add_f32_e32 v81, v153, v81
	v_add_f32_e32 v81, v154, v81
	v_pk_mul_f32 v[156:157], v[108:109], v[108:109]
	v_add_f32_e32 v81, v155, v81
	v_add_f32_e32 v81, v156, v81
	v_pk_mul_f32 v[158:159], v[110:111], v[110:111]
	v_add_f32_e32 v81, v157, v81
	v_add_f32_e32 v81, v158, v81
	v_pk_mul_f32 v[160:161], v[112:113], v[112:113]
	v_add_f32_e32 v81, v159, v81
	v_add_f32_e32 v81, v160, v81
	v_add_f32_e32 v81, v161, v81
	ds_bpermute_b32 v130, v74, v81
	s_waitcnt lgkmcnt(0)
;   DI const float* ln_g() const { return (const float*)sp[6]; }
;   DI const float* ln_b() const { return (const float*)sp[7]; }
; DI float wsum(float v) { for (int o = 32; o > 0; o >>= 1) v += __shfl_xor(v, o); return v; }
; DI void row_ln(float (&v)[32], const float* __restrict__ g, const float* __restrict__ bta, int lane) {
;     ...
; #pragma unroll
;   for (int i = 0; i < 32; ++i) { v[i] -= mean; sq += v[i] * v[i]; }
;   const float rstd = rsqrtf(wsum(sq) * (1.f / DM) + EPS);
; #pragma unroll
;   for (int j = 0; j < 8; ++j) {
;     const f32x4 gg = *(const f32x4*)(g + lane * 4 + 256 * j), bb = *(const f32x4*)(bta + lane * 4 + 256 * j);
; #pragma unroll
;     for (int e = 0; e < 4; ++e) v[4 * j + e] = v[4 * j + e] * rstd * gg[e] + bb[e];
;   }
; DI void phase_final(const Params& p, char* smem) {
;     ...
;     row_ln(v, p.ln_g() + DM, p.ln_b() + DM, lane);
;     float* d = p.out + (long)i * DM;
; #pragma unroll
;     for (int j = 0; j < 8; ++j) { const f32x4 o = {v[4 * j], v[4 * j + 1], v[4 * j + 2], v[4 * j + 3]}; *(f32x4*)(d + lane * 4 + 256 * j) = o; }
	v_add_f32_e32 v81, v81, v130
	ds_bpermute_b32 v130, v75, v81
	s_waitcnt lgkmcnt(0)
	v_add_f32_e32 v81, v81, v130
	ds_bpermute_b32 v130, v76, v81
	s_waitcnt lgkmcnt(0)
	v_add_f32_e32 v81, v81, v130
	ds_bpermute_b32 v130, v77, v81
	s_waitcnt lgkmcnt(0)
	v_add_f32_e32 v81, v81, v130
	ds_bpermute_b32 v132, v78, v81
	v_lshlrev_b64 v[130:131], 13, v[48:49]
	v_lshl_add_u64 v[130:131], v[52:53], 0, v[130:131]
	v_add_u32_e32 v48, s7, v48
	v_cmp_lt_i32_e64 s[0:1], s6, v48
	s_waitcnt lgkmcnt(0)
	v_add_f32_e32 v49, v81, v132
	ds_bpermute_b32 v81, v79, v49
	v_add_co_u32_e32 v132, vcc, s4, v130
	s_or_b64 s[2:3], s[0:1], s[2:3]
	s_nop 0
	v_addc_co_u32_e32 v133, vcc, 0, v131, vcc
	s_waitcnt lgkmcnt(0)
	v_add_f32_e32 v49, v49, v81
	v_fmamk_f32 v49, v49, 0x3a000000, v80
	v_mul_f32_e32 v81, 0x4b800000, v49
	v_cmp_gt_f32_e32 vcc, s5, v49
	s_nop 1
	v_cndmask_b32_e32 v49, v49, v81, vcc
	v_rsq_f32_e32 v49, v49
	s_nop 0
	v_mul_f32_e32 v81, 0x45800000, v49
	v_cndmask_b32_e32 v134, v49, v81, vcc
	v_pk_mul_f32 v[82:83], v[82:83], v[134:135] op_sel_hi:[1,0]
	v_pk_mul_f32 v[84:85], v[84:85], v[134:135] op_sel_hi:[1,0]
	v_pk_mul_f32 v[86:87], v[86:87], v[134:135] op_sel_hi:[1,0]
	v_pk_mul_f32 v[88:89], v[88:89], v[134:135] op_sel_hi:[1,0]
	v_pk_mul_f32 v[90:91], v[90:91], v[134:135] op_sel_hi:[1,0]
	v_pk_mul_f32 v[92:93], v[92:93], v[134:135] op_sel_hi:[1,0]
	v_pk_mul_f32 v[94:95], v[94:95], v[134:135] op_sel_hi:[1,0]
	v_pk_mul_f32 v[96:97], v[96:97], v[134:135] op_sel_hi:[1,0]
	v_pk_mul_f32 v[98:99], v[98:99], v[134:135] op_sel_hi:[1,0]
	v_pk_mul_f32 v[100:101], v[100:101], v[134:135] op_sel_hi:[1,0]
	v_pk_mul_f32 v[102:103], v[102:103], v[134:135] op_sel_hi:[1,0]
	v_pk_mul_f32 v[104:105], v[104:105], v[134:135] op_sel_hi:[1,0]
	v_pk_mul_f32 v[106:107], v[106:107], v[134:135] op_sel_hi:[1,0]
	v_pk_mul_f32 v[108:109], v[108:109], v[134:135] op_sel_hi:[1,0]
	v_pk_mul_f32 v[110:111], v[110:111], v[134:135] op_sel_hi:[1,0]
	v_pk_mul_f32 v[112:113], v[112:113], v[134:135] op_sel_hi:[1,0]
	s_waitcnt vmcnt(0)
	v_pk_fma_f32 v[2:3], v[2:3], v[84:85], v[14:15]
	v_pk_fma_f32 v[0:1], v[0:1], v[82:83], v[12:13]
	v_pk_fma_f32 v[6:7], v[6:7], v[88:89], v[10:11]
	v_pk_fma_f32 v[4:5], v[4:5], v[86:87], v[8:9]
	v_pk_fma_f32 v[10:11], v[18:19], v[92:93], v[30:31]
	v_pk_fma_f32 v[8:9], v[16:17], v[90:91], v[28:29]
	v_pk_fma_f32 v[14:15], v[22:23], v[96:97], v[26:27]
	v_pk_fma_f32 v[12:13], v[20:21], v[94:95], v[24:25]
	v_pk_fma_f32 v[18:19], v[34:35], v[100:101], v[38:39]
	v_pk_fma_f32 v[16:17], v[32:33], v[98:99], v[36:37]
	v_pk_fma_f32 v[22:23], v[42:43], v[104:105], v[46:47]
	v_pk_fma_f32 v[20:21], v[40:41], v[102:103], v[44:45]
	v_pk_fma_f32 v[26:27], v[116:117], v[108:109], v[120:121]
	v_pk_fma_f32 v[24:25], v[114:115], v[106:107], v[118:119]
	v_pk_fma_f32 v[30:31], v[124:125], v[112:113], v[128:129]
	v_pk_fma_f32 v[28:29], v[122:123], v[110:111], v[126:127]
	global_store_dwordx4 v[130:131], v[0:3], off
	global_store_dwordx4 v[130:131], v[4:7], off offset:1024
	global_store_dwordx4 v[130:131], v[8:11], off offset:2048
	global_store_dwordx4 v[130:131], v[12:15], off offset:3072
	global_store_dwordx4 v[132:133], v[16:19], off
	global_store_dwordx4 v[132:133], v[20:23], off offset:1024
	global_store_dwordx4 v[132:133], v[24:27], off offset:2048
	global_store_dwordx4 v[132:133], v[28:31], off offset:3072
	s_andn2_b64 exec, exec, s[2:3]
	s_cbranch_execnz .LBB0_2262
